# v44 with per-segment K-loop s_setprio toggles removed and one static priority raise for waves 0-3 per GEMM phase (reset at the seam)
# baseline (speedup 1.0000x reference)
; __device__ __forceinline__ int tid_now(int wave_s) { unsigned z = 0u; asm volatile("" : "+v"(z)); return (wave_s << 6) | (int)__builtin_amdgcn_mbcnt_hi(~0u, __builtin_amdgcn_mbcnt_lo(~0u, z)); }
; __device__ __forceinline__ unsigned xb_add(unsigned* p, unsigned v) { return __hip_atomic_fetch_add(p, v, __ATOMIC_RELAXED, __HIP_MEMORY_SCOPE_AGENT); }
; __device__ __forceinline__ void xcd_barrier(const XcdBarrier& b) {
;     asm volatile("s_waitcnt vmcnt(0)" ::: "memory");
;     __syncthreads();
;     if (tid_now(b.w) == 0) {
;         unsigned* bar = b.bar;
;         __builtin_amdgcn_s_waitcnt(0);
;         unsigned nloc = b.st[0], nx = b.st[1];
;         if (nloc == 0u) { xcd_barrier_complete(bar, b.x, nloc, nx, b.np); b.st[0] = nloc; b.st[1] = nx; }
;         const unsigned old = xb_add(&bar[XB_XSUB(b.x)], 1u);
.LBB0_141:
	s_setprio 0
	s_cmp_gt_i32 s35, 1
	s_cselect_b64 s[52:53], -1, 0
	s_and_b64 s[0:1], s[60:61], s[52:53]
	s_andn2_b64 vcc, exec, s[0:1]
	s_cbranch_vccnz .LBB0_195
	v_mov_b32_e32 v0, 0
	s_waitcnt vmcnt(0)
	s_waitcnt lgkmcnt(0)
	s_barrier
	s_nop 0
	v_mbcnt_lo_u32_b32 v0, -1, v0
	v_mbcnt_hi_u32_b32 v0, -1, v0
	v_or_b32_e32 v0, s33, v0
	v_cmp_eq_u32_e32 vcc, 0, v0
	s_and_saveexec_b64 s[0:1], vcc
	s_cbranch_execz .LBB0_194
	s_add_i32 s2, 0, 0x27f60
	v_mov_b32_e32 v0, s2
	s_waitcnt vmcnt(0) expcnt(0) lgkmcnt(0)
	ds_read_b32 v2, v0
	s_add_i32 s2, 0, 0x27f64
	v_mov_b32_e32 v0, s2
	ds_read_b32 v0, v0
	s_waitcnt lgkmcnt(1)
	v_cmp_ne_u32_e32 vcc, 0, v2
	s_cbranch_vccnz .LBB0_158
	v_readlane_b32 s16, v254, 43
	v_readlane_b32 s18, v254, 45
	v_readlane_b32 s19, v254, 46
	s_add_u32 s2, s18, 0x4200
	s_addc_u32 s3, s19, 0
	s_add_u32 s14, s18, 0x4400
	s_addc_u32 s15, s19, 0
	s_add_u32 s20, s18, 0x4500
	s_addc_u32 s21, s19, 0
	s_add_u32 s22, s18, 0x4600
	s_addc_u32 s23, s19, 0
	s_add_u32 s60, s18, 0x4700
	s_addc_u32 s61, s19, 0
	s_add_u32 s62, s18, 0x4800
	s_addc_u32 s63, s19, 0
	s_add_u32 s64, s18, 0x4900
	s_addc_u32 s65, s19, 0
	s_add_u32 s66, s18, 0x4a00
	s_addc_u32 s67, s19, 0
	s_add_u32 s68, s18, 0x4b00
	s_addc_u32 s69, s19, 0
	s_add_u32 s70, s18, 0x4c00
	s_addc_u32 s71, s19, 0
	s_add_u32 s72, s18, 0x4d00
	s_addc_u32 s73, s19, 0
	s_add_u32 s74, s18, 0x4e00
	s_addc_u32 s75, s19, 0
	s_add_u32 s76, s18, 0x4f00
	s_addc_u32 s77, s19, 0
	s_add_u32 s78, s18, 0x5000
	s_addc_u32 s79, s19, 0
	s_add_u32 s80, s18, 0x5100
	s_addc_u32 s81, s19, 0
	s_add_u32 s82, s18, 0x5200
	s_addc_u32 s83, s19, 0
	s_add_u32 s84, s18, 0x5300
	s_addc_u32 s85, s19, 0
	s_mov_b32 s8, 1
	v_mov_b32_e32 v16, 0
	v_readlane_b32 s17, v254, 44
	s_branch .LBB0_146

; __device__ __forceinline__ int tid_now(int wave_s) { unsigned z = 0u; asm volatile("" : "+v"(z)); return (wave_s << 6) | (int)__builtin_amdgcn_mbcnt_hi(~0u, __builtin_amdgcn_mbcnt_lo(~0u, z)); }
; __device__ __forceinline__ unsigned xb_add(unsigned* p, unsigned v) { return __hip_atomic_fetch_add(p, v, __ATOMIC_RELAXED, __HIP_MEMORY_SCOPE_AGENT); }
; __device__ __forceinline__ void xcd_barrier(const XcdBarrier& b) {
;     asm volatile("s_waitcnt vmcnt(0)" ::: "memory");
;     __syncthreads();
;     if (tid_now(b.w) == 0) {
;         unsigned* bar = b.bar;
;         __builtin_amdgcn_s_waitcnt(0);
;         unsigned nloc = b.st[0], nx = b.st[1];
;         if (nloc == 0u) { xcd_barrier_complete(bar, b.x, nloc, nx, b.np); b.st[0] = nloc; b.st[1] = nx; }
;         const unsigned old = xb_add(&bar[XB_XSUB(b.x)], 1u);
.LBB0_709:
	s_setprio 0
	s_cmp_gt_i32 s35, 2
	s_cselect_b64 s[0:1], -1, 0
	s_and_b64 s[2:3], s[22:23], s[0:1]
	s_andn2_b64 vcc, exec, s[2:3]
	s_cbranch_vccnz .LBB0_763
	s_waitcnt vmcnt(0)
	v_mov_b32_e32 v0, 0
	s_waitcnt vmcnt(0)
	s_waitcnt lgkmcnt(0)
	s_barrier
	s_nop 0
	v_mbcnt_lo_u32_b32 v0, -1, v0
	v_mbcnt_hi_u32_b32 v0, -1, v0
	v_or_b32_e32 v0, s33, v0
	v_cmp_eq_u32_e32 vcc, 0, v0
	s_and_saveexec_b64 s[2:3], vcc
	s_cbranch_execz .LBB0_762
	s_add_i32 s4, 0, 0x27f68
	v_mov_b32_e32 v0, s4
	s_waitcnt vmcnt(0) expcnt(0) lgkmcnt(0)
	ds_read_b32 v2, v0
	s_add_i32 s4, 0, 0x27f6c
	v_mov_b32_e32 v0, s4
	ds_read_b32 v0, v0
	s_waitcnt lgkmcnt(1)
	v_cmp_ne_u32_e32 vcc, 0, v2
	s_cbranch_vccnz .LBB0_726
	s_add_u32 s4, s10, 0x1000
	s_addc_u32 s5, s11, 0
	s_add_u32 s22, s10, 0x1100
	s_addc_u32 s23, s11, 0
	s_add_u32 s60, s10, 0x1200
	s_addc_u32 s61, s11, 0
	s_add_u32 s62, s10, 0x1300
	s_addc_u32 s63, s11, 0
	s_mov_b32 s6, 1
	v_mov_b32_e32 v16, 0
	s_branch .LBB0_714

; #define PG8_STAGE(bufoff, gbase, voff) do { _Pragma("unroll") for (int _i = 0; _i < 2; ++_i) \
;         __builtin_amdgcn_global_load_lds((const unsigned*)((const char*)(gbase) + (voff)[_i]), (PG8_LAS unsigned*)(lds + (bufoff) + ldsw + _i * 8192), 16, 0, 0); } while (0)
; #define PG8_WAIT_V(n) asm volatile("s_waitcnt vmcnt(" #n ")" ::: "memory")
; #define PG8_BAR __builtin_amdgcn_s_barrier()
; template <class Epi, class Sched, bool ALIGN_EPI = false, bool SP2 = false, bool A_TILED = false>
; __device__ __forceinline__ void gemm_phase(PG8_LAS unsigned char* lds, const Gemm g, const Sched& S, const Epi& E, const int wave_s) {
;     ...
;     for (int i = 0; i < 2; ++i) { int R, C; stage_rc(tid * 16 + i * 8192, R, C); const int Rb = Epi::PERM ? ((R & ~31) + perm32(R & 31)) : R;
;         voffA[i] = A_TILED ? (unsigned)(tid * 16 + i * 8192) : (unsigned)(R * K + C) * 2u; voffB[i] = (unsigned)(Rb * K + C) * 2u; }
;     const size_t kstep = (size_t)(BK * 2);
;     const size_t hstep = (size_t)HALF * K * 2;
;     const size_t tstep = 2 * hstep;
;     const size_t kstepA = A_TILED ? (size_t)32768 : kstep, hstepA = A_TILED ? (size_t)16384 : hstep, tstepA = A_TILED ? (size_t)nt * 32768 : tstep;
;     const unsigned ldsw = (unsigned)wid * 1024u;
;     const int aoff = lds_byte(wr * 64 + fr, fq * 8), boff = lds_byte(wc * 32 + fr, fq * 8);
;     ...
;     if constexpr (SP2) {
;         PG8_STAGE(PG8_SB(0, 0), cB, voffB); PG8_STAGE(PG8_SB(0, 1), cB + hstep, voffB); PG8_STAGE(PG8_SA(0, 0), cA, voffA); PG8_STAGE(PG8_SA(0, 1), cA + hstepA, voffA);
;         if (wr == 1) PG8_BAR;
;         PG8_WAIT_V(2); PG8_BAR;
;         PG8_STAGE(PG8_SB(1, 0), cB + kstep, voffB); PG8_STAGE(PG8_SA(1, 0), cA + kstepA, voffA); PG8_STAGE(PG8_SB(1, 1), cB + hstep + kstep, voffB);
;         PG8_WAIT_V(6); PG8_BAR;
.LBB0_771:
	s_ashr_i32 s40, s86, 31
	s_add_u32 s0, s0, s29
	s_addc_u32 s1, s1, 0
	s_add_u32 s60, s0, 0x22600000
	s_addc_u32 s61, s1, 0
	s_lshl_b32 s0, s42, 5
	s_mov_b64 s[62:63], 0x80
	s_and_b32 s42, s0, 0x60
	s_add_i32 m0, s23, 0x18000
	v_lshl_add_u64 v[6:7], v[6:7], 0, s[62:63]
	s_lshl_b32 s41, s43, 6
	s_lshl_b32 s46, s43, 13
	s_lshl_b32 s47, s42, 7
	s_waitcnt vmcnt(2)
	s_barrier
	global_load_lds_dwordx4 v[6:7], off
	v_lshl_add_u64 v[4:5], v[4:5], 0, s[62:63]
	s_add_i32 m0, s23, 0x1a000
	s_add_i32 s43, s23, 0x8000
	s_add_i32 s44, s23, 0xa000
	global_load_lds_dwordx4 v[4:5], off
	v_lshl_add_u64 v[0:1], v[0:1], 0, s[62:63]
	s_mov_b32 m0, s43
	s_add_u32 s0, s80, 0x80080
	global_load_lds_dwordx4 v[0:1], off
	v_lshl_add_u64 v[0:1], v[2:3], 0, s[62:63]
	s_mov_b32 m0, s44
	s_addc_u32 s1, s81, 0
	global_load_lds_dwordx4 v[0:1], off
	s_add_i32 m0, s23, 0x1c000
	v_lshl_add_u64 v[0:1], s[0:1], 0, v[128:129]
	global_load_lds_dwordx4 v128, s[0:1]
	v_lshl_add_u64 v[0:1], s[0:1], 0, v[130:131]
	s_add_i32 m0, s23, 0x1e000
	s_movk_i32 s0, 0x3c0
	global_load_lds_dwordx4 v[0:1], off
	v_and_b32_e32 v0, 48, v8
	v_lshlrev_b32_e32 v1, 6, v8
	v_and_or_b32 v0, v1, s0, v0
	v_lshlrev_b32_e32 v1, 2, v8
	v_and_b32_e32 v1, 32, v1
	v_bitop3_b32 v2, v0, s46, v1 bitop3:0xde
	v_bitop3_b32 v148, s47, v0, v1 bitop3:0xf6
	v_lshlrev_b32_e32 v0, 15, v9
	v_and_b32_e32 v0, 0xffff0000, v0
	v_lshl_add_u32 v0, v10, 12, v0
	v_and_b32_e32 v1, 1, v9
	v_lshl_or_b32 v0, v1, 6, v0
	v_lshl_add_u32 v136, v11, 1, v0
	v_lshlrev_b32_e32 v0, 15, v13
	v_and_b32_e32 v0, 0xffff0000, v0
	s_waitcnt vmcnt(6)
	s_mov_b32 s98, 0
	s_bitcmp1_b32 s33, 8
	s_cbranch_scc1 .Lsp_1
	s_setprio 1
.Lsp_1:
	s_cmpk_lt_u32 s45, 0x100
	v_lshl_add_u32 v0, v12, 12, v0
	v_and_b32_e32 v1, 1, v13
	s_sext_i32_i16 s50, s64
	s_cselect_b64 s[64:65], -1, 0
	v_mov_b32_e32 v137, 0
	v_lshl_or_b32 v0, v1, 6, v0
	s_add_i32 s45, 0, 0x10000
	s_add_i32 s46, 0, 0x14000
	v_lshl_add_u32 v138, v14, 1, v0
	v_mov_b32_e32 v139, v137
	s_mov_b64 s[66:67], 0x180
	v_add_u32_e32 v149, s45, v148
	v_add_u32_e32 v150, s46, v148
	v_add_u32_e32 v151, 0, v2
	s_mov_b64 s[68:69], 0x100
	s_movk_i32 s47, 0x3000
	s_add_i32 s48, s23, 0xc000
	s_add_i32 s49, s23, 0xe000
	s_barrier
	s_branch .LBB0_774

; template <class Epi, class Sched, bool ALIGN_EPI = false, bool SP2 = false, bool A_TILED = false>
; __device__ __forceinline__ void gemm_phase(PG8_LAS unsigned char* lds, const Gemm g, const Sched& S, const Epi& E, const int wave_s) {
;     ...
;         constexpr bool PEEL = SP2 && !Epi::AFTER_DRAIN;
;         if constexpr (PEEL) {
;             const char* a1 = cA + kstepA; const char* a2 = cA + 2 * kstepA; const char* b2 = cB + 2 * kstep; const char* a3 = a2 + kstepA; const char* b3 = b2 + kstep;
;             PG8_ITER(PG8_MMAZ)
.Lpw_1:
	s_barrier
	v_mfma_f32_16x16x32_bf16 v[88:91], v[0:3], v[56:59], 0
	v_mfma_f32_16x16x32_bf16 v[64:67], v[0:3], v[32:35], 0
	v_mfma_f32_16x16x32_bf16 v[68:71], v[8:11], v[32:35], 0
	v_mfma_f32_16x16x32_bf16 v[72:75], v[0:3], v[40:43], 0
	v_mfma_f32_16x16x32_bf16 v[76:79], v[8:11], v[40:43], 0
	v_mfma_f32_16x16x32_bf16 v[80:83], v[0:3], v[48:51], 0
	v_mfma_f32_16x16x32_bf16 v[84:87], v[8:11], v[48:51], 0
	v_mfma_f32_16x16x32_bf16 v[92:95], v[4:7], v[60:63], v[88:91]
	v_mfma_f32_16x16x32_bf16 v[88:91], v[8:11], v[56:59], 0
	v_mfma_f32_16x16x32_bf16 v[64:67], v[4:7], v[36:39], v[64:67]
	v_mfma_f32_16x16x32_bf16 v[68:71], v[12:15], v[36:39], v[68:71]
	v_mfma_f32_16x16x32_bf16 v[72:75], v[4:7], v[44:47], v[72:75]
	v_mfma_f32_16x16x32_bf16 v[76:79], v[12:15], v[44:47], v[76:79]
	v_mfma_f32_16x16x32_bf16 v[80:83], v[4:7], v[52:55], v[80:83]
	v_mfma_f32_16x16x32_bf16 v[84:87], v[12:15], v[52:55], v[84:87]
	v_mfma_f32_16x16x32_bf16 v[100:103], v[12:15], v[60:63], v[88:91]
	v_mfma_f32_16x16x32_bf16 v[88:91], v[16:19], v[32:35], 0
	v_mfma_f32_16x16x32_bf16 v[32:35], v[24:27], v[32:35], 0
	v_mfma_f32_16x16x32_bf16 v[108:111], v[20:23], v[36:39], v[88:91]
	v_mfma_f32_16x16x32_bf16 v[32:35], v[28:31], v[36:39], v[32:35]
	v_mfma_f32_16x16x32_bf16 v[36:39], v[16:19], v[40:43], 0
	v_mfma_f32_16x16x32_bf16 v[40:43], v[24:27], v[40:43], 0
	v_mfma_f32_16x16x32_bf16 v[36:39], v[20:23], v[44:47], v[36:39]
	v_mfma_f32_16x16x32_bf16 v[40:43], v[28:31], v[44:47], v[40:43]
	v_mfma_f32_16x16x32_bf16 v[44:47], v[16:19], v[48:51], 0
	v_mfma_f32_16x16x32_bf16 v[48:51], v[24:27], v[48:51], 0
	v_mfma_f32_16x16x32_bf16 v[44:47], v[20:23], v[52:55], v[44:47]
	v_mfma_f32_16x16x32_bf16 v[52:55], v[28:31], v[52:55], v[48:51]
	v_mfma_f32_16x16x32_bf16 v[48:51], v[16:19], v[56:59], 0
	v_mfma_f32_16x16x32_bf16 v[152:155], v[20:23], v[60:63], v[48:51]
	v_mfma_f32_16x16x32_bf16 v[48:51], v[24:27], v[56:59], 0
	v_mfma_f32_16x16x32_bf16 v[156:159], v[28:31], v[60:63], v[48:51]
	s_barrier
	s_add_i32 s55, s45, s15
	v_lshl_add_u64 v[146:147], s[80:81], 0, v[128:129]
	s_add_i32 s56, s55, 0x2000
	v_lshl_add_u64 v[120:121], v[146:147], 0, s[68:69]
	s_mov_b32 m0, s55
	v_lshl_add_u64 v[252:253], s[80:81], 0, v[130:131]
	s_add_u32 s58, s80, 0x80100
	ds_read_b128 v[48:51], v151 offset:16384
	ds_read_b128 v[56:59], v151 offset:17408
	ds_read_b128 v[60:63], v151 offset:18432
	ds_read_b128 v[88:91], v151 offset:19456
	ds_read_b128 v[96:99], v151 offset:20480
	ds_read_b128 v[104:107], v151 offset:21504
	ds_read_b128 v[112:115], v151 offset:22528
	ds_read_b128 v[116:119], v151 offset:23552
	global_load_lds_dwordx4 v[120:121], off
	v_lshl_add_u64 v[120:121], v[252:253], 0, s[68:69]
	s_mov_b32 m0, s56
	s_addc_u32 s59, s81, 0
	s_add_i32 s57, s46, s15
	global_load_lds_dwordx4 v[120:121], off
	v_lshl_add_u64 v[120:121], s[58:59], 0, v[128:129]
	s_mov_b32 m0, s57
	v_lshl_add_u64 v[140:141], s[82:83], 0, v[134:135]
	global_load_lds_dwordx4 v128, s[58:59]
	v_lshl_add_u64 v[120:121], s[58:59], 0, v[130:131]
	s_add_i32 s58, s57, 0x2000
	s_mov_b32 m0, s58
	v_lshl_add_u64 v[142:143], s[82:83], 0, v[132:133]
	global_load_lds_dwordx4 v[120:121], off
	v_lshl_add_u64 v[120:121], v[140:141], 0, s[68:69]
	s_mov_b32 m0, s23
	s_nop 0
	global_load_lds_dwordx4 v[120:121], off
	v_lshl_add_u64 v[120:121], v[142:143], 0, s[68:69]
	s_mov_b32 m0, s36
	s_nop 0
	global_load_lds_dwordx4 v[120:121], off
	s_waitcnt vmcnt(24) lgkmcnt(0)
	s_cmp_lg_u32 s98, 0
	s_cbranch_scc1 .Lpw_2
	s_waitcnt vmcnt(8)
.Lpw_2:
	s_barrier
	v_mfma_f32_16x16x32_bf16 v[120:123], v[0:3], v[48:51], 0
	v_mfma_f32_16x16x32_bf16 v[160:163], v[4:7], v[56:59], v[120:123]
	v_mfma_f32_16x16x32_bf16 v[120:123], v[8:11], v[48:51], 0
	v_mfma_f32_16x16x32_bf16 v[164:167], v[12:15], v[56:59], v[120:123]
	v_mfma_f32_16x16x32_bf16 v[120:123], v[0:3], v[60:63], 0
	v_mfma_f32_16x16x32_bf16 v[168:171], v[4:7], v[88:91], v[120:123]
	v_mfma_f32_16x16x32_bf16 v[120:123], v[8:11], v[60:63], 0
	v_mfma_f32_16x16x32_bf16 v[172:175], v[12:15], v[88:91], v[120:123]
	v_mfma_f32_16x16x32_bf16 v[120:123], v[0:3], v[96:99], 0
	v_mfma_f32_16x16x32_bf16 v[0:3], v[0:3], v[112:115], 0
	v_mfma_f32_16x16x32_bf16 v[176:179], v[4:7], v[104:107], v[120:123]
	v_mfma_f32_16x16x32_bf16 v[0:3], v[4:7], v[116:119], v[0:3]
	v_mfma_f32_16x16x32_bf16 v[4:7], v[8:11], v[112:115], 0
	v_mfma_f32_16x16x32_bf16 v[120:123], v[8:11], v[96:99], 0
	v_mfma_f32_16x16x32_bf16 v[4:7], v[12:15], v[116:119], v[4:7]
	v_mfma_f32_16x16x32_bf16 v[180:183], v[12:15], v[104:107], v[120:123]
	v_mfma_f32_16x16x32_bf16 v[8:11], v[16:19], v[48:51], 0
	v_mfma_f32_16x16x32_bf16 v[12:15], v[20:23], v[56:59], v[8:11]
	v_mfma_f32_16x16x32_bf16 v[8:11], v[24:27], v[48:51], 0
	v_mfma_f32_16x16x32_bf16 v[184:187], v[28:31], v[56:59], v[8:11]
	v_mfma_f32_16x16x32_bf16 v[8:11], v[16:19], v[60:63], 0
	v_mfma_f32_16x16x32_bf16 v[188:191], v[20:23], v[88:91], v[8:11]
	v_mfma_f32_16x16x32_bf16 v[8:11], v[24:27], v[60:63], 0
	v_mfma_f32_16x16x32_bf16 v[192:195], v[28:31], v[88:91], v[8:11]
	v_mfma_f32_16x16x32_bf16 v[8:11], v[16:19], v[96:99], 0
	v_mfma_f32_16x16x32_bf16 v[196:199], v[20:23], v[104:107], v[8:11]
	v_mfma_f32_16x16x32_bf16 v[8:11], v[24:27], v[96:99], 0
	v_mfma_f32_16x16x32_bf16 v[200:203], v[28:31], v[104:107], v[8:11]
	v_mfma_f32_16x16x32_bf16 v[8:11], v[16:19], v[112:115], 0
	v_mfma_f32_16x16x32_bf16 v[204:207], v[20:23], v[116:119], v[8:11]
	v_mfma_f32_16x16x32_bf16 v[8:11], v[24:27], v[112:115], 0
	v_mfma_f32_16x16x32_bf16 v[208:211], v[28:31], v[116:119], v[8:11]
	s_barrier
; template <class Epi, class Sched, bool ALIGN_EPI = false, bool SP2 = false, bool A_TILED = false>
; __device__ __forceinline__ void gemm_phase(PG8_LAS unsigned char* lds, const Gemm g, const Sched& S, const Epi& E, const int wave_s) {
;     ...
;         constexpr bool PEEL = SP2 && !Epi::AFTER_DRAIN;
;         if constexpr (PEEL) {
;             const char* a1 = cA + kstepA; const char* a2 = cA + 2 * kstepA; const char* b2 = cB + 2 * kstep; const char* a3 = a2 + kstepA; const char* b3 = b2 + kstep;
;             PG8_ITER(PG8_MMAZ)
	s_add_i32 s59, 0, 0x18000
	s_add_i32 s73, 0, 0x1c000
	v_add_u32_e32 v144, s59, v148
	v_add_u32_e32 v145, s73, v148
	s_nop 0
	ds_read_b128 v[8:11], v144
	ds_read_b128 v[20:23], v144 offset:1024
	ds_read_b128 v[28:31], v144 offset:2048
	ds_read_b128 v[212:215], v144 offset:3072
	ds_read_b128 v[216:219], v145
	ds_read_b128 v[220:223], v145 offset:1024
	ds_read_b128 v[224:227], v145 offset:2048
	ds_read_b128 v[228:231], v145 offset:3072
	s_add_u32 s84, s82, 0x80100
	s_addc_u32 s85, s83, 0
	s_mov_b32 m0, s37
	v_lshl_add_u64 v[48:49], s[84:85], 0, v[134:135]
	ds_read_b128 v[16:19], v151 offset:32768
	ds_read_b128 v[24:27], v151 offset:33792
	ds_read_b128 v[60:63], v151 offset:34816
	ds_read_b128 v[232:235], v151 offset:35840
	ds_read_b128 v[236:239], v151 offset:36864
	ds_read_b128 v[240:243], v151 offset:37888
	ds_read_b128 v[244:247], v151 offset:38912
	ds_read_b128 v[248:251], v151 offset:39936
	global_load_lds_dwordx4 v134, s[84:85]
	v_lshl_add_u64 v[48:49], s[84:85], 0, v[132:133]
	s_mov_b32 m0, s38
	s_nop 0
	global_load_lds_dwordx4 v132, s[84:85]
	s_waitcnt vmcnt(8) lgkmcnt(0)
	s_barrier
	v_mfma_f32_16x16x32_bf16 v[48:51], v[8:11], v[16:19], v[64:67]
	v_mfma_f32_16x16x32_bf16 v[120:123], v[20:23], v[24:27], v[48:51]
	v_mfma_f32_16x16x32_bf16 v[48:51], v[28:31], v[16:19], v[68:71]
	v_mfma_f32_16x16x32_bf16 v[112:115], v[212:215], v[24:27], v[48:51]
	v_mfma_f32_16x16x32_bf16 v[48:51], v[8:11], v[60:63], v[72:75]
	v_mfma_f32_16x16x32_bf16 v[104:107], v[20:23], v[232:235], v[48:51]
	v_mfma_f32_16x16x32_bf16 v[48:51], v[28:31], v[60:63], v[76:79]
	v_mfma_f32_16x16x32_bf16 v[96:99], v[212:215], v[232:235], v[48:51]
	v_mfma_f32_16x16x32_bf16 v[48:51], v[8:11], v[236:239], v[80:83]
	v_mfma_f32_16x16x32_bf16 v[88:91], v[20:23], v[240:243], v[48:51]
	v_mfma_f32_16x16x32_bf16 v[48:51], v[28:31], v[236:239], v[84:87]
	v_mfma_f32_16x16x32_bf16 v[80:83], v[212:215], v[240:243], v[48:51]
	v_mfma_f32_16x16x32_bf16 v[48:51], v[8:11], v[244:247], v[92:95]
	v_mfma_f32_16x16x32_bf16 v[56:59], v[20:23], v[248:251], v[48:51]
	v_mfma_f32_16x16x32_bf16 v[48:51], v[28:31], v[244:247], v[100:103]
	v_mfma_f32_16x16x32_bf16 v[48:51], v[212:215], v[248:251], v[48:51]
	v_mfma_f32_16x16x32_bf16 v[64:67], v[216:219], v[16:19], v[108:111]
	v_mfma_f32_16x16x32_bf16 v[16:19], v[224:227], v[16:19], v[32:35]
	v_mfma_f32_16x16x32_bf16 v[116:119], v[228:231], v[24:27], v[16:19]
	v_mfma_f32_16x16x32_bf16 v[16:19], v[216:219], v[60:63], v[36:39]
	v_mfma_f32_16x16x32_bf16 v[108:111], v[220:223], v[232:235], v[16:19]
	v_mfma_f32_16x16x32_bf16 v[16:19], v[224:227], v[60:63], v[40:43]
	v_mfma_f32_16x16x32_bf16 v[100:103], v[228:231], v[232:235], v[16:19]
	v_mfma_f32_16x16x32_bf16 v[16:19], v[216:219], v[236:239], v[44:47]
	v_mfma_f32_16x16x32_bf16 v[92:95], v[220:223], v[240:243], v[16:19]
	v_mfma_f32_16x16x32_bf16 v[16:19], v[224:227], v[236:239], v[52:55]
	v_mfma_f32_16x16x32_bf16 v[84:87], v[228:231], v[240:243], v[16:19]
	v_mfma_f32_16x16x32_bf16 v[16:19], v[216:219], v[244:247], v[152:155]
	v_mfma_f32_16x16x32_bf16 v[60:63], v[220:223], v[248:251], v[16:19]
	v_mfma_f32_16x16x32_bf16 v[16:19], v[224:227], v[244:247], v[156:159]
	v_mfma_f32_16x16x32_bf16 v[124:127], v[220:223], v[24:27], v[64:67]
	v_mfma_f32_16x16x32_bf16 v[52:55], v[228:231], v[248:251], v[16:19]
	s_barrier
	s_add_i32 s59, s59, s15
	s_add_i32 s71, s59, 0x2000
	s_nop 1
	v_lshl_add_u64 v[16:17], v[146:147], 0, s[66:67]
	s_mov_b32 m0, s59
	s_add_u32 s84, s80, 0x80180
	ds_read_b128 v[36:39], v151 offset:49152
	ds_read_b128 v[44:47], v151 offset:50176
	ds_read_b128 v[152:155], v151 offset:51200
	ds_read_b128 v[156:159], v151 offset:52224
	ds_read_b128 v[232:235], v151 offset:53248
	ds_read_b128 v[236:239], v151 offset:54272
	ds_read_b128 v[240:243], v151 offset:55296
	ds_read_b128 v[244:247], v151 offset:56320
	global_load_lds_dwordx4 v[16:17], off
	v_lshl_add_u64 v[16:17], v[252:253], 0, s[66:67]
	s_mov_b32 m0, s71
	s_addc_u32 s85, s81, 0
	s_add_i32 s73, s73, s15
	global_load_lds_dwordx4 v[16:17], off
	v_lshl_add_u64 v[16:17], s[84:85], 0, v[128:129]
	s_mov_b32 m0, s73
	s_add_i32 s79, s73, 0x2000
	global_load_lds_dwordx4 v128, s[84:85]
	v_lshl_add_u64 v[16:17], s[84:85], 0, v[130:131]
	s_mov_b32 m0, s79
	s_nop 0
	global_load_lds_dwordx4 v130, s[84:85]
	v_lshl_add_u64 v[16:17], v[140:141], 0, s[66:67]
	s_mov_b32 m0, s43
	s_nop 0
	global_load_lds_dwordx4 v[16:17], off
	v_lshl_add_u64 v[16:17], v[142:143], 0, s[66:67]
	s_mov_b32 m0, s44
	s_nop 0
	global_load_lds_dwordx4 v[16:17], off
	s_waitcnt vmcnt(8) lgkmcnt(0)
	s_barrier
	v_mfma_f32_16x16x32_bf16 v[16:19], v[8:11], v[36:39], v[160:163]
	v_mfma_f32_16x16x32_bf16 v[72:75], v[20:23], v[44:47], v[16:19]
	v_mfma_f32_16x16x32_bf16 v[16:19], v[28:31], v[36:39], v[164:167]
	v_mfma_f32_16x16x32_bf16 v[64:67], v[212:215], v[44:47], v[16:19]
	v_mfma_f32_16x16x32_bf16 v[16:19], v[8:11], v[152:155], v[168:171]
	v_mfma_f32_16x16x32_bf16 v[40:43], v[20:23], v[156:159], v[16:19]
	v_mfma_f32_16x16x32_bf16 v[16:19], v[28:31], v[152:155], v[172:175]
	v_mfma_f32_16x16x32_bf16 v[32:35], v[212:215], v[156:159], v[16:19]
	v_mfma_f32_16x16x32_bf16 v[16:19], v[8:11], v[232:235], v[176:179]
	v_mfma_f32_16x16x32_bf16 v[0:3], v[8:11], v[240:243], v[0:3]
	v_mfma_f32_16x16x32_bf16 v[24:27], v[20:23], v[236:239], v[16:19]
	v_mfma_f32_16x16x32_bf16 v[16:19], v[28:31], v[232:235], v[180:183]
	v_mfma_f32_16x16x32_bf16 v[8:11], v[20:23], v[244:247], v[0:3]
	v_mfma_f32_16x16x32_bf16 v[0:3], v[28:31], v[240:243], v[4:7]
	v_mfma_f32_16x16x32_bf16 v[16:19], v[212:215], v[236:239], v[16:19]
	v_mfma_f32_16x16x32_bf16 v[0:3], v[212:215], v[244:247], v[0:3]
	v_mfma_f32_16x16x32_bf16 v[4:7], v[216:219], v[36:39], v[12:15]
	v_mfma_f32_16x16x32_bf16 v[76:79], v[220:223], v[44:47], v[4:7]
	v_mfma_f32_16x16x32_bf16 v[4:7], v[224:227], v[36:39], v[184:187]
	v_mfma_f32_16x16x32_bf16 v[68:71], v[228:231], v[44:47], v[4:7]
	v_mfma_f32_16x16x32_bf16 v[4:7], v[216:219], v[152:155], v[188:191]
	v_mfma_f32_16x16x32_bf16 v[44:47], v[220:223], v[156:159], v[4:7]
	v_mfma_f32_16x16x32_bf16 v[4:7], v[224:227], v[152:155], v[192:195]
	v_mfma_f32_16x16x32_bf16 v[36:39], v[228:231], v[156:159], v[4:7]
	v_mfma_f32_16x16x32_bf16 v[4:7], v[216:219], v[232:235], v[196:199]
	v_mfma_f32_16x16x32_bf16 v[28:31], v[220:223], v[236:239], v[4:7]
	v_mfma_f32_16x16x32_bf16 v[4:7], v[224:227], v[232:235], v[200:203]
	v_mfma_f32_16x16x32_bf16 v[20:23], v[228:231], v[236:239], v[4:7]
	v_mfma_f32_16x16x32_bf16 v[4:7], v[216:219], v[240:243], v[204:207]
	v_mfma_f32_16x16x32_bf16 v[12:15], v[220:223], v[244:247], v[4:7]
	v_mfma_f32_16x16x32_bf16 v[4:7], v[224:227], v[240:243], v[208:211]
	v_mfma_f32_16x16x32_bf16 v[4:7], v[228:231], v[244:247], v[4:7]
	s_barrier
	s_add_u32 s88, s80, 0x200
	s_addc_u32 s89, s81, 0
	s_add_u32 s80, s82, 0x80180
	s_addc_u32 s81, s83, 0
	s_mov_b32 s90, 0
; #define PG8_MMA(ai, bj, At, Bt) do { __builtin_amdgcn_s_setprio(1); _Pragma("unroll") for (int m = 0; m < 4; ++m) _Pragma("unroll") for (int n = 0; n < 2; ++n) _Pragma("unroll") for (int k = 0; k < 2; ++k) \
;         acc[ai][bj][m][n] = __builtin_amdgcn_mfma_f32_16x16x32_bf16(Bt[n][k], At[m][k], acc[ai][bj][m][n], 0, 0, 0); __builtin_amdgcn_s_setprio(0); } while (0)
; template <class Epi, class Sched, bool ALIGN_EPI = false, bool SP2 = false, bool A_TILED = false>
; __device__ __forceinline__ void gemm_phase(PG8_LAS unsigned char* lds, const Gemm g, const Sched& S, const Epi& E, const int wave_s) {
;     ...
;         for (int t = PEEL ? 2 : 0; t < nt; t += 2) {
;             const bool last = (t == nt - 2);
;             const char* a1 = cA + (size_t)(t + 1) * kstepA;
;             const char* a2 = last ? nA : cA + (size_t)(t + 2) * kstepA; const char* b2 = last ? nB : cB + (size_t)(t + 2) * kstep;
;             const char* a3 = a2 + kstepA; const char* b3 = b2 + kstep;
;             if (last && has_next) S.a_ready(nxt);
;             if constexpr (SP2) {
;             PG8_ITER(PG8_MMA)
.LBB0_777:
	ds_read_b128 v[152:155], v149
	ds_read_b128 v[156:159], v149 offset:1024
	ds_read_b128 v[160:163], v149 offset:2048
	ds_read_b128 v[164:167], v149 offset:3072
	ds_read_b128 v[168:171], v150
	ds_read_b128 v[172:175], v150 offset:1024
	ds_read_b128 v[176:179], v150 offset:2048
	ds_read_b128 v[180:183], v150 offset:3072
	s_add_u32 s82, s80, 0xfff80080
	s_addc_u32 s83, s81, -1
	s_cmp_eq_u32 s90, 28
	s_cselect_b32 s85, s51, s83
	s_cselect_b32 s84, s52, s82
	s_cselect_b32 s83, s53, s89
	s_cselect_b32 s82, s54, s88
	s_mov_b32 m0, s48
	v_lshl_add_u64 v[140:141], s[80:81], 0, v[138:139]
	ds_read_b128 v[184:187], v151
	ds_read_b128 v[188:191], v151 offset:1024
	ds_read_b128 v[192:195], v151 offset:2048
	ds_read_b128 v[196:199], v151 offset:3072
	ds_read_b128 v[200:203], v151 offset:4096
	ds_read_b128 v[204:207], v151 offset:5120
	ds_read_b128 v[208:211], v151 offset:6144
	ds_read_b128 v[212:215], v151 offset:7168
	global_load_lds_dwordx4 v138, s[80:81]
	v_lshl_add_u64 v[140:141], s[80:81], 0, v[136:137]
	s_mov_b32 m0, s49
	s_nop 0
	global_load_lds_dwordx4 v136, s[80:81]
	s_waitcnt vmcnt(8) lgkmcnt(0)
	s_barrier
	v_mfma_f32_16x16x32_bf16 v[120:123], v[152:155], v[184:187], v[120:123]
	v_mfma_f32_16x16x32_bf16 v[112:115], v[160:163], v[184:187], v[112:115]
	v_mfma_f32_16x16x32_bf16 v[104:107], v[152:155], v[192:195], v[104:107]
	v_mfma_f32_16x16x32_bf16 v[96:99], v[160:163], v[192:195], v[96:99]
	v_mfma_f32_16x16x32_bf16 v[88:91], v[152:155], v[200:203], v[88:91]
	v_mfma_f32_16x16x32_bf16 v[80:83], v[160:163], v[200:203], v[80:83]
	v_mfma_f32_16x16x32_bf16 v[56:59], v[152:155], v[208:211], v[56:59]
	v_mfma_f32_16x16x32_bf16 v[48:51], v[160:163], v[208:211], v[48:51]
	v_mfma_f32_16x16x32_bf16 v[120:123], v[156:159], v[188:191], v[120:123]
	v_mfma_f32_16x16x32_bf16 v[112:115], v[164:167], v[188:191], v[112:115]
	v_mfma_f32_16x16x32_bf16 v[104:107], v[156:159], v[196:199], v[104:107]
	v_mfma_f32_16x16x32_bf16 v[96:99], v[164:167], v[196:199], v[96:99]
	v_mfma_f32_16x16x32_bf16 v[88:91], v[156:159], v[204:207], v[88:91]
	v_mfma_f32_16x16x32_bf16 v[80:83], v[164:167], v[204:207], v[80:83]
	v_mfma_f32_16x16x32_bf16 v[56:59], v[156:159], v[212:215], v[56:59]
	v_mfma_f32_16x16x32_bf16 v[48:51], v[164:167], v[212:215], v[48:51]
	v_mfma_f32_16x16x32_bf16 v[124:127], v[168:171], v[184:187], v[124:127]
	v_mfma_f32_16x16x32_bf16 v[116:119], v[176:179], v[184:187], v[116:119]
	v_mfma_f32_16x16x32_bf16 v[108:111], v[168:171], v[192:195], v[108:111]
	v_mfma_f32_16x16x32_bf16 v[100:103], v[176:179], v[192:195], v[100:103]
	v_mfma_f32_16x16x32_bf16 v[92:95], v[168:171], v[200:203], v[92:95]
	v_mfma_f32_16x16x32_bf16 v[84:87], v[176:179], v[200:203], v[84:87]
	v_mfma_f32_16x16x32_bf16 v[60:63], v[168:171], v[208:211], v[60:63]
	v_mfma_f32_16x16x32_bf16 v[52:55], v[176:179], v[208:211], v[52:55]
	v_mfma_f32_16x16x32_bf16 v[124:127], v[172:175], v[188:191], v[124:127]
	v_mfma_f32_16x16x32_bf16 v[116:119], v[180:183], v[188:191], v[116:119]
	v_mfma_f32_16x16x32_bf16 v[108:111], v[172:175], v[196:199], v[108:111]
	v_mfma_f32_16x16x32_bf16 v[100:103], v[180:183], v[196:199], v[100:103]
	v_mfma_f32_16x16x32_bf16 v[92:95], v[172:175], v[204:207], v[92:95]
	v_mfma_f32_16x16x32_bf16 v[84:87], v[180:183], v[204:207], v[84:87]
	v_mfma_f32_16x16x32_bf16 v[60:63], v[172:175], v[212:215], v[60:63]
	v_mfma_f32_16x16x32_bf16 v[52:55], v[180:183], v[212:215], v[52:55]
	s_barrier
	s_mov_b32 m0, s55
	v_lshl_add_u64 v[140:141], s[82:83], 0, v[128:129]
	s_add_u32 s94, s82, 0x80000
	ds_read_b128 v[184:187], v151 offset:16384
	ds_read_b128 v[188:191], v151 offset:17408
	ds_read_b128 v[192:195], v151 offset:18432
	ds_read_b128 v[196:199], v151 offset:19456
	ds_read_b128 v[200:203], v151 offset:20480
	ds_read_b128 v[204:207], v151 offset:21504
	ds_read_b128 v[208:211], v151 offset:22528
	ds_read_b128 v[212:215], v151 offset:23552
	global_load_lds_dwordx4 v128, s[82:83]
	v_lshl_add_u64 v[142:143], s[82:83], 0, v[130:131]
	s_mov_b32 m0, s56
	s_addc_u32 s95, s83, 0
	global_load_lds_dwordx4 v130, s[82:83]
	v_lshl_add_u64 v[146:147], s[94:95], 0, v[128:129]
	s_mov_b32 m0, s57
	v_lshl_add_u64 v[216:217], s[84:85], 0, v[132:133]
	global_load_lds_dwordx4 v128, s[94:95]
	v_lshl_add_u64 v[146:147], s[94:95], 0, v[130:131]
	s_mov_b32 m0, s58
	s_nop 0
	global_load_lds_dwordx4 v130, s[94:95]
	v_lshl_add_u64 v[146:147], s[84:85], 0, v[134:135]
	s_mov_b32 m0, s23
	s_nop 0
	global_load_lds_dwordx4 v134, s[84:85]
	s_mov_b32 m0, s36
	s_nop 0
	global_load_lds_dwordx4 v132, s[84:85]
	s_waitcnt vmcnt(8) lgkmcnt(0)
	s_barrier
; #define PG8_MMA(ai, bj, At, Bt) do { __builtin_amdgcn_s_setprio(1); _Pragma("unroll") for (int m = 0; m < 4; ++m) _Pragma("unroll") for (int n = 0; n < 2; ++n) _Pragma("unroll") for (int k = 0; k < 2; ++k) \
;         acc[ai][bj][m][n] = __builtin_amdgcn_mfma_f32_16x16x32_bf16(Bt[n][k], At[m][k], acc[ai][bj][m][n], 0, 0, 0); __builtin_amdgcn_s_setprio(0); } while (0)
; template <class Epi, class Sched, bool ALIGN_EPI = false, bool SP2 = false, bool A_TILED = false>
; __device__ __forceinline__ void gemm_phase(PG8_LAS unsigned char* lds, const Gemm g, const Sched& S, const Epi& E, const int wave_s) {
;     ...
;         for (int t = PEEL ? 2 : 0; t < nt; t += 2) {
;             const bool last = (t == nt - 2);
;             const char* a1 = cA + (size_t)(t + 1) * kstepA;
;             const char* a2 = last ? nA : cA + (size_t)(t + 2) * kstepA; const char* b2 = last ? nB : cB + (size_t)(t + 2) * kstep;
;             const char* a3 = a2 + kstepA; const char* b3 = b2 + kstep;
;             if (last && has_next) S.a_ready(nxt);
;             if constexpr (SP2) {
;             PG8_ITER(PG8_MMA)
	v_mfma_f32_16x16x32_bf16 v[72:75], v[152:155], v[184:187], v[72:75]
	v_mfma_f32_16x16x32_bf16 v[64:67], v[160:163], v[184:187], v[64:67]
	v_mfma_f32_16x16x32_bf16 v[40:43], v[152:155], v[192:195], v[40:43]
	v_mfma_f32_16x16x32_bf16 v[32:35], v[160:163], v[192:195], v[32:35]
	v_mfma_f32_16x16x32_bf16 v[24:27], v[152:155], v[200:203], v[24:27]
	v_mfma_f32_16x16x32_bf16 v[16:19], v[160:163], v[200:203], v[16:19]
	v_mfma_f32_16x16x32_bf16 v[8:11], v[152:155], v[208:211], v[8:11]
	v_mfma_f32_16x16x32_bf16 v[0:3], v[160:163], v[208:211], v[0:3]
	v_mfma_f32_16x16x32_bf16 v[72:75], v[156:159], v[188:191], v[72:75]
	v_mfma_f32_16x16x32_bf16 v[64:67], v[164:167], v[188:191], v[64:67]
	v_mfma_f32_16x16x32_bf16 v[40:43], v[156:159], v[196:199], v[40:43]
	v_mfma_f32_16x16x32_bf16 v[32:35], v[164:167], v[196:199], v[32:35]
	v_mfma_f32_16x16x32_bf16 v[24:27], v[156:159], v[204:207], v[24:27]
	v_mfma_f32_16x16x32_bf16 v[16:19], v[164:167], v[204:207], v[16:19]
	v_mfma_f32_16x16x32_bf16 v[8:11], v[156:159], v[212:215], v[8:11]
	v_mfma_f32_16x16x32_bf16 v[0:3], v[164:167], v[212:215], v[0:3]
	v_mfma_f32_16x16x32_bf16 v[76:79], v[168:171], v[184:187], v[76:79]
	v_mfma_f32_16x16x32_bf16 v[68:71], v[176:179], v[184:187], v[68:71]
	v_mfma_f32_16x16x32_bf16 v[44:47], v[168:171], v[192:195], v[44:47]
	v_mfma_f32_16x16x32_bf16 v[36:39], v[176:179], v[192:195], v[36:39]
	v_mfma_f32_16x16x32_bf16 v[28:31], v[168:171], v[200:203], v[28:31]
	v_mfma_f32_16x16x32_bf16 v[20:23], v[176:179], v[200:203], v[20:23]
	v_mfma_f32_16x16x32_bf16 v[12:15], v[168:171], v[208:211], v[12:15]
	v_mfma_f32_16x16x32_bf16 v[4:7], v[176:179], v[208:211], v[4:7]
	v_mfma_f32_16x16x32_bf16 v[76:79], v[172:175], v[188:191], v[76:79]
	v_mfma_f32_16x16x32_bf16 v[68:71], v[180:183], v[188:191], v[68:71]
	v_mfma_f32_16x16x32_bf16 v[44:47], v[172:175], v[196:199], v[44:47]
	v_mfma_f32_16x16x32_bf16 v[36:39], v[180:183], v[196:199], v[36:39]
	v_mfma_f32_16x16x32_bf16 v[28:31], v[172:175], v[204:207], v[28:31]
	v_mfma_f32_16x16x32_bf16 v[20:23], v[180:183], v[204:207], v[20:23]
	v_mfma_f32_16x16x32_bf16 v[12:15], v[172:175], v[212:215], v[12:15]
	v_mfma_f32_16x16x32_bf16 v[4:7], v[180:183], v[212:215], v[4:7]
	s_barrier
	ds_read_b128 v[152:155], v144
	ds_read_b128 v[156:159], v144 offset:1024
	ds_read_b128 v[160:163], v144 offset:2048
	ds_read_b128 v[164:167], v144 offset:3072
	ds_read_b128 v[168:171], v145
	ds_read_b128 v[172:175], v145 offset:1024
	ds_read_b128 v[176:179], v145 offset:2048
	ds_read_b128 v[180:183], v145 offset:3072
	s_add_u32 s84, s84, 0x80000
	s_addc_u32 s85, s85, 0
	s_mov_b32 m0, s37
	v_lshl_add_u64 v[218:219], s[84:85], 0, v[134:135]
	ds_read_b128 v[184:187], v151 offset:32768
	ds_read_b128 v[188:191], v151 offset:33792
	ds_read_b128 v[192:195], v151 offset:34816
	ds_read_b128 v[196:199], v151 offset:35840
	ds_read_b128 v[200:203], v151 offset:36864
	ds_read_b128 v[204:207], v151 offset:37888
	ds_read_b128 v[208:211], v151 offset:38912
	ds_read_b128 v[212:215], v151 offset:39936
	global_load_lds_dwordx4 v134, s[84:85]
	v_lshl_add_u64 v[218:219], s[84:85], 0, v[132:133]
	s_mov_b32 m0, s38
	s_nop 0
	global_load_lds_dwordx4 v132, s[84:85]
	s_waitcnt vmcnt(8) lgkmcnt(0)
	s_barrier
	v_mfma_f32_16x16x32_bf16 v[120:123], v[152:155], v[184:187], v[120:123]
	v_mfma_f32_16x16x32_bf16 v[112:115], v[160:163], v[184:187], v[112:115]
	v_mfma_f32_16x16x32_bf16 v[104:107], v[152:155], v[192:195], v[104:107]
	v_mfma_f32_16x16x32_bf16 v[96:99], v[160:163], v[192:195], v[96:99]
	v_mfma_f32_16x16x32_bf16 v[88:91], v[152:155], v[200:203], v[88:91]
	v_mfma_f32_16x16x32_bf16 v[80:83], v[160:163], v[200:203], v[80:83]
	v_mfma_f32_16x16x32_bf16 v[56:59], v[152:155], v[208:211], v[56:59]
	v_mfma_f32_16x16x32_bf16 v[48:51], v[160:163], v[208:211], v[48:51]
	v_mfma_f32_16x16x32_bf16 v[120:123], v[156:159], v[188:191], v[120:123]
	v_mfma_f32_16x16x32_bf16 v[112:115], v[164:167], v[188:191], v[112:115]
	v_mfma_f32_16x16x32_bf16 v[104:107], v[156:159], v[196:199], v[104:107]
	v_mfma_f32_16x16x32_bf16 v[96:99], v[164:167], v[196:199], v[96:99]
	v_mfma_f32_16x16x32_bf16 v[88:91], v[156:159], v[204:207], v[88:91]
	v_mfma_f32_16x16x32_bf16 v[80:83], v[164:167], v[204:207], v[80:83]
	v_mfma_f32_16x16x32_bf16 v[56:59], v[156:159], v[212:215], v[56:59]
	v_mfma_f32_16x16x32_bf16 v[48:51], v[164:167], v[212:215], v[48:51]
	v_mfma_f32_16x16x32_bf16 v[124:127], v[168:171], v[184:187], v[124:127]
	v_mfma_f32_16x16x32_bf16 v[116:119], v[176:179], v[184:187], v[116:119]
	v_mfma_f32_16x16x32_bf16 v[108:111], v[168:171], v[192:195], v[108:111]
	v_mfma_f32_16x16x32_bf16 v[100:103], v[176:179], v[192:195], v[100:103]
	v_mfma_f32_16x16x32_bf16 v[92:95], v[168:171], v[200:203], v[92:95]
	v_mfma_f32_16x16x32_bf16 v[84:87], v[176:179], v[200:203], v[84:87]
	v_mfma_f32_16x16x32_bf16 v[60:63], v[168:171], v[208:211], v[60:63]
	v_mfma_f32_16x16x32_bf16 v[52:55], v[176:179], v[208:211], v[52:55]
	v_mfma_f32_16x16x32_bf16 v[124:127], v[172:175], v[188:191], v[124:127]
	v_mfma_f32_16x16x32_bf16 v[116:119], v[180:183], v[188:191], v[116:119]
	v_mfma_f32_16x16x32_bf16 v[108:111], v[172:175], v[196:199], v[108:111]
	v_mfma_f32_16x16x32_bf16 v[100:103], v[180:183], v[196:199], v[100:103]
	v_mfma_f32_16x16x32_bf16 v[92:95], v[172:175], v[204:207], v[92:95]
	v_mfma_f32_16x16x32_bf16 v[84:87], v[180:183], v[204:207], v[84:87]
	v_mfma_f32_16x16x32_bf16 v[60:63], v[172:175], v[212:215], v[60:63]
	v_mfma_f32_16x16x32_bf16 v[52:55], v[180:183], v[212:215], v[52:55]
	s_barrier
; #define PG8_MMA(ai, bj, At, Bt) do { __builtin_amdgcn_s_setprio(1); _Pragma("unroll") for (int m = 0; m < 4; ++m) _Pragma("unroll") for (int n = 0; n < 2; ++n) _Pragma("unroll") for (int k = 0; k < 2; ++k) \
;         acc[ai][bj][m][n] = __builtin_amdgcn_mfma_f32_16x16x32_bf16(Bt[n][k], At[m][k], acc[ai][bj][m][n], 0, 0, 0); __builtin_amdgcn_s_setprio(0); } while (0)
; template <class Epi, class Sched, bool ALIGN_EPI = false, bool SP2 = false, bool A_TILED = false>
; __device__ __forceinline__ void gemm_phase(PG8_LAS unsigned char* lds, const Gemm g, const Sched& S, const Epi& E, const int wave_s) {
;     ...
;         for (int t = PEEL ? 2 : 0; t < nt; t += 2) {
;             const bool last = (t == nt - 2);
;             const char* a1 = cA + (size_t)(t + 1) * kstepA;
;             const char* a2 = last ? nA : cA + (size_t)(t + 2) * kstepA; const char* b2 = last ? nB : cB + (size_t)(t + 2) * kstep;
;             const char* a3 = a2 + kstepA; const char* b3 = b2 + kstep;
;             if (last && has_next) S.a_ready(nxt);
;             if constexpr (SP2) {
;             PG8_ITER(PG8_MMA)
	s_mov_b32 m0, s59
	v_lshl_add_u64 v[140:141], v[140:141], 0, s[62:63]
	s_add_u32 s82, s82, 0x80080
	ds_read_b128 v[184:187], v151 offset:49152
	ds_read_b128 v[188:191], v151 offset:50176
	ds_read_b128 v[192:195], v151 offset:51200
	ds_read_b128 v[196:199], v151 offset:52224
	ds_read_b128 v[200:203], v151 offset:53248
	ds_read_b128 v[204:207], v151 offset:54272
	ds_read_b128 v[208:211], v151 offset:55296
	ds_read_b128 v[212:215], v151 offset:56320
	global_load_lds_dwordx4 v[140:141], off
	v_lshl_add_u64 v[140:141], v[142:143], 0, s[62:63]
	s_mov_b32 m0, s71
	s_addc_u32 s83, s83, 0
	global_load_lds_dwordx4 v[140:141], off
	v_lshl_add_u64 v[140:141], s[82:83], 0, v[128:129]
	s_mov_b32 m0, s73
	s_nop 0
	global_load_lds_dwordx4 v128, s[82:83]
	v_lshl_add_u64 v[140:141], s[82:83], 0, v[130:131]
	s_mov_b32 m0, s79
	s_nop 0
	global_load_lds_dwordx4 v130, s[82:83]
	v_lshl_add_u64 v[140:141], v[146:147], 0, s[62:63]
	s_mov_b32 m0, s43
	s_nop 0
	global_load_lds_dwordx4 v[140:141], off
	v_lshl_add_u64 v[140:141], v[216:217], 0, s[62:63]
	s_mov_b32 m0, s44
	s_nop 0
	global_load_lds_dwordx4 v[140:141], off
	s_waitcnt vmcnt(8) lgkmcnt(0)
	s_barrier
	v_mfma_f32_16x16x32_bf16 v[72:75], v[152:155], v[184:187], v[72:75]
	v_mfma_f32_16x16x32_bf16 v[64:67], v[160:163], v[184:187], v[64:67]
	v_mfma_f32_16x16x32_bf16 v[40:43], v[152:155], v[192:195], v[40:43]
	v_mfma_f32_16x16x32_bf16 v[32:35], v[160:163], v[192:195], v[32:35]
	v_mfma_f32_16x16x32_bf16 v[24:27], v[152:155], v[200:203], v[24:27]
	v_mfma_f32_16x16x32_bf16 v[16:19], v[160:163], v[200:203], v[16:19]
	v_mfma_f32_16x16x32_bf16 v[8:11], v[152:155], v[208:211], v[8:11]
	v_mfma_f32_16x16x32_bf16 v[0:3], v[160:163], v[208:211], v[0:3]
	v_mfma_f32_16x16x32_bf16 v[72:75], v[156:159], v[188:191], v[72:75]
	v_mfma_f32_16x16x32_bf16 v[64:67], v[164:167], v[188:191], v[64:67]
	v_mfma_f32_16x16x32_bf16 v[40:43], v[156:159], v[196:199], v[40:43]
	v_mfma_f32_16x16x32_bf16 v[32:35], v[164:167], v[196:199], v[32:35]
	v_mfma_f32_16x16x32_bf16 v[24:27], v[156:159], v[204:207], v[24:27]
	v_mfma_f32_16x16x32_bf16 v[16:19], v[164:167], v[204:207], v[16:19]
	v_mfma_f32_16x16x32_bf16 v[8:11], v[156:159], v[212:215], v[8:11]
	v_mfma_f32_16x16x32_bf16 v[0:3], v[164:167], v[212:215], v[0:3]
	v_mfma_f32_16x16x32_bf16 v[76:79], v[168:171], v[184:187], v[76:79]
	v_mfma_f32_16x16x32_bf16 v[68:71], v[176:179], v[184:187], v[68:71]
	v_mfma_f32_16x16x32_bf16 v[44:47], v[168:171], v[192:195], v[44:47]
	v_mfma_f32_16x16x32_bf16 v[36:39], v[176:179], v[192:195], v[36:39]
	v_mfma_f32_16x16x32_bf16 v[28:31], v[168:171], v[200:203], v[28:31]
	v_mfma_f32_16x16x32_bf16 v[20:23], v[176:179], v[200:203], v[20:23]
	v_mfma_f32_16x16x32_bf16 v[12:15], v[168:171], v[208:211], v[12:15]
	v_mfma_f32_16x16x32_bf16 v[4:7], v[176:179], v[208:211], v[4:7]
	v_mfma_f32_16x16x32_bf16 v[76:79], v[172:175], v[188:191], v[76:79]
	v_mfma_f32_16x16x32_bf16 v[68:71], v[180:183], v[188:191], v[68:71]
	v_mfma_f32_16x16x32_bf16 v[44:47], v[172:175], v[196:199], v[44:47]
	v_mfma_f32_16x16x32_bf16 v[36:39], v[180:183], v[196:199], v[36:39]
	v_mfma_f32_16x16x32_bf16 v[28:31], v[172:175], v[204:207], v[28:31]
	v_mfma_f32_16x16x32_bf16 v[20:23], v[180:183], v[204:207], v[20:23]
	v_mfma_f32_16x16x32_bf16 v[12:15], v[172:175], v[212:215], v[12:15]
	v_mfma_f32_16x16x32_bf16 v[4:7], v[180:183], v[212:215], v[4:7]
	s_barrier
	s_add_i32 s90, s90, 2
	s_add_u32 s88, s88, 0x100
	s_addc_u32 s89, s89, 0
	s_add_u32 s80, s80, 0x100
	s_addc_u32 s81, s81, 0
	s_cmp_gt_u32 s90, 29
	s_cbranch_scc0 .LBB0_777
	s_and_b64 vcc, exec, s[64:65]
	s_cbranch_vccz .LBB0_780
	s_barrier

; __device__ __forceinline__ int tid_now(int wave_s) { unsigned z = 0u; asm volatile("" : "+v"(z)); return (wave_s << 6) | (int)__builtin_amdgcn_mbcnt_hi(~0u, __builtin_amdgcn_mbcnt_lo(~0u, z)); }
; __device__ __forceinline__ unsigned xb_add(unsigned* p, unsigned v) { return __hip_atomic_fetch_add(p, v, __ATOMIC_RELAXED, __HIP_MEMORY_SCOPE_AGENT); }
; __device__ __forceinline__ void xcd_barrier(const XcdBarrier& b) {
;     asm volatile("s_waitcnt vmcnt(0)" ::: "memory");
;     __syncthreads();
;     if (tid_now(b.w) == 0) {
;         unsigned* bar = b.bar;
;         __builtin_amdgcn_s_waitcnt(0);
;         unsigned nloc = b.st[0], nx = b.st[1];
;         if (nloc == 0u) { xcd_barrier_complete(bar, b.x, nloc, nx, b.np); b.st[0] = nloc; b.st[1] = nx; }
;         const unsigned old = xb_add(&bar[XB_XSUB(b.x)], 1u);
.LBB0_784:
	s_setprio 0
	s_cmp_gt_i32 s35, 3
	s_cselect_b64 s[0:1], -1, 0
	s_and_b64 s[2:3], s[2:3], s[0:1]
	s_andn2_b64 vcc, exec, s[2:3]
	s_cbranch_vccnz .LBB0_838
	s_waitcnt vmcnt(0)
	v_mov_b32_e32 v0, 0
	s_waitcnt vmcnt(0)
	s_waitcnt lgkmcnt(0)
	s_barrier
	s_nop 0
	v_mbcnt_lo_u32_b32 v0, -1, v0
	v_mbcnt_hi_u32_b32 v0, -1, v0
	v_or_b32_e32 v0, s33, v0
	v_cmp_eq_u32_e32 vcc, 0, v0
	s_and_saveexec_b64 s[2:3], vcc
	s_cbranch_execz .LBB0_837
	s_add_i32 s4, 0, 0x27f68
	v_mov_b32_e32 v0, s4
	s_waitcnt vmcnt(0) expcnt(0) lgkmcnt(0)
	ds_read_b32 v2, v0
	s_add_i32 s4, 0, 0x27f6c
	v_mov_b32_e32 v0, s4
	ds_read_b32 v0, v0
	s_waitcnt lgkmcnt(1)
	v_cmp_ne_u32_e32 vcc, 0, v2
	s_cbranch_vccnz .LBB0_801
	s_add_u32 s4, s10, 0x1000
	s_addc_u32 s5, s11, 0
	s_add_u32 s60, s10, 0x1100
	s_addc_u32 s61, s11, 0
	s_add_u32 s62, s10, 0x1200
	s_addc_u32 s63, s11, 0
	s_add_u32 s64, s10, 0x1300
	s_addc_u32 s65, s11, 0
	s_mov_b32 s6, 1
	v_mov_b32_e32 v16, 0
	s_branch .LBB0_789

; __device__ __forceinline__ int tid_now(int wave_s) { unsigned z = 0u; asm volatile("" : "+v"(z)); return (wave_s << 6) | (int)__builtin_amdgcn_mbcnt_hi(~0u, __builtin_amdgcn_mbcnt_lo(~0u, z)); }
; __device__ __forceinline__ unsigned xb_add(unsigned* p, unsigned v) { return __hip_atomic_fetch_add(p, v, __ATOMIC_RELAXED, __HIP_MEMORY_SCOPE_AGENT); }
; __device__ __forceinline__ void xcd_barrier(const XcdBarrier& b) {
;     asm volatile("s_waitcnt vmcnt(0)" ::: "memory");
;     __syncthreads();
;     if (tid_now(b.w) == 0) {
;         unsigned* bar = b.bar;
;         __builtin_amdgcn_s_waitcnt(0);
;         unsigned nloc = b.st[0], nx = b.st[1];
;         if (nloc == 0u) { xcd_barrier_complete(bar, b.x, nloc, nx, b.np); b.st[0] = nloc; b.st[1] = nx; }
;         const unsigned old = xb_add(&bar[XB_XSUB(b.x)], 1u);
.LBB0_977:
	s_setprio 0
	s_cmp_gt_i32 s35, 4
	s_cselect_b64 s[0:1], -1, 0
	s_and_b64 s[2:3], s[2:3], s[0:1]
	s_andn2_b64 vcc, exec, s[2:3]
	s_cbranch_vccnz .LBB0_1031
	s_waitcnt vmcnt(0)
	v_mov_b32_e32 v0, 0
	s_waitcnt vmcnt(0)
	s_waitcnt lgkmcnt(0)
	s_barrier
	s_nop 0
	v_mbcnt_lo_u32_b32 v0, -1, v0
	v_mbcnt_hi_u32_b32 v0, -1, v0
	v_or_b32_e32 v0, s33, v0
	v_cmp_eq_u32_e32 vcc, 0, v0
	s_and_saveexec_b64 s[2:3], vcc
	s_cbranch_execz .LBB0_1030
	s_add_i32 s4, 0, 0x27f68
	v_mov_b32_e32 v0, s4
	s_waitcnt vmcnt(0) expcnt(0) lgkmcnt(0)
	ds_read_b32 v2, v0
	s_add_i32 s4, 0, 0x27f6c
	v_mov_b32_e32 v0, s4
	ds_read_b32 v0, v0
	s_waitcnt lgkmcnt(1)
	v_cmp_ne_u32_e32 vcc, 0, v2
	s_cbranch_vccnz .LBB0_994
	s_add_u32 s4, s10, 0x1000
	s_addc_u32 s5, s11, 0
	s_add_u32 s60, s10, 0x1100
	s_addc_u32 s61, s11, 0
	s_add_u32 s62, s10, 0x1200
	s_addc_u32 s63, s11, 0
	s_add_u32 s64, s10, 0x1300
	s_addc_u32 s65, s11, 0
	s_mov_b32 s6, 1
	v_mov_b32_e32 v16, 0
	s_branch .LBB0_982

; #define PG8_STAGE(bufoff, gbase, voff) do { _Pragma("unroll") for (int _i = 0; _i < 2; ++_i) \
;         __builtin_amdgcn_global_load_lds((const unsigned*)((const char*)(gbase) + (voff)[_i]), (PG8_LAS unsigned*)(lds + (bufoff) + ldsw + _i * 8192), 16, 0, 0); } while (0)
; #define PG8_WAIT_V(n) asm volatile("s_waitcnt vmcnt(" #n ")" ::: "memory")
; template <class Epi, class Sched, bool ALIGN_EPI = false, bool SP2 = false, bool A_TILED = false>
; __device__ __forceinline__ void gemm_phase(PG8_LAS unsigned char* lds, const Gemm g, const Sched& S, const Epi& E, const int wave_s) {
;     ...
;     if constexpr (SP2) {
;         PG8_STAGE(PG8_SB(0, 0), cB, voffB); PG8_STAGE(PG8_SB(0, 1), cB + hstep, voffB); PG8_STAGE(PG8_SA(0, 0), cA, voffA); PG8_STAGE(PG8_SA(0, 1), cA + hstepA, voffA);
;         if (wr == 1) PG8_BAR;
;         PG8_WAIT_V(2); PG8_BAR;
;         PG8_STAGE(PG8_SB(1, 0), cB + kstep, voffB); PG8_STAGE(PG8_SA(1, 0), cA + kstepA, voffA); PG8_STAGE(PG8_SB(1, 1), cB + hstep + kstep, voffB);
;         PG8_WAIT_V(6); PG8_BAR;
;     } else {
;         PG8_STAGE(PG8_SB(0, 0), cB, voffB); PG8_STAGE(PG8_SA(0, 0), cA, voffA); PG8_STAGE(PG8_SB(0, 1), cB + hstep, voffB); PG8_STAGE(PG8_SA(0, 1), cA + hstepA, voffA);
;         if (wr == 1) PG8_BAR;
;         PG8_WAIT_V(4); PG8_BAR;
;         PG8_STAGE(PG8_SB(1, 0), cB + kstep, voffB); PG8_STAGE(PG8_SA(1, 0), cA + kstepA, voffA); PG8_STAGE(PG8_SB(1, 1), cB + hstep + kstep, voffB);
;         PG8_WAIT_V(6); PG8_BAR;
;     }
;     for (;;) {
;         const bool has_next = Epi::AFTER_DRAIN ? false : S.next(ui + 1, nxt);
;         const char* nA = has_next ? (const char*)g.A + (size_t)nxt.pm * tstepA : cA; const char* nB = has_next ? (const char*)g.Bt + (size_t)nxt.pn * tstep : cB;
;         constexpr bool PEEL = SP2 && !Epi::AFTER_DRAIN;
;         if constexpr (PEEL) {
;             const char* a1 = cA + kstepA; const char* a2 = cA + 2 * kstepA; const char* b2 = cB + 2 * kstep; const char* a3 = a2 + kstepA; const char* b3 = b2 + kstep;
;             PG8_ITER(PG8_MMAZ)
;         } else {
; #pragma unroll
;             for (int a = 0; a < 2; ++a)
; #pragma unroll
;                 for (int b = 0; b < 2; ++b)
; #pragma unroll
;                     for (int m = 0; m < 4; ++m)
; #pragma unroll
;                         for (int n = 0; n < 2; ++n) acc[a][b][m][n] = (f32x4){0.f, 0.f, 0.f, 0.f};
.LBB0_1042:
	v_and_b32_e32 v15, 48, v8
	v_lshlrev_b32_e32 v16, 6, v8
	s_movk_i32 s36, 0x3c0
	v_lshlrev_b32_e32 v8, 2, v8
	s_and_b32 s9, s7, 3
	s_lshl_b32 s8, s23, 6
	s_lshl_b32 s23, s23, 13
	v_and_or_b32 v15, v16, s36, v15
	v_and_b32_e32 v8, 32, v8
	s_mov_b64 s[66:67], 0x80
	v_bitop3_b32 v16, v15, s23, v8 bitop3:0xde
	s_lshl_b32 s23, s9, 12
	s_add_i32 m0, s14, 0x18000
	v_lshl_add_u64 v[6:7], v[6:7], 0, s[66:67]
	v_bitop3_b32 v8, v15, s23, v8 bitop3:0xde
	s_waitcnt vmcnt(2)
	s_barrier
	global_load_lds_dwordx4 v[6:7], off
	v_lshl_add_u64 v[4:5], v[4:5], 0, s[66:67]
	s_add_i32 m0, s14, 0x1a000
	s_add_i32 s23, s14, 0x8000
	s_add_i32 s36, s14, 0xa000
	global_load_lds_dwordx4 v[4:5], off
	v_lshl_add_u64 v[2:3], v[2:3], 0, s[66:67]
	s_mov_b32 m0, s23
	s_add_u32 s38, s0, 0x80080
	global_load_lds_dwordx4 v[2:3], off
	v_lshl_add_u64 v[0:1], v[0:1], 0, s[66:67]
	s_mov_b32 m0, s36
	s_addc_u32 s39, s1, 0
	global_load_lds_dwordx4 v[0:1], off
	s_add_i32 m0, s14, 0x1c000
	v_lshl_add_u64 v[0:1], s[38:39], 0, v[130:131]
	global_load_lds_dwordx4 v130, s[38:39]
	v_lshl_add_u64 v[0:1], s[38:39], 0, v[134:135]
	s_add_i32 m0, s14, 0x1e000
	s_mov_b64 s[40:41], 0x20680080
	global_load_lds_dwordx4 v134, s[38:39]
	v_lshlrev_b32_e32 v0, 15, v12
	v_and_b32_e32 v0, 0xffff0000, v0
	v_lshl_add_u32 v0, v13, 12, v0
	v_and_b32_e32 v1, 1, v12
	v_lshl_or_b32 v0, v1, 6, v0
	v_lshl_add_u32 v0, v14, 1, v0
	v_mov_b32_e32 v1, v131
	v_lshl_add_u64 v[0:1], s[68:69], 0, v[0:1]
	v_lshl_add_u64 v[136:137], v[0:1], 0, s[40:41]
	v_lshlrev_b32_e32 v0, 15, v9
	v_and_b32_e32 v0, 0xffff0000, v0
	v_lshl_add_u32 v0, v10, 12, v0
	v_and_b32_e32 v1, 1, v9
	s_add_u32 s37, s70, 0x3200100
	v_lshl_or_b32 v0, v1, 6, v0
	s_addc_u32 s38, s71, 0
	v_lshl_add_u32 v0, v11, 1, v0
	v_mov_b32_e32 v1, v131
	v_lshl_add_u64 v[0:1], s[68:69], 0, v[0:1]
	s_add_u32 s39, s68, 0x20600100
	s_waitcnt vmcnt(6)
	v_lshl_add_u64 v[138:139], v[0:1], 0, s[40:41]
	s_addc_u32 s40, s69, 0
	s_bitcmp1_b32 s33, 8
	s_cbranch_scc1 .Lsp_2
	s_setprio 1
.Lsp_2:
	s_add_i32 s44, 0, 0x10000
	s_add_i32 s46, 0, 0x14000
	s_add_i32 s48, 0, 0x18000
	s_add_i32 s51, 0, 0x1c000
	v_add_u32_e32 v140, s44, v8
	v_add_u32_e32 v141, s46, v8
	s_add_i32 s44, s44, s50
	s_add_i32 s46, s46, s50
	v_add_u32_e32 v143, s48, v8
	s_add_i32 s48, s48, s50
	s_add_i32 s50, s51, s50
	s_mov_b32 s41, -2
	v_add_u32_e32 v142, 0, v16
	s_add_i32 s42, s14, 0xc000
	s_add_i32 s43, s14, 0xe000
	s_add_i32 s45, s44, 0x2000
	s_add_i32 s47, s46, 0x2000
	v_add_u32_e32 v144, s51, v8
	s_add_i32 s49, s48, 0x2000
	s_add_i32 s51, s50, 0x2000
	s_mov_b64 s[68:69], 0x100
	v_mov_b32_e32 v0, v131
	v_mov_b32_e32 v1, v131
	v_mov_b32_e32 v2, v131
	v_mov_b32_e32 v3, v131
	v_mov_b32_e32 v4, v131
	v_mov_b32_e32 v5, v131
	v_mov_b32_e32 v6, v131
	v_mov_b32_e32 v7, v131
	v_mov_b32_e32 v24, v131
	v_mov_b32_e32 v25, v131
	v_mov_b32_e32 v26, v131
	v_mov_b32_e32 v27, v131
	v_mov_b32_e32 v28, v131
	v_mov_b32_e32 v29, v131
	v_mov_b32_e32 v30, v131
	v_mov_b32_e32 v31, v131
	v_mov_b32_e32 v88, v131
	v_mov_b32_e32 v89, v131
	v_mov_b32_e32 v90, v131
	v_mov_b32_e32 v91, v131
	v_mov_b32_e32 v92, v131
	v_mov_b32_e32 v93, v131
	v_mov_b32_e32 v94, v131
	v_mov_b32_e32 v95, v131
	v_mov_b32_e32 v112, v131
	v_mov_b32_e32 v113, v131
	v_mov_b32_e32 v114, v131
	v_mov_b32_e32 v115, v131
	v_mov_b32_e32 v116, v131
	v_mov_b32_e32 v117, v131
	v_mov_b32_e32 v118, v131
	v_mov_b32_e32 v119, v131
	v_mov_b32_e32 v16, v131
	v_mov_b32_e32 v17, v131
	v_mov_b32_e32 v18, v131
	v_mov_b32_e32 v19, v131
	v_mov_b32_e32 v20, v131
	v_mov_b32_e32 v21, v131
	v_mov_b32_e32 v22, v131
	v_mov_b32_e32 v23, v131
	v_mov_b32_e32 v76, v131
	v_mov_b32_e32 v77, v131
	v_mov_b32_e32 v78, v131
	v_mov_b32_e32 v79, v131
	v_mov_b32_e32 v84, v131
	v_mov_b32_e32 v85, v131
	v_mov_b32_e32 v86, v131
	v_mov_b32_e32 v87, v131
	v_mov_b32_e32 v120, v131
	v_mov_b32_e32 v121, v131
	v_mov_b32_e32 v122, v131
	v_mov_b32_e32 v123, v131
	v_mov_b32_e32 v124, v131
	v_mov_b32_e32 v125, v131
	v_mov_b32_e32 v126, v131
	v_mov_b32_e32 v127, v131
	v_mov_b32_e32 v104, v131
	v_mov_b32_e32 v105, v131
	v_mov_b32_e32 v106, v131
	v_mov_b32_e32 v107, v131
	v_mov_b32_e32 v108, v131
	v_mov_b32_e32 v109, v131
	v_mov_b32_e32 v110, v131
	v_mov_b32_e32 v111, v131
	v_mov_b32_e32 v96, v131
	v_mov_b32_e32 v97, v131
	v_mov_b32_e32 v98, v131
	v_mov_b32_e32 v99, v131
	v_mov_b32_e32 v100, v131
	v_mov_b32_e32 v101, v131
	v_mov_b32_e32 v102, v131
	v_mov_b32_e32 v103, v131
	v_mov_b32_e32 v64, v131
	v_mov_b32_e32 v65, v131
	v_mov_b32_e32 v66, v131
	v_mov_b32_e32 v67, v131
	v_mov_b32_e32 v68, v131
	v_mov_b32_e32 v69, v131
	v_mov_b32_e32 v70, v131
	v_mov_b32_e32 v71, v131
	v_mov_b32_e32 v48, v131
	v_mov_b32_e32 v49, v131
	v_mov_b32_e32 v50, v131
	v_mov_b32_e32 v51, v131
	v_mov_b32_e32 v52, v131
	v_mov_b32_e32 v53, v131
	v_mov_b32_e32 v54, v131
	v_mov_b32_e32 v55, v131
	v_mov_b32_e32 v40, v131
	v_mov_b32_e32 v41, v131
	v_mov_b32_e32 v42, v131
	v_mov_b32_e32 v43, v131
	v_mov_b32_e32 v44, v131
	v_mov_b32_e32 v45, v131
	v_mov_b32_e32 v46, v131
	v_mov_b32_e32 v47, v131
	v_mov_b32_e32 v72, v131
	v_mov_b32_e32 v73, v131
	v_mov_b32_e32 v74, v131
	v_mov_b32_e32 v75, v131
	v_mov_b32_e32 v80, v131
	v_mov_b32_e32 v81, v131
	v_mov_b32_e32 v82, v131
	v_mov_b32_e32 v83, v131
	v_mov_b32_e32 v56, v131
	v_mov_b32_e32 v57, v131
	v_mov_b32_e32 v58, v131
	v_mov_b32_e32 v59, v131
	v_mov_b32_e32 v60, v131
	v_mov_b32_e32 v61, v131
	v_mov_b32_e32 v62, v131
	v_mov_b32_e32 v63, v131
	v_mov_b32_e32 v32, v131
	v_mov_b32_e32 v33, v131
	v_mov_b32_e32 v34, v131
	v_mov_b32_e32 v35, v131
	v_mov_b32_e32 v36, v131
	v_mov_b32_e32 v37, v131
	v_mov_b32_e32 v38, v131
	v_mov_b32_e32 v39, v131
	v_mov_b32_e32 v12, v131
	v_mov_b32_e32 v13, v131
	v_mov_b32_e32 v14, v131
	v_mov_b32_e32 v15, v131
	v_mov_b32_e32 v8, v131
	v_mov_b32_e32 v9, v131
	v_mov_b32_e32 v10, v131
	v_mov_b32_e32 v11, v131
	s_barrier
; #define PG8_MMA(ai, bj, At, Bt) do { __builtin_amdgcn_s_setprio(1); _Pragma("unroll") for (int m = 0; m < 4; ++m) _Pragma("unroll") for (int n = 0; n < 2; ++n) _Pragma("unroll") for (int k = 0; k < 2; ++k) \
;         acc[ai][bj][m][n] = __builtin_amdgcn_mfma_f32_16x16x32_bf16(Bt[n][k], At[m][k], acc[ai][bj][m][n], 0, 0, 0); __builtin_amdgcn_s_setprio(0); } while (0)
; template <class Epi, class Sched, bool ALIGN_EPI = false, bool SP2 = false, bool A_TILED = false>
; __device__ __forceinline__ void gemm_phase(PG8_LAS unsigned char* lds, const Gemm g, const Sched& S, const Epi& E, const int wave_s) {
;     ...
;         for (int t = PEEL ? 2 : 0; t < nt; t += 2) {
;             const bool last = (t == nt - 2);
;             const char* a1 = cA + (size_t)(t + 1) * kstepA;
;             const char* a2 = last ? nA : cA + (size_t)(t + 2) * kstepA; const char* b2 = last ? nB : cB + (size_t)(t + 2) * kstep;
;             const char* a3 = a2 + kstepA; const char* b3 = b2 + kstep;
;             if (last && has_next) S.a_ready(nxt);
;             if constexpr (SP2) {
;             PG8_ITER(PG8_MMA)
.LBB0_1043:
	ds_read_b128 v[146:149], v140
	ds_read_b128 v[150:153], v140 offset:1024
	ds_read_b128 v[154:157], v140 offset:2048
	ds_read_b128 v[158:161], v140 offset:3072
	ds_read_b128 v[162:165], v141
	ds_read_b128 v[166:169], v141 offset:1024
	ds_read_b128 v[170:173], v141 offset:2048
	ds_read_b128 v[174:177], v141 offset:3072
	s_add_u32 s52, s62, s39
	s_addc_u32 s53, s63, s40
	s_add_u32 s54, s62, s37
	s_addc_u32 s55, s63, s38
	s_cmp_eq_u32 s41, 28
	s_cselect_b32 s73, s5, s53
	s_cselect_b32 s72, s4, s52
	s_cselect_b32 s71, s1, s55
	s_cselect_b32 s70, s0, s54
	s_mov_b32 m0, s42
	v_lshl_add_u64 v[210:211], s[62:63], 0, v[138:139]
	ds_read_b128 v[178:181], v142
	ds_read_b128 v[182:185], v142 offset:1024
	ds_read_b128 v[186:189], v142 offset:2048
	ds_read_b128 v[190:193], v142 offset:3072
	ds_read_b128 v[194:197], v142 offset:4096
	ds_read_b128 v[198:201], v142 offset:5120
	ds_read_b128 v[202:205], v142 offset:6144
	ds_read_b128 v[206:209], v142 offset:7168
	global_load_lds_dwordx4 v[210:211], off
	v_lshl_add_u64 v[210:211], s[62:63], 0, v[136:137]
	s_mov_b32 m0, s43
	s_nop 0
	global_load_lds_dwordx4 v[210:211], off
	s_waitcnt vmcnt(8) lgkmcnt(0)
	s_barrier
	v_mfma_f32_16x16x32_bf16 v[8:11], v[146:149], v[178:181], v[8:11]
	v_mfma_f32_16x16x32_bf16 v[12:15], v[154:157], v[178:181], v[12:15]
	v_mfma_f32_16x16x32_bf16 v[36:39], v[146:149], v[186:189], v[36:39]
	v_mfma_f32_16x16x32_bf16 v[32:35], v[154:157], v[186:189], v[32:35]
	v_mfma_f32_16x16x32_bf16 v[60:63], v[146:149], v[194:197], v[60:63]
	v_mfma_f32_16x16x32_bf16 v[56:59], v[154:157], v[194:197], v[56:59]
	v_mfma_f32_16x16x32_bf16 v[80:83], v[146:149], v[202:205], v[80:83]
	v_mfma_f32_16x16x32_bf16 v[72:75], v[154:157], v[202:205], v[72:75]
	v_mfma_f32_16x16x32_bf16 v[8:11], v[150:153], v[182:185], v[8:11]
	v_mfma_f32_16x16x32_bf16 v[12:15], v[158:161], v[182:185], v[12:15]
	v_mfma_f32_16x16x32_bf16 v[36:39], v[150:153], v[190:193], v[36:39]
	v_mfma_f32_16x16x32_bf16 v[32:35], v[158:161], v[190:193], v[32:35]
	v_mfma_f32_16x16x32_bf16 v[60:63], v[150:153], v[198:201], v[60:63]
	v_mfma_f32_16x16x32_bf16 v[56:59], v[158:161], v[198:201], v[56:59]
	v_mfma_f32_16x16x32_bf16 v[80:83], v[150:153], v[206:209], v[80:83]
	v_mfma_f32_16x16x32_bf16 v[72:75], v[158:161], v[206:209], v[72:75]
	v_mfma_f32_16x16x32_bf16 v[44:47], v[162:165], v[178:181], v[44:47]
	v_mfma_f32_16x16x32_bf16 v[40:43], v[170:173], v[178:181], v[40:43]
	v_mfma_f32_16x16x32_bf16 v[52:55], v[162:165], v[186:189], v[52:55]
	v_mfma_f32_16x16x32_bf16 v[48:51], v[170:173], v[186:189], v[48:51]
	v_mfma_f32_16x16x32_bf16 v[68:71], v[162:165], v[194:197], v[68:71]
	v_mfma_f32_16x16x32_bf16 v[64:67], v[170:173], v[194:197], v[64:67]
	v_mfma_f32_16x16x32_bf16 v[100:103], v[162:165], v[202:205], v[100:103]
	v_mfma_f32_16x16x32_bf16 v[96:99], v[170:173], v[202:205], v[96:99]
	v_mfma_f32_16x16x32_bf16 v[44:47], v[166:169], v[182:185], v[44:47]
	v_mfma_f32_16x16x32_bf16 v[40:43], v[174:177], v[182:185], v[40:43]
	v_mfma_f32_16x16x32_bf16 v[52:55], v[166:169], v[190:193], v[52:55]
	v_mfma_f32_16x16x32_bf16 v[48:51], v[174:177], v[190:193], v[48:51]
	v_mfma_f32_16x16x32_bf16 v[68:71], v[166:169], v[198:201], v[68:71]
	v_mfma_f32_16x16x32_bf16 v[64:67], v[174:177], v[198:201], v[64:67]
	v_mfma_f32_16x16x32_bf16 v[100:103], v[166:169], v[206:209], v[100:103]
	v_mfma_f32_16x16x32_bf16 v[96:99], v[174:177], v[206:209], v[96:99]
	s_barrier
	s_mov_b32 m0, s44
	v_lshl_add_u64 v[210:211], s[70:71], 0, v[130:131]
	s_add_u32 s52, s70, 0x80000
	ds_read_b128 v[178:181], v142 offset:16384
	ds_read_b128 v[182:185], v142 offset:17408
	ds_read_b128 v[186:189], v142 offset:18432
	ds_read_b128 v[190:193], v142 offset:19456
	ds_read_b128 v[194:197], v142 offset:20480
	ds_read_b128 v[198:201], v142 offset:21504
	ds_read_b128 v[202:205], v142 offset:22528
	ds_read_b128 v[206:209], v142 offset:23552
	global_load_lds_dwordx4 v130, s[70:71]
	v_lshl_add_u64 v[212:213], s[70:71], 0, v[134:135]
	s_mov_b32 m0, s45
	s_addc_u32 s53, s71, 0
	global_load_lds_dwordx4 v134, s[70:71]
	v_lshl_add_u64 v[214:215], s[52:53], 0, v[130:131]
	s_mov_b32 m0, s46
	v_lshl_add_u64 v[216:217], s[72:73], 0, v[132:133]
	global_load_lds_dwordx4 v130, s[52:53]
	v_lshl_add_u64 v[214:215], s[52:53], 0, v[134:135]
	s_mov_b32 m0, s47
	s_nop 0
	global_load_lds_dwordx4 v134, s[52:53]
	v_lshl_add_u64 v[214:215], s[72:73], 0, v[128:129]
	s_mov_b32 m0, s14
	s_nop 0
	global_load_lds_dwordx4 v128, s[72:73]
	s_mov_b32 m0, s15
	s_nop 0
	global_load_lds_dwordx4 v132, s[72:73]
	s_waitcnt vmcnt(8) lgkmcnt(0)
	s_barrier
; #define PG8_MMA(ai, bj, At, Bt) do { __builtin_amdgcn_s_setprio(1); _Pragma("unroll") for (int m = 0; m < 4; ++m) _Pragma("unroll") for (int n = 0; n < 2; ++n) _Pragma("unroll") for (int k = 0; k < 2; ++k) \
;         acc[ai][bj][m][n] = __builtin_amdgcn_mfma_f32_16x16x32_bf16(Bt[n][k], At[m][k], acc[ai][bj][m][n], 0, 0, 0); __builtin_amdgcn_s_setprio(0); } while (0)
; template <class Epi, class Sched, bool ALIGN_EPI = false, bool SP2 = false, bool A_TILED = false>
; __device__ __forceinline__ void gemm_phase(PG8_LAS unsigned char* lds, const Gemm g, const Sched& S, const Epi& E, const int wave_s) {
;     ...
;         for (int t = PEEL ? 2 : 0; t < nt; t += 2) {
;             const bool last = (t == nt - 2);
;             const char* a1 = cA + (size_t)(t + 1) * kstepA;
;             const char* a2 = last ? nA : cA + (size_t)(t + 2) * kstepA; const char* b2 = last ? nB : cB + (size_t)(t + 2) * kstep;
;             const char* a3 = a2 + kstepA; const char* b3 = b2 + kstep;
;             if (last && has_next) S.a_ready(nxt);
;             if constexpr (SP2) {
;             PG8_ITER(PG8_MMA)
	v_mfma_f32_16x16x32_bf16 v[108:111], v[146:149], v[178:181], v[108:111]
	v_mfma_f32_16x16x32_bf16 v[104:107], v[154:157], v[178:181], v[104:107]
	v_mfma_f32_16x16x32_bf16 v[124:127], v[146:149], v[186:189], v[124:127]
	v_mfma_f32_16x16x32_bf16 v[120:123], v[154:157], v[186:189], v[120:123]
	v_mfma_f32_16x16x32_bf16 v[84:87], v[146:149], v[194:197], v[84:87]
	v_mfma_f32_16x16x32_bf16 v[76:79], v[154:157], v[194:197], v[76:79]
	v_mfma_f32_16x16x32_bf16 v[20:23], v[146:149], v[202:205], v[20:23]
	v_mfma_f32_16x16x32_bf16 v[16:19], v[154:157], v[202:205], v[16:19]
	v_mfma_f32_16x16x32_bf16 v[108:111], v[150:153], v[182:185], v[108:111]
	v_mfma_f32_16x16x32_bf16 v[104:107], v[158:161], v[182:185], v[104:107]
	v_mfma_f32_16x16x32_bf16 v[124:127], v[150:153], v[190:193], v[124:127]
	v_mfma_f32_16x16x32_bf16 v[120:123], v[158:161], v[190:193], v[120:123]
	v_mfma_f32_16x16x32_bf16 v[84:87], v[150:153], v[198:201], v[84:87]
	v_mfma_f32_16x16x32_bf16 v[76:79], v[158:161], v[198:201], v[76:79]
	v_mfma_f32_16x16x32_bf16 v[20:23], v[150:153], v[206:209], v[20:23]
	v_mfma_f32_16x16x32_bf16 v[16:19], v[158:161], v[206:209], v[16:19]
	v_mfma_f32_16x16x32_bf16 v[116:119], v[162:165], v[178:181], v[116:119]
	v_mfma_f32_16x16x32_bf16 v[112:115], v[170:173], v[178:181], v[112:115]
	v_mfma_f32_16x16x32_bf16 v[92:95], v[162:165], v[186:189], v[92:95]
	v_mfma_f32_16x16x32_bf16 v[88:91], v[170:173], v[186:189], v[88:91]
	v_mfma_f32_16x16x32_bf16 v[28:31], v[162:165], v[194:197], v[28:31]
	v_mfma_f32_16x16x32_bf16 v[24:27], v[170:173], v[194:197], v[24:27]
	v_mfma_f32_16x16x32_bf16 v[4:7], v[162:165], v[202:205], v[4:7]
	v_mfma_f32_16x16x32_bf16 v[0:3], v[170:173], v[202:205], v[0:3]
	v_mfma_f32_16x16x32_bf16 v[116:119], v[166:169], v[182:185], v[116:119]
	v_mfma_f32_16x16x32_bf16 v[112:115], v[174:177], v[182:185], v[112:115]
	v_mfma_f32_16x16x32_bf16 v[92:95], v[166:169], v[190:193], v[92:95]
	v_mfma_f32_16x16x32_bf16 v[88:91], v[174:177], v[190:193], v[88:91]
	v_mfma_f32_16x16x32_bf16 v[28:31], v[166:169], v[198:201], v[28:31]
	v_mfma_f32_16x16x32_bf16 v[24:27], v[174:177], v[198:201], v[24:27]
	v_mfma_f32_16x16x32_bf16 v[4:7], v[166:169], v[206:209], v[4:7]
	v_mfma_f32_16x16x32_bf16 v[0:3], v[174:177], v[206:209], v[0:3]
	s_barrier
	ds_read_b128 v[146:149], v143
	ds_read_b128 v[150:153], v143 offset:1024
	ds_read_b128 v[154:157], v143 offset:2048
	ds_read_b128 v[158:161], v143 offset:3072
	ds_read_b128 v[162:165], v144
	ds_read_b128 v[166:169], v144 offset:1024
	ds_read_b128 v[170:173], v144 offset:2048
	ds_read_b128 v[174:177], v144 offset:3072
	s_add_u32 s52, s72, 0x80000
	s_addc_u32 s53, s73, 0
	s_mov_b32 m0, s21
	v_lshl_add_u64 v[218:219], s[52:53], 0, v[128:129]
	ds_read_b128 v[178:181], v142 offset:32768
	ds_read_b128 v[182:185], v142 offset:33792
	ds_read_b128 v[186:189], v142 offset:34816
	ds_read_b128 v[190:193], v142 offset:35840
	ds_read_b128 v[194:197], v142 offset:36864
	ds_read_b128 v[198:201], v142 offset:37888
	ds_read_b128 v[202:205], v142 offset:38912
	ds_read_b128 v[206:209], v142 offset:39936
	global_load_lds_dwordx4 v128, s[52:53]
	v_lshl_add_u64 v[218:219], s[52:53], 0, v[132:133]
	s_mov_b32 m0, s22
	s_nop 0
	global_load_lds_dwordx4 v132, s[52:53]
	s_waitcnt vmcnt(8) lgkmcnt(0)
	s_barrier
	v_mfma_f32_16x16x32_bf16 v[8:11], v[146:149], v[178:181], v[8:11]
	v_mfma_f32_16x16x32_bf16 v[12:15], v[154:157], v[178:181], v[12:15]
	v_mfma_f32_16x16x32_bf16 v[36:39], v[146:149], v[186:189], v[36:39]
	v_mfma_f32_16x16x32_bf16 v[32:35], v[154:157], v[186:189], v[32:35]
	v_mfma_f32_16x16x32_bf16 v[60:63], v[146:149], v[194:197], v[60:63]
	v_mfma_f32_16x16x32_bf16 v[56:59], v[154:157], v[194:197], v[56:59]
	v_mfma_f32_16x16x32_bf16 v[80:83], v[146:149], v[202:205], v[80:83]
	v_mfma_f32_16x16x32_bf16 v[72:75], v[154:157], v[202:205], v[72:75]
	v_mfma_f32_16x16x32_bf16 v[8:11], v[150:153], v[182:185], v[8:11]
	v_mfma_f32_16x16x32_bf16 v[12:15], v[158:161], v[182:185], v[12:15]
	v_mfma_f32_16x16x32_bf16 v[36:39], v[150:153], v[190:193], v[36:39]
	v_mfma_f32_16x16x32_bf16 v[32:35], v[158:161], v[190:193], v[32:35]
	v_mfma_f32_16x16x32_bf16 v[60:63], v[150:153], v[198:201], v[60:63]
	v_mfma_f32_16x16x32_bf16 v[56:59], v[158:161], v[198:201], v[56:59]
	v_mfma_f32_16x16x32_bf16 v[80:83], v[150:153], v[206:209], v[80:83]
	v_mfma_f32_16x16x32_bf16 v[72:75], v[158:161], v[206:209], v[72:75]
	v_mfma_f32_16x16x32_bf16 v[44:47], v[162:165], v[178:181], v[44:47]
	v_mfma_f32_16x16x32_bf16 v[40:43], v[170:173], v[178:181], v[40:43]
	v_mfma_f32_16x16x32_bf16 v[52:55], v[162:165], v[186:189], v[52:55]
	v_mfma_f32_16x16x32_bf16 v[48:51], v[170:173], v[186:189], v[48:51]
	v_mfma_f32_16x16x32_bf16 v[68:71], v[162:165], v[194:197], v[68:71]
	v_mfma_f32_16x16x32_bf16 v[64:67], v[170:173], v[194:197], v[64:67]
	v_mfma_f32_16x16x32_bf16 v[100:103], v[162:165], v[202:205], v[100:103]
	v_mfma_f32_16x16x32_bf16 v[96:99], v[170:173], v[202:205], v[96:99]
	v_mfma_f32_16x16x32_bf16 v[44:47], v[166:169], v[182:185], v[44:47]
	v_mfma_f32_16x16x32_bf16 v[40:43], v[174:177], v[182:185], v[40:43]
	v_mfma_f32_16x16x32_bf16 v[52:55], v[166:169], v[190:193], v[52:55]
	v_mfma_f32_16x16x32_bf16 v[48:51], v[174:177], v[190:193], v[48:51]
	v_mfma_f32_16x16x32_bf16 v[68:71], v[166:169], v[198:201], v[68:71]
	v_mfma_f32_16x16x32_bf16 v[64:67], v[174:177], v[198:201], v[64:67]
	v_mfma_f32_16x16x32_bf16 v[100:103], v[166:169], v[206:209], v[100:103]
	v_mfma_f32_16x16x32_bf16 v[96:99], v[174:177], v[206:209], v[96:99]
	s_barrier
; template <class Epi, class Sched, bool ALIGN_EPI = false, bool SP2 = false, bool A_TILED = false>
; __device__ __forceinline__ void gemm_phase(PG8_LAS unsigned char* lds, const Gemm g, const Sched& S, const Epi& E, const int wave_s) {
;     ...
;         for (int t = PEEL ? 2 : 0; t < nt; t += 2) {
;             const bool last = (t == nt - 2);
;             const char* a1 = cA + (size_t)(t + 1) * kstepA;
;             const char* a2 = last ? nA : cA + (size_t)(t + 2) * kstepA; const char* b2 = last ? nB : cB + (size_t)(t + 2) * kstep;
;             const char* a3 = a2 + kstepA; const char* b3 = b2 + kstep;
;             if (last && has_next) S.a_ready(nxt);
;             if constexpr (SP2) {
;             PG8_ITER(PG8_MMA)
;             } else {
;             PG8_LDB(B0, 0, 0); PG8_SCHED; PG8_LDA(At, 0, 0); PG8_STAGE(PG8_SA(1, 1), a1 + hstepA, voffA);
;             PG8_WAIT_L(8); PG8_BAR; PG8_WAIT_L(0); PG8_MMA(0, 0, At, B0); PG8_BAR; PG8_SCHED;
;             PG8_LDB(B1, 0, 1); PG8_STAGE(PG8_SB(0, 0), b2, voffB);
;             PG8_BAR; PG8_WAIT_L(0); PG8_MMA(0, 1, At, B1); PG8_BAR;
;             PG8_LDA(At, 0, 1); PG8_STAGE(PG8_SA(0, 0), a2, voffA);
;             PG8_BAR; PG8_WAIT_L(0); PG8_MMA(1, 0, At, B0); PG8_BAR; PG8_SCHED;
;             PG8_STAGE(PG8_SB(0, 1), b2 + hstep, voffB);
;             PG8_WAIT_V(6); PG8_BAR; PG8_MMA(1, 1, At, B1); PG8_BAR;
;             PG8_LDB(B0, 1, 0); PG8_SCHED; PG8_LDA(At, 1, 0); PG8_STAGE(PG8_SA(0, 1), a2 + hstepA, voffA);
;             PG8_WAIT_L(8); PG8_BAR; PG8_WAIT_L(0); PG8_MMA(0, 0, At, B0); PG8_BAR; PG8_SCHED;
;             PG8_LDB(B1, 1, 1); PG8_STAGE(PG8_SB(1, 0), b3, voffB);
;             PG8_BAR; PG8_WAIT_L(0); PG8_MMA(0, 1, At, B1); PG8_BAR;
;             PG8_LDA(At, 1, 1); PG8_STAGE(PG8_SA(1, 0), a3, voffA);
;             PG8_BAR; PG8_WAIT_L(0); PG8_MMA(1, 0, At, B0); PG8_BAR; PG8_SCHED;
;             PG8_STAGE(PG8_SB(1, 1), b3 + hstep, voffB);
;             PG8_WAIT_V(6); PG8_BAR; PG8_MMA(1, 1, At, B1); PG8_BAR;
;             }
;         }
;         if constexpr (ALIGN_EPI) { if (wr == 0) PG8_BAR; }
;         if constexpr (!Epi::AFTER_DRAIN) { int te = tid_now(wave_s); asm volatile("" : "+v"(te));
;             E(acc, cur, wr, wc, te & 15, (te & 63) >> 4); S.done(cur); }
;         if (!has_next) break;
;         cur = nxt; cA = nA; cB = nB; ++ui;
;         if constexpr (ALIGN_EPI) { if (wr == 1) PG8_BAR; }
	s_mov_b32 m0, s48
	v_lshl_add_u64 v[210:211], v[210:211], 0, s[66:67]
	s_add_u32 s52, s70, 0x80080
	ds_read_b128 v[178:181], v142 offset:49152
	ds_read_b128 v[182:185], v142 offset:50176
	ds_read_b128 v[186:189], v142 offset:51200
	ds_read_b128 v[190:193], v142 offset:52224
	ds_read_b128 v[194:197], v142 offset:53248
	ds_read_b128 v[198:201], v142 offset:54272
	ds_read_b128 v[202:205], v142 offset:55296
	ds_read_b128 v[206:209], v142 offset:56320
	global_load_lds_dwordx4 v[210:211], off
	v_lshl_add_u64 v[210:211], v[212:213], 0, s[66:67]
	s_mov_b32 m0, s49
	s_addc_u32 s53, s71, 0
	global_load_lds_dwordx4 v[210:211], off
	v_lshl_add_u64 v[210:211], s[52:53], 0, v[130:131]
	s_mov_b32 m0, s50
	s_nop 0
	global_load_lds_dwordx4 v130, s[52:53]
	v_lshl_add_u64 v[210:211], s[52:53], 0, v[134:135]
	s_mov_b32 m0, s51
	s_nop 0
	global_load_lds_dwordx4 v134, s[52:53]
	v_lshl_add_u64 v[210:211], v[214:215], 0, s[66:67]
	s_mov_b32 m0, s23
	s_nop 0
	global_load_lds_dwordx4 v[210:211], off
	v_lshl_add_u64 v[210:211], v[216:217], 0, s[66:67]
	s_mov_b32 m0, s36
	s_nop 0
	global_load_lds_dwordx4 v[210:211], off
	s_waitcnt vmcnt(8) lgkmcnt(0)
	s_barrier
	v_mfma_f32_16x16x32_bf16 v[108:111], v[146:149], v[178:181], v[108:111]
	v_mfma_f32_16x16x32_bf16 v[104:107], v[154:157], v[178:181], v[104:107]
	v_mfma_f32_16x16x32_bf16 v[124:127], v[146:149], v[186:189], v[124:127]
	v_mfma_f32_16x16x32_bf16 v[120:123], v[154:157], v[186:189], v[120:123]
	v_mfma_f32_16x16x32_bf16 v[84:87], v[146:149], v[194:197], v[84:87]
	v_mfma_f32_16x16x32_bf16 v[76:79], v[154:157], v[194:197], v[76:79]
	v_mfma_f32_16x16x32_bf16 v[20:23], v[146:149], v[202:205], v[20:23]
	v_mfma_f32_16x16x32_bf16 v[16:19], v[154:157], v[202:205], v[16:19]
	v_mfma_f32_16x16x32_bf16 v[108:111], v[150:153], v[182:185], v[108:111]
	v_mfma_f32_16x16x32_bf16 v[104:107], v[158:161], v[182:185], v[104:107]
	v_mfma_f32_16x16x32_bf16 v[124:127], v[150:153], v[190:193], v[124:127]
	v_mfma_f32_16x16x32_bf16 v[120:123], v[158:161], v[190:193], v[120:123]
	v_mfma_f32_16x16x32_bf16 v[84:87], v[150:153], v[198:201], v[84:87]
	v_mfma_f32_16x16x32_bf16 v[76:79], v[158:161], v[198:201], v[76:79]
	v_mfma_f32_16x16x32_bf16 v[20:23], v[150:153], v[206:209], v[20:23]
	v_mfma_f32_16x16x32_bf16 v[16:19], v[158:161], v[206:209], v[16:19]
	v_mfma_f32_16x16x32_bf16 v[116:119], v[162:165], v[178:181], v[116:119]
	v_mfma_f32_16x16x32_bf16 v[112:115], v[170:173], v[178:181], v[112:115]
	v_mfma_f32_16x16x32_bf16 v[92:95], v[162:165], v[186:189], v[92:95]
	v_mfma_f32_16x16x32_bf16 v[88:91], v[170:173], v[186:189], v[88:91]
	v_mfma_f32_16x16x32_bf16 v[28:31], v[162:165], v[194:197], v[28:31]
	v_mfma_f32_16x16x32_bf16 v[24:27], v[170:173], v[194:197], v[24:27]
	v_mfma_f32_16x16x32_bf16 v[4:7], v[162:165], v[202:205], v[4:7]
	v_mfma_f32_16x16x32_bf16 v[0:3], v[170:173], v[202:205], v[0:3]
	v_mfma_f32_16x16x32_bf16 v[116:119], v[166:169], v[182:185], v[116:119]
	v_mfma_f32_16x16x32_bf16 v[112:115], v[174:177], v[182:185], v[112:115]
	v_mfma_f32_16x16x32_bf16 v[92:95], v[166:169], v[190:193], v[92:95]
	v_mfma_f32_16x16x32_bf16 v[88:91], v[174:177], v[190:193], v[88:91]
	v_mfma_f32_16x16x32_bf16 v[28:31], v[166:169], v[198:201], v[28:31]
	v_mfma_f32_16x16x32_bf16 v[24:27], v[174:177], v[198:201], v[24:27]
	v_mfma_f32_16x16x32_bf16 v[4:7], v[166:169], v[206:209], v[4:7]
	v_mfma_f32_16x16x32_bf16 v[0:3], v[174:177], v[206:209], v[0:3]
	s_barrier
	s_add_i32 s41, s41, 2
	s_add_u32 s37, s37, 0x100
	s_addc_u32 s38, s38, 0
	s_add_u32 s39, s39, 0x100
	s_addc_u32 s40, s40, 0
	v_lshl_add_u64 v[136:137], v[136:137], 0, s[68:69]
	s_cmp_gt_u32 s41, 29
	v_lshl_add_u64 v[138:139], v[138:139], 0, s[68:69]
	s_cbranch_scc0 .LBB0_1043
	s_waitcnt vmcnt(0)
	s_cmpk_lt_u32 s6, 0x100
	s_cbranch_scc0 .LBB0_1046
	s_barrier

; __device__ __forceinline__ int tid_now(int wave_s) { unsigned z = 0u; asm volatile("" : "+v"(z)); return (wave_s << 6) | (int)__builtin_amdgcn_mbcnt_hi(~0u, __builtin_amdgcn_mbcnt_lo(~0u, z)); }
; __device__ __forceinline__ unsigned xb_add(unsigned* p, unsigned v) { return __hip_atomic_fetch_add(p, v, __ATOMIC_RELAXED, __HIP_MEMORY_SCOPE_AGENT); }
; __device__ __forceinline__ void xcd_barrier(const XcdBarrier& b) {
;     asm volatile("s_waitcnt vmcnt(0)" ::: "memory");
;     __syncthreads();
;     if (tid_now(b.w) == 0) {
;         unsigned* bar = b.bar;
;         __builtin_amdgcn_s_waitcnt(0);
;         unsigned nloc = b.st[0], nx = b.st[1];
;         if (nloc == 0u) { xcd_barrier_complete(bar, b.x, nloc, nx, b.np); b.st[0] = nloc; b.st[1] = nx; }
;         const unsigned old = xb_add(&bar[XB_XSUB(b.x)], 1u);
.LBB0_1087:
	s_setprio 0
	s_cmp_gt_i32 s35, 5
	s_cselect_b64 s[0:1], -1, 0
	s_and_b64 s[2:3], s[60:61], s[0:1]
	s_andn2_b64 vcc, exec, s[2:3]
	s_cbranch_vccnz .LBB0_1141
	s_waitcnt vmcnt(0)
	v_mov_b32_e32 v0, 0
	s_waitcnt vmcnt(0)
	s_waitcnt lgkmcnt(0)
	s_barrier
	s_nop 0
	v_mbcnt_lo_u32_b32 v0, -1, v0
	v_mbcnt_hi_u32_b32 v0, -1, v0
	v_or_b32_e32 v0, s33, v0
	v_cmp_eq_u32_e32 vcc, 0, v0
	s_and_saveexec_b64 s[2:3], vcc
	s_cbranch_execz .LBB0_1140
	s_add_i32 s4, 0, 0x27f68
	v_mov_b32_e32 v0, s4
	s_waitcnt vmcnt(0) expcnt(0) lgkmcnt(0)
	ds_read_b32 v2, v0
	s_add_i32 s4, 0, 0x27f6c
	v_mov_b32_e32 v0, s4
	ds_read_b32 v0, v0
	s_waitcnt lgkmcnt(1)
	v_cmp_ne_u32_e32 vcc, 0, v2
	s_cbranch_vccnz .LBB0_1104
	s_add_u32 s4, s10, 0x1000
	s_addc_u32 s5, s11, 0
	s_add_u32 s12, s10, 0x1100
	s_addc_u32 s13, s11, 0
	s_add_u32 s60, s10, 0x1200
	s_addc_u32 s61, s11, 0
	s_add_u32 s62, s10, 0x1300
	s_addc_u32 s63, s11, 0
	s_mov_b32 s6, 1
	v_mov_b32_e32 v16, 0
	s_branch .LBB0_1092

; #define PG8_STAGE(bufoff, gbase, voff) do { _Pragma("unroll") for (int _i = 0; _i < 2; ++_i) \
;         __builtin_amdgcn_global_load_lds((const unsigned*)((const char*)(gbase) + (voff)[_i]), (PG8_LAS unsigned*)(lds + (bufoff) + ldsw + _i * 8192), 16, 0, 0); } while (0)
; #define PG8_WAIT_V(n) asm volatile("s_waitcnt vmcnt(" #n ")" ::: "memory")
; #define PG8_BAR __builtin_amdgcn_s_barrier()
; template <class Epi, class Sched, bool ALIGN_EPI = false, bool SP2 = false, bool A_TILED = false>
; __device__ __forceinline__ void gemm_phase(PG8_LAS unsigned char* lds, const Gemm g, const Sched& S, const Epi& E, const int wave_s) {
;     ...
;     for (int i = 0; i < 2; ++i) { int R, C; stage_rc(tid * 16 + i * 8192, R, C); const int Rb = Epi::PERM ? ((R & ~31) + perm32(R & 31)) : R;
;         voffA[i] = A_TILED ? (unsigned)(tid * 16 + i * 8192) : (unsigned)(R * K + C) * 2u; voffB[i] = (unsigned)(Rb * K + C) * 2u; }
;     const size_t kstep = (size_t)(BK * 2);
;     const size_t hstep = (size_t)HALF * K * 2;
;     const size_t tstep = 2 * hstep;
;     const size_t kstepA = A_TILED ? (size_t)32768 : kstep, hstepA = A_TILED ? (size_t)16384 : hstep, tstepA = A_TILED ? (size_t)nt * 32768 : tstep;
;     const unsigned ldsw = (unsigned)wid * 1024u;
;     const int aoff = lds_byte(wr * 64 + fr, fq * 8), boff = lds_byte(wc * 32 + fr, fq * 8);
;     ...
;     if constexpr (SP2) {
;         PG8_STAGE(PG8_SB(0, 0), cB, voffB); PG8_STAGE(PG8_SB(0, 1), cB + hstep, voffB); PG8_STAGE(PG8_SA(0, 0), cA, voffA); PG8_STAGE(PG8_SA(0, 1), cA + hstepA, voffA);
;         if (wr == 1) PG8_BAR;
;         PG8_WAIT_V(2); PG8_BAR;
;         PG8_STAGE(PG8_SB(1, 0), cB + kstep, voffB); PG8_STAGE(PG8_SA(1, 0), cA + kstepA, voffA); PG8_STAGE(PG8_SB(1, 1), cB + hstep + kstep, voffB);
;         PG8_WAIT_V(6); PG8_BAR;
.LBB0_1145:
	s_ashr_i32 s40, s86, 31
	s_add_u32 s41, s0, 0x34600000
	s_addc_u32 s42, s1, 0
	s_lshl_b32 s47, s12, 13
	s_mov_b64 s[12:13], 0x80
	s_and_b32 s0, s46, 3
	s_add_i32 m0, s22, 0x18000
	v_lshl_add_u64 v[6:7], v[6:7], 0, s[12:13]
	s_lshl_b32 s48, s0, 12
	s_waitcnt vmcnt(2)
	s_barrier
	global_load_lds_dwordx4 v[6:7], off
	v_lshl_add_u64 v[4:5], v[4:5], 0, s[12:13]
	s_add_i32 m0, s22, 0x1a000
	s_add_i32 s43, s22, 0x8000
	s_add_i32 s44, s22, 0xa000
	global_load_lds_dwordx4 v[4:5], off
	v_lshl_add_u64 v[0:1], v[0:1], 0, s[12:13]
	s_mov_b32 m0, s43
	s_add_u32 s0, s76, 0x80080
	global_load_lds_dwordx4 v[0:1], off
	v_lshl_add_u64 v[0:1], v[2:3], 0, s[12:13]
	s_mov_b32 m0, s44
	s_addc_u32 s1, s77, 0
	global_load_lds_dwordx4 v[0:1], off
	s_add_i32 m0, s22, 0x1c000
	v_lshl_add_u64 v[0:1], s[0:1], 0, v[128:129]
	global_load_lds_dwordx4 v128, s[0:1]
	v_lshl_add_u64 v[0:1], s[0:1], 0, v[130:131]
	s_add_i32 m0, s22, 0x1e000
	s_cmpk_lt_u32 s45, 0x100
	global_load_lds_dwordx4 v130, s[0:1]
	v_and_b32_e32 v0, 15, v8
	v_and_b32_e32 v1, 48, v8
	v_lshl_or_b32 v0, v0, 6, v1
	v_lshlrev_b32_e32 v1, 2, v8
	v_and_b32_e32 v1, 32, v1
	v_bitop3_b32 v2, v0, s47, v1 bitop3:0xde
	v_bitop3_b32 v144, v0, s48, v1 bitop3:0xde
	v_lshlrev_b32_e32 v0, 15, v9
	v_and_b32_e32 v0, 0xffff0000, v0
	v_lshl_add_u32 v0, v10, 12, v0
	v_and_b32_e32 v1, 1, v9
	v_lshl_or_b32 v0, v1, 6, v0
	v_lshl_add_u32 v136, v11, 1, v0
	v_lshlrev_b32_e32 v0, 15, v13
	v_and_b32_e32 v0, 0xffff0000, v0
	s_sext_i32_i16 s49, s60
	s_waitcnt vmcnt(6)
	s_mov_b32 s98, 0
	s_cselect_b64 s[60:61], -1, 0
	s_bitcmp1_b32 s33, 8
	s_cbranch_scc1 .Lsp_3
	s_setprio 1
.Lsp_3:
	s_and_b32 s0, s15, 0x400
	v_lshl_add_u32 v0, v12, 12, v0
	v_and_b32_e32 v1, 1, v13
	s_bfe_u32 s45, s46, 0x10001
	s_or_b32 s46, s0, s47
	v_mov_b32_e32 v137, 0
	v_lshl_or_b32 v0, v1, 6, v0
	s_add_i32 s47, 0, 0x10000
	s_add_i32 s48, 0, 0x14000
	v_lshl_add_u32 v138, v14, 1, v0
	v_mov_b32_e32 v139, v137
	v_mov_b64_e32 v[140:141], 0x200
	v_mov_b64_e32 v[142:143], 0x1ff
	v_add_u32_e32 v145, s47, v144
	v_add_u32_e32 v146, s48, v144
	v_add_u32_e32 v147, 0, v2
	s_mov_b64 s[62:63], 0x100
	s_mov_b64 s[64:65], 0x180
	s_barrier
	s_branch .LBB0_1148

; template <class Epi, class Sched, bool ALIGN_EPI = false, bool SP2 = false, bool A_TILED = false>
; __device__ __forceinline__ void gemm_phase(PG8_LAS unsigned char* lds, const Gemm g, const Sched& S, const Epi& E, const int wave_s) {
;     ...
;         constexpr bool PEEL = SP2 && !Epi::AFTER_DRAIN;
;         if constexpr (PEEL) {
;             const char* a1 = cA + kstepA; const char* a2 = cA + 2 * kstepA; const char* b2 = cB + 2 * kstep; const char* a3 = a2 + kstepA; const char* b3 = b2 + kstep;
;             PG8_ITER(PG8_MMAZ)
.Lpw_3:
	s_barrier
	v_mfma_f32_16x16x32_bf16 v[88:91], v[0:3], v[56:59], 0
	v_mfma_f32_16x16x32_bf16 v[64:67], v[0:3], v[32:35], 0
	v_mfma_f32_16x16x32_bf16 v[68:71], v[8:11], v[32:35], 0
	v_mfma_f32_16x16x32_bf16 v[72:75], v[0:3], v[40:43], 0
	v_mfma_f32_16x16x32_bf16 v[76:79], v[8:11], v[40:43], 0
	v_mfma_f32_16x16x32_bf16 v[80:83], v[0:3], v[48:51], 0
	v_mfma_f32_16x16x32_bf16 v[84:87], v[8:11], v[48:51], 0
	v_mfma_f32_16x16x32_bf16 v[96:99], v[4:7], v[60:63], v[88:91]
	v_mfma_f32_16x16x32_bf16 v[88:91], v[8:11], v[56:59], 0
	v_mfma_f32_16x16x32_bf16 v[64:67], v[4:7], v[36:39], v[64:67]
	v_mfma_f32_16x16x32_bf16 v[68:71], v[12:15], v[36:39], v[68:71]
	v_mfma_f32_16x16x32_bf16 v[72:75], v[4:7], v[44:47], v[72:75]
	v_mfma_f32_16x16x32_bf16 v[76:79], v[12:15], v[44:47], v[76:79]
	v_mfma_f32_16x16x32_bf16 v[80:83], v[4:7], v[52:55], v[80:83]
	v_mfma_f32_16x16x32_bf16 v[84:87], v[12:15], v[52:55], v[84:87]
	v_mfma_f32_16x16x32_bf16 v[100:103], v[12:15], v[60:63], v[88:91]
	v_mfma_f32_16x16x32_bf16 v[88:91], v[16:19], v[32:35], 0
	v_mfma_f32_16x16x32_bf16 v[32:35], v[24:27], v[32:35], 0
	v_mfma_f32_16x16x32_bf16 v[112:115], v[20:23], v[36:39], v[88:91]
	v_mfma_f32_16x16x32_bf16 v[32:35], v[28:31], v[36:39], v[32:35]
	v_mfma_f32_16x16x32_bf16 v[36:39], v[16:19], v[40:43], 0
	v_mfma_f32_16x16x32_bf16 v[40:43], v[24:27], v[40:43], 0
	v_mfma_f32_16x16x32_bf16 v[36:39], v[20:23], v[44:47], v[36:39]
	v_mfma_f32_16x16x32_bf16 v[40:43], v[28:31], v[44:47], v[40:43]
	v_mfma_f32_16x16x32_bf16 v[44:47], v[16:19], v[48:51], 0
	v_mfma_f32_16x16x32_bf16 v[48:51], v[24:27], v[48:51], 0
	v_mfma_f32_16x16x32_bf16 v[44:47], v[20:23], v[52:55], v[44:47]
	v_mfma_f32_16x16x32_bf16 v[48:51], v[28:31], v[52:55], v[48:51]
	v_mfma_f32_16x16x32_bf16 v[52:55], v[16:19], v[56:59], 0
	v_mfma_f32_16x16x32_bf16 v[56:59], v[24:27], v[56:59], 0
	v_mfma_f32_16x16x32_bf16 v[52:55], v[20:23], v[60:63], v[52:55]
	v_mfma_f32_16x16x32_bf16 v[56:59], v[28:31], v[60:63], v[56:59]
	s_barrier
	s_add_i32 s56, s47, s15
	v_lshl_add_u64 v[242:243], s[76:77], 0, v[128:129]
	s_add_i32 s57, s56, 0x2000
	v_lshl_add_u64 v[148:149], v[242:243], 0, s[62:63]
	s_mov_b32 m0, s56
	v_lshl_add_u64 v[244:245], s[76:77], 0, v[130:131]
	s_add_u32 s80, s76, 0x80100
	ds_read_b128 v[60:63], v147 offset:16384
	ds_read_b128 v[88:91], v147 offset:17408
	ds_read_b128 v[92:95], v147 offset:18432
	ds_read_b128 v[104:107], v147 offset:19456
	ds_read_b128 v[108:111], v147 offset:20480
	ds_read_b128 v[116:119], v147 offset:21504
	ds_read_b128 v[120:123], v147 offset:22528
	ds_read_b128 v[124:127], v147 offset:23552
	global_load_lds_dwordx4 v[148:149], off
	v_lshl_add_u64 v[148:149], v[244:245], 0, s[62:63]
	s_mov_b32 m0, s57
	s_addc_u32 s81, s77, 0
	s_add_i32 s58, s48, s15
	global_load_lds_dwordx4 v[148:149], off
	v_lshl_add_u64 v[148:149], s[80:81], 0, v[128:129]
	s_mov_b32 m0, s58
	s_add_i32 s59, s58, 0x2000
	global_load_lds_dwordx4 v128, s[80:81]
	v_lshl_add_u64 v[148:149], s[80:81], 0, v[130:131]
	s_mov_b32 m0, s59
	v_lshl_add_u64 v[246:247], s[78:79], 0, v[134:135]
	global_load_lds_dwordx4 v130, s[80:81]
	v_lshl_add_u64 v[148:149], v[246:247], 0, s[62:63]
	s_mov_b32 m0, s22
	v_lshl_add_u64 v[248:249], s[78:79], 0, v[132:133]
	global_load_lds_dwordx4 v[148:149], off
	v_lshl_add_u64 v[148:149], v[248:249], 0, s[62:63]
	s_mov_b32 m0, s23
	s_nop 0
	global_load_lds_dwordx4 v[148:149], off
	s_waitcnt vmcnt(24) lgkmcnt(0)
	s_cmp_lg_u32 s98, 0
	s_cbranch_scc1 .Lpw_4
	s_waitcnt vmcnt(8)
.Lpw_4:
	s_barrier
	v_mfma_f32_16x16x32_bf16 v[148:151], v[0:3], v[60:63], 0
	v_mfma_f32_16x16x32_bf16 v[158:161], v[0:3], v[92:95], 0
	v_mfma_f32_16x16x32_bf16 v[166:169], v[0:3], v[108:111], 0
	v_mfma_f32_16x16x32_bf16 v[0:3], v[0:3], v[120:123], 0
	v_mfma_f32_16x16x32_bf16 v[150:153], v[4:7], v[88:91], v[148:151]
	v_mfma_f32_16x16x32_bf16 v[158:161], v[4:7], v[104:107], v[158:161]
	v_mfma_f32_16x16x32_bf16 v[166:169], v[4:7], v[116:119], v[166:169]
	v_mfma_f32_16x16x32_bf16 v[0:3], v[4:7], v[124:127], v[0:3]
	v_mfma_f32_16x16x32_bf16 v[4:7], v[8:11], v[120:123], 0
	v_mfma_f32_16x16x32_bf16 v[154:157], v[8:11], v[60:63], 0
	v_mfma_f32_16x16x32_bf16 v[162:165], v[8:11], v[92:95], 0
	v_mfma_f32_16x16x32_bf16 v[170:173], v[8:11], v[108:111], 0
	v_mfma_f32_16x16x32_bf16 v[4:7], v[12:15], v[124:127], v[4:7]
	v_mfma_f32_16x16x32_bf16 v[154:157], v[12:15], v[88:91], v[154:157]
	v_mfma_f32_16x16x32_bf16 v[162:165], v[12:15], v[104:107], v[162:165]
	v_mfma_f32_16x16x32_bf16 v[170:173], v[12:15], v[116:119], v[170:173]
	v_mfma_f32_16x16x32_bf16 v[8:11], v[16:19], v[60:63], 0
	v_mfma_f32_16x16x32_bf16 v[174:177], v[20:23], v[88:91], v[8:11]
	v_mfma_f32_16x16x32_bf16 v[8:11], v[24:27], v[60:63], 0
	v_mfma_f32_16x16x32_bf16 v[60:63], v[28:31], v[88:91], v[8:11]
	v_mfma_f32_16x16x32_bf16 v[8:11], v[16:19], v[92:95], 0
	v_mfma_f32_16x16x32_bf16 v[178:181], v[20:23], v[104:107], v[8:11]
	v_mfma_f32_16x16x32_bf16 v[8:11], v[24:27], v[92:95], 0
	v_mfma_f32_16x16x32_bf16 v[182:185], v[28:31], v[104:107], v[8:11]
	v_mfma_f32_16x16x32_bf16 v[8:11], v[16:19], v[108:111], 0
	v_mfma_f32_16x16x32_bf16 v[186:189], v[20:23], v[116:119], v[8:11]
	v_mfma_f32_16x16x32_bf16 v[8:11], v[24:27], v[108:111], 0
	v_mfma_f32_16x16x32_bf16 v[190:193], v[28:31], v[116:119], v[8:11]
	v_mfma_f32_16x16x32_bf16 v[8:11], v[16:19], v[120:123], 0
	v_mfma_f32_16x16x32_bf16 v[194:197], v[20:23], v[124:127], v[8:11]
	v_mfma_f32_16x16x32_bf16 v[8:11], v[24:27], v[120:123], 0
	v_mfma_f32_16x16x32_bf16 v[198:201], v[28:31], v[124:127], v[8:11]
	s_barrier
; template <class Epi, class Sched, bool ALIGN_EPI = false, bool SP2 = false, bool A_TILED = false>
; __device__ __forceinline__ void gemm_phase(PG8_LAS unsigned char* lds, const Gemm g, const Sched& S, const Epi& E, const int wave_s) {
;     ...
;         constexpr bool PEEL = SP2 && !Epi::AFTER_DRAIN;
;         if constexpr (PEEL) {
;             const char* a1 = cA + kstepA; const char* a2 = cA + 2 * kstepA; const char* b2 = cB + 2 * kstep; const char* a3 = a2 + kstepA; const char* b3 = b2 + kstep;
;             PG8_ITER(PG8_MMAZ)
	s_add_i32 s67, 0, 0x18000
	s_add_i32 s75, 0, 0x1c000
	v_add_u32_e32 v148, s67, v144
	v_add_u32_e32 v149, s75, v144
	s_nop 0
	ds_read_b128 v[8:11], v148
	ds_read_b128 v[12:15], v148 offset:1024
	ds_read_b128 v[16:19], v148 offset:2048
	ds_read_b128 v[20:23], v148 offset:3072
	ds_read_b128 v[202:205], v149
	ds_read_b128 v[206:209], v149 offset:1024
	ds_read_b128 v[210:213], v149 offset:2048
	ds_read_b128 v[214:217], v149 offset:3072
	s_add_u32 s80, s78, 0x80100
	s_addc_u32 s81, s79, 0
	s_mov_b32 m0, s36
	v_lshl_add_u64 v[88:89], s[80:81], 0, v[134:135]
	ds_read_b128 v[24:27], v147 offset:32768
	ds_read_b128 v[28:31], v147 offset:33792
	ds_read_b128 v[218:221], v147 offset:34816
	ds_read_b128 v[222:225], v147 offset:35840
	ds_read_b128 v[226:229], v147 offset:36864
	ds_read_b128 v[230:233], v147 offset:37888
	ds_read_b128 v[234:237], v147 offset:38912
	ds_read_b128 v[238:241], v147 offset:39936
	global_load_lds_dwordx4 v134, s[80:81]
	v_lshl_add_u64 v[88:89], s[80:81], 0, v[132:133]
	s_mov_b32 m0, s37
	s_nop 0
	global_load_lds_dwordx4 v132, s[80:81]
	s_waitcnt vmcnt(8) lgkmcnt(0)
	s_barrier
	v_mfma_f32_16x16x32_bf16 v[64:67], v[8:11], v[24:27], v[64:67]
	v_mfma_f32_16x16x32_bf16 v[120:123], v[12:15], v[28:31], v[64:67]
	v_mfma_f32_16x16x32_bf16 v[64:67], v[16:19], v[24:27], v[68:71]
	v_mfma_f32_16x16x32_bf16 v[124:127], v[20:23], v[28:31], v[64:67]
	v_mfma_f32_16x16x32_bf16 v[64:67], v[8:11], v[218:221], v[72:75]
	v_mfma_f32_16x16x32_bf16 v[104:107], v[12:15], v[222:225], v[64:67]
	v_mfma_f32_16x16x32_bf16 v[64:67], v[16:19], v[218:221], v[76:79]
	v_mfma_f32_16x16x32_bf16 v[108:111], v[20:23], v[222:225], v[64:67]
	v_mfma_f32_16x16x32_bf16 v[64:67], v[8:11], v[226:229], v[80:83]
	v_mfma_f32_16x16x32_bf16 v[88:91], v[12:15], v[230:233], v[64:67]
	v_mfma_f32_16x16x32_bf16 v[64:67], v[16:19], v[226:229], v[84:87]
	v_mfma_f32_16x16x32_bf16 v[92:95], v[20:23], v[230:233], v[64:67]
	v_mfma_f32_16x16x32_bf16 v[64:67], v[8:11], v[234:237], v[96:99]
	v_mfma_f32_16x16x32_bf16 v[68:71], v[16:19], v[234:237], v[100:103]
	v_mfma_f32_16x16x32_bf16 v[64:67], v[12:15], v[238:241], v[64:67]
	v_mfma_f32_16x16x32_bf16 v[68:71], v[20:23], v[238:241], v[68:71]
	v_mfma_f32_16x16x32_bf16 v[72:75], v[202:205], v[24:27], v[112:115]
	v_mfma_f32_16x16x32_bf16 v[24:27], v[210:213], v[24:27], v[32:35]
	v_mfma_f32_16x16x32_bf16 v[116:119], v[214:217], v[28:31], v[24:27]
	v_mfma_f32_16x16x32_bf16 v[24:27], v[202:205], v[218:221], v[36:39]
	v_mfma_f32_16x16x32_bf16 v[96:99], v[206:209], v[222:225], v[24:27]
	v_mfma_f32_16x16x32_bf16 v[24:27], v[210:213], v[218:221], v[40:43]
	v_mfma_f32_16x16x32_bf16 v[100:103], v[214:217], v[222:225], v[24:27]
	v_mfma_f32_16x16x32_bf16 v[24:27], v[202:205], v[226:229], v[44:47]
	v_mfma_f32_16x16x32_bf16 v[80:83], v[206:209], v[230:233], v[24:27]
	v_mfma_f32_16x16x32_bf16 v[24:27], v[210:213], v[226:229], v[48:51]
	v_mfma_f32_16x16x32_bf16 v[84:87], v[214:217], v[230:233], v[24:27]
	v_mfma_f32_16x16x32_bf16 v[24:27], v[202:205], v[234:237], v[52:55]
	v_mfma_f32_16x16x32_bf16 v[48:51], v[206:209], v[238:241], v[24:27]
	v_mfma_f32_16x16x32_bf16 v[24:27], v[210:213], v[234:237], v[56:59]
	v_mfma_f32_16x16x32_bf16 v[112:115], v[206:209], v[28:31], v[72:75]
	v_mfma_f32_16x16x32_bf16 v[52:55], v[214:217], v[238:241], v[24:27]
	s_barrier
	s_add_i32 s67, s67, s15
	s_add_i32 s69, s67, 0x2000
	s_nop 1
	v_lshl_add_u64 v[24:25], v[242:243], 0, s[64:65]
	s_mov_b32 m0, s67
	s_add_u32 s80, s76, 0x80180
	ds_read_b128 v[32:35], v147 offset:49152
	ds_read_b128 v[36:39], v147 offset:50176
	ds_read_b128 v[218:221], v147 offset:51200
	ds_read_b128 v[222:225], v147 offset:52224
	ds_read_b128 v[226:229], v147 offset:53248
	ds_read_b128 v[230:233], v147 offset:54272
	ds_read_b128 v[234:237], v147 offset:55296
	ds_read_b128 v[238:241], v147 offset:56320
	global_load_lds_dwordx4 v[24:25], off
	v_lshl_add_u64 v[24:25], v[244:245], 0, s[64:65]
	s_mov_b32 m0, s69
	s_addc_u32 s81, s77, 0
	s_add_i32 s75, s75, s15
	global_load_lds_dwordx4 v[24:25], off
	v_lshl_add_u64 v[24:25], s[80:81], 0, v[128:129]
	s_mov_b32 m0, s75
	s_add_i32 s82, s75, 0x2000
	global_load_lds_dwordx4 v128, s[80:81]
	v_lshl_add_u64 v[24:25], s[80:81], 0, v[130:131]
	s_mov_b32 m0, s82
	s_nop 0
	global_load_lds_dwordx4 v130, s[80:81]
	v_lshl_add_u64 v[24:25], v[246:247], 0, s[64:65]
	s_mov_b32 m0, s43
	s_nop 0
	global_load_lds_dwordx4 v[24:25], off
	v_lshl_add_u64 v[24:25], v[248:249], 0, s[64:65]
	s_mov_b32 m0, s44
	s_nop 0
	global_load_lds_dwordx4 v[24:25], off
	s_waitcnt vmcnt(8) lgkmcnt(0)
	s_barrier
	v_mfma_f32_16x16x32_bf16 v[24:27], v[8:11], v[32:35], v[150:153]
	v_mfma_f32_16x16x32_bf16 v[72:75], v[12:15], v[36:39], v[24:27]
	v_mfma_f32_16x16x32_bf16 v[24:27], v[16:19], v[32:35], v[154:157]
	v_mfma_f32_16x16x32_bf16 v[76:79], v[20:23], v[36:39], v[24:27]
	v_mfma_f32_16x16x32_bf16 v[24:27], v[8:11], v[218:221], v[158:161]
	v_mfma_f32_16x16x32_bf16 v[40:43], v[12:15], v[222:225], v[24:27]
	v_mfma_f32_16x16x32_bf16 v[24:27], v[16:19], v[218:221], v[162:165]
	v_mfma_f32_16x16x32_bf16 v[0:3], v[8:11], v[234:237], v[0:3]
	v_mfma_f32_16x16x32_bf16 v[44:47], v[20:23], v[222:225], v[24:27]
	v_mfma_f32_16x16x32_bf16 v[24:27], v[8:11], v[226:229], v[166:169]
	v_mfma_f32_16x16x32_bf16 v[28:31], v[16:19], v[226:229], v[170:173]
	v_mfma_f32_16x16x32_bf16 v[8:11], v[12:15], v[238:241], v[0:3]
	v_mfma_f32_16x16x32_bf16 v[0:3], v[16:19], v[234:237], v[4:7]
	v_mfma_f32_16x16x32_bf16 v[24:27], v[12:15], v[230:233], v[24:27]
	v_mfma_f32_16x16x32_bf16 v[28:31], v[20:23], v[230:233], v[28:31]
	v_mfma_f32_16x16x32_bf16 v[12:15], v[20:23], v[238:241], v[0:3]
	v_mfma_f32_16x16x32_bf16 v[0:3], v[202:205], v[32:35], v[174:177]
	v_mfma_f32_16x16x32_bf16 v[56:59], v[206:209], v[36:39], v[0:3]
	v_mfma_f32_16x16x32_bf16 v[0:3], v[210:213], v[32:35], v[60:63]
	v_mfma_f32_16x16x32_bf16 v[60:63], v[214:217], v[36:39], v[0:3]
	v_mfma_f32_16x16x32_bf16 v[0:3], v[202:205], v[218:221], v[178:181]
	v_mfma_f32_16x16x32_bf16 v[32:35], v[206:209], v[222:225], v[0:3]
	v_mfma_f32_16x16x32_bf16 v[0:3], v[210:213], v[218:221], v[182:185]
	v_mfma_f32_16x16x32_bf16 v[36:39], v[214:217], v[222:225], v[0:3]
	v_mfma_f32_16x16x32_bf16 v[0:3], v[202:205], v[226:229], v[186:189]
	v_mfma_f32_16x16x32_bf16 v[16:19], v[206:209], v[230:233], v[0:3]
	v_mfma_f32_16x16x32_bf16 v[0:3], v[210:213], v[226:229], v[190:193]
	v_mfma_f32_16x16x32_bf16 v[20:23], v[214:217], v[230:233], v[0:3]
	v_mfma_f32_16x16x32_bf16 v[0:3], v[202:205], v[234:237], v[194:197]
	v_mfma_f32_16x16x32_bf16 v[4:7], v[210:213], v[234:237], v[198:201]
	v_mfma_f32_16x16x32_bf16 v[0:3], v[206:209], v[238:241], v[0:3]
	v_mfma_f32_16x16x32_bf16 v[4:7], v[214:217], v[238:241], v[4:7]
	s_barrier
	s_add_u32 s83, s76, 0x200
	s_addc_u32 s84, s77, 0
	s_add_u32 s76, s78, 0x80180
	s_addc_u32 s77, s79, 0
	s_mov_b32 s85, 0
; #define PG8_MMA(ai, bj, At, Bt) do { __builtin_amdgcn_s_setprio(1); _Pragma("unroll") for (int m = 0; m < 4; ++m) _Pragma("unroll") for (int n = 0; n < 2; ++n) _Pragma("unroll") for (int k = 0; k < 2; ++k) \
;         acc[ai][bj][m][n] = __builtin_amdgcn_mfma_f32_16x16x32_bf16(Bt[n][k], At[m][k], acc[ai][bj][m][n], 0, 0, 0); __builtin_amdgcn_s_setprio(0); } while (0)
; template <class Epi, class Sched, bool ALIGN_EPI = false, bool SP2 = false, bool A_TILED = false>
; __device__ __forceinline__ void gemm_phase(PG8_LAS unsigned char* lds, const Gemm g, const Sched& S, const Epi& E, const int wave_s) {
;     ...
;         for (int t = PEEL ? 2 : 0; t < nt; t += 2) {
;             const bool last = (t == nt - 2);
;             const char* a1 = cA + (size_t)(t + 1) * kstepA;
;             const char* a2 = last ? nA : cA + (size_t)(t + 2) * kstepA; const char* b2 = last ? nB : cB + (size_t)(t + 2) * kstep;
;             const char* a3 = a2 + kstepA; const char* b3 = b2 + kstep;
;             if (last && has_next) S.a_ready(nxt);
;             if constexpr (SP2) {
;             PG8_ITER(PG8_MMA)
.LBB0_1155:
	ds_read_b128 v[150:153], v145
	ds_read_b128 v[154:157], v145 offset:1024
	ds_read_b128 v[158:161], v145 offset:2048
	ds_read_b128 v[162:165], v145 offset:3072
	ds_read_b128 v[166:169], v146
	ds_read_b128 v[170:173], v146 offset:1024
	ds_read_b128 v[174:177], v146 offset:2048
	ds_read_b128 v[178:181], v146 offset:3072
	s_add_u32 s78, s76, 0xfff80080
	s_addc_u32 s79, s77, -1
	s_cmp_eq_u32 s85, 28
	s_cselect_b32 s81, s50, s79
	s_cselect_b32 s80, s51, s78
	s_cselect_b32 s79, s52, s84
	s_cselect_b32 s78, s53, s83
	s_mov_b32 m0, s54
	v_lshl_add_u64 v[214:215], s[76:77], 0, v[138:139]
	ds_read_b128 v[182:185], v147
	ds_read_b128 v[186:189], v147 offset:1024
	ds_read_b128 v[190:193], v147 offset:2048
	ds_read_b128 v[194:197], v147 offset:3072
	ds_read_b128 v[198:201], v147 offset:4096
	ds_read_b128 v[202:205], v147 offset:5120
	ds_read_b128 v[206:209], v147 offset:6144
	ds_read_b128 v[210:213], v147 offset:7168
	global_load_lds_dwordx4 v138, s[76:77]
	v_lshl_add_u64 v[214:215], s[76:77], 0, v[136:137]
	s_mov_b32 m0, s55
	s_nop 0
	global_load_lds_dwordx4 v136, s[76:77]
	s_waitcnt vmcnt(8) lgkmcnt(0)
	s_barrier
	v_mfma_f32_16x16x32_bf16 v[120:123], v[150:153], v[182:185], v[120:123]
	v_mfma_f32_16x16x32_bf16 v[124:127], v[158:161], v[182:185], v[124:127]
	v_mfma_f32_16x16x32_bf16 v[104:107], v[150:153], v[190:193], v[104:107]
	v_mfma_f32_16x16x32_bf16 v[108:111], v[158:161], v[190:193], v[108:111]
	v_mfma_f32_16x16x32_bf16 v[88:91], v[150:153], v[198:201], v[88:91]
	v_mfma_f32_16x16x32_bf16 v[92:95], v[158:161], v[198:201], v[92:95]
	v_mfma_f32_16x16x32_bf16 v[64:67], v[150:153], v[206:209], v[64:67]
	v_mfma_f32_16x16x32_bf16 v[68:71], v[158:161], v[206:209], v[68:71]
	v_mfma_f32_16x16x32_bf16 v[120:123], v[154:157], v[186:189], v[120:123]
	v_mfma_f32_16x16x32_bf16 v[124:127], v[162:165], v[186:189], v[124:127]
	v_mfma_f32_16x16x32_bf16 v[104:107], v[154:157], v[194:197], v[104:107]
	v_mfma_f32_16x16x32_bf16 v[108:111], v[162:165], v[194:197], v[108:111]
	v_mfma_f32_16x16x32_bf16 v[88:91], v[154:157], v[202:205], v[88:91]
	v_mfma_f32_16x16x32_bf16 v[92:95], v[162:165], v[202:205], v[92:95]
	v_mfma_f32_16x16x32_bf16 v[64:67], v[154:157], v[210:213], v[64:67]
	v_mfma_f32_16x16x32_bf16 v[68:71], v[162:165], v[210:213], v[68:71]
	v_mfma_f32_16x16x32_bf16 v[112:115], v[166:169], v[182:185], v[112:115]
	v_mfma_f32_16x16x32_bf16 v[116:119], v[174:177], v[182:185], v[116:119]
	v_mfma_f32_16x16x32_bf16 v[96:99], v[166:169], v[190:193], v[96:99]
	v_mfma_f32_16x16x32_bf16 v[100:103], v[174:177], v[190:193], v[100:103]
	v_mfma_f32_16x16x32_bf16 v[80:83], v[166:169], v[198:201], v[80:83]
	v_mfma_f32_16x16x32_bf16 v[84:87], v[174:177], v[198:201], v[84:87]
	v_mfma_f32_16x16x32_bf16 v[48:51], v[166:169], v[206:209], v[48:51]
	v_mfma_f32_16x16x32_bf16 v[52:55], v[174:177], v[206:209], v[52:55]
	v_mfma_f32_16x16x32_bf16 v[112:115], v[170:173], v[186:189], v[112:115]
	v_mfma_f32_16x16x32_bf16 v[116:119], v[178:181], v[186:189], v[116:119]
	v_mfma_f32_16x16x32_bf16 v[96:99], v[170:173], v[194:197], v[96:99]
	v_mfma_f32_16x16x32_bf16 v[100:103], v[178:181], v[194:197], v[100:103]
	v_mfma_f32_16x16x32_bf16 v[80:83], v[170:173], v[202:205], v[80:83]
	v_mfma_f32_16x16x32_bf16 v[84:87], v[178:181], v[202:205], v[84:87]
	v_mfma_f32_16x16x32_bf16 v[48:51], v[170:173], v[210:213], v[48:51]
	v_mfma_f32_16x16x32_bf16 v[52:55], v[178:181], v[210:213], v[52:55]
	s_barrier
	s_mov_b32 m0, s56
	v_lshl_add_u64 v[214:215], s[78:79], 0, v[128:129]
	s_add_u32 s88, s78, 0x80000
	ds_read_b128 v[182:185], v147 offset:16384
	ds_read_b128 v[186:189], v147 offset:17408
	ds_read_b128 v[190:193], v147 offset:18432
	ds_read_b128 v[194:197], v147 offset:19456
	ds_read_b128 v[198:201], v147 offset:20480
	ds_read_b128 v[202:205], v147 offset:21504
	ds_read_b128 v[206:209], v147 offset:22528
	ds_read_b128 v[210:213], v147 offset:23552
	global_load_lds_dwordx4 v128, s[78:79]
	v_lshl_add_u64 v[216:217], s[78:79], 0, v[130:131]
	s_mov_b32 m0, s57
	s_addc_u32 s89, s79, 0
	global_load_lds_dwordx4 v130, s[78:79]
	v_lshl_add_u64 v[218:219], s[88:89], 0, v[128:129]
	s_mov_b32 m0, s58
	v_lshl_add_u64 v[220:221], s[80:81], 0, v[132:133]
	global_load_lds_dwordx4 v128, s[88:89]
	v_lshl_add_u64 v[218:219], s[88:89], 0, v[130:131]
	s_mov_b32 m0, s59
	s_nop 0
	global_load_lds_dwordx4 v130, s[88:89]
	v_lshl_add_u64 v[218:219], s[80:81], 0, v[134:135]
	s_mov_b32 m0, s22
	s_nop 0
	global_load_lds_dwordx4 v134, s[80:81]
	s_mov_b32 m0, s23
	s_nop 0
	global_load_lds_dwordx4 v132, s[80:81]
	s_waitcnt vmcnt(8) lgkmcnt(0)
	s_barrier
; #define PG8_MMA(ai, bj, At, Bt) do { __builtin_amdgcn_s_setprio(1); _Pragma("unroll") for (int m = 0; m < 4; ++m) _Pragma("unroll") for (int n = 0; n < 2; ++n) _Pragma("unroll") for (int k = 0; k < 2; ++k) \
;         acc[ai][bj][m][n] = __builtin_amdgcn_mfma_f32_16x16x32_bf16(Bt[n][k], At[m][k], acc[ai][bj][m][n], 0, 0, 0); __builtin_amdgcn_s_setprio(0); } while (0)
; template <class Epi, class Sched, bool ALIGN_EPI = false, bool SP2 = false, bool A_TILED = false>
; __device__ __forceinline__ void gemm_phase(PG8_LAS unsigned char* lds, const Gemm g, const Sched& S, const Epi& E, const int wave_s) {
;     ...
;         for (int t = PEEL ? 2 : 0; t < nt; t += 2) {
;             const bool last = (t == nt - 2);
;             const char* a1 = cA + (size_t)(t + 1) * kstepA;
;             const char* a2 = last ? nA : cA + (size_t)(t + 2) * kstepA; const char* b2 = last ? nB : cB + (size_t)(t + 2) * kstep;
;             const char* a3 = a2 + kstepA; const char* b3 = b2 + kstep;
;             if (last && has_next) S.a_ready(nxt);
;             if constexpr (SP2) {
;             PG8_ITER(PG8_MMA)
	v_mfma_f32_16x16x32_bf16 v[72:75], v[150:153], v[182:185], v[72:75]
	v_mfma_f32_16x16x32_bf16 v[76:79], v[158:161], v[182:185], v[76:79]
	v_mfma_f32_16x16x32_bf16 v[40:43], v[150:153], v[190:193], v[40:43]
	v_mfma_f32_16x16x32_bf16 v[44:47], v[158:161], v[190:193], v[44:47]
	v_mfma_f32_16x16x32_bf16 v[24:27], v[150:153], v[198:201], v[24:27]
	v_mfma_f32_16x16x32_bf16 v[28:31], v[158:161], v[198:201], v[28:31]
	v_mfma_f32_16x16x32_bf16 v[8:11], v[150:153], v[206:209], v[8:11]
	v_mfma_f32_16x16x32_bf16 v[12:15], v[158:161], v[206:209], v[12:15]
	v_mfma_f32_16x16x32_bf16 v[72:75], v[154:157], v[186:189], v[72:75]
	v_mfma_f32_16x16x32_bf16 v[76:79], v[162:165], v[186:189], v[76:79]
	v_mfma_f32_16x16x32_bf16 v[40:43], v[154:157], v[194:197], v[40:43]
	v_mfma_f32_16x16x32_bf16 v[44:47], v[162:165], v[194:197], v[44:47]
	v_mfma_f32_16x16x32_bf16 v[24:27], v[154:157], v[202:205], v[24:27]
	v_mfma_f32_16x16x32_bf16 v[28:31], v[162:165], v[202:205], v[28:31]
	v_mfma_f32_16x16x32_bf16 v[8:11], v[154:157], v[210:213], v[8:11]
	v_mfma_f32_16x16x32_bf16 v[12:15], v[162:165], v[210:213], v[12:15]
	v_mfma_f32_16x16x32_bf16 v[56:59], v[166:169], v[182:185], v[56:59]
	v_mfma_f32_16x16x32_bf16 v[60:63], v[174:177], v[182:185], v[60:63]
	v_mfma_f32_16x16x32_bf16 v[32:35], v[166:169], v[190:193], v[32:35]
	v_mfma_f32_16x16x32_bf16 v[36:39], v[174:177], v[190:193], v[36:39]
	v_mfma_f32_16x16x32_bf16 v[16:19], v[166:169], v[198:201], v[16:19]
	v_mfma_f32_16x16x32_bf16 v[20:23], v[174:177], v[198:201], v[20:23]
	v_mfma_f32_16x16x32_bf16 v[0:3], v[166:169], v[206:209], v[0:3]
	v_mfma_f32_16x16x32_bf16 v[4:7], v[174:177], v[206:209], v[4:7]
	v_mfma_f32_16x16x32_bf16 v[56:59], v[170:173], v[186:189], v[56:59]
	v_mfma_f32_16x16x32_bf16 v[60:63], v[178:181], v[186:189], v[60:63]
	v_mfma_f32_16x16x32_bf16 v[32:35], v[170:173], v[194:197], v[32:35]
	v_mfma_f32_16x16x32_bf16 v[36:39], v[178:181], v[194:197], v[36:39]
	v_mfma_f32_16x16x32_bf16 v[16:19], v[170:173], v[202:205], v[16:19]
	v_mfma_f32_16x16x32_bf16 v[20:23], v[178:181], v[202:205], v[20:23]
	v_mfma_f32_16x16x32_bf16 v[0:3], v[170:173], v[210:213], v[0:3]
	v_mfma_f32_16x16x32_bf16 v[4:7], v[178:181], v[210:213], v[4:7]
	s_barrier
	ds_read_b128 v[150:153], v148
	ds_read_b128 v[154:157], v148 offset:1024
	ds_read_b128 v[158:161], v148 offset:2048
	ds_read_b128 v[162:165], v148 offset:3072
	ds_read_b128 v[166:169], v149
	ds_read_b128 v[170:173], v149 offset:1024
	ds_read_b128 v[174:177], v149 offset:2048
	ds_read_b128 v[178:181], v149 offset:3072
	s_add_u32 s80, s80, 0x80000
	s_addc_u32 s81, s81, 0
	s_mov_b32 m0, s36
	v_lshl_add_u64 v[222:223], s[80:81], 0, v[134:135]
	ds_read_b128 v[182:185], v147 offset:32768
	ds_read_b128 v[186:189], v147 offset:33792
	ds_read_b128 v[190:193], v147 offset:34816
	ds_read_b128 v[194:197], v147 offset:35840
	ds_read_b128 v[198:201], v147 offset:36864
	ds_read_b128 v[202:205], v147 offset:37888
	ds_read_b128 v[206:209], v147 offset:38912
	ds_read_b128 v[210:213], v147 offset:39936
	global_load_lds_dwordx4 v134, s[80:81]
	v_lshl_add_u64 v[222:223], s[80:81], 0, v[132:133]
	s_mov_b32 m0, s37
	s_nop 0
	global_load_lds_dwordx4 v132, s[80:81]
	s_waitcnt vmcnt(8) lgkmcnt(0)
	s_barrier
	v_mfma_f32_16x16x32_bf16 v[120:123], v[150:153], v[182:185], v[120:123]
	v_mfma_f32_16x16x32_bf16 v[124:127], v[158:161], v[182:185], v[124:127]
	v_mfma_f32_16x16x32_bf16 v[104:107], v[150:153], v[190:193], v[104:107]
	v_mfma_f32_16x16x32_bf16 v[108:111], v[158:161], v[190:193], v[108:111]
	v_mfma_f32_16x16x32_bf16 v[88:91], v[150:153], v[198:201], v[88:91]
	v_mfma_f32_16x16x32_bf16 v[92:95], v[158:161], v[198:201], v[92:95]
	v_mfma_f32_16x16x32_bf16 v[64:67], v[150:153], v[206:209], v[64:67]
	v_mfma_f32_16x16x32_bf16 v[68:71], v[158:161], v[206:209], v[68:71]
	v_mfma_f32_16x16x32_bf16 v[120:123], v[154:157], v[186:189], v[120:123]
	v_mfma_f32_16x16x32_bf16 v[124:127], v[162:165], v[186:189], v[124:127]
	v_mfma_f32_16x16x32_bf16 v[104:107], v[154:157], v[194:197], v[104:107]
	v_mfma_f32_16x16x32_bf16 v[108:111], v[162:165], v[194:197], v[108:111]
	v_mfma_f32_16x16x32_bf16 v[88:91], v[154:157], v[202:205], v[88:91]
	v_mfma_f32_16x16x32_bf16 v[92:95], v[162:165], v[202:205], v[92:95]
	v_mfma_f32_16x16x32_bf16 v[64:67], v[154:157], v[210:213], v[64:67]
	v_mfma_f32_16x16x32_bf16 v[68:71], v[162:165], v[210:213], v[68:71]
	v_mfma_f32_16x16x32_bf16 v[112:115], v[166:169], v[182:185], v[112:115]
	v_mfma_f32_16x16x32_bf16 v[116:119], v[174:177], v[182:185], v[116:119]
	v_mfma_f32_16x16x32_bf16 v[96:99], v[166:169], v[190:193], v[96:99]
	v_mfma_f32_16x16x32_bf16 v[100:103], v[174:177], v[190:193], v[100:103]
	v_mfma_f32_16x16x32_bf16 v[80:83], v[166:169], v[198:201], v[80:83]
	v_mfma_f32_16x16x32_bf16 v[84:87], v[174:177], v[198:201], v[84:87]
	v_mfma_f32_16x16x32_bf16 v[48:51], v[166:169], v[206:209], v[48:51]
	v_mfma_f32_16x16x32_bf16 v[52:55], v[174:177], v[206:209], v[52:55]
	v_mfma_f32_16x16x32_bf16 v[112:115], v[170:173], v[186:189], v[112:115]
	v_mfma_f32_16x16x32_bf16 v[116:119], v[178:181], v[186:189], v[116:119]
	v_mfma_f32_16x16x32_bf16 v[96:99], v[170:173], v[194:197], v[96:99]
	v_mfma_f32_16x16x32_bf16 v[100:103], v[178:181], v[194:197], v[100:103]
	v_mfma_f32_16x16x32_bf16 v[80:83], v[170:173], v[202:205], v[80:83]
	v_mfma_f32_16x16x32_bf16 v[84:87], v[178:181], v[202:205], v[84:87]
	v_mfma_f32_16x16x32_bf16 v[48:51], v[170:173], v[210:213], v[48:51]
	v_mfma_f32_16x16x32_bf16 v[52:55], v[178:181], v[210:213], v[52:55]
	s_barrier
; #define PG8_MMA(ai, bj, At, Bt) do { __builtin_amdgcn_s_setprio(1); _Pragma("unroll") for (int m = 0; m < 4; ++m) _Pragma("unroll") for (int n = 0; n < 2; ++n) _Pragma("unroll") for (int k = 0; k < 2; ++k) \
;         acc[ai][bj][m][n] = __builtin_amdgcn_mfma_f32_16x16x32_bf16(Bt[n][k], At[m][k], acc[ai][bj][m][n], 0, 0, 0); __builtin_amdgcn_s_setprio(0); } while (0)
; template <class Epi, class Sched, bool ALIGN_EPI = false, bool SP2 = false, bool A_TILED = false>
; __device__ __forceinline__ void gemm_phase(PG8_LAS unsigned char* lds, const Gemm g, const Sched& S, const Epi& E, const int wave_s) {
;     ...
;         for (int t = PEEL ? 2 : 0; t < nt; t += 2) {
;             const bool last = (t == nt - 2);
;             const char* a1 = cA + (size_t)(t + 1) * kstepA;
;             const char* a2 = last ? nA : cA + (size_t)(t + 2) * kstepA; const char* b2 = last ? nB : cB + (size_t)(t + 2) * kstep;
;             const char* a3 = a2 + kstepA; const char* b3 = b2 + kstep;
;             if (last && has_next) S.a_ready(nxt);
;             if constexpr (SP2) {
;             PG8_ITER(PG8_MMA)
	s_mov_b32 m0, s67
	v_lshl_add_u64 v[214:215], v[214:215], 0, s[12:13]
	s_add_u32 s78, s78, 0x80080
	ds_read_b128 v[182:185], v147 offset:49152
	ds_read_b128 v[186:189], v147 offset:50176
	ds_read_b128 v[190:193], v147 offset:51200
	ds_read_b128 v[194:197], v147 offset:52224
	ds_read_b128 v[198:201], v147 offset:53248
	ds_read_b128 v[202:205], v147 offset:54272
	ds_read_b128 v[206:209], v147 offset:55296
	ds_read_b128 v[210:213], v147 offset:56320
	global_load_lds_dwordx4 v[214:215], off
	v_lshl_add_u64 v[214:215], v[216:217], 0, s[12:13]
	s_mov_b32 m0, s69
	s_addc_u32 s79, s79, 0
	global_load_lds_dwordx4 v[214:215], off
	v_lshl_add_u64 v[214:215], s[78:79], 0, v[128:129]
	s_mov_b32 m0, s75
	s_nop 0
	global_load_lds_dwordx4 v128, s[78:79]
	v_lshl_add_u64 v[214:215], s[78:79], 0, v[130:131]
	s_mov_b32 m0, s82
	s_nop 0
	global_load_lds_dwordx4 v130, s[78:79]
	v_lshl_add_u64 v[214:215], v[218:219], 0, s[12:13]
	s_mov_b32 m0, s43
	s_nop 0
	global_load_lds_dwordx4 v[214:215], off
	v_lshl_add_u64 v[214:215], v[220:221], 0, s[12:13]
	s_mov_b32 m0, s44
	s_nop 0
	global_load_lds_dwordx4 v[214:215], off
	s_waitcnt vmcnt(8) lgkmcnt(0)
	s_barrier
	v_mfma_f32_16x16x32_bf16 v[72:75], v[150:153], v[182:185], v[72:75]
	v_mfma_f32_16x16x32_bf16 v[76:79], v[158:161], v[182:185], v[76:79]
	v_mfma_f32_16x16x32_bf16 v[40:43], v[150:153], v[190:193], v[40:43]
	v_mfma_f32_16x16x32_bf16 v[44:47], v[158:161], v[190:193], v[44:47]
	v_mfma_f32_16x16x32_bf16 v[24:27], v[150:153], v[198:201], v[24:27]
	v_mfma_f32_16x16x32_bf16 v[28:31], v[158:161], v[198:201], v[28:31]
	v_mfma_f32_16x16x32_bf16 v[8:11], v[150:153], v[206:209], v[8:11]
	v_mfma_f32_16x16x32_bf16 v[12:15], v[158:161], v[206:209], v[12:15]
	v_mfma_f32_16x16x32_bf16 v[72:75], v[154:157], v[186:189], v[72:75]
	v_mfma_f32_16x16x32_bf16 v[76:79], v[162:165], v[186:189], v[76:79]
	v_mfma_f32_16x16x32_bf16 v[40:43], v[154:157], v[194:197], v[40:43]
	v_mfma_f32_16x16x32_bf16 v[44:47], v[162:165], v[194:197], v[44:47]
	v_mfma_f32_16x16x32_bf16 v[24:27], v[154:157], v[202:205], v[24:27]
	v_mfma_f32_16x16x32_bf16 v[28:31], v[162:165], v[202:205], v[28:31]
	v_mfma_f32_16x16x32_bf16 v[8:11], v[154:157], v[210:213], v[8:11]
	v_mfma_f32_16x16x32_bf16 v[12:15], v[162:165], v[210:213], v[12:15]
	v_mfma_f32_16x16x32_bf16 v[56:59], v[166:169], v[182:185], v[56:59]
	v_mfma_f32_16x16x32_bf16 v[60:63], v[174:177], v[182:185], v[60:63]
	v_mfma_f32_16x16x32_bf16 v[32:35], v[166:169], v[190:193], v[32:35]
	v_mfma_f32_16x16x32_bf16 v[36:39], v[174:177], v[190:193], v[36:39]
	v_mfma_f32_16x16x32_bf16 v[16:19], v[166:169], v[198:201], v[16:19]
	v_mfma_f32_16x16x32_bf16 v[20:23], v[174:177], v[198:201], v[20:23]
	v_mfma_f32_16x16x32_bf16 v[0:3], v[166:169], v[206:209], v[0:3]
	v_mfma_f32_16x16x32_bf16 v[4:7], v[174:177], v[206:209], v[4:7]
	v_mfma_f32_16x16x32_bf16 v[56:59], v[170:173], v[186:189], v[56:59]
	v_mfma_f32_16x16x32_bf16 v[60:63], v[178:181], v[186:189], v[60:63]
	v_mfma_f32_16x16x32_bf16 v[32:35], v[170:173], v[194:197], v[32:35]
	v_mfma_f32_16x16x32_bf16 v[36:39], v[178:181], v[194:197], v[36:39]
	v_mfma_f32_16x16x32_bf16 v[16:19], v[170:173], v[202:205], v[16:19]
	v_mfma_f32_16x16x32_bf16 v[20:23], v[178:181], v[202:205], v[20:23]
	v_mfma_f32_16x16x32_bf16 v[0:3], v[170:173], v[210:213], v[0:3]
	v_mfma_f32_16x16x32_bf16 v[4:7], v[178:181], v[210:213], v[4:7]
	s_barrier
	s_add_i32 s85, s85, 2
	s_add_u32 s83, s83, 0x100
	s_addc_u32 s84, s84, 0
	s_add_u32 s76, s76, 0x100
	s_addc_u32 s77, s77, 0
	s_cmp_gt_u32 s85, 29
	s_cbranch_scc0 .LBB0_1155
	s_and_b64 vcc, exec, s[60:61]
	s_cbranch_vccz .LBB0_1158
	s_barrier

; __device__ __forceinline__ int tid_now(int wave_s) { unsigned z = 0u; asm volatile("" : "+v"(z)); return (wave_s << 6) | (int)__builtin_amdgcn_mbcnt_hi(~0u, __builtin_amdgcn_mbcnt_lo(~0u, z)); }
; __device__ __forceinline__ unsigned xb_add(unsigned* p, unsigned v) { return __hip_atomic_fetch_add(p, v, __ATOMIC_RELAXED, __HIP_MEMORY_SCOPE_AGENT); }
; __device__ __forceinline__ void xcd_barrier(const XcdBarrier& b) {
;     asm volatile("s_waitcnt vmcnt(0)" ::: "memory");
;     __syncthreads();
;     if (tid_now(b.w) == 0) {
;         unsigned* bar = b.bar;
;         __builtin_amdgcn_s_waitcnt(0);
;         unsigned nloc = b.st[0], nx = b.st[1];
;         if (nloc == 0u) { xcd_barrier_complete(bar, b.x, nloc, nx, b.np); b.st[0] = nloc; b.st[1] = nx; }
;         const unsigned old = xb_add(&bar[XB_XSUB(b.x)], 1u);
.LBB0_1162:
	s_setprio 0
	s_cmp_gt_i32 s35, 6
	s_cselect_b64 s[0:1], -1, 0
	s_and_b64 s[2:3], s[2:3], s[0:1]
	s_andn2_b64 vcc, exec, s[2:3]
	s_cbranch_vccnz .LBB0_1216
	s_waitcnt vmcnt(0)
	v_mov_b32_e32 v0, 0
	s_waitcnt vmcnt(0)
	s_waitcnt lgkmcnt(0)
	s_barrier
	s_nop 0
	v_mbcnt_lo_u32_b32 v0, -1, v0
	v_mbcnt_hi_u32_b32 v0, -1, v0
	v_or_b32_e32 v0, s33, v0
	v_cmp_eq_u32_e32 vcc, 0, v0
	s_and_saveexec_b64 s[2:3], vcc
	s_cbranch_execz .LBB0_1215
	s_add_i32 s4, 0, 0x27f68
	v_mov_b32_e32 v0, s4
	s_waitcnt vmcnt(0) expcnt(0) lgkmcnt(0)
	ds_read_b32 v2, v0
	s_add_i32 s4, 0, 0x27f6c
	v_mov_b32_e32 v0, s4
	ds_read_b32 v0, v0
	s_waitcnt lgkmcnt(1)
	v_cmp_ne_u32_e32 vcc, 0, v2
	s_cbranch_vccnz .LBB0_1179
	s_add_u32 s4, s10, 0x1000
	s_addc_u32 s5, s11, 0
	s_add_u32 s12, s10, 0x1100
	s_addc_u32 s13, s11, 0
	s_add_u32 s60, s10, 0x1200
	s_addc_u32 s61, s11, 0
	s_add_u32 s62, s10, 0x1300
	s_addc_u32 s63, s11, 0
	s_mov_b32 s6, 1
	v_mov_b32_e32 v16, 0
	s_branch .LBB0_1167

; #define PG8_STAGE(bufoff, gbase, voff) do { _Pragma("unroll") for (int _i = 0; _i < 2; ++_i) \
;         __builtin_amdgcn_global_load_lds((const unsigned*)((const char*)(gbase) + (voff)[_i]), (PG8_LAS unsigned*)(lds + (bufoff) + ldsw + _i * 8192), 16, 0, 0); } while (0)
; #define PG8_WAIT_V(n) asm volatile("s_waitcnt vmcnt(" #n ")" ::: "memory")
; template <class Epi, class Sched, bool ALIGN_EPI = false, bool SP2 = false, bool A_TILED = false>
; __device__ __forceinline__ void gemm_phase(PG8_LAS unsigned char* lds, const Gemm g, const Sched& S, const Epi& E, const int wave_s) {
;     ...
;     if constexpr (SP2) {
;         PG8_STAGE(PG8_SB(0, 0), cB, voffB); PG8_STAGE(PG8_SB(0, 1), cB + hstep, voffB); PG8_STAGE(PG8_SA(0, 0), cA, voffA); PG8_STAGE(PG8_SA(0, 1), cA + hstepA, voffA);
;         if (wr == 1) PG8_BAR;
;         PG8_WAIT_V(2); PG8_BAR;
;         PG8_STAGE(PG8_SB(1, 0), cB + kstep, voffB); PG8_STAGE(PG8_SA(1, 0), cA + kstepA, voffA); PG8_STAGE(PG8_SB(1, 1), cB + hstep + kstep, voffB);
;         PG8_WAIT_V(6); PG8_BAR;
;     } else {
;         PG8_STAGE(PG8_SB(0, 0), cB, voffB); PG8_STAGE(PG8_SA(0, 0), cA, voffA); PG8_STAGE(PG8_SB(0, 1), cB + hstep, voffB); PG8_STAGE(PG8_SA(0, 1), cA + hstepA, voffA);
;         if (wr == 1) PG8_BAR;
;         PG8_WAIT_V(4); PG8_BAR;
;         PG8_STAGE(PG8_SB(1, 0), cB + kstep, voffB); PG8_STAGE(PG8_SA(1, 0), cA + kstepA, voffA); PG8_STAGE(PG8_SB(1, 1), cB + hstep + kstep, voffB);
;         PG8_WAIT_V(6); PG8_BAR;
;     }
;     for (;;) {
;         const bool has_next = Epi::AFTER_DRAIN ? false : S.next(ui + 1, nxt);
;         const char* nA = has_next ? (const char*)g.A + (size_t)nxt.pm * tstepA : cA; const char* nB = has_next ? (const char*)g.Bt + (size_t)nxt.pn * tstep : cB;
;         constexpr bool PEEL = SP2 && !Epi::AFTER_DRAIN;
;         if constexpr (PEEL) {
;             const char* a1 = cA + kstepA; const char* a2 = cA + 2 * kstepA; const char* b2 = cB + 2 * kstep; const char* a3 = a2 + kstepA; const char* b3 = b2 + kstep;
;             PG8_ITER(PG8_MMAZ)
;         } else {
; #pragma unroll
;             for (int a = 0; a < 2; ++a)
; #pragma unroll
;                 for (int b = 0; b < 2; ++b)
; #pragma unroll
;                     for (int m = 0; m < 4; ++m)
; #pragma unroll
;                         for (int n = 0; n < 2; ++n) acc[a][b][m][n] = (f32x4){0.f, 0.f, 0.f, 0.f};
.LBB0_1227:
	v_and_b32_e32 v5, 48, v4
	v_lshlrev_b32_e32 v6, 6, v4
	s_movk_i32 s36, 0x3c0
	v_lshlrev_b32_e32 v4, 2, v4
	s_mov_b64 s[64:65], 0x80
	s_and_b32 s7, s9, 3
	s_lshl_b32 s6, s23, 6
	s_lshl_b32 s23, s23, 13
	v_and_or_b32 v5, v6, s36, v5
	v_and_b32_e32 v4, 32, v4
	s_add_i32 m0, s14, 0x18000
	v_lshl_add_u64 v[2:3], v[2:3], 0, s[64:65]
	v_bitop3_b32 v6, v5, s23, v4 bitop3:0xde
	s_lshl_b32 s23, s7, 12
	s_waitcnt vmcnt(2)
	s_barrier
	global_load_lds_dwordx4 v[2:3], off
	s_add_i32 m0, s14, 0x1a000
	s_add_u32 s36, s4, 0x8000
	v_bitop3_b32 v4, v5, s23, v4 bitop3:0xde
	v_lshl_add_u64 v[0:1], v[0:1], 0, s[64:65]
	s_addc_u32 s37, s5, 0
	s_add_i32 s23, s14, 0x8000
	global_load_lds_dwordx4 v[0:1], off
	v_lshl_add_u64 v[0:1], s[36:37], 0, v[32:33]
	s_mov_b32 m0, s23
	s_mov_b64 s[40:41], 0x3460c000
	global_load_lds_dwordx4 v32, s[36:37]
	v_lshl_add_u64 v[0:1], s[36:37], 0, v[132:133]
	s_add_i32 s36, s14, 0xa000
	s_add_u32 s38, s0, 0x200080
	s_mov_b32 m0, s36
	s_addc_u32 s39, s1, 0
	global_load_lds_dwordx4 v[0:1], off
	s_add_i32 m0, s14, 0x1c000
	v_lshl_add_u64 v[0:1], s[38:39], 0, v[34:35]
	global_load_lds_dwordx4 v34, s[38:39]
	v_lshl_add_u64 v[0:1], s[38:39], 0, v[134:135]
	s_add_i32 m0, s14, 0x1e000
	s_add_u32 s37, s68, 0x12600100
	global_load_lds_dwordx4 v134, s[38:39]
	s_addc_u32 s38, s69, 0
	v_lshl_add_u64 v[0:1], s[66:67], 0, v[132:133]
	v_lshl_add_u64 v[136:137], v[0:1], 0, s[40:41]
	v_lshl_add_u64 v[0:1], s[66:67], 0, v[32:33]
	s_add_u32 s39, s66, 0x34610000
	s_waitcnt vmcnt(6)
	v_lshl_add_u64 v[138:139], v[0:1], 0, s[40:41]
	s_addc_u32 s40, s67, 0
	s_bitcmp1_b32 s33, 8
	s_cbranch_scc1 .Lsp_4
	s_setprio 1
.Lsp_4:
	s_add_i32 s44, 0, 0x10000
	s_add_i32 s46, 0, 0x14000
	s_add_i32 s48, 0, 0x18000
	s_add_i32 s51, 0, 0x1c000
	v_add_u32_e32 v140, s44, v4
	v_add_u32_e32 v141, s46, v4
	s_add_i32 s44, s44, s50
	s_add_i32 s46, s46, s50
	v_add_u32_e32 v143, s48, v4
	s_add_i32 s48, s48, s50
	s_add_i32 s50, s51, s50
	s_mov_b32 s41, -2
	v_add_u32_e32 v142, 0, v6
	s_add_i32 s42, s14, 0xc000
	s_add_i32 s43, s14, 0xe000
	s_add_i32 s45, s44, 0x2000
	s_add_i32 s47, s46, 0x2000
	v_add_u32_e32 v144, s51, v4
	s_add_i32 s49, s48, 0x2000
	s_add_i32 s51, s50, 0x2000
	s_mov_b64 s[66:67], 0x10000
	v_mov_b32_e32 v0, v35
	v_mov_b32_e32 v1, v35
	v_mov_b32_e32 v2, v35
	v_mov_b32_e32 v3, v35
	v_mov_b32_e32 v4, v35
	v_mov_b32_e32 v5, v35
	v_mov_b32_e32 v6, v35
	v_mov_b32_e32 v7, v35
	v_mov_b32_e32 v40, v35
	v_mov_b32_e32 v41, v35
	v_mov_b32_e32 v42, v35
	v_mov_b32_e32 v43, v35
	v_mov_b32_e32 v44, v35
	v_mov_b32_e32 v45, v35
	v_mov_b32_e32 v46, v35
	v_mov_b32_e32 v47, v35
	v_mov_b32_e32 v88, v35
	v_mov_b32_e32 v89, v35
	v_mov_b32_e32 v90, v35
	v_mov_b32_e32 v91, v35
	v_mov_b32_e32 v92, v35
	v_mov_b32_e32 v93, v35
	v_mov_b32_e32 v94, v35
	v_mov_b32_e32 v95, v35
	v_mov_b32_e32 v112, v35
	v_mov_b32_e32 v113, v35
	v_mov_b32_e32 v114, v35
	v_mov_b32_e32 v115, v35
	v_mov_b32_e32 v124, v35
	v_mov_b32_e32 v125, v35
	v_mov_b32_e32 v126, v35
	v_mov_b32_e32 v127, v35
	v_mov_b32_e32 v24, v35
	v_mov_b32_e32 v25, v35
	v_mov_b32_e32 v26, v35
	v_mov_b32_e32 v27, v35
	v_mov_b32_e32 v36, v35
	v_mov_b32_e32 v37, v35
	v_mov_b32_e32 v38, v35
	v_mov_b32_e32 v39, v35
	v_mov_b32_e32 v80, v35
	v_mov_b32_e32 v81, v35
	v_mov_b32_e32 v82, v35
	v_mov_b32_e32 v83, v35
	v_mov_b32_e32 v84, v35
	v_mov_b32_e32 v85, v35
	v_mov_b32_e32 v86, v35
	v_mov_b32_e32 v87, v35
	v_mov_b32_e32 v120, v35
	v_mov_b32_e32 v121, v35
	v_mov_b32_e32 v122, v35
	v_mov_b32_e32 v123, v35
	v_mov_b32_e32 v116, v35
	v_mov_b32_e32 v117, v35
	v_mov_b32_e32 v118, v35
	v_mov_b32_e32 v119, v35
	v_mov_b32_e32 v104, v35
	v_mov_b32_e32 v105, v35
	v_mov_b32_e32 v106, v35
	v_mov_b32_e32 v107, v35
	v_mov_b32_e32 v100, v35
	v_mov_b32_e32 v101, v35
	v_mov_b32_e32 v102, v35
	v_mov_b32_e32 v103, v35
	v_mov_b32_e32 v96, v35
	v_mov_b32_e32 v97, v35
	v_mov_b32_e32 v98, v35
	v_mov_b32_e32 v99, v35
	v_mov_b32_e32 v108, v35
	v_mov_b32_e32 v109, v35
	v_mov_b32_e32 v110, v35
	v_mov_b32_e32 v111, v35
	v_mov_b32_e32 v64, v35
	v_mov_b32_e32 v65, v35
	v_mov_b32_e32 v66, v35
	v_mov_b32_e32 v67, v35
	v_mov_b32_e32 v72, v35
	v_mov_b32_e32 v73, v35
	v_mov_b32_e32 v74, v35
	v_mov_b32_e32 v75, v35
	v_mov_b32_e32 v48, v35
	v_mov_b32_e32 v49, v35
	v_mov_b32_e32 v50, v35
	v_mov_b32_e32 v51, v35
	v_mov_b32_e32 v56, v35
	v_mov_b32_e32 v57, v35
	v_mov_b32_e32 v58, v35
	v_mov_b32_e32 v59, v35
	v_mov_b32_e32 v16, v35
	v_mov_b32_e32 v17, v35
	v_mov_b32_e32 v18, v35
	v_mov_b32_e32 v19, v35
	v_mov_b32_e32 v28, v35
	v_mov_b32_e32 v29, v35
	v_mov_b32_e32 v30, v35
	v_mov_b32_e32 v31, v35
	v_mov_b32_e32 v68, v35
	v_mov_b32_e32 v69, v35
	v_mov_b32_e32 v70, v35
	v_mov_b32_e32 v71, v35
	v_mov_b32_e32 v128, v35
	v_mov_b32_e32 v129, v35
	v_mov_b32_e32 v130, v35
	v_mov_b32_e32 v131, v35
	v_mov_b32_e32 v52, v35
	v_mov_b32_e32 v53, v35
	v_mov_b32_e32 v54, v35
	v_mov_b32_e32 v55, v35
	v_mov_b32_e32 v76, v35
	v_mov_b32_e32 v77, v35
	v_mov_b32_e32 v78, v35
	v_mov_b32_e32 v79, v35
	v_mov_b32_e32 v20, v35
	v_mov_b32_e32 v21, v35
	v_mov_b32_e32 v22, v35
	v_mov_b32_e32 v23, v35
	v_mov_b32_e32 v60, v35
	v_mov_b32_e32 v61, v35
	v_mov_b32_e32 v62, v35
	v_mov_b32_e32 v63, v35
	v_mov_b32_e32 v12, v35
	v_mov_b32_e32 v13, v35
	v_mov_b32_e32 v14, v35
	v_mov_b32_e32 v15, v35
	v_mov_b32_e32 v8, v35
	v_mov_b32_e32 v9, v35
	v_mov_b32_e32 v10, v35
	v_mov_b32_e32 v11, v35
	s_barrier
; #define PG8_MMA(ai, bj, At, Bt) do { __builtin_amdgcn_s_setprio(1); _Pragma("unroll") for (int m = 0; m < 4; ++m) _Pragma("unroll") for (int n = 0; n < 2; ++n) _Pragma("unroll") for (int k = 0; k < 2; ++k) \
;         acc[ai][bj][m][n] = __builtin_amdgcn_mfma_f32_16x16x32_bf16(Bt[n][k], At[m][k], acc[ai][bj][m][n], 0, 0, 0); __builtin_amdgcn_s_setprio(0); } while (0)
; template <class Epi, class Sched, bool ALIGN_EPI = false, bool SP2 = false, bool A_TILED = false>
; __device__ __forceinline__ void gemm_phase(PG8_LAS unsigned char* lds, const Gemm g, const Sched& S, const Epi& E, const int wave_s) {
;     ...
;         for (int t = PEEL ? 2 : 0; t < nt; t += 2) {
;             const bool last = (t == nt - 2);
;             const char* a1 = cA + (size_t)(t + 1) * kstepA;
;             const char* a2 = last ? nA : cA + (size_t)(t + 2) * kstepA; const char* b2 = last ? nB : cB + (size_t)(t + 2) * kstep;
;             const char* a3 = a2 + kstepA; const char* b3 = b2 + kstep;
;             if (last && has_next) S.a_ready(nxt);
;             if constexpr (SP2) {
;             PG8_ITER(PG8_MMA)
.LBB0_1228:
	ds_read_b128 v[146:149], v140
	ds_read_b128 v[150:153], v140 offset:1024
	ds_read_b128 v[154:157], v140 offset:2048
	ds_read_b128 v[158:161], v140 offset:3072
	ds_read_b128 v[162:165], v141
	ds_read_b128 v[166:169], v141 offset:1024
	ds_read_b128 v[170:173], v141 offset:2048
	ds_read_b128 v[174:177], v141 offset:3072
	s_add_u32 s52, s12, s39
	s_addc_u32 s53, s13, s40
	s_add_u32 s54, s12, s37
	s_addc_u32 s55, s13, s38
	s_cmpk_eq_i32 s41, 0x7c
	s_cselect_b32 s72, s4, s52
	s_cselect_b32 s73, s5, s53
	s_cselect_b32 s70, s0, s54
	s_cselect_b32 s71, s1, s55
	s_add_u32 s68, s72, 0x8000
	s_addc_u32 s69, s73, 0
	s_mov_b32 m0, s42
	v_lshl_add_u64 v[210:211], s[12:13], 0, v[138:139]
	ds_read_b128 v[178:181], v142
	ds_read_b128 v[182:185], v142 offset:1024
	ds_read_b128 v[186:189], v142 offset:2048
	ds_read_b128 v[190:193], v142 offset:3072
	ds_read_b128 v[194:197], v142 offset:4096
	ds_read_b128 v[198:201], v142 offset:5120
	ds_read_b128 v[202:205], v142 offset:6144
	ds_read_b128 v[206:209], v142 offset:7168
	global_load_lds_dwordx4 v[210:211], off
	v_lshl_add_u64 v[210:211], s[12:13], 0, v[136:137]
	s_mov_b32 m0, s43
	s_nop 0
	global_load_lds_dwordx4 v[210:211], off
	s_waitcnt vmcnt(8) lgkmcnt(0)
	s_barrier
	v_mfma_f32_16x16x32_bf16 v[8:11], v[146:149], v[178:181], v[8:11]
	v_mfma_f32_16x16x32_bf16 v[12:15], v[154:157], v[178:181], v[12:15]
	v_mfma_f32_16x16x32_bf16 v[60:63], v[146:149], v[186:189], v[60:63]
	v_mfma_f32_16x16x32_bf16 v[20:23], v[154:157], v[186:189], v[20:23]
	v_mfma_f32_16x16x32_bf16 v[76:79], v[146:149], v[194:197], v[76:79]
	v_mfma_f32_16x16x32_bf16 v[52:55], v[154:157], v[194:197], v[52:55]
	v_mfma_f32_16x16x32_bf16 v[128:131], v[146:149], v[202:205], v[128:131]
	v_mfma_f32_16x16x32_bf16 v[68:71], v[154:157], v[202:205], v[68:71]
	v_mfma_f32_16x16x32_bf16 v[8:11], v[150:153], v[182:185], v[8:11]
	v_mfma_f32_16x16x32_bf16 v[12:15], v[158:161], v[182:185], v[12:15]
	v_mfma_f32_16x16x32_bf16 v[60:63], v[150:153], v[190:193], v[60:63]
	v_mfma_f32_16x16x32_bf16 v[20:23], v[158:161], v[190:193], v[20:23]
	v_mfma_f32_16x16x32_bf16 v[76:79], v[150:153], v[198:201], v[76:79]
	v_mfma_f32_16x16x32_bf16 v[52:55], v[158:161], v[198:201], v[52:55]
	v_mfma_f32_16x16x32_bf16 v[128:131], v[150:153], v[206:209], v[128:131]
	v_mfma_f32_16x16x32_bf16 v[68:71], v[158:161], v[206:209], v[68:71]
	v_mfma_f32_16x16x32_bf16 v[28:31], v[162:165], v[178:181], v[28:31]
	v_mfma_f32_16x16x32_bf16 v[16:19], v[170:173], v[178:181], v[16:19]
	v_mfma_f32_16x16x32_bf16 v[56:59], v[162:165], v[186:189], v[56:59]
	v_mfma_f32_16x16x32_bf16 v[48:51], v[170:173], v[186:189], v[48:51]
	v_mfma_f32_16x16x32_bf16 v[72:75], v[162:165], v[194:197], v[72:75]
	v_mfma_f32_16x16x32_bf16 v[64:67], v[170:173], v[194:197], v[64:67]
	v_mfma_f32_16x16x32_bf16 v[108:111], v[162:165], v[202:205], v[108:111]
	v_mfma_f32_16x16x32_bf16 v[96:99], v[170:173], v[202:205], v[96:99]
	v_mfma_f32_16x16x32_bf16 v[28:31], v[166:169], v[182:185], v[28:31]
	v_mfma_f32_16x16x32_bf16 v[16:19], v[174:177], v[182:185], v[16:19]
	v_mfma_f32_16x16x32_bf16 v[56:59], v[166:169], v[190:193], v[56:59]
	v_mfma_f32_16x16x32_bf16 v[48:51], v[174:177], v[190:193], v[48:51]
	v_mfma_f32_16x16x32_bf16 v[72:75], v[166:169], v[198:201], v[72:75]
	v_mfma_f32_16x16x32_bf16 v[64:67], v[174:177], v[198:201], v[64:67]
	v_mfma_f32_16x16x32_bf16 v[108:111], v[166:169], v[206:209], v[108:111]
	v_mfma_f32_16x16x32_bf16 v[96:99], v[174:177], v[206:209], v[96:99]
	s_barrier
	s_mov_b32 m0, s44
	v_lshl_add_u64 v[210:211], s[70:71], 0, v[34:35]
	s_add_u32 s52, s70, 0x200000
	ds_read_b128 v[178:181], v142 offset:16384
	ds_read_b128 v[182:185], v142 offset:17408
	ds_read_b128 v[186:189], v142 offset:18432
	ds_read_b128 v[190:193], v142 offset:19456
	ds_read_b128 v[194:197], v142 offset:20480
	ds_read_b128 v[198:201], v142 offset:21504
	ds_read_b128 v[202:205], v142 offset:22528
	ds_read_b128 v[206:209], v142 offset:23552
	global_load_lds_dwordx4 v34, s[70:71]
	v_lshl_add_u64 v[212:213], s[70:71], 0, v[134:135]
	s_mov_b32 m0, s45
	s_addc_u32 s53, s71, 0
	global_load_lds_dwordx4 v134, s[70:71]
	v_lshl_add_u64 v[214:215], s[52:53], 0, v[34:35]
	s_mov_b32 m0, s46
	s_nop 0
	global_load_lds_dwordx4 v34, s[52:53]
	v_lshl_add_u64 v[214:215], s[52:53], 0, v[134:135]
	s_mov_b32 m0, s47
	s_nop 0
	global_load_lds_dwordx4 v134, s[52:53]
	v_lshl_add_u64 v[214:215], s[72:73], 0, v[32:33]
	s_mov_b32 m0, s14
	s_nop 0
	global_load_lds_dwordx4 v32, s[72:73]
	v_lshl_add_u64 v[214:215], s[72:73], 0, v[132:133]
	s_mov_b32 m0, s15
	s_nop 0
	global_load_lds_dwordx4 v132, s[72:73]
	s_waitcnt vmcnt(8) lgkmcnt(0)
	s_barrier
; #define PG8_MMA(ai, bj, At, Bt) do { __builtin_amdgcn_s_setprio(1); _Pragma("unroll") for (int m = 0; m < 4; ++m) _Pragma("unroll") for (int n = 0; n < 2; ++n) _Pragma("unroll") for (int k = 0; k < 2; ++k) \
;         acc[ai][bj][m][n] = __builtin_amdgcn_mfma_f32_16x16x32_bf16(Bt[n][k], At[m][k], acc[ai][bj][m][n], 0, 0, 0); __builtin_amdgcn_s_setprio(0); } while (0)
; template <class Epi, class Sched, bool ALIGN_EPI = false, bool SP2 = false, bool A_TILED = false>
; __device__ __forceinline__ void gemm_phase(PG8_LAS unsigned char* lds, const Gemm g, const Sched& S, const Epi& E, const int wave_s) {
;     ...
;         for (int t = PEEL ? 2 : 0; t < nt; t += 2) {
;             const bool last = (t == nt - 2);
;             const char* a1 = cA + (size_t)(t + 1) * kstepA;
;             const char* a2 = last ? nA : cA + (size_t)(t + 2) * kstepA; const char* b2 = last ? nB : cB + (size_t)(t + 2) * kstep;
;             const char* a3 = a2 + kstepA; const char* b3 = b2 + kstep;
;             if (last && has_next) S.a_ready(nxt);
;             if constexpr (SP2) {
;             PG8_ITER(PG8_MMA)
	v_mfma_f32_16x16x32_bf16 v[100:103], v[146:149], v[178:181], v[100:103]
	v_mfma_f32_16x16x32_bf16 v[104:107], v[154:157], v[178:181], v[104:107]
	v_mfma_f32_16x16x32_bf16 v[116:119], v[146:149], v[186:189], v[116:119]
	v_mfma_f32_16x16x32_bf16 v[120:123], v[154:157], v[186:189], v[120:123]
	v_mfma_f32_16x16x32_bf16 v[84:87], v[146:149], v[194:197], v[84:87]
	v_mfma_f32_16x16x32_bf16 v[80:83], v[154:157], v[194:197], v[80:83]
	v_mfma_f32_16x16x32_bf16 v[36:39], v[146:149], v[202:205], v[36:39]
	v_mfma_f32_16x16x32_bf16 v[24:27], v[154:157], v[202:205], v[24:27]
	v_mfma_f32_16x16x32_bf16 v[100:103], v[150:153], v[182:185], v[100:103]
	v_mfma_f32_16x16x32_bf16 v[104:107], v[158:161], v[182:185], v[104:107]
	v_mfma_f32_16x16x32_bf16 v[116:119], v[150:153], v[190:193], v[116:119]
	v_mfma_f32_16x16x32_bf16 v[120:123], v[158:161], v[190:193], v[120:123]
	v_mfma_f32_16x16x32_bf16 v[84:87], v[150:153], v[198:201], v[84:87]
	v_mfma_f32_16x16x32_bf16 v[80:83], v[158:161], v[198:201], v[80:83]
	v_mfma_f32_16x16x32_bf16 v[36:39], v[150:153], v[206:209], v[36:39]
	v_mfma_f32_16x16x32_bf16 v[24:27], v[158:161], v[206:209], v[24:27]
	v_mfma_f32_16x16x32_bf16 v[124:127], v[162:165], v[178:181], v[124:127]
	v_mfma_f32_16x16x32_bf16 v[112:115], v[170:173], v[178:181], v[112:115]
	v_mfma_f32_16x16x32_bf16 v[92:95], v[162:165], v[186:189], v[92:95]
	v_mfma_f32_16x16x32_bf16 v[88:91], v[170:173], v[186:189], v[88:91]
	v_mfma_f32_16x16x32_bf16 v[44:47], v[162:165], v[194:197], v[44:47]
	v_mfma_f32_16x16x32_bf16 v[40:43], v[170:173], v[194:197], v[40:43]
	v_mfma_f32_16x16x32_bf16 v[4:7], v[162:165], v[202:205], v[4:7]
	v_mfma_f32_16x16x32_bf16 v[0:3], v[170:173], v[202:205], v[0:3]
	v_mfma_f32_16x16x32_bf16 v[124:127], v[166:169], v[182:185], v[124:127]
	v_mfma_f32_16x16x32_bf16 v[112:115], v[174:177], v[182:185], v[112:115]
	v_mfma_f32_16x16x32_bf16 v[92:95], v[166:169], v[190:193], v[92:95]
	v_mfma_f32_16x16x32_bf16 v[88:91], v[174:177], v[190:193], v[88:91]
	v_mfma_f32_16x16x32_bf16 v[44:47], v[166:169], v[198:201], v[44:47]
	v_mfma_f32_16x16x32_bf16 v[40:43], v[174:177], v[198:201], v[40:43]
	v_mfma_f32_16x16x32_bf16 v[4:7], v[166:169], v[206:209], v[4:7]
	v_mfma_f32_16x16x32_bf16 v[0:3], v[174:177], v[206:209], v[0:3]
	s_barrier
	ds_read_b128 v[146:149], v143
	ds_read_b128 v[150:153], v143 offset:1024
	ds_read_b128 v[154:157], v143 offset:2048
	ds_read_b128 v[158:161], v143 offset:3072
	ds_read_b128 v[162:165], v144
	ds_read_b128 v[166:169], v144 offset:1024
	ds_read_b128 v[170:173], v144 offset:2048
	ds_read_b128 v[174:177], v144 offset:3072
	s_add_u32 s52, s72, 0x4000
	s_addc_u32 s53, s73, 0
	s_mov_b32 m0, s21
	v_lshl_add_u64 v[214:215], s[52:53], 0, v[32:33]
	ds_read_b128 v[178:181], v142 offset:32768
	ds_read_b128 v[182:185], v142 offset:33792
	ds_read_b128 v[186:189], v142 offset:34816
	ds_read_b128 v[190:193], v142 offset:35840
	ds_read_b128 v[194:197], v142 offset:36864
	ds_read_b128 v[198:201], v142 offset:37888
	ds_read_b128 v[202:205], v142 offset:38912
	ds_read_b128 v[206:209], v142 offset:39936
	global_load_lds_dwordx4 v32, s[52:53]
	v_lshl_add_u64 v[214:215], s[52:53], 0, v[132:133]
	s_mov_b32 m0, s22
	s_nop 0
	global_load_lds_dwordx4 v132, s[52:53]
	s_waitcnt vmcnt(8) lgkmcnt(0)
	s_barrier
	v_mfma_f32_16x16x32_bf16 v[8:11], v[146:149], v[178:181], v[8:11]
	v_mfma_f32_16x16x32_bf16 v[12:15], v[154:157], v[178:181], v[12:15]
	v_mfma_f32_16x16x32_bf16 v[60:63], v[146:149], v[186:189], v[60:63]
	v_mfma_f32_16x16x32_bf16 v[20:23], v[154:157], v[186:189], v[20:23]
	v_mfma_f32_16x16x32_bf16 v[76:79], v[146:149], v[194:197], v[76:79]
	v_mfma_f32_16x16x32_bf16 v[52:55], v[154:157], v[194:197], v[52:55]
	v_mfma_f32_16x16x32_bf16 v[128:131], v[146:149], v[202:205], v[128:131]
	v_mfma_f32_16x16x32_bf16 v[68:71], v[154:157], v[202:205], v[68:71]
	v_mfma_f32_16x16x32_bf16 v[8:11], v[150:153], v[182:185], v[8:11]
	v_mfma_f32_16x16x32_bf16 v[12:15], v[158:161], v[182:185], v[12:15]
	v_mfma_f32_16x16x32_bf16 v[60:63], v[150:153], v[190:193], v[60:63]
	v_mfma_f32_16x16x32_bf16 v[20:23], v[158:161], v[190:193], v[20:23]
	v_mfma_f32_16x16x32_bf16 v[76:79], v[150:153], v[198:201], v[76:79]
	v_mfma_f32_16x16x32_bf16 v[52:55], v[158:161], v[198:201], v[52:55]
	v_mfma_f32_16x16x32_bf16 v[128:131], v[150:153], v[206:209], v[128:131]
	v_mfma_f32_16x16x32_bf16 v[68:71], v[158:161], v[206:209], v[68:71]
	v_mfma_f32_16x16x32_bf16 v[28:31], v[162:165], v[178:181], v[28:31]
	v_mfma_f32_16x16x32_bf16 v[16:19], v[170:173], v[178:181], v[16:19]
	v_mfma_f32_16x16x32_bf16 v[56:59], v[162:165], v[186:189], v[56:59]
	v_mfma_f32_16x16x32_bf16 v[48:51], v[170:173], v[186:189], v[48:51]
	v_mfma_f32_16x16x32_bf16 v[72:75], v[162:165], v[194:197], v[72:75]
	v_mfma_f32_16x16x32_bf16 v[64:67], v[170:173], v[194:197], v[64:67]
	v_mfma_f32_16x16x32_bf16 v[108:111], v[162:165], v[202:205], v[108:111]
	v_mfma_f32_16x16x32_bf16 v[96:99], v[170:173], v[202:205], v[96:99]
	v_mfma_f32_16x16x32_bf16 v[28:31], v[166:169], v[182:185], v[28:31]
	v_mfma_f32_16x16x32_bf16 v[16:19], v[174:177], v[182:185], v[16:19]
	v_mfma_f32_16x16x32_bf16 v[56:59], v[166:169], v[190:193], v[56:59]
	v_mfma_f32_16x16x32_bf16 v[48:51], v[174:177], v[190:193], v[48:51]
	v_mfma_f32_16x16x32_bf16 v[72:75], v[166:169], v[198:201], v[72:75]
	v_mfma_f32_16x16x32_bf16 v[64:67], v[174:177], v[198:201], v[64:67]
	v_mfma_f32_16x16x32_bf16 v[108:111], v[166:169], v[206:209], v[108:111]
	v_mfma_f32_16x16x32_bf16 v[96:99], v[174:177], v[206:209], v[96:99]
	s_barrier
; #define PG8_MMA(ai, bj, At, Bt) do { __builtin_amdgcn_s_setprio(1); _Pragma("unroll") for (int m = 0; m < 4; ++m) _Pragma("unroll") for (int n = 0; n < 2; ++n) _Pragma("unroll") for (int k = 0; k < 2; ++k) \
;         acc[ai][bj][m][n] = __builtin_amdgcn_mfma_f32_16x16x32_bf16(Bt[n][k], At[m][k], acc[ai][bj][m][n], 0, 0, 0); __builtin_amdgcn_s_setprio(0); } while (0)
; template <class Epi, class Sched, bool ALIGN_EPI = false, bool SP2 = false, bool A_TILED = false>
; __device__ __forceinline__ void gemm_phase(PG8_LAS unsigned char* lds, const Gemm g, const Sched& S, const Epi& E, const int wave_s) {
;     ...
;         for (int t = PEEL ? 2 : 0; t < nt; t += 2) {
;             const bool last = (t == nt - 2);
;             const char* a1 = cA + (size_t)(t + 1) * kstepA;
;             const char* a2 = last ? nA : cA + (size_t)(t + 2) * kstepA; const char* b2 = last ? nB : cB + (size_t)(t + 2) * kstep;
;             const char* a3 = a2 + kstepA; const char* b3 = b2 + kstep;
;             if (last && has_next) S.a_ready(nxt);
;             if constexpr (SP2) {
;             PG8_ITER(PG8_MMA)
	s_mov_b32 m0, s48
	v_lshl_add_u64 v[210:211], v[210:211], 0, s[64:65]
	s_add_u32 s52, s70, 0x200080
	ds_read_b128 v[178:181], v142 offset:49152
	ds_read_b128 v[182:185], v142 offset:50176
	ds_read_b128 v[186:189], v142 offset:51200
	ds_read_b128 v[190:193], v142 offset:52224
	ds_read_b128 v[194:197], v142 offset:53248
	ds_read_b128 v[198:201], v142 offset:54272
	ds_read_b128 v[202:205], v142 offset:55296
	ds_read_b128 v[206:209], v142 offset:56320
	global_load_lds_dwordx4 v[210:211], off
	v_lshl_add_u64 v[210:211], v[212:213], 0, s[64:65]
	s_mov_b32 m0, s49
	s_addc_u32 s53, s71, 0
	global_load_lds_dwordx4 v[210:211], off
	v_lshl_add_u64 v[210:211], s[52:53], 0, v[34:35]
	s_mov_b32 m0, s50
	s_nop 0
	global_load_lds_dwordx4 v34, s[52:53]
	v_lshl_add_u64 v[210:211], s[52:53], 0, v[134:135]
	s_mov_b32 m0, s51
	s_nop 0
	global_load_lds_dwordx4 v134, s[52:53]
	v_lshl_add_u64 v[210:211], s[68:69], 0, v[32:33]
	s_mov_b32 m0, s23
	s_nop 0
	global_load_lds_dwordx4 v32, s[68:69]
	v_lshl_add_u64 v[210:211], s[68:69], 0, v[132:133]
	s_mov_b32 m0, s36
	s_nop 0
	global_load_lds_dwordx4 v132, s[68:69]
	s_waitcnt vmcnt(8) lgkmcnt(0)
	s_barrier
	v_mfma_f32_16x16x32_bf16 v[100:103], v[146:149], v[178:181], v[100:103]
	v_mfma_f32_16x16x32_bf16 v[104:107], v[154:157], v[178:181], v[104:107]
	v_mfma_f32_16x16x32_bf16 v[116:119], v[146:149], v[186:189], v[116:119]
	v_mfma_f32_16x16x32_bf16 v[120:123], v[154:157], v[186:189], v[120:123]
	v_mfma_f32_16x16x32_bf16 v[84:87], v[146:149], v[194:197], v[84:87]
	v_mfma_f32_16x16x32_bf16 v[80:83], v[154:157], v[194:197], v[80:83]
	v_mfma_f32_16x16x32_bf16 v[36:39], v[146:149], v[202:205], v[36:39]
	v_mfma_f32_16x16x32_bf16 v[24:27], v[154:157], v[202:205], v[24:27]
	v_mfma_f32_16x16x32_bf16 v[100:103], v[150:153], v[182:185], v[100:103]
	v_mfma_f32_16x16x32_bf16 v[104:107], v[158:161], v[182:185], v[104:107]
	v_mfma_f32_16x16x32_bf16 v[116:119], v[150:153], v[190:193], v[116:119]
	v_mfma_f32_16x16x32_bf16 v[120:123], v[158:161], v[190:193], v[120:123]
	v_mfma_f32_16x16x32_bf16 v[84:87], v[150:153], v[198:201], v[84:87]
	v_mfma_f32_16x16x32_bf16 v[80:83], v[158:161], v[198:201], v[80:83]
	v_mfma_f32_16x16x32_bf16 v[36:39], v[150:153], v[206:209], v[36:39]
	v_mfma_f32_16x16x32_bf16 v[24:27], v[158:161], v[206:209], v[24:27]
	v_mfma_f32_16x16x32_bf16 v[124:127], v[162:165], v[178:181], v[124:127]
	v_mfma_f32_16x16x32_bf16 v[112:115], v[170:173], v[178:181], v[112:115]
	v_mfma_f32_16x16x32_bf16 v[92:95], v[162:165], v[186:189], v[92:95]
	v_mfma_f32_16x16x32_bf16 v[88:91], v[170:173], v[186:189], v[88:91]
	v_mfma_f32_16x16x32_bf16 v[44:47], v[162:165], v[194:197], v[44:47]
	v_mfma_f32_16x16x32_bf16 v[40:43], v[170:173], v[194:197], v[40:43]
	v_mfma_f32_16x16x32_bf16 v[4:7], v[162:165], v[202:205], v[4:7]
	v_mfma_f32_16x16x32_bf16 v[0:3], v[170:173], v[202:205], v[0:3]
	v_mfma_f32_16x16x32_bf16 v[124:127], v[166:169], v[182:185], v[124:127]
	v_mfma_f32_16x16x32_bf16 v[112:115], v[174:177], v[182:185], v[112:115]
	v_mfma_f32_16x16x32_bf16 v[92:95], v[166:169], v[190:193], v[92:95]
	v_mfma_f32_16x16x32_bf16 v[88:91], v[174:177], v[190:193], v[88:91]
	v_mfma_f32_16x16x32_bf16 v[44:47], v[166:169], v[198:201], v[44:47]
	v_mfma_f32_16x16x32_bf16 v[40:43], v[174:177], v[198:201], v[40:43]
	v_mfma_f32_16x16x32_bf16 v[4:7], v[166:169], v[206:209], v[4:7]
	v_mfma_f32_16x16x32_bf16 v[0:3], v[174:177], v[206:209], v[0:3]
	s_barrier
	s_add_i32 s41, s41, 2
	s_add_u32 s37, s37, 0x100
	s_addc_u32 s38, s38, 0
	s_add_u32 s39, s39, 0x10000
	s_addc_u32 s40, s40, 0
	v_lshl_add_u64 v[136:137], v[136:137], 0, s[66:67]
	s_cmpk_gt_u32 s41, 0x7d
	v_lshl_add_u64 v[138:139], v[138:139], 0, s[66:67]
	s_cbranch_scc0 .LBB0_1228
	s_waitcnt vmcnt(0)
	s_cmpk_lt_u32 s8, 0x100
	s_cbranch_scc0 .LBB0_1231
	s_barrier

; __device__ __forceinline__ int tid_now(int wave_s) { unsigned z = 0u; asm volatile("" : "+v"(z)); return (wave_s << 6) | (int)__builtin_amdgcn_mbcnt_hi(~0u, __builtin_amdgcn_mbcnt_lo(~0u, z)); }
; __device__ __forceinline__ unsigned xb_ld(unsigned* p)              { return __hip_atomic_load(p, __ATOMIC_RELAXED, __HIP_MEMORY_SCOPE_AGENT); }
; __device__ __forceinline__ unsigned xb_add(unsigned* p, unsigned v) { return __hip_atomic_fetch_add(p, v, __ATOMIC_RELAXED, __HIP_MEMORY_SCOPE_AGENT); }
; #define XB_SPIN(cond, bar) do { unsigned _sp = 0; while (cond) { __builtin_amdgcn_s_sleep(1); \
;     if ((++_sp & 255u) == 0u) { if (xb_ld(&(bar)[XB_TMO])) break; if (_sp > XB_SPIN_CAP) { atomicAdd(&(bar)[XB_TMO], 1u); break; } } } } while (0)
; __device__ __forceinline__ void xcd_barrier(const XcdBarrier& b) {
;     asm volatile("s_waitcnt vmcnt(0)" ::: "memory");
;     __syncthreads();
;     if (tid_now(b.w) == 0) {
;         unsigned* bar = b.bar;
;         __builtin_amdgcn_s_waitcnt(0);
;         unsigned nloc = b.st[0], nx = b.st[1];
;         if (nloc == 0u) { xcd_barrier_complete(bar, b.x, nloc, nx, b.np); b.st[0] = nloc; b.st[1] = nx; }
;         const unsigned old = xb_add(&bar[XB_XSUB(b.x)], 1u);
;         const unsigned gen = old / nloc;
;         if (old + 1u == (gen + 1u) * nloc) {
;             __builtin_amdgcn_fence(__ATOMIC_RELEASE, "agent");
;             asm volatile("s_waitcnt vmcnt(0)" ::: "memory");
;             const unsigned og = xb_add(&bar[XB_TOP], 1u);
;             const unsigned tg = og / nx;
;             if (og + 1u == (tg + 1u) * nx) xb_add(&bar[XB_TOPGEN], 1u);
;             else XB_SPIN(xb_ld(&bar[XB_TOPGEN]) == tg, bar);
;             __builtin_amdgcn_fence(__ATOMIC_ACQUIRE, "agent");
;             xb_add(&bar[XB_XGEN(b.x)], 1u);
;             asm volatile("s_waitcnt vmcnt(0)" ::: "memory");
;         } else {
;             XB_SPIN(xb_ld(&bar[XB_XGEN(b.x)]) == gen, bar);
;             __builtin_amdgcn_fence(__ATOMIC_ACQUIRE, "agent");
;             asm volatile("s_waitcnt vmcnt(0)" ::: "memory");
;         }
;     }
;     __syncthreads();
; }
.LBB0_1272:
	s_setprio 0
	s_cmp_gt_i32 s35, 7
	s_cselect_b64 s[12:13], -1, 0
	s_and_b64 s[0:1], s[60:61], s[12:13]
	s_andn2_b64 vcc, exec, s[0:1]
	s_cbranch_vccnz .LBB0_1326
	s_waitcnt vmcnt(0)
	v_mov_b32_e32 v0, 0
	s_waitcnt vmcnt(0)
	s_waitcnt lgkmcnt(0)
	s_barrier
	s_nop 0
	v_mbcnt_lo_u32_b32 v0, -1, v0
	v_mbcnt_hi_u32_b32 v0, -1, v0
	v_or_b32_e32 v0, s33, v0
	v_cmp_eq_u32_e32 vcc, 0, v0
	s_and_saveexec_b64 s[0:1], vcc
	s_cbranch_execz .LBB0_1325
	s_add_i32 s2, 0, 0x27f68
	v_mov_b32_e32 v0, s2
	s_waitcnt vmcnt(0) expcnt(0) lgkmcnt(0)
	ds_read_b32 v2, v0
	s_add_i32 s2, 0, 0x27f6c
	v_mov_b32_e32 v0, s2
	ds_read_b32 v0, v0
	s_waitcnt lgkmcnt(1)
	v_cmp_ne_u32_e32 vcc, 0, v2
	s_cbranch_vccnz .LBB0_1289
	s_add_u32 s2, s10, 0x1000
	s_addc_u32 s3, s11, 0
	s_add_u32 s4, s10, 0x1100
	s_addc_u32 s5, s11, 0
	s_add_u32 s60, s10, 0x1200
	s_addc_u32 s61, s11, 0
	s_add_u32 s62, s10, 0x1300
	s_addc_u32 s63, s11, 0
	s_mov_b32 s6, 1
	v_mov_b32_e32 v16, 0
	s_branch .LBB0_1277

; #define PG8_STAGE(bufoff, gbase, voff) do { _Pragma("unroll") for (int _i = 0; _i < 2; ++_i) \
;         __builtin_amdgcn_global_load_lds((const unsigned*)((const char*)(gbase) + (voff)[_i]), (PG8_LAS unsigned*)(lds + (bufoff) + ldsw + _i * 8192), 16, 0, 0); } while (0)
; #define PG8_WAIT_V(n) asm volatile("s_waitcnt vmcnt(" #n ")" ::: "memory")
; #define PG8_BAR __builtin_amdgcn_s_barrier()
; template <class Epi, class Sched, bool ALIGN_EPI = false, bool SP2 = false, bool A_TILED = false>
; __device__ __forceinline__ void gemm_phase(PG8_LAS unsigned char* lds, const Gemm g, const Sched& S, const Epi& E, const int wave_s) {
;     ...
;     const int tid = tid_, wid = __builtin_amdgcn_readfirstlane(tid >> 6), lane = tid & 63, wr = wid >> 2, wc = wid & 3, fr = lane & 15, fq = lane >> 4;
;     const int K = g.K, nt = K / BK;
;     unsigned voffA[2], voffB[2];
; #pragma unroll
;     for (int i = 0; i < 2; ++i) { int R, C; stage_rc(tid * 16 + i * 8192, R, C); const int Rb = Epi::PERM ? ((R & ~31) + perm32(R & 31)) : R;
;         voffA[i] = A_TILED ? (unsigned)(tid * 16 + i * 8192) : (unsigned)(R * K + C) * 2u; voffB[i] = (unsigned)(Rb * K + C) * 2u; }
;     const size_t kstep = (size_t)(BK * 2);
;     const size_t hstep = (size_t)HALF * K * 2;
;     const size_t tstep = 2 * hstep;
;     const size_t kstepA = A_TILED ? (size_t)32768 : kstep, hstepA = A_TILED ? (size_t)16384 : hstep, tstepA = A_TILED ? (size_t)nt * 32768 : tstep;
;     const unsigned ldsw = (unsigned)wid * 1024u;
;     const int aoff = lds_byte(wr * 64 + fr, fq * 8), boff = lds_byte(wc * 32 + fr, fq * 8);
;     ...
;     if constexpr (SP2) {
;         PG8_STAGE(PG8_SB(0, 0), cB, voffB); PG8_STAGE(PG8_SB(0, 1), cB + hstep, voffB); PG8_STAGE(PG8_SA(0, 0), cA, voffA); PG8_STAGE(PG8_SA(0, 1), cA + hstepA, voffA);
;         if (wr == 1) PG8_BAR;
;         PG8_WAIT_V(2); PG8_BAR;
;         PG8_STAGE(PG8_SB(1, 0), cB + kstep, voffB); PG8_STAGE(PG8_SA(1, 0), cA + kstepA, voffA); PG8_STAGE(PG8_SB(1, 1), cB + hstep + kstep, voffB);
;         PG8_WAIT_V(6); PG8_BAR;
.LBB0_1613:
	s_ashr_i32 s40, s86, 31
	s_sext_i32_i16 s50, s12
	s_add_u32 s12, s2, 0x22600000
	s_addc_u32 s13, s3, 0
	v_and_b32_e32 v15, 48, v14
	v_lshlrev_b32_e32 v16, 6, v14
	s_movk_i32 s3, 0x3c0
	v_lshlrev_b32_e32 v14, 2, v14
	s_mov_b64 s[60:61], 0x80
	s_and_b32 s46, s41, 3
	s_lshl_b32 s2, s42, 13
	v_and_or_b32 v15, v16, s3, v15
	v_and_b32_e32 v14, 32, v14
	s_add_i32 m0, s23, 0x18000
	v_lshl_add_u64 v[6:7], v[6:7], 0, s[60:61]
	s_lshl_b32 s41, s42, 6
	v_bitop3_b32 v16, v15, s2, v14 bitop3:0xde
	s_lshl_b32 s42, s46, 5
	s_lshl_b32 s2, s46, 12
	s_waitcnt vmcnt(2)
	s_barrier
	global_load_lds_dwordx4 v[6:7], off
	v_lshl_add_u64 v[4:5], v[4:5], 0, s[60:61]
	s_add_i32 m0, s23, 0x1a000
	s_add_i32 s43, s23, 0x8000
	s_add_i32 s44, s23, 0xa000
	v_bitop3_b32 v148, v15, s2, v14 bitop3:0xde
	global_load_lds_dwordx4 v[4:5], off
	v_lshl_add_u64 v[0:1], v[0:1], 0, s[60:61]
	s_mov_b32 m0, s43
	s_add_u32 s2, s78, 0x80080
	global_load_lds_dwordx4 v[0:1], off
	v_lshl_add_u64 v[0:1], v[2:3], 0, s[60:61]
	s_mov_b32 m0, s44
	s_addc_u32 s3, s79, 0
	global_load_lds_dwordx4 v[0:1], off
	s_add_i32 m0, s23, 0x1c000
	v_lshl_add_u64 v[0:1], s[2:3], 0, v[128:129]
	global_load_lds_dwordx4 v128, s[2:3]
	v_lshl_add_u64 v[0:1], s[2:3], 0, v[130:131]
	s_add_i32 m0, s23, 0x1e000
	s_cmpk_lt_u32 s45, 0x100
	global_load_lds_dwordx4 v130, s[2:3]
	v_lshlrev_b32_e32 v0, 15, v8
	v_and_b32_e32 v0, 0xffff0000, v0
	v_lshl_add_u32 v0, v9, 12, v0
	v_and_b32_e32 v1, 1, v8
	v_lshl_or_b32 v0, v1, 6, v0
	v_lshl_add_u32 v136, v10, 1, v0
	v_lshlrev_b32_e32 v0, 15, v12
	v_and_b32_e32 v0, 0xffff0000, v0
	s_waitcnt vmcnt(6)
	s_mov_b32 s98, 0
	v_lshl_add_u32 v0, v11, 12, v0
	v_and_b32_e32 v1, 1, v12
	s_cselect_b64 s[62:63], -1, 0
	s_bitcmp1_b32 s33, 8
	s_cbranch_scc1 .Lsp_5
	s_setprio 1
.Lsp_5:
	s_lshl_b32 s45, s46, 4
	v_mov_b32_e32 v137, 0
	v_lshl_or_b32 v0, v1, 6, v0
	s_add_i32 s46, 0, 0x10000
	s_add_i32 s47, 0, 0x14000
	v_lshl_add_u32 v138, v13, 1, v0
	v_mov_b32_e32 v139, v137
	v_add_u32_e32 v149, s46, v148
	v_add_u32_e32 v150, s47, v148
	v_add_u32_e32 v151, 0, v16
	s_mov_b64 s[64:65], 0x100
	s_mov_b64 s[66:67], 0x180
	s_mov_b32 s48, 0xc2fc0000
	s_mov_b32 s49, 0x9000
	v_mov_b32_e32 v152, 0x42800000
	v_not_b32_e32 v153, 63
	s_barrier
	s_branch .LBB0_1616

.Lpw_5:
	s_barrier
	v_mfma_f32_16x16x32_bf16 v[88:91], v[0:3], v[56:59], 0
	v_mfma_f32_16x16x32_bf16 v[64:67], v[0:3], v[32:35], 0
	v_mfma_f32_16x16x32_bf16 v[68:71], v[8:11], v[32:35], 0
	v_mfma_f32_16x16x32_bf16 v[72:75], v[0:3], v[40:43], 0
	v_mfma_f32_16x16x32_bf16 v[76:79], v[8:11], v[40:43], 0
	v_mfma_f32_16x16x32_bf16 v[80:83], v[0:3], v[48:51], 0
	v_mfma_f32_16x16x32_bf16 v[84:87], v[8:11], v[48:51], 0
	v_mfma_f32_16x16x32_bf16 v[96:99], v[4:7], v[60:63], v[88:91]
	v_mfma_f32_16x16x32_bf16 v[88:91], v[8:11], v[56:59], 0
	v_mfma_f32_16x16x32_bf16 v[64:67], v[4:7], v[36:39], v[64:67]
	v_mfma_f32_16x16x32_bf16 v[68:71], v[12:15], v[36:39], v[68:71]
	v_mfma_f32_16x16x32_bf16 v[72:75], v[4:7], v[44:47], v[72:75]
	v_mfma_f32_16x16x32_bf16 v[76:79], v[12:15], v[44:47], v[76:79]
	v_mfma_f32_16x16x32_bf16 v[80:83], v[4:7], v[52:55], v[80:83]
	v_mfma_f32_16x16x32_bf16 v[84:87], v[12:15], v[52:55], v[84:87]
	v_mfma_f32_16x16x32_bf16 v[100:103], v[12:15], v[60:63], v[88:91]
	v_mfma_f32_16x16x32_bf16 v[88:91], v[16:19], v[32:35], 0
	v_mfma_f32_16x16x32_bf16 v[32:35], v[24:27], v[32:35], 0
	v_mfma_f32_16x16x32_bf16 v[112:115], v[20:23], v[36:39], v[88:91]
	v_mfma_f32_16x16x32_bf16 v[32:35], v[28:31], v[36:39], v[32:35]
	v_mfma_f32_16x16x32_bf16 v[36:39], v[16:19], v[40:43], 0
	v_mfma_f32_16x16x32_bf16 v[40:43], v[24:27], v[40:43], 0
	v_mfma_f32_16x16x32_bf16 v[36:39], v[20:23], v[44:47], v[36:39]
	v_mfma_f32_16x16x32_bf16 v[40:43], v[28:31], v[44:47], v[40:43]
	v_mfma_f32_16x16x32_bf16 v[44:47], v[16:19], v[48:51], 0
	v_mfma_f32_16x16x32_bf16 v[48:51], v[24:27], v[48:51], 0
	v_mfma_f32_16x16x32_bf16 v[44:47], v[20:23], v[52:55], v[44:47]
	v_mfma_f32_16x16x32_bf16 v[48:51], v[28:31], v[52:55], v[48:51]
	v_mfma_f32_16x16x32_bf16 v[52:55], v[16:19], v[56:59], 0
	v_mfma_f32_16x16x32_bf16 v[56:59], v[24:27], v[56:59], 0
	v_mfma_f32_16x16x32_bf16 v[52:55], v[20:23], v[60:63], v[52:55]
	v_mfma_f32_16x16x32_bf16 v[56:59], v[28:31], v[60:63], v[56:59]
	s_barrier
	s_add_i32 s57, s46, s15
	v_lshl_add_u64 v[250:251], s[78:79], 0, v[128:129]
	s_add_i32 s58, s57, 0x2000
	v_lshl_add_u64 v[144:145], v[250:251], 0, s[64:65]
	s_mov_b32 m0, s57
	v_lshl_add_u64 v[252:253], s[78:79], 0, v[130:131]
	s_add_u32 s82, s78, 0x80100
	ds_read_b128 v[60:63], v151 offset:16384
	ds_read_b128 v[88:91], v151 offset:17408
	ds_read_b128 v[92:95], v151 offset:18432
	ds_read_b128 v[104:107], v151 offset:19456
	ds_read_b128 v[108:111], v151 offset:20480
	ds_read_b128 v[116:119], v151 offset:21504
	ds_read_b128 v[120:123], v151 offset:22528
	ds_read_b128 v[124:127], v151 offset:23552
	global_load_lds_dwordx4 v[144:145], off
	v_lshl_add_u64 v[144:145], v[252:253], 0, s[64:65]
	s_mov_b32 m0, s58
	s_addc_u32 s83, s79, 0
	s_add_i32 s59, s47, s15
	global_load_lds_dwordx4 v[144:145], off
	v_lshl_add_u64 v[144:145], s[82:83], 0, v[128:129]
	s_mov_b32 m0, s59
	s_add_i32 s69, s59, 0x2000
	global_load_lds_dwordx4 v128, s[82:83]
	v_lshl_add_u64 v[144:145], s[82:83], 0, v[130:131]
	s_mov_b32 m0, s69
	v_lshl_add_u64 v[140:141], s[80:81], 0, v[134:135]
	global_load_lds_dwordx4 v130, s[82:83]
	v_lshl_add_u64 v[144:145], v[140:141], 0, s[64:65]
	s_mov_b32 m0, s23
	v_lshl_add_u64 v[142:143], s[80:81], 0, v[132:133]
	global_load_lds_dwordx4 v[144:145], off
	v_lshl_add_u64 v[144:145], v[142:143], 0, s[64:65]
	s_mov_b32 m0, s36
	s_nop 0
	global_load_lds_dwordx4 v[144:145], off
	s_waitcnt vmcnt(24) lgkmcnt(0)
	s_cmp_lg_u32 s98, 0
	s_cbranch_scc1 .Lpw_6
	s_waitcnt vmcnt(8)
.Lpw_6:
	s_barrier
	v_mfma_f32_16x16x32_bf16 v[144:147], v[0:3], v[60:63], 0
	v_mfma_f32_16x16x32_bf16 v[154:157], v[4:7], v[88:91], v[144:147]
	v_mfma_f32_16x16x32_bf16 v[144:147], v[8:11], v[60:63], 0
	v_mfma_f32_16x16x32_bf16 v[158:161], v[12:15], v[88:91], v[144:147]
	v_mfma_f32_16x16x32_bf16 v[144:147], v[0:3], v[92:95], 0
	v_mfma_f32_16x16x32_bf16 v[162:165], v[4:7], v[104:107], v[144:147]
	v_mfma_f32_16x16x32_bf16 v[144:147], v[8:11], v[92:95], 0
	v_mfma_f32_16x16x32_bf16 v[166:169], v[12:15], v[104:107], v[144:147]
	v_mfma_f32_16x16x32_bf16 v[144:147], v[0:3], v[108:111], 0
	v_mfma_f32_16x16x32_bf16 v[0:3], v[0:3], v[120:123], 0
	v_mfma_f32_16x16x32_bf16 v[170:173], v[4:7], v[116:119], v[144:147]
	v_mfma_f32_16x16x32_bf16 v[0:3], v[4:7], v[124:127], v[0:3]
	v_mfma_f32_16x16x32_bf16 v[4:7], v[8:11], v[120:123], 0
	v_mfma_f32_16x16x32_bf16 v[144:147], v[8:11], v[108:111], 0
	v_mfma_f32_16x16x32_bf16 v[4:7], v[12:15], v[124:127], v[4:7]
	v_mfma_f32_16x16x32_bf16 v[174:177], v[12:15], v[116:119], v[144:147]
	v_mfma_f32_16x16x32_bf16 v[8:11], v[16:19], v[60:63], 0
	v_mfma_f32_16x16x32_bf16 v[178:181], v[20:23], v[88:91], v[8:11]
	v_mfma_f32_16x16x32_bf16 v[8:11], v[24:27], v[60:63], 0
	v_mfma_f32_16x16x32_bf16 v[182:185], v[28:31], v[88:91], v[8:11]
	v_mfma_f32_16x16x32_bf16 v[8:11], v[16:19], v[92:95], 0
	v_mfma_f32_16x16x32_bf16 v[186:189], v[20:23], v[104:107], v[8:11]
	v_mfma_f32_16x16x32_bf16 v[8:11], v[24:27], v[92:95], 0
	v_mfma_f32_16x16x32_bf16 v[190:193], v[28:31], v[104:107], v[8:11]
	v_mfma_f32_16x16x32_bf16 v[8:11], v[16:19], v[108:111], 0
	v_mfma_f32_16x16x32_bf16 v[194:197], v[20:23], v[116:119], v[8:11]
	v_mfma_f32_16x16x32_bf16 v[8:11], v[24:27], v[108:111], 0
	v_mfma_f32_16x16x32_bf16 v[198:201], v[28:31], v[116:119], v[8:11]
	v_mfma_f32_16x16x32_bf16 v[8:11], v[16:19], v[120:123], 0
	v_mfma_f32_16x16x32_bf16 v[202:205], v[20:23], v[124:127], v[8:11]
	v_mfma_f32_16x16x32_bf16 v[8:11], v[24:27], v[120:123], 0
	v_mfma_f32_16x16x32_bf16 v[206:209], v[28:31], v[124:127], v[8:11]
	s_barrier
; template <class Epi, class Sched, bool ALIGN_EPI = false, bool SP2 = false, bool A_TILED = false>
; __device__ __forceinline__ void gemm_phase(PG8_LAS unsigned char* lds, const Gemm g, const Sched& S, const Epi& E, const int wave_s) {
;     ...
; #pragma nounroll
;         for (int t = PEEL ? 2 : 0; t < nt; t += 2) {
;             const bool last = (t == nt - 2);
;             const char* a1 = cA + (size_t)(t + 1) * kstepA;
;             const char* a2 = last ? nA : cA + (size_t)(t + 2) * kstepA; const char* b2 = last ? nB : cB + (size_t)(t + 2) * kstep;
;             const char* a3 = a2 + kstepA; const char* b3 = b2 + kstep;
	s_add_i32 s71, 0, 0x18000
	s_add_i32 s88, 0, 0x1c000
	v_add_u32_e32 v144, s71, v148
	v_add_u32_e32 v145, s88, v148
	s_nop 0
	ds_read_b128 v[8:11], v144
	ds_read_b128 v[12:15], v144 offset:1024
	ds_read_b128 v[16:19], v144 offset:2048
	ds_read_b128 v[20:23], v144 offset:3072
	ds_read_b128 v[210:213], v145
	ds_read_b128 v[214:217], v145 offset:1024
	ds_read_b128 v[218:221], v145 offset:2048
	ds_read_b128 v[222:225], v145 offset:3072
	s_add_u32 s82, s80, 0x80100
	s_addc_u32 s83, s81, 0
	s_mov_b32 m0, s37
	v_lshl_add_u64 v[88:89], s[82:83], 0, v[134:135]
	ds_read_b128 v[24:27], v151 offset:32768
	ds_read_b128 v[28:31], v151 offset:33792
	ds_read_b128 v[60:63], v151 offset:34816
	ds_read_b128 v[226:229], v151 offset:35840
	ds_read_b128 v[230:233], v151 offset:36864
	ds_read_b128 v[234:237], v151 offset:37888
	ds_read_b128 v[238:241], v151 offset:38912
	ds_read_b128 v[242:245], v151 offset:39936
	global_load_lds_dwordx4 v134, s[82:83]
	v_lshl_add_u64 v[88:89], s[82:83], 0, v[132:133]
	s_mov_b32 m0, s38
	s_nop 0
	global_load_lds_dwordx4 v132, s[82:83]
	s_waitcnt vmcnt(8) lgkmcnt(0)
	s_barrier
	v_mfma_f32_16x16x32_bf16 v[64:67], v[8:11], v[24:27], v[64:67]
	v_mfma_f32_16x16x32_bf16 v[124:127], v[12:15], v[28:31], v[64:67]
	v_mfma_f32_16x16x32_bf16 v[64:67], v[16:19], v[24:27], v[68:71]
	v_mfma_f32_16x16x32_bf16 v[120:123], v[20:23], v[28:31], v[64:67]
	v_mfma_f32_16x16x32_bf16 v[64:67], v[8:11], v[60:63], v[72:75]
	v_mfma_f32_16x16x32_bf16 v[108:111], v[12:15], v[226:229], v[64:67]
	v_mfma_f32_16x16x32_bf16 v[64:67], v[16:19], v[60:63], v[76:79]
	v_mfma_f32_16x16x32_bf16 v[104:107], v[20:23], v[226:229], v[64:67]
	v_mfma_f32_16x16x32_bf16 v[64:67], v[8:11], v[230:233], v[80:83]
	v_mfma_f32_16x16x32_bf16 v[92:95], v[12:15], v[234:237], v[64:67]
	v_mfma_f32_16x16x32_bf16 v[64:67], v[16:19], v[230:233], v[84:87]
	v_mfma_f32_16x16x32_bf16 v[88:91], v[20:23], v[234:237], v[64:67]
	v_mfma_f32_16x16x32_bf16 v[64:67], v[8:11], v[238:241], v[96:99]
	v_mfma_f32_16x16x32_bf16 v[76:79], v[12:15], v[242:245], v[64:67]
	v_mfma_f32_16x16x32_bf16 v[64:67], v[16:19], v[238:241], v[100:103]
	v_mfma_f32_16x16x32_bf16 v[72:75], v[20:23], v[242:245], v[64:67]
	v_mfma_f32_16x16x32_bf16 v[64:67], v[210:213], v[24:27], v[112:115]
	v_mfma_f32_16x16x32_bf16 v[24:27], v[218:221], v[24:27], v[32:35]
	v_mfma_f32_16x16x32_bf16 v[112:115], v[222:225], v[28:31], v[24:27]
	v_mfma_f32_16x16x32_bf16 v[24:27], v[210:213], v[60:63], v[36:39]
	v_mfma_f32_16x16x32_bf16 v[100:103], v[214:217], v[226:229], v[24:27]
	v_mfma_f32_16x16x32_bf16 v[24:27], v[218:221], v[60:63], v[40:43]
	v_mfma_f32_16x16x32_bf16 v[96:99], v[222:225], v[226:229], v[24:27]
	v_mfma_f32_16x16x32_bf16 v[24:27], v[210:213], v[230:233], v[44:47]
	v_mfma_f32_16x16x32_bf16 v[84:87], v[214:217], v[234:237], v[24:27]
	v_mfma_f32_16x16x32_bf16 v[24:27], v[218:221], v[230:233], v[48:51]
	v_mfma_f32_16x16x32_bf16 v[80:83], v[222:225], v[234:237], v[24:27]
	v_mfma_f32_16x16x32_bf16 v[24:27], v[210:213], v[238:241], v[52:55]
	v_mfma_f32_16x16x32_bf16 v[68:71], v[214:217], v[242:245], v[24:27]
	v_mfma_f32_16x16x32_bf16 v[24:27], v[218:221], v[238:241], v[56:59]
	v_mfma_f32_16x16x32_bf16 v[116:119], v[214:217], v[28:31], v[64:67]
	v_mfma_f32_16x16x32_bf16 v[64:67], v[222:225], v[242:245], v[24:27]
	s_barrier
	s_add_i32 s71, s71, s15
	s_add_i32 s77, s71, 0x2000
	s_nop 1
	v_lshl_add_u64 v[24:25], v[250:251], 0, s[66:67]
	s_mov_b32 m0, s71
	s_add_u32 s82, s78, 0x80180
	ds_read_b128 v[32:35], v151 offset:49152
	ds_read_b128 v[36:39], v151 offset:50176
	ds_read_b128 v[226:229], v151 offset:51200
	ds_read_b128 v[230:233], v151 offset:52224
	ds_read_b128 v[234:237], v151 offset:53248
	ds_read_b128 v[238:241], v151 offset:54272
	ds_read_b128 v[242:245], v151 offset:55296
	ds_read_b128 v[246:249], v151 offset:56320
	global_load_lds_dwordx4 v[24:25], off
	v_lshl_add_u64 v[24:25], v[252:253], 0, s[66:67]
	s_mov_b32 m0, s77
	s_addc_u32 s83, s79, 0
	s_add_i32 s88, s88, s15
	global_load_lds_dwordx4 v[24:25], off
	v_lshl_add_u64 v[24:25], s[82:83], 0, v[128:129]
	s_mov_b32 m0, s88
	s_add_i32 s89, s88, 0x2000
	global_load_lds_dwordx4 v128, s[82:83]
	v_lshl_add_u64 v[24:25], s[82:83], 0, v[130:131]
	s_mov_b32 m0, s89
	s_nop 0
	global_load_lds_dwordx4 v130, s[82:83]
	v_lshl_add_u64 v[24:25], v[140:141], 0, s[66:67]
	s_mov_b32 m0, s43
	s_nop 0
	global_load_lds_dwordx4 v[24:25], off
	v_lshl_add_u64 v[24:25], v[142:143], 0, s[66:67]
	s_mov_b32 m0, s44
	s_nop 0
	global_load_lds_dwordx4 v[24:25], off
	s_waitcnt vmcnt(8) lgkmcnt(0)
	s_barrier
	v_mfma_f32_16x16x32_bf16 v[24:27], v[8:11], v[32:35], v[154:157]
	v_mfma_f32_16x16x32_bf16 v[60:63], v[12:15], v[36:39], v[24:27]
	v_mfma_f32_16x16x32_bf16 v[24:27], v[16:19], v[32:35], v[158:161]
	v_mfma_f32_16x16x32_bf16 v[56:59], v[20:23], v[36:39], v[24:27]
	v_mfma_f32_16x16x32_bf16 v[24:27], v[8:11], v[226:229], v[162:165]
	v_mfma_f32_16x16x32_bf16 v[44:47], v[12:15], v[230:233], v[24:27]
	v_mfma_f32_16x16x32_bf16 v[24:27], v[16:19], v[226:229], v[166:169]
	v_mfma_f32_16x16x32_bf16 v[40:43], v[20:23], v[230:233], v[24:27]
	v_mfma_f32_16x16x32_bf16 v[24:27], v[8:11], v[234:237], v[170:173]
	v_mfma_f32_16x16x32_bf16 v[0:3], v[8:11], v[242:245], v[0:3]
	v_mfma_f32_16x16x32_bf16 v[28:31], v[12:15], v[238:241], v[24:27]
	v_mfma_f32_16x16x32_bf16 v[24:27], v[16:19], v[234:237], v[174:177]
	v_mfma_f32_16x16x32_bf16 v[12:15], v[12:15], v[246:249], v[0:3]
	v_mfma_f32_16x16x32_bf16 v[0:3], v[16:19], v[242:245], v[4:7]
	v_mfma_f32_16x16x32_bf16 v[24:27], v[20:23], v[238:241], v[24:27]
	v_mfma_f32_16x16x32_bf16 v[8:11], v[20:23], v[246:249], v[0:3]
	v_mfma_f32_16x16x32_bf16 v[0:3], v[210:213], v[32:35], v[178:181]
	v_mfma_f32_16x16x32_bf16 v[52:55], v[214:217], v[36:39], v[0:3]
	v_mfma_f32_16x16x32_bf16 v[0:3], v[218:221], v[32:35], v[182:185]
	v_mfma_f32_16x16x32_bf16 v[48:51], v[222:225], v[36:39], v[0:3]
	v_mfma_f32_16x16x32_bf16 v[0:3], v[210:213], v[226:229], v[186:189]
	v_mfma_f32_16x16x32_bf16 v[36:39], v[214:217], v[230:233], v[0:3]
	v_mfma_f32_16x16x32_bf16 v[0:3], v[218:221], v[226:229], v[190:193]
	v_mfma_f32_16x16x32_bf16 v[32:35], v[222:225], v[230:233], v[0:3]
	v_mfma_f32_16x16x32_bf16 v[0:3], v[210:213], v[234:237], v[194:197]
	v_mfma_f32_16x16x32_bf16 v[20:23], v[214:217], v[238:241], v[0:3]
	v_mfma_f32_16x16x32_bf16 v[0:3], v[218:221], v[234:237], v[198:201]
	v_mfma_f32_16x16x32_bf16 v[16:19], v[222:225], v[238:241], v[0:3]
	v_mfma_f32_16x16x32_bf16 v[0:3], v[210:213], v[242:245], v[202:205]
	v_mfma_f32_16x16x32_bf16 v[4:7], v[214:217], v[246:249], v[0:3]
	v_mfma_f32_16x16x32_bf16 v[0:3], v[218:221], v[242:245], v[206:209]
	v_mfma_f32_16x16x32_bf16 v[0:3], v[222:225], v[246:249], v[0:3]
	s_barrier
	s_add_u32 s90, s78, 0x200
	s_addc_u32 s85, s79, 0
	s_add_u32 s78, s80, 0x80180
	s_addc_u32 s79, s81, 0
	s_mov_b32 s91, 0
; #define PG8_MMA(ai, bj, At, Bt) do { __builtin_amdgcn_s_setprio(1); _Pragma("unroll") for (int m = 0; m < 4; ++m) _Pragma("unroll") for (int n = 0; n < 2; ++n) _Pragma("unroll") for (int k = 0; k < 2; ++k) \
;         acc[ai][bj][m][n] = __builtin_amdgcn_mfma_f32_16x16x32_bf16(Bt[n][k], At[m][k], acc[ai][bj][m][n], 0, 0, 0); __builtin_amdgcn_s_setprio(0); } while (0)
; template <class Epi, class Sched, bool ALIGN_EPI = false, bool SP2 = false, bool A_TILED = false>
; __device__ __forceinline__ void gemm_phase(PG8_LAS unsigned char* lds, const Gemm g, const Sched& S, const Epi& E, const int wave_s) {
;     ...
;         for (int t = PEEL ? 2 : 0; t < nt; t += 2) {
;             const bool last = (t == nt - 2);
;             const char* a1 = cA + (size_t)(t + 1) * kstepA;
;             const char* a2 = last ? nA : cA + (size_t)(t + 2) * kstepA; const char* b2 = last ? nB : cB + (size_t)(t + 2) * kstep;
;             const char* a3 = a2 + kstepA; const char* b3 = b2 + kstep;
;             if (last && has_next) S.a_ready(nxt);
;             if constexpr (SP2) {
;             PG8_ITER(PG8_MMA)
.LBB0_1619:
	ds_read_b128 v[154:157], v149
	ds_read_b128 v[158:161], v149 offset:1024
	ds_read_b128 v[162:165], v149 offset:2048
	ds_read_b128 v[166:169], v149 offset:3072
	ds_read_b128 v[170:173], v150
	ds_read_b128 v[174:177], v150 offset:1024
	ds_read_b128 v[178:181], v150 offset:2048
	ds_read_b128 v[182:185], v150 offset:3072
	s_add_u32 s80, s78, 0xfff80080
	s_addc_u32 s81, s79, -1
	s_cmp_eq_u32 s91, 28
	s_cselect_b32 s83, s51, s81
	s_cselect_b32 s82, s52, s80
	s_cselect_b32 s81, s53, s85
	s_cselect_b32 s80, s54, s90
	s_mov_b32 m0, s55
	v_lshl_add_u64 v[140:141], s[78:79], 0, v[138:139]
	ds_read_b128 v[186:189], v151
	ds_read_b128 v[190:193], v151 offset:1024
	ds_read_b128 v[194:197], v151 offset:2048
	ds_read_b128 v[198:201], v151 offset:3072
	ds_read_b128 v[202:205], v151 offset:4096
	ds_read_b128 v[206:209], v151 offset:5120
	ds_read_b128 v[210:213], v151 offset:6144
	ds_read_b128 v[214:217], v151 offset:7168
	global_load_lds_dwordx4 v138, s[78:79]
	v_lshl_add_u64 v[140:141], s[78:79], 0, v[136:137]
	s_mov_b32 m0, s56
	s_nop 0
	global_load_lds_dwordx4 v136, s[78:79]
	s_waitcnt vmcnt(8) lgkmcnt(0)
	s_barrier
	v_mfma_f32_16x16x32_bf16 v[124:127], v[154:157], v[186:189], v[124:127]
	v_mfma_f32_16x16x32_bf16 v[120:123], v[162:165], v[186:189], v[120:123]
	v_mfma_f32_16x16x32_bf16 v[108:111], v[154:157], v[194:197], v[108:111]
	v_mfma_f32_16x16x32_bf16 v[104:107], v[162:165], v[194:197], v[104:107]
	v_mfma_f32_16x16x32_bf16 v[92:95], v[154:157], v[202:205], v[92:95]
	v_mfma_f32_16x16x32_bf16 v[88:91], v[162:165], v[202:205], v[88:91]
	v_mfma_f32_16x16x32_bf16 v[76:79], v[154:157], v[210:213], v[76:79]
	v_mfma_f32_16x16x32_bf16 v[72:75], v[162:165], v[210:213], v[72:75]
	v_mfma_f32_16x16x32_bf16 v[124:127], v[158:161], v[190:193], v[124:127]
	v_mfma_f32_16x16x32_bf16 v[120:123], v[166:169], v[190:193], v[120:123]
	v_mfma_f32_16x16x32_bf16 v[108:111], v[158:161], v[198:201], v[108:111]
	v_mfma_f32_16x16x32_bf16 v[104:107], v[166:169], v[198:201], v[104:107]
	v_mfma_f32_16x16x32_bf16 v[92:95], v[158:161], v[206:209], v[92:95]
	v_mfma_f32_16x16x32_bf16 v[88:91], v[166:169], v[206:209], v[88:91]
	v_mfma_f32_16x16x32_bf16 v[76:79], v[158:161], v[214:217], v[76:79]
	v_mfma_f32_16x16x32_bf16 v[72:75], v[166:169], v[214:217], v[72:75]
	v_mfma_f32_16x16x32_bf16 v[116:119], v[170:173], v[186:189], v[116:119]
	v_mfma_f32_16x16x32_bf16 v[112:115], v[178:181], v[186:189], v[112:115]
	v_mfma_f32_16x16x32_bf16 v[100:103], v[170:173], v[194:197], v[100:103]
	v_mfma_f32_16x16x32_bf16 v[96:99], v[178:181], v[194:197], v[96:99]
	v_mfma_f32_16x16x32_bf16 v[84:87], v[170:173], v[202:205], v[84:87]
	v_mfma_f32_16x16x32_bf16 v[80:83], v[178:181], v[202:205], v[80:83]
	v_mfma_f32_16x16x32_bf16 v[68:71], v[170:173], v[210:213], v[68:71]
	v_mfma_f32_16x16x32_bf16 v[64:67], v[178:181], v[210:213], v[64:67]
	v_mfma_f32_16x16x32_bf16 v[116:119], v[174:177], v[190:193], v[116:119]
	v_mfma_f32_16x16x32_bf16 v[112:115], v[182:185], v[190:193], v[112:115]
	v_mfma_f32_16x16x32_bf16 v[100:103], v[174:177], v[198:201], v[100:103]
	v_mfma_f32_16x16x32_bf16 v[96:99], v[182:185], v[198:201], v[96:99]
	v_mfma_f32_16x16x32_bf16 v[84:87], v[174:177], v[206:209], v[84:87]
	v_mfma_f32_16x16x32_bf16 v[80:83], v[182:185], v[206:209], v[80:83]
	v_mfma_f32_16x16x32_bf16 v[68:71], v[174:177], v[214:217], v[68:71]
	v_mfma_f32_16x16x32_bf16 v[64:67], v[182:185], v[214:217], v[64:67]
	s_barrier
	s_mov_b32 m0, s57
	v_lshl_add_u64 v[140:141], s[80:81], 0, v[128:129]
	s_add_u32 s94, s80, 0x80000
	ds_read_b128 v[186:189], v151 offset:16384
	ds_read_b128 v[190:193], v151 offset:17408
	ds_read_b128 v[194:197], v151 offset:18432
	ds_read_b128 v[198:201], v151 offset:19456
	ds_read_b128 v[202:205], v151 offset:20480
	ds_read_b128 v[206:209], v151 offset:21504
	ds_read_b128 v[210:213], v151 offset:22528
	ds_read_b128 v[214:217], v151 offset:23552
	global_load_lds_dwordx4 v128, s[80:81]
	v_lshl_add_u64 v[142:143], s[80:81], 0, v[130:131]
	s_mov_b32 m0, s58
	s_addc_u32 s95, s81, 0
	global_load_lds_dwordx4 v130, s[80:81]
	v_lshl_add_u64 v[146:147], s[94:95], 0, v[128:129]
	s_mov_b32 m0, s59
	v_lshl_add_u64 v[218:219], s[82:83], 0, v[132:133]
	global_load_lds_dwordx4 v128, s[94:95]
	v_lshl_add_u64 v[146:147], s[94:95], 0, v[130:131]
	s_mov_b32 m0, s69
	s_nop 0
	global_load_lds_dwordx4 v130, s[94:95]
	v_lshl_add_u64 v[146:147], s[82:83], 0, v[134:135]
	s_mov_b32 m0, s23
	s_nop 0
	global_load_lds_dwordx4 v134, s[82:83]
	s_mov_b32 m0, s36
	s_nop 0
	global_load_lds_dwordx4 v132, s[82:83]
	s_waitcnt vmcnt(8) lgkmcnt(0)
	s_barrier
	v_mfma_f32_16x16x32_bf16 v[60:63], v[154:157], v[186:189], v[60:63]
	v_mfma_f32_16x16x32_bf16 v[56:59], v[162:165], v[186:189], v[56:59]
	v_mfma_f32_16x16x32_bf16 v[44:47], v[154:157], v[194:197], v[44:47]
	v_mfma_f32_16x16x32_bf16 v[40:43], v[162:165], v[194:197], v[40:43]
	v_mfma_f32_16x16x32_bf16 v[28:31], v[154:157], v[202:205], v[28:31]
	v_mfma_f32_16x16x32_bf16 v[24:27], v[162:165], v[202:205], v[24:27]
	v_mfma_f32_16x16x32_bf16 v[12:15], v[154:157], v[210:213], v[12:15]
	v_mfma_f32_16x16x32_bf16 v[8:11], v[162:165], v[210:213], v[8:11]
	v_mfma_f32_16x16x32_bf16 v[60:63], v[158:161], v[190:193], v[60:63]
	v_mfma_f32_16x16x32_bf16 v[56:59], v[166:169], v[190:193], v[56:59]
	v_mfma_f32_16x16x32_bf16 v[44:47], v[158:161], v[198:201], v[44:47]
	v_mfma_f32_16x16x32_bf16 v[40:43], v[166:169], v[198:201], v[40:43]
	v_mfma_f32_16x16x32_bf16 v[28:31], v[158:161], v[206:209], v[28:31]
	v_mfma_f32_16x16x32_bf16 v[24:27], v[166:169], v[206:209], v[24:27]
	v_mfma_f32_16x16x32_bf16 v[12:15], v[158:161], v[214:217], v[12:15]
	v_mfma_f32_16x16x32_bf16 v[8:11], v[166:169], v[214:217], v[8:11]
	v_mfma_f32_16x16x32_bf16 v[52:55], v[170:173], v[186:189], v[52:55]
	v_mfma_f32_16x16x32_bf16 v[48:51], v[178:181], v[186:189], v[48:51]
	v_mfma_f32_16x16x32_bf16 v[36:39], v[170:173], v[194:197], v[36:39]
	v_mfma_f32_16x16x32_bf16 v[32:35], v[178:181], v[194:197], v[32:35]
	v_mfma_f32_16x16x32_bf16 v[20:23], v[170:173], v[202:205], v[20:23]
	v_mfma_f32_16x16x32_bf16 v[16:19], v[178:181], v[202:205], v[16:19]
	v_mfma_f32_16x16x32_bf16 v[4:7], v[170:173], v[210:213], v[4:7]
	v_mfma_f32_16x16x32_bf16 v[0:3], v[178:181], v[210:213], v[0:3]
	v_mfma_f32_16x16x32_bf16 v[52:55], v[174:177], v[190:193], v[52:55]
	v_mfma_f32_16x16x32_bf16 v[48:51], v[182:185], v[190:193], v[48:51]
	v_mfma_f32_16x16x32_bf16 v[36:39], v[174:177], v[198:201], v[36:39]
	v_mfma_f32_16x16x32_bf16 v[32:35], v[182:185], v[198:201], v[32:35]
	v_mfma_f32_16x16x32_bf16 v[20:23], v[174:177], v[206:209], v[20:23]
	v_mfma_f32_16x16x32_bf16 v[16:19], v[182:185], v[206:209], v[16:19]
	v_mfma_f32_16x16x32_bf16 v[4:7], v[174:177], v[214:217], v[4:7]
	v_mfma_f32_16x16x32_bf16 v[0:3], v[182:185], v[214:217], v[0:3]
	s_barrier
	ds_read_b128 v[154:157], v144
	ds_read_b128 v[158:161], v144 offset:1024
	ds_read_b128 v[162:165], v144 offset:2048
	ds_read_b128 v[166:169], v144 offset:3072
	ds_read_b128 v[170:173], v145
	ds_read_b128 v[174:177], v145 offset:1024
	ds_read_b128 v[178:181], v145 offset:2048
	ds_read_b128 v[182:185], v145 offset:3072
	s_add_u32 s82, s82, 0x80000
	s_addc_u32 s83, s83, 0
	s_mov_b32 m0, s37
	v_lshl_add_u64 v[220:221], s[82:83], 0, v[134:135]
	ds_read_b128 v[186:189], v151 offset:32768
	ds_read_b128 v[190:193], v151 offset:33792
	ds_read_b128 v[194:197], v151 offset:34816
	ds_read_b128 v[198:201], v151 offset:35840
	ds_read_b128 v[202:205], v151 offset:36864
	ds_read_b128 v[206:209], v151 offset:37888
	ds_read_b128 v[210:213], v151 offset:38912
	ds_read_b128 v[214:217], v151 offset:39936
	global_load_lds_dwordx4 v134, s[82:83]
	v_lshl_add_u64 v[220:221], s[82:83], 0, v[132:133]
	s_mov_b32 m0, s38
	s_nop 0
	global_load_lds_dwordx4 v132, s[82:83]
	s_waitcnt vmcnt(8) lgkmcnt(0)
	s_barrier
	v_mfma_f32_16x16x32_bf16 v[124:127], v[154:157], v[186:189], v[124:127]
	v_mfma_f32_16x16x32_bf16 v[120:123], v[162:165], v[186:189], v[120:123]
	v_mfma_f32_16x16x32_bf16 v[108:111], v[154:157], v[194:197], v[108:111]
	v_mfma_f32_16x16x32_bf16 v[104:107], v[162:165], v[194:197], v[104:107]
	v_mfma_f32_16x16x32_bf16 v[92:95], v[154:157], v[202:205], v[92:95]
	v_mfma_f32_16x16x32_bf16 v[88:91], v[162:165], v[202:205], v[88:91]
	v_mfma_f32_16x16x32_bf16 v[76:79], v[154:157], v[210:213], v[76:79]
	v_mfma_f32_16x16x32_bf16 v[72:75], v[162:165], v[210:213], v[72:75]
	v_mfma_f32_16x16x32_bf16 v[124:127], v[158:161], v[190:193], v[124:127]
	v_mfma_f32_16x16x32_bf16 v[120:123], v[166:169], v[190:193], v[120:123]
	v_mfma_f32_16x16x32_bf16 v[108:111], v[158:161], v[198:201], v[108:111]
	v_mfma_f32_16x16x32_bf16 v[104:107], v[166:169], v[198:201], v[104:107]
	v_mfma_f32_16x16x32_bf16 v[92:95], v[158:161], v[206:209], v[92:95]
	v_mfma_f32_16x16x32_bf16 v[88:91], v[166:169], v[206:209], v[88:91]
	v_mfma_f32_16x16x32_bf16 v[76:79], v[158:161], v[214:217], v[76:79]
	v_mfma_f32_16x16x32_bf16 v[72:75], v[166:169], v[214:217], v[72:75]
	v_mfma_f32_16x16x32_bf16 v[116:119], v[170:173], v[186:189], v[116:119]
	v_mfma_f32_16x16x32_bf16 v[112:115], v[178:181], v[186:189], v[112:115]
	v_mfma_f32_16x16x32_bf16 v[100:103], v[170:173], v[194:197], v[100:103]
	v_mfma_f32_16x16x32_bf16 v[96:99], v[178:181], v[194:197], v[96:99]
	v_mfma_f32_16x16x32_bf16 v[84:87], v[170:173], v[202:205], v[84:87]
	v_mfma_f32_16x16x32_bf16 v[80:83], v[178:181], v[202:205], v[80:83]
	v_mfma_f32_16x16x32_bf16 v[68:71], v[170:173], v[210:213], v[68:71]
	v_mfma_f32_16x16x32_bf16 v[64:67], v[178:181], v[210:213], v[64:67]
	v_mfma_f32_16x16x32_bf16 v[116:119], v[174:177], v[190:193], v[116:119]
	v_mfma_f32_16x16x32_bf16 v[112:115], v[182:185], v[190:193], v[112:115]
	v_mfma_f32_16x16x32_bf16 v[100:103], v[174:177], v[198:201], v[100:103]
	v_mfma_f32_16x16x32_bf16 v[96:99], v[182:185], v[198:201], v[96:99]
	v_mfma_f32_16x16x32_bf16 v[84:87], v[174:177], v[206:209], v[84:87]
	v_mfma_f32_16x16x32_bf16 v[80:83], v[182:185], v[206:209], v[80:83]
	v_mfma_f32_16x16x32_bf16 v[68:71], v[174:177], v[214:217], v[68:71]
	v_mfma_f32_16x16x32_bf16 v[64:67], v[182:185], v[214:217], v[64:67]
	s_barrier
; #define PG8_MMA(ai, bj, At, Bt) do { __builtin_amdgcn_s_setprio(1); _Pragma("unroll") for (int m = 0; m < 4; ++m) _Pragma("unroll") for (int n = 0; n < 2; ++n) _Pragma("unroll") for (int k = 0; k < 2; ++k) \
;         acc[ai][bj][m][n] = __builtin_amdgcn_mfma_f32_16x16x32_bf16(Bt[n][k], At[m][k], acc[ai][bj][m][n], 0, 0, 0); __builtin_amdgcn_s_setprio(0); } while (0)
; template <class Epi, class Sched, bool ALIGN_EPI = false, bool SP2 = false, bool A_TILED = false>
; __device__ __forceinline__ void gemm_phase(PG8_LAS unsigned char* lds, const Gemm g, const Sched& S, const Epi& E, const int wave_s) {
;     ...
;         for (int t = PEEL ? 2 : 0; t < nt; t += 2) {
;             const bool last = (t == nt - 2);
;             const char* a1 = cA + (size_t)(t + 1) * kstepA;
;             const char* a2 = last ? nA : cA + (size_t)(t + 2) * kstepA; const char* b2 = last ? nB : cB + (size_t)(t + 2) * kstep;
;             const char* a3 = a2 + kstepA; const char* b3 = b2 + kstep;
;             if (last && has_next) S.a_ready(nxt);
;             if constexpr (SP2) {
;             PG8_ITER(PG8_MMA)
	s_mov_b32 m0, s71
	v_lshl_add_u64 v[140:141], v[140:141], 0, s[60:61]
	s_add_u32 s80, s80, 0x80080
	ds_read_b128 v[186:189], v151 offset:49152
	ds_read_b128 v[190:193], v151 offset:50176
	ds_read_b128 v[194:197], v151 offset:51200
	ds_read_b128 v[198:201], v151 offset:52224
	ds_read_b128 v[202:205], v151 offset:53248
	ds_read_b128 v[206:209], v151 offset:54272
	ds_read_b128 v[210:213], v151 offset:55296
	ds_read_b128 v[214:217], v151 offset:56320
	global_load_lds_dwordx4 v[140:141], off
	v_lshl_add_u64 v[140:141], v[142:143], 0, s[60:61]
	s_mov_b32 m0, s77
	s_addc_u32 s81, s81, 0
	global_load_lds_dwordx4 v[140:141], off
	v_lshl_add_u64 v[140:141], s[80:81], 0, v[128:129]
	s_mov_b32 m0, s88
	s_nop 0
	global_load_lds_dwordx4 v128, s[80:81]
	v_lshl_add_u64 v[140:141], s[80:81], 0, v[130:131]
	s_mov_b32 m0, s89
	s_nop 0
	global_load_lds_dwordx4 v130, s[80:81]
	v_lshl_add_u64 v[140:141], v[146:147], 0, s[60:61]
	s_mov_b32 m0, s43
	s_nop 0
	global_load_lds_dwordx4 v[140:141], off
	v_lshl_add_u64 v[140:141], v[218:219], 0, s[60:61]
	s_mov_b32 m0, s44
	s_nop 0
	global_load_lds_dwordx4 v[140:141], off
	s_waitcnt vmcnt(8) lgkmcnt(0)
	s_barrier
	v_mfma_f32_16x16x32_bf16 v[60:63], v[154:157], v[186:189], v[60:63]
	v_mfma_f32_16x16x32_bf16 v[56:59], v[162:165], v[186:189], v[56:59]
	v_mfma_f32_16x16x32_bf16 v[44:47], v[154:157], v[194:197], v[44:47]
	v_mfma_f32_16x16x32_bf16 v[40:43], v[162:165], v[194:197], v[40:43]
	v_mfma_f32_16x16x32_bf16 v[28:31], v[154:157], v[202:205], v[28:31]
	v_mfma_f32_16x16x32_bf16 v[24:27], v[162:165], v[202:205], v[24:27]
	v_mfma_f32_16x16x32_bf16 v[12:15], v[154:157], v[210:213], v[12:15]
	v_mfma_f32_16x16x32_bf16 v[8:11], v[162:165], v[210:213], v[8:11]
	v_mfma_f32_16x16x32_bf16 v[60:63], v[158:161], v[190:193], v[60:63]
	v_mfma_f32_16x16x32_bf16 v[56:59], v[166:169], v[190:193], v[56:59]
	v_mfma_f32_16x16x32_bf16 v[44:47], v[158:161], v[198:201], v[44:47]
	v_mfma_f32_16x16x32_bf16 v[40:43], v[166:169], v[198:201], v[40:43]
	v_mfma_f32_16x16x32_bf16 v[28:31], v[158:161], v[206:209], v[28:31]
	v_mfma_f32_16x16x32_bf16 v[24:27], v[166:169], v[206:209], v[24:27]
	v_mfma_f32_16x16x32_bf16 v[12:15], v[158:161], v[214:217], v[12:15]
	v_mfma_f32_16x16x32_bf16 v[8:11], v[166:169], v[214:217], v[8:11]
	v_mfma_f32_16x16x32_bf16 v[52:55], v[170:173], v[186:189], v[52:55]
	v_mfma_f32_16x16x32_bf16 v[48:51], v[178:181], v[186:189], v[48:51]
	v_mfma_f32_16x16x32_bf16 v[36:39], v[170:173], v[194:197], v[36:39]
	v_mfma_f32_16x16x32_bf16 v[32:35], v[178:181], v[194:197], v[32:35]
	v_mfma_f32_16x16x32_bf16 v[20:23], v[170:173], v[202:205], v[20:23]
	v_mfma_f32_16x16x32_bf16 v[16:19], v[178:181], v[202:205], v[16:19]
	v_mfma_f32_16x16x32_bf16 v[4:7], v[170:173], v[210:213], v[4:7]
	v_mfma_f32_16x16x32_bf16 v[0:3], v[178:181], v[210:213], v[0:3]
	v_mfma_f32_16x16x32_bf16 v[52:55], v[174:177], v[190:193], v[52:55]
	v_mfma_f32_16x16x32_bf16 v[48:51], v[182:185], v[190:193], v[48:51]
	v_mfma_f32_16x16x32_bf16 v[36:39], v[174:177], v[198:201], v[36:39]
	v_mfma_f32_16x16x32_bf16 v[32:35], v[182:185], v[198:201], v[32:35]
	v_mfma_f32_16x16x32_bf16 v[20:23], v[174:177], v[206:209], v[20:23]
	v_mfma_f32_16x16x32_bf16 v[16:19], v[182:185], v[206:209], v[16:19]
	v_mfma_f32_16x16x32_bf16 v[4:7], v[174:177], v[214:217], v[4:7]
	v_mfma_f32_16x16x32_bf16 v[0:3], v[182:185], v[214:217], v[0:3]
	s_barrier
	s_add_i32 s91, s91, 2
	s_add_u32 s90, s90, 0x100
	s_addc_u32 s85, s85, 0
	s_add_u32 s78, s78, 0x100
	s_addc_u32 s79, s79, 0
	s_cmp_gt_u32 s91, 29
	s_cbranch_scc0 .LBB0_1619
	s_and_b64 vcc, exec, s[62:63]
	s_cbranch_vccz .LBB0_1622
	s_barrier

; __device__ __forceinline__ int tid_now(int wave_s) { unsigned z = 0u; asm volatile("" : "+v"(z)); return (wave_s << 6) | (int)__builtin_amdgcn_mbcnt_hi(~0u, __builtin_amdgcn_mbcnt_lo(~0u, z)); }
; __device__ __forceinline__ unsigned xb_ld(unsigned* p)              { return __hip_atomic_load(p, __ATOMIC_RELAXED, __HIP_MEMORY_SCOPE_AGENT); }
; __device__ __forceinline__ unsigned xb_add(unsigned* p, unsigned v) { return __hip_atomic_fetch_add(p, v, __ATOMIC_RELAXED, __HIP_MEMORY_SCOPE_AGENT); }
; #define XB_SPIN(cond, bar) do { unsigned _sp = 0; while (cond) { __builtin_amdgcn_s_sleep(1); \
;     if ((++_sp & 255u) == 0u) { if (xb_ld(&(bar)[XB_TMO])) break; if (_sp > XB_SPIN_CAP) { atomicAdd(&(bar)[XB_TMO], 1u); break; } } } } while (0)
; __device__ __forceinline__ void xcd_barrier(const XcdBarrier& b) {
;     asm volatile("s_waitcnt vmcnt(0)" ::: "memory");
;     __syncthreads();
;     if (tid_now(b.w) == 0) {
;         unsigned* bar = b.bar;
;         __builtin_amdgcn_s_waitcnt(0);
;         unsigned nloc = b.st[0], nx = b.st[1];
;         if (nloc == 0u) { xcd_barrier_complete(bar, b.x, nloc, nx, b.np); b.st[0] = nloc; b.st[1] = nx; }
;         const unsigned old = xb_add(&bar[XB_XSUB(b.x)], 1u);
;         const unsigned gen = old / nloc;
;         if (old + 1u == (gen + 1u) * nloc) {
;             __builtin_amdgcn_fence(__ATOMIC_RELEASE, "agent");
;             asm volatile("s_waitcnt vmcnt(0)" ::: "memory");
;             const unsigned og = xb_add(&bar[XB_TOP], 1u);
;             const unsigned tg = og / nx;
;             if (og + 1u == (tg + 1u) * nx) xb_add(&bar[XB_TOPGEN], 1u);
;             else XB_SPIN(xb_ld(&bar[XB_TOPGEN]) == tg, bar);
;             __builtin_amdgcn_fence(__ATOMIC_ACQUIRE, "agent");
;             xb_add(&bar[XB_XGEN(b.x)], 1u);
;             asm volatile("s_waitcnt vmcnt(0)" ::: "memory");
;         } else {
;             XB_SPIN(xb_ld(&bar[XB_XGEN(b.x)]) == gen, bar);
;             __builtin_amdgcn_fence(__ATOMIC_ACQUIRE, "agent");
;             asm volatile("s_waitcnt vmcnt(0)" ::: "memory");
;         }
;     }
;     __syncthreads();
; }
.LBB0_1626:
	s_setprio 0
	s_cmp_gt_i32 s35, 8
	s_cselect_b64 s[2:3], -1, 0
	s_and_b64 s[0:1], s[4:5], s[2:3]
	s_andn2_b64 vcc, exec, s[0:1]
	s_cbranch_vccnz .LBB0_1680
	v_mov_b32_e32 v0, 0
	s_waitcnt vmcnt(0)
	s_waitcnt vmcnt(0) lgkmcnt(0)
	s_barrier
	s_nop 0
	v_mbcnt_lo_u32_b32 v0, -1, v0
	v_mbcnt_hi_u32_b32 v0, -1, v0
	v_or_b32_e32 v0, s33, v0
	v_cmp_eq_u32_e32 vcc, 0, v0
	s_and_saveexec_b64 s[4:5], vcc
	s_cbranch_execz .LBB0_1679
	s_add_i32 s0, 0, 0x27f68
	v_mov_b32_e32 v0, s0
	s_waitcnt vmcnt(0) expcnt(0) lgkmcnt(0)
	ds_read_b32 v2, v0
	s_add_i32 s0, 0, 0x27f6c
	v_mov_b32_e32 v0, s0
	ds_read_b32 v0, v0
	s_waitcnt lgkmcnt(1)
	v_cmp_ne_u32_e32 vcc, 0, v2
	s_cbranch_vccnz .LBB0_1643
	s_add_u32 s6, s10, 0x1000
	s_addc_u32 s7, s11, 0
	s_add_u32 s12, s10, 0x1100
	s_addc_u32 s13, s11, 0
	s_add_u32 s60, s10, 0x1200
	s_addc_u32 s61, s11, 0
	s_add_u32 s62, s10, 0x1300
	s_addc_u32 s63, s11, 0
	s_mov_b32 s0, 1
	v_mov_b32_e32 v16, 0
	s_branch .LBB0_1631

; __device__ __forceinline__ int tid_now(int wave_s) { unsigned z = 0u; asm volatile("" : "+v"(z)); return (wave_s << 6) | (int)__builtin_amdgcn_mbcnt_hi(~0u, __builtin_amdgcn_mbcnt_lo(~0u, z)); }
; __device__ __forceinline__ unsigned xb_ld(unsigned* p)              { return __hip_atomic_load(p, __ATOMIC_RELAXED, __HIP_MEMORY_SCOPE_AGENT); }
; __device__ __forceinline__ unsigned xb_add(unsigned* p, unsigned v) { return __hip_atomic_fetch_add(p, v, __ATOMIC_RELAXED, __HIP_MEMORY_SCOPE_AGENT); }
; #define XB_SPIN(cond, bar) do { unsigned _sp = 0; while (cond) { __builtin_amdgcn_s_sleep(1); \
;     if ((++_sp & 255u) == 0u) { if (xb_ld(&(bar)[XB_TMO])) break; if (_sp > XB_SPIN_CAP) { atomicAdd(&(bar)[XB_TMO], 1u); break; } } } } while (0)
; __device__ __forceinline__ void xcd_barrier(const XcdBarrier& b) {
;     asm volatile("s_waitcnt vmcnt(0)" ::: "memory");
;     __syncthreads();
;     if (tid_now(b.w) == 0) {
;         unsigned* bar = b.bar;
;         __builtin_amdgcn_s_waitcnt(0);
;         unsigned nloc = b.st[0], nx = b.st[1];
;         if (nloc == 0u) { xcd_barrier_complete(bar, b.x, nloc, nx, b.np); b.st[0] = nloc; b.st[1] = nx; }
;         const unsigned old = xb_add(&bar[XB_XSUB(b.x)], 1u);
;         const unsigned gen = old / nloc;
;         if (old + 1u == (gen + 1u) * nloc) {
;             __builtin_amdgcn_fence(__ATOMIC_RELEASE, "agent");
;             asm volatile("s_waitcnt vmcnt(0)" ::: "memory");
;             const unsigned og = xb_add(&bar[XB_TOP], 1u);
;             const unsigned tg = og / nx;
;             if (og + 1u == (tg + 1u) * nx) xb_add(&bar[XB_TOPGEN], 1u);
;             else XB_SPIN(xb_ld(&bar[XB_TOPGEN]) == tg, bar);
;             __builtin_amdgcn_fence(__ATOMIC_ACQUIRE, "agent");
;             xb_add(&bar[XB_XGEN(b.x)], 1u);
;             asm volatile("s_waitcnt vmcnt(0)" ::: "memory");
;         } else {
;             XB_SPIN(xb_ld(&bar[XB_XGEN(b.x)]) == gen, bar);
;             __builtin_amdgcn_fence(__ATOMIC_ACQUIRE, "agent");
;             asm volatile("s_waitcnt vmcnt(0)" ::: "memory");
;         }
;     }
;     __syncthreads();
; }
.LBB0_1717:
	s_setprio 0
	s_cmp_gt_i32 s35, 9
	s_cselect_b64 s[2:3], -1, 0
	s_and_b64 s[0:1], s[6:7], s[2:3]
	s_andn2_b64 vcc, exec, s[0:1]
	s_cbranch_vccnz .LBB0_1771
	s_waitcnt vmcnt(0)
	v_mov_b32_e32 v0, 0
	s_waitcnt vmcnt(0)
	s_waitcnt lgkmcnt(0)
	s_barrier
	s_nop 0
	v_mbcnt_lo_u32_b32 v0, -1, v0
	v_mbcnt_hi_u32_b32 v0, -1, v0
	v_or_b32_e32 v0, s33, v0
	v_cmp_eq_u32_e32 vcc, 0, v0
	s_and_saveexec_b64 s[4:5], vcc
	s_cbranch_execz .LBB0_1770
	s_add_i32 s0, 0, 0x27f68
	v_mov_b32_e32 v0, s0
	s_waitcnt vmcnt(0) expcnt(0) lgkmcnt(0)
	ds_read_b32 v2, v0
	s_add_i32 s0, 0, 0x27f6c
	v_mov_b32_e32 v0, s0
	ds_read_b32 v0, v0
	s_waitcnt lgkmcnt(1)
	v_cmp_ne_u32_e32 vcc, 0, v2
	s_cbranch_vccnz .LBB0_1734
	s_add_u32 s6, s10, 0x1000
	s_addc_u32 s7, s11, 0
	s_add_u32 s12, s10, 0x1100
	s_addc_u32 s13, s11, 0
	s_add_u32 s60, s10, 0x1200
	s_addc_u32 s61, s11, 0
	s_add_u32 s62, s10, 0x1300
	s_addc_u32 s63, s11, 0
	s_mov_b32 s0, 1
	v_mov_b32_e32 v16, 0
	s_branch .LBB0_1722

; __device__ __forceinline__ int tid_now(int wave_s) { unsigned z = 0u; asm volatile("" : "+v"(z)); return (wave_s << 6) | (int)__builtin_amdgcn_mbcnt_hi(~0u, __builtin_amdgcn_mbcnt_lo(~0u, z)); }
; __device__ __forceinline__ unsigned xb_ld(unsigned* p)              { return __hip_atomic_load(p, __ATOMIC_RELAXED, __HIP_MEMORY_SCOPE_AGENT); }
; __device__ __forceinline__ unsigned xb_add(unsigned* p, unsigned v) { return __hip_atomic_fetch_add(p, v, __ATOMIC_RELAXED, __HIP_MEMORY_SCOPE_AGENT); }
; #define XB_SPIN(cond, bar) do { unsigned _sp = 0; while (cond) { __builtin_amdgcn_s_sleep(1); \
;     if ((++_sp & 255u) == 0u) { if (xb_ld(&(bar)[XB_TMO])) break; if (_sp > XB_SPIN_CAP) { atomicAdd(&(bar)[XB_TMO], 1u); break; } } } } while (0)
; __device__ __forceinline__ void xcd_barrier(const XcdBarrier& b) {
;     asm volatile("s_waitcnt vmcnt(0)" ::: "memory");
;     __syncthreads();
;     if (tid_now(b.w) == 0) {
;         unsigned* bar = b.bar;
;         __builtin_amdgcn_s_waitcnt(0);
;         unsigned nloc = b.st[0], nx = b.st[1];
;         if (nloc == 0u) { xcd_barrier_complete(bar, b.x, nloc, nx, b.np); b.st[0] = nloc; b.st[1] = nx; }
;         const unsigned old = xb_add(&bar[XB_XSUB(b.x)], 1u);
;         const unsigned gen = old / nloc;
;         if (old + 1u == (gen + 1u) * nloc) {
;             __builtin_amdgcn_fence(__ATOMIC_RELEASE, "agent");
;             asm volatile("s_waitcnt vmcnt(0)" ::: "memory");
;             const unsigned og = xb_add(&bar[XB_TOP], 1u);
;             const unsigned tg = og / nx;
;             if (og + 1u == (tg + 1u) * nx) xb_add(&bar[XB_TOPGEN], 1u);
;             else XB_SPIN(xb_ld(&bar[XB_TOPGEN]) == tg, bar);
;             __builtin_amdgcn_fence(__ATOMIC_ACQUIRE, "agent");
;             xb_add(&bar[XB_XGEN(b.x)], 1u);
;             asm volatile("s_waitcnt vmcnt(0)" ::: "memory");
;         } else {
;             XB_SPIN(xb_ld(&bar[XB_XGEN(b.x)]) == gen, bar);
;             __builtin_amdgcn_fence(__ATOMIC_ACQUIRE, "agent");
;             asm volatile("s_waitcnt vmcnt(0)" ::: "memory");
;         }
;     }
;     __syncthreads();
; }
.LBB0_1775:
	s_setprio 0
	s_cmp_gt_i32 s35, 10
	s_cselect_b64 s[2:3], -1, 0
	s_and_b64 s[0:1], s[4:5], s[2:3]
	s_andn2_b64 vcc, exec, s[0:1]
	s_cbranch_vccnz .LBB0_1829
	s_waitcnt vmcnt(0)
	v_mov_b32_e32 v0, 0
	s_waitcnt vmcnt(0)
	s_waitcnt lgkmcnt(0)
	s_barrier
	s_nop 0
	v_mbcnt_lo_u32_b32 v0, -1, v0
	v_mbcnt_hi_u32_b32 v0, -1, v0
	v_or_b32_e32 v0, s33, v0
	v_cmp_eq_u32_e32 vcc, 0, v0
	s_and_saveexec_b64 s[4:5], vcc
	s_cbranch_execz .LBB0_1828
	s_add_i32 s0, 0, 0x27f68
	v_mov_b32_e32 v0, s0
	s_waitcnt vmcnt(0) expcnt(0) lgkmcnt(0)
	ds_read_b32 v2, v0
	s_add_i32 s0, 0, 0x27f6c
	v_mov_b32_e32 v0, s0
	ds_read_b32 v0, v0
	s_waitcnt lgkmcnt(1)
	v_cmp_ne_u32_e32 vcc, 0, v2
	s_cbranch_vccnz .LBB0_1792
	s_add_u32 s6, s10, 0x1000
	s_addc_u32 s7, s11, 0
	s_add_u32 s12, s10, 0x1100
	s_addc_u32 s13, s11, 0
	s_add_u32 s60, s10, 0x1200
	s_addc_u32 s61, s11, 0
	s_add_u32 s62, s10, 0x1300
	s_addc_u32 s63, s11, 0
	s_mov_b32 s0, 1
	v_mov_b32_e32 v16, 0
	s_branch .LBB0_1780

; #define PG8_STAGE(bufoff, gbase, voff) do { _Pragma("unroll") for (int _i = 0; _i < 2; ++_i) \
;         __builtin_amdgcn_global_load_lds((const unsigned*)((const char*)(gbase) + (voff)[_i]), (PG8_LAS unsigned*)(lds + (bufoff) + ldsw + _i * 8192), 16, 0, 0); } while (0)
; #define PG8_WAIT_V(n) asm volatile("s_waitcnt vmcnt(" #n ")" ::: "memory")
; template <class Epi, class Sched, bool ALIGN_EPI = false, bool SP2 = false, bool A_TILED = false>
; __device__ __forceinline__ void gemm_phase(PG8_LAS unsigned char* lds, const Gemm g, const Sched& S, const Epi& E, const int wave_s) {
;     ...
;     if constexpr (SP2) {
;         PG8_STAGE(PG8_SB(0, 0), cB, voffB); PG8_STAGE(PG8_SB(0, 1), cB + hstep, voffB); PG8_STAGE(PG8_SA(0, 0), cA, voffA); PG8_STAGE(PG8_SA(0, 1), cA + hstepA, voffA);
;         if (wr == 1) PG8_BAR;
;         PG8_WAIT_V(2); PG8_BAR;
;         PG8_STAGE(PG8_SB(1, 0), cB + kstep, voffB); PG8_STAGE(PG8_SA(1, 0), cA + kstepA, voffA); PG8_STAGE(PG8_SB(1, 1), cB + hstep + kstep, voffB);
;         PG8_WAIT_V(6); PG8_BAR;
;     } else {
;         PG8_STAGE(PG8_SB(0, 0), cB, voffB); PG8_STAGE(PG8_SA(0, 0), cA, voffA); PG8_STAGE(PG8_SB(0, 1), cB + hstep, voffB); PG8_STAGE(PG8_SA(0, 1), cA + hstepA, voffA);
;         if (wr == 1) PG8_BAR;
;         PG8_WAIT_V(4); PG8_BAR;
;         PG8_STAGE(PG8_SB(1, 0), cB + kstep, voffB); PG8_STAGE(PG8_SA(1, 0), cA + kstepA, voffA); PG8_STAGE(PG8_SB(1, 1), cB + hstep + kstep, voffB);
;         PG8_WAIT_V(6); PG8_BAR;
;     }
;     for (;;) {
;         const bool has_next = Epi::AFTER_DRAIN ? false : S.next(ui + 1, nxt);
;         const char* nA = has_next ? (const char*)g.A + (size_t)nxt.pm * tstepA : cA; const char* nB = has_next ? (const char*)g.Bt + (size_t)nxt.pn * tstep : cB;
;         constexpr bool PEEL = SP2 && !Epi::AFTER_DRAIN;
;         if constexpr (PEEL) {
;             const char* a1 = cA + kstepA; const char* a2 = cA + 2 * kstepA; const char* b2 = cB + 2 * kstep; const char* a3 = a2 + kstepA; const char* b3 = b2 + kstep;
;             PG8_ITER(PG8_MMAZ)
;         } else {
; #pragma unroll
;             for (int a = 0; a < 2; ++a)
; #pragma unroll
;                 for (int b = 0; b < 2; ++b)
; #pragma unroll
;                     for (int m = 0; m < 4; ++m)
; #pragma unroll
;                         for (int n = 0; n < 2; ++n) acc[a][b][m][n] = (f32x4){0.f, 0.f, 0.f, 0.f};
.LBB0_1840:
	v_and_b32_e32 v15, 48, v8
	v_lshlrev_b32_e32 v16, 6, v8
	s_movk_i32 s36, 0x3c0
	v_lshlrev_b32_e32 v8, 2, v8
	s_and_b32 s9, s1, 3
	s_lshl_b32 s8, s23, 6
	s_lshl_b32 s23, s23, 13
	v_and_or_b32 v15, v16, s36, v15
	v_and_b32_e32 v8, 32, v8
	s_mov_b64 s[64:65], 0x80
	v_bitop3_b32 v16, v15, s23, v8 bitop3:0xde
	s_lshl_b32 s23, s9, 12
	s_add_i32 m0, s14, 0x18000
	v_lshl_add_u64 v[6:7], v[6:7], 0, s[64:65]
	v_bitop3_b32 v8, v15, s23, v8 bitop3:0xde
	s_waitcnt vmcnt(2)
	s_barrier
	global_load_lds_dwordx4 v[6:7], off
	v_lshl_add_u64 v[4:5], v[4:5], 0, s[64:65]
	s_add_i32 m0, s14, 0x1a000
	s_add_i32 s23, s14, 0x8000
	s_add_i32 s36, s14, 0xa000
	global_load_lds_dwordx4 v[4:5], off
	v_lshl_add_u64 v[2:3], v[2:3], 0, s[64:65]
	s_mov_b32 m0, s23
	s_add_u32 s38, s2, 0x80080
	global_load_lds_dwordx4 v[2:3], off
	v_lshl_add_u64 v[0:1], v[0:1], 0, s[64:65]
	s_mov_b32 m0, s36
	s_addc_u32 s39, s3, 0
	global_load_lds_dwordx4 v[0:1], off
	s_add_i32 m0, s14, 0x1c000
	v_lshl_add_u64 v[0:1], s[38:39], 0, v[34:35]
	global_load_lds_dwordx4 v34, s[38:39]
	v_lshl_add_u64 v[0:1], s[38:39], 0, v[134:135]
	s_add_i32 m0, s14, 0x1e000
	s_mov_b64 s[40:41], 0x20680080
	global_load_lds_dwordx4 v134, s[38:39]
	v_lshlrev_b32_e32 v0, 15, v12
	v_and_b32_e32 v0, 0xffff0000, v0
	v_lshl_add_u32 v0, v13, 12, v0
	v_and_b32_e32 v1, 1, v12
	v_lshl_or_b32 v0, v1, 6, v0
	v_lshl_add_u32 v0, v14, 1, v0
	v_mov_b32_e32 v1, v35
	v_lshl_add_u64 v[0:1], s[66:67], 0, v[0:1]
	v_lshl_add_u64 v[136:137], v[0:1], 0, s[40:41]
	v_lshlrev_b32_e32 v0, 15, v9
	v_and_b32_e32 v0, 0xffff0000, v0
	v_lshl_add_u32 v0, v10, 12, v0
	v_and_b32_e32 v1, 1, v9
	s_add_u32 s37, s68, 0x8a00100
	v_lshl_or_b32 v0, v1, 6, v0
	s_addc_u32 s38, s69, 0
	v_lshl_add_u32 v0, v11, 1, v0
	v_mov_b32_e32 v1, v35
	v_lshl_add_u64 v[0:1], s[66:67], 0, v[0:1]
	s_add_u32 s39, s66, 0x20600100
	s_waitcnt vmcnt(6)
	v_lshl_add_u64 v[138:139], v[0:1], 0, s[40:41]
	s_addc_u32 s40, s67, 0
	s_bitcmp1_b32 s33, 8
	s_cbranch_scc1 .Lsp_6
	s_setprio 1
.Lsp_6:
	s_add_i32 s44, 0, 0x10000
	s_add_i32 s46, 0, 0x14000
	s_add_i32 s48, 0, 0x18000
	s_add_i32 s51, 0, 0x1c000
	v_add_u32_e32 v140, s44, v8
	v_add_u32_e32 v141, s46, v8
	s_add_i32 s44, s44, s50
	s_add_i32 s46, s46, s50
	v_add_u32_e32 v143, s48, v8
	s_add_i32 s48, s48, s50
	s_add_i32 s50, s51, s50
	s_mov_b32 s41, -2
	v_add_u32_e32 v142, 0, v16
	s_add_i32 s42, s14, 0xc000
	s_add_i32 s43, s14, 0xe000
	s_add_i32 s45, s44, 0x2000
	s_add_i32 s47, s46, 0x2000
	v_add_u32_e32 v144, s51, v8
	s_add_i32 s49, s48, 0x2000
	s_add_i32 s51, s50, 0x2000
	s_mov_b64 s[66:67], 0x100
	v_mov_b32_e32 v0, v35
	v_mov_b32_e32 v1, v35
	v_mov_b32_e32 v2, v35
	v_mov_b32_e32 v3, v35
	v_mov_b32_e32 v4, v35
	v_mov_b32_e32 v5, v35
	v_mov_b32_e32 v6, v35
	v_mov_b32_e32 v7, v35
	v_mov_b32_e32 v40, v35
	v_mov_b32_e32 v41, v35
	v_mov_b32_e32 v42, v35
	v_mov_b32_e32 v43, v35
	v_mov_b32_e32 v44, v35
	v_mov_b32_e32 v45, v35
	v_mov_b32_e32 v46, v35
	v_mov_b32_e32 v47, v35
	v_mov_b32_e32 v88, v35
	v_mov_b32_e32 v89, v35
	v_mov_b32_e32 v90, v35
	v_mov_b32_e32 v91, v35
	v_mov_b32_e32 v92, v35
	v_mov_b32_e32 v93, v35
	v_mov_b32_e32 v94, v35
	v_mov_b32_e32 v95, v35
	v_mov_b32_e32 v112, v35
	v_mov_b32_e32 v113, v35
	v_mov_b32_e32 v114, v35
	v_mov_b32_e32 v115, v35
	v_mov_b32_e32 v124, v35
	v_mov_b32_e32 v125, v35
	v_mov_b32_e32 v126, v35
	v_mov_b32_e32 v127, v35
	v_mov_b32_e32 v28, v35
	v_mov_b32_e32 v29, v35
	v_mov_b32_e32 v30, v35
	v_mov_b32_e32 v31, v35
	v_mov_b32_e32 v36, v35
	v_mov_b32_e32 v37, v35
	v_mov_b32_e32 v38, v35
	v_mov_b32_e32 v39, v35
	v_mov_b32_e32 v80, v35
	v_mov_b32_e32 v81, v35
	v_mov_b32_e32 v82, v35
	v_mov_b32_e32 v83, v35
	v_mov_b32_e32 v84, v35
	v_mov_b32_e32 v85, v35
	v_mov_b32_e32 v86, v35
	v_mov_b32_e32 v87, v35
	v_mov_b32_e32 v120, v35
	v_mov_b32_e32 v121, v35
	v_mov_b32_e32 v122, v35
	v_mov_b32_e32 v123, v35
	v_mov_b32_e32 v116, v35
	v_mov_b32_e32 v117, v35
	v_mov_b32_e32 v118, v35
	v_mov_b32_e32 v119, v35
	v_mov_b32_e32 v104, v35
	v_mov_b32_e32 v105, v35
	v_mov_b32_e32 v106, v35
	v_mov_b32_e32 v107, v35
	v_mov_b32_e32 v100, v35
	v_mov_b32_e32 v101, v35
	v_mov_b32_e32 v102, v35
	v_mov_b32_e32 v103, v35
	v_mov_b32_e32 v96, v35
	v_mov_b32_e32 v97, v35
	v_mov_b32_e32 v98, v35
	v_mov_b32_e32 v99, v35
	v_mov_b32_e32 v108, v35
	v_mov_b32_e32 v109, v35
	v_mov_b32_e32 v110, v35
	v_mov_b32_e32 v111, v35
	v_mov_b32_e32 v64, v35
	v_mov_b32_e32 v65, v35
	v_mov_b32_e32 v66, v35
	v_mov_b32_e32 v67, v35
	v_mov_b32_e32 v72, v35
	v_mov_b32_e32 v73, v35
	v_mov_b32_e32 v74, v35
	v_mov_b32_e32 v75, v35
	v_mov_b32_e32 v48, v35
	v_mov_b32_e32 v49, v35
	v_mov_b32_e32 v50, v35
	v_mov_b32_e32 v51, v35
	v_mov_b32_e32 v56, v35
	v_mov_b32_e32 v57, v35
	v_mov_b32_e32 v58, v35
	v_mov_b32_e32 v59, v35
	v_mov_b32_e32 v16, v35
	v_mov_b32_e32 v17, v35
	v_mov_b32_e32 v18, v35
	v_mov_b32_e32 v19, v35
	v_mov_b32_e32 v24, v35
	v_mov_b32_e32 v25, v35
	v_mov_b32_e32 v26, v35
	v_mov_b32_e32 v27, v35
	v_mov_b32_e32 v68, v35
	v_mov_b32_e32 v69, v35
	v_mov_b32_e32 v70, v35
	v_mov_b32_e32 v71, v35
	v_mov_b32_e32 v128, v35
	v_mov_b32_e32 v129, v35
	v_mov_b32_e32 v130, v35
	v_mov_b32_e32 v131, v35
	v_mov_b32_e32 v52, v35
	v_mov_b32_e32 v53, v35
	v_mov_b32_e32 v54, v35
	v_mov_b32_e32 v55, v35
	v_mov_b32_e32 v76, v35
	v_mov_b32_e32 v77, v35
	v_mov_b32_e32 v78, v35
	v_mov_b32_e32 v79, v35
	v_mov_b32_e32 v20, v35
	v_mov_b32_e32 v21, v35
	v_mov_b32_e32 v22, v35
	v_mov_b32_e32 v23, v35
	v_mov_b32_e32 v60, v35
	v_mov_b32_e32 v61, v35
	v_mov_b32_e32 v62, v35
	v_mov_b32_e32 v63, v35
	v_mov_b32_e32 v12, v35
	v_mov_b32_e32 v13, v35
	v_mov_b32_e32 v14, v35
	v_mov_b32_e32 v15, v35
	v_mov_b32_e32 v8, v35
	v_mov_b32_e32 v9, v35
	v_mov_b32_e32 v10, v35
	v_mov_b32_e32 v11, v35
	s_barrier
; #define PG8_MMA(ai, bj, At, Bt) do { __builtin_amdgcn_s_setprio(1); _Pragma("unroll") for (int m = 0; m < 4; ++m) _Pragma("unroll") for (int n = 0; n < 2; ++n) _Pragma("unroll") for (int k = 0; k < 2; ++k) \
;         acc[ai][bj][m][n] = __builtin_amdgcn_mfma_f32_16x16x32_bf16(Bt[n][k], At[m][k], acc[ai][bj][m][n], 0, 0, 0); __builtin_amdgcn_s_setprio(0); } while (0)
; template <class Epi, class Sched, bool ALIGN_EPI = false, bool SP2 = false, bool A_TILED = false>
; __device__ __forceinline__ void gemm_phase(PG8_LAS unsigned char* lds, const Gemm g, const Sched& S, const Epi& E, const int wave_s) {
;     ...
;         for (int t = PEEL ? 2 : 0; t < nt; t += 2) {
;             const bool last = (t == nt - 2);
;             const char* a1 = cA + (size_t)(t + 1) * kstepA;
;             const char* a2 = last ? nA : cA + (size_t)(t + 2) * kstepA; const char* b2 = last ? nB : cB + (size_t)(t + 2) * kstep;
;             const char* a3 = a2 + kstepA; const char* b3 = b2 + kstep;
;             if (last && has_next) S.a_ready(nxt);
;             if constexpr (SP2) {
;             PG8_ITER(PG8_MMA)
.LBB0_1841:
	ds_read_b128 v[146:149], v140
	ds_read_b128 v[150:153], v140 offset:1024
	ds_read_b128 v[154:157], v140 offset:2048
	ds_read_b128 v[158:161], v140 offset:3072
	ds_read_b128 v[162:165], v141
	ds_read_b128 v[166:169], v141 offset:1024
	ds_read_b128 v[170:173], v141 offset:2048
	ds_read_b128 v[174:177], v141 offset:3072
	s_add_u32 s52, s60, s39
	s_addc_u32 s53, s61, s40
	s_add_u32 s54, s60, s37
	s_addc_u32 s55, s61, s38
	s_cmp_eq_u32 s41, 28
	s_cselect_b32 s71, s7, s53
	s_cselect_b32 s70, s6, s52
	s_cselect_b32 s69, s3, s55
	s_cselect_b32 s68, s2, s54
	s_mov_b32 m0, s42
	v_lshl_add_u64 v[210:211], s[60:61], 0, v[138:139]
	ds_read_b128 v[178:181], v142
	ds_read_b128 v[182:185], v142 offset:1024
	ds_read_b128 v[186:189], v142 offset:2048
	ds_read_b128 v[190:193], v142 offset:3072
	ds_read_b128 v[194:197], v142 offset:4096
	ds_read_b128 v[198:201], v142 offset:5120
	ds_read_b128 v[202:205], v142 offset:6144
	ds_read_b128 v[206:209], v142 offset:7168
	global_load_lds_dwordx4 v[210:211], off
	v_lshl_add_u64 v[210:211], s[60:61], 0, v[136:137]
	s_mov_b32 m0, s43
	s_nop 0
	global_load_lds_dwordx4 v[210:211], off
	s_waitcnt vmcnt(8) lgkmcnt(0)
	s_barrier
	v_mfma_f32_16x16x32_bf16 v[8:11], v[146:149], v[178:181], v[8:11]
	v_mfma_f32_16x16x32_bf16 v[12:15], v[154:157], v[178:181], v[12:15]
	v_mfma_f32_16x16x32_bf16 v[60:63], v[146:149], v[186:189], v[60:63]
	v_mfma_f32_16x16x32_bf16 v[20:23], v[154:157], v[186:189], v[20:23]
	v_mfma_f32_16x16x32_bf16 v[76:79], v[146:149], v[194:197], v[76:79]
	v_mfma_f32_16x16x32_bf16 v[52:55], v[154:157], v[194:197], v[52:55]
	v_mfma_f32_16x16x32_bf16 v[128:131], v[146:149], v[202:205], v[128:131]
	v_mfma_f32_16x16x32_bf16 v[68:71], v[154:157], v[202:205], v[68:71]
	v_mfma_f32_16x16x32_bf16 v[8:11], v[150:153], v[182:185], v[8:11]
	v_mfma_f32_16x16x32_bf16 v[12:15], v[158:161], v[182:185], v[12:15]
	v_mfma_f32_16x16x32_bf16 v[60:63], v[150:153], v[190:193], v[60:63]
	v_mfma_f32_16x16x32_bf16 v[20:23], v[158:161], v[190:193], v[20:23]
	v_mfma_f32_16x16x32_bf16 v[76:79], v[150:153], v[198:201], v[76:79]
	v_mfma_f32_16x16x32_bf16 v[52:55], v[158:161], v[198:201], v[52:55]
	v_mfma_f32_16x16x32_bf16 v[128:131], v[150:153], v[206:209], v[128:131]
	v_mfma_f32_16x16x32_bf16 v[68:71], v[158:161], v[206:209], v[68:71]
	v_mfma_f32_16x16x32_bf16 v[24:27], v[162:165], v[178:181], v[24:27]
	v_mfma_f32_16x16x32_bf16 v[16:19], v[170:173], v[178:181], v[16:19]
	v_mfma_f32_16x16x32_bf16 v[56:59], v[162:165], v[186:189], v[56:59]
	v_mfma_f32_16x16x32_bf16 v[48:51], v[170:173], v[186:189], v[48:51]
	v_mfma_f32_16x16x32_bf16 v[72:75], v[162:165], v[194:197], v[72:75]
	v_mfma_f32_16x16x32_bf16 v[64:67], v[170:173], v[194:197], v[64:67]
	v_mfma_f32_16x16x32_bf16 v[108:111], v[162:165], v[202:205], v[108:111]
	v_mfma_f32_16x16x32_bf16 v[96:99], v[170:173], v[202:205], v[96:99]
	v_mfma_f32_16x16x32_bf16 v[24:27], v[166:169], v[182:185], v[24:27]
	v_mfma_f32_16x16x32_bf16 v[16:19], v[174:177], v[182:185], v[16:19]
	v_mfma_f32_16x16x32_bf16 v[56:59], v[166:169], v[190:193], v[56:59]
	v_mfma_f32_16x16x32_bf16 v[48:51], v[174:177], v[190:193], v[48:51]
	v_mfma_f32_16x16x32_bf16 v[72:75], v[166:169], v[198:201], v[72:75]
	v_mfma_f32_16x16x32_bf16 v[64:67], v[174:177], v[198:201], v[64:67]
	v_mfma_f32_16x16x32_bf16 v[108:111], v[166:169], v[206:209], v[108:111]
	v_mfma_f32_16x16x32_bf16 v[96:99], v[174:177], v[206:209], v[96:99]
	s_barrier
	s_mov_b32 m0, s44
	v_lshl_add_u64 v[210:211], s[68:69], 0, v[34:35]
	s_add_u32 s52, s68, 0x80000
	ds_read_b128 v[178:181], v142 offset:16384
	ds_read_b128 v[182:185], v142 offset:17408
	ds_read_b128 v[186:189], v142 offset:18432
	ds_read_b128 v[190:193], v142 offset:19456
	ds_read_b128 v[194:197], v142 offset:20480
	ds_read_b128 v[198:201], v142 offset:21504
	ds_read_b128 v[202:205], v142 offset:22528
	ds_read_b128 v[206:209], v142 offset:23552
	global_load_lds_dwordx4 v34, s[68:69]
	v_lshl_add_u64 v[212:213], s[68:69], 0, v[134:135]
	s_mov_b32 m0, s45
	s_addc_u32 s53, s69, 0
	global_load_lds_dwordx4 v134, s[68:69]
	v_lshl_add_u64 v[214:215], s[52:53], 0, v[34:35]
	s_mov_b32 m0, s46
	v_lshl_add_u64 v[216:217], s[70:71], 0, v[132:133]
	global_load_lds_dwordx4 v34, s[52:53]
	v_lshl_add_u64 v[214:215], s[52:53], 0, v[134:135]
	s_mov_b32 m0, s47
	s_nop 0
	global_load_lds_dwordx4 v134, s[52:53]
	v_lshl_add_u64 v[214:215], s[70:71], 0, v[32:33]
	s_mov_b32 m0, s14
	s_nop 0
	global_load_lds_dwordx4 v32, s[70:71]
	s_mov_b32 m0, s15
	s_nop 0
	global_load_lds_dwordx4 v132, s[70:71]
	s_waitcnt vmcnt(8) lgkmcnt(0)
	s_barrier
	v_mfma_f32_16x16x32_bf16 v[100:103], v[146:149], v[178:181], v[100:103]
	v_mfma_f32_16x16x32_bf16 v[104:107], v[154:157], v[178:181], v[104:107]
	v_mfma_f32_16x16x32_bf16 v[116:119], v[146:149], v[186:189], v[116:119]
	v_mfma_f32_16x16x32_bf16 v[120:123], v[154:157], v[186:189], v[120:123]
	v_mfma_f32_16x16x32_bf16 v[84:87], v[146:149], v[194:197], v[84:87]
	v_mfma_f32_16x16x32_bf16 v[80:83], v[154:157], v[194:197], v[80:83]
	v_mfma_f32_16x16x32_bf16 v[36:39], v[146:149], v[202:205], v[36:39]
	v_mfma_f32_16x16x32_bf16 v[28:31], v[154:157], v[202:205], v[28:31]
	v_mfma_f32_16x16x32_bf16 v[100:103], v[150:153], v[182:185], v[100:103]
	v_mfma_f32_16x16x32_bf16 v[104:107], v[158:161], v[182:185], v[104:107]
	v_mfma_f32_16x16x32_bf16 v[116:119], v[150:153], v[190:193], v[116:119]
	v_mfma_f32_16x16x32_bf16 v[120:123], v[158:161], v[190:193], v[120:123]
	v_mfma_f32_16x16x32_bf16 v[84:87], v[150:153], v[198:201], v[84:87]
	v_mfma_f32_16x16x32_bf16 v[80:83], v[158:161], v[198:201], v[80:83]
	v_mfma_f32_16x16x32_bf16 v[36:39], v[150:153], v[206:209], v[36:39]
	v_mfma_f32_16x16x32_bf16 v[28:31], v[158:161], v[206:209], v[28:31]
	v_mfma_f32_16x16x32_bf16 v[124:127], v[162:165], v[178:181], v[124:127]
	v_mfma_f32_16x16x32_bf16 v[112:115], v[170:173], v[178:181], v[112:115]
	v_mfma_f32_16x16x32_bf16 v[92:95], v[162:165], v[186:189], v[92:95]
	v_mfma_f32_16x16x32_bf16 v[88:91], v[170:173], v[186:189], v[88:91]
	v_mfma_f32_16x16x32_bf16 v[44:47], v[162:165], v[194:197], v[44:47]
	v_mfma_f32_16x16x32_bf16 v[40:43], v[170:173], v[194:197], v[40:43]
	v_mfma_f32_16x16x32_bf16 v[4:7], v[162:165], v[202:205], v[4:7]
	v_mfma_f32_16x16x32_bf16 v[0:3], v[170:173], v[202:205], v[0:3]
	v_mfma_f32_16x16x32_bf16 v[124:127], v[166:169], v[182:185], v[124:127]
	v_mfma_f32_16x16x32_bf16 v[112:115], v[174:177], v[182:185], v[112:115]
	v_mfma_f32_16x16x32_bf16 v[92:95], v[166:169], v[190:193], v[92:95]
	v_mfma_f32_16x16x32_bf16 v[88:91], v[174:177], v[190:193], v[88:91]
	v_mfma_f32_16x16x32_bf16 v[44:47], v[166:169], v[198:201], v[44:47]
	v_mfma_f32_16x16x32_bf16 v[40:43], v[174:177], v[198:201], v[40:43]
	v_mfma_f32_16x16x32_bf16 v[4:7], v[166:169], v[206:209], v[4:7]
	v_mfma_f32_16x16x32_bf16 v[0:3], v[174:177], v[206:209], v[0:3]
	s_barrier
	ds_read_b128 v[146:149], v143
	ds_read_b128 v[150:153], v143 offset:1024
	ds_read_b128 v[154:157], v143 offset:2048
	ds_read_b128 v[158:161], v143 offset:3072
	ds_read_b128 v[162:165], v144
	ds_read_b128 v[166:169], v144 offset:1024
	ds_read_b128 v[170:173], v144 offset:2048
	ds_read_b128 v[174:177], v144 offset:3072
	s_add_u32 s52, s70, 0x80000
	s_addc_u32 s53, s71, 0
	s_mov_b32 m0, s21
	v_lshl_add_u64 v[218:219], s[52:53], 0, v[32:33]
	ds_read_b128 v[178:181], v142 offset:32768
	ds_read_b128 v[182:185], v142 offset:33792
	ds_read_b128 v[186:189], v142 offset:34816
	ds_read_b128 v[190:193], v142 offset:35840
	ds_read_b128 v[194:197], v142 offset:36864
	ds_read_b128 v[198:201], v142 offset:37888
	ds_read_b128 v[202:205], v142 offset:38912
	ds_read_b128 v[206:209], v142 offset:39936
	global_load_lds_dwordx4 v32, s[52:53]
	v_lshl_add_u64 v[218:219], s[52:53], 0, v[132:133]
	s_mov_b32 m0, s22
	s_nop 0
	global_load_lds_dwordx4 v132, s[52:53]
	s_waitcnt vmcnt(8) lgkmcnt(0)
	s_barrier
	v_mfma_f32_16x16x32_bf16 v[8:11], v[146:149], v[178:181], v[8:11]
	v_mfma_f32_16x16x32_bf16 v[12:15], v[154:157], v[178:181], v[12:15]
	v_mfma_f32_16x16x32_bf16 v[60:63], v[146:149], v[186:189], v[60:63]
	v_mfma_f32_16x16x32_bf16 v[20:23], v[154:157], v[186:189], v[20:23]
	v_mfma_f32_16x16x32_bf16 v[76:79], v[146:149], v[194:197], v[76:79]
	v_mfma_f32_16x16x32_bf16 v[52:55], v[154:157], v[194:197], v[52:55]
	v_mfma_f32_16x16x32_bf16 v[128:131], v[146:149], v[202:205], v[128:131]
	v_mfma_f32_16x16x32_bf16 v[68:71], v[154:157], v[202:205], v[68:71]
	v_mfma_f32_16x16x32_bf16 v[8:11], v[150:153], v[182:185], v[8:11]
	v_mfma_f32_16x16x32_bf16 v[12:15], v[158:161], v[182:185], v[12:15]
	v_mfma_f32_16x16x32_bf16 v[60:63], v[150:153], v[190:193], v[60:63]
	v_mfma_f32_16x16x32_bf16 v[20:23], v[158:161], v[190:193], v[20:23]
	v_mfma_f32_16x16x32_bf16 v[76:79], v[150:153], v[198:201], v[76:79]
	v_mfma_f32_16x16x32_bf16 v[52:55], v[158:161], v[198:201], v[52:55]
	v_mfma_f32_16x16x32_bf16 v[128:131], v[150:153], v[206:209], v[128:131]
	v_mfma_f32_16x16x32_bf16 v[68:71], v[158:161], v[206:209], v[68:71]
	v_mfma_f32_16x16x32_bf16 v[24:27], v[162:165], v[178:181], v[24:27]
	v_mfma_f32_16x16x32_bf16 v[16:19], v[170:173], v[178:181], v[16:19]
	v_mfma_f32_16x16x32_bf16 v[56:59], v[162:165], v[186:189], v[56:59]
	v_mfma_f32_16x16x32_bf16 v[48:51], v[170:173], v[186:189], v[48:51]
	v_mfma_f32_16x16x32_bf16 v[72:75], v[162:165], v[194:197], v[72:75]
	v_mfma_f32_16x16x32_bf16 v[64:67], v[170:173], v[194:197], v[64:67]
	v_mfma_f32_16x16x32_bf16 v[108:111], v[162:165], v[202:205], v[108:111]
	v_mfma_f32_16x16x32_bf16 v[96:99], v[170:173], v[202:205], v[96:99]
	v_mfma_f32_16x16x32_bf16 v[24:27], v[166:169], v[182:185], v[24:27]
	v_mfma_f32_16x16x32_bf16 v[16:19], v[174:177], v[182:185], v[16:19]
	v_mfma_f32_16x16x32_bf16 v[56:59], v[166:169], v[190:193], v[56:59]
	v_mfma_f32_16x16x32_bf16 v[48:51], v[174:177], v[190:193], v[48:51]
	v_mfma_f32_16x16x32_bf16 v[72:75], v[166:169], v[198:201], v[72:75]
	v_mfma_f32_16x16x32_bf16 v[64:67], v[174:177], v[198:201], v[64:67]
	v_mfma_f32_16x16x32_bf16 v[108:111], v[166:169], v[206:209], v[108:111]
	v_mfma_f32_16x16x32_bf16 v[96:99], v[174:177], v[206:209], v[96:99]
	s_barrier
; #define PG8_MMA(ai, bj, At, Bt) do { __builtin_amdgcn_s_setprio(1); _Pragma("unroll") for (int m = 0; m < 4; ++m) _Pragma("unroll") for (int n = 0; n < 2; ++n) _Pragma("unroll") for (int k = 0; k < 2; ++k) \
;         acc[ai][bj][m][n] = __builtin_amdgcn_mfma_f32_16x16x32_bf16(Bt[n][k], At[m][k], acc[ai][bj][m][n], 0, 0, 0); __builtin_amdgcn_s_setprio(0); } while (0)
; template <class Epi, class Sched, bool ALIGN_EPI = false, bool SP2 = false, bool A_TILED = false>
; __device__ __forceinline__ void gemm_phase(PG8_LAS unsigned char* lds, const Gemm g, const Sched& S, const Epi& E, const int wave_s) {
;     ...
;         for (int t = PEEL ? 2 : 0; t < nt; t += 2) {
;             const bool last = (t == nt - 2);
;             const char* a1 = cA + (size_t)(t + 1) * kstepA;
;             const char* a2 = last ? nA : cA + (size_t)(t + 2) * kstepA; const char* b2 = last ? nB : cB + (size_t)(t + 2) * kstep;
;             const char* a3 = a2 + kstepA; const char* b3 = b2 + kstep;
;             if (last && has_next) S.a_ready(nxt);
;             if constexpr (SP2) {
;             PG8_ITER(PG8_MMA)
	s_mov_b32 m0, s48
	v_lshl_add_u64 v[210:211], v[210:211], 0, s[64:65]
	s_add_u32 s52, s68, 0x80080
	ds_read_b128 v[178:181], v142 offset:49152
	ds_read_b128 v[182:185], v142 offset:50176
	ds_read_b128 v[186:189], v142 offset:51200
	ds_read_b128 v[190:193], v142 offset:52224
	ds_read_b128 v[194:197], v142 offset:53248
	ds_read_b128 v[198:201], v142 offset:54272
	ds_read_b128 v[202:205], v142 offset:55296
	ds_read_b128 v[206:209], v142 offset:56320
	global_load_lds_dwordx4 v[210:211], off
	v_lshl_add_u64 v[210:211], v[212:213], 0, s[64:65]
	s_mov_b32 m0, s49
	s_addc_u32 s53, s69, 0
	global_load_lds_dwordx4 v[210:211], off
	v_lshl_add_u64 v[210:211], s[52:53], 0, v[34:35]
	s_mov_b32 m0, s50
	s_nop 0
	global_load_lds_dwordx4 v34, s[52:53]
	v_lshl_add_u64 v[210:211], s[52:53], 0, v[134:135]
	s_mov_b32 m0, s51
	s_nop 0
	global_load_lds_dwordx4 v134, s[52:53]
	v_lshl_add_u64 v[210:211], v[214:215], 0, s[64:65]
	s_mov_b32 m0, s23
	s_nop 0
	global_load_lds_dwordx4 v[210:211], off
	v_lshl_add_u64 v[210:211], v[216:217], 0, s[64:65]
	s_mov_b32 m0, s36
	s_nop 0
	global_load_lds_dwordx4 v[210:211], off
	s_waitcnt vmcnt(8) lgkmcnt(0)
	s_barrier
	v_mfma_f32_16x16x32_bf16 v[100:103], v[146:149], v[178:181], v[100:103]
	v_mfma_f32_16x16x32_bf16 v[104:107], v[154:157], v[178:181], v[104:107]
	v_mfma_f32_16x16x32_bf16 v[116:119], v[146:149], v[186:189], v[116:119]
	v_mfma_f32_16x16x32_bf16 v[120:123], v[154:157], v[186:189], v[120:123]
	v_mfma_f32_16x16x32_bf16 v[84:87], v[146:149], v[194:197], v[84:87]
	v_mfma_f32_16x16x32_bf16 v[80:83], v[154:157], v[194:197], v[80:83]
	v_mfma_f32_16x16x32_bf16 v[36:39], v[146:149], v[202:205], v[36:39]
	v_mfma_f32_16x16x32_bf16 v[28:31], v[154:157], v[202:205], v[28:31]
	v_mfma_f32_16x16x32_bf16 v[100:103], v[150:153], v[182:185], v[100:103]
	v_mfma_f32_16x16x32_bf16 v[104:107], v[158:161], v[182:185], v[104:107]
	v_mfma_f32_16x16x32_bf16 v[116:119], v[150:153], v[190:193], v[116:119]
	v_mfma_f32_16x16x32_bf16 v[120:123], v[158:161], v[190:193], v[120:123]
	v_mfma_f32_16x16x32_bf16 v[84:87], v[150:153], v[198:201], v[84:87]
	v_mfma_f32_16x16x32_bf16 v[80:83], v[158:161], v[198:201], v[80:83]
	v_mfma_f32_16x16x32_bf16 v[36:39], v[150:153], v[206:209], v[36:39]
	v_mfma_f32_16x16x32_bf16 v[28:31], v[158:161], v[206:209], v[28:31]
	v_mfma_f32_16x16x32_bf16 v[124:127], v[162:165], v[178:181], v[124:127]
	v_mfma_f32_16x16x32_bf16 v[112:115], v[170:173], v[178:181], v[112:115]
	v_mfma_f32_16x16x32_bf16 v[92:95], v[162:165], v[186:189], v[92:95]
	v_mfma_f32_16x16x32_bf16 v[88:91], v[170:173], v[186:189], v[88:91]
	v_mfma_f32_16x16x32_bf16 v[44:47], v[162:165], v[194:197], v[44:47]
	v_mfma_f32_16x16x32_bf16 v[40:43], v[170:173], v[194:197], v[40:43]
	v_mfma_f32_16x16x32_bf16 v[4:7], v[162:165], v[202:205], v[4:7]
	v_mfma_f32_16x16x32_bf16 v[0:3], v[170:173], v[202:205], v[0:3]
	v_mfma_f32_16x16x32_bf16 v[124:127], v[166:169], v[182:185], v[124:127]
	v_mfma_f32_16x16x32_bf16 v[112:115], v[174:177], v[182:185], v[112:115]
	v_mfma_f32_16x16x32_bf16 v[92:95], v[166:169], v[190:193], v[92:95]
	v_mfma_f32_16x16x32_bf16 v[88:91], v[174:177], v[190:193], v[88:91]
	v_mfma_f32_16x16x32_bf16 v[44:47], v[166:169], v[198:201], v[44:47]
	v_mfma_f32_16x16x32_bf16 v[40:43], v[174:177], v[198:201], v[40:43]
	v_mfma_f32_16x16x32_bf16 v[4:7], v[166:169], v[206:209], v[4:7]
	v_mfma_f32_16x16x32_bf16 v[0:3], v[174:177], v[206:209], v[0:3]
	s_barrier
	s_add_i32 s41, s41, 2
	s_add_u32 s37, s37, 0x100
	s_addc_u32 s38, s38, 0
	s_add_u32 s39, s39, 0x100
	s_addc_u32 s40, s40, 0
	v_lshl_add_u64 v[136:137], v[136:137], 0, s[66:67]
	s_cmp_gt_u32 s41, 29
	v_lshl_add_u64 v[138:139], v[138:139], 0, s[66:67]
	s_cbranch_scc0 .LBB0_1841
	s_waitcnt vmcnt(0)
	s_cmpk_lt_u32 s0, 0x100
	s_cbranch_scc0 .LBB0_1844
	s_barrier

; __device__ __forceinline__ int tid_now(int wave_s) { unsigned z = 0u; asm volatile("" : "+v"(z)); return (wave_s << 6) | (int)__builtin_amdgcn_mbcnt_hi(~0u, __builtin_amdgcn_mbcnt_lo(~0u, z)); }
; __device__ __forceinline__ unsigned xb_ld(unsigned* p)              { return __hip_atomic_load(p, __ATOMIC_RELAXED, __HIP_MEMORY_SCOPE_AGENT); }
; __device__ __forceinline__ unsigned xb_add(unsigned* p, unsigned v) { return __hip_atomic_fetch_add(p, v, __ATOMIC_RELAXED, __HIP_MEMORY_SCOPE_AGENT); }
; #define XB_SPIN(cond, bar) do { unsigned _sp = 0; while (cond) { __builtin_amdgcn_s_sleep(1); \
;     if ((++_sp & 255u) == 0u) { if (xb_ld(&(bar)[XB_TMO])) break; if (_sp > XB_SPIN_CAP) { atomicAdd(&(bar)[XB_TMO], 1u); break; } } } } while (0)
; __device__ __forceinline__ void xcd_barrier(const XcdBarrier& b) {
;     asm volatile("s_waitcnt vmcnt(0)" ::: "memory");
;     __syncthreads();
;     if (tid_now(b.w) == 0) {
;         unsigned* bar = b.bar;
;         __builtin_amdgcn_s_waitcnt(0);
;         unsigned nloc = b.st[0], nx = b.st[1];
;         if (nloc == 0u) { xcd_barrier_complete(bar, b.x, nloc, nx, b.np); b.st[0] = nloc; b.st[1] = nx; }
;         const unsigned old = xb_add(&bar[XB_XSUB(b.x)], 1u);
;         const unsigned gen = old / nloc;
;         if (old + 1u == (gen + 1u) * nloc) {
;             __builtin_amdgcn_fence(__ATOMIC_RELEASE, "agent");
;             asm volatile("s_waitcnt vmcnt(0)" ::: "memory");
;             const unsigned og = xb_add(&bar[XB_TOP], 1u);
;             const unsigned tg = og / nx;
;             if (og + 1u == (tg + 1u) * nx) xb_add(&bar[XB_TOPGEN], 1u);
;             else XB_SPIN(xb_ld(&bar[XB_TOPGEN]) == tg, bar);
;             __builtin_amdgcn_fence(__ATOMIC_ACQUIRE, "agent");
;             xb_add(&bar[XB_XGEN(b.x)], 1u);
;             asm volatile("s_waitcnt vmcnt(0)" ::: "memory");
;         } else {
;             XB_SPIN(xb_ld(&bar[XB_XGEN(b.x)]) == gen, bar);
;             __builtin_amdgcn_fence(__ATOMIC_ACQUIRE, "agent");
;             asm volatile("s_waitcnt vmcnt(0)" ::: "memory");
;         }
;     }
;     __syncthreads();
; }
.LBB0_1885:
	s_setprio 0
	s_cmp_gt_i32 s35, 11
	s_cselect_b64 s[2:3], -1, 0
	s_and_b64 s[0:1], s[12:13], s[2:3]
	s_andn2_b64 vcc, exec, s[0:1]
	s_cbranch_vccnz .LBB0_1939
	s_waitcnt vmcnt(0)
	v_mov_b32_e32 v0, 0
	s_waitcnt vmcnt(0)
	s_waitcnt lgkmcnt(0)
	s_barrier
	s_nop 0
	v_mbcnt_lo_u32_b32 v0, -1, v0
	v_mbcnt_hi_u32_b32 v0, -1, v0
	v_or_b32_e32 v0, s33, v0
	v_cmp_eq_u32_e32 vcc, 0, v0
	s_and_saveexec_b64 s[4:5], vcc
	s_cbranch_execz .LBB0_1938
	s_add_i32 s0, 0, 0x27f68
	v_mov_b32_e32 v0, s0
	s_waitcnt vmcnt(0) expcnt(0) lgkmcnt(0)
	ds_read_b32 v2, v0
	s_add_i32 s0, 0, 0x27f6c
	v_mov_b32_e32 v0, s0
	ds_read_b32 v0, v0
	s_waitcnt lgkmcnt(1)
	v_cmp_ne_u32_e32 vcc, 0, v2
	s_cbranch_vccnz .LBB0_1902
	s_add_u32 s6, s10, 0x1000
	s_addc_u32 s7, s11, 0
	s_add_u32 s12, s10, 0x1100
	s_addc_u32 s13, s11, 0
	s_add_u32 s60, s10, 0x1200
	s_addc_u32 s61, s11, 0
	s_add_u32 s62, s10, 0x1300
	s_addc_u32 s63, s11, 0
	s_mov_b32 s0, 1
	v_mov_b32_e32 v16, 0
	s_branch .LBB0_1890

; #define PG8_STAGE(bufoff, gbase, voff) do { _Pragma("unroll") for (int _i = 0; _i < 2; ++_i) \
;         __builtin_amdgcn_global_load_lds((const unsigned*)((const char*)(gbase) + (voff)[_i]), (PG8_LAS unsigned*)(lds + (bufoff) + ldsw + _i * 8192), 16, 0, 0); } while (0)
; #define PG8_WAIT_V(n) asm volatile("s_waitcnt vmcnt(" #n ")" ::: "memory")
; #define PG8_BAR __builtin_amdgcn_s_barrier()
; template <class Epi, class Sched, bool ALIGN_EPI = false, bool SP2 = false, bool A_TILED = false>
; __device__ __forceinline__ void gemm_phase(PG8_LAS unsigned char* lds, const Gemm g, const Sched& S, const Epi& E, const int wave_s) {
;     ...
;     const int tid = tid_, wid = __builtin_amdgcn_readfirstlane(tid >> 6), lane = tid & 63, wr = wid >> 2, wc = wid & 3, fr = lane & 15, fq = lane >> 4;
;     const int K = g.K, nt = K / BK;
;     unsigned voffA[2], voffB[2];
; #pragma unroll
;     for (int i = 0; i < 2; ++i) { int R, C; stage_rc(tid * 16 + i * 8192, R, C); const int Rb = Epi::PERM ? ((R & ~31) + perm32(R & 31)) : R;
;         voffA[i] = A_TILED ? (unsigned)(tid * 16 + i * 8192) : (unsigned)(R * K + C) * 2u; voffB[i] = (unsigned)(Rb * K + C) * 2u; }
;     const size_t kstep = (size_t)(BK * 2);
;     const size_t hstep = (size_t)HALF * K * 2;
;     const size_t tstep = 2 * hstep;
;     const size_t kstepA = A_TILED ? (size_t)32768 : kstep, hstepA = A_TILED ? (size_t)16384 : hstep, tstepA = A_TILED ? (size_t)nt * 32768 : tstep;
;     const unsigned ldsw = (unsigned)wid * 1024u;
;     const int aoff = lds_byte(wr * 64 + fr, fq * 8), boff = lds_byte(wc * 32 + fr, fq * 8);
;     ...
;     if constexpr (SP2) {
;         PG8_STAGE(PG8_SB(0, 0), cB, voffB); PG8_STAGE(PG8_SB(0, 1), cB + hstep, voffB); PG8_STAGE(PG8_SA(0, 0), cA, voffA); PG8_STAGE(PG8_SA(0, 1), cA + hstepA, voffA);
;         if (wr == 1) PG8_BAR;
;         PG8_WAIT_V(2); PG8_BAR;
;         PG8_STAGE(PG8_SB(1, 0), cB + kstep, voffB); PG8_STAGE(PG8_SA(1, 0), cA + kstepA, voffA); PG8_STAGE(PG8_SB(1, 1), cB + hstep + kstep, voffB);
;         PG8_WAIT_V(6); PG8_BAR;
.LBB0_1943:
	s_ashr_i32 s40, s86, 31
	s_add_u32 s41, s2, 0x34600000
	s_sext_i32_i16 s49, s12
	s_addc_u32 s42, s3, 0
	s_lshl_b32 s47, s13, 13
	s_mov_b64 s[12:13], 0x80
	s_and_b32 s2, s46, 3
	v_and_b32_e32 v15, 15, v14
	v_and_b32_e32 v16, 48, v14
	v_lshlrev_b32_e32 v14, 2, v14
	s_add_i32 m0, s22, 0x18000
	v_lshl_add_u64 v[6:7], v[6:7], 0, s[12:13]
	v_lshl_or_b32 v15, v15, 6, v16
	v_and_b32_e32 v14, 32, v14
	s_lshl_b32 s2, s2, 12
	s_waitcnt vmcnt(2)
	s_barrier
	global_load_lds_dwordx4 v[6:7], off
	v_lshl_add_u64 v[4:5], v[4:5], 0, s[12:13]
	s_add_i32 m0, s22, 0x1a000
	s_add_i32 s43, s22, 0x8000
	s_add_i32 s44, s22, 0xa000
	v_bitop3_b32 v144, v15, s2, v14 bitop3:0xde
	global_load_lds_dwordx4 v[4:5], off
	v_lshl_add_u64 v[0:1], v[0:1], 0, s[12:13]
	s_mov_b32 m0, s43
	s_add_u32 s2, s76, 0x80080
	global_load_lds_dwordx4 v[0:1], off
	v_lshl_add_u64 v[0:1], v[2:3], 0, s[12:13]
	s_mov_b32 m0, s44
	s_addc_u32 s3, s77, 0
	global_load_lds_dwordx4 v[0:1], off
	s_add_i32 m0, s22, 0x1c000
	v_lshl_add_u64 v[0:1], s[2:3], 0, v[128:129]
	global_load_lds_dwordx4 v128, s[2:3]
	v_lshl_add_u64 v[0:1], s[2:3], 0, v[130:131]
	s_add_i32 m0, s22, 0x1e000
	s_cmpk_lt_u32 s45, 0x100
	global_load_lds_dwordx4 v130, s[2:3]
	v_lshlrev_b32_e32 v0, 15, v8
	v_and_b32_e32 v0, 0xffff0000, v0
	v_lshl_add_u32 v0, v9, 12, v0
	v_and_b32_e32 v1, 1, v8
	v_lshl_or_b32 v0, v1, 6, v0
	v_lshl_add_u32 v136, v10, 1, v0
	v_lshlrev_b32_e32 v0, 15, v12
	v_and_b32_e32 v0, 0xffff0000, v0
	s_waitcnt vmcnt(6)
	s_mov_b32 s98, 0
	s_cselect_b64 s[60:61], -1, 0
	s_bitcmp1_b32 s33, 8
	s_cbranch_scc1 .Lsp_7
	s_setprio 1
.Lsp_7:
	s_and_b32 s2, s15, 0x400
	v_lshl_add_u32 v0, v11, 12, v0
	v_and_b32_e32 v1, 1, v12
	v_bitop3_b32 v16, v15, s47, v14 bitop3:0xde
	s_bfe_u32 s45, s46, 0x10001
	s_or_b32 s46, s2, s47
	v_mov_b32_e32 v137, 0
	v_lshl_or_b32 v0, v1, 6, v0
	s_add_i32 s47, 0, 0x10000
	s_add_i32 s48, 0, 0x14000
	v_lshl_add_u32 v138, v13, 1, v0
	v_mov_b32_e32 v139, v137
	v_mov_b64_e32 v[140:141], 0x200
	v_mov_b64_e32 v[142:143], 0x1ff
	v_add_u32_e32 v145, s47, v144
	v_add_u32_e32 v146, s48, v144
	v_add_u32_e32 v147, 0, v16
	s_mov_b64 s[62:63], 0x100
	s_mov_b64 s[64:65], 0x180
	s_barrier
	s_branch .LBB0_1946

.Lpw_8:
	s_barrier
	v_mfma_f32_16x16x32_bf16 v[148:151], v[0:3], v[60:63], 0
	v_mfma_f32_16x16x32_bf16 v[158:161], v[0:3], v[92:95], 0
	v_mfma_f32_16x16x32_bf16 v[166:169], v[0:3], v[108:111], 0
	v_mfma_f32_16x16x32_bf16 v[0:3], v[0:3], v[120:123], 0
	v_mfma_f32_16x16x32_bf16 v[150:153], v[4:7], v[88:91], v[148:151]
	v_mfma_f32_16x16x32_bf16 v[158:161], v[4:7], v[104:107], v[158:161]
	v_mfma_f32_16x16x32_bf16 v[166:169], v[4:7], v[116:119], v[166:169]
	v_mfma_f32_16x16x32_bf16 v[0:3], v[4:7], v[124:127], v[0:3]
	v_mfma_f32_16x16x32_bf16 v[4:7], v[8:11], v[120:123], 0
	v_mfma_f32_16x16x32_bf16 v[154:157], v[8:11], v[60:63], 0
	v_mfma_f32_16x16x32_bf16 v[162:165], v[8:11], v[92:95], 0
	v_mfma_f32_16x16x32_bf16 v[170:173], v[8:11], v[108:111], 0
	v_mfma_f32_16x16x32_bf16 v[4:7], v[12:15], v[124:127], v[4:7]
	v_mfma_f32_16x16x32_bf16 v[154:157], v[12:15], v[88:91], v[154:157]
	v_mfma_f32_16x16x32_bf16 v[162:165], v[12:15], v[104:107], v[162:165]
	v_mfma_f32_16x16x32_bf16 v[170:173], v[12:15], v[116:119], v[170:173]
	v_mfma_f32_16x16x32_bf16 v[8:11], v[16:19], v[60:63], 0
	v_mfma_f32_16x16x32_bf16 v[174:177], v[20:23], v[88:91], v[8:11]
	v_mfma_f32_16x16x32_bf16 v[8:11], v[24:27], v[60:63], 0
	v_mfma_f32_16x16x32_bf16 v[60:63], v[28:31], v[88:91], v[8:11]
	v_mfma_f32_16x16x32_bf16 v[8:11], v[16:19], v[92:95], 0
	v_mfma_f32_16x16x32_bf16 v[178:181], v[20:23], v[104:107], v[8:11]
	v_mfma_f32_16x16x32_bf16 v[8:11], v[24:27], v[92:95], 0
	v_mfma_f32_16x16x32_bf16 v[182:185], v[28:31], v[104:107], v[8:11]
	v_mfma_f32_16x16x32_bf16 v[8:11], v[16:19], v[108:111], 0
	v_mfma_f32_16x16x32_bf16 v[186:189], v[20:23], v[116:119], v[8:11]
	v_mfma_f32_16x16x32_bf16 v[8:11], v[24:27], v[108:111], 0
	v_mfma_f32_16x16x32_bf16 v[190:193], v[28:31], v[116:119], v[8:11]
	v_mfma_f32_16x16x32_bf16 v[8:11], v[16:19], v[120:123], 0
	v_mfma_f32_16x16x32_bf16 v[194:197], v[20:23], v[124:127], v[8:11]
	v_mfma_f32_16x16x32_bf16 v[8:11], v[24:27], v[120:123], 0
	v_mfma_f32_16x16x32_bf16 v[198:201], v[28:31], v[124:127], v[8:11]
	s_barrier
	s_add_i32 s67, 0, 0x18000
	s_add_i32 s75, 0, 0x1c000
	v_add_u32_e32 v148, s67, v144
	v_add_u32_e32 v149, s75, v144
	s_nop 0
	ds_read_b128 v[8:11], v148
	ds_read_b128 v[12:15], v148 offset:1024
	ds_read_b128 v[16:19], v148 offset:2048
	ds_read_b128 v[20:23], v148 offset:3072
	ds_read_b128 v[202:205], v149
	ds_read_b128 v[206:209], v149 offset:1024
	ds_read_b128 v[210:213], v149 offset:2048
	ds_read_b128 v[214:217], v149 offset:3072
	s_add_u32 s80, s78, 0x80100
	s_addc_u32 s81, s79, 0
	s_mov_b32 m0, s36
	v_lshl_add_u64 v[88:89], s[80:81], 0, v[134:135]
	ds_read_b128 v[24:27], v147 offset:32768
	ds_read_b128 v[28:31], v147 offset:33792
	ds_read_b128 v[218:221], v147 offset:34816
	ds_read_b128 v[222:225], v147 offset:35840
	ds_read_b128 v[226:229], v147 offset:36864
	ds_read_b128 v[230:233], v147 offset:37888
	ds_read_b128 v[234:237], v147 offset:38912
	ds_read_b128 v[238:241], v147 offset:39936
	global_load_lds_dwordx4 v134, s[80:81]
	v_lshl_add_u64 v[88:89], s[80:81], 0, v[132:133]
	s_mov_b32 m0, s37
	s_nop 0
	global_load_lds_dwordx4 v132, s[80:81]
	s_waitcnt vmcnt(8) lgkmcnt(0)
	s_barrier
	v_mfma_f32_16x16x32_bf16 v[64:67], v[8:11], v[24:27], v[64:67]
	v_mfma_f32_16x16x32_bf16 v[120:123], v[12:15], v[28:31], v[64:67]
	v_mfma_f32_16x16x32_bf16 v[64:67], v[16:19], v[24:27], v[68:71]
	v_mfma_f32_16x16x32_bf16 v[124:127], v[20:23], v[28:31], v[64:67]
	v_mfma_f32_16x16x32_bf16 v[64:67], v[8:11], v[218:221], v[72:75]
	v_mfma_f32_16x16x32_bf16 v[104:107], v[12:15], v[222:225], v[64:67]
	v_mfma_f32_16x16x32_bf16 v[64:67], v[16:19], v[218:221], v[76:79]
	v_mfma_f32_16x16x32_bf16 v[108:111], v[20:23], v[222:225], v[64:67]
	v_mfma_f32_16x16x32_bf16 v[64:67], v[8:11], v[226:229], v[80:83]
	v_mfma_f32_16x16x32_bf16 v[88:91], v[12:15], v[230:233], v[64:67]
	v_mfma_f32_16x16x32_bf16 v[64:67], v[16:19], v[226:229], v[84:87]
	v_mfma_f32_16x16x32_bf16 v[92:95], v[20:23], v[230:233], v[64:67]
	v_mfma_f32_16x16x32_bf16 v[64:67], v[8:11], v[234:237], v[96:99]
	v_mfma_f32_16x16x32_bf16 v[68:71], v[16:19], v[234:237], v[100:103]
	v_mfma_f32_16x16x32_bf16 v[64:67], v[12:15], v[238:241], v[64:67]
	v_mfma_f32_16x16x32_bf16 v[68:71], v[20:23], v[238:241], v[68:71]
	v_mfma_f32_16x16x32_bf16 v[72:75], v[202:205], v[24:27], v[112:115]
	v_mfma_f32_16x16x32_bf16 v[24:27], v[210:213], v[24:27], v[32:35]
	v_mfma_f32_16x16x32_bf16 v[116:119], v[214:217], v[28:31], v[24:27]
	v_mfma_f32_16x16x32_bf16 v[24:27], v[202:205], v[218:221], v[36:39]
	v_mfma_f32_16x16x32_bf16 v[96:99], v[206:209], v[222:225], v[24:27]
	v_mfma_f32_16x16x32_bf16 v[24:27], v[210:213], v[218:221], v[40:43]
	v_mfma_f32_16x16x32_bf16 v[100:103], v[214:217], v[222:225], v[24:27]
	v_mfma_f32_16x16x32_bf16 v[24:27], v[202:205], v[226:229], v[44:47]
	v_mfma_f32_16x16x32_bf16 v[80:83], v[206:209], v[230:233], v[24:27]
	v_mfma_f32_16x16x32_bf16 v[24:27], v[210:213], v[226:229], v[48:51]
	v_mfma_f32_16x16x32_bf16 v[84:87], v[214:217], v[230:233], v[24:27]
	v_mfma_f32_16x16x32_bf16 v[24:27], v[202:205], v[234:237], v[52:55]
	v_mfma_f32_16x16x32_bf16 v[48:51], v[206:209], v[238:241], v[24:27]
	v_mfma_f32_16x16x32_bf16 v[24:27], v[210:213], v[234:237], v[56:59]
	v_mfma_f32_16x16x32_bf16 v[112:115], v[206:209], v[28:31], v[72:75]
	v_mfma_f32_16x16x32_bf16 v[52:55], v[214:217], v[238:241], v[24:27]
	s_barrier
; #define PG8_MMA(ai, bj, At, Bt) do { __builtin_amdgcn_s_setprio(1); _Pragma("unroll") for (int m = 0; m < 4; ++m) _Pragma("unroll") for (int n = 0; n < 2; ++n) _Pragma("unroll") for (int k = 0; k < 2; ++k) \
;         acc[ai][bj][m][n] = __builtin_amdgcn_mfma_f32_16x16x32_bf16(Bt[n][k], At[m][k], acc[ai][bj][m][n], 0, 0, 0); __builtin_amdgcn_s_setprio(0); } while (0)
; template <class Epi, class Sched, bool ALIGN_EPI = false, bool SP2 = false, bool A_TILED = false>
; __device__ __forceinline__ void gemm_phase(PG8_LAS unsigned char* lds, const Gemm g, const Sched& S, const Epi& E, const int wave_s) {
;     ...
; #pragma nounroll
;         for (int t = PEEL ? 2 : 0; t < nt; t += 2) {
;             const bool last = (t == nt - 2);
;             const char* a1 = cA + (size_t)(t + 1) * kstepA;
;             const char* a2 = last ? nA : cA + (size_t)(t + 2) * kstepA; const char* b2 = last ? nB : cB + (size_t)(t + 2) * kstep;
;             const char* a3 = a2 + kstepA; const char* b3 = b2 + kstep;
;             if (last && has_next) S.a_ready(nxt);
;             if constexpr (SP2) {
;             PG8_ITER(PG8_MMA)
	s_add_i32 s67, s67, s15
	s_add_i32 s69, s67, 0x2000
	s_nop 1
	v_lshl_add_u64 v[24:25], v[242:243], 0, s[64:65]
	s_mov_b32 m0, s67
	s_add_u32 s80, s76, 0x80180
	ds_read_b128 v[32:35], v147 offset:49152
	ds_read_b128 v[36:39], v147 offset:50176
	ds_read_b128 v[218:221], v147 offset:51200
	ds_read_b128 v[222:225], v147 offset:52224
	ds_read_b128 v[226:229], v147 offset:53248
	ds_read_b128 v[230:233], v147 offset:54272
	ds_read_b128 v[234:237], v147 offset:55296
	ds_read_b128 v[238:241], v147 offset:56320
	global_load_lds_dwordx4 v[24:25], off
	v_lshl_add_u64 v[24:25], v[244:245], 0, s[64:65]
	s_mov_b32 m0, s69
	s_addc_u32 s81, s77, 0
	s_add_i32 s75, s75, s15
	global_load_lds_dwordx4 v[24:25], off
	v_lshl_add_u64 v[24:25], s[80:81], 0, v[128:129]
	s_mov_b32 m0, s75
	s_add_i32 s82, s75, 0x2000
	global_load_lds_dwordx4 v128, s[80:81]
	v_lshl_add_u64 v[24:25], s[80:81], 0, v[130:131]
	s_mov_b32 m0, s82
	s_nop 0
	global_load_lds_dwordx4 v130, s[80:81]
	v_lshl_add_u64 v[24:25], v[246:247], 0, s[64:65]
	s_mov_b32 m0, s43
	s_nop 0
	global_load_lds_dwordx4 v[24:25], off
	v_lshl_add_u64 v[24:25], v[248:249], 0, s[64:65]
	s_mov_b32 m0, s44
	s_nop 0
	global_load_lds_dwordx4 v[24:25], off
	s_waitcnt vmcnt(8) lgkmcnt(0)
	s_barrier
	v_mfma_f32_16x16x32_bf16 v[24:27], v[8:11], v[32:35], v[150:153]
	v_mfma_f32_16x16x32_bf16 v[72:75], v[12:15], v[36:39], v[24:27]
	v_mfma_f32_16x16x32_bf16 v[24:27], v[16:19], v[32:35], v[154:157]
	v_mfma_f32_16x16x32_bf16 v[76:79], v[20:23], v[36:39], v[24:27]
	v_mfma_f32_16x16x32_bf16 v[24:27], v[8:11], v[218:221], v[158:161]
	v_mfma_f32_16x16x32_bf16 v[40:43], v[12:15], v[222:225], v[24:27]
	v_mfma_f32_16x16x32_bf16 v[24:27], v[16:19], v[218:221], v[162:165]
	v_mfma_f32_16x16x32_bf16 v[0:3], v[8:11], v[234:237], v[0:3]
	v_mfma_f32_16x16x32_bf16 v[44:47], v[20:23], v[222:225], v[24:27]
	v_mfma_f32_16x16x32_bf16 v[24:27], v[8:11], v[226:229], v[166:169]
	v_mfma_f32_16x16x32_bf16 v[28:31], v[16:19], v[226:229], v[170:173]
	v_mfma_f32_16x16x32_bf16 v[8:11], v[12:15], v[238:241], v[0:3]
	v_mfma_f32_16x16x32_bf16 v[0:3], v[16:19], v[234:237], v[4:7]
	v_mfma_f32_16x16x32_bf16 v[24:27], v[12:15], v[230:233], v[24:27]
	v_mfma_f32_16x16x32_bf16 v[28:31], v[20:23], v[230:233], v[28:31]
	v_mfma_f32_16x16x32_bf16 v[12:15], v[20:23], v[238:241], v[0:3]
	v_mfma_f32_16x16x32_bf16 v[0:3], v[202:205], v[32:35], v[174:177]
	v_mfma_f32_16x16x32_bf16 v[56:59], v[206:209], v[36:39], v[0:3]
	v_mfma_f32_16x16x32_bf16 v[0:3], v[210:213], v[32:35], v[60:63]
	v_mfma_f32_16x16x32_bf16 v[60:63], v[214:217], v[36:39], v[0:3]
	v_mfma_f32_16x16x32_bf16 v[0:3], v[202:205], v[218:221], v[178:181]
	v_mfma_f32_16x16x32_bf16 v[32:35], v[206:209], v[222:225], v[0:3]
	v_mfma_f32_16x16x32_bf16 v[0:3], v[210:213], v[218:221], v[182:185]
	v_mfma_f32_16x16x32_bf16 v[36:39], v[214:217], v[222:225], v[0:3]
	v_mfma_f32_16x16x32_bf16 v[0:3], v[202:205], v[226:229], v[186:189]
	v_mfma_f32_16x16x32_bf16 v[16:19], v[206:209], v[230:233], v[0:3]
	v_mfma_f32_16x16x32_bf16 v[0:3], v[210:213], v[226:229], v[190:193]
	v_mfma_f32_16x16x32_bf16 v[20:23], v[214:217], v[230:233], v[0:3]
	v_mfma_f32_16x16x32_bf16 v[0:3], v[202:205], v[234:237], v[194:197]
	v_mfma_f32_16x16x32_bf16 v[4:7], v[210:213], v[234:237], v[198:201]
	v_mfma_f32_16x16x32_bf16 v[0:3], v[206:209], v[238:241], v[0:3]
	v_mfma_f32_16x16x32_bf16 v[4:7], v[214:217], v[238:241], v[4:7]
	s_barrier
	s_add_u32 s83, s76, 0x200
	s_addc_u32 s85, s77, 0
	s_add_u32 s76, s78, 0x80180
	s_addc_u32 s77, s79, 0
	s_mov_b32 s88, 0
.LBB0_1953:
	ds_read_b128 v[150:153], v145
	ds_read_b128 v[154:157], v145 offset:1024
	ds_read_b128 v[158:161], v145 offset:2048
	ds_read_b128 v[162:165], v145 offset:3072
	ds_read_b128 v[166:169], v146
	ds_read_b128 v[170:173], v146 offset:1024
	ds_read_b128 v[174:177], v146 offset:2048
	ds_read_b128 v[178:181], v146 offset:3072
	s_add_u32 s78, s76, 0xfff80080
	s_addc_u32 s79, s77, -1
	s_cmp_eq_u32 s88, 28
	s_cselect_b32 s81, s50, s79
	s_cselect_b32 s80, s51, s78
	s_cselect_b32 s79, s52, s85
	s_cselect_b32 s78, s53, s83
	s_mov_b32 m0, s54
	v_lshl_add_u64 v[214:215], s[76:77], 0, v[138:139]
	ds_read_b128 v[182:185], v147
	ds_read_b128 v[186:189], v147 offset:1024
	ds_read_b128 v[190:193], v147 offset:2048
	ds_read_b128 v[194:197], v147 offset:3072
	ds_read_b128 v[198:201], v147 offset:4096
	ds_read_b128 v[202:205], v147 offset:5120
	ds_read_b128 v[206:209], v147 offset:6144
	ds_read_b128 v[210:213], v147 offset:7168
	global_load_lds_dwordx4 v138, s[76:77]
	v_lshl_add_u64 v[214:215], s[76:77], 0, v[136:137]
	s_mov_b32 m0, s55
	s_nop 0
	global_load_lds_dwordx4 v136, s[76:77]
	s_waitcnt vmcnt(8) lgkmcnt(0)
	s_barrier
	v_mfma_f32_16x16x32_bf16 v[120:123], v[150:153], v[182:185], v[120:123]
	v_mfma_f32_16x16x32_bf16 v[124:127], v[158:161], v[182:185], v[124:127]
	v_mfma_f32_16x16x32_bf16 v[104:107], v[150:153], v[190:193], v[104:107]
	v_mfma_f32_16x16x32_bf16 v[108:111], v[158:161], v[190:193], v[108:111]
	v_mfma_f32_16x16x32_bf16 v[88:91], v[150:153], v[198:201], v[88:91]
	v_mfma_f32_16x16x32_bf16 v[92:95], v[158:161], v[198:201], v[92:95]
	v_mfma_f32_16x16x32_bf16 v[64:67], v[150:153], v[206:209], v[64:67]
	v_mfma_f32_16x16x32_bf16 v[68:71], v[158:161], v[206:209], v[68:71]
	v_mfma_f32_16x16x32_bf16 v[120:123], v[154:157], v[186:189], v[120:123]
	v_mfma_f32_16x16x32_bf16 v[124:127], v[162:165], v[186:189], v[124:127]
	v_mfma_f32_16x16x32_bf16 v[104:107], v[154:157], v[194:197], v[104:107]
	v_mfma_f32_16x16x32_bf16 v[108:111], v[162:165], v[194:197], v[108:111]
	v_mfma_f32_16x16x32_bf16 v[88:91], v[154:157], v[202:205], v[88:91]
	v_mfma_f32_16x16x32_bf16 v[92:95], v[162:165], v[202:205], v[92:95]
	v_mfma_f32_16x16x32_bf16 v[64:67], v[154:157], v[210:213], v[64:67]
	v_mfma_f32_16x16x32_bf16 v[68:71], v[162:165], v[210:213], v[68:71]
	v_mfma_f32_16x16x32_bf16 v[112:115], v[166:169], v[182:185], v[112:115]
	v_mfma_f32_16x16x32_bf16 v[116:119], v[174:177], v[182:185], v[116:119]
	v_mfma_f32_16x16x32_bf16 v[96:99], v[166:169], v[190:193], v[96:99]
	v_mfma_f32_16x16x32_bf16 v[100:103], v[174:177], v[190:193], v[100:103]
	v_mfma_f32_16x16x32_bf16 v[80:83], v[166:169], v[198:201], v[80:83]
	v_mfma_f32_16x16x32_bf16 v[84:87], v[174:177], v[198:201], v[84:87]
	v_mfma_f32_16x16x32_bf16 v[48:51], v[166:169], v[206:209], v[48:51]
	v_mfma_f32_16x16x32_bf16 v[52:55], v[174:177], v[206:209], v[52:55]
	v_mfma_f32_16x16x32_bf16 v[112:115], v[170:173], v[186:189], v[112:115]
	v_mfma_f32_16x16x32_bf16 v[116:119], v[178:181], v[186:189], v[116:119]
	v_mfma_f32_16x16x32_bf16 v[96:99], v[170:173], v[194:197], v[96:99]
	v_mfma_f32_16x16x32_bf16 v[100:103], v[178:181], v[194:197], v[100:103]
	v_mfma_f32_16x16x32_bf16 v[80:83], v[170:173], v[202:205], v[80:83]
	v_mfma_f32_16x16x32_bf16 v[84:87], v[178:181], v[202:205], v[84:87]
	v_mfma_f32_16x16x32_bf16 v[48:51], v[170:173], v[210:213], v[48:51]
	v_mfma_f32_16x16x32_bf16 v[52:55], v[178:181], v[210:213], v[52:55]
	s_barrier
	s_mov_b32 m0, s56
	v_lshl_add_u64 v[214:215], s[78:79], 0, v[128:129]
	s_add_u32 s90, s78, 0x80000
	ds_read_b128 v[182:185], v147 offset:16384
	ds_read_b128 v[186:189], v147 offset:17408
	ds_read_b128 v[190:193], v147 offset:18432
	ds_read_b128 v[194:197], v147 offset:19456
	ds_read_b128 v[198:201], v147 offset:20480
	ds_read_b128 v[202:205], v147 offset:21504
	ds_read_b128 v[206:209], v147 offset:22528
	ds_read_b128 v[210:213], v147 offset:23552
	global_load_lds_dwordx4 v128, s[78:79]
	v_lshl_add_u64 v[216:217], s[78:79], 0, v[130:131]
	s_mov_b32 m0, s57
	s_addc_u32 s91, s79, 0
	global_load_lds_dwordx4 v130, s[78:79]
	v_lshl_add_u64 v[218:219], s[90:91], 0, v[128:129]
	s_mov_b32 m0, s58
	v_lshl_add_u64 v[220:221], s[80:81], 0, v[132:133]
	global_load_lds_dwordx4 v128, s[90:91]
	v_lshl_add_u64 v[218:219], s[90:91], 0, v[130:131]
	s_mov_b32 m0, s59
	s_nop 0
	global_load_lds_dwordx4 v130, s[90:91]
	v_lshl_add_u64 v[218:219], s[80:81], 0, v[134:135]
	s_mov_b32 m0, s22
	s_nop 0
	global_load_lds_dwordx4 v134, s[80:81]
	s_mov_b32 m0, s23
	s_nop 0
	global_load_lds_dwordx4 v132, s[80:81]
	s_waitcnt vmcnt(8) lgkmcnt(0)
	s_barrier
	v_mfma_f32_16x16x32_bf16 v[72:75], v[150:153], v[182:185], v[72:75]
	v_mfma_f32_16x16x32_bf16 v[76:79], v[158:161], v[182:185], v[76:79]
	v_mfma_f32_16x16x32_bf16 v[40:43], v[150:153], v[190:193], v[40:43]
	v_mfma_f32_16x16x32_bf16 v[44:47], v[158:161], v[190:193], v[44:47]
	v_mfma_f32_16x16x32_bf16 v[24:27], v[150:153], v[198:201], v[24:27]
	v_mfma_f32_16x16x32_bf16 v[28:31], v[158:161], v[198:201], v[28:31]
	v_mfma_f32_16x16x32_bf16 v[8:11], v[150:153], v[206:209], v[8:11]
	v_mfma_f32_16x16x32_bf16 v[12:15], v[158:161], v[206:209], v[12:15]
	v_mfma_f32_16x16x32_bf16 v[72:75], v[154:157], v[186:189], v[72:75]
	v_mfma_f32_16x16x32_bf16 v[76:79], v[162:165], v[186:189], v[76:79]
	v_mfma_f32_16x16x32_bf16 v[40:43], v[154:157], v[194:197], v[40:43]
	v_mfma_f32_16x16x32_bf16 v[44:47], v[162:165], v[194:197], v[44:47]
	v_mfma_f32_16x16x32_bf16 v[24:27], v[154:157], v[202:205], v[24:27]
	v_mfma_f32_16x16x32_bf16 v[28:31], v[162:165], v[202:205], v[28:31]
	v_mfma_f32_16x16x32_bf16 v[8:11], v[154:157], v[210:213], v[8:11]
	v_mfma_f32_16x16x32_bf16 v[12:15], v[162:165], v[210:213], v[12:15]
	v_mfma_f32_16x16x32_bf16 v[56:59], v[166:169], v[182:185], v[56:59]
	v_mfma_f32_16x16x32_bf16 v[60:63], v[174:177], v[182:185], v[60:63]
	v_mfma_f32_16x16x32_bf16 v[32:35], v[166:169], v[190:193], v[32:35]
	v_mfma_f32_16x16x32_bf16 v[36:39], v[174:177], v[190:193], v[36:39]
	v_mfma_f32_16x16x32_bf16 v[16:19], v[166:169], v[198:201], v[16:19]
	v_mfma_f32_16x16x32_bf16 v[20:23], v[174:177], v[198:201], v[20:23]
	v_mfma_f32_16x16x32_bf16 v[0:3], v[166:169], v[206:209], v[0:3]
	v_mfma_f32_16x16x32_bf16 v[4:7], v[174:177], v[206:209], v[4:7]
	v_mfma_f32_16x16x32_bf16 v[56:59], v[170:173], v[186:189], v[56:59]
	v_mfma_f32_16x16x32_bf16 v[60:63], v[178:181], v[186:189], v[60:63]
	v_mfma_f32_16x16x32_bf16 v[32:35], v[170:173], v[194:197], v[32:35]
	v_mfma_f32_16x16x32_bf16 v[36:39], v[178:181], v[194:197], v[36:39]
	v_mfma_f32_16x16x32_bf16 v[16:19], v[170:173], v[202:205], v[16:19]
	v_mfma_f32_16x16x32_bf16 v[20:23], v[178:181], v[202:205], v[20:23]
	v_mfma_f32_16x16x32_bf16 v[0:3], v[170:173], v[210:213], v[0:3]
	v_mfma_f32_16x16x32_bf16 v[4:7], v[178:181], v[210:213], v[4:7]
	s_barrier
; #define PG8_MMA(ai, bj, At, Bt) do { __builtin_amdgcn_s_setprio(1); _Pragma("unroll") for (int m = 0; m < 4; ++m) _Pragma("unroll") for (int n = 0; n < 2; ++n) _Pragma("unroll") for (int k = 0; k < 2; ++k) \
;         acc[ai][bj][m][n] = __builtin_amdgcn_mfma_f32_16x16x32_bf16(Bt[n][k], At[m][k], acc[ai][bj][m][n], 0, 0, 0); __builtin_amdgcn_s_setprio(0); } while (0)
; template <class Epi, class Sched, bool ALIGN_EPI = false, bool SP2 = false, bool A_TILED = false>
; __device__ __forceinline__ void gemm_phase(PG8_LAS unsigned char* lds, const Gemm g, const Sched& S, const Epi& E, const int wave_s) {
;     ...
;         for (int t = PEEL ? 2 : 0; t < nt; t += 2) {
;             const bool last = (t == nt - 2);
;             const char* a1 = cA + (size_t)(t + 1) * kstepA;
;             const char* a2 = last ? nA : cA + (size_t)(t + 2) * kstepA; const char* b2 = last ? nB : cB + (size_t)(t + 2) * kstep;
;             const char* a3 = a2 + kstepA; const char* b3 = b2 + kstep;
;             if (last && has_next) S.a_ready(nxt);
;             if constexpr (SP2) {
;             PG8_ITER(PG8_MMA)
	ds_read_b128 v[150:153], v148
	ds_read_b128 v[154:157], v148 offset:1024
	ds_read_b128 v[158:161], v148 offset:2048
	ds_read_b128 v[162:165], v148 offset:3072
	ds_read_b128 v[166:169], v149
	ds_read_b128 v[170:173], v149 offset:1024
	ds_read_b128 v[174:177], v149 offset:2048
	ds_read_b128 v[178:181], v149 offset:3072
	s_add_u32 s80, s80, 0x80000
	s_addc_u32 s81, s81, 0
	s_mov_b32 m0, s36
	v_lshl_add_u64 v[222:223], s[80:81], 0, v[134:135]
	ds_read_b128 v[182:185], v147 offset:32768
	ds_read_b128 v[186:189], v147 offset:33792
	ds_read_b128 v[190:193], v147 offset:34816
	ds_read_b128 v[194:197], v147 offset:35840
	ds_read_b128 v[198:201], v147 offset:36864
	ds_read_b128 v[202:205], v147 offset:37888
	ds_read_b128 v[206:209], v147 offset:38912
	ds_read_b128 v[210:213], v147 offset:39936
	global_load_lds_dwordx4 v134, s[80:81]
	v_lshl_add_u64 v[222:223], s[80:81], 0, v[132:133]
	s_mov_b32 m0, s37
	s_nop 0
	global_load_lds_dwordx4 v132, s[80:81]
	s_waitcnt vmcnt(8) lgkmcnt(0)
	s_barrier
	v_mfma_f32_16x16x32_bf16 v[120:123], v[150:153], v[182:185], v[120:123]
	v_mfma_f32_16x16x32_bf16 v[124:127], v[158:161], v[182:185], v[124:127]
	v_mfma_f32_16x16x32_bf16 v[104:107], v[150:153], v[190:193], v[104:107]
	v_mfma_f32_16x16x32_bf16 v[108:111], v[158:161], v[190:193], v[108:111]
	v_mfma_f32_16x16x32_bf16 v[88:91], v[150:153], v[198:201], v[88:91]
	v_mfma_f32_16x16x32_bf16 v[92:95], v[158:161], v[198:201], v[92:95]
	v_mfma_f32_16x16x32_bf16 v[64:67], v[150:153], v[206:209], v[64:67]
	v_mfma_f32_16x16x32_bf16 v[68:71], v[158:161], v[206:209], v[68:71]
	v_mfma_f32_16x16x32_bf16 v[120:123], v[154:157], v[186:189], v[120:123]
	v_mfma_f32_16x16x32_bf16 v[124:127], v[162:165], v[186:189], v[124:127]
	v_mfma_f32_16x16x32_bf16 v[104:107], v[154:157], v[194:197], v[104:107]
	v_mfma_f32_16x16x32_bf16 v[108:111], v[162:165], v[194:197], v[108:111]
	v_mfma_f32_16x16x32_bf16 v[88:91], v[154:157], v[202:205], v[88:91]
	v_mfma_f32_16x16x32_bf16 v[92:95], v[162:165], v[202:205], v[92:95]
	v_mfma_f32_16x16x32_bf16 v[64:67], v[154:157], v[210:213], v[64:67]
	v_mfma_f32_16x16x32_bf16 v[68:71], v[162:165], v[210:213], v[68:71]
	v_mfma_f32_16x16x32_bf16 v[112:115], v[166:169], v[182:185], v[112:115]
	v_mfma_f32_16x16x32_bf16 v[116:119], v[174:177], v[182:185], v[116:119]
	v_mfma_f32_16x16x32_bf16 v[96:99], v[166:169], v[190:193], v[96:99]
	v_mfma_f32_16x16x32_bf16 v[100:103], v[174:177], v[190:193], v[100:103]
	v_mfma_f32_16x16x32_bf16 v[80:83], v[166:169], v[198:201], v[80:83]
	v_mfma_f32_16x16x32_bf16 v[84:87], v[174:177], v[198:201], v[84:87]
	v_mfma_f32_16x16x32_bf16 v[48:51], v[166:169], v[206:209], v[48:51]
	v_mfma_f32_16x16x32_bf16 v[52:55], v[174:177], v[206:209], v[52:55]
	v_mfma_f32_16x16x32_bf16 v[112:115], v[170:173], v[186:189], v[112:115]
	v_mfma_f32_16x16x32_bf16 v[116:119], v[178:181], v[186:189], v[116:119]
	v_mfma_f32_16x16x32_bf16 v[96:99], v[170:173], v[194:197], v[96:99]
	v_mfma_f32_16x16x32_bf16 v[100:103], v[178:181], v[194:197], v[100:103]
	v_mfma_f32_16x16x32_bf16 v[80:83], v[170:173], v[202:205], v[80:83]
	v_mfma_f32_16x16x32_bf16 v[84:87], v[178:181], v[202:205], v[84:87]
	v_mfma_f32_16x16x32_bf16 v[48:51], v[170:173], v[210:213], v[48:51]
	v_mfma_f32_16x16x32_bf16 v[52:55], v[178:181], v[210:213], v[52:55]
	s_barrier
	s_mov_b32 m0, s67
	v_lshl_add_u64 v[214:215], v[214:215], 0, s[12:13]
	s_add_u32 s78, s78, 0x80080
	ds_read_b128 v[182:185], v147 offset:49152
	ds_read_b128 v[186:189], v147 offset:50176
	ds_read_b128 v[190:193], v147 offset:51200
	ds_read_b128 v[194:197], v147 offset:52224
	ds_read_b128 v[198:201], v147 offset:53248
	ds_read_b128 v[202:205], v147 offset:54272
	ds_read_b128 v[206:209], v147 offset:55296
	ds_read_b128 v[210:213], v147 offset:56320
	global_load_lds_dwordx4 v[214:215], off
	v_lshl_add_u64 v[214:215], v[216:217], 0, s[12:13]
	s_mov_b32 m0, s69
	s_addc_u32 s79, s79, 0
	global_load_lds_dwordx4 v[214:215], off
	v_lshl_add_u64 v[214:215], s[78:79], 0, v[128:129]
	s_mov_b32 m0, s75
	s_nop 0
	global_load_lds_dwordx4 v128, s[78:79]
	v_lshl_add_u64 v[214:215], s[78:79], 0, v[130:131]
	s_mov_b32 m0, s82
	s_nop 0
	global_load_lds_dwordx4 v130, s[78:79]
	v_lshl_add_u64 v[214:215], v[218:219], 0, s[12:13]
	s_mov_b32 m0, s43
	s_nop 0
	global_load_lds_dwordx4 v[214:215], off
	v_lshl_add_u64 v[214:215], v[220:221], 0, s[12:13]
	s_mov_b32 m0, s44
	s_nop 0
	global_load_lds_dwordx4 v[214:215], off
	s_waitcnt vmcnt(8) lgkmcnt(0)
	s_barrier
	v_mfma_f32_16x16x32_bf16 v[72:75], v[150:153], v[182:185], v[72:75]
	v_mfma_f32_16x16x32_bf16 v[76:79], v[158:161], v[182:185], v[76:79]
	v_mfma_f32_16x16x32_bf16 v[40:43], v[150:153], v[190:193], v[40:43]
	v_mfma_f32_16x16x32_bf16 v[44:47], v[158:161], v[190:193], v[44:47]
	v_mfma_f32_16x16x32_bf16 v[24:27], v[150:153], v[198:201], v[24:27]
	v_mfma_f32_16x16x32_bf16 v[28:31], v[158:161], v[198:201], v[28:31]
	v_mfma_f32_16x16x32_bf16 v[8:11], v[150:153], v[206:209], v[8:11]
	v_mfma_f32_16x16x32_bf16 v[12:15], v[158:161], v[206:209], v[12:15]
	v_mfma_f32_16x16x32_bf16 v[72:75], v[154:157], v[186:189], v[72:75]
	v_mfma_f32_16x16x32_bf16 v[76:79], v[162:165], v[186:189], v[76:79]
	v_mfma_f32_16x16x32_bf16 v[40:43], v[154:157], v[194:197], v[40:43]
	v_mfma_f32_16x16x32_bf16 v[44:47], v[162:165], v[194:197], v[44:47]
	v_mfma_f32_16x16x32_bf16 v[24:27], v[154:157], v[202:205], v[24:27]
	v_mfma_f32_16x16x32_bf16 v[28:31], v[162:165], v[202:205], v[28:31]
	v_mfma_f32_16x16x32_bf16 v[8:11], v[154:157], v[210:213], v[8:11]
	v_mfma_f32_16x16x32_bf16 v[12:15], v[162:165], v[210:213], v[12:15]
	v_mfma_f32_16x16x32_bf16 v[56:59], v[166:169], v[182:185], v[56:59]
	v_mfma_f32_16x16x32_bf16 v[60:63], v[174:177], v[182:185], v[60:63]
	v_mfma_f32_16x16x32_bf16 v[32:35], v[166:169], v[190:193], v[32:35]
	v_mfma_f32_16x16x32_bf16 v[36:39], v[174:177], v[190:193], v[36:39]
	v_mfma_f32_16x16x32_bf16 v[16:19], v[166:169], v[198:201], v[16:19]
	v_mfma_f32_16x16x32_bf16 v[20:23], v[174:177], v[198:201], v[20:23]
	v_mfma_f32_16x16x32_bf16 v[0:3], v[166:169], v[206:209], v[0:3]
	v_mfma_f32_16x16x32_bf16 v[4:7], v[174:177], v[206:209], v[4:7]
	v_mfma_f32_16x16x32_bf16 v[56:59], v[170:173], v[186:189], v[56:59]
	v_mfma_f32_16x16x32_bf16 v[60:63], v[178:181], v[186:189], v[60:63]
	v_mfma_f32_16x16x32_bf16 v[32:35], v[170:173], v[194:197], v[32:35]
	v_mfma_f32_16x16x32_bf16 v[36:39], v[178:181], v[194:197], v[36:39]
	v_mfma_f32_16x16x32_bf16 v[16:19], v[170:173], v[202:205], v[16:19]
	v_mfma_f32_16x16x32_bf16 v[20:23], v[178:181], v[202:205], v[20:23]
	v_mfma_f32_16x16x32_bf16 v[0:3], v[170:173], v[210:213], v[0:3]
	v_mfma_f32_16x16x32_bf16 v[4:7], v[178:181], v[210:213], v[4:7]
	s_barrier
	s_add_i32 s88, s88, 2
	s_add_u32 s83, s83, 0x100
	s_addc_u32 s85, s85, 0
	s_add_u32 s76, s76, 0x100
	s_addc_u32 s77, s77, 0
	s_cmp_gt_u32 s88, 29
	s_cbranch_scc0 .LBB0_1953
	s_and_b64 vcc, exec, s[60:61]
	s_cbranch_vccz .LBB0_1956
	s_barrier

; __device__ __forceinline__ int tid_now(int wave_s) { unsigned z = 0u; asm volatile("" : "+v"(z)); return (wave_s << 6) | (int)__builtin_amdgcn_mbcnt_hi(~0u, __builtin_amdgcn_mbcnt_lo(~0u, z)); }
; __device__ __forceinline__ unsigned xb_ld(unsigned* p)              { return __hip_atomic_load(p, __ATOMIC_RELAXED, __HIP_MEMORY_SCOPE_AGENT); }
; __device__ __forceinline__ unsigned xb_add(unsigned* p, unsigned v) { return __hip_atomic_fetch_add(p, v, __ATOMIC_RELAXED, __HIP_MEMORY_SCOPE_AGENT); }
; #define XB_SPIN(cond, bar) do { unsigned _sp = 0; while (cond) { __builtin_amdgcn_s_sleep(1); \
;     if ((++_sp & 255u) == 0u) { if (xb_ld(&(bar)[XB_TMO])) break; if (_sp > XB_SPIN_CAP) { atomicAdd(&(bar)[XB_TMO], 1u); break; } } } } while (0)
; __device__ __forceinline__ void xcd_barrier(const XcdBarrier& b) {
;     asm volatile("s_waitcnt vmcnt(0)" ::: "memory");
;     __syncthreads();
;     if (tid_now(b.w) == 0) {
;         unsigned* bar = b.bar;
;         __builtin_amdgcn_s_waitcnt(0);
;         unsigned nloc = b.st[0], nx = b.st[1];
;         if (nloc == 0u) { xcd_barrier_complete(bar, b.x, nloc, nx, b.np); b.st[0] = nloc; b.st[1] = nx; }
;         const unsigned old = xb_add(&bar[XB_XSUB(b.x)], 1u);
;         const unsigned gen = old / nloc;
;         if (old + 1u == (gen + 1u) * nloc) {
;             __builtin_amdgcn_fence(__ATOMIC_RELEASE, "agent");
;             asm volatile("s_waitcnt vmcnt(0)" ::: "memory");
;             const unsigned og = xb_add(&bar[XB_TOP], 1u);
;             const unsigned tg = og / nx;
;             if (og + 1u == (tg + 1u) * nx) xb_add(&bar[XB_TOPGEN], 1u);
;             else XB_SPIN(xb_ld(&bar[XB_TOPGEN]) == tg, bar);
;             __builtin_amdgcn_fence(__ATOMIC_ACQUIRE, "agent");
;             xb_add(&bar[XB_XGEN(b.x)], 1u);
;             asm volatile("s_waitcnt vmcnt(0)" ::: "memory");
;         } else {
;             XB_SPIN(xb_ld(&bar[XB_XGEN(b.x)]) == gen, bar);
;             __builtin_amdgcn_fence(__ATOMIC_ACQUIRE, "agent");
;             asm volatile("s_waitcnt vmcnt(0)" ::: "memory");
;         }
;     }
;     __syncthreads();
; }
.LBB0_1960:
	s_setprio 0
	s_cmp_gt_i32 s35, 12
	s_cselect_b64 s[2:3], -1, 0
	s_and_b64 s[0:1], s[4:5], s[2:3]
	s_andn2_b64 vcc, exec, s[0:1]
	s_cbranch_vccnz .LBB0_2014
	s_waitcnt vmcnt(0)
	v_mov_b32_e32 v0, 0
	s_waitcnt vmcnt(0)
	s_waitcnt lgkmcnt(0)
	s_barrier
	s_nop 0
	v_mbcnt_lo_u32_b32 v0, -1, v0
	v_mbcnt_hi_u32_b32 v0, -1, v0
	v_or_b32_e32 v0, s33, v0
	v_cmp_eq_u32_e32 vcc, 0, v0
	s_and_saveexec_b64 s[4:5], vcc
	s_cbranch_execz .LBB0_2013
	s_add_i32 s0, 0, 0x27f68
	v_mov_b32_e32 v0, s0
	s_waitcnt vmcnt(0) expcnt(0) lgkmcnt(0)
	ds_read_b32 v2, v0
	s_add_i32 s0, 0, 0x27f6c
	v_mov_b32_e32 v0, s0
	ds_read_b32 v0, v0
	s_waitcnt lgkmcnt(1)
	v_cmp_ne_u32_e32 vcc, 0, v2
	s_cbranch_vccnz .LBB0_1977
	s_add_u32 s6, s10, 0x1000
	s_addc_u32 s7, s11, 0
	s_add_u32 s12, s10, 0x1100
	s_addc_u32 s13, s11, 0
	s_add_u32 s60, s10, 0x1200
	s_addc_u32 s61, s11, 0
	s_add_u32 s62, s10, 0x1300
	s_addc_u32 s63, s11, 0
	s_mov_b32 s0, 1
	v_mov_b32_e32 v16, 0
	s_branch .LBB0_1965

; #define PG8_STAGE(bufoff, gbase, voff) do { _Pragma("unroll") for (int _i = 0; _i < 2; ++_i) \
;         __builtin_amdgcn_global_load_lds((const unsigned*)((const char*)(gbase) + (voff)[_i]), (PG8_LAS unsigned*)(lds + (bufoff) + ldsw + _i * 8192), 16, 0, 0); } while (0)
; #define PG8_WAIT_V(n) asm volatile("s_waitcnt vmcnt(" #n ")" ::: "memory")
; #define PG8_BAR __builtin_amdgcn_s_barrier()
; template <class Epi, class Sched, bool ALIGN_EPI = false, bool SP2 = false, bool A_TILED = false>
; __device__ __forceinline__ void gemm_phase(PG8_LAS unsigned char* lds, const Gemm g, const Sched& S, const Epi& E, const int wave_s) {
;     ...
;     const int tid = tid_, wid = __builtin_amdgcn_readfirstlane(tid >> 6), lane = tid & 63, wr = wid >> 2, wc = wid & 3, fr = lane & 15, fq = lane >> 4;
;     const int K = g.K, nt = K / BK;
;     unsigned voffA[2], voffB[2];
; #pragma unroll
;     for (int i = 0; i < 2; ++i) { int R, C; stage_rc(tid * 16 + i * 8192, R, C); const int Rb = Epi::PERM ? ((R & ~31) + perm32(R & 31)) : R;
;         voffA[i] = A_TILED ? (unsigned)(tid * 16 + i * 8192) : (unsigned)(R * K + C) * 2u; voffB[i] = (unsigned)(Rb * K + C) * 2u; }
;     const size_t kstep = (size_t)(BK * 2);
;     const size_t hstep = (size_t)HALF * K * 2;
;     const size_t tstep = 2 * hstep;
;     const size_t kstepA = A_TILED ? (size_t)32768 : kstep, hstepA = A_TILED ? (size_t)16384 : hstep, tstepA = A_TILED ? (size_t)nt * 32768 : tstep;
;     const unsigned ldsw = (unsigned)wid * 1024u;
;     const int aoff = lds_byte(wr * 64 + fr, fq * 8), boff = lds_byte(wc * 32 + fr, fq * 8);
;     ...
;     if constexpr (SP2) {
;         PG8_STAGE(PG8_SB(0, 0), cB, voffB); PG8_STAGE(PG8_SB(0, 1), cB + hstep, voffB); PG8_STAGE(PG8_SA(0, 0), cA, voffA); PG8_STAGE(PG8_SA(0, 1), cA + hstepA, voffA);
;         if (wr == 1) PG8_BAR;
;         PG8_WAIT_V(2); PG8_BAR;
;         PG8_STAGE(PG8_SB(1, 0), cB + kstep, voffB); PG8_STAGE(PG8_SA(1, 0), cA + kstepA, voffA); PG8_STAGE(PG8_SB(1, 1), cB + hstep + kstep, voffB);
;         PG8_WAIT_V(6); PG8_BAR;
.LBB0_2025:
	v_and_b32_e32 v5, 48, v4
	v_lshlrev_b32_e32 v6, 6, v4
	s_movk_i32 s36, 0x3c0
	v_lshlrev_b32_e32 v4, 2, v4
	s_mov_b64 s[64:65], 0x80
	s_and_b32 s9, s1, 3
	s_lshl_b32 s8, s23, 6
	s_lshl_b32 s23, s23, 13
	v_and_or_b32 v5, v6, s36, v5
	v_and_b32_e32 v4, 32, v4
	s_add_i32 m0, s14, 0x18000
	v_lshl_add_u64 v[2:3], v[2:3], 0, s[64:65]
	v_bitop3_b32 v6, v5, s23, v4 bitop3:0xde
	s_lshl_b32 s23, s9, 12
	s_waitcnt vmcnt(2)
	s_barrier
	global_load_lds_dwordx4 v[2:3], off
	s_add_i32 m0, s14, 0x1a000
	s_add_u32 s36, s6, 0x8000
	v_bitop3_b32 v4, v5, s23, v4 bitop3:0xde
	v_lshl_add_u64 v[0:1], v[0:1], 0, s[64:65]
	s_addc_u32 s37, s7, 0
	s_add_i32 s23, s14, 0x8000
	global_load_lds_dwordx4 v[0:1], off
	v_lshl_add_u64 v[0:1], s[36:37], 0, v[32:33]
	s_mov_b32 m0, s23
	s_mov_b64 s[40:41], 0x3460c000
	global_load_lds_dwordx4 v32, s[36:37]
	v_lshl_add_u64 v[0:1], s[36:37], 0, v[132:133]
	s_add_i32 s36, s14, 0xa000
	s_add_u32 s38, s2, 0x200080
	s_mov_b32 m0, s36
	s_addc_u32 s39, s3, 0
	global_load_lds_dwordx4 v[0:1], off
	s_add_i32 m0, s14, 0x1c000
	v_lshl_add_u64 v[0:1], s[38:39], 0, v[34:35]
	global_load_lds_dwordx4 v34, s[38:39]
	v_lshl_add_u64 v[0:1], s[38:39], 0, v[134:135]
	s_add_i32 m0, s14, 0x1e000
	s_add_u32 s37, s68, 0x14600100
	global_load_lds_dwordx4 v134, s[38:39]
	s_addc_u32 s38, s69, 0
	v_lshl_add_u64 v[0:1], s[66:67], 0, v[132:133]
	v_lshl_add_u64 v[136:137], v[0:1], 0, s[40:41]
	v_lshl_add_u64 v[0:1], s[66:67], 0, v[32:33]
	s_add_u32 s39, s66, 0x34610000
	s_waitcnt vmcnt(6)
	v_lshl_add_u64 v[138:139], v[0:1], 0, s[40:41]
	s_addc_u32 s40, s67, 0
	s_bitcmp1_b32 s33, 8
	s_cbranch_scc1 .Lsp_8
	s_setprio 1

; #define PG8_MMA(ai, bj, At, Bt) do { __builtin_amdgcn_s_setprio(1); _Pragma("unroll") for (int m = 0; m < 4; ++m) _Pragma("unroll") for (int n = 0; n < 2; ++n) _Pragma("unroll") for (int k = 0; k < 2; ++k) \
;         acc[ai][bj][m][n] = __builtin_amdgcn_mfma_f32_16x16x32_bf16(Bt[n][k], At[m][k], acc[ai][bj][m][n], 0, 0, 0); __builtin_amdgcn_s_setprio(0); } while (0)
; template <class Epi, class Sched, bool ALIGN_EPI = false, bool SP2 = false, bool A_TILED = false>
; __device__ __forceinline__ void gemm_phase(PG8_LAS unsigned char* lds, const Gemm g, const Sched& S, const Epi& E, const int wave_s) {
;     ...
;         for (int t = PEEL ? 2 : 0; t < nt; t += 2) {
;             const bool last = (t == nt - 2);
;             const char* a1 = cA + (size_t)(t + 1) * kstepA;
;             const char* a2 = last ? nA : cA + (size_t)(t + 2) * kstepA; const char* b2 = last ? nB : cB + (size_t)(t + 2) * kstep;
;             const char* a3 = a2 + kstepA; const char* b3 = b2 + kstep;
;             if (last && has_next) S.a_ready(nxt);
;             if constexpr (SP2) {
;             PG8_ITER(PG8_MMA)
.LBB0_2026:
	ds_read_b128 v[146:149], v140
	ds_read_b128 v[150:153], v140 offset:1024
	ds_read_b128 v[154:157], v140 offset:2048
	ds_read_b128 v[158:161], v140 offset:3072
	ds_read_b128 v[162:165], v141
	ds_read_b128 v[166:169], v141 offset:1024
	ds_read_b128 v[170:173], v141 offset:2048
	ds_read_b128 v[174:177], v141 offset:3072
	s_add_u32 s52, s60, s39
	s_addc_u32 s53, s61, s40
	s_add_u32 s54, s60, s37
	s_addc_u32 s55, s61, s38
	s_cmpk_eq_i32 s41, 0x7c
	s_cselect_b32 s72, s6, s52
	s_cselect_b32 s73, s7, s53
	s_cselect_b32 s70, s2, s54
	s_cselect_b32 s71, s3, s55
	s_add_u32 s68, s72, 0x8000
	s_addc_u32 s69, s73, 0
	s_mov_b32 m0, s42
	v_lshl_add_u64 v[210:211], s[60:61], 0, v[138:139]
	ds_read_b128 v[178:181], v142
	ds_read_b128 v[182:185], v142 offset:1024
	ds_read_b128 v[186:189], v142 offset:2048
	ds_read_b128 v[190:193], v142 offset:3072
	ds_read_b128 v[194:197], v142 offset:4096
	ds_read_b128 v[198:201], v142 offset:5120
	ds_read_b128 v[202:205], v142 offset:6144
	ds_read_b128 v[206:209], v142 offset:7168
	global_load_lds_dwordx4 v[210:211], off
	v_lshl_add_u64 v[210:211], s[60:61], 0, v[136:137]
	s_mov_b32 m0, s43
	s_nop 0
	global_load_lds_dwordx4 v[210:211], off
	s_waitcnt vmcnt(8) lgkmcnt(0)
	s_barrier
	v_mfma_f32_16x16x32_bf16 v[8:11], v[146:149], v[178:181], v[8:11]
	v_mfma_f32_16x16x32_bf16 v[12:15], v[154:157], v[178:181], v[12:15]
	v_mfma_f32_16x16x32_bf16 v[60:63], v[146:149], v[186:189], v[60:63]
	v_mfma_f32_16x16x32_bf16 v[20:23], v[154:157], v[186:189], v[20:23]
	v_mfma_f32_16x16x32_bf16 v[76:79], v[146:149], v[194:197], v[76:79]
	v_mfma_f32_16x16x32_bf16 v[52:55], v[154:157], v[194:197], v[52:55]
	v_mfma_f32_16x16x32_bf16 v[128:131], v[146:149], v[202:205], v[128:131]
	v_mfma_f32_16x16x32_bf16 v[68:71], v[154:157], v[202:205], v[68:71]
	v_mfma_f32_16x16x32_bf16 v[8:11], v[150:153], v[182:185], v[8:11]
	v_mfma_f32_16x16x32_bf16 v[12:15], v[158:161], v[182:185], v[12:15]
	v_mfma_f32_16x16x32_bf16 v[60:63], v[150:153], v[190:193], v[60:63]
	v_mfma_f32_16x16x32_bf16 v[20:23], v[158:161], v[190:193], v[20:23]
	v_mfma_f32_16x16x32_bf16 v[76:79], v[150:153], v[198:201], v[76:79]
	v_mfma_f32_16x16x32_bf16 v[52:55], v[158:161], v[198:201], v[52:55]
	v_mfma_f32_16x16x32_bf16 v[128:131], v[150:153], v[206:209], v[128:131]
	v_mfma_f32_16x16x32_bf16 v[68:71], v[158:161], v[206:209], v[68:71]
	v_mfma_f32_16x16x32_bf16 v[28:31], v[162:165], v[178:181], v[28:31]
	v_mfma_f32_16x16x32_bf16 v[16:19], v[170:173], v[178:181], v[16:19]
	v_mfma_f32_16x16x32_bf16 v[56:59], v[162:165], v[186:189], v[56:59]
	v_mfma_f32_16x16x32_bf16 v[48:51], v[170:173], v[186:189], v[48:51]
	v_mfma_f32_16x16x32_bf16 v[72:75], v[162:165], v[194:197], v[72:75]
	v_mfma_f32_16x16x32_bf16 v[64:67], v[170:173], v[194:197], v[64:67]
	v_mfma_f32_16x16x32_bf16 v[108:111], v[162:165], v[202:205], v[108:111]
	v_mfma_f32_16x16x32_bf16 v[96:99], v[170:173], v[202:205], v[96:99]
	v_mfma_f32_16x16x32_bf16 v[28:31], v[166:169], v[182:185], v[28:31]
	v_mfma_f32_16x16x32_bf16 v[16:19], v[174:177], v[182:185], v[16:19]
	v_mfma_f32_16x16x32_bf16 v[56:59], v[166:169], v[190:193], v[56:59]
	v_mfma_f32_16x16x32_bf16 v[48:51], v[174:177], v[190:193], v[48:51]
	v_mfma_f32_16x16x32_bf16 v[72:75], v[166:169], v[198:201], v[72:75]
	v_mfma_f32_16x16x32_bf16 v[64:67], v[174:177], v[198:201], v[64:67]
	v_mfma_f32_16x16x32_bf16 v[108:111], v[166:169], v[206:209], v[108:111]
	v_mfma_f32_16x16x32_bf16 v[96:99], v[174:177], v[206:209], v[96:99]
	s_barrier
	s_mov_b32 m0, s44
	v_lshl_add_u64 v[210:211], s[70:71], 0, v[34:35]
	s_add_u32 s52, s70, 0x200000
	ds_read_b128 v[178:181], v142 offset:16384
	ds_read_b128 v[182:185], v142 offset:17408
	ds_read_b128 v[186:189], v142 offset:18432
	ds_read_b128 v[190:193], v142 offset:19456
	ds_read_b128 v[194:197], v142 offset:20480
	ds_read_b128 v[198:201], v142 offset:21504
	ds_read_b128 v[202:205], v142 offset:22528
	ds_read_b128 v[206:209], v142 offset:23552
	global_load_lds_dwordx4 v34, s[70:71]
	v_lshl_add_u64 v[212:213], s[70:71], 0, v[134:135]
	s_mov_b32 m0, s45
	s_addc_u32 s53, s71, 0
	global_load_lds_dwordx4 v134, s[70:71]
	v_lshl_add_u64 v[214:215], s[52:53], 0, v[34:35]
	s_mov_b32 m0, s46
	s_nop 0
	global_load_lds_dwordx4 v34, s[52:53]
	v_lshl_add_u64 v[214:215], s[52:53], 0, v[134:135]
	s_mov_b32 m0, s47
	s_nop 0
	global_load_lds_dwordx4 v134, s[52:53]
	v_lshl_add_u64 v[214:215], s[72:73], 0, v[32:33]
	s_mov_b32 m0, s14
	s_nop 0
	global_load_lds_dwordx4 v32, s[72:73]
	v_lshl_add_u64 v[214:215], s[72:73], 0, v[132:133]
	s_mov_b32 m0, s15
	s_nop 0
	global_load_lds_dwordx4 v132, s[72:73]
	s_waitcnt vmcnt(8) lgkmcnt(0)
	s_barrier
	v_mfma_f32_16x16x32_bf16 v[100:103], v[146:149], v[178:181], v[100:103]
	v_mfma_f32_16x16x32_bf16 v[104:107], v[154:157], v[178:181], v[104:107]
	v_mfma_f32_16x16x32_bf16 v[116:119], v[146:149], v[186:189], v[116:119]
	v_mfma_f32_16x16x32_bf16 v[120:123], v[154:157], v[186:189], v[120:123]
	v_mfma_f32_16x16x32_bf16 v[84:87], v[146:149], v[194:197], v[84:87]
	v_mfma_f32_16x16x32_bf16 v[80:83], v[154:157], v[194:197], v[80:83]
	v_mfma_f32_16x16x32_bf16 v[36:39], v[146:149], v[202:205], v[36:39]
	v_mfma_f32_16x16x32_bf16 v[24:27], v[154:157], v[202:205], v[24:27]
	v_mfma_f32_16x16x32_bf16 v[100:103], v[150:153], v[182:185], v[100:103]
	v_mfma_f32_16x16x32_bf16 v[104:107], v[158:161], v[182:185], v[104:107]
	v_mfma_f32_16x16x32_bf16 v[116:119], v[150:153], v[190:193], v[116:119]
	v_mfma_f32_16x16x32_bf16 v[120:123], v[158:161], v[190:193], v[120:123]
	v_mfma_f32_16x16x32_bf16 v[84:87], v[150:153], v[198:201], v[84:87]
	v_mfma_f32_16x16x32_bf16 v[80:83], v[158:161], v[198:201], v[80:83]
	v_mfma_f32_16x16x32_bf16 v[36:39], v[150:153], v[206:209], v[36:39]
	v_mfma_f32_16x16x32_bf16 v[24:27], v[158:161], v[206:209], v[24:27]
	v_mfma_f32_16x16x32_bf16 v[124:127], v[162:165], v[178:181], v[124:127]
	v_mfma_f32_16x16x32_bf16 v[112:115], v[170:173], v[178:181], v[112:115]
	v_mfma_f32_16x16x32_bf16 v[92:95], v[162:165], v[186:189], v[92:95]
	v_mfma_f32_16x16x32_bf16 v[88:91], v[170:173], v[186:189], v[88:91]
	v_mfma_f32_16x16x32_bf16 v[44:47], v[162:165], v[194:197], v[44:47]
	v_mfma_f32_16x16x32_bf16 v[40:43], v[170:173], v[194:197], v[40:43]
	v_mfma_f32_16x16x32_bf16 v[4:7], v[162:165], v[202:205], v[4:7]
	v_mfma_f32_16x16x32_bf16 v[0:3], v[170:173], v[202:205], v[0:3]
	v_mfma_f32_16x16x32_bf16 v[124:127], v[166:169], v[182:185], v[124:127]
	v_mfma_f32_16x16x32_bf16 v[112:115], v[174:177], v[182:185], v[112:115]
	v_mfma_f32_16x16x32_bf16 v[92:95], v[166:169], v[190:193], v[92:95]
	v_mfma_f32_16x16x32_bf16 v[88:91], v[174:177], v[190:193], v[88:91]
	v_mfma_f32_16x16x32_bf16 v[44:47], v[166:169], v[198:201], v[44:47]
	v_mfma_f32_16x16x32_bf16 v[40:43], v[174:177], v[198:201], v[40:43]
	v_mfma_f32_16x16x32_bf16 v[4:7], v[166:169], v[206:209], v[4:7]
	v_mfma_f32_16x16x32_bf16 v[0:3], v[174:177], v[206:209], v[0:3]
	s_barrier
	ds_read_b128 v[146:149], v143
	ds_read_b128 v[150:153], v143 offset:1024
	ds_read_b128 v[154:157], v143 offset:2048
	ds_read_b128 v[158:161], v143 offset:3072
	ds_read_b128 v[162:165], v144
	ds_read_b128 v[166:169], v144 offset:1024
	ds_read_b128 v[170:173], v144 offset:2048
	ds_read_b128 v[174:177], v144 offset:3072
	s_add_u32 s52, s72, 0x4000
	s_addc_u32 s53, s73, 0
	s_mov_b32 m0, s21
	v_lshl_add_u64 v[214:215], s[52:53], 0, v[32:33]
	ds_read_b128 v[178:181], v142 offset:32768
	ds_read_b128 v[182:185], v142 offset:33792
	ds_read_b128 v[186:189], v142 offset:34816
	ds_read_b128 v[190:193], v142 offset:35840
	ds_read_b128 v[194:197], v142 offset:36864
	ds_read_b128 v[198:201], v142 offset:37888
	ds_read_b128 v[202:205], v142 offset:38912
	ds_read_b128 v[206:209], v142 offset:39936
	global_load_lds_dwordx4 v32, s[52:53]
	v_lshl_add_u64 v[214:215], s[52:53], 0, v[132:133]
	s_mov_b32 m0, s22
	s_nop 0
	global_load_lds_dwordx4 v132, s[52:53]
	s_waitcnt vmcnt(8) lgkmcnt(0)
	s_barrier
	v_mfma_f32_16x16x32_bf16 v[8:11], v[146:149], v[178:181], v[8:11]
	v_mfma_f32_16x16x32_bf16 v[12:15], v[154:157], v[178:181], v[12:15]
	v_mfma_f32_16x16x32_bf16 v[60:63], v[146:149], v[186:189], v[60:63]
	v_mfma_f32_16x16x32_bf16 v[20:23], v[154:157], v[186:189], v[20:23]
	v_mfma_f32_16x16x32_bf16 v[76:79], v[146:149], v[194:197], v[76:79]
	v_mfma_f32_16x16x32_bf16 v[52:55], v[154:157], v[194:197], v[52:55]
	v_mfma_f32_16x16x32_bf16 v[128:131], v[146:149], v[202:205], v[128:131]
	v_mfma_f32_16x16x32_bf16 v[68:71], v[154:157], v[202:205], v[68:71]
	v_mfma_f32_16x16x32_bf16 v[8:11], v[150:153], v[182:185], v[8:11]
	v_mfma_f32_16x16x32_bf16 v[12:15], v[158:161], v[182:185], v[12:15]
	v_mfma_f32_16x16x32_bf16 v[60:63], v[150:153], v[190:193], v[60:63]
	v_mfma_f32_16x16x32_bf16 v[20:23], v[158:161], v[190:193], v[20:23]
	v_mfma_f32_16x16x32_bf16 v[76:79], v[150:153], v[198:201], v[76:79]
	v_mfma_f32_16x16x32_bf16 v[52:55], v[158:161], v[198:201], v[52:55]
	v_mfma_f32_16x16x32_bf16 v[128:131], v[150:153], v[206:209], v[128:131]
	v_mfma_f32_16x16x32_bf16 v[68:71], v[158:161], v[206:209], v[68:71]
	v_mfma_f32_16x16x32_bf16 v[28:31], v[162:165], v[178:181], v[28:31]
	v_mfma_f32_16x16x32_bf16 v[16:19], v[170:173], v[178:181], v[16:19]
	v_mfma_f32_16x16x32_bf16 v[56:59], v[162:165], v[186:189], v[56:59]
	v_mfma_f32_16x16x32_bf16 v[48:51], v[170:173], v[186:189], v[48:51]
	v_mfma_f32_16x16x32_bf16 v[72:75], v[162:165], v[194:197], v[72:75]
	v_mfma_f32_16x16x32_bf16 v[64:67], v[170:173], v[194:197], v[64:67]
	v_mfma_f32_16x16x32_bf16 v[108:111], v[162:165], v[202:205], v[108:111]
	v_mfma_f32_16x16x32_bf16 v[96:99], v[170:173], v[202:205], v[96:99]
	v_mfma_f32_16x16x32_bf16 v[28:31], v[166:169], v[182:185], v[28:31]
	v_mfma_f32_16x16x32_bf16 v[16:19], v[174:177], v[182:185], v[16:19]
	v_mfma_f32_16x16x32_bf16 v[56:59], v[166:169], v[190:193], v[56:59]
	v_mfma_f32_16x16x32_bf16 v[48:51], v[174:177], v[190:193], v[48:51]
	v_mfma_f32_16x16x32_bf16 v[72:75], v[166:169], v[198:201], v[72:75]
	v_mfma_f32_16x16x32_bf16 v[64:67], v[174:177], v[198:201], v[64:67]
	v_mfma_f32_16x16x32_bf16 v[108:111], v[166:169], v[206:209], v[108:111]
	v_mfma_f32_16x16x32_bf16 v[96:99], v[174:177], v[206:209], v[96:99]
	s_barrier
; #define PG8_MMA(ai, bj, At, Bt) do { __builtin_amdgcn_s_setprio(1); _Pragma("unroll") for (int m = 0; m < 4; ++m) _Pragma("unroll") for (int n = 0; n < 2; ++n) _Pragma("unroll") for (int k = 0; k < 2; ++k) \
;         acc[ai][bj][m][n] = __builtin_amdgcn_mfma_f32_16x16x32_bf16(Bt[n][k], At[m][k], acc[ai][bj][m][n], 0, 0, 0); __builtin_amdgcn_s_setprio(0); } while (0)
; template <class Epi, class Sched, bool ALIGN_EPI = false, bool SP2 = false, bool A_TILED = false>
; __device__ __forceinline__ void gemm_phase(PG8_LAS unsigned char* lds, const Gemm g, const Sched& S, const Epi& E, const int wave_s) {
;     ...
;         for (int t = PEEL ? 2 : 0; t < nt; t += 2) {
;             const bool last = (t == nt - 2);
;             const char* a1 = cA + (size_t)(t + 1) * kstepA;
;             const char* a2 = last ? nA : cA + (size_t)(t + 2) * kstepA; const char* b2 = last ? nB : cB + (size_t)(t + 2) * kstep;
;             const char* a3 = a2 + kstepA; const char* b3 = b2 + kstep;
;             if (last && has_next) S.a_ready(nxt);
;             if constexpr (SP2) {
;             PG8_ITER(PG8_MMA)
	s_mov_b32 m0, s48
	v_lshl_add_u64 v[210:211], v[210:211], 0, s[64:65]
	s_add_u32 s52, s70, 0x200080
	ds_read_b128 v[178:181], v142 offset:49152
	ds_read_b128 v[182:185], v142 offset:50176
	ds_read_b128 v[186:189], v142 offset:51200
	ds_read_b128 v[190:193], v142 offset:52224
	ds_read_b128 v[194:197], v142 offset:53248
	ds_read_b128 v[198:201], v142 offset:54272
	ds_read_b128 v[202:205], v142 offset:55296
	ds_read_b128 v[206:209], v142 offset:56320
	global_load_lds_dwordx4 v[210:211], off
	v_lshl_add_u64 v[210:211], v[212:213], 0, s[64:65]
	s_mov_b32 m0, s49
	s_addc_u32 s53, s71, 0
	global_load_lds_dwordx4 v[210:211], off
	v_lshl_add_u64 v[210:211], s[52:53], 0, v[34:35]
	s_mov_b32 m0, s50
	s_nop 0
	global_load_lds_dwordx4 v34, s[52:53]
	v_lshl_add_u64 v[210:211], s[52:53], 0, v[134:135]
	s_mov_b32 m0, s51
	s_nop 0
	global_load_lds_dwordx4 v134, s[52:53]
	v_lshl_add_u64 v[210:211], s[68:69], 0, v[32:33]
	s_mov_b32 m0, s23
	s_nop 0
	global_load_lds_dwordx4 v32, s[68:69]
	v_lshl_add_u64 v[210:211], s[68:69], 0, v[132:133]
	s_mov_b32 m0, s36
	s_nop 0
	global_load_lds_dwordx4 v132, s[68:69]
	s_waitcnt vmcnt(8) lgkmcnt(0)
	s_barrier
	v_mfma_f32_16x16x32_bf16 v[100:103], v[146:149], v[178:181], v[100:103]
	v_mfma_f32_16x16x32_bf16 v[104:107], v[154:157], v[178:181], v[104:107]
	v_mfma_f32_16x16x32_bf16 v[116:119], v[146:149], v[186:189], v[116:119]
	v_mfma_f32_16x16x32_bf16 v[120:123], v[154:157], v[186:189], v[120:123]
	v_mfma_f32_16x16x32_bf16 v[84:87], v[146:149], v[194:197], v[84:87]
	v_mfma_f32_16x16x32_bf16 v[80:83], v[154:157], v[194:197], v[80:83]
	v_mfma_f32_16x16x32_bf16 v[36:39], v[146:149], v[202:205], v[36:39]
	v_mfma_f32_16x16x32_bf16 v[24:27], v[154:157], v[202:205], v[24:27]
	v_mfma_f32_16x16x32_bf16 v[100:103], v[150:153], v[182:185], v[100:103]
	v_mfma_f32_16x16x32_bf16 v[104:107], v[158:161], v[182:185], v[104:107]
	v_mfma_f32_16x16x32_bf16 v[116:119], v[150:153], v[190:193], v[116:119]
	v_mfma_f32_16x16x32_bf16 v[120:123], v[158:161], v[190:193], v[120:123]
	v_mfma_f32_16x16x32_bf16 v[84:87], v[150:153], v[198:201], v[84:87]
	v_mfma_f32_16x16x32_bf16 v[80:83], v[158:161], v[198:201], v[80:83]
	v_mfma_f32_16x16x32_bf16 v[36:39], v[150:153], v[206:209], v[36:39]
	v_mfma_f32_16x16x32_bf16 v[24:27], v[158:161], v[206:209], v[24:27]
	v_mfma_f32_16x16x32_bf16 v[124:127], v[162:165], v[178:181], v[124:127]
	v_mfma_f32_16x16x32_bf16 v[112:115], v[170:173], v[178:181], v[112:115]
	v_mfma_f32_16x16x32_bf16 v[92:95], v[162:165], v[186:189], v[92:95]
	v_mfma_f32_16x16x32_bf16 v[88:91], v[170:173], v[186:189], v[88:91]
	v_mfma_f32_16x16x32_bf16 v[44:47], v[162:165], v[194:197], v[44:47]
	v_mfma_f32_16x16x32_bf16 v[40:43], v[170:173], v[194:197], v[40:43]
	v_mfma_f32_16x16x32_bf16 v[4:7], v[162:165], v[202:205], v[4:7]
	v_mfma_f32_16x16x32_bf16 v[0:3], v[170:173], v[202:205], v[0:3]
	v_mfma_f32_16x16x32_bf16 v[124:127], v[166:169], v[182:185], v[124:127]
	v_mfma_f32_16x16x32_bf16 v[112:115], v[174:177], v[182:185], v[112:115]
	v_mfma_f32_16x16x32_bf16 v[92:95], v[166:169], v[190:193], v[92:95]
	v_mfma_f32_16x16x32_bf16 v[88:91], v[174:177], v[190:193], v[88:91]
	v_mfma_f32_16x16x32_bf16 v[44:47], v[166:169], v[198:201], v[44:47]
	v_mfma_f32_16x16x32_bf16 v[40:43], v[174:177], v[198:201], v[40:43]
	v_mfma_f32_16x16x32_bf16 v[4:7], v[166:169], v[206:209], v[4:7]
	v_mfma_f32_16x16x32_bf16 v[0:3], v[174:177], v[206:209], v[0:3]
	s_barrier
	s_add_i32 s41, s41, 2
	s_add_u32 s37, s37, 0x100
	s_addc_u32 s38, s38, 0
	s_add_u32 s39, s39, 0x10000
	s_addc_u32 s40, s40, 0
	v_lshl_add_u64 v[136:137], v[136:137], 0, s[66:67]
	s_cmpk_gt_u32 s41, 0x7d
	v_lshl_add_u64 v[138:139], v[138:139], 0, s[66:67]
	s_cbranch_scc0 .LBB0_2026
	s_waitcnt vmcnt(0)
	s_cmpk_lt_u32 s0, 0x100
	s_cbranch_scc0 .LBB0_2029
	s_barrier

; __device__ __forceinline__ int tid_now(int wave_s) { unsigned z = 0u; asm volatile("" : "+v"(z)); return (wave_s << 6) | (int)__builtin_amdgcn_mbcnt_hi(~0u, __builtin_amdgcn_mbcnt_lo(~0u, z)); }
; __device__ __forceinline__ unsigned xb_ld(unsigned* p)              { return __hip_atomic_load(p, __ATOMIC_RELAXED, __HIP_MEMORY_SCOPE_AGENT); }
; __device__ __forceinline__ unsigned xb_add(unsigned* p, unsigned v) { return __hip_atomic_fetch_add(p, v, __ATOMIC_RELAXED, __HIP_MEMORY_SCOPE_AGENT); }
; #define XB_SPIN(cond, bar) do { unsigned _sp = 0; while (cond) { __builtin_amdgcn_s_sleep(1); \
;     if ((++_sp & 255u) == 0u) { if (xb_ld(&(bar)[XB_TMO])) break; if (_sp > XB_SPIN_CAP) { atomicAdd(&(bar)[XB_TMO], 1u); break; } } } } while (0)
; __device__ __forceinline__ void xcd_barrier(const XcdBarrier& b) {
;     asm volatile("s_waitcnt vmcnt(0)" ::: "memory");
;     __syncthreads();
;     if (tid_now(b.w) == 0) {
;         unsigned* bar = b.bar;
;         __builtin_amdgcn_s_waitcnt(0);
;         unsigned nloc = b.st[0], nx = b.st[1];
;         if (nloc == 0u) { xcd_barrier_complete(bar, b.x, nloc, nx, b.np); b.st[0] = nloc; b.st[1] = nx; }
;         const unsigned old = xb_add(&bar[XB_XSUB(b.x)], 1u);
;         const unsigned gen = old / nloc;
;         if (old + 1u == (gen + 1u) * nloc) {
;             __builtin_amdgcn_fence(__ATOMIC_RELEASE, "agent");
;             asm volatile("s_waitcnt vmcnt(0)" ::: "memory");
;             const unsigned og = xb_add(&bar[XB_TOP], 1u);
;             const unsigned tg = og / nx;
;             if (og + 1u == (tg + 1u) * nx) xb_add(&bar[XB_TOPGEN], 1u);
;             else XB_SPIN(xb_ld(&bar[XB_TOPGEN]) == tg, bar);
;             __builtin_amdgcn_fence(__ATOMIC_ACQUIRE, "agent");
;             xb_add(&bar[XB_XGEN(b.x)], 1u);
;             asm volatile("s_waitcnt vmcnt(0)" ::: "memory");
;         } else {
;             XB_SPIN(xb_ld(&bar[XB_XGEN(b.x)]) == gen, bar);
;             __builtin_amdgcn_fence(__ATOMIC_ACQUIRE, "agent");
;             asm volatile("s_waitcnt vmcnt(0)" ::: "memory");
;         }
;     }
;     __syncthreads();
; }
.LBB0_2070:
	s_setprio 0
	s_cmp_gt_i32 s35, 13
	s_cselect_b64 s[6:7], -1, 0
	s_and_b64 s[0:1], s[12:13], s[6:7]
	s_andn2_b64 vcc, exec, s[0:1]
	s_cbranch_vccnz .LBB0_2124
	s_waitcnt vmcnt(0)
	v_mov_b32_e32 v0, 0
	s_waitcnt vmcnt(0)
	s_waitcnt lgkmcnt(0)
	s_barrier
	s_nop 0
	v_mbcnt_lo_u32_b32 v0, -1, v0
	v_mbcnt_hi_u32_b32 v0, -1, v0
	v_or_b32_e32 v0, s33, v0
	v_cmp_eq_u32_e32 vcc, 0, v0
	s_and_saveexec_b64 s[2:3], vcc
	s_cbranch_execz .LBB0_2123
	s_add_i32 s0, 0, 0x27f68
	v_mov_b32_e32 v0, s0
	s_waitcnt vmcnt(0) expcnt(0) lgkmcnt(0)
	ds_read_b32 v2, v0
	s_add_i32 s0, 0, 0x27f6c
	v_mov_b32_e32 v0, s0
	ds_read_b32 v0, v0
	s_waitcnt lgkmcnt(1)
	v_cmp_ne_u32_e32 vcc, 0, v2
	s_cbranch_vccnz .LBB0_2087
	s_add_u32 s4, s10, 0x1000
	s_addc_u32 s5, s11, 0
	s_add_u32 s12, s10, 0x1100
	s_addc_u32 s13, s11, 0
	s_add_u32 s60, s10, 0x1200
	s_addc_u32 s61, s11, 0
	s_add_u32 s62, s10, 0x1300
	s_addc_u32 s63, s11, 0
	s_mov_b32 s0, 1
	v_mov_b32_e32 v16, 0
	s_branch .LBB0_2075

; #define PG8_STAGE(bufoff, gbase, voff) do { _Pragma("unroll") for (int _i = 0; _i < 2; ++_i) \
;         __builtin_amdgcn_global_load_lds((const unsigned*)((const char*)(gbase) + (voff)[_i]), (PG8_LAS unsigned*)(lds + (bufoff) + ldsw + _i * 8192), 16, 0, 0); } while (0)
; #define PG8_WAIT_V(n) asm volatile("s_waitcnt vmcnt(" #n ")" ::: "memory")
; #define PG8_BAR __builtin_amdgcn_s_barrier()
; template <class Epi, class Sched, bool ALIGN_EPI = false, bool SP2 = false, bool A_TILED = false>
; __device__ __forceinline__ void gemm_phase(PG8_LAS unsigned char* lds, const Gemm g, const Sched& S, const Epi& E, const int wave_s) {
;     ...
;     const int tid = tid_, wid = __builtin_amdgcn_readfirstlane(tid >> 6), lane = tid & 63, wr = wid >> 2, wc = wid & 3, fr = lane & 15, fq = lane >> 4;
;     const int K = g.K, nt = K / BK;
;     unsigned voffA[2], voffB[2];
; #pragma unroll
;     for (int i = 0; i < 2; ++i) { int R, C; stage_rc(tid * 16 + i * 8192, R, C); const int Rb = Epi::PERM ? ((R & ~31) + perm32(R & 31)) : R;
;         voffA[i] = A_TILED ? (unsigned)(tid * 16 + i * 8192) : (unsigned)(R * K + C) * 2u; voffB[i] = (unsigned)(Rb * K + C) * 2u; }
;     const size_t kstep = (size_t)(BK * 2);
;     const size_t hstep = (size_t)HALF * K * 2;
;     const size_t tstep = 2 * hstep;
;     const size_t kstepA = A_TILED ? (size_t)32768 : kstep, hstepA = A_TILED ? (size_t)16384 : hstep, tstepA = A_TILED ? (size_t)nt * 32768 : tstep;
;     const unsigned ldsw = (unsigned)wid * 1024u;
;     const int aoff = lds_byte(wr * 64 + fr, fq * 8), boff = lds_byte(wc * 32 + fr, fq * 8);
;     ...
;     if constexpr (SP2) {
;         PG8_STAGE(PG8_SB(0, 0), cB, voffB); PG8_STAGE(PG8_SB(0, 1), cB + hstep, voffB); PG8_STAGE(PG8_SA(0, 0), cA, voffA); PG8_STAGE(PG8_SA(0, 1), cA + hstepA, voffA);
;         if (wr == 1) PG8_BAR;
;         PG8_WAIT_V(2); PG8_BAR;
;         PG8_STAGE(PG8_SB(1, 0), cB + kstep, voffB); PG8_STAGE(PG8_SA(1, 0), cA + kstepA, voffA); PG8_STAGE(PG8_SB(1, 1), cB + hstep + kstep, voffB);
;         PG8_WAIT_V(6); PG8_BAR;
.LBB0_2411:
	s_sext_i32_i8 s44, s12
	s_mul_i32 s12, s96, 0x7c00000
	s_ashr_i32 s39, s86, 31
	s_add_u32 s2, s2, s12
	s_addc_u32 s3, s3, 0
	s_add_u32 s12, s2, 0x22600000
	s_addc_u32 s13, s3, 0
	v_and_b32_e32 v15, 48, v14
	v_lshlrev_b32_e32 v16, 6, v14
	s_movk_i32 s3, 0x3c0
	v_lshlrev_b32_e32 v14, 2, v14
	s_lshl_b32 s2, s42, 13
	v_and_or_b32 v15, v16, s3, v15
	v_and_b32_e32 v14, 32, v14
	v_bitop3_b32 v16, v15, s2, v14 bitop3:0xde
	s_lshl_b32 s2, s41, 5
	s_mov_b64 s[62:63], 0x80
	s_and_b32 s41, s2, 0x60
	s_add_i32 m0, s22, 0x18000
	v_lshl_add_u64 v[6:7], v[6:7], 0, s[62:63]
	s_lshl_b32 s40, s42, 6
	s_lshl_b32 s2, s41, 7
	s_waitcnt vmcnt(2)
	s_barrier
	global_load_lds_dwordx4 v[6:7], off
	v_lshl_add_u64 v[4:5], v[4:5], 0, s[62:63]
	s_add_i32 m0, s22, 0x1a000
	s_add_i32 s42, s22, 0x8000
	s_add_i32 s43, s22, 0xa000
	v_bitop3_b32 v140, s2, v15, v14 bitop3:0xf6
	global_load_lds_dwordx4 v[4:5], off
	v_lshl_add_u64 v[0:1], v[0:1], 0, s[62:63]
	s_mov_b32 m0, s42
	s_add_u32 s2, s78, 0x80080
	global_load_lds_dwordx4 v[0:1], off
	v_lshl_add_u64 v[0:1], v[2:3], 0, s[62:63]
	s_mov_b32 m0, s43
	s_addc_u32 s3, s79, 0
	global_load_lds_dwordx4 v[0:1], off
	s_add_i32 m0, s22, 0x1c000
	v_lshl_add_u64 v[0:1], s[2:3], 0, v[128:129]
	global_load_lds_dwordx4 v128, s[2:3]
	v_lshl_add_u64 v[0:1], s[2:3], 0, v[130:131]
	s_add_i32 m0, s22, 0x1e000
	s_cmpk_lt_u32 s45, 0x100
	global_load_lds_dwordx4 v130, s[2:3]
	v_lshlrev_b32_e32 v0, 15, v8
	v_and_b32_e32 v0, 0xffff0000, v0
	v_lshl_add_u32 v0, v9, 12, v0
	v_and_b32_e32 v1, 1, v8
	v_lshl_or_b32 v0, v1, 6, v0
	v_lshl_add_u32 v132, v10, 1, v0
	v_lshlrev_b32_e32 v0, 15, v11
	v_and_b32_e32 v0, 0xffff0000, v0
	s_waitcnt vmcnt(6)
	s_mov_b32 s98, 0
	v_lshl_add_u32 v0, v12, 12, v0
	v_and_b32_e32 v1, 1, v11
	s_cselect_b64 s[64:65], -1, 0
	s_bitcmp1_b32 s33, 8
	s_cbranch_scc1 .Lsp_9
	s_setprio 1
.Lsp_9:
	v_mov_b32_e32 v133, 0
	v_lshl_or_b32 v0, v1, 6, v0
	s_add_i32 s45, 0, 0x10000
	s_add_i32 s46, 0, 0x14000
	v_lshl_add_u32 v134, v13, 1, v0
	v_mov_b32_e32 v135, v133
	v_add_u32_e32 v141, s45, v140
	v_add_u32_e32 v142, s46, v140
	v_add_u32_e32 v143, 0, v16
	s_mov_b64 s[66:67], 0x100
	s_mov_b64 s[68:69], 0x180
	s_movk_i32 s47, 0x1400
	s_add_i32 s48, s22, 0xc000
	s_add_i32 s49, s22, 0xe000
	s_barrier
	s_branch .LBB0_2414

.Lpw_9:
	s_barrier
	v_mfma_f32_16x16x32_bf16 v[64:67], v[0:3], v[32:35], 0
	v_mfma_f32_16x16x32_bf16 v[68:71], v[8:11], v[32:35], 0
	v_mfma_f32_16x16x32_bf16 v[72:75], v[0:3], v[40:43], 0
	v_mfma_f32_16x16x32_bf16 v[76:79], v[8:11], v[40:43], 0
	v_mfma_f32_16x16x32_bf16 v[80:83], v[0:3], v[48:51], 0
	v_mfma_f32_16x16x32_bf16 v[84:87], v[8:11], v[48:51], 0
	v_mfma_f32_16x16x32_bf16 v[88:91], v[0:3], v[56:59], 0
	v_mfma_f32_16x16x32_bf16 v[92:95], v[8:11], v[56:59], 0
	v_mfma_f32_16x16x32_bf16 v[64:67], v[4:7], v[36:39], v[64:67]
	v_mfma_f32_16x16x32_bf16 v[68:71], v[12:15], v[36:39], v[68:71]
	v_mfma_f32_16x16x32_bf16 v[72:75], v[4:7], v[44:47], v[72:75]
	v_mfma_f32_16x16x32_bf16 v[76:79], v[12:15], v[44:47], v[76:79]
	v_mfma_f32_16x16x32_bf16 v[80:83], v[4:7], v[52:55], v[80:83]
	v_mfma_f32_16x16x32_bf16 v[84:87], v[12:15], v[52:55], v[84:87]
	v_mfma_f32_16x16x32_bf16 v[88:91], v[4:7], v[60:63], v[88:91]
	v_mfma_f32_16x16x32_bf16 v[92:95], v[12:15], v[60:63], v[92:95]
	v_mfma_f32_16x16x32_bf16 v[96:99], v[16:19], v[32:35], 0
	v_mfma_f32_16x16x32_bf16 v[32:35], v[24:27], v[32:35], 0
	v_mfma_f32_16x16x32_bf16 v[96:99], v[20:23], v[36:39], v[96:99]
	v_mfma_f32_16x16x32_bf16 v[32:35], v[28:31], v[36:39], v[32:35]
	v_mfma_f32_16x16x32_bf16 v[36:39], v[16:19], v[40:43], 0
	v_mfma_f32_16x16x32_bf16 v[40:43], v[24:27], v[40:43], 0
	v_mfma_f32_16x16x32_bf16 v[36:39], v[20:23], v[44:47], v[36:39]
	v_mfma_f32_16x16x32_bf16 v[40:43], v[28:31], v[44:47], v[40:43]
	v_mfma_f32_16x16x32_bf16 v[44:47], v[16:19], v[48:51], 0
	v_mfma_f32_16x16x32_bf16 v[48:51], v[24:27], v[48:51], 0
	v_mfma_f32_16x16x32_bf16 v[100:103], v[28:31], v[52:55], v[48:51]
	v_mfma_f32_16x16x32_bf16 v[48:51], v[16:19], v[56:59], 0
	v_mfma_f32_16x16x32_bf16 v[104:107], v[20:23], v[60:63], v[48:51]
	v_mfma_f32_16x16x32_bf16 v[48:51], v[24:27], v[56:59], 0
	v_mfma_f32_16x16x32_bf16 v[44:47], v[20:23], v[52:55], v[44:47]
	v_mfma_f32_16x16x32_bf16 v[108:111], v[28:31], v[60:63], v[48:51]
	s_barrier
	s_add_i32 s54, s45, s15
	v_lshl_add_u64 v[250:251], s[78:79], 0, v[128:129]
	s_add_i32 s55, s54, 0x2000
	v_lshl_add_u64 v[144:145], v[250:251], 0, s[66:67]
	s_mov_b32 m0, s54
	v_lshl_add_u64 v[252:253], s[78:79], 0, v[130:131]
	s_add_u32 s58, s78, 0x80100
	ds_read_b128 v[48:51], v143 offset:16384
	ds_read_b128 v[52:55], v143 offset:17408
	ds_read_b128 v[56:59], v143 offset:18432
	ds_read_b128 v[60:63], v143 offset:19456
	ds_read_b128 v[112:115], v143 offset:20480
	ds_read_b128 v[116:119], v143 offset:21504
	ds_read_b128 v[120:123], v143 offset:22528
	ds_read_b128 v[124:127], v143 offset:23552
	global_load_lds_dwordx4 v[144:145], off
	v_lshl_add_u64 v[144:145], v[252:253], 0, s[66:67]
	s_mov_b32 m0, s55
	s_addc_u32 s59, s79, 0
	s_add_i32 s56, s46, s15
	global_load_lds_dwordx4 v[144:145], off
	v_lshl_add_u64 v[144:145], s[58:59], 0, v[128:129]
	s_mov_b32 m0, s56
	s_add_i32 s57, s56, 0x2000
	global_load_lds_dwordx4 v128, s[58:59]
	v_lshl_add_u64 v[144:145], s[58:59], 0, v[130:131]
	s_mov_b32 m0, s57
	v_lshl_add_u64 v[136:137], s[80:81], 0, v[128:129]
	global_load_lds_dwordx4 v130, s[58:59]
	v_lshl_add_u64 v[144:145], v[136:137], 0, s[66:67]
	s_mov_b32 m0, s22
	v_lshl_add_u64 v[138:139], s[80:81], 0, v[130:131]
	global_load_lds_dwordx4 v[144:145], off
	v_lshl_add_u64 v[144:145], v[138:139], 0, s[66:67]
	s_mov_b32 m0, s23
	s_nop 0
	global_load_lds_dwordx4 v[144:145], off
	s_waitcnt vmcnt(40) lgkmcnt(0)
	s_cmp_lg_u32 s98, 0
	s_cbranch_scc1 .Lpw_10
	s_waitcnt vmcnt(8)
.Lpw_10:
	s_barrier
	v_mfma_f32_16x16x32_bf16 v[144:147], v[0:3], v[48:51], 0
	v_mfma_f32_16x16x32_bf16 v[154:157], v[0:3], v[56:59], 0
	v_mfma_f32_16x16x32_bf16 v[162:165], v[0:3], v[112:115], 0
	v_mfma_f32_16x16x32_bf16 v[0:3], v[0:3], v[120:123], 0
	v_mfma_f32_16x16x32_bf16 v[150:153], v[8:11], v[48:51], 0
	v_mfma_f32_16x16x32_bf16 v[158:161], v[8:11], v[56:59], 0
	v_mfma_f32_16x16x32_bf16 v[166:169], v[8:11], v[112:115], 0
	v_mfma_f32_16x16x32_bf16 v[170:173], v[4:7], v[124:127], v[0:3]
	v_mfma_f32_16x16x32_bf16 v[0:3], v[8:11], v[120:123], 0
	v_mfma_f32_16x16x32_bf16 v[146:149], v[4:7], v[52:55], v[144:147]
	v_mfma_f32_16x16x32_bf16 v[150:153], v[12:15], v[52:55], v[150:153]
	v_mfma_f32_16x16x32_bf16 v[154:157], v[4:7], v[60:63], v[154:157]
	v_mfma_f32_16x16x32_bf16 v[158:161], v[12:15], v[60:63], v[158:161]
	v_mfma_f32_16x16x32_bf16 v[162:165], v[4:7], v[116:119], v[162:165]
	v_mfma_f32_16x16x32_bf16 v[166:169], v[12:15], v[116:119], v[166:169]
	v_mfma_f32_16x16x32_bf16 v[174:177], v[12:15], v[124:127], v[0:3]
	v_mfma_f32_16x16x32_bf16 v[0:3], v[16:19], v[48:51], 0
	v_mfma_f32_16x16x32_bf16 v[178:181], v[20:23], v[52:55], v[0:3]
	v_mfma_f32_16x16x32_bf16 v[0:3], v[24:27], v[48:51], 0
	v_mfma_f32_16x16x32_bf16 v[182:185], v[28:31], v[52:55], v[0:3]
	v_mfma_f32_16x16x32_bf16 v[0:3], v[16:19], v[56:59], 0
	v_mfma_f32_16x16x32_bf16 v[186:189], v[20:23], v[60:63], v[0:3]
	v_mfma_f32_16x16x32_bf16 v[0:3], v[24:27], v[56:59], 0
	v_mfma_f32_16x16x32_bf16 v[190:193], v[28:31], v[60:63], v[0:3]
	v_mfma_f32_16x16x32_bf16 v[0:3], v[16:19], v[112:115], 0
	v_mfma_f32_16x16x32_bf16 v[194:197], v[20:23], v[116:119], v[0:3]
	v_mfma_f32_16x16x32_bf16 v[0:3], v[24:27], v[112:115], 0
	v_mfma_f32_16x16x32_bf16 v[198:201], v[28:31], v[116:119], v[0:3]
	v_mfma_f32_16x16x32_bf16 v[0:3], v[16:19], v[120:123], 0
	v_mfma_f32_16x16x32_bf16 v[202:205], v[20:23], v[124:127], v[0:3]
	v_mfma_f32_16x16x32_bf16 v[0:3], v[24:27], v[120:123], 0
	v_mfma_f32_16x16x32_bf16 v[206:209], v[28:31], v[124:127], v[0:3]
	s_barrier
; template <class Epi, class Sched, bool ALIGN_EPI = false, bool SP2 = false, bool A_TILED = false>
; __device__ __forceinline__ void gemm_phase(PG8_LAS unsigned char* lds, const Gemm g, const Sched& S, const Epi& E, const int wave_s) {
;     ...
; #pragma nounroll
;         for (int t = PEEL ? 2 : 0; t < nt; t += 2) {
;             const bool last = (t == nt - 2);
;             const char* a1 = cA + (size_t)(t + 1) * kstepA;
;             const char* a2 = last ? nA : cA + (size_t)(t + 2) * kstepA; const char* b2 = last ? nB : cB + (size_t)(t + 2) * kstep;
;             const char* a3 = a2 + kstepA; const char* b3 = b2 + kstep;
	s_add_i32 s61, 0, 0x18000
	s_add_i32 s71, 0, 0x1c000
	v_add_u32_e32 v144, s61, v140
	v_add_u32_e32 v145, s71, v140
	ds_read_b128 v[112:115], v144
	ds_read_b128 v[116:119], v144 offset:1024
	ds_read_b128 v[120:123], v144 offset:2048
	ds_read_b128 v[124:127], v144 offset:3072
	ds_read_b128 v[210:213], v145
	ds_read_b128 v[214:217], v145 offset:1024
	ds_read_b128 v[218:221], v145 offset:2048
	ds_read_b128 v[222:225], v145 offset:3072
	s_add_u32 s58, s80, 0x80100
	s_addc_u32 s59, s81, 0
	s_mov_b32 m0, s36
	v_lshl_add_u64 v[0:1], s[58:59], 0, v[128:129]
	ds_read_b128 v[48:51], v143 offset:32768
	ds_read_b128 v[52:55], v143 offset:33792
	ds_read_b128 v[226:229], v143 offset:34816
	ds_read_b128 v[230:233], v143 offset:35840
	ds_read_b128 v[234:237], v143 offset:36864
	ds_read_b128 v[238:241], v143 offset:37888
	ds_read_b128 v[242:245], v143 offset:38912
	ds_read_b128 v[246:249], v143 offset:39936
	global_load_lds_dwordx4 v128, s[58:59]
	v_lshl_add_u64 v[0:1], s[58:59], 0, v[130:131]
	s_mov_b32 m0, s37
	s_nop 0
	global_load_lds_dwordx4 v130, s[58:59]
	s_waitcnt vmcnt(8) lgkmcnt(0)
	s_barrier
	v_mfma_f32_16x16x32_bf16 v[0:3], v[112:115], v[48:51], v[64:67]
	v_mfma_f32_16x16x32_bf16 v[24:27], v[116:119], v[52:55], v[0:3]
	v_mfma_f32_16x16x32_bf16 v[0:3], v[120:123], v[48:51], v[68:71]
	v_mfma_f32_16x16x32_bf16 v[28:31], v[124:127], v[52:55], v[0:3]
	v_mfma_f32_16x16x32_bf16 v[0:3], v[112:115], v[226:229], v[72:75]
	v_mfma_f32_16x16x32_bf16 v[16:19], v[116:119], v[230:233], v[0:3]
	v_mfma_f32_16x16x32_bf16 v[0:3], v[120:123], v[226:229], v[76:79]
	v_mfma_f32_16x16x32_bf16 v[20:23], v[124:127], v[230:233], v[0:3]
	v_mfma_f32_16x16x32_bf16 v[0:3], v[112:115], v[234:237], v[80:83]
	v_mfma_f32_16x16x32_bf16 v[8:11], v[116:119], v[238:241], v[0:3]
	v_mfma_f32_16x16x32_bf16 v[0:3], v[120:123], v[234:237], v[84:87]
	v_mfma_f32_16x16x32_bf16 v[12:15], v[124:127], v[238:241], v[0:3]
	v_mfma_f32_16x16x32_bf16 v[0:3], v[112:115], v[242:245], v[88:91]
	v_mfma_f32_16x16x32_bf16 v[4:7], v[120:123], v[242:245], v[92:95]
	v_mfma_f32_16x16x32_bf16 v[0:3], v[116:119], v[246:249], v[0:3]
	v_mfma_f32_16x16x32_bf16 v[4:7], v[124:127], v[246:249], v[4:7]
	v_mfma_f32_16x16x32_bf16 v[32:35], v[218:221], v[48:51], v[32:35]
	v_mfma_f32_16x16x32_bf16 v[60:63], v[222:225], v[52:55], v[32:35]
	v_mfma_f32_16x16x32_bf16 v[32:35], v[210:213], v[226:229], v[36:39]
	v_mfma_f32_16x16x32_bf16 v[56:59], v[210:213], v[48:51], v[96:99]
	v_mfma_f32_16x16x32_bf16 v[48:51], v[214:217], v[230:233], v[32:35]
	v_mfma_f32_16x16x32_bf16 v[32:35], v[218:221], v[226:229], v[40:43]
	v_mfma_f32_16x16x32_bf16 v[56:59], v[214:217], v[52:55], v[56:59]
	v_mfma_f32_16x16x32_bf16 v[52:55], v[222:225], v[230:233], v[32:35]
	v_mfma_f32_16x16x32_bf16 v[32:35], v[210:213], v[234:237], v[44:47]
	v_mfma_f32_16x16x32_bf16 v[40:43], v[214:217], v[238:241], v[32:35]
	v_mfma_f32_16x16x32_bf16 v[32:35], v[218:221], v[234:237], v[100:103]
	v_mfma_f32_16x16x32_bf16 v[44:47], v[222:225], v[238:241], v[32:35]
	v_mfma_f32_16x16x32_bf16 v[32:35], v[210:213], v[242:245], v[104:107]
	v_mfma_f32_16x16x32_bf16 v[36:39], v[218:221], v[242:245], v[108:111]
	v_mfma_f32_16x16x32_bf16 v[32:35], v[214:217], v[246:249], v[32:35]
	v_mfma_f32_16x16x32_bf16 v[36:39], v[222:225], v[246:249], v[36:39]
	s_barrier
	s_add_i32 s58, s61, s15
	s_add_i32 s59, s58, 0x2000
	v_lshl_add_u64 v[64:65], v[250:251], 0, s[68:69]
	s_mov_b32 m0, s58
	s_add_u32 s82, s78, 0x80180
	ds_read_b128 v[96:99], v143 offset:49152
	ds_read_b128 v[100:103], v143 offset:50176
	ds_read_b128 v[104:107], v143 offset:51200
	ds_read_b128 v[108:111], v143 offset:52224
	ds_read_b128 v[226:229], v143 offset:53248
	ds_read_b128 v[230:233], v143 offset:54272
	ds_read_b128 v[234:237], v143 offset:55296
	ds_read_b128 v[238:241], v143 offset:56320
	global_load_lds_dwordx4 v[64:65], off
	v_lshl_add_u64 v[64:65], v[252:253], 0, s[68:69]
	s_mov_b32 m0, s59
	s_addc_u32 s83, s79, 0
	s_add_i32 s61, s71, s15
	global_load_lds_dwordx4 v[64:65], off
	v_lshl_add_u64 v[64:65], s[82:83], 0, v[128:129]
	s_mov_b32 m0, s61
	s_add_i32 s71, s61, 0x2000
	global_load_lds_dwordx4 v128, s[82:83]
	v_lshl_add_u64 v[64:65], s[82:83], 0, v[130:131]
	s_mov_b32 m0, s71
	s_nop 0
	global_load_lds_dwordx4 v130, s[82:83]
	v_lshl_add_u64 v[64:65], v[136:137], 0, s[68:69]
	s_mov_b32 m0, s42
	s_nop 0
	global_load_lds_dwordx4 v[64:65], off
	v_lshl_add_u64 v[64:65], v[138:139], 0, s[68:69]
	s_mov_b32 m0, s43
	s_nop 0
	global_load_lds_dwordx4 v[64:65], off
	s_waitcnt vmcnt(8) lgkmcnt(0)
	s_barrier
	v_mfma_f32_16x16x32_bf16 v[64:67], v[112:115], v[96:99], v[146:149]
	v_mfma_f32_16x16x32_bf16 v[88:91], v[116:119], v[100:103], v[64:67]
	v_mfma_f32_16x16x32_bf16 v[64:67], v[120:123], v[96:99], v[150:153]
	v_mfma_f32_16x16x32_bf16 v[92:95], v[124:127], v[100:103], v[64:67]
	v_mfma_f32_16x16x32_bf16 v[64:67], v[112:115], v[104:107], v[154:157]
	v_mfma_f32_16x16x32_bf16 v[80:83], v[116:119], v[108:111], v[64:67]
	v_mfma_f32_16x16x32_bf16 v[64:67], v[120:123], v[104:107], v[158:161]
	v_mfma_f32_16x16x32_bf16 v[84:87], v[124:127], v[108:111], v[64:67]
	v_mfma_f32_16x16x32_bf16 v[64:67], v[112:115], v[226:229], v[162:165]
	v_mfma_f32_16x16x32_bf16 v[72:75], v[116:119], v[230:233], v[64:67]
	v_mfma_f32_16x16x32_bf16 v[64:67], v[120:123], v[226:229], v[166:169]
	v_mfma_f32_16x16x32_bf16 v[76:79], v[124:127], v[230:233], v[64:67]
	v_mfma_f32_16x16x32_bf16 v[64:67], v[112:115], v[234:237], v[170:173]
	v_mfma_f32_16x16x32_bf16 v[68:71], v[120:123], v[234:237], v[174:177]
	v_mfma_f32_16x16x32_bf16 v[64:67], v[116:119], v[238:241], v[64:67]
	v_mfma_f32_16x16x32_bf16 v[68:71], v[124:127], v[238:241], v[68:71]
	v_mfma_f32_16x16x32_bf16 v[112:115], v[210:213], v[96:99], v[178:181]
	v_mfma_f32_16x16x32_bf16 v[96:99], v[218:221], v[96:99], v[182:185]
	v_mfma_f32_16x16x32_bf16 v[124:127], v[222:225], v[100:103], v[96:99]
	v_mfma_f32_16x16x32_bf16 v[96:99], v[210:213], v[104:107], v[186:189]
	v_mfma_f32_16x16x32_bf16 v[120:123], v[214:217], v[100:103], v[112:115]
	v_mfma_f32_16x16x32_bf16 v[112:115], v[214:217], v[108:111], v[96:99]
	v_mfma_f32_16x16x32_bf16 v[96:99], v[218:221], v[104:107], v[190:193]
	v_mfma_f32_16x16x32_bf16 v[116:119], v[222:225], v[108:111], v[96:99]
	v_mfma_f32_16x16x32_bf16 v[96:99], v[210:213], v[226:229], v[194:197]
	v_mfma_f32_16x16x32_bf16 v[104:107], v[214:217], v[230:233], v[96:99]
	v_mfma_f32_16x16x32_bf16 v[96:99], v[218:221], v[226:229], v[198:201]
	v_mfma_f32_16x16x32_bf16 v[108:111], v[222:225], v[230:233], v[96:99]
	v_mfma_f32_16x16x32_bf16 v[96:99], v[210:213], v[234:237], v[202:205]
	v_mfma_f32_16x16x32_bf16 v[100:103], v[218:221], v[234:237], v[206:209]
	v_mfma_f32_16x16x32_bf16 v[96:99], v[214:217], v[238:241], v[96:99]
	v_mfma_f32_16x16x32_bf16 v[100:103], v[222:225], v[238:241], v[100:103]
	s_barrier
	s_add_u32 s73, s78, 0x200
	s_addc_u32 s85, s79, 0
	s_add_u32 s78, s80, 0x80180
	s_addc_u32 s79, s81, 0
	s_mov_b32 s88, 0
; #define PG8_MMA(ai, bj, At, Bt) do { __builtin_amdgcn_s_setprio(1); _Pragma("unroll") for (int m = 0; m < 4; ++m) _Pragma("unroll") for (int n = 0; n < 2; ++n) _Pragma("unroll") for (int k = 0; k < 2; ++k) \
;         acc[ai][bj][m][n] = __builtin_amdgcn_mfma_f32_16x16x32_bf16(Bt[n][k], At[m][k], acc[ai][bj][m][n], 0, 0, 0); __builtin_amdgcn_s_setprio(0); } while (0)
; template <class Epi, class Sched, bool ALIGN_EPI = false, bool SP2 = false, bool A_TILED = false>
; __device__ __forceinline__ void gemm_phase(PG8_LAS unsigned char* lds, const Gemm g, const Sched& S, const Epi& E, const int wave_s) {
;     ...
;         for (int t = PEEL ? 2 : 0; t < nt; t += 2) {
;             const bool last = (t == nt - 2);
;             const char* a1 = cA + (size_t)(t + 1) * kstepA;
;             const char* a2 = last ? nA : cA + (size_t)(t + 2) * kstepA; const char* b2 = last ? nB : cB + (size_t)(t + 2) * kstep;
;             const char* a3 = a2 + kstepA; const char* b3 = b2 + kstep;
;             if (last && has_next) S.a_ready(nxt);
;             if constexpr (SP2) {
;             PG8_ITER(PG8_MMA)
.LBB0_2417:
	ds_read_b128 v[146:149], v141
	ds_read_b128 v[150:153], v141 offset:1024
	ds_read_b128 v[154:157], v141 offset:2048
	ds_read_b128 v[158:161], v141 offset:3072
	ds_read_b128 v[162:165], v142
	ds_read_b128 v[166:169], v142 offset:1024
	ds_read_b128 v[170:173], v142 offset:2048
	ds_read_b128 v[174:177], v142 offset:3072
	s_add_u32 s80, s78, 0xfff80080
	s_addc_u32 s81, s79, -1
	s_cmp_eq_u32 s88, 28
	s_cselect_b32 s83, s50, s81
	s_cselect_b32 s82, s51, s80
	s_cselect_b32 s81, s52, s85
	s_cselect_b32 s80, s53, s73
	s_mov_b32 m0, s48
	v_lshl_add_u64 v[136:137], s[78:79], 0, v[134:135]
	ds_read_b128 v[178:181], v143
	ds_read_b128 v[182:185], v143 offset:1024
	ds_read_b128 v[186:189], v143 offset:2048
	ds_read_b128 v[190:193], v143 offset:3072
	ds_read_b128 v[194:197], v143 offset:4096
	ds_read_b128 v[198:201], v143 offset:5120
	ds_read_b128 v[202:205], v143 offset:6144
	ds_read_b128 v[206:209], v143 offset:7168
	global_load_lds_dwordx4 v134, s[78:79]
	v_lshl_add_u64 v[136:137], s[78:79], 0, v[132:133]
	s_mov_b32 m0, s49
	s_nop 0
	global_load_lds_dwordx4 v132, s[78:79]
	s_waitcnt vmcnt(8) lgkmcnt(0)
	s_barrier
	v_mfma_f32_16x16x32_bf16 v[24:27], v[146:149], v[178:181], v[24:27]
	v_mfma_f32_16x16x32_bf16 v[28:31], v[154:157], v[178:181], v[28:31]
	v_mfma_f32_16x16x32_bf16 v[16:19], v[146:149], v[186:189], v[16:19]
	v_mfma_f32_16x16x32_bf16 v[20:23], v[154:157], v[186:189], v[20:23]
	v_mfma_f32_16x16x32_bf16 v[8:11], v[146:149], v[194:197], v[8:11]
	v_mfma_f32_16x16x32_bf16 v[12:15], v[154:157], v[194:197], v[12:15]
	v_mfma_f32_16x16x32_bf16 v[0:3], v[146:149], v[202:205], v[0:3]
	v_mfma_f32_16x16x32_bf16 v[4:7], v[154:157], v[202:205], v[4:7]
	v_mfma_f32_16x16x32_bf16 v[24:27], v[150:153], v[182:185], v[24:27]
	v_mfma_f32_16x16x32_bf16 v[28:31], v[158:161], v[182:185], v[28:31]
	v_mfma_f32_16x16x32_bf16 v[16:19], v[150:153], v[190:193], v[16:19]
	v_mfma_f32_16x16x32_bf16 v[20:23], v[158:161], v[190:193], v[20:23]
	v_mfma_f32_16x16x32_bf16 v[8:11], v[150:153], v[198:201], v[8:11]
	v_mfma_f32_16x16x32_bf16 v[12:15], v[158:161], v[198:201], v[12:15]
	v_mfma_f32_16x16x32_bf16 v[0:3], v[150:153], v[206:209], v[0:3]
	v_mfma_f32_16x16x32_bf16 v[4:7], v[158:161], v[206:209], v[4:7]
	v_mfma_f32_16x16x32_bf16 v[56:59], v[162:165], v[178:181], v[56:59]
	v_mfma_f32_16x16x32_bf16 v[60:63], v[170:173], v[178:181], v[60:63]
	v_mfma_f32_16x16x32_bf16 v[48:51], v[162:165], v[186:189], v[48:51]
	v_mfma_f32_16x16x32_bf16 v[52:55], v[170:173], v[186:189], v[52:55]
	v_mfma_f32_16x16x32_bf16 v[40:43], v[162:165], v[194:197], v[40:43]
	v_mfma_f32_16x16x32_bf16 v[44:47], v[170:173], v[194:197], v[44:47]
	v_mfma_f32_16x16x32_bf16 v[32:35], v[162:165], v[202:205], v[32:35]
	v_mfma_f32_16x16x32_bf16 v[36:39], v[170:173], v[202:205], v[36:39]
	v_mfma_f32_16x16x32_bf16 v[56:59], v[166:169], v[182:185], v[56:59]
	v_mfma_f32_16x16x32_bf16 v[60:63], v[174:177], v[182:185], v[60:63]
	v_mfma_f32_16x16x32_bf16 v[48:51], v[166:169], v[190:193], v[48:51]
	v_mfma_f32_16x16x32_bf16 v[52:55], v[174:177], v[190:193], v[52:55]
	v_mfma_f32_16x16x32_bf16 v[40:43], v[166:169], v[198:201], v[40:43]
	v_mfma_f32_16x16x32_bf16 v[44:47], v[174:177], v[198:201], v[44:47]
	v_mfma_f32_16x16x32_bf16 v[32:35], v[166:169], v[206:209], v[32:35]
	v_mfma_f32_16x16x32_bf16 v[36:39], v[174:177], v[206:209], v[36:39]
	s_barrier
	s_mov_b32 m0, s54
	v_lshl_add_u64 v[136:137], s[80:81], 0, v[128:129]
	s_add_u32 s90, s80, 0x80000
	ds_read_b128 v[178:181], v143 offset:16384
	ds_read_b128 v[182:185], v143 offset:17408
	ds_read_b128 v[186:189], v143 offset:18432
	ds_read_b128 v[190:193], v143 offset:19456
	ds_read_b128 v[194:197], v143 offset:20480
	ds_read_b128 v[198:201], v143 offset:21504
	ds_read_b128 v[202:205], v143 offset:22528
	ds_read_b128 v[206:209], v143 offset:23552
	global_load_lds_dwordx4 v128, s[80:81]
	v_lshl_add_u64 v[138:139], s[80:81], 0, v[130:131]
	s_mov_b32 m0, s55
	s_addc_u32 s91, s81, 0
	global_load_lds_dwordx4 v130, s[80:81]
	v_lshl_add_u64 v[210:211], s[90:91], 0, v[128:129]
	s_mov_b32 m0, s56
	v_lshl_add_u64 v[212:213], s[82:83], 0, v[130:131]
	global_load_lds_dwordx4 v128, s[90:91]
	v_lshl_add_u64 v[210:211], s[90:91], 0, v[130:131]
	s_mov_b32 m0, s57
	s_nop 0
	global_load_lds_dwordx4 v130, s[90:91]
	v_lshl_add_u64 v[210:211], s[82:83], 0, v[128:129]
	s_mov_b32 m0, s22
	s_nop 0
	global_load_lds_dwordx4 v128, s[82:83]
	s_mov_b32 m0, s23
	s_nop 0
	global_load_lds_dwordx4 v130, s[82:83]
	s_waitcnt vmcnt(8) lgkmcnt(0)
	s_barrier
	v_mfma_f32_16x16x32_bf16 v[88:91], v[146:149], v[178:181], v[88:91]
	v_mfma_f32_16x16x32_bf16 v[92:95], v[154:157], v[178:181], v[92:95]
	v_mfma_f32_16x16x32_bf16 v[80:83], v[146:149], v[186:189], v[80:83]
	v_mfma_f32_16x16x32_bf16 v[84:87], v[154:157], v[186:189], v[84:87]
	v_mfma_f32_16x16x32_bf16 v[72:75], v[146:149], v[194:197], v[72:75]
	v_mfma_f32_16x16x32_bf16 v[76:79], v[154:157], v[194:197], v[76:79]
	v_mfma_f32_16x16x32_bf16 v[64:67], v[146:149], v[202:205], v[64:67]
	v_mfma_f32_16x16x32_bf16 v[68:71], v[154:157], v[202:205], v[68:71]
	v_mfma_f32_16x16x32_bf16 v[88:91], v[150:153], v[182:185], v[88:91]
	v_mfma_f32_16x16x32_bf16 v[92:95], v[158:161], v[182:185], v[92:95]
	v_mfma_f32_16x16x32_bf16 v[80:83], v[150:153], v[190:193], v[80:83]
	v_mfma_f32_16x16x32_bf16 v[84:87], v[158:161], v[190:193], v[84:87]
	v_mfma_f32_16x16x32_bf16 v[72:75], v[150:153], v[198:201], v[72:75]
	v_mfma_f32_16x16x32_bf16 v[76:79], v[158:161], v[198:201], v[76:79]
	v_mfma_f32_16x16x32_bf16 v[64:67], v[150:153], v[206:209], v[64:67]
	v_mfma_f32_16x16x32_bf16 v[68:71], v[158:161], v[206:209], v[68:71]
	v_mfma_f32_16x16x32_bf16 v[120:123], v[162:165], v[178:181], v[120:123]
	v_mfma_f32_16x16x32_bf16 v[124:127], v[170:173], v[178:181], v[124:127]
	v_mfma_f32_16x16x32_bf16 v[112:115], v[162:165], v[186:189], v[112:115]
	v_mfma_f32_16x16x32_bf16 v[116:119], v[170:173], v[186:189], v[116:119]
	v_mfma_f32_16x16x32_bf16 v[104:107], v[162:165], v[194:197], v[104:107]
	v_mfma_f32_16x16x32_bf16 v[108:111], v[170:173], v[194:197], v[108:111]
	v_mfma_f32_16x16x32_bf16 v[96:99], v[162:165], v[202:205], v[96:99]
	v_mfma_f32_16x16x32_bf16 v[100:103], v[170:173], v[202:205], v[100:103]
	v_mfma_f32_16x16x32_bf16 v[120:123], v[166:169], v[182:185], v[120:123]
	v_mfma_f32_16x16x32_bf16 v[124:127], v[174:177], v[182:185], v[124:127]
	v_mfma_f32_16x16x32_bf16 v[112:115], v[166:169], v[190:193], v[112:115]
	v_mfma_f32_16x16x32_bf16 v[116:119], v[174:177], v[190:193], v[116:119]
	v_mfma_f32_16x16x32_bf16 v[104:107], v[166:169], v[198:201], v[104:107]
	v_mfma_f32_16x16x32_bf16 v[108:111], v[174:177], v[198:201], v[108:111]
	v_mfma_f32_16x16x32_bf16 v[96:99], v[166:169], v[206:209], v[96:99]
	v_mfma_f32_16x16x32_bf16 v[100:103], v[174:177], v[206:209], v[100:103]
	s_barrier
; #define PG8_STAGE(bufoff, gbase, voff) do { _Pragma("unroll") for (int _i = 0; _i < 2; ++_i) \
;         __builtin_amdgcn_global_load_lds((const unsigned*)((const char*)(gbase) + (voff)[_i]), (PG8_LAS unsigned*)(lds + (bufoff) + ldsw + _i * 8192), 16, 0, 0); } while (0)
; #define PG8_BAR __builtin_amdgcn_s_barrier()
; template <class Epi, class Sched, bool ALIGN_EPI = false, bool SP2 = false, bool A_TILED = false>
; __device__ __forceinline__ void gemm_phase(PG8_LAS unsigned char* lds, const Gemm g, const Sched& S, const Epi& E, const int wave_s) {
;     ...
;         for (int t = PEEL ? 2 : 0; t < nt; t += 2) {
;             const bool last = (t == nt - 2);
;             const char* a1 = cA + (size_t)(t + 1) * kstepA;
;             const char* a2 = last ? nA : cA + (size_t)(t + 2) * kstepA; const char* b2 = last ? nB : cB + (size_t)(t + 2) * kstep;
;             const char* a3 = a2 + kstepA; const char* b3 = b2 + kstep;
;             if (last && has_next) S.a_ready(nxt);
;             if constexpr (SP2) {
;             PG8_ITER(PG8_MMA)
;             } else {
;             PG8_LDB(B0, 0, 0); PG8_SCHED; PG8_LDA(At, 0, 0); PG8_STAGE(PG8_SA(1, 1), a1 + hstepA, voffA);
;             PG8_WAIT_L(8); PG8_BAR; PG8_WAIT_L(0); PG8_MMA(0, 0, At, B0); PG8_BAR; PG8_SCHED;
;             PG8_LDB(B1, 0, 1); PG8_STAGE(PG8_SB(0, 0), b2, voffB);
;             PG8_BAR; PG8_WAIT_L(0); PG8_MMA(0, 1, At, B1); PG8_BAR;
;             PG8_LDA(At, 0, 1); PG8_STAGE(PG8_SA(0, 0), a2, voffA);
;             PG8_BAR; PG8_WAIT_L(0); PG8_MMA(1, 0, At, B0); PG8_BAR; PG8_SCHED;
;             PG8_STAGE(PG8_SB(0, 1), b2 + hstep, voffB);
;             PG8_WAIT_V(6); PG8_BAR; PG8_MMA(1, 1, At, B1); PG8_BAR;
;             PG8_LDB(B0, 1, 0); PG8_SCHED; PG8_LDA(At, 1, 0); PG8_STAGE(PG8_SA(0, 1), a2 + hstepA, voffA);
;             PG8_WAIT_L(8); PG8_BAR; PG8_WAIT_L(0); PG8_MMA(0, 0, At, B0); PG8_BAR; PG8_SCHED;
;             PG8_LDB(B1, 1, 1); PG8_STAGE(PG8_SB(1, 0), b3, voffB);
;             PG8_BAR; PG8_WAIT_L(0); PG8_MMA(0, 1, At, B1); PG8_BAR;
;             PG8_LDA(At, 1, 1); PG8_STAGE(PG8_SA(1, 0), a3, voffA);
;             PG8_BAR; PG8_WAIT_L(0); PG8_MMA(1, 0, At, B0); PG8_BAR; PG8_SCHED;
;             PG8_STAGE(PG8_SB(1, 1), b3 + hstep, voffB);
;             PG8_WAIT_V(6); PG8_BAR; PG8_MMA(1, 1, At, B1); PG8_BAR;
;             }
;         }
;         if constexpr (ALIGN_EPI) { if (wr == 0) PG8_BAR; }
	ds_read_b128 v[146:149], v144
	ds_read_b128 v[150:153], v144 offset:1024
	ds_read_b128 v[154:157], v144 offset:2048
	ds_read_b128 v[158:161], v144 offset:3072
	ds_read_b128 v[162:165], v145
	ds_read_b128 v[166:169], v145 offset:1024
	ds_read_b128 v[170:173], v145 offset:2048
	ds_read_b128 v[174:177], v145 offset:3072
	s_add_u32 s82, s82, 0x80000
	s_addc_u32 s83, s83, 0
	s_mov_b32 m0, s36
	v_lshl_add_u64 v[214:215], s[82:83], 0, v[128:129]
	ds_read_b128 v[178:181], v143 offset:32768
	ds_read_b128 v[182:185], v143 offset:33792
	ds_read_b128 v[186:189], v143 offset:34816
	ds_read_b128 v[190:193], v143 offset:35840
	ds_read_b128 v[194:197], v143 offset:36864
	ds_read_b128 v[198:201], v143 offset:37888
	ds_read_b128 v[202:205], v143 offset:38912
	ds_read_b128 v[206:209], v143 offset:39936
	global_load_lds_dwordx4 v128, s[82:83]
	v_lshl_add_u64 v[214:215], s[82:83], 0, v[130:131]
	s_mov_b32 m0, s37
	s_nop 0
	global_load_lds_dwordx4 v130, s[82:83]
	s_waitcnt vmcnt(8) lgkmcnt(0)
	s_barrier
	v_mfma_f32_16x16x32_bf16 v[24:27], v[146:149], v[178:181], v[24:27]
	v_mfma_f32_16x16x32_bf16 v[28:31], v[154:157], v[178:181], v[28:31]
	v_mfma_f32_16x16x32_bf16 v[16:19], v[146:149], v[186:189], v[16:19]
	v_mfma_f32_16x16x32_bf16 v[20:23], v[154:157], v[186:189], v[20:23]
	v_mfma_f32_16x16x32_bf16 v[8:11], v[146:149], v[194:197], v[8:11]
	v_mfma_f32_16x16x32_bf16 v[12:15], v[154:157], v[194:197], v[12:15]
	v_mfma_f32_16x16x32_bf16 v[0:3], v[146:149], v[202:205], v[0:3]
	v_mfma_f32_16x16x32_bf16 v[4:7], v[154:157], v[202:205], v[4:7]
	v_mfma_f32_16x16x32_bf16 v[24:27], v[150:153], v[182:185], v[24:27]
	v_mfma_f32_16x16x32_bf16 v[28:31], v[158:161], v[182:185], v[28:31]
	v_mfma_f32_16x16x32_bf16 v[16:19], v[150:153], v[190:193], v[16:19]
	v_mfma_f32_16x16x32_bf16 v[20:23], v[158:161], v[190:193], v[20:23]
	v_mfma_f32_16x16x32_bf16 v[8:11], v[150:153], v[198:201], v[8:11]
	v_mfma_f32_16x16x32_bf16 v[12:15], v[158:161], v[198:201], v[12:15]
	v_mfma_f32_16x16x32_bf16 v[0:3], v[150:153], v[206:209], v[0:3]
	v_mfma_f32_16x16x32_bf16 v[4:7], v[158:161], v[206:209], v[4:7]
	v_mfma_f32_16x16x32_bf16 v[56:59], v[162:165], v[178:181], v[56:59]
	v_mfma_f32_16x16x32_bf16 v[60:63], v[170:173], v[178:181], v[60:63]
	v_mfma_f32_16x16x32_bf16 v[48:51], v[162:165], v[186:189], v[48:51]
	v_mfma_f32_16x16x32_bf16 v[52:55], v[170:173], v[186:189], v[52:55]
	v_mfma_f32_16x16x32_bf16 v[40:43], v[162:165], v[194:197], v[40:43]
	v_mfma_f32_16x16x32_bf16 v[44:47], v[170:173], v[194:197], v[44:47]
	v_mfma_f32_16x16x32_bf16 v[32:35], v[162:165], v[202:205], v[32:35]
	v_mfma_f32_16x16x32_bf16 v[36:39], v[170:173], v[202:205], v[36:39]
	v_mfma_f32_16x16x32_bf16 v[56:59], v[166:169], v[182:185], v[56:59]
	v_mfma_f32_16x16x32_bf16 v[60:63], v[174:177], v[182:185], v[60:63]
	v_mfma_f32_16x16x32_bf16 v[48:51], v[166:169], v[190:193], v[48:51]
	v_mfma_f32_16x16x32_bf16 v[52:55], v[174:177], v[190:193], v[52:55]
	v_mfma_f32_16x16x32_bf16 v[40:43], v[166:169], v[198:201], v[40:43]
	v_mfma_f32_16x16x32_bf16 v[44:47], v[174:177], v[198:201], v[44:47]
	v_mfma_f32_16x16x32_bf16 v[32:35], v[166:169], v[206:209], v[32:35]
	v_mfma_f32_16x16x32_bf16 v[36:39], v[174:177], v[206:209], v[36:39]
	s_barrier
	s_mov_b32 m0, s58
	v_lshl_add_u64 v[136:137], v[136:137], 0, s[62:63]
	s_add_u32 s80, s80, 0x80080
	ds_read_b128 v[178:181], v143 offset:49152
	ds_read_b128 v[182:185], v143 offset:50176
	ds_read_b128 v[186:189], v143 offset:51200
	ds_read_b128 v[190:193], v143 offset:52224
	ds_read_b128 v[194:197], v143 offset:53248
	ds_read_b128 v[198:201], v143 offset:54272
	ds_read_b128 v[202:205], v143 offset:55296
	ds_read_b128 v[206:209], v143 offset:56320
	global_load_lds_dwordx4 v[136:137], off
	v_lshl_add_u64 v[136:137], v[138:139], 0, s[62:63]
	s_mov_b32 m0, s59
	s_addc_u32 s81, s81, 0
	global_load_lds_dwordx4 v[136:137], off
	v_lshl_add_u64 v[136:137], s[80:81], 0, v[128:129]
	s_mov_b32 m0, s61
	s_nop 0
	global_load_lds_dwordx4 v128, s[80:81]
	v_lshl_add_u64 v[136:137], s[80:81], 0, v[130:131]
	s_mov_b32 m0, s71
	s_nop 0
	global_load_lds_dwordx4 v130, s[80:81]
	v_lshl_add_u64 v[136:137], v[210:211], 0, s[62:63]
	s_mov_b32 m0, s42
	s_nop 0
	global_load_lds_dwordx4 v[136:137], off
	v_lshl_add_u64 v[136:137], v[212:213], 0, s[62:63]
	s_mov_b32 m0, s43
	s_nop 0
	global_load_lds_dwordx4 v[136:137], off
	s_waitcnt vmcnt(8) lgkmcnt(0)
	s_barrier
	v_mfma_f32_16x16x32_bf16 v[88:91], v[146:149], v[178:181], v[88:91]
	v_mfma_f32_16x16x32_bf16 v[92:95], v[154:157], v[178:181], v[92:95]
	v_mfma_f32_16x16x32_bf16 v[80:83], v[146:149], v[186:189], v[80:83]
	v_mfma_f32_16x16x32_bf16 v[84:87], v[154:157], v[186:189], v[84:87]
	v_mfma_f32_16x16x32_bf16 v[72:75], v[146:149], v[194:197], v[72:75]
	v_mfma_f32_16x16x32_bf16 v[76:79], v[154:157], v[194:197], v[76:79]
	v_mfma_f32_16x16x32_bf16 v[64:67], v[146:149], v[202:205], v[64:67]
	v_mfma_f32_16x16x32_bf16 v[68:71], v[154:157], v[202:205], v[68:71]
	v_mfma_f32_16x16x32_bf16 v[88:91], v[150:153], v[182:185], v[88:91]
	v_mfma_f32_16x16x32_bf16 v[92:95], v[158:161], v[182:185], v[92:95]
	v_mfma_f32_16x16x32_bf16 v[80:83], v[150:153], v[190:193], v[80:83]
	v_mfma_f32_16x16x32_bf16 v[84:87], v[158:161], v[190:193], v[84:87]
	v_mfma_f32_16x16x32_bf16 v[72:75], v[150:153], v[198:201], v[72:75]
	v_mfma_f32_16x16x32_bf16 v[76:79], v[158:161], v[198:201], v[76:79]
	v_mfma_f32_16x16x32_bf16 v[64:67], v[150:153], v[206:209], v[64:67]
	v_mfma_f32_16x16x32_bf16 v[68:71], v[158:161], v[206:209], v[68:71]
	v_mfma_f32_16x16x32_bf16 v[120:123], v[162:165], v[178:181], v[120:123]
	v_mfma_f32_16x16x32_bf16 v[124:127], v[170:173], v[178:181], v[124:127]
	v_mfma_f32_16x16x32_bf16 v[112:115], v[162:165], v[186:189], v[112:115]
	v_mfma_f32_16x16x32_bf16 v[116:119], v[170:173], v[186:189], v[116:119]
	v_mfma_f32_16x16x32_bf16 v[104:107], v[162:165], v[194:197], v[104:107]
	v_mfma_f32_16x16x32_bf16 v[108:111], v[170:173], v[194:197], v[108:111]
	v_mfma_f32_16x16x32_bf16 v[96:99], v[162:165], v[202:205], v[96:99]
	v_mfma_f32_16x16x32_bf16 v[100:103], v[170:173], v[202:205], v[100:103]
	v_mfma_f32_16x16x32_bf16 v[120:123], v[166:169], v[182:185], v[120:123]
	v_mfma_f32_16x16x32_bf16 v[124:127], v[174:177], v[182:185], v[124:127]
	v_mfma_f32_16x16x32_bf16 v[112:115], v[166:169], v[190:193], v[112:115]
	v_mfma_f32_16x16x32_bf16 v[116:119], v[174:177], v[190:193], v[116:119]
	v_mfma_f32_16x16x32_bf16 v[104:107], v[166:169], v[198:201], v[104:107]
	v_mfma_f32_16x16x32_bf16 v[108:111], v[174:177], v[198:201], v[108:111]
	v_mfma_f32_16x16x32_bf16 v[96:99], v[166:169], v[206:209], v[96:99]
	v_mfma_f32_16x16x32_bf16 v[100:103], v[174:177], v[206:209], v[100:103]
	s_barrier
	s_add_i32 s88, s88, 2
	s_add_u32 s73, s73, 0x100
	s_addc_u32 s85, s85, 0
	s_add_u32 s78, s78, 0x100
	s_addc_u32 s79, s79, 0
	s_cmp_gt_u32 s88, 29
	s_cbranch_scc0 .LBB0_2417
	s_and_b64 vcc, exec, s[64:65]
	s_cbranch_vccz .LBB0_2420
	s_barrier

; __device__ __forceinline__ int tid_now(int wave_s) { unsigned z = 0u; asm volatile("" : "+v"(z)); return (wave_s << 6) | (int)__builtin_amdgcn_mbcnt_hi(~0u, __builtin_amdgcn_mbcnt_lo(~0u, z)); }
; __device__ __forceinline__ unsigned xb_add(unsigned* p, unsigned v) { return __hip_atomic_fetch_add(p, v, __ATOMIC_RELAXED, __HIP_MEMORY_SCOPE_AGENT); }
; __device__ __forceinline__ void xcd_barrier(const XcdBarrier& b) {
;     asm volatile("s_waitcnt vmcnt(0)" ::: "memory");
;     __syncthreads();
;     if (tid_now(b.w) == 0) {
;         unsigned* bar = b.bar;
;         __builtin_amdgcn_s_waitcnt(0);
;         unsigned nloc = b.st[0], nx = b.st[1];
;         if (nloc == 0u) { xcd_barrier_complete(bar, b.x, nloc, nx, b.np); b.st[0] = nloc; b.st[1] = nx; }
;         const unsigned old = xb_add(&bar[XB_XSUB(b.x)], 1u);
.LBB0_2424:
	s_setprio 0
	s_cmp_gt_i32 s35, 14
	s_cselect_b64 s[2:3], -1, 0
	s_and_b64 s[0:1], s[4:5], s[2:3]
	s_andn2_b64 vcc, exec, s[0:1]
	s_cbranch_vccnz .LBB0_2478
	v_mov_b32_e32 v0, 0
	s_waitcnt vmcnt(0)
	s_waitcnt vmcnt(0) lgkmcnt(0)
	s_barrier
	s_nop 0
	v_mbcnt_lo_u32_b32 v0, -1, v0
	v_mbcnt_hi_u32_b32 v0, -1, v0
	v_or_b32_e32 v0, s33, v0
	v_cmp_eq_u32_e32 vcc, 0, v0
	s_and_saveexec_b64 s[4:5], vcc
	s_cbranch_execz .LBB0_2477
	s_add_i32 s0, 0, 0x27f68
	v_mov_b32_e32 v0, s0
	s_waitcnt vmcnt(0) expcnt(0) lgkmcnt(0)
	ds_read_b32 v2, v0
	s_add_i32 s0, 0, 0x27f6c
	v_mov_b32_e32 v0, s0
	ds_read_b32 v0, v0
	s_waitcnt lgkmcnt(1)
	v_cmp_ne_u32_e32 vcc, 0, v2
	s_cbranch_vccnz .LBB0_2441
	s_add_u32 s6, s10, 0x1000
	s_addc_u32 s7, s11, 0
	s_add_u32 s12, s10, 0x1100
	s_addc_u32 s13, s11, 0
	s_add_u32 s60, s10, 0x1200
	s_addc_u32 s61, s11, 0
	s_add_u32 s62, s10, 0x1300
	s_addc_u32 s63, s11, 0
	s_mov_b32 s0, 1
	v_mov_b32_e32 v16, 0
	s_branch .LBB0_2429

; __device__ __forceinline__ int tid_now(int wave_s) { unsigned z = 0u; asm volatile("" : "+v"(z)); return (wave_s << 6) | (int)__builtin_amdgcn_mbcnt_hi(~0u, __builtin_amdgcn_mbcnt_lo(~0u, z)); }
; __device__ __forceinline__ unsigned xb_add(unsigned* p, unsigned v) { return __hip_atomic_fetch_add(p, v, __ATOMIC_RELAXED, __HIP_MEMORY_SCOPE_AGENT); }
; __device__ __forceinline__ void xcd_barrier(const XcdBarrier& b) {
;     asm volatile("s_waitcnt vmcnt(0)" ::: "memory");
;     __syncthreads();
;     if (tid_now(b.w) == 0) {
;         unsigned* bar = b.bar;
;         __builtin_amdgcn_s_waitcnt(0);
;         unsigned nloc = b.st[0], nx = b.st[1];
;         if (nloc == 0u) { xcd_barrier_complete(bar, b.x, nloc, nx, b.np); b.st[0] = nloc; b.st[1] = nx; }
;         const unsigned old = xb_add(&bar[XB_XSUB(b.x)], 1u);
.LBB0_2482:
	s_setprio 0
	s_cmp_gt_i32 s35, 15
	s_cselect_b64 s[2:3], -1, 0
	s_and_b64 s[0:1], s[6:7], s[2:3]
	s_andn2_b64 vcc, exec, s[0:1]
	s_cbranch_vccnz .LBB0_2536
	v_mov_b32_e32 v0, 0
	s_waitcnt vmcnt(0)
	s_waitcnt vmcnt(0) lgkmcnt(0)
	s_barrier
	s_nop 0
	v_mbcnt_lo_u32_b32 v0, -1, v0
	v_mbcnt_hi_u32_b32 v0, -1, v0
	v_or_b32_e32 v0, s33, v0
	v_cmp_eq_u32_e32 vcc, 0, v0
	s_and_saveexec_b64 s[4:5], vcc
	s_cbranch_execz .LBB0_2535
	s_add_i32 s0, 0, 0x27f68
	v_mov_b32_e32 v0, s0
	s_waitcnt vmcnt(0) expcnt(0) lgkmcnt(0)
	ds_read_b32 v2, v0
	s_add_i32 s0, 0, 0x27f6c
	v_mov_b32_e32 v0, s0
	ds_read_b32 v0, v0
	s_waitcnt lgkmcnt(1)
	v_cmp_ne_u32_e32 vcc, 0, v2
	s_cbranch_vccnz .LBB0_2499
	s_add_u32 s6, s10, 0x1000
	s_addc_u32 s7, s11, 0
	s_add_u32 s12, s10, 0x1100
	s_addc_u32 s13, s11, 0
	s_add_u32 s44, s10, 0x1200
	s_addc_u32 s45, s11, 0
	s_add_u32 s46, s10, 0x1300
	s_addc_u32 s47, s11, 0
	s_mov_b32 s0, 1
	v_mov_b32_e32 v16, 0
	s_branch .LBB0_2487

; #define PG8_STAGE(bufoff, gbase, voff) do { _Pragma("unroll") for (int _i = 0; _i < 2; ++_i) \
;         __builtin_amdgcn_global_load_lds((const unsigned*)((const char*)(gbase) + (voff)[_i]), (PG8_LAS unsigned*)(lds + (bufoff) + ldsw + _i * 8192), 16, 0, 0); } while (0)
; #define PG8_WAIT_V(n) asm volatile("s_waitcnt vmcnt(" #n ")" ::: "memory")
; #define PG8_BAR __builtin_amdgcn_s_barrier()
; template <class Epi, class Sched, bool ALIGN_EPI = false, bool SP2 = false, bool A_TILED = false>
; __device__ __forceinline__ void gemm_phase(PG8_LAS unsigned char* lds, const Gemm g, const Sched& S, const Epi& E, const int wave_s) {
;     ...
;     for (int i = 0; i < 2; ++i) { int R, C; stage_rc(tid * 16 + i * 8192, R, C); const int Rb = Epi::PERM ? ((R & ~31) + perm32(R & 31)) : R;
;         voffA[i] = A_TILED ? (unsigned)(tid * 16 + i * 8192) : (unsigned)(R * K + C) * 2u; voffB[i] = (unsigned)(Rb * K + C) * 2u; }
;     const size_t kstep = (size_t)(BK * 2);
;     const size_t hstep = (size_t)HALF * K * 2;
;     const size_t tstep = 2 * hstep;
;     const size_t kstepA = A_TILED ? (size_t)32768 : kstep, hstepA = A_TILED ? (size_t)16384 : hstep, tstepA = A_TILED ? (size_t)nt * 32768 : tstep;
;     const unsigned ldsw = (unsigned)wid * 1024u;
;     const int aoff = lds_byte(wr * 64 + fr, fq * 8), boff = lds_byte(wc * 32 + fr, fq * 8);
;     ...
;     if constexpr (SP2) {
;         PG8_STAGE(PG8_SB(0, 0), cB, voffB); PG8_STAGE(PG8_SB(0, 1), cB + hstep, voffB); PG8_STAGE(PG8_SA(0, 0), cA, voffA); PG8_STAGE(PG8_SA(0, 1), cA + hstepA, voffA);
;         if (wr == 1) PG8_BAR;
;         PG8_WAIT_V(2); PG8_BAR;
;         PG8_STAGE(PG8_SB(1, 0), cB + kstep, voffB); PG8_STAGE(PG8_SA(1, 0), cA + kstepA, voffA); PG8_STAGE(PG8_SB(1, 1), cB + hstep + kstep, voffB);
;         PG8_WAIT_V(6); PG8_BAR;
;     } else {
;         PG8_STAGE(PG8_SB(0, 0), cB, voffB); PG8_STAGE(PG8_SA(0, 0), cA, voffA); PG8_STAGE(PG8_SB(0, 1), cB + hstep, voffB); PG8_STAGE(PG8_SA(0, 1), cA + hstepA, voffA);
;         if (wr == 1) PG8_BAR;
;         PG8_WAIT_V(4); PG8_BAR;
;         PG8_STAGE(PG8_SB(1, 0), cB + kstep, voffB); PG8_STAGE(PG8_SA(1, 0), cA + kstepA, voffA); PG8_STAGE(PG8_SB(1, 1), cB + hstep + kstep, voffB);
;         PG8_WAIT_V(6); PG8_BAR;
;     }
.LBB0_2540:
	s_sext_i32_i8 s5, s2
	s_mul_i32 s2, s96, 0x7800000
	s_add_u32 s2, s12, s2
	s_addc_u32 s44, s13, 0
	s_add_u32 s60, s2, 0x24600000
	s_addc_u32 s61, s44, 0
	v_and_b32_e32 v15, 48, v14
	v_lshlrev_b32_e32 v16, 6, v14
	s_movk_i32 s44, 0x3c0
	v_lshlrev_b32_e32 v14, 2, v14
	s_lshl_b32 s2, s50, 13
	v_and_or_b32 v15, v16, s44, v15
	v_and_b32_e32 v14, 32, v14
	v_bitop3_b32 v16, v15, s2, v14 bitop3:0xde
	s_lshl_b32 s2, s8, 5
	s_mov_b64 s[62:63], 0x80
	s_lshl_b32 s49, s50, 6
	s_and_b32 s50, s2, 0x60
	s_add_i32 m0, s38, 0x18000
	v_lshl_add_u64 v[6:7], v[6:7], 0, s[62:63]
	s_lshl_b32 s2, s50, 7
	s_waitcnt vmcnt(2)
	s_barrier
	global_load_lds_dwordx4 v[6:7], off
	v_lshl_add_u64 v[4:5], v[4:5], 0, s[62:63]
	s_add_i32 m0, s38, 0x1a000
	s_add_i32 s51, s38, 0x8000
	s_add_i32 s52, s38, 0xa000
	global_load_lds_dwordx4 v[4:5], off
	v_lshl_add_u64 v[0:1], v[0:1], 0, s[62:63]
	s_mov_b32 m0, s51
	s_add_u32 s54, s78, 0x20080
	global_load_lds_dwordx4 v[0:1], off
	v_lshl_add_u64 v[0:1], v[2:3], 0, s[62:63]
	s_mov_b32 m0, s52
	s_addc_u32 s55, s79, 0
	global_load_lds_dwordx4 v[0:1], off
	s_add_i32 m0, s38, 0x1c000
	v_lshl_add_u64 v[0:1], s[54:55], 0, v[128:129]
	global_load_lds_dwordx4 v128, s[54:55]
	v_lshl_add_u64 v[0:1], s[54:55], 0, v[130:131]
	s_add_i32 m0, s38, 0x1e000
	s_cmpk_lt_u32 s3, 0x100
	global_load_lds_dwordx4 v130, s[54:55]
	v_lshlrev_b32_e32 v0, 13, v8
	v_and_b32_e32 v0, 0xffffc000, v0
	v_lshl_add_u32 v0, v9, 10, v0
	v_and_b32_e32 v1, 1, v8
	v_lshl_or_b32 v0, v1, 6, v0
	v_lshl_add_u32 v136, v10, 1, v0
	v_lshlrev_b32_e32 v0, 13, v12
	v_and_b32_e32 v0, 0xffffc000, v0
	s_waitcnt vmcnt(6)
	s_mov_b32 s98, 0
	v_lshl_add_u32 v0, v11, 10, v0
	v_and_b32_e32 v1, 1, v12
	v_bitop3_b32 v148, s2, v15, v14 bitop3:0xf6
	s_cselect_b64 s[64:65], -1, 0
	s_bitcmp1_b32 s33, 8
	s_cbranch_scc1 .Lsp_10
	s_setprio 1
.Lsp_10:
	v_lshl_or_b32 v0, v1, 6, v0
	s_add_i32 s53, 0, 0x10000
	s_add_i32 s54, 0, 0x14000
	s_mov_b32 s48, 0
	v_mov_b32_e32 v137, v129
	v_lshl_add_u32 v138, v13, 1, v0
	v_mov_b32_e32 v139, v129
	v_add_u32_e32 v149, s53, v148
	v_add_u32_e32 v150, s54, v148
	v_add_u32_e32 v151, 0, v16
	s_mov_b64 s[66:67], 0x100
	s_mov_b64 s[68:69], 0x180
	s_mov_b32 s55, 0xc2fc0000
	s_movk_i32 s56, 0x7f
	s_movk_i32 s57, 0x1800
	v_mov_b32_e32 v152, 0x42800000
	v_not_b32_e32 v153, 63
	s_barrier
	s_branch .LBB0_2543

; template <class Epi, class Sched, bool ALIGN_EPI = false, bool SP2 = false, bool A_TILED = false>
; __device__ __forceinline__ void gemm_phase(PG8_LAS unsigned char* lds, const Gemm g, const Sched& S, const Epi& E, const int wave_s) {
;     ...
;         constexpr bool PEEL = SP2 && !Epi::AFTER_DRAIN;
;         if constexpr (PEEL) {
;             const char* a1 = cA + kstepA; const char* a2 = cA + 2 * kstepA; const char* b2 = cB + 2 * kstep; const char* a3 = a2 + kstepA; const char* b3 = b2 + kstep;
;             PG8_ITER(PG8_MMAZ)
.Lpw_11:
	s_barrier
	v_mfma_f32_16x16x32_bf16 v[88:91], v[0:3], v[56:59], 0
	v_mfma_f32_16x16x32_bf16 v[64:67], v[0:3], v[32:35], 0
	v_mfma_f32_16x16x32_bf16 v[68:71], v[8:11], v[32:35], 0
	v_mfma_f32_16x16x32_bf16 v[72:75], v[0:3], v[40:43], 0
	v_mfma_f32_16x16x32_bf16 v[76:79], v[8:11], v[40:43], 0
	v_mfma_f32_16x16x32_bf16 v[80:83], v[0:3], v[48:51], 0
	v_mfma_f32_16x16x32_bf16 v[84:87], v[8:11], v[48:51], 0
	v_mfma_f32_16x16x32_bf16 v[96:99], v[4:7], v[60:63], v[88:91]
	v_mfma_f32_16x16x32_bf16 v[88:91], v[8:11], v[56:59], 0
	v_mfma_f32_16x16x32_bf16 v[64:67], v[4:7], v[36:39], v[64:67]
	v_mfma_f32_16x16x32_bf16 v[68:71], v[12:15], v[36:39], v[68:71]
	v_mfma_f32_16x16x32_bf16 v[72:75], v[4:7], v[44:47], v[72:75]
	v_mfma_f32_16x16x32_bf16 v[76:79], v[12:15], v[44:47], v[76:79]
	v_mfma_f32_16x16x32_bf16 v[80:83], v[4:7], v[52:55], v[80:83]
	v_mfma_f32_16x16x32_bf16 v[84:87], v[12:15], v[52:55], v[84:87]
	v_mfma_f32_16x16x32_bf16 v[100:103], v[12:15], v[60:63], v[88:91]
	v_mfma_f32_16x16x32_bf16 v[88:91], v[16:19], v[32:35], 0
	v_mfma_f32_16x16x32_bf16 v[32:35], v[24:27], v[32:35], 0
	v_mfma_f32_16x16x32_bf16 v[112:115], v[20:23], v[36:39], v[88:91]
	v_mfma_f32_16x16x32_bf16 v[32:35], v[28:31], v[36:39], v[32:35]
	v_mfma_f32_16x16x32_bf16 v[36:39], v[16:19], v[40:43], 0
	v_mfma_f32_16x16x32_bf16 v[40:43], v[24:27], v[40:43], 0
	v_mfma_f32_16x16x32_bf16 v[36:39], v[20:23], v[44:47], v[36:39]
	v_mfma_f32_16x16x32_bf16 v[40:43], v[28:31], v[44:47], v[40:43]
	v_mfma_f32_16x16x32_bf16 v[44:47], v[16:19], v[48:51], 0
	v_mfma_f32_16x16x32_bf16 v[48:51], v[24:27], v[48:51], 0
	v_mfma_f32_16x16x32_bf16 v[44:47], v[20:23], v[52:55], v[44:47]
	v_mfma_f32_16x16x32_bf16 v[48:51], v[28:31], v[52:55], v[48:51]
	v_mfma_f32_16x16x32_bf16 v[52:55], v[16:19], v[56:59], 0
	v_mfma_f32_16x16x32_bf16 v[56:59], v[24:27], v[56:59], 0
	v_mfma_f32_16x16x32_bf16 v[52:55], v[20:23], v[60:63], v[52:55]
	v_mfma_f32_16x16x32_bf16 v[56:59], v[28:31], v[60:63], v[56:59]
	s_barrier
	s_add_i32 s90, s53, s37
	v_lshl_add_u64 v[250:251], s[78:79], 0, v[128:129]
	s_add_i32 s91, s90, 0x2000
	v_lshl_add_u64 v[144:145], v[250:251], 0, s[66:67]
	s_mov_b32 m0, s90
	v_lshl_add_u64 v[252:253], s[78:79], 0, v[130:131]
	s_add_u32 s82, s78, 0x20100
	ds_read_b128 v[60:63], v151 offset:16384
	ds_read_b128 v[88:91], v151 offset:17408
	ds_read_b128 v[92:95], v151 offset:18432
	ds_read_b128 v[104:107], v151 offset:19456
	ds_read_b128 v[108:111], v151 offset:20480
	ds_read_b128 v[116:119], v151 offset:21504
	ds_read_b128 v[120:123], v151 offset:22528
	ds_read_b128 v[124:127], v151 offset:23552
	global_load_lds_dwordx4 v[144:145], off
	v_lshl_add_u64 v[144:145], v[252:253], 0, s[66:67]
	s_mov_b32 m0, s91
	s_addc_u32 s83, s79, 0
	s_add_i32 s93, s54, s37
	global_load_lds_dwordx4 v[144:145], off
	v_lshl_add_u64 v[144:145], s[82:83], 0, v[128:129]
	s_mov_b32 m0, s93
	s_add_i32 s95, s93, 0x2000
	global_load_lds_dwordx4 v128, s[82:83]
	v_lshl_add_u64 v[144:145], s[82:83], 0, v[130:131]
	s_mov_b32 m0, s95
	v_lshl_add_u64 v[140:141], s[80:81], 0, v[134:135]
	global_load_lds_dwordx4 v130, s[82:83]
	v_lshl_add_u64 v[144:145], v[140:141], 0, s[66:67]
	s_mov_b32 m0, s38
	v_lshl_add_u64 v[142:143], s[80:81], 0, v[132:133]
	global_load_lds_dwordx4 v[144:145], off
	v_lshl_add_u64 v[144:145], v[142:143], 0, s[66:67]
	s_mov_b32 m0, s39
	s_nop 0
	global_load_lds_dwordx4 v[144:145], off
	s_waitcnt vmcnt(24) lgkmcnt(0)
	s_cmp_lg_u32 s98, 0
	s_cbranch_scc1 .Lpw_12
	s_waitcnt vmcnt(8)
.Lpw_12:
	s_barrier
	v_mfma_f32_16x16x32_bf16 v[144:147], v[0:3], v[60:63], 0
	v_mfma_f32_16x16x32_bf16 v[154:157], v[4:7], v[88:91], v[144:147]
	v_mfma_f32_16x16x32_bf16 v[144:147], v[8:11], v[60:63], 0
	v_mfma_f32_16x16x32_bf16 v[158:161], v[12:15], v[88:91], v[144:147]
	v_mfma_f32_16x16x32_bf16 v[144:147], v[0:3], v[92:95], 0
	v_mfma_f32_16x16x32_bf16 v[162:165], v[4:7], v[104:107], v[144:147]
	v_mfma_f32_16x16x32_bf16 v[144:147], v[8:11], v[92:95], 0
	v_mfma_f32_16x16x32_bf16 v[166:169], v[12:15], v[104:107], v[144:147]
	v_mfma_f32_16x16x32_bf16 v[144:147], v[0:3], v[108:111], 0
	v_mfma_f32_16x16x32_bf16 v[0:3], v[0:3], v[120:123], 0
	v_mfma_f32_16x16x32_bf16 v[170:173], v[4:7], v[116:119], v[144:147]
	v_mfma_f32_16x16x32_bf16 v[0:3], v[4:7], v[124:127], v[0:3]
	v_mfma_f32_16x16x32_bf16 v[4:7], v[8:11], v[120:123], 0
	v_mfma_f32_16x16x32_bf16 v[144:147], v[8:11], v[108:111], 0
	v_mfma_f32_16x16x32_bf16 v[4:7], v[12:15], v[124:127], v[4:7]
	v_mfma_f32_16x16x32_bf16 v[174:177], v[12:15], v[116:119], v[144:147]
	v_mfma_f32_16x16x32_bf16 v[8:11], v[16:19], v[60:63], 0
	v_mfma_f32_16x16x32_bf16 v[178:181], v[20:23], v[88:91], v[8:11]
	v_mfma_f32_16x16x32_bf16 v[8:11], v[24:27], v[60:63], 0
	v_mfma_f32_16x16x32_bf16 v[182:185], v[28:31], v[88:91], v[8:11]
	v_mfma_f32_16x16x32_bf16 v[8:11], v[16:19], v[92:95], 0
	v_mfma_f32_16x16x32_bf16 v[186:189], v[20:23], v[104:107], v[8:11]
	v_mfma_f32_16x16x32_bf16 v[8:11], v[24:27], v[92:95], 0
	v_mfma_f32_16x16x32_bf16 v[190:193], v[28:31], v[104:107], v[8:11]
	v_mfma_f32_16x16x32_bf16 v[8:11], v[16:19], v[108:111], 0
	v_mfma_f32_16x16x32_bf16 v[194:197], v[20:23], v[116:119], v[8:11]
	v_mfma_f32_16x16x32_bf16 v[8:11], v[24:27], v[108:111], 0
	v_mfma_f32_16x16x32_bf16 v[198:201], v[28:31], v[116:119], v[8:11]
	v_mfma_f32_16x16x32_bf16 v[8:11], v[16:19], v[120:123], 0
	v_mfma_f32_16x16x32_bf16 v[202:205], v[20:23], v[124:127], v[8:11]
	v_mfma_f32_16x16x32_bf16 v[8:11], v[24:27], v[120:123], 0
	v_mfma_f32_16x16x32_bf16 v[206:209], v[28:31], v[124:127], v[8:11]
	s_barrier
; template <class Epi, class Sched, bool ALIGN_EPI = false, bool SP2 = false, bool A_TILED = false>
; __device__ __forceinline__ void gemm_phase(PG8_LAS unsigned char* lds, const Gemm g, const Sched& S, const Epi& E, const int wave_s) {
;     ...
;         for (int t = PEEL ? 2 : 0; t < nt; t += 2) {
;             const bool last = (t == nt - 2);
;             const char* a1 = cA + (size_t)(t + 1) * kstepA;
;             const char* a2 = last ? nA : cA + (size_t)(t + 2) * kstepA; const char* b2 = last ? nB : cB + (size_t)(t + 2) * kstep;
;             const char* a3 = a2 + kstepA; const char* b3 = b2 + kstep;
	s_add_i32 s96, 0, 0x18000
	s_add_i32 vcc_lo, 0, 0x1c000
	v_add_u32_e32 v144, s96, v148
	v_add_u32_e32 v145, vcc_lo, v148
	s_nop 0
	ds_read_b128 v[8:11], v144
	ds_read_b128 v[12:15], v144 offset:1024
	ds_read_b128 v[16:19], v144 offset:2048
	ds_read_b128 v[20:23], v144 offset:3072
	ds_read_b128 v[210:213], v145
	ds_read_b128 v[214:217], v145 offset:1024
	ds_read_b128 v[218:221], v145 offset:2048
	ds_read_b128 v[222:225], v145 offset:3072
	s_add_u32 s82, s80, 0x20100
	s_addc_u32 s83, s81, 0
	s_mov_b32 m0, s40
	v_lshl_add_u64 v[88:89], s[82:83], 0, v[134:135]
	ds_read_b128 v[24:27], v151 offset:32768
	ds_read_b128 v[28:31], v151 offset:33792
	ds_read_b128 v[60:63], v151 offset:34816
	ds_read_b128 v[226:229], v151 offset:35840
	ds_read_b128 v[230:233], v151 offset:36864
	ds_read_b128 v[234:237], v151 offset:37888
	ds_read_b128 v[238:241], v151 offset:38912
	ds_read_b128 v[242:245], v151 offset:39936
	global_load_lds_dwordx4 v134, s[82:83]
	v_lshl_add_u64 v[88:89], s[82:83], 0, v[132:133]
	s_mov_b32 m0, s41
	s_nop 0
	global_load_lds_dwordx4 v132, s[82:83]
	s_waitcnt vmcnt(8) lgkmcnt(0)
	s_barrier
	v_mfma_f32_16x16x32_bf16 v[64:67], v[8:11], v[24:27], v[64:67]
	v_mfma_f32_16x16x32_bf16 v[124:127], v[12:15], v[28:31], v[64:67]
	v_mfma_f32_16x16x32_bf16 v[64:67], v[16:19], v[24:27], v[68:71]
	v_mfma_f32_16x16x32_bf16 v[120:123], v[20:23], v[28:31], v[64:67]
	v_mfma_f32_16x16x32_bf16 v[64:67], v[8:11], v[60:63], v[72:75]
	v_mfma_f32_16x16x32_bf16 v[108:111], v[12:15], v[226:229], v[64:67]
	v_mfma_f32_16x16x32_bf16 v[64:67], v[16:19], v[60:63], v[76:79]
	v_mfma_f32_16x16x32_bf16 v[104:107], v[20:23], v[226:229], v[64:67]
	v_mfma_f32_16x16x32_bf16 v[64:67], v[8:11], v[230:233], v[80:83]
	v_mfma_f32_16x16x32_bf16 v[92:95], v[12:15], v[234:237], v[64:67]
	v_mfma_f32_16x16x32_bf16 v[64:67], v[16:19], v[230:233], v[84:87]
	v_mfma_f32_16x16x32_bf16 v[88:91], v[20:23], v[234:237], v[64:67]
	v_mfma_f32_16x16x32_bf16 v[64:67], v[8:11], v[238:241], v[96:99]
	v_mfma_f32_16x16x32_bf16 v[76:79], v[12:15], v[242:245], v[64:67]
	v_mfma_f32_16x16x32_bf16 v[64:67], v[16:19], v[238:241], v[100:103]
	v_mfma_f32_16x16x32_bf16 v[72:75], v[20:23], v[242:245], v[64:67]
	v_mfma_f32_16x16x32_bf16 v[64:67], v[210:213], v[24:27], v[112:115]
	v_mfma_f32_16x16x32_bf16 v[24:27], v[218:221], v[24:27], v[32:35]
	v_mfma_f32_16x16x32_bf16 v[112:115], v[222:225], v[28:31], v[24:27]
	v_mfma_f32_16x16x32_bf16 v[24:27], v[210:213], v[60:63], v[36:39]
	v_mfma_f32_16x16x32_bf16 v[100:103], v[214:217], v[226:229], v[24:27]
	v_mfma_f32_16x16x32_bf16 v[24:27], v[218:221], v[60:63], v[40:43]
	v_mfma_f32_16x16x32_bf16 v[96:99], v[222:225], v[226:229], v[24:27]
	v_mfma_f32_16x16x32_bf16 v[24:27], v[210:213], v[230:233], v[44:47]
	v_mfma_f32_16x16x32_bf16 v[84:87], v[214:217], v[234:237], v[24:27]
	v_mfma_f32_16x16x32_bf16 v[24:27], v[218:221], v[230:233], v[48:51]
	v_mfma_f32_16x16x32_bf16 v[80:83], v[222:225], v[234:237], v[24:27]
	v_mfma_f32_16x16x32_bf16 v[24:27], v[210:213], v[238:241], v[52:55]
	v_mfma_f32_16x16x32_bf16 v[68:71], v[214:217], v[242:245], v[24:27]
	v_mfma_f32_16x16x32_bf16 v[24:27], v[218:221], v[238:241], v[56:59]
	v_mfma_f32_16x16x32_bf16 v[116:119], v[214:217], v[28:31], v[64:67]
	v_mfma_f32_16x16x32_bf16 v[64:67], v[222:225], v[242:245], v[24:27]
	s_barrier
	s_add_i32 s96, s96, s37
	s_add_i32 s97, s96, 0x2000
	s_nop 1
	v_lshl_add_u64 v[24:25], v[250:251], 0, s[68:69]
	s_mov_b32 m0, s96
	s_add_u32 s82, s78, 0x20180
	ds_read_b128 v[32:35], v151 offset:49152
	ds_read_b128 v[36:39], v151 offset:50176
	ds_read_b128 v[226:229], v151 offset:51200
	ds_read_b128 v[230:233], v151 offset:52224
	ds_read_b128 v[234:237], v151 offset:53248
	ds_read_b128 v[238:241], v151 offset:54272
	ds_read_b128 v[242:245], v151 offset:55296
	ds_read_b128 v[246:249], v151 offset:56320
	global_load_lds_dwordx4 v[24:25], off
	v_lshl_add_u64 v[24:25], v[252:253], 0, s[68:69]
	s_mov_b32 m0, s97
	s_addc_u32 s83, s79, 0
	s_add_i32 vcc_lo, vcc_lo, s37
	global_load_lds_dwordx4 v[24:25], off
	v_lshl_add_u64 v[24:25], s[82:83], 0, v[128:129]
	s_mov_b32 m0, vcc_lo
	s_add_i32 vcc_hi, vcc_lo, 0x2000
	global_load_lds_dwordx4 v128, s[82:83]
	v_lshl_add_u64 v[24:25], s[82:83], 0, v[130:131]
	s_mov_b32 m0, vcc_hi
	s_nop 0
	global_load_lds_dwordx4 v130, s[82:83]
	v_lshl_add_u64 v[24:25], v[140:141], 0, s[68:69]
	s_mov_b32 m0, s51
	s_nop 0
	global_load_lds_dwordx4 v[24:25], off
	v_lshl_add_u64 v[24:25], v[142:143], 0, s[68:69]
	s_mov_b32 m0, s52
	s_nop 0
	global_load_lds_dwordx4 v[24:25], off
	s_waitcnt vmcnt(8) lgkmcnt(0)
	s_barrier
	v_mfma_f32_16x16x32_bf16 v[24:27], v[8:11], v[32:35], v[154:157]
	v_mfma_f32_16x16x32_bf16 v[60:63], v[12:15], v[36:39], v[24:27]
	v_mfma_f32_16x16x32_bf16 v[24:27], v[16:19], v[32:35], v[158:161]
	v_mfma_f32_16x16x32_bf16 v[56:59], v[20:23], v[36:39], v[24:27]
	v_mfma_f32_16x16x32_bf16 v[24:27], v[8:11], v[226:229], v[162:165]
	v_mfma_f32_16x16x32_bf16 v[44:47], v[12:15], v[230:233], v[24:27]
	v_mfma_f32_16x16x32_bf16 v[24:27], v[16:19], v[226:229], v[166:169]
	v_mfma_f32_16x16x32_bf16 v[40:43], v[20:23], v[230:233], v[24:27]
	v_mfma_f32_16x16x32_bf16 v[24:27], v[8:11], v[234:237], v[170:173]
	v_mfma_f32_16x16x32_bf16 v[0:3], v[8:11], v[242:245], v[0:3]
	v_mfma_f32_16x16x32_bf16 v[28:31], v[12:15], v[238:241], v[24:27]
	v_mfma_f32_16x16x32_bf16 v[24:27], v[16:19], v[234:237], v[174:177]
	v_mfma_f32_16x16x32_bf16 v[12:15], v[12:15], v[246:249], v[0:3]
	v_mfma_f32_16x16x32_bf16 v[0:3], v[16:19], v[242:245], v[4:7]
	v_mfma_f32_16x16x32_bf16 v[24:27], v[20:23], v[238:241], v[24:27]
	v_mfma_f32_16x16x32_bf16 v[8:11], v[20:23], v[246:249], v[0:3]
	v_mfma_f32_16x16x32_bf16 v[0:3], v[210:213], v[32:35], v[178:181]
	v_mfma_f32_16x16x32_bf16 v[52:55], v[214:217], v[36:39], v[0:3]
	v_mfma_f32_16x16x32_bf16 v[0:3], v[218:221], v[32:35], v[182:185]
	v_mfma_f32_16x16x32_bf16 v[48:51], v[222:225], v[36:39], v[0:3]
	v_mfma_f32_16x16x32_bf16 v[0:3], v[210:213], v[226:229], v[186:189]
	v_mfma_f32_16x16x32_bf16 v[36:39], v[214:217], v[230:233], v[0:3]
	v_mfma_f32_16x16x32_bf16 v[0:3], v[218:221], v[226:229], v[190:193]
	v_mfma_f32_16x16x32_bf16 v[32:35], v[222:225], v[230:233], v[0:3]
	v_mfma_f32_16x16x32_bf16 v[0:3], v[210:213], v[234:237], v[194:197]
	v_mfma_f32_16x16x32_bf16 v[20:23], v[214:217], v[238:241], v[0:3]
	v_mfma_f32_16x16x32_bf16 v[0:3], v[218:221], v[234:237], v[198:201]
	v_mfma_f32_16x16x32_bf16 v[16:19], v[222:225], v[238:241], v[0:3]
	v_mfma_f32_16x16x32_bf16 v[0:3], v[210:213], v[242:245], v[202:205]
	v_mfma_f32_16x16x32_bf16 v[4:7], v[214:217], v[246:249], v[0:3]
	v_mfma_f32_16x16x32_bf16 v[0:3], v[218:221], v[242:245], v[206:209]
	v_mfma_f32_16x16x32_bf16 v[0:3], v[222:225], v[246:249], v[0:3]
	s_barrier
	s_add_u32 s85, s78, 0x200
	s_addc_u32 s8, s79, 0
	s_add_u32 s78, s80, 0x20180
	s_addc_u32 s79, s81, 0
	s_mov_b32 s94, 0
; #define PG8_MMA(ai, bj, At, Bt) do { __builtin_amdgcn_s_setprio(1); _Pragma("unroll") for (int m = 0; m < 4; ++m) _Pragma("unroll") for (int n = 0; n < 2; ++n) _Pragma("unroll") for (int k = 0; k < 2; ++k) \
;         acc[ai][bj][m][n] = __builtin_amdgcn_mfma_f32_16x16x32_bf16(Bt[n][k], At[m][k], acc[ai][bj][m][n], 0, 0, 0); __builtin_amdgcn_s_setprio(0); } while (0)
; template <class Epi, class Sched, bool ALIGN_EPI = false, bool SP2 = false, bool A_TILED = false>
; __device__ __forceinline__ void gemm_phase(PG8_LAS unsigned char* lds, const Gemm g, const Sched& S, const Epi& E, const int wave_s) {
;     ...
;         for (int t = PEEL ? 2 : 0; t < nt; t += 2) {
;             const bool last = (t == nt - 2);
;             const char* a1 = cA + (size_t)(t + 1) * kstepA;
;             const char* a2 = last ? nA : cA + (size_t)(t + 2) * kstepA; const char* b2 = last ? nB : cB + (size_t)(t + 2) * kstep;
;             const char* a3 = a2 + kstepA; const char* b3 = b2 + kstep;
;             if (last && has_next) S.a_ready(nxt);
;             if constexpr (SP2) {
;             PG8_ITER(PG8_MMA)
.LBB0_2546:
	ds_read_b128 v[154:157], v149
	ds_read_b128 v[158:161], v149 offset:1024
	ds_read_b128 v[162:165], v149 offset:2048
	ds_read_b128 v[166:169], v149 offset:3072
	ds_read_b128 v[170:173], v150
	ds_read_b128 v[174:177], v150 offset:1024
	ds_read_b128 v[178:181], v150 offset:2048
	ds_read_b128 v[182:185], v150 offset:3072
	s_add_u32 s44, s78, 0xfffe0080
	s_addc_u32 s45, s79, -1
	s_cmp_eq_u32 s94, 4
	s_cselect_b32 s83, s58, s45
	s_cselect_b32 s82, s59, s44
	s_cselect_b32 s81, s71, s8
	s_cselect_b32 s80, s73, s85
	s_mov_b32 m0, s88
	v_lshl_add_u64 v[140:141], s[78:79], 0, v[138:139]
	ds_read_b128 v[186:189], v151
	ds_read_b128 v[190:193], v151 offset:1024
	ds_read_b128 v[194:197], v151 offset:2048
	ds_read_b128 v[198:201], v151 offset:3072
	ds_read_b128 v[202:205], v151 offset:4096
	ds_read_b128 v[206:209], v151 offset:5120
	ds_read_b128 v[210:213], v151 offset:6144
	ds_read_b128 v[214:217], v151 offset:7168
	global_load_lds_dwordx4 v138, s[78:79]
	v_lshl_add_u64 v[140:141], s[78:79], 0, v[136:137]
	s_mov_b32 m0, s89
	s_nop 0
	global_load_lds_dwordx4 v136, s[78:79]
	s_waitcnt vmcnt(8) lgkmcnt(0)
	s_barrier
	v_mfma_f32_16x16x32_bf16 v[124:127], v[154:157], v[186:189], v[124:127]
	v_mfma_f32_16x16x32_bf16 v[120:123], v[162:165], v[186:189], v[120:123]
	v_mfma_f32_16x16x32_bf16 v[108:111], v[154:157], v[194:197], v[108:111]
	v_mfma_f32_16x16x32_bf16 v[104:107], v[162:165], v[194:197], v[104:107]
	v_mfma_f32_16x16x32_bf16 v[92:95], v[154:157], v[202:205], v[92:95]
	v_mfma_f32_16x16x32_bf16 v[88:91], v[162:165], v[202:205], v[88:91]
	v_mfma_f32_16x16x32_bf16 v[76:79], v[154:157], v[210:213], v[76:79]
	v_mfma_f32_16x16x32_bf16 v[72:75], v[162:165], v[210:213], v[72:75]
	v_mfma_f32_16x16x32_bf16 v[124:127], v[158:161], v[190:193], v[124:127]
	v_mfma_f32_16x16x32_bf16 v[120:123], v[166:169], v[190:193], v[120:123]
	v_mfma_f32_16x16x32_bf16 v[108:111], v[158:161], v[198:201], v[108:111]
	v_mfma_f32_16x16x32_bf16 v[104:107], v[166:169], v[198:201], v[104:107]
	v_mfma_f32_16x16x32_bf16 v[92:95], v[158:161], v[206:209], v[92:95]
	v_mfma_f32_16x16x32_bf16 v[88:91], v[166:169], v[206:209], v[88:91]
	v_mfma_f32_16x16x32_bf16 v[76:79], v[158:161], v[214:217], v[76:79]
	v_mfma_f32_16x16x32_bf16 v[72:75], v[166:169], v[214:217], v[72:75]
	v_mfma_f32_16x16x32_bf16 v[116:119], v[170:173], v[186:189], v[116:119]
	v_mfma_f32_16x16x32_bf16 v[112:115], v[178:181], v[186:189], v[112:115]
	v_mfma_f32_16x16x32_bf16 v[100:103], v[170:173], v[194:197], v[100:103]
	v_mfma_f32_16x16x32_bf16 v[96:99], v[178:181], v[194:197], v[96:99]
	v_mfma_f32_16x16x32_bf16 v[84:87], v[170:173], v[202:205], v[84:87]
	v_mfma_f32_16x16x32_bf16 v[80:83], v[178:181], v[202:205], v[80:83]
	v_mfma_f32_16x16x32_bf16 v[68:71], v[170:173], v[210:213], v[68:71]
	v_mfma_f32_16x16x32_bf16 v[64:67], v[178:181], v[210:213], v[64:67]
	v_mfma_f32_16x16x32_bf16 v[116:119], v[174:177], v[190:193], v[116:119]
	v_mfma_f32_16x16x32_bf16 v[112:115], v[182:185], v[190:193], v[112:115]
	v_mfma_f32_16x16x32_bf16 v[100:103], v[174:177], v[198:201], v[100:103]
	v_mfma_f32_16x16x32_bf16 v[96:99], v[182:185], v[198:201], v[96:99]
	v_mfma_f32_16x16x32_bf16 v[84:87], v[174:177], v[206:209], v[84:87]
	v_mfma_f32_16x16x32_bf16 v[80:83], v[182:185], v[206:209], v[80:83]
	v_mfma_f32_16x16x32_bf16 v[68:71], v[174:177], v[214:217], v[68:71]
	v_mfma_f32_16x16x32_bf16 v[64:67], v[182:185], v[214:217], v[64:67]
	s_barrier
	s_mov_b32 m0, s90
	v_lshl_add_u64 v[140:141], s[80:81], 0, v[128:129]
	s_add_u32 s44, s80, 0x20000
	ds_read_b128 v[186:189], v151 offset:16384
	ds_read_b128 v[190:193], v151 offset:17408
	ds_read_b128 v[194:197], v151 offset:18432
	ds_read_b128 v[198:201], v151 offset:19456
	ds_read_b128 v[202:205], v151 offset:20480
	ds_read_b128 v[206:209], v151 offset:21504
	ds_read_b128 v[210:213], v151 offset:22528
	ds_read_b128 v[214:217], v151 offset:23552
	global_load_lds_dwordx4 v128, s[80:81]
	v_lshl_add_u64 v[142:143], s[80:81], 0, v[130:131]
	s_mov_b32 m0, s91
	s_addc_u32 s45, s81, 0
	global_load_lds_dwordx4 v130, s[80:81]
	v_lshl_add_u64 v[146:147], s[44:45], 0, v[128:129]
	s_mov_b32 m0, s93
	v_lshl_add_u64 v[218:219], s[82:83], 0, v[132:133]
	global_load_lds_dwordx4 v128, s[44:45]
	v_lshl_add_u64 v[146:147], s[44:45], 0, v[130:131]
	s_mov_b32 m0, s95
	s_nop 0
	global_load_lds_dwordx4 v130, s[44:45]
	v_lshl_add_u64 v[146:147], s[82:83], 0, v[134:135]
	s_mov_b32 m0, s38
	s_nop 0
	global_load_lds_dwordx4 v134, s[82:83]
	s_mov_b32 m0, s39
	s_nop 0
	global_load_lds_dwordx4 v132, s[82:83]
	s_waitcnt vmcnt(8) lgkmcnt(0)
	s_barrier
	v_mfma_f32_16x16x32_bf16 v[60:63], v[154:157], v[186:189], v[60:63]
	v_mfma_f32_16x16x32_bf16 v[56:59], v[162:165], v[186:189], v[56:59]
	v_mfma_f32_16x16x32_bf16 v[44:47], v[154:157], v[194:197], v[44:47]
	v_mfma_f32_16x16x32_bf16 v[40:43], v[162:165], v[194:197], v[40:43]
	v_mfma_f32_16x16x32_bf16 v[28:31], v[154:157], v[202:205], v[28:31]
	v_mfma_f32_16x16x32_bf16 v[24:27], v[162:165], v[202:205], v[24:27]
	v_mfma_f32_16x16x32_bf16 v[12:15], v[154:157], v[210:213], v[12:15]
	v_mfma_f32_16x16x32_bf16 v[8:11], v[162:165], v[210:213], v[8:11]
	v_mfma_f32_16x16x32_bf16 v[60:63], v[158:161], v[190:193], v[60:63]
	v_mfma_f32_16x16x32_bf16 v[56:59], v[166:169], v[190:193], v[56:59]
	v_mfma_f32_16x16x32_bf16 v[44:47], v[158:161], v[198:201], v[44:47]
	v_mfma_f32_16x16x32_bf16 v[40:43], v[166:169], v[198:201], v[40:43]
	v_mfma_f32_16x16x32_bf16 v[28:31], v[158:161], v[206:209], v[28:31]
	v_mfma_f32_16x16x32_bf16 v[24:27], v[166:169], v[206:209], v[24:27]
	v_mfma_f32_16x16x32_bf16 v[12:15], v[158:161], v[214:217], v[12:15]
	v_mfma_f32_16x16x32_bf16 v[8:11], v[166:169], v[214:217], v[8:11]
	v_mfma_f32_16x16x32_bf16 v[52:55], v[170:173], v[186:189], v[52:55]
	v_mfma_f32_16x16x32_bf16 v[48:51], v[178:181], v[186:189], v[48:51]
	v_mfma_f32_16x16x32_bf16 v[36:39], v[170:173], v[194:197], v[36:39]
	v_mfma_f32_16x16x32_bf16 v[32:35], v[178:181], v[194:197], v[32:35]
	v_mfma_f32_16x16x32_bf16 v[20:23], v[170:173], v[202:205], v[20:23]
	v_mfma_f32_16x16x32_bf16 v[16:19], v[178:181], v[202:205], v[16:19]
	v_mfma_f32_16x16x32_bf16 v[4:7], v[170:173], v[210:213], v[4:7]
	v_mfma_f32_16x16x32_bf16 v[0:3], v[178:181], v[210:213], v[0:3]
	v_mfma_f32_16x16x32_bf16 v[52:55], v[174:177], v[190:193], v[52:55]
	v_mfma_f32_16x16x32_bf16 v[48:51], v[182:185], v[190:193], v[48:51]
	v_mfma_f32_16x16x32_bf16 v[36:39], v[174:177], v[198:201], v[36:39]
	v_mfma_f32_16x16x32_bf16 v[32:35], v[182:185], v[198:201], v[32:35]
	v_mfma_f32_16x16x32_bf16 v[20:23], v[174:177], v[206:209], v[20:23]
	v_mfma_f32_16x16x32_bf16 v[16:19], v[182:185], v[206:209], v[16:19]
	v_mfma_f32_16x16x32_bf16 v[4:7], v[174:177], v[214:217], v[4:7]
	v_mfma_f32_16x16x32_bf16 v[0:3], v[182:185], v[214:217], v[0:3]
	s_barrier
	ds_read_b128 v[154:157], v144
	ds_read_b128 v[158:161], v144 offset:1024
	ds_read_b128 v[162:165], v144 offset:2048
	ds_read_b128 v[166:169], v144 offset:3072
	ds_read_b128 v[170:173], v145
	ds_read_b128 v[174:177], v145 offset:1024
	ds_read_b128 v[178:181], v145 offset:2048
	ds_read_b128 v[182:185], v145 offset:3072
	s_add_u32 s44, s82, 0x20000
	s_addc_u32 s45, s83, 0
	s_mov_b32 m0, s40
	v_lshl_add_u64 v[220:221], s[44:45], 0, v[134:135]
	ds_read_b128 v[186:189], v151 offset:32768
	ds_read_b128 v[190:193], v151 offset:33792
	ds_read_b128 v[194:197], v151 offset:34816
	ds_read_b128 v[198:201], v151 offset:35840
	ds_read_b128 v[202:205], v151 offset:36864
	ds_read_b128 v[206:209], v151 offset:37888
	ds_read_b128 v[210:213], v151 offset:38912
	ds_read_b128 v[214:217], v151 offset:39936
	global_load_lds_dwordx4 v134, s[44:45]
	v_lshl_add_u64 v[220:221], s[44:45], 0, v[132:133]
	s_mov_b32 m0, s41
	s_nop 0
	global_load_lds_dwordx4 v132, s[44:45]
	s_waitcnt vmcnt(8) lgkmcnt(0)
	s_barrier
	v_mfma_f32_16x16x32_bf16 v[124:127], v[154:157], v[186:189], v[124:127]
	v_mfma_f32_16x16x32_bf16 v[120:123], v[162:165], v[186:189], v[120:123]
	v_mfma_f32_16x16x32_bf16 v[108:111], v[154:157], v[194:197], v[108:111]
	v_mfma_f32_16x16x32_bf16 v[104:107], v[162:165], v[194:197], v[104:107]
	v_mfma_f32_16x16x32_bf16 v[92:95], v[154:157], v[202:205], v[92:95]
	v_mfma_f32_16x16x32_bf16 v[88:91], v[162:165], v[202:205], v[88:91]
	v_mfma_f32_16x16x32_bf16 v[76:79], v[154:157], v[210:213], v[76:79]
	v_mfma_f32_16x16x32_bf16 v[72:75], v[162:165], v[210:213], v[72:75]
	v_mfma_f32_16x16x32_bf16 v[124:127], v[158:161], v[190:193], v[124:127]
	v_mfma_f32_16x16x32_bf16 v[120:123], v[166:169], v[190:193], v[120:123]
	v_mfma_f32_16x16x32_bf16 v[108:111], v[158:161], v[198:201], v[108:111]
	v_mfma_f32_16x16x32_bf16 v[104:107], v[166:169], v[198:201], v[104:107]
	v_mfma_f32_16x16x32_bf16 v[92:95], v[158:161], v[206:209], v[92:95]
	v_mfma_f32_16x16x32_bf16 v[88:91], v[166:169], v[206:209], v[88:91]
	v_mfma_f32_16x16x32_bf16 v[76:79], v[158:161], v[214:217], v[76:79]
	v_mfma_f32_16x16x32_bf16 v[72:75], v[166:169], v[214:217], v[72:75]
	v_mfma_f32_16x16x32_bf16 v[116:119], v[170:173], v[186:189], v[116:119]
	v_mfma_f32_16x16x32_bf16 v[112:115], v[178:181], v[186:189], v[112:115]
	v_mfma_f32_16x16x32_bf16 v[100:103], v[170:173], v[194:197], v[100:103]
	v_mfma_f32_16x16x32_bf16 v[96:99], v[178:181], v[194:197], v[96:99]
	v_mfma_f32_16x16x32_bf16 v[84:87], v[170:173], v[202:205], v[84:87]
	v_mfma_f32_16x16x32_bf16 v[80:83], v[178:181], v[202:205], v[80:83]
	v_mfma_f32_16x16x32_bf16 v[68:71], v[170:173], v[210:213], v[68:71]
	v_mfma_f32_16x16x32_bf16 v[64:67], v[178:181], v[210:213], v[64:67]
	v_mfma_f32_16x16x32_bf16 v[116:119], v[174:177], v[190:193], v[116:119]
	v_mfma_f32_16x16x32_bf16 v[112:115], v[182:185], v[190:193], v[112:115]
	v_mfma_f32_16x16x32_bf16 v[100:103], v[174:177], v[198:201], v[100:103]
	v_mfma_f32_16x16x32_bf16 v[96:99], v[182:185], v[198:201], v[96:99]
	v_mfma_f32_16x16x32_bf16 v[84:87], v[174:177], v[206:209], v[84:87]
	v_mfma_f32_16x16x32_bf16 v[80:83], v[182:185], v[206:209], v[80:83]
	v_mfma_f32_16x16x32_bf16 v[68:71], v[174:177], v[214:217], v[68:71]
	v_mfma_f32_16x16x32_bf16 v[64:67], v[182:185], v[214:217], v[64:67]
	s_barrier
; #define PG8_STAGE(bufoff, gbase, voff) do { _Pragma("unroll") for (int _i = 0; _i < 2; ++_i) \
;         __builtin_amdgcn_global_load_lds((const unsigned*)((const char*)(gbase) + (voff)[_i]), (PG8_LAS unsigned*)(lds + (bufoff) + ldsw + _i * 8192), 16, 0, 0); } while (0)
; #define PG8_BAR __builtin_amdgcn_s_barrier()
; template <class Epi, class Sched, bool ALIGN_EPI = false, bool SP2 = false, bool A_TILED = false>
; __device__ __forceinline__ void gemm_phase(PG8_LAS unsigned char* lds, const Gemm g, const Sched& S, const Epi& E, const int wave_s) {
;     ...
;         for (int t = PEEL ? 2 : 0; t < nt; t += 2) {
;             const bool last = (t == nt - 2);
;             const char* a1 = cA + (size_t)(t + 1) * kstepA;
;             const char* a2 = last ? nA : cA + (size_t)(t + 2) * kstepA; const char* b2 = last ? nB : cB + (size_t)(t + 2) * kstep;
;             const char* a3 = a2 + kstepA; const char* b3 = b2 + kstep;
;             if (last && has_next) S.a_ready(nxt);
;             if constexpr (SP2) {
;             PG8_ITER(PG8_MMA)
;             } else {
;             PG8_LDB(B0, 0, 0); PG8_SCHED; PG8_LDA(At, 0, 0); PG8_STAGE(PG8_SA(1, 1), a1 + hstepA, voffA);
;             PG8_WAIT_L(8); PG8_BAR; PG8_WAIT_L(0); PG8_MMA(0, 0, At, B0); PG8_BAR; PG8_SCHED;
;             PG8_LDB(B1, 0, 1); PG8_STAGE(PG8_SB(0, 0), b2, voffB);
;             PG8_BAR; PG8_WAIT_L(0); PG8_MMA(0, 1, At, B1); PG8_BAR;
;             PG8_LDA(At, 0, 1); PG8_STAGE(PG8_SA(0, 0), a2, voffA);
;             PG8_BAR; PG8_WAIT_L(0); PG8_MMA(1, 0, At, B0); PG8_BAR; PG8_SCHED;
;             PG8_STAGE(PG8_SB(0, 1), b2 + hstep, voffB);
;             PG8_WAIT_V(6); PG8_BAR; PG8_MMA(1, 1, At, B1); PG8_BAR;
;             PG8_LDB(B0, 1, 0); PG8_SCHED; PG8_LDA(At, 1, 0); PG8_STAGE(PG8_SA(0, 1), a2 + hstepA, voffA);
;             PG8_WAIT_L(8); PG8_BAR; PG8_WAIT_L(0); PG8_MMA(0, 0, At, B0); PG8_BAR; PG8_SCHED;
;             PG8_LDB(B1, 1, 1); PG8_STAGE(PG8_SB(1, 0), b3, voffB);
;             PG8_BAR; PG8_WAIT_L(0); PG8_MMA(0, 1, At, B1); PG8_BAR;
;             PG8_LDA(At, 1, 1); PG8_STAGE(PG8_SA(1, 0), a3, voffA);
;             PG8_BAR; PG8_WAIT_L(0); PG8_MMA(1, 0, At, B0); PG8_BAR; PG8_SCHED;
;             PG8_STAGE(PG8_SB(1, 1), b3 + hstep, voffB);
;             PG8_WAIT_V(6); PG8_BAR; PG8_MMA(1, 1, At, B1); PG8_BAR;
;             }
;         }
;         if constexpr (ALIGN_EPI) { if (wr == 0) PG8_BAR; }
	s_mov_b32 m0, s96
	v_lshl_add_u64 v[140:141], v[140:141], 0, s[62:63]
	s_add_u32 s44, s80, 0x20080
	ds_read_b128 v[186:189], v151 offset:49152
	ds_read_b128 v[190:193], v151 offset:50176
	ds_read_b128 v[194:197], v151 offset:51200
	ds_read_b128 v[198:201], v151 offset:52224
	ds_read_b128 v[202:205], v151 offset:53248
	ds_read_b128 v[206:209], v151 offset:54272
	ds_read_b128 v[210:213], v151 offset:55296
	ds_read_b128 v[214:217], v151 offset:56320
	global_load_lds_dwordx4 v[140:141], off
	v_lshl_add_u64 v[140:141], v[142:143], 0, s[62:63]
	s_mov_b32 m0, s97
	s_addc_u32 s45, s81, 0
	global_load_lds_dwordx4 v[140:141], off
	v_lshl_add_u64 v[140:141], s[44:45], 0, v[128:129]
	s_mov_b32 m0, vcc_lo
	s_nop 0
	global_load_lds_dwordx4 v128, s[44:45]
	v_lshl_add_u64 v[140:141], s[44:45], 0, v[130:131]
	s_mov_b32 m0, vcc_hi
	s_nop 0
	global_load_lds_dwordx4 v130, s[44:45]
	v_lshl_add_u64 v[140:141], v[146:147], 0, s[62:63]
	s_mov_b32 m0, s51
	s_nop 0
	global_load_lds_dwordx4 v[140:141], off
	v_lshl_add_u64 v[140:141], v[218:219], 0, s[62:63]
	s_mov_b32 m0, s52
	s_nop 0
	global_load_lds_dwordx4 v[140:141], off
	s_waitcnt vmcnt(8) lgkmcnt(0)
	s_barrier
	v_mfma_f32_16x16x32_bf16 v[60:63], v[154:157], v[186:189], v[60:63]
	v_mfma_f32_16x16x32_bf16 v[56:59], v[162:165], v[186:189], v[56:59]
	v_mfma_f32_16x16x32_bf16 v[44:47], v[154:157], v[194:197], v[44:47]
	v_mfma_f32_16x16x32_bf16 v[40:43], v[162:165], v[194:197], v[40:43]
	v_mfma_f32_16x16x32_bf16 v[28:31], v[154:157], v[202:205], v[28:31]
	v_mfma_f32_16x16x32_bf16 v[24:27], v[162:165], v[202:205], v[24:27]
	v_mfma_f32_16x16x32_bf16 v[12:15], v[154:157], v[210:213], v[12:15]
	v_mfma_f32_16x16x32_bf16 v[8:11], v[162:165], v[210:213], v[8:11]
	v_mfma_f32_16x16x32_bf16 v[60:63], v[158:161], v[190:193], v[60:63]
	v_mfma_f32_16x16x32_bf16 v[56:59], v[166:169], v[190:193], v[56:59]
	v_mfma_f32_16x16x32_bf16 v[44:47], v[158:161], v[198:201], v[44:47]
	v_mfma_f32_16x16x32_bf16 v[40:43], v[166:169], v[198:201], v[40:43]
	v_mfma_f32_16x16x32_bf16 v[28:31], v[158:161], v[206:209], v[28:31]
	v_mfma_f32_16x16x32_bf16 v[24:27], v[166:169], v[206:209], v[24:27]
	v_mfma_f32_16x16x32_bf16 v[12:15], v[158:161], v[214:217], v[12:15]
	v_mfma_f32_16x16x32_bf16 v[8:11], v[166:169], v[214:217], v[8:11]
	v_mfma_f32_16x16x32_bf16 v[52:55], v[170:173], v[186:189], v[52:55]
	v_mfma_f32_16x16x32_bf16 v[48:51], v[178:181], v[186:189], v[48:51]
	v_mfma_f32_16x16x32_bf16 v[36:39], v[170:173], v[194:197], v[36:39]
	v_mfma_f32_16x16x32_bf16 v[32:35], v[178:181], v[194:197], v[32:35]
	v_mfma_f32_16x16x32_bf16 v[20:23], v[170:173], v[202:205], v[20:23]
	v_mfma_f32_16x16x32_bf16 v[16:19], v[178:181], v[202:205], v[16:19]
	v_mfma_f32_16x16x32_bf16 v[4:7], v[170:173], v[210:213], v[4:7]
	v_mfma_f32_16x16x32_bf16 v[0:3], v[178:181], v[210:213], v[0:3]
	v_mfma_f32_16x16x32_bf16 v[52:55], v[174:177], v[190:193], v[52:55]
	v_mfma_f32_16x16x32_bf16 v[48:51], v[182:185], v[190:193], v[48:51]
	v_mfma_f32_16x16x32_bf16 v[36:39], v[174:177], v[198:201], v[36:39]
	v_mfma_f32_16x16x32_bf16 v[32:35], v[182:185], v[198:201], v[32:35]
	v_mfma_f32_16x16x32_bf16 v[20:23], v[174:177], v[206:209], v[20:23]
	v_mfma_f32_16x16x32_bf16 v[16:19], v[182:185], v[206:209], v[16:19]
	v_mfma_f32_16x16x32_bf16 v[4:7], v[174:177], v[214:217], v[4:7]
	v_mfma_f32_16x16x32_bf16 v[0:3], v[182:185], v[214:217], v[0:3]
	s_barrier
	s_add_i32 s94, s94, 2
	s_add_u32 s85, s85, 0x100
	s_addc_u32 s8, s8, 0
	s_add_u32 s78, s78, 0x100
	s_addc_u32 s79, s79, 0
	s_cmp_gt_u32 s94, 5
	s_cbranch_scc0 .LBB0_2546
	s_and_b64 vcc, exec, s[64:65]
	s_cbranch_vccz .LBB0_2549
	s_barrier

; #define PG8_STAGE(bufoff, gbase, voff) do { _Pragma("unroll") for (int _i = 0; _i < 2; ++_i) \
;         __builtin_amdgcn_global_load_lds((const unsigned*)((const char*)(gbase) + (voff)[_i]), (PG8_LAS unsigned*)(lds + (bufoff) + ldsw + _i * 8192), 16, 0, 0); } while (0)
; #define PG8_WAIT_V(n) asm volatile("s_waitcnt vmcnt(" #n ")" ::: "memory")
; #define PG8_BAR __builtin_amdgcn_s_barrier()
; template <class Epi, class Sched, bool ALIGN_EPI = false, bool SP2 = false, bool A_TILED = false>
; __device__ __forceinline__ void gemm_phase(PG8_LAS unsigned char* lds, const Gemm g, const Sched& S, const Epi& E, const int wave_s) {
;     ...
;     for (int i = 0; i < 2; ++i) { int R, C; stage_rc(tid * 16 + i * 8192, R, C); const int Rb = Epi::PERM ? ((R & ~31) + perm32(R & 31)) : R;
;         voffA[i] = A_TILED ? (unsigned)(tid * 16 + i * 8192) : (unsigned)(R * K + C) * 2u; voffB[i] = (unsigned)(Rb * K + C) * 2u; }
;     const size_t kstep = (size_t)(BK * 2);
;     const size_t hstep = (size_t)HALF * K * 2;
;     const size_t tstep = 2 * hstep;
;     const size_t kstepA = A_TILED ? (size_t)32768 : kstep, hstepA = A_TILED ? (size_t)16384 : hstep, tstepA = A_TILED ? (size_t)nt * 32768 : tstep;
;     const unsigned ldsw = (unsigned)wid * 1024u;
;     const int aoff = lds_byte(wr * 64 + fr, fq * 8), boff = lds_byte(wc * 32 + fr, fq * 8);
;     ...
;     if constexpr (SP2) {
;         PG8_STAGE(PG8_SB(0, 0), cB, voffB); PG8_STAGE(PG8_SB(0, 1), cB + hstep, voffB); PG8_STAGE(PG8_SA(0, 0), cA, voffA); PG8_STAGE(PG8_SA(0, 1), cA + hstepA, voffA);
;         if (wr == 1) PG8_BAR;
;         PG8_WAIT_V(2); PG8_BAR;
;         PG8_STAGE(PG8_SB(1, 0), cB + kstep, voffB); PG8_STAGE(PG8_SA(1, 0), cA + kstepA, voffA); PG8_STAGE(PG8_SB(1, 1), cB + hstep + kstep, voffB);
;         PG8_WAIT_V(6); PG8_BAR;
;     } else {
;         PG8_STAGE(PG8_SB(0, 0), cB, voffB); PG8_STAGE(PG8_SA(0, 0), cA, voffA); PG8_STAGE(PG8_SB(0, 1), cB + hstep, voffB); PG8_STAGE(PG8_SA(0, 1), cA + hstepA, voffA);
;         if (wr == 1) PG8_BAR;
;         PG8_WAIT_V(4); PG8_BAR;
;         PG8_STAGE(PG8_SB(1, 0), cB + kstep, voffB); PG8_STAGE(PG8_SA(1, 0), cA + kstepA, voffA); PG8_STAGE(PG8_SB(1, 1), cB + hstep + kstep, voffB);
;         PG8_WAIT_V(6); PG8_BAR;
;     }
.LBB0_2556:
	s_mul_i32 s40, s96, 0x7000000
	s_add_u32 s12, s12, s40
	s_addc_u32 s13, s13, 0
	s_add_u32 s12, s12, 0x25e00000
	s_addc_u32 s13, s13, 0
	s_lshl_b32 s41, s41, 5
	s_mov_b64 s[44:45], 0x80
	s_and_b32 s41, s41, 0x60
	s_add_i32 m0, s0, 0x18000
	v_lshl_add_u64 v[6:7], v[6:7], 0, s[44:45]
	s_lshl_b32 s40, s42, 6
	s_lshl_b32 s48, s42, 13
	s_lshl_b32 s49, s41, 7
	s_waitcnt vmcnt(2)
	s_barrier
	global_load_lds_dwordx4 v[6:7], off
	v_lshl_add_u64 v[4:5], v[4:5], 0, s[44:45]
	s_add_i32 m0, s0, 0x1a000
	s_add_i32 s42, s0, 0x8000
	s_add_i32 s43, s0, 0xa000
	global_load_lds_dwordx4 v[4:5], off
	v_lshl_add_u64 v[0:1], v[0:1], 0, s[44:45]
	s_mov_b32 m0, s42
	s_add_u32 s46, s74, 0x20080
	global_load_lds_dwordx4 v[0:1], off
	v_lshl_add_u64 v[0:1], v[2:3], 0, s[44:45]
	s_mov_b32 m0, s43
	s_addc_u32 s47, s75, 0
	global_load_lds_dwordx4 v[0:1], off
	s_add_i32 m0, s0, 0x1c000
	v_lshl_add_u64 v[0:1], s[46:47], 0, v[128:129]
	global_load_lds_dwordx4 v128, s[46:47]
	v_lshl_add_u64 v[0:1], s[46:47], 0, v[130:131]
	s_add_i32 m0, s0, 0x1e000
	s_sext_i32_i8 s50, s2
	global_load_lds_dwordx4 v130, s[46:47]
	v_and_b32_e32 v0, 48, v10
	v_lshlrev_b32_e32 v1, 6, v10
	s_movk_i32 s2, 0x3c0
	v_and_or_b32 v0, v1, s2, v0
	v_lshlrev_b32_e32 v1, 2, v10
	v_and_b32_e32 v1, 32, v1
	v_bitop3_b32 v2, v0, s48, v1 bitop3:0xde
	v_bitop3_b32 v146, s49, v0, v1 bitop3:0xf6
	v_lshlrev_b32_e32 v0, 13, v8
	v_and_b32_e32 v0, 0xffffc000, v0
	v_lshl_add_u32 v0, v9, 10, v0
	v_and_b32_e32 v1, 1, v8
	v_lshl_or_b32 v0, v1, 6, v0
	v_lshl_add_u32 v136, v11, 1, v0
	v_lshlrev_b32_e32 v0, 13, v13
	v_and_b32_e32 v0, 0xffffc000, v0
	s_waitcnt vmcnt(6)
	s_mov_b32 s98, 0
	s_bitcmp1_b32 s33, 8
	s_cbranch_scc1 .Lsp_11
	s_setprio 1
.Lsp_11:
	s_cmpk_lt_u32 s3, 0x100
	v_lshl_add_u32 v0, v12, 10, v0
	v_and_b32_e32 v1, 1, v13
	s_cselect_b64 s[46:47], -1, 0
	v_mov_b32_e32 v137, 0
	v_lshl_or_b32 v0, v1, 6, v0
	s_add_i32 s48, 0, 0x10000
	s_add_i32 s49, 0, 0x14000
	v_lshl_add_u32 v138, v14, 1, v0
	v_mov_b32_e32 v139, v137
	s_mov_b64 s[60:61], 0x100
	v_add_u32_e32 v147, s48, v146
	v_add_u32_e32 v148, s49, v146
	v_add_u32_e32 v149, 0, v2
	s_mov_b64 s[62:63], 0x180
	s_barrier
	s_branch .LBB0_2559

; template <class Epi, class Sched, bool ALIGN_EPI = false, bool SP2 = false, bool A_TILED = false>
; __device__ __forceinline__ void gemm_phase(PG8_LAS unsigned char* lds, const Gemm g, const Sched& S, const Epi& E, const int wave_s) {
;     ...
;         constexpr bool PEEL = SP2 && !Epi::AFTER_DRAIN;
;         if constexpr (PEEL) {
;             const char* a1 = cA + kstepA; const char* a2 = cA + 2 * kstepA; const char* b2 = cB + 2 * kstep; const char* a3 = a2 + kstepA; const char* b3 = b2 + kstep;
;             PG8_ITER(PG8_MMAZ)
.Lpw_13:
	s_barrier
	v_mfma_f32_16x16x32_bf16 v[88:91], v[0:3], v[56:59], 0
	v_mfma_f32_16x16x32_bf16 v[64:67], v[0:3], v[32:35], 0
	v_mfma_f32_16x16x32_bf16 v[68:71], v[8:11], v[32:35], 0
	v_mfma_f32_16x16x32_bf16 v[72:75], v[0:3], v[40:43], 0
	v_mfma_f32_16x16x32_bf16 v[76:79], v[8:11], v[40:43], 0
	v_mfma_f32_16x16x32_bf16 v[80:83], v[0:3], v[48:51], 0
	v_mfma_f32_16x16x32_bf16 v[84:87], v[8:11], v[48:51], 0
	v_mfma_f32_16x16x32_bf16 v[92:95], v[4:7], v[60:63], v[88:91]
	v_mfma_f32_16x16x32_bf16 v[88:91], v[8:11], v[56:59], 0
	v_mfma_f32_16x16x32_bf16 v[64:67], v[4:7], v[36:39], v[64:67]
	v_mfma_f32_16x16x32_bf16 v[68:71], v[12:15], v[36:39], v[68:71]
	v_mfma_f32_16x16x32_bf16 v[72:75], v[4:7], v[44:47], v[72:75]
	v_mfma_f32_16x16x32_bf16 v[76:79], v[12:15], v[44:47], v[76:79]
	v_mfma_f32_16x16x32_bf16 v[80:83], v[4:7], v[52:55], v[80:83]
	v_mfma_f32_16x16x32_bf16 v[84:87], v[12:15], v[52:55], v[84:87]
	v_mfma_f32_16x16x32_bf16 v[100:103], v[12:15], v[60:63], v[88:91]
	v_mfma_f32_16x16x32_bf16 v[88:91], v[16:19], v[32:35], 0
	v_mfma_f32_16x16x32_bf16 v[32:35], v[24:27], v[32:35], 0
	v_mfma_f32_16x16x32_bf16 v[108:111], v[20:23], v[36:39], v[88:91]
	v_mfma_f32_16x16x32_bf16 v[32:35], v[28:31], v[36:39], v[32:35]
	v_mfma_f32_16x16x32_bf16 v[36:39], v[16:19], v[40:43], 0
	v_mfma_f32_16x16x32_bf16 v[40:43], v[24:27], v[40:43], 0
	v_mfma_f32_16x16x32_bf16 v[36:39], v[20:23], v[44:47], v[36:39]
	v_mfma_f32_16x16x32_bf16 v[40:43], v[28:31], v[44:47], v[40:43]
	v_mfma_f32_16x16x32_bf16 v[44:47], v[16:19], v[48:51], 0
	v_mfma_f32_16x16x32_bf16 v[48:51], v[24:27], v[48:51], 0
	v_mfma_f32_16x16x32_bf16 v[44:47], v[20:23], v[52:55], v[44:47]
	v_mfma_f32_16x16x32_bf16 v[52:55], v[28:31], v[52:55], v[48:51]
	v_mfma_f32_16x16x32_bf16 v[48:51], v[16:19], v[56:59], 0
	v_mfma_f32_16x16x32_bf16 v[150:153], v[20:23], v[60:63], v[48:51]
	v_mfma_f32_16x16x32_bf16 v[48:51], v[24:27], v[56:59], 0
	v_mfma_f32_16x16x32_bf16 v[154:157], v[28:31], v[60:63], v[48:51]
	s_barrier
	s_add_i32 s57, s48, s36
	v_lshl_add_u64 v[250:251], s[74:75], 0, v[128:129]
	s_add_i32 s58, s57, 0x2000
	v_lshl_add_u64 v[120:121], v[250:251], 0, s[60:61]
	s_mov_b32 m0, s57
	v_lshl_add_u64 v[252:253], s[74:75], 0, v[130:131]
	s_add_u32 s78, s74, 0x20100
	ds_read_b128 v[48:51], v149 offset:16384
	ds_read_b128 v[56:59], v149 offset:17408
	ds_read_b128 v[60:63], v149 offset:18432
	ds_read_b128 v[88:91], v149 offset:19456
	ds_read_b128 v[96:99], v149 offset:20480
	ds_read_b128 v[104:107], v149 offset:21504
	ds_read_b128 v[112:115], v149 offset:22528
	ds_read_b128 v[116:119], v149 offset:23552
	global_load_lds_dwordx4 v[120:121], off
	v_lshl_add_u64 v[120:121], v[252:253], 0, s[60:61]
	s_mov_b32 m0, s58
	s_addc_u32 s79, s75, 0
	s_add_i32 s59, s49, s36
	global_load_lds_dwordx4 v[120:121], off
	v_lshl_add_u64 v[120:121], s[78:79], 0, v[128:129]
	s_mov_b32 m0, s59
	s_add_i32 s65, s59, 0x2000
	global_load_lds_dwordx4 v128, s[78:79]
	v_lshl_add_u64 v[120:121], s[78:79], 0, v[130:131]
	s_mov_b32 m0, s65
	v_lshl_add_u64 v[140:141], s[76:77], 0, v[134:135]
	global_load_lds_dwordx4 v130, s[78:79]
	v_lshl_add_u64 v[120:121], v[140:141], 0, s[60:61]
	s_mov_b32 m0, s0
	v_lshl_add_u64 v[142:143], s[76:77], 0, v[132:133]
	global_load_lds_dwordx4 v[120:121], off
	v_lshl_add_u64 v[120:121], v[142:143], 0, s[60:61]
	s_mov_b32 m0, s1
	s_nop 0
	global_load_lds_dwordx4 v[120:121], off
	s_waitcnt vmcnt(24) lgkmcnt(0)
	s_cmp_lg_u32 s98, 0
	s_cbranch_scc1 .Lpw_14
	s_waitcnt vmcnt(8)
.Lpw_14:
	s_barrier
	v_mfma_f32_16x16x32_bf16 v[120:123], v[0:3], v[48:51], 0
	v_mfma_f32_16x16x32_bf16 v[158:161], v[4:7], v[56:59], v[120:123]
	v_mfma_f32_16x16x32_bf16 v[120:123], v[8:11], v[48:51], 0
	v_mfma_f32_16x16x32_bf16 v[162:165], v[12:15], v[56:59], v[120:123]
	v_mfma_f32_16x16x32_bf16 v[120:123], v[0:3], v[60:63], 0
	v_mfma_f32_16x16x32_bf16 v[166:169], v[4:7], v[88:91], v[120:123]
	v_mfma_f32_16x16x32_bf16 v[120:123], v[8:11], v[60:63], 0
	v_mfma_f32_16x16x32_bf16 v[170:173], v[12:15], v[88:91], v[120:123]
	v_mfma_f32_16x16x32_bf16 v[120:123], v[0:3], v[96:99], 0
	v_mfma_f32_16x16x32_bf16 v[0:3], v[0:3], v[112:115], 0
	v_mfma_f32_16x16x32_bf16 v[174:177], v[4:7], v[104:107], v[120:123]
	v_mfma_f32_16x16x32_bf16 v[0:3], v[4:7], v[116:119], v[0:3]
	v_mfma_f32_16x16x32_bf16 v[4:7], v[8:11], v[112:115], 0
	v_mfma_f32_16x16x32_bf16 v[120:123], v[8:11], v[96:99], 0
	v_mfma_f32_16x16x32_bf16 v[4:7], v[12:15], v[116:119], v[4:7]
	v_mfma_f32_16x16x32_bf16 v[178:181], v[12:15], v[104:107], v[120:123]
	v_mfma_f32_16x16x32_bf16 v[8:11], v[16:19], v[48:51], 0
	v_mfma_f32_16x16x32_bf16 v[182:185], v[20:23], v[56:59], v[8:11]
	v_mfma_f32_16x16x32_bf16 v[8:11], v[24:27], v[48:51], 0
	v_mfma_f32_16x16x32_bf16 v[186:189], v[28:31], v[56:59], v[8:11]
	v_mfma_f32_16x16x32_bf16 v[8:11], v[16:19], v[60:63], 0
	v_mfma_f32_16x16x32_bf16 v[190:193], v[20:23], v[88:91], v[8:11]
	v_mfma_f32_16x16x32_bf16 v[8:11], v[24:27], v[60:63], 0
	v_mfma_f32_16x16x32_bf16 v[194:197], v[28:31], v[88:91], v[8:11]
	v_mfma_f32_16x16x32_bf16 v[8:11], v[16:19], v[96:99], 0
	v_mfma_f32_16x16x32_bf16 v[198:201], v[20:23], v[104:107], v[8:11]
	v_mfma_f32_16x16x32_bf16 v[8:11], v[24:27], v[96:99], 0
	v_mfma_f32_16x16x32_bf16 v[202:205], v[28:31], v[104:107], v[8:11]
	v_mfma_f32_16x16x32_bf16 v[8:11], v[16:19], v[112:115], 0
	v_mfma_f32_16x16x32_bf16 v[206:209], v[20:23], v[116:119], v[8:11]
	v_mfma_f32_16x16x32_bf16 v[8:11], v[24:27], v[112:115], 0
	v_mfma_f32_16x16x32_bf16 v[210:213], v[28:31], v[116:119], v[8:11]
	s_barrier
; template <class Epi, class Sched, bool ALIGN_EPI = false, bool SP2 = false, bool A_TILED = false>
; __device__ __forceinline__ void gemm_phase(PG8_LAS unsigned char* lds, const Gemm g, const Sched& S, const Epi& E, const int wave_s) {
;     ...
;         for (int t = PEEL ? 2 : 0; t < nt; t += 2) {
;             const bool last = (t == nt - 2);
;             const char* a1 = cA + (size_t)(t + 1) * kstepA;
;             const char* a2 = last ? nA : cA + (size_t)(t + 2) * kstepA; const char* b2 = last ? nB : cB + (size_t)(t + 2) * kstep;
;             const char* a3 = a2 + kstepA; const char* b3 = b2 + kstep;
	s_add_i32 s67, 0, 0x18000
	s_add_i32 s80, 0, 0x1c000
	v_add_u32_e32 v144, s67, v146
	v_add_u32_e32 v145, s80, v146
	s_nop 0
	ds_read_b128 v[8:11], v144
	ds_read_b128 v[12:15], v144 offset:1024
	ds_read_b128 v[16:19], v144 offset:2048
	ds_read_b128 v[20:23], v144 offset:3072
	ds_read_b128 v[214:217], v145
	ds_read_b128 v[218:221], v145 offset:1024
	ds_read_b128 v[222:225], v145 offset:2048
	ds_read_b128 v[226:229], v145 offset:3072
	s_add_u32 s78, s76, 0x20100
	s_addc_u32 s79, s77, 0
	s_mov_b32 m0, s37
	v_lshl_add_u64 v[48:49], s[78:79], 0, v[134:135]
	ds_read_b128 v[24:27], v149 offset:32768
	ds_read_b128 v[28:31], v149 offset:33792
	ds_read_b128 v[60:63], v149 offset:34816
	ds_read_b128 v[230:233], v149 offset:35840
	ds_read_b128 v[234:237], v149 offset:36864
	ds_read_b128 v[238:241], v149 offset:37888
	ds_read_b128 v[242:245], v149 offset:38912
	ds_read_b128 v[246:249], v149 offset:39936
	global_load_lds_dwordx4 v134, s[78:79]
	v_lshl_add_u64 v[48:49], s[78:79], 0, v[132:133]
	s_mov_b32 m0, s38
	s_nop 0
	global_load_lds_dwordx4 v132, s[78:79]
	s_waitcnt vmcnt(8) lgkmcnt(0)
	s_barrier
	v_mfma_f32_16x16x32_bf16 v[48:51], v[8:11], v[24:27], v[64:67]
	v_mfma_f32_16x16x32_bf16 v[120:123], v[12:15], v[28:31], v[48:51]
	v_mfma_f32_16x16x32_bf16 v[48:51], v[16:19], v[24:27], v[68:71]
	v_mfma_f32_16x16x32_bf16 v[112:115], v[20:23], v[28:31], v[48:51]
	v_mfma_f32_16x16x32_bf16 v[48:51], v[8:11], v[60:63], v[72:75]
	v_mfma_f32_16x16x32_bf16 v[104:107], v[12:15], v[230:233], v[48:51]
	v_mfma_f32_16x16x32_bf16 v[48:51], v[16:19], v[60:63], v[76:79]
	v_mfma_f32_16x16x32_bf16 v[96:99], v[20:23], v[230:233], v[48:51]
	v_mfma_f32_16x16x32_bf16 v[48:51], v[8:11], v[234:237], v[80:83]
	v_mfma_f32_16x16x32_bf16 v[88:91], v[12:15], v[238:241], v[48:51]
	v_mfma_f32_16x16x32_bf16 v[48:51], v[16:19], v[234:237], v[84:87]
	v_mfma_f32_16x16x32_bf16 v[80:83], v[20:23], v[238:241], v[48:51]
	v_mfma_f32_16x16x32_bf16 v[48:51], v[8:11], v[242:245], v[92:95]
	v_mfma_f32_16x16x32_bf16 v[56:59], v[12:15], v[246:249], v[48:51]
	v_mfma_f32_16x16x32_bf16 v[48:51], v[16:19], v[242:245], v[100:103]
	v_mfma_f32_16x16x32_bf16 v[48:51], v[20:23], v[246:249], v[48:51]
	v_mfma_f32_16x16x32_bf16 v[64:67], v[214:217], v[24:27], v[108:111]
	v_mfma_f32_16x16x32_bf16 v[24:27], v[222:225], v[24:27], v[32:35]
	v_mfma_f32_16x16x32_bf16 v[116:119], v[226:229], v[28:31], v[24:27]
	v_mfma_f32_16x16x32_bf16 v[24:27], v[214:217], v[60:63], v[36:39]
	v_mfma_f32_16x16x32_bf16 v[108:111], v[218:221], v[230:233], v[24:27]
	v_mfma_f32_16x16x32_bf16 v[24:27], v[222:225], v[60:63], v[40:43]
	v_mfma_f32_16x16x32_bf16 v[100:103], v[226:229], v[230:233], v[24:27]
	v_mfma_f32_16x16x32_bf16 v[24:27], v[214:217], v[234:237], v[44:47]
	v_mfma_f32_16x16x32_bf16 v[92:95], v[218:221], v[238:241], v[24:27]
	v_mfma_f32_16x16x32_bf16 v[24:27], v[222:225], v[234:237], v[52:55]
	v_mfma_f32_16x16x32_bf16 v[84:87], v[226:229], v[238:241], v[24:27]
	v_mfma_f32_16x16x32_bf16 v[24:27], v[214:217], v[242:245], v[150:153]
	v_mfma_f32_16x16x32_bf16 v[60:63], v[218:221], v[246:249], v[24:27]
	v_mfma_f32_16x16x32_bf16 v[24:27], v[222:225], v[242:245], v[154:157]
	v_mfma_f32_16x16x32_bf16 v[124:127], v[218:221], v[28:31], v[64:67]
	v_mfma_f32_16x16x32_bf16 v[52:55], v[226:229], v[246:249], v[24:27]
	s_barrier
	s_add_i32 s67, s67, s36
	s_add_i32 s71, s67, 0x2000
	s_nop 1
	v_lshl_add_u64 v[24:25], v[250:251], 0, s[62:63]
	s_mov_b32 m0, s67
	s_add_u32 s78, s74, 0x20180
	ds_read_b128 v[32:35], v149 offset:49152
	ds_read_b128 v[36:39], v149 offset:50176
	ds_read_b128 v[150:153], v149 offset:51200
	ds_read_b128 v[154:157], v149 offset:52224
	ds_read_b128 v[230:233], v149 offset:53248
	ds_read_b128 v[234:237], v149 offset:54272
	ds_read_b128 v[238:241], v149 offset:55296
	ds_read_b128 v[242:245], v149 offset:56320
	global_load_lds_dwordx4 v[24:25], off
	v_lshl_add_u64 v[24:25], v[252:253], 0, s[62:63]
	s_mov_b32 m0, s71
	s_addc_u32 s79, s75, 0
	s_add_i32 s80, s80, s36
	global_load_lds_dwordx4 v[24:25], off
	v_lshl_add_u64 v[24:25], s[78:79], 0, v[128:129]
	s_mov_b32 m0, s80
	s_add_i32 s81, s80, 0x2000
	global_load_lds_dwordx4 v128, s[78:79]
	v_lshl_add_u64 v[24:25], s[78:79], 0, v[130:131]
	s_mov_b32 m0, s81
	s_nop 0
	global_load_lds_dwordx4 v130, s[78:79]
	v_lshl_add_u64 v[24:25], v[140:141], 0, s[62:63]
	s_mov_b32 m0, s42
	s_nop 0
	global_load_lds_dwordx4 v[24:25], off
	v_lshl_add_u64 v[24:25], v[142:143], 0, s[62:63]
	s_mov_b32 m0, s43
	s_nop 0
	global_load_lds_dwordx4 v[24:25], off
	s_waitcnt vmcnt(8) lgkmcnt(0)
	s_barrier
	v_mfma_f32_16x16x32_bf16 v[24:27], v[8:11], v[32:35], v[158:161]
	v_mfma_f32_16x16x32_bf16 v[76:79], v[12:15], v[36:39], v[24:27]
	v_mfma_f32_16x16x32_bf16 v[24:27], v[16:19], v[32:35], v[162:165]
	v_mfma_f32_16x16x32_bf16 v[72:75], v[20:23], v[36:39], v[24:27]
	v_mfma_f32_16x16x32_bf16 v[24:27], v[8:11], v[150:153], v[166:169]
	v_mfma_f32_16x16x32_bf16 v[44:47], v[12:15], v[154:157], v[24:27]
	v_mfma_f32_16x16x32_bf16 v[24:27], v[16:19], v[150:153], v[170:173]
	v_mfma_f32_16x16x32_bf16 v[40:43], v[20:23], v[154:157], v[24:27]
	v_mfma_f32_16x16x32_bf16 v[24:27], v[8:11], v[230:233], v[174:177]
	v_mfma_f32_16x16x32_bf16 v[0:3], v[8:11], v[238:241], v[0:3]
	v_mfma_f32_16x16x32_bf16 v[28:31], v[12:15], v[234:237], v[24:27]
	v_mfma_f32_16x16x32_bf16 v[24:27], v[16:19], v[230:233], v[178:181]
	v_mfma_f32_16x16x32_bf16 v[12:15], v[12:15], v[242:245], v[0:3]
	v_mfma_f32_16x16x32_bf16 v[0:3], v[16:19], v[238:241], v[4:7]
	v_mfma_f32_16x16x32_bf16 v[24:27], v[20:23], v[234:237], v[24:27]
	v_mfma_f32_16x16x32_bf16 v[8:11], v[20:23], v[242:245], v[0:3]
	v_mfma_f32_16x16x32_bf16 v[0:3], v[214:217], v[32:35], v[182:185]
	v_mfma_f32_16x16x32_bf16 v[68:71], v[218:221], v[36:39], v[0:3]
	v_mfma_f32_16x16x32_bf16 v[0:3], v[222:225], v[32:35], v[186:189]
	v_mfma_f32_16x16x32_bf16 v[64:67], v[226:229], v[36:39], v[0:3]
	v_mfma_f32_16x16x32_bf16 v[0:3], v[214:217], v[150:153], v[190:193]
	v_mfma_f32_16x16x32_bf16 v[36:39], v[218:221], v[154:157], v[0:3]
	v_mfma_f32_16x16x32_bf16 v[0:3], v[222:225], v[150:153], v[194:197]
	v_mfma_f32_16x16x32_bf16 v[32:35], v[226:229], v[154:157], v[0:3]
	v_mfma_f32_16x16x32_bf16 v[0:3], v[214:217], v[230:233], v[198:201]
	v_mfma_f32_16x16x32_bf16 v[20:23], v[218:221], v[234:237], v[0:3]
	v_mfma_f32_16x16x32_bf16 v[0:3], v[222:225], v[230:233], v[202:205]
	v_mfma_f32_16x16x32_bf16 v[16:19], v[226:229], v[234:237], v[0:3]
	v_mfma_f32_16x16x32_bf16 v[0:3], v[214:217], v[238:241], v[206:209]
	v_mfma_f32_16x16x32_bf16 v[4:7], v[218:221], v[242:245], v[0:3]
	v_mfma_f32_16x16x32_bf16 v[0:3], v[222:225], v[238:241], v[210:213]
	v_mfma_f32_16x16x32_bf16 v[0:3], v[226:229], v[242:245], v[0:3]
	s_barrier
	s_add_u32 s82, s74, 0x200
	s_addc_u32 s83, s75, 0
	s_add_u32 s74, s76, 0x20180
	s_addc_u32 s75, s77, 0
	s_mov_b32 s85, 0
; #define PG8_MMA(ai, bj, At, Bt) do { __builtin_amdgcn_s_setprio(1); _Pragma("unroll") for (int m = 0; m < 4; ++m) _Pragma("unroll") for (int n = 0; n < 2; ++n) _Pragma("unroll") for (int k = 0; k < 2; ++k) \
;         acc[ai][bj][m][n] = __builtin_amdgcn_mfma_f32_16x16x32_bf16(Bt[n][k], At[m][k], acc[ai][bj][m][n], 0, 0, 0); __builtin_amdgcn_s_setprio(0); } while (0)
; template <class Epi, class Sched, bool ALIGN_EPI = false, bool SP2 = false, bool A_TILED = false>
; __device__ __forceinline__ void gemm_phase(PG8_LAS unsigned char* lds, const Gemm g, const Sched& S, const Epi& E, const int wave_s) {
;     ...
;         for (int t = PEEL ? 2 : 0; t < nt; t += 2) {
;             const bool last = (t == nt - 2);
;             const char* a1 = cA + (size_t)(t + 1) * kstepA;
;             const char* a2 = last ? nA : cA + (size_t)(t + 2) * kstepA; const char* b2 = last ? nB : cB + (size_t)(t + 2) * kstep;
;             const char* a3 = a2 + kstepA; const char* b3 = b2 + kstep;
;             if (last && has_next) S.a_ready(nxt);
;             if constexpr (SP2) {
;             PG8_ITER(PG8_MMA)
.LBB0_2566:
	ds_read_b128 v[150:153], v147
	ds_read_b128 v[154:157], v147 offset:1024
	ds_read_b128 v[158:161], v147 offset:2048
	ds_read_b128 v[162:165], v147 offset:3072
	ds_read_b128 v[166:169], v148
	ds_read_b128 v[170:173], v148 offset:1024
	ds_read_b128 v[174:177], v148 offset:2048
	ds_read_b128 v[178:181], v148 offset:3072
	s_add_u32 s76, s74, 0xfffe0080
	s_addc_u32 s77, s75, -1
	s_cmp_eq_u32 s85, 4
	s_cselect_b32 s79, s51, s77
	s_cselect_b32 s78, s52, s76
	s_cselect_b32 s77, s53, s83
	s_cselect_b32 s76, s54, s82
	s_mov_b32 m0, s55
	v_lshl_add_u64 v[140:141], s[74:75], 0, v[138:139]
	ds_read_b128 v[182:185], v149
	ds_read_b128 v[186:189], v149 offset:1024
	ds_read_b128 v[190:193], v149 offset:2048
	ds_read_b128 v[194:197], v149 offset:3072
	ds_read_b128 v[198:201], v149 offset:4096
	ds_read_b128 v[202:205], v149 offset:5120
	ds_read_b128 v[206:209], v149 offset:6144
	ds_read_b128 v[210:213], v149 offset:7168
	global_load_lds_dwordx4 v138, s[74:75]
	v_lshl_add_u64 v[140:141], s[74:75], 0, v[136:137]
	s_mov_b32 m0, s56
	s_nop 0
	global_load_lds_dwordx4 v136, s[74:75]
	s_waitcnt vmcnt(8) lgkmcnt(0)
	s_barrier
	v_mfma_f32_16x16x32_bf16 v[120:123], v[150:153], v[182:185], v[120:123]
	v_mfma_f32_16x16x32_bf16 v[112:115], v[158:161], v[182:185], v[112:115]
	v_mfma_f32_16x16x32_bf16 v[104:107], v[150:153], v[190:193], v[104:107]
	v_mfma_f32_16x16x32_bf16 v[96:99], v[158:161], v[190:193], v[96:99]
	v_mfma_f32_16x16x32_bf16 v[88:91], v[150:153], v[198:201], v[88:91]
	v_mfma_f32_16x16x32_bf16 v[80:83], v[158:161], v[198:201], v[80:83]
	v_mfma_f32_16x16x32_bf16 v[56:59], v[150:153], v[206:209], v[56:59]
	v_mfma_f32_16x16x32_bf16 v[48:51], v[158:161], v[206:209], v[48:51]
	v_mfma_f32_16x16x32_bf16 v[120:123], v[154:157], v[186:189], v[120:123]
	v_mfma_f32_16x16x32_bf16 v[112:115], v[162:165], v[186:189], v[112:115]
	v_mfma_f32_16x16x32_bf16 v[104:107], v[154:157], v[194:197], v[104:107]
	v_mfma_f32_16x16x32_bf16 v[96:99], v[162:165], v[194:197], v[96:99]
	v_mfma_f32_16x16x32_bf16 v[88:91], v[154:157], v[202:205], v[88:91]
	v_mfma_f32_16x16x32_bf16 v[80:83], v[162:165], v[202:205], v[80:83]
	v_mfma_f32_16x16x32_bf16 v[56:59], v[154:157], v[210:213], v[56:59]
	v_mfma_f32_16x16x32_bf16 v[48:51], v[162:165], v[210:213], v[48:51]
	v_mfma_f32_16x16x32_bf16 v[124:127], v[166:169], v[182:185], v[124:127]
	v_mfma_f32_16x16x32_bf16 v[116:119], v[174:177], v[182:185], v[116:119]
	v_mfma_f32_16x16x32_bf16 v[108:111], v[166:169], v[190:193], v[108:111]
	v_mfma_f32_16x16x32_bf16 v[100:103], v[174:177], v[190:193], v[100:103]
	v_mfma_f32_16x16x32_bf16 v[92:95], v[166:169], v[198:201], v[92:95]
	v_mfma_f32_16x16x32_bf16 v[84:87], v[174:177], v[198:201], v[84:87]
	v_mfma_f32_16x16x32_bf16 v[60:63], v[166:169], v[206:209], v[60:63]
	v_mfma_f32_16x16x32_bf16 v[52:55], v[174:177], v[206:209], v[52:55]
	v_mfma_f32_16x16x32_bf16 v[124:127], v[170:173], v[186:189], v[124:127]
	v_mfma_f32_16x16x32_bf16 v[116:119], v[178:181], v[186:189], v[116:119]
	v_mfma_f32_16x16x32_bf16 v[108:111], v[170:173], v[194:197], v[108:111]
	v_mfma_f32_16x16x32_bf16 v[100:103], v[178:181], v[194:197], v[100:103]
	v_mfma_f32_16x16x32_bf16 v[92:95], v[170:173], v[202:205], v[92:95]
	v_mfma_f32_16x16x32_bf16 v[84:87], v[178:181], v[202:205], v[84:87]
	v_mfma_f32_16x16x32_bf16 v[60:63], v[170:173], v[210:213], v[60:63]
	v_mfma_f32_16x16x32_bf16 v[52:55], v[178:181], v[210:213], v[52:55]
	s_barrier
	s_mov_b32 m0, s57
	v_lshl_add_u64 v[140:141], s[76:77], 0, v[128:129]
	s_add_u32 s88, s76, 0x20000
	ds_read_b128 v[182:185], v149 offset:16384
	ds_read_b128 v[186:189], v149 offset:17408
	ds_read_b128 v[190:193], v149 offset:18432
	ds_read_b128 v[194:197], v149 offset:19456
	ds_read_b128 v[198:201], v149 offset:20480
	ds_read_b128 v[202:205], v149 offset:21504
	ds_read_b128 v[206:209], v149 offset:22528
	ds_read_b128 v[210:213], v149 offset:23552
	global_load_lds_dwordx4 v128, s[76:77]
	v_lshl_add_u64 v[142:143], s[76:77], 0, v[130:131]
	s_mov_b32 m0, s58
	s_addc_u32 s89, s77, 0
	global_load_lds_dwordx4 v130, s[76:77]
	v_lshl_add_u64 v[214:215], s[88:89], 0, v[128:129]
	s_mov_b32 m0, s59
	v_lshl_add_u64 v[216:217], s[78:79], 0, v[132:133]
	global_load_lds_dwordx4 v128, s[88:89]
	v_lshl_add_u64 v[214:215], s[88:89], 0, v[130:131]
	s_mov_b32 m0, s65
	s_nop 0
	global_load_lds_dwordx4 v130, s[88:89]
	v_lshl_add_u64 v[214:215], s[78:79], 0, v[134:135]
	s_mov_b32 m0, s0
	s_nop 0
	global_load_lds_dwordx4 v134, s[78:79]
	s_mov_b32 m0, s1
	s_nop 0
	global_load_lds_dwordx4 v132, s[78:79]
	s_waitcnt vmcnt(8) lgkmcnt(0)
	s_barrier
	v_mfma_f32_16x16x32_bf16 v[76:79], v[150:153], v[182:185], v[76:79]
	v_mfma_f32_16x16x32_bf16 v[72:75], v[158:161], v[182:185], v[72:75]
	v_mfma_f32_16x16x32_bf16 v[44:47], v[150:153], v[190:193], v[44:47]
	v_mfma_f32_16x16x32_bf16 v[40:43], v[158:161], v[190:193], v[40:43]
	v_mfma_f32_16x16x32_bf16 v[28:31], v[150:153], v[198:201], v[28:31]
	v_mfma_f32_16x16x32_bf16 v[24:27], v[158:161], v[198:201], v[24:27]
	v_mfma_f32_16x16x32_bf16 v[12:15], v[150:153], v[206:209], v[12:15]
	v_mfma_f32_16x16x32_bf16 v[8:11], v[158:161], v[206:209], v[8:11]
	v_mfma_f32_16x16x32_bf16 v[76:79], v[154:157], v[186:189], v[76:79]
	v_mfma_f32_16x16x32_bf16 v[72:75], v[162:165], v[186:189], v[72:75]
	v_mfma_f32_16x16x32_bf16 v[44:47], v[154:157], v[194:197], v[44:47]
	v_mfma_f32_16x16x32_bf16 v[40:43], v[162:165], v[194:197], v[40:43]
	v_mfma_f32_16x16x32_bf16 v[28:31], v[154:157], v[202:205], v[28:31]
	v_mfma_f32_16x16x32_bf16 v[24:27], v[162:165], v[202:205], v[24:27]
	v_mfma_f32_16x16x32_bf16 v[12:15], v[154:157], v[210:213], v[12:15]
	v_mfma_f32_16x16x32_bf16 v[8:11], v[162:165], v[210:213], v[8:11]
	v_mfma_f32_16x16x32_bf16 v[68:71], v[166:169], v[182:185], v[68:71]
	v_mfma_f32_16x16x32_bf16 v[64:67], v[174:177], v[182:185], v[64:67]
	v_mfma_f32_16x16x32_bf16 v[36:39], v[166:169], v[190:193], v[36:39]
	v_mfma_f32_16x16x32_bf16 v[32:35], v[174:177], v[190:193], v[32:35]
	v_mfma_f32_16x16x32_bf16 v[20:23], v[166:169], v[198:201], v[20:23]
	v_mfma_f32_16x16x32_bf16 v[16:19], v[174:177], v[198:201], v[16:19]
	v_mfma_f32_16x16x32_bf16 v[4:7], v[166:169], v[206:209], v[4:7]
	v_mfma_f32_16x16x32_bf16 v[0:3], v[174:177], v[206:209], v[0:3]
	v_mfma_f32_16x16x32_bf16 v[68:71], v[170:173], v[186:189], v[68:71]
	v_mfma_f32_16x16x32_bf16 v[64:67], v[178:181], v[186:189], v[64:67]
	v_mfma_f32_16x16x32_bf16 v[36:39], v[170:173], v[194:197], v[36:39]
	v_mfma_f32_16x16x32_bf16 v[32:35], v[178:181], v[194:197], v[32:35]
	v_mfma_f32_16x16x32_bf16 v[20:23], v[170:173], v[202:205], v[20:23]
	v_mfma_f32_16x16x32_bf16 v[16:19], v[178:181], v[202:205], v[16:19]
	v_mfma_f32_16x16x32_bf16 v[4:7], v[170:173], v[210:213], v[4:7]
	v_mfma_f32_16x16x32_bf16 v[0:3], v[178:181], v[210:213], v[0:3]
	s_barrier
	ds_read_b128 v[150:153], v144
	ds_read_b128 v[154:157], v144 offset:1024
	ds_read_b128 v[158:161], v144 offset:2048
	ds_read_b128 v[162:165], v144 offset:3072
	ds_read_b128 v[166:169], v145
	ds_read_b128 v[170:173], v145 offset:1024
	ds_read_b128 v[174:177], v145 offset:2048
	ds_read_b128 v[178:181], v145 offset:3072
	s_add_u32 s78, s78, 0x20000
	s_addc_u32 s79, s79, 0
	s_mov_b32 m0, s37
	v_lshl_add_u64 v[218:219], s[78:79], 0, v[134:135]
	ds_read_b128 v[182:185], v149 offset:32768
	ds_read_b128 v[186:189], v149 offset:33792
	ds_read_b128 v[190:193], v149 offset:34816
	ds_read_b128 v[194:197], v149 offset:35840
	ds_read_b128 v[198:201], v149 offset:36864
	ds_read_b128 v[202:205], v149 offset:37888
	ds_read_b128 v[206:209], v149 offset:38912
	ds_read_b128 v[210:213], v149 offset:39936
	global_load_lds_dwordx4 v134, s[78:79]
	v_lshl_add_u64 v[218:219], s[78:79], 0, v[132:133]
	s_mov_b32 m0, s38
	s_nop 0
	global_load_lds_dwordx4 v132, s[78:79]
	s_waitcnt vmcnt(8) lgkmcnt(0)
	s_barrier
	v_mfma_f32_16x16x32_bf16 v[120:123], v[150:153], v[182:185], v[120:123]
	v_mfma_f32_16x16x32_bf16 v[112:115], v[158:161], v[182:185], v[112:115]
	v_mfma_f32_16x16x32_bf16 v[104:107], v[150:153], v[190:193], v[104:107]
	v_mfma_f32_16x16x32_bf16 v[96:99], v[158:161], v[190:193], v[96:99]
	v_mfma_f32_16x16x32_bf16 v[88:91], v[150:153], v[198:201], v[88:91]
	v_mfma_f32_16x16x32_bf16 v[80:83], v[158:161], v[198:201], v[80:83]
	v_mfma_f32_16x16x32_bf16 v[56:59], v[150:153], v[206:209], v[56:59]
	v_mfma_f32_16x16x32_bf16 v[48:51], v[158:161], v[206:209], v[48:51]
	v_mfma_f32_16x16x32_bf16 v[120:123], v[154:157], v[186:189], v[120:123]
	v_mfma_f32_16x16x32_bf16 v[112:115], v[162:165], v[186:189], v[112:115]
	v_mfma_f32_16x16x32_bf16 v[104:107], v[154:157], v[194:197], v[104:107]
	v_mfma_f32_16x16x32_bf16 v[96:99], v[162:165], v[194:197], v[96:99]
	v_mfma_f32_16x16x32_bf16 v[88:91], v[154:157], v[202:205], v[88:91]
	v_mfma_f32_16x16x32_bf16 v[80:83], v[162:165], v[202:205], v[80:83]
	v_mfma_f32_16x16x32_bf16 v[56:59], v[154:157], v[210:213], v[56:59]
	v_mfma_f32_16x16x32_bf16 v[48:51], v[162:165], v[210:213], v[48:51]
	v_mfma_f32_16x16x32_bf16 v[124:127], v[166:169], v[182:185], v[124:127]
	v_mfma_f32_16x16x32_bf16 v[116:119], v[174:177], v[182:185], v[116:119]
	v_mfma_f32_16x16x32_bf16 v[108:111], v[166:169], v[190:193], v[108:111]
	v_mfma_f32_16x16x32_bf16 v[100:103], v[174:177], v[190:193], v[100:103]
	v_mfma_f32_16x16x32_bf16 v[92:95], v[166:169], v[198:201], v[92:95]
	v_mfma_f32_16x16x32_bf16 v[84:87], v[174:177], v[198:201], v[84:87]
	v_mfma_f32_16x16x32_bf16 v[60:63], v[166:169], v[206:209], v[60:63]
	v_mfma_f32_16x16x32_bf16 v[52:55], v[174:177], v[206:209], v[52:55]
	v_mfma_f32_16x16x32_bf16 v[124:127], v[170:173], v[186:189], v[124:127]
	v_mfma_f32_16x16x32_bf16 v[116:119], v[178:181], v[186:189], v[116:119]
	v_mfma_f32_16x16x32_bf16 v[108:111], v[170:173], v[194:197], v[108:111]
	v_mfma_f32_16x16x32_bf16 v[100:103], v[178:181], v[194:197], v[100:103]
	v_mfma_f32_16x16x32_bf16 v[92:95], v[170:173], v[202:205], v[92:95]
	v_mfma_f32_16x16x32_bf16 v[84:87], v[178:181], v[202:205], v[84:87]
	v_mfma_f32_16x16x32_bf16 v[60:63], v[170:173], v[210:213], v[60:63]
	v_mfma_f32_16x16x32_bf16 v[52:55], v[178:181], v[210:213], v[52:55]
	s_barrier
; #define PG8_STAGE(bufoff, gbase, voff) do { _Pragma("unroll") for (int _i = 0; _i < 2; ++_i) \
;         __builtin_amdgcn_global_load_lds((const unsigned*)((const char*)(gbase) + (voff)[_i]), (PG8_LAS unsigned*)(lds + (bufoff) + ldsw + _i * 8192), 16, 0, 0); } while (0)
; #define PG8_BAR __builtin_amdgcn_s_barrier()
; template <class Epi, class Sched, bool ALIGN_EPI = false, bool SP2 = false, bool A_TILED = false>
; __device__ __forceinline__ void gemm_phase(PG8_LAS unsigned char* lds, const Gemm g, const Sched& S, const Epi& E, const int wave_s) {
;     ...
;         for (int t = PEEL ? 2 : 0; t < nt; t += 2) {
;             const bool last = (t == nt - 2);
;             const char* a1 = cA + (size_t)(t + 1) * kstepA;
;             const char* a2 = last ? nA : cA + (size_t)(t + 2) * kstepA; const char* b2 = last ? nB : cB + (size_t)(t + 2) * kstep;
;             const char* a3 = a2 + kstepA; const char* b3 = b2 + kstep;
;             if (last && has_next) S.a_ready(nxt);
;             if constexpr (SP2) {
;             PG8_ITER(PG8_MMA)
;             } else {
;             PG8_LDB(B0, 0, 0); PG8_SCHED; PG8_LDA(At, 0, 0); PG8_STAGE(PG8_SA(1, 1), a1 + hstepA, voffA);
;             PG8_WAIT_L(8); PG8_BAR; PG8_WAIT_L(0); PG8_MMA(0, 0, At, B0); PG8_BAR; PG8_SCHED;
;             PG8_LDB(B1, 0, 1); PG8_STAGE(PG8_SB(0, 0), b2, voffB);
;             PG8_BAR; PG8_WAIT_L(0); PG8_MMA(0, 1, At, B1); PG8_BAR;
;             PG8_LDA(At, 0, 1); PG8_STAGE(PG8_SA(0, 0), a2, voffA);
;             PG8_BAR; PG8_WAIT_L(0); PG8_MMA(1, 0, At, B0); PG8_BAR; PG8_SCHED;
;             PG8_STAGE(PG8_SB(0, 1), b2 + hstep, voffB);
;             PG8_WAIT_V(6); PG8_BAR; PG8_MMA(1, 1, At, B1); PG8_BAR;
;             PG8_LDB(B0, 1, 0); PG8_SCHED; PG8_LDA(At, 1, 0); PG8_STAGE(PG8_SA(0, 1), a2 + hstepA, voffA);
;             PG8_WAIT_L(8); PG8_BAR; PG8_WAIT_L(0); PG8_MMA(0, 0, At, B0); PG8_BAR; PG8_SCHED;
;             PG8_LDB(B1, 1, 1); PG8_STAGE(PG8_SB(1, 0), b3, voffB);
;             PG8_BAR; PG8_WAIT_L(0); PG8_MMA(0, 1, At, B1); PG8_BAR;
;             PG8_LDA(At, 1, 1); PG8_STAGE(PG8_SA(1, 0), a3, voffA);
;             PG8_BAR; PG8_WAIT_L(0); PG8_MMA(1, 0, At, B0); PG8_BAR; PG8_SCHED;
;             PG8_STAGE(PG8_SB(1, 1), b3 + hstep, voffB);
;             PG8_WAIT_V(6); PG8_BAR; PG8_MMA(1, 1, At, B1); PG8_BAR;
;             }
;         }
;         if constexpr (ALIGN_EPI) { if (wr == 0) PG8_BAR; }
	s_mov_b32 m0, s67
	v_lshl_add_u64 v[140:141], v[140:141], 0, s[44:45]
	s_add_u32 s76, s76, 0x20080
	ds_read_b128 v[182:185], v149 offset:49152
	ds_read_b128 v[186:189], v149 offset:50176
	ds_read_b128 v[190:193], v149 offset:51200
	ds_read_b128 v[194:197], v149 offset:52224
	ds_read_b128 v[198:201], v149 offset:53248
	ds_read_b128 v[202:205], v149 offset:54272
	ds_read_b128 v[206:209], v149 offset:55296
	ds_read_b128 v[210:213], v149 offset:56320
	global_load_lds_dwordx4 v[140:141], off
	v_lshl_add_u64 v[140:141], v[142:143], 0, s[44:45]
	s_mov_b32 m0, s71
	s_addc_u32 s77, s77, 0
	global_load_lds_dwordx4 v[140:141], off
	v_lshl_add_u64 v[140:141], s[76:77], 0, v[128:129]
	s_mov_b32 m0, s80
	s_nop 0
	global_load_lds_dwordx4 v128, s[76:77]
	v_lshl_add_u64 v[140:141], s[76:77], 0, v[130:131]
	s_mov_b32 m0, s81
	s_nop 0
	global_load_lds_dwordx4 v130, s[76:77]
	v_lshl_add_u64 v[140:141], v[214:215], 0, s[44:45]
	s_mov_b32 m0, s42
	s_nop 0
	global_load_lds_dwordx4 v[140:141], off
	v_lshl_add_u64 v[140:141], v[216:217], 0, s[44:45]
	s_mov_b32 m0, s43
	s_nop 0
	global_load_lds_dwordx4 v[140:141], off
	s_waitcnt vmcnt(8) lgkmcnt(0)
	s_barrier
	v_mfma_f32_16x16x32_bf16 v[76:79], v[150:153], v[182:185], v[76:79]
	v_mfma_f32_16x16x32_bf16 v[72:75], v[158:161], v[182:185], v[72:75]
	v_mfma_f32_16x16x32_bf16 v[44:47], v[150:153], v[190:193], v[44:47]
	v_mfma_f32_16x16x32_bf16 v[40:43], v[158:161], v[190:193], v[40:43]
	v_mfma_f32_16x16x32_bf16 v[28:31], v[150:153], v[198:201], v[28:31]
	v_mfma_f32_16x16x32_bf16 v[24:27], v[158:161], v[198:201], v[24:27]
	v_mfma_f32_16x16x32_bf16 v[12:15], v[150:153], v[206:209], v[12:15]
	v_mfma_f32_16x16x32_bf16 v[8:11], v[158:161], v[206:209], v[8:11]
	v_mfma_f32_16x16x32_bf16 v[76:79], v[154:157], v[186:189], v[76:79]
	v_mfma_f32_16x16x32_bf16 v[72:75], v[162:165], v[186:189], v[72:75]
	v_mfma_f32_16x16x32_bf16 v[44:47], v[154:157], v[194:197], v[44:47]
	v_mfma_f32_16x16x32_bf16 v[40:43], v[162:165], v[194:197], v[40:43]
	v_mfma_f32_16x16x32_bf16 v[28:31], v[154:157], v[202:205], v[28:31]
	v_mfma_f32_16x16x32_bf16 v[24:27], v[162:165], v[202:205], v[24:27]
	v_mfma_f32_16x16x32_bf16 v[12:15], v[154:157], v[210:213], v[12:15]
	v_mfma_f32_16x16x32_bf16 v[8:11], v[162:165], v[210:213], v[8:11]
	v_mfma_f32_16x16x32_bf16 v[68:71], v[166:169], v[182:185], v[68:71]
	v_mfma_f32_16x16x32_bf16 v[64:67], v[174:177], v[182:185], v[64:67]
	v_mfma_f32_16x16x32_bf16 v[36:39], v[166:169], v[190:193], v[36:39]
	v_mfma_f32_16x16x32_bf16 v[32:35], v[174:177], v[190:193], v[32:35]
	v_mfma_f32_16x16x32_bf16 v[20:23], v[166:169], v[198:201], v[20:23]
	v_mfma_f32_16x16x32_bf16 v[16:19], v[174:177], v[198:201], v[16:19]
	v_mfma_f32_16x16x32_bf16 v[4:7], v[166:169], v[206:209], v[4:7]
	v_mfma_f32_16x16x32_bf16 v[0:3], v[174:177], v[206:209], v[0:3]
	v_mfma_f32_16x16x32_bf16 v[68:71], v[170:173], v[186:189], v[68:71]
	v_mfma_f32_16x16x32_bf16 v[64:67], v[178:181], v[186:189], v[64:67]
	v_mfma_f32_16x16x32_bf16 v[36:39], v[170:173], v[194:197], v[36:39]
	v_mfma_f32_16x16x32_bf16 v[32:35], v[178:181], v[194:197], v[32:35]
	v_mfma_f32_16x16x32_bf16 v[20:23], v[170:173], v[202:205], v[20:23]
	v_mfma_f32_16x16x32_bf16 v[16:19], v[178:181], v[202:205], v[16:19]
	v_mfma_f32_16x16x32_bf16 v[4:7], v[170:173], v[210:213], v[4:7]
	v_mfma_f32_16x16x32_bf16 v[0:3], v[178:181], v[210:213], v[0:3]
	s_barrier
	s_add_i32 s85, s85, 2
	s_add_u32 s82, s82, 0x100
	s_addc_u32 s83, s83, 0
	s_add_u32 s74, s74, 0x100
	s_addc_u32 s75, s75, 0
	s_cmp_gt_u32 s85, 5
	s_cbranch_scc0 .LBB0_2566
	s_and_b64 vcc, exec, s[46:47]
	s_cbranch_vccz .LBB0_2569
	s_barrier

; __device__ __forceinline__ int tid_now(int wave_s) { unsigned z = 0u; asm volatile("" : "+v"(z)); return (wave_s << 6) | (int)__builtin_amdgcn_mbcnt_hi(~0u, __builtin_amdgcn_mbcnt_lo(~0u, z)); }
; __device__ __forceinline__ unsigned xb_add(unsigned* p, unsigned v) { return __hip_atomic_fetch_add(p, v, __ATOMIC_RELAXED, __HIP_MEMORY_SCOPE_AGENT); }
; __device__ __forceinline__ void xcd_barrier(const XcdBarrier& b) {
;     asm volatile("s_waitcnt vmcnt(0)" ::: "memory");
;     __syncthreads();
;     if (tid_now(b.w) == 0) {
;         unsigned* bar = b.bar;
;         __builtin_amdgcn_s_waitcnt(0);
;         unsigned nloc = b.st[0], nx = b.st[1];
;         if (nloc == 0u) { xcd_barrier_complete(bar, b.x, nloc, nx, b.np); b.st[0] = nloc; b.st[1] = nx; }
;         const unsigned old = xb_add(&bar[XB_XSUB(b.x)], 1u);
.LBB0_2573:
	s_setprio 0
	s_cmp_gt_i32 s35, 16
	s_cselect_b64 s[2:3], -1, 0
	s_and_b64 s[0:1], s[6:7], s[2:3]
	s_andn2_b64 vcc, exec, s[0:1]
	s_cbranch_vccnz .LBB0_2627
	v_mov_b32_e32 v0, 0
	s_waitcnt vmcnt(0)
	s_waitcnt vmcnt(0) lgkmcnt(0)
	s_barrier
	s_nop 0
	v_mbcnt_lo_u32_b32 v0, -1, v0
	v_mbcnt_hi_u32_b32 v0, -1, v0
	v_or_b32_e32 v0, s33, v0
	v_cmp_eq_u32_e32 vcc, 0, v0
	s_and_saveexec_b64 s[4:5], vcc
	s_cbranch_execz .LBB0_2626
	s_add_i32 s0, 0, 0x27f68
	v_mov_b32_e32 v0, s0
	s_waitcnt vmcnt(0) expcnt(0) lgkmcnt(0)
	ds_read_b32 v2, v0
	s_add_i32 s0, 0, 0x27f6c
	v_mov_b32_e32 v0, s0
	ds_read_b32 v0, v0
	s_waitcnt lgkmcnt(1)
	v_cmp_ne_u32_e32 vcc, 0, v2
	s_cbranch_vccnz .LBB0_2590
	s_add_u32 s6, s10, 0x1000
	s_addc_u32 s7, s11, 0
	s_add_u32 s12, s10, 0x1100
	s_addc_u32 s13, s11, 0
	s_add_u32 s44, s10, 0x1200
	s_addc_u32 s45, s11, 0
	s_add_u32 s46, s10, 0x1300
	s_addc_u32 s47, s11, 0
	s_mov_b32 s0, 1
	v_mov_b32_e32 v16, 0
	s_branch .LBB0_2578

; __device__ __forceinline__ int tid_now(int wave_s) { unsigned z = 0u; asm volatile("" : "+v"(z)); return (wave_s << 6) | (int)__builtin_amdgcn_mbcnt_hi(~0u, __builtin_amdgcn_mbcnt_lo(~0u, z)); }
; __device__ __forceinline__ unsigned xb_add(unsigned* p, unsigned v) { return __hip_atomic_fetch_add(p, v, __ATOMIC_RELAXED, __HIP_MEMORY_SCOPE_AGENT); }
; __device__ __forceinline__ void xcd_barrier(const XcdBarrier& b) {
;     asm volatile("s_waitcnt vmcnt(0)" ::: "memory");
;     __syncthreads();
;     if (tid_now(b.w) == 0) {
;         unsigned* bar = b.bar;
;         __builtin_amdgcn_s_waitcnt(0);
;         unsigned nloc = b.st[0], nx = b.st[1];
;         if (nloc == 0u) { xcd_barrier_complete(bar, b.x, nloc, nx, b.np); b.st[0] = nloc; b.st[1] = nx; }
;         const unsigned old = xb_add(&bar[XB_XSUB(b.x)], 1u);
.LBB0_2663:
	s_setprio 0
	s_cmp_gt_i32 s35, 17
	s_cselect_b64 s[2:3], -1, 0
	s_and_b64 s[0:1], s[6:7], s[2:3]
	s_andn2_b64 vcc, exec, s[0:1]
	s_cbranch_vccnz .LBB0_2717
	v_mov_b32_e32 v0, 0
	s_waitcnt vmcnt(0)
	s_waitcnt vmcnt(0) lgkmcnt(0)
	s_barrier
	s_nop 0
	v_mbcnt_lo_u32_b32 v0, -1, v0
	v_mbcnt_hi_u32_b32 v0, -1, v0
	v_or_b32_e32 v0, s33, v0
	v_cmp_eq_u32_e32 vcc, 0, v0
	s_and_saveexec_b64 s[4:5], vcc
	s_cbranch_execz .LBB0_2716
	s_add_i32 s0, 0, 0x27f68
	v_mov_b32_e32 v0, s0
	s_waitcnt vmcnt(0) expcnt(0) lgkmcnt(0)
	ds_read_b32 v2, v0
	s_add_i32 s0, 0, 0x27f6c
	v_mov_b32_e32 v0, s0
	ds_read_b32 v0, v0
	s_waitcnt lgkmcnt(1)
	v_cmp_ne_u32_e32 vcc, 0, v2
	s_cbranch_vccnz .LBB0_2680
	s_add_u32 s6, s10, 0x1000
	s_addc_u32 s7, s11, 0
	s_add_u32 s12, s10, 0x1100
	s_addc_u32 s13, s11, 0
	s_add_u32 s44, s10, 0x1200
	s_addc_u32 s45, s11, 0
	s_add_u32 s46, s10, 0x1300
	s_addc_u32 s47, s11, 0
	s_mov_b32 s0, 1
	v_mov_b32_e32 v16, 0
	s_branch .LBB0_2668

; #define PG8_STAGE(bufoff, gbase, voff) do { _Pragma("unroll") for (int _i = 0; _i < 2; ++_i) \
;         __builtin_amdgcn_global_load_lds((const unsigned*)((const char*)(gbase) + (voff)[_i]), (PG8_LAS unsigned*)(lds + (bufoff) + ldsw + _i * 8192), 16, 0, 0); } while (0)
; #define PG8_WAIT_V(n) asm volatile("s_waitcnt vmcnt(" #n ")" ::: "memory")
; template <class Epi, class Sched, bool ALIGN_EPI = false, bool SP2 = false, bool A_TILED = false>
; __device__ __forceinline__ void gemm_phase(PG8_LAS unsigned char* lds, const Gemm g, const Sched& S, const Epi& E, const int wave_s) {
;     ...
;     if constexpr (SP2) {
;         PG8_STAGE(PG8_SB(0, 0), cB, voffB); PG8_STAGE(PG8_SB(0, 1), cB + hstep, voffB); PG8_STAGE(PG8_SA(0, 0), cA, voffA); PG8_STAGE(PG8_SA(0, 1), cA + hstepA, voffA);
;         if (wr == 1) PG8_BAR;
;         PG8_WAIT_V(2); PG8_BAR;
;         PG8_STAGE(PG8_SB(1, 0), cB + kstep, voffB); PG8_STAGE(PG8_SA(1, 0), cA + kstepA, voffA); PG8_STAGE(PG8_SB(1, 1), cB + hstep + kstep, voffB);
;         PG8_WAIT_V(6); PG8_BAR;
;     } else {
;         PG8_STAGE(PG8_SB(0, 0), cB, voffB); PG8_STAGE(PG8_SA(0, 0), cA, voffA); PG8_STAGE(PG8_SB(0, 1), cB + hstep, voffB); PG8_STAGE(PG8_SA(0, 1), cA + hstepA, voffA);
;         if (wr == 1) PG8_BAR;
;         PG8_WAIT_V(4); PG8_BAR;
;         PG8_STAGE(PG8_SB(1, 0), cB + kstep, voffB); PG8_STAGE(PG8_SA(1, 0), cA + kstepA, voffA); PG8_STAGE(PG8_SB(1, 1), cB + hstep + kstep, voffB);
;         PG8_WAIT_V(6); PG8_BAR;
;     }
;     for (;;) {
;         const bool has_next = Epi::AFTER_DRAIN ? false : S.next(ui + 1, nxt);
;         const char* nA = has_next ? (const char*)g.A + (size_t)nxt.pm * tstepA : cA; const char* nB = has_next ? (const char*)g.Bt + (size_t)nxt.pn * tstep : cB;
;         constexpr bool PEEL = SP2 && !Epi::AFTER_DRAIN;
;         if constexpr (PEEL) {
;             const char* a1 = cA + kstepA; const char* a2 = cA + 2 * kstepA; const char* b2 = cB + 2 * kstep; const char* a3 = a2 + kstepA; const char* b3 = b2 + kstep;
;             PG8_ITER(PG8_MMAZ)
;         } else {
; #pragma unroll
;             for (int a = 0; a < 2; ++a)
; #pragma unroll
;                 for (int b = 0; b < 2; ++b)
; #pragma unroll
;                     for (int m = 0; m < 4; ++m)
; #pragma unroll
;                         for (int n = 0; n < 2; ++n) acc[a][b][m][n] = (f32x4){0.f, 0.f, 0.f, 0.f};
.LBB0_2728:
	v_and_b32_e32 v15, 48, v8
	v_lshlrev_b32_e32 v16, 6, v8
	s_movk_i32 s36, 0x3c0
	v_lshlrev_b32_e32 v8, 2, v8
	s_and_b32 s9, s1, 3
	s_lshl_b32 s8, s23, 6
	s_lshl_b32 s23, s23, 13
	v_and_or_b32 v15, v16, s36, v15
	v_and_b32_e32 v8, 32, v8
	s_mov_b64 s[60:61], 0x80
	v_bitop3_b32 v16, v15, s23, v8 bitop3:0xde
	s_lshl_b32 s23, s9, 12
	s_add_i32 m0, s14, 0x18000
	v_lshl_add_u64 v[6:7], v[6:7], 0, s[60:61]
	v_bitop3_b32 v8, v15, s23, v8 bitop3:0xde
	s_waitcnt vmcnt(2)
	s_barrier
	global_load_lds_dwordx4 v[6:7], off
	v_lshl_add_u64 v[4:5], v[4:5], 0, s[60:61]
	s_add_i32 m0, s14, 0x1a000
	s_add_i32 s23, s14, 0x8000
	s_add_i32 s36, s14, 0xa000
	global_load_lds_dwordx4 v[4:5], off
	v_lshl_add_u64 v[2:3], v[2:3], 0, s[60:61]
	s_mov_b32 m0, s23
	s_add_u32 s38, s2, 0x80080
	global_load_lds_dwordx4 v[2:3], off
	v_lshl_add_u64 v[0:1], v[0:1], 0, s[60:61]
	s_mov_b32 m0, s36
	s_addc_u32 s39, s3, 0
	global_load_lds_dwordx4 v[0:1], off
	s_add_i32 m0, s14, 0x1c000
	v_lshl_add_u64 v[0:1], s[38:39], 0, v[34:35]
	global_load_lds_dwordx4 v34, s[38:39]
	v_lshl_add_u64 v[0:1], s[38:39], 0, v[134:135]
	s_add_i32 m0, s14, 0x1e000
	s_mov_b64 s[40:41], 0x20680080
	global_load_lds_dwordx4 v134, s[38:39]
	v_lshlrev_b32_e32 v0, 15, v12
	v_and_b32_e32 v0, 0xffff0000, v0
	v_lshl_add_u32 v0, v13, 12, v0
	v_and_b32_e32 v1, 1, v12
	v_lshl_or_b32 v0, v1, 6, v0
	v_lshl_add_u32 v0, v14, 1, v0
	v_mov_b32_e32 v1, v35
	v_lshl_add_u64 v[0:1], s[62:63], 0, v[0:1]
	v_lshl_add_u64 v[136:137], v[0:1], 0, s[40:41]
	v_lshlrev_b32_e32 v0, 15, v9
	v_and_b32_e32 v0, 0xffff0000, v0
	v_lshl_add_u32 v0, v10, 12, v0
	v_and_b32_e32 v1, 1, v9
	s_add_u32 s37, s64, 0x9e00100
	v_lshl_or_b32 v0, v1, 6, v0
	s_addc_u32 s38, s65, 0
	v_lshl_add_u32 v0, v11, 1, v0
	v_mov_b32_e32 v1, v35
	v_lshl_add_u64 v[0:1], s[62:63], 0, v[0:1]
	s_add_u32 s39, s62, 0x20600100
	s_waitcnt vmcnt(6)
	v_lshl_add_u64 v[138:139], v[0:1], 0, s[40:41]
	s_addc_u32 s40, s63, 0
	s_bitcmp1_b32 s33, 8
	s_cbranch_scc1 .Lsp_12
	s_setprio 1
.Lsp_12:
	s_add_i32 s47, 0, 0x10000
	s_add_i32 s49, 0, 0x14000
	s_add_i32 s51, 0, 0x18000
	s_add_i32 s54, 0, 0x1c000
	v_add_u32_e32 v140, s47, v8
	v_add_u32_e32 v141, s49, v8
	s_add_i32 s47, s47, s53
	s_add_i32 s49, s49, s53
	v_add_u32_e32 v143, s51, v8
	s_add_i32 s51, s51, s53
	s_add_i32 s53, s54, s53
	s_mov_b32 s41, -2
	v_add_u32_e32 v142, 0, v16
	s_add_i32 s42, s14, 0xc000
	s_add_i32 s43, s14, 0xe000
	s_add_i32 s48, s47, 0x2000
	s_add_i32 s50, s49, 0x2000
	v_add_u32_e32 v144, s54, v8
	s_add_i32 s52, s51, 0x2000
	s_add_i32 s54, s53, 0x2000
	s_mov_b64 s[62:63], 0x100
	v_mov_b32_e32 v0, v35
	v_mov_b32_e32 v1, v35
	v_mov_b32_e32 v2, v35
	v_mov_b32_e32 v3, v35
	v_mov_b32_e32 v4, v35
	v_mov_b32_e32 v5, v35
	v_mov_b32_e32 v6, v35
	v_mov_b32_e32 v7, v35
	v_mov_b32_e32 v40, v35
	v_mov_b32_e32 v41, v35
	v_mov_b32_e32 v42, v35
	v_mov_b32_e32 v43, v35
	v_mov_b32_e32 v44, v35
	v_mov_b32_e32 v45, v35
	v_mov_b32_e32 v46, v35
	v_mov_b32_e32 v47, v35
	v_mov_b32_e32 v88, v35
	v_mov_b32_e32 v89, v35
	v_mov_b32_e32 v90, v35
	v_mov_b32_e32 v91, v35
	v_mov_b32_e32 v92, v35
	v_mov_b32_e32 v93, v35
	v_mov_b32_e32 v94, v35
	v_mov_b32_e32 v95, v35
	v_mov_b32_e32 v112, v35
	v_mov_b32_e32 v113, v35
	v_mov_b32_e32 v114, v35
	v_mov_b32_e32 v115, v35
	v_mov_b32_e32 v124, v35
	v_mov_b32_e32 v125, v35
	v_mov_b32_e32 v126, v35
	v_mov_b32_e32 v127, v35
	v_mov_b32_e32 v28, v35
	v_mov_b32_e32 v29, v35
	v_mov_b32_e32 v30, v35
	v_mov_b32_e32 v31, v35
	v_mov_b32_e32 v36, v35
	v_mov_b32_e32 v37, v35
	v_mov_b32_e32 v38, v35
	v_mov_b32_e32 v39, v35
	v_mov_b32_e32 v80, v35
	v_mov_b32_e32 v81, v35
	v_mov_b32_e32 v82, v35
	v_mov_b32_e32 v83, v35
	v_mov_b32_e32 v84, v35
	v_mov_b32_e32 v85, v35
	v_mov_b32_e32 v86, v35
	v_mov_b32_e32 v87, v35
	v_mov_b32_e32 v120, v35
	v_mov_b32_e32 v121, v35
	v_mov_b32_e32 v122, v35
	v_mov_b32_e32 v123, v35
	v_mov_b32_e32 v116, v35
	v_mov_b32_e32 v117, v35
	v_mov_b32_e32 v118, v35
	v_mov_b32_e32 v119, v35
	v_mov_b32_e32 v104, v35
	v_mov_b32_e32 v105, v35
	v_mov_b32_e32 v106, v35
	v_mov_b32_e32 v107, v35
	v_mov_b32_e32 v100, v35
	v_mov_b32_e32 v101, v35
	v_mov_b32_e32 v102, v35
	v_mov_b32_e32 v103, v35
	v_mov_b32_e32 v96, v35
	v_mov_b32_e32 v97, v35
	v_mov_b32_e32 v98, v35
	v_mov_b32_e32 v99, v35
	v_mov_b32_e32 v108, v35
	v_mov_b32_e32 v109, v35
	v_mov_b32_e32 v110, v35
	v_mov_b32_e32 v111, v35
	v_mov_b32_e32 v64, v35
	v_mov_b32_e32 v65, v35
	v_mov_b32_e32 v66, v35
	v_mov_b32_e32 v67, v35
	v_mov_b32_e32 v72, v35
	v_mov_b32_e32 v73, v35
	v_mov_b32_e32 v74, v35
	v_mov_b32_e32 v75, v35
	v_mov_b32_e32 v48, v35
	v_mov_b32_e32 v49, v35
	v_mov_b32_e32 v50, v35
	v_mov_b32_e32 v51, v35
	v_mov_b32_e32 v56, v35
	v_mov_b32_e32 v57, v35
	v_mov_b32_e32 v58, v35
	v_mov_b32_e32 v59, v35
	v_mov_b32_e32 v16, v35
	v_mov_b32_e32 v17, v35
	v_mov_b32_e32 v18, v35
	v_mov_b32_e32 v19, v35
	v_mov_b32_e32 v24, v35
	v_mov_b32_e32 v25, v35
	v_mov_b32_e32 v26, v35
	v_mov_b32_e32 v27, v35
	v_mov_b32_e32 v68, v35
	v_mov_b32_e32 v69, v35
	v_mov_b32_e32 v70, v35
	v_mov_b32_e32 v71, v35
	v_mov_b32_e32 v128, v35
	v_mov_b32_e32 v129, v35
	v_mov_b32_e32 v130, v35
	v_mov_b32_e32 v131, v35
	v_mov_b32_e32 v52, v35
	v_mov_b32_e32 v53, v35
	v_mov_b32_e32 v54, v35
	v_mov_b32_e32 v55, v35
	v_mov_b32_e32 v76, v35
	v_mov_b32_e32 v77, v35
	v_mov_b32_e32 v78, v35
	v_mov_b32_e32 v79, v35
	v_mov_b32_e32 v20, v35
	v_mov_b32_e32 v21, v35
	v_mov_b32_e32 v22, v35
	v_mov_b32_e32 v23, v35
	v_mov_b32_e32 v60, v35
	v_mov_b32_e32 v61, v35
	v_mov_b32_e32 v62, v35
	v_mov_b32_e32 v63, v35
	v_mov_b32_e32 v12, v35
	v_mov_b32_e32 v13, v35
	v_mov_b32_e32 v14, v35
	v_mov_b32_e32 v15, v35
	v_mov_b32_e32 v8, v35
	v_mov_b32_e32 v9, v35
	v_mov_b32_e32 v10, v35
	v_mov_b32_e32 v11, v35
	s_barrier
; #define PG8_MMA(ai, bj, At, Bt) do { __builtin_amdgcn_s_setprio(1); _Pragma("unroll") for (int m = 0; m < 4; ++m) _Pragma("unroll") for (int n = 0; n < 2; ++n) _Pragma("unroll") for (int k = 0; k < 2; ++k) \
;         acc[ai][bj][m][n] = __builtin_amdgcn_mfma_f32_16x16x32_bf16(Bt[n][k], At[m][k], acc[ai][bj][m][n], 0, 0, 0); __builtin_amdgcn_s_setprio(0); } while (0)
; template <class Epi, class Sched, bool ALIGN_EPI = false, bool SP2 = false, bool A_TILED = false>
; __device__ __forceinline__ void gemm_phase(PG8_LAS unsigned char* lds, const Gemm g, const Sched& S, const Epi& E, const int wave_s) {
;     ...
;         for (int t = PEEL ? 2 : 0; t < nt; t += 2) {
;             const bool last = (t == nt - 2);
;             const char* a1 = cA + (size_t)(t + 1) * kstepA;
;             const char* a2 = last ? nA : cA + (size_t)(t + 2) * kstepA; const char* b2 = last ? nB : cB + (size_t)(t + 2) * kstep;
;             const char* a3 = a2 + kstepA; const char* b3 = b2 + kstep;
;             if (last && has_next) S.a_ready(nxt);
;             if constexpr (SP2) {
;             PG8_ITER(PG8_MMA)
.LBB0_2729:
	ds_read_b128 v[146:149], v140
	ds_read_b128 v[150:153], v140 offset:1024
	ds_read_b128 v[154:157], v140 offset:2048
	ds_read_b128 v[158:161], v140 offset:3072
	ds_read_b128 v[162:165], v141
	ds_read_b128 v[166:169], v141 offset:1024
	ds_read_b128 v[170:173], v141 offset:2048
	ds_read_b128 v[174:177], v141 offset:3072
	s_add_u32 s55, s44, s39
	s_addc_u32 s56, s45, s40
	s_add_u32 s57, s44, s37
	s_addc_u32 s58, s45, s38
	s_cmp_eq_u32 s41, 28
	s_cselect_b32 s67, s7, s56
	s_cselect_b32 s66, s6, s55
	s_cselect_b32 s65, s3, s58
	s_cselect_b32 s64, s2, s57
	s_mov_b32 m0, s42
	v_lshl_add_u64 v[210:211], s[44:45], 0, v[138:139]
	ds_read_b128 v[178:181], v142
	ds_read_b128 v[182:185], v142 offset:1024
	ds_read_b128 v[186:189], v142 offset:2048
	ds_read_b128 v[190:193], v142 offset:3072
	ds_read_b128 v[194:197], v142 offset:4096
	ds_read_b128 v[198:201], v142 offset:5120
	ds_read_b128 v[202:205], v142 offset:6144
	ds_read_b128 v[206:209], v142 offset:7168
	global_load_lds_dwordx4 v[210:211], off
	v_lshl_add_u64 v[210:211], s[44:45], 0, v[136:137]
	s_mov_b32 m0, s43
	s_nop 0
	global_load_lds_dwordx4 v[210:211], off
	s_waitcnt vmcnt(8) lgkmcnt(0)
	s_barrier
	v_mfma_f32_16x16x32_bf16 v[8:11], v[146:149], v[178:181], v[8:11]
	v_mfma_f32_16x16x32_bf16 v[12:15], v[154:157], v[178:181], v[12:15]
	v_mfma_f32_16x16x32_bf16 v[60:63], v[146:149], v[186:189], v[60:63]
	v_mfma_f32_16x16x32_bf16 v[20:23], v[154:157], v[186:189], v[20:23]
	v_mfma_f32_16x16x32_bf16 v[76:79], v[146:149], v[194:197], v[76:79]
	v_mfma_f32_16x16x32_bf16 v[52:55], v[154:157], v[194:197], v[52:55]
	v_mfma_f32_16x16x32_bf16 v[128:131], v[146:149], v[202:205], v[128:131]
	v_mfma_f32_16x16x32_bf16 v[68:71], v[154:157], v[202:205], v[68:71]
	v_mfma_f32_16x16x32_bf16 v[8:11], v[150:153], v[182:185], v[8:11]
	v_mfma_f32_16x16x32_bf16 v[12:15], v[158:161], v[182:185], v[12:15]
	v_mfma_f32_16x16x32_bf16 v[60:63], v[150:153], v[190:193], v[60:63]
	v_mfma_f32_16x16x32_bf16 v[20:23], v[158:161], v[190:193], v[20:23]
	v_mfma_f32_16x16x32_bf16 v[76:79], v[150:153], v[198:201], v[76:79]
	v_mfma_f32_16x16x32_bf16 v[52:55], v[158:161], v[198:201], v[52:55]
	v_mfma_f32_16x16x32_bf16 v[128:131], v[150:153], v[206:209], v[128:131]
	v_mfma_f32_16x16x32_bf16 v[68:71], v[158:161], v[206:209], v[68:71]
	v_mfma_f32_16x16x32_bf16 v[24:27], v[162:165], v[178:181], v[24:27]
	v_mfma_f32_16x16x32_bf16 v[16:19], v[170:173], v[178:181], v[16:19]
	v_mfma_f32_16x16x32_bf16 v[56:59], v[162:165], v[186:189], v[56:59]
	v_mfma_f32_16x16x32_bf16 v[48:51], v[170:173], v[186:189], v[48:51]
	v_mfma_f32_16x16x32_bf16 v[72:75], v[162:165], v[194:197], v[72:75]
	v_mfma_f32_16x16x32_bf16 v[64:67], v[170:173], v[194:197], v[64:67]
	v_mfma_f32_16x16x32_bf16 v[108:111], v[162:165], v[202:205], v[108:111]
	v_mfma_f32_16x16x32_bf16 v[96:99], v[170:173], v[202:205], v[96:99]
	v_mfma_f32_16x16x32_bf16 v[24:27], v[166:169], v[182:185], v[24:27]
	v_mfma_f32_16x16x32_bf16 v[16:19], v[174:177], v[182:185], v[16:19]
	v_mfma_f32_16x16x32_bf16 v[56:59], v[166:169], v[190:193], v[56:59]
	v_mfma_f32_16x16x32_bf16 v[48:51], v[174:177], v[190:193], v[48:51]
	v_mfma_f32_16x16x32_bf16 v[72:75], v[166:169], v[198:201], v[72:75]
	v_mfma_f32_16x16x32_bf16 v[64:67], v[174:177], v[198:201], v[64:67]
	v_mfma_f32_16x16x32_bf16 v[108:111], v[166:169], v[206:209], v[108:111]
	v_mfma_f32_16x16x32_bf16 v[96:99], v[174:177], v[206:209], v[96:99]
	s_barrier
	s_mov_b32 m0, s47
	v_lshl_add_u64 v[210:211], s[64:65], 0, v[34:35]
	s_add_u32 s56, s64, 0x80000
	ds_read_b128 v[178:181], v142 offset:16384
	ds_read_b128 v[182:185], v142 offset:17408
	ds_read_b128 v[186:189], v142 offset:18432
	ds_read_b128 v[190:193], v142 offset:19456
	ds_read_b128 v[194:197], v142 offset:20480
	ds_read_b128 v[198:201], v142 offset:21504
	ds_read_b128 v[202:205], v142 offset:22528
	ds_read_b128 v[206:209], v142 offset:23552
	global_load_lds_dwordx4 v34, s[64:65]
	v_lshl_add_u64 v[212:213], s[64:65], 0, v[134:135]
	s_mov_b32 m0, s48
	s_addc_u32 s57, s65, 0
	global_load_lds_dwordx4 v134, s[64:65]
	v_lshl_add_u64 v[214:215], s[56:57], 0, v[34:35]
	s_mov_b32 m0, s49
	v_lshl_add_u64 v[216:217], s[66:67], 0, v[132:133]
	global_load_lds_dwordx4 v34, s[56:57]
	v_lshl_add_u64 v[214:215], s[56:57], 0, v[134:135]
	s_mov_b32 m0, s50
	s_nop 0
	global_load_lds_dwordx4 v134, s[56:57]
	v_lshl_add_u64 v[214:215], s[66:67], 0, v[32:33]
	s_mov_b32 m0, s14
	s_nop 0
	global_load_lds_dwordx4 v32, s[66:67]
	s_mov_b32 m0, s15
	s_nop 0
	global_load_lds_dwordx4 v132, s[66:67]
	s_waitcnt vmcnt(8) lgkmcnt(0)
	s_barrier
	v_mfma_f32_16x16x32_bf16 v[100:103], v[146:149], v[178:181], v[100:103]
	v_mfma_f32_16x16x32_bf16 v[104:107], v[154:157], v[178:181], v[104:107]
	v_mfma_f32_16x16x32_bf16 v[116:119], v[146:149], v[186:189], v[116:119]
	v_mfma_f32_16x16x32_bf16 v[120:123], v[154:157], v[186:189], v[120:123]
	v_mfma_f32_16x16x32_bf16 v[84:87], v[146:149], v[194:197], v[84:87]
	v_mfma_f32_16x16x32_bf16 v[80:83], v[154:157], v[194:197], v[80:83]
	v_mfma_f32_16x16x32_bf16 v[36:39], v[146:149], v[202:205], v[36:39]
	v_mfma_f32_16x16x32_bf16 v[28:31], v[154:157], v[202:205], v[28:31]
	v_mfma_f32_16x16x32_bf16 v[100:103], v[150:153], v[182:185], v[100:103]
	v_mfma_f32_16x16x32_bf16 v[104:107], v[158:161], v[182:185], v[104:107]
	v_mfma_f32_16x16x32_bf16 v[116:119], v[150:153], v[190:193], v[116:119]
	v_mfma_f32_16x16x32_bf16 v[120:123], v[158:161], v[190:193], v[120:123]
	v_mfma_f32_16x16x32_bf16 v[84:87], v[150:153], v[198:201], v[84:87]
	v_mfma_f32_16x16x32_bf16 v[80:83], v[158:161], v[198:201], v[80:83]
	v_mfma_f32_16x16x32_bf16 v[36:39], v[150:153], v[206:209], v[36:39]
	v_mfma_f32_16x16x32_bf16 v[28:31], v[158:161], v[206:209], v[28:31]
	v_mfma_f32_16x16x32_bf16 v[124:127], v[162:165], v[178:181], v[124:127]
	v_mfma_f32_16x16x32_bf16 v[112:115], v[170:173], v[178:181], v[112:115]
	v_mfma_f32_16x16x32_bf16 v[92:95], v[162:165], v[186:189], v[92:95]
	v_mfma_f32_16x16x32_bf16 v[88:91], v[170:173], v[186:189], v[88:91]
	v_mfma_f32_16x16x32_bf16 v[44:47], v[162:165], v[194:197], v[44:47]
	v_mfma_f32_16x16x32_bf16 v[40:43], v[170:173], v[194:197], v[40:43]
	v_mfma_f32_16x16x32_bf16 v[4:7], v[162:165], v[202:205], v[4:7]
	v_mfma_f32_16x16x32_bf16 v[0:3], v[170:173], v[202:205], v[0:3]
	v_mfma_f32_16x16x32_bf16 v[124:127], v[166:169], v[182:185], v[124:127]
	v_mfma_f32_16x16x32_bf16 v[112:115], v[174:177], v[182:185], v[112:115]
	v_mfma_f32_16x16x32_bf16 v[92:95], v[166:169], v[190:193], v[92:95]
	v_mfma_f32_16x16x32_bf16 v[88:91], v[174:177], v[190:193], v[88:91]
	v_mfma_f32_16x16x32_bf16 v[44:47], v[166:169], v[198:201], v[44:47]
	v_mfma_f32_16x16x32_bf16 v[40:43], v[174:177], v[198:201], v[40:43]
	v_mfma_f32_16x16x32_bf16 v[4:7], v[166:169], v[206:209], v[4:7]
	v_mfma_f32_16x16x32_bf16 v[0:3], v[174:177], v[206:209], v[0:3]
	s_barrier
	ds_read_b128 v[146:149], v143
	ds_read_b128 v[150:153], v143 offset:1024
	ds_read_b128 v[154:157], v143 offset:2048
	ds_read_b128 v[158:161], v143 offset:3072
	ds_read_b128 v[162:165], v144
	ds_read_b128 v[166:169], v144 offset:1024
	ds_read_b128 v[170:173], v144 offset:2048
	ds_read_b128 v[174:177], v144 offset:3072
	s_add_u32 s56, s66, 0x80000
	s_addc_u32 s57, s67, 0
	s_mov_b32 m0, s21
	v_lshl_add_u64 v[218:219], s[56:57], 0, v[32:33]
	ds_read_b128 v[178:181], v142 offset:32768
	ds_read_b128 v[182:185], v142 offset:33792
	ds_read_b128 v[186:189], v142 offset:34816
	ds_read_b128 v[190:193], v142 offset:35840
	ds_read_b128 v[194:197], v142 offset:36864
	ds_read_b128 v[198:201], v142 offset:37888
	ds_read_b128 v[202:205], v142 offset:38912
	ds_read_b128 v[206:209], v142 offset:39936
	global_load_lds_dwordx4 v32, s[56:57]
	v_lshl_add_u64 v[218:219], s[56:57], 0, v[132:133]
	s_mov_b32 m0, s22
	s_nop 0
	global_load_lds_dwordx4 v132, s[56:57]
	s_waitcnt vmcnt(8) lgkmcnt(0)
	s_barrier
	v_mfma_f32_16x16x32_bf16 v[8:11], v[146:149], v[178:181], v[8:11]
	v_mfma_f32_16x16x32_bf16 v[12:15], v[154:157], v[178:181], v[12:15]
	v_mfma_f32_16x16x32_bf16 v[60:63], v[146:149], v[186:189], v[60:63]
	v_mfma_f32_16x16x32_bf16 v[20:23], v[154:157], v[186:189], v[20:23]
	v_mfma_f32_16x16x32_bf16 v[76:79], v[146:149], v[194:197], v[76:79]
	v_mfma_f32_16x16x32_bf16 v[52:55], v[154:157], v[194:197], v[52:55]
	v_mfma_f32_16x16x32_bf16 v[128:131], v[146:149], v[202:205], v[128:131]
	v_mfma_f32_16x16x32_bf16 v[68:71], v[154:157], v[202:205], v[68:71]
	v_mfma_f32_16x16x32_bf16 v[8:11], v[150:153], v[182:185], v[8:11]
	v_mfma_f32_16x16x32_bf16 v[12:15], v[158:161], v[182:185], v[12:15]
	v_mfma_f32_16x16x32_bf16 v[60:63], v[150:153], v[190:193], v[60:63]
	v_mfma_f32_16x16x32_bf16 v[20:23], v[158:161], v[190:193], v[20:23]
	v_mfma_f32_16x16x32_bf16 v[76:79], v[150:153], v[198:201], v[76:79]
	v_mfma_f32_16x16x32_bf16 v[52:55], v[158:161], v[198:201], v[52:55]
	v_mfma_f32_16x16x32_bf16 v[128:131], v[150:153], v[206:209], v[128:131]
	v_mfma_f32_16x16x32_bf16 v[68:71], v[158:161], v[206:209], v[68:71]
	v_mfma_f32_16x16x32_bf16 v[24:27], v[162:165], v[178:181], v[24:27]
	v_mfma_f32_16x16x32_bf16 v[16:19], v[170:173], v[178:181], v[16:19]
	v_mfma_f32_16x16x32_bf16 v[56:59], v[162:165], v[186:189], v[56:59]
	v_mfma_f32_16x16x32_bf16 v[48:51], v[170:173], v[186:189], v[48:51]
	v_mfma_f32_16x16x32_bf16 v[72:75], v[162:165], v[194:197], v[72:75]
	v_mfma_f32_16x16x32_bf16 v[64:67], v[170:173], v[194:197], v[64:67]
	v_mfma_f32_16x16x32_bf16 v[108:111], v[162:165], v[202:205], v[108:111]
	v_mfma_f32_16x16x32_bf16 v[96:99], v[170:173], v[202:205], v[96:99]
	v_mfma_f32_16x16x32_bf16 v[24:27], v[166:169], v[182:185], v[24:27]
	v_mfma_f32_16x16x32_bf16 v[16:19], v[174:177], v[182:185], v[16:19]
	v_mfma_f32_16x16x32_bf16 v[56:59], v[166:169], v[190:193], v[56:59]
	v_mfma_f32_16x16x32_bf16 v[48:51], v[174:177], v[190:193], v[48:51]
	v_mfma_f32_16x16x32_bf16 v[72:75], v[166:169], v[198:201], v[72:75]
	v_mfma_f32_16x16x32_bf16 v[64:67], v[174:177], v[198:201], v[64:67]
	v_mfma_f32_16x16x32_bf16 v[108:111], v[166:169], v[206:209], v[108:111]
	v_mfma_f32_16x16x32_bf16 v[96:99], v[174:177], v[206:209], v[96:99]
	s_barrier
; template <class Epi, class Sched, bool ALIGN_EPI = false, bool SP2 = false, bool A_TILED = false>
; __device__ __forceinline__ void gemm_phase(PG8_LAS unsigned char* lds, const Gemm g, const Sched& S, const Epi& E, const int wave_s) {
;     ...
;         for (int t = PEEL ? 2 : 0; t < nt; t += 2) {
;             const bool last = (t == nt - 2);
;             const char* a1 = cA + (size_t)(t + 1) * kstepA;
;             const char* a2 = last ? nA : cA + (size_t)(t + 2) * kstepA; const char* b2 = last ? nB : cB + (size_t)(t + 2) * kstep;
;             const char* a3 = a2 + kstepA; const char* b3 = b2 + kstep;
;             if (last && has_next) S.a_ready(nxt);
;             if constexpr (SP2) {
;             PG8_ITER(PG8_MMA)
;             } else {
;             PG8_LDB(B0, 0, 0); PG8_SCHED; PG8_LDA(At, 0, 0); PG8_STAGE(PG8_SA(1, 1), a1 + hstepA, voffA);
;             PG8_WAIT_L(8); PG8_BAR; PG8_WAIT_L(0); PG8_MMA(0, 0, At, B0); PG8_BAR; PG8_SCHED;
;             PG8_LDB(B1, 0, 1); PG8_STAGE(PG8_SB(0, 0), b2, voffB);
;             PG8_BAR; PG8_WAIT_L(0); PG8_MMA(0, 1, At, B1); PG8_BAR;
;             PG8_LDA(At, 0, 1); PG8_STAGE(PG8_SA(0, 0), a2, voffA);
;             PG8_BAR; PG8_WAIT_L(0); PG8_MMA(1, 0, At, B0); PG8_BAR; PG8_SCHED;
;             PG8_STAGE(PG8_SB(0, 1), b2 + hstep, voffB);
;             PG8_WAIT_V(6); PG8_BAR; PG8_MMA(1, 1, At, B1); PG8_BAR;
;             PG8_LDB(B0, 1, 0); PG8_SCHED; PG8_LDA(At, 1, 0); PG8_STAGE(PG8_SA(0, 1), a2 + hstepA, voffA);
;             PG8_WAIT_L(8); PG8_BAR; PG8_WAIT_L(0); PG8_MMA(0, 0, At, B0); PG8_BAR; PG8_SCHED;
;             PG8_LDB(B1, 1, 1); PG8_STAGE(PG8_SB(1, 0), b3, voffB);
;             PG8_BAR; PG8_WAIT_L(0); PG8_MMA(0, 1, At, B1); PG8_BAR;
;             PG8_LDA(At, 1, 1); PG8_STAGE(PG8_SA(1, 0), a3, voffA);
;             PG8_BAR; PG8_WAIT_L(0); PG8_MMA(1, 0, At, B0); PG8_BAR; PG8_SCHED;
;             PG8_STAGE(PG8_SB(1, 1), b3 + hstep, voffB);
;             PG8_WAIT_V(6); PG8_BAR; PG8_MMA(1, 1, At, B1); PG8_BAR;
;             }
;         }
;         if constexpr (ALIGN_EPI) { if (wr == 0) PG8_BAR; }
;         if constexpr (!Epi::AFTER_DRAIN) { int te = tid_now(wave_s); asm volatile("" : "+v"(te));
;             E(acc, cur, wr, wc, te & 15, (te & 63) >> 4); S.done(cur); }
;         if (!has_next) break;
;         cur = nxt; cA = nA; cB = nB; ++ui;
;         if constexpr (ALIGN_EPI) { if (wr == 1) PG8_BAR; }
	s_mov_b32 m0, s51
	v_lshl_add_u64 v[210:211], v[210:211], 0, s[60:61]
	s_add_u32 s56, s64, 0x80080
	ds_read_b128 v[178:181], v142 offset:49152
	ds_read_b128 v[182:185], v142 offset:50176
	ds_read_b128 v[186:189], v142 offset:51200
	ds_read_b128 v[190:193], v142 offset:52224
	ds_read_b128 v[194:197], v142 offset:53248
	ds_read_b128 v[198:201], v142 offset:54272
	ds_read_b128 v[202:205], v142 offset:55296
	ds_read_b128 v[206:209], v142 offset:56320
	global_load_lds_dwordx4 v[210:211], off
	v_lshl_add_u64 v[210:211], v[212:213], 0, s[60:61]
	s_mov_b32 m0, s52
	s_addc_u32 s57, s65, 0
	global_load_lds_dwordx4 v[210:211], off
	v_lshl_add_u64 v[210:211], s[56:57], 0, v[34:35]
	s_mov_b32 m0, s53
	s_nop 0
	global_load_lds_dwordx4 v34, s[56:57]
	v_lshl_add_u64 v[210:211], s[56:57], 0, v[134:135]
	s_mov_b32 m0, s54
	s_nop 0
	global_load_lds_dwordx4 v134, s[56:57]
	v_lshl_add_u64 v[210:211], v[214:215], 0, s[60:61]
	s_mov_b32 m0, s23
	s_nop 0
	global_load_lds_dwordx4 v[210:211], off
	v_lshl_add_u64 v[210:211], v[216:217], 0, s[60:61]
	s_mov_b32 m0, s36
	s_nop 0
	global_load_lds_dwordx4 v[210:211], off
	s_waitcnt vmcnt(8) lgkmcnt(0)
	s_barrier
	v_mfma_f32_16x16x32_bf16 v[100:103], v[146:149], v[178:181], v[100:103]
	v_mfma_f32_16x16x32_bf16 v[104:107], v[154:157], v[178:181], v[104:107]
	v_mfma_f32_16x16x32_bf16 v[116:119], v[146:149], v[186:189], v[116:119]
	v_mfma_f32_16x16x32_bf16 v[120:123], v[154:157], v[186:189], v[120:123]
	v_mfma_f32_16x16x32_bf16 v[84:87], v[146:149], v[194:197], v[84:87]
	v_mfma_f32_16x16x32_bf16 v[80:83], v[154:157], v[194:197], v[80:83]
	v_mfma_f32_16x16x32_bf16 v[36:39], v[146:149], v[202:205], v[36:39]
	v_mfma_f32_16x16x32_bf16 v[28:31], v[154:157], v[202:205], v[28:31]
	v_mfma_f32_16x16x32_bf16 v[100:103], v[150:153], v[182:185], v[100:103]
	v_mfma_f32_16x16x32_bf16 v[104:107], v[158:161], v[182:185], v[104:107]
	v_mfma_f32_16x16x32_bf16 v[116:119], v[150:153], v[190:193], v[116:119]
	v_mfma_f32_16x16x32_bf16 v[120:123], v[158:161], v[190:193], v[120:123]
	v_mfma_f32_16x16x32_bf16 v[84:87], v[150:153], v[198:201], v[84:87]
	v_mfma_f32_16x16x32_bf16 v[80:83], v[158:161], v[198:201], v[80:83]
	v_mfma_f32_16x16x32_bf16 v[36:39], v[150:153], v[206:209], v[36:39]
	v_mfma_f32_16x16x32_bf16 v[28:31], v[158:161], v[206:209], v[28:31]
	v_mfma_f32_16x16x32_bf16 v[124:127], v[162:165], v[178:181], v[124:127]
	v_mfma_f32_16x16x32_bf16 v[112:115], v[170:173], v[178:181], v[112:115]
	v_mfma_f32_16x16x32_bf16 v[92:95], v[162:165], v[186:189], v[92:95]
	v_mfma_f32_16x16x32_bf16 v[88:91], v[170:173], v[186:189], v[88:91]
	v_mfma_f32_16x16x32_bf16 v[44:47], v[162:165], v[194:197], v[44:47]
	v_mfma_f32_16x16x32_bf16 v[40:43], v[170:173], v[194:197], v[40:43]
	v_mfma_f32_16x16x32_bf16 v[4:7], v[162:165], v[202:205], v[4:7]
	v_mfma_f32_16x16x32_bf16 v[0:3], v[170:173], v[202:205], v[0:3]
	v_mfma_f32_16x16x32_bf16 v[124:127], v[166:169], v[182:185], v[124:127]
	v_mfma_f32_16x16x32_bf16 v[112:115], v[174:177], v[182:185], v[112:115]
	v_mfma_f32_16x16x32_bf16 v[92:95], v[166:169], v[190:193], v[92:95]
	v_mfma_f32_16x16x32_bf16 v[88:91], v[174:177], v[190:193], v[88:91]
	v_mfma_f32_16x16x32_bf16 v[44:47], v[166:169], v[198:201], v[44:47]
	v_mfma_f32_16x16x32_bf16 v[40:43], v[174:177], v[198:201], v[40:43]
	v_mfma_f32_16x16x32_bf16 v[4:7], v[166:169], v[206:209], v[4:7]
	v_mfma_f32_16x16x32_bf16 v[0:3], v[174:177], v[206:209], v[0:3]
	s_barrier
	s_add_i32 s41, s41, 2
	s_add_u32 s37, s37, 0x100
	s_addc_u32 s38, s38, 0
	s_add_u32 s39, s39, 0x100
	s_addc_u32 s40, s40, 0
	v_lshl_add_u64 v[136:137], v[136:137], 0, s[62:63]
	s_cmp_gt_u32 s41, 29
	v_lshl_add_u64 v[138:139], v[138:139], 0, s[62:63]
	s_cbranch_scc0 .LBB0_2729
	s_waitcnt vmcnt(0)
	s_cmpk_lt_u32 s0, 0x100
	s_cbranch_scc0 .LBB0_2732
	s_barrier

; __device__ __forceinline__ int tid_now(int wave_s) { unsigned z = 0u; asm volatile("" : "+v"(z)); return (wave_s << 6) | (int)__builtin_amdgcn_mbcnt_hi(~0u, __builtin_amdgcn_mbcnt_lo(~0u, z)); }
; __device__ __forceinline__ unsigned xb_add(unsigned* p, unsigned v) { return __hip_atomic_fetch_add(p, v, __ATOMIC_RELAXED, __HIP_MEMORY_SCOPE_AGENT); }
; __device__ __forceinline__ void xcd_barrier(const XcdBarrier& b) {
;     asm volatile("s_waitcnt vmcnt(0)" ::: "memory");
;     __syncthreads();
;     if (tid_now(b.w) == 0) {
;         unsigned* bar = b.bar;
;         __builtin_amdgcn_s_waitcnt(0);
;         unsigned nloc = b.st[0], nx = b.st[1];
;         if (nloc == 0u) { xcd_barrier_complete(bar, b.x, nloc, nx, b.np); b.st[0] = nloc; b.st[1] = nx; }
;         const unsigned old = xb_add(&bar[XB_XSUB(b.x)], 1u);
.LBB0_2773:
	s_setprio 0
	s_cmp_gt_i32 s35, 18
	s_cselect_b64 s[2:3], -1, 0
	s_and_b64 s[0:1], s[12:13], s[2:3]
	s_andn2_b64 vcc, exec, s[0:1]
	s_cbranch_vccnz .LBB0_2827
	v_mov_b32_e32 v0, 0
	s_waitcnt vmcnt(0)
	s_waitcnt vmcnt(0) lgkmcnt(0)
	s_barrier
	s_nop 0
	v_mbcnt_lo_u32_b32 v0, -1, v0
	v_mbcnt_hi_u32_b32 v0, -1, v0
	v_or_b32_e32 v0, s33, v0
	v_cmp_eq_u32_e32 vcc, 0, v0
	s_and_saveexec_b64 s[4:5], vcc
	s_cbranch_execz .LBB0_2826
	s_add_i32 s0, 0, 0x27f68
	v_mov_b32_e32 v0, s0
	s_waitcnt vmcnt(0) expcnt(0) lgkmcnt(0)
	ds_read_b32 v2, v0
	s_add_i32 s0, 0, 0x27f6c
	v_mov_b32_e32 v0, s0
	ds_read_b32 v0, v0
	s_waitcnt lgkmcnt(1)
	v_cmp_ne_u32_e32 vcc, 0, v2
	s_cbranch_vccnz .LBB0_2790
	s_add_u32 s6, s10, 0x1000
	s_addc_u32 s7, s11, 0
	s_add_u32 s12, s10, 0x1100
	s_addc_u32 s13, s11, 0
	s_add_u32 s44, s10, 0x1200
	s_addc_u32 s45, s11, 0
	s_add_u32 s46, s10, 0x1300
	s_addc_u32 s47, s11, 0
	s_mov_b32 s0, 1
	v_mov_b32_e32 v16, 0
	s_branch .LBB0_2778

; #define PG8_STAGE(bufoff, gbase, voff) do { _Pragma("unroll") for (int _i = 0; _i < 2; ++_i) \
;         __builtin_amdgcn_global_load_lds((const unsigned*)((const char*)(gbase) + (voff)[_i]), (PG8_LAS unsigned*)(lds + (bufoff) + ldsw + _i * 8192), 16, 0, 0); } while (0)
; #define PG8_WAIT_V(n) asm volatile("s_waitcnt vmcnt(" #n ")" ::: "memory")
; #define PG8_BAR __builtin_amdgcn_s_barrier()
; template <class Epi, class Sched, bool ALIGN_EPI = false, bool SP2 = false, bool A_TILED = false>
; __device__ __forceinline__ void gemm_phase(PG8_LAS unsigned char* lds, const Gemm g, const Sched& S, const Epi& E, const int wave_s) {
;     ...
;     for (int i = 0; i < 2; ++i) { int R, C; stage_rc(tid * 16 + i * 8192, R, C); const int Rb = Epi::PERM ? ((R & ~31) + perm32(R & 31)) : R;
;         voffA[i] = A_TILED ? (unsigned)(tid * 16 + i * 8192) : (unsigned)(R * K + C) * 2u; voffB[i] = (unsigned)(Rb * K + C) * 2u; }
;     const size_t kstep = (size_t)(BK * 2);
;     const size_t hstep = (size_t)HALF * K * 2;
;     const size_t tstep = 2 * hstep;
;     const size_t kstepA = A_TILED ? (size_t)32768 : kstep, hstepA = A_TILED ? (size_t)16384 : hstep, tstepA = A_TILED ? (size_t)nt * 32768 : tstep;
;     const unsigned ldsw = (unsigned)wid * 1024u;
;     const int aoff = lds_byte(wr * 64 + fr, fq * 8), boff = lds_byte(wc * 32 + fr, fq * 8);
;     ...
;     if constexpr (SP2) {
;         PG8_STAGE(PG8_SB(0, 0), cB, voffB); PG8_STAGE(PG8_SB(0, 1), cB + hstep, voffB); PG8_STAGE(PG8_SA(0, 0), cA, voffA); PG8_STAGE(PG8_SA(0, 1), cA + hstepA, voffA);
;         if (wr == 1) PG8_BAR;
;         PG8_WAIT_V(2); PG8_BAR;
;         PG8_STAGE(PG8_SB(1, 0), cB + kstep, voffB); PG8_STAGE(PG8_SA(1, 0), cA + kstepA, voffA); PG8_STAGE(PG8_SB(1, 1), cB + hstep + kstep, voffB);
;         PG8_WAIT_V(6); PG8_BAR;
;     } else {
;         PG8_STAGE(PG8_SB(0, 0), cB, voffB); PG8_STAGE(PG8_SA(0, 0), cA, voffA); PG8_STAGE(PG8_SB(0, 1), cB + hstep, voffB); PG8_STAGE(PG8_SA(0, 1), cA + hstepA, voffA);
;         if (wr == 1) PG8_BAR;
;         PG8_WAIT_V(4); PG8_BAR;
;         PG8_STAGE(PG8_SB(1, 0), cB + kstep, voffB); PG8_STAGE(PG8_SA(1, 0), cA + kstepA, voffA); PG8_STAGE(PG8_SB(1, 1), cB + hstep + kstep, voffB);
;         PG8_WAIT_V(6); PG8_BAR;
;     }
.LBB0_2831:
	s_ashr_i32 s40, s86, 31
	s_add_u32 s41, s2, 0x34600000
	s_addc_u32 s42, s3, 0
	s_lshl_b32 s47, s12, 13
	s_mov_b64 s[12:13], 0x80
	s_and_b32 s2, s46, 3
	s_add_i32 m0, s22, 0x18000
	v_lshl_add_u64 v[6:7], v[6:7], 0, s[12:13]
	s_lshl_b32 s49, s2, 12
	s_waitcnt vmcnt(2)
	s_barrier
	global_load_lds_dwordx4 v[6:7], off
	v_lshl_add_u64 v[4:5], v[4:5], 0, s[12:13]
	s_add_i32 m0, s22, 0x1a000
	s_add_i32 s43, s22, 0x8000
	s_add_i32 s48, s22, 0xa000
	global_load_lds_dwordx4 v[4:5], off
	v_lshl_add_u64 v[0:1], v[0:1], 0, s[12:13]
	s_mov_b32 m0, s43
	s_add_u32 s2, s72, 0x80080
	global_load_lds_dwordx4 v[0:1], off
	v_lshl_add_u64 v[0:1], v[2:3], 0, s[12:13]
	s_mov_b32 m0, s48
	s_addc_u32 s3, s73, 0
	global_load_lds_dwordx4 v[0:1], off
	s_add_i32 m0, s22, 0x1c000
	v_lshl_add_u64 v[0:1], s[2:3], 0, v[128:129]
	global_load_lds_dwordx4 v128, s[2:3]
	v_lshl_add_u64 v[0:1], s[2:3], 0, v[130:131]
	s_add_i32 m0, s22, 0x1e000
	s_cmpk_lt_u32 s45, 0x100
	global_load_lds_dwordx4 v130, s[2:3]
	v_and_b32_e32 v0, 15, v8
	v_and_b32_e32 v1, 48, v8
	v_lshl_or_b32 v0, v0, 6, v1
	v_lshlrev_b32_e32 v1, 2, v8
	v_and_b32_e32 v1, 32, v1
	v_bitop3_b32 v2, v0, s47, v1 bitop3:0xde
	v_bitop3_b32 v144, v0, s49, v1 bitop3:0xde
	v_lshlrev_b32_e32 v0, 15, v9
	v_and_b32_e32 v0, 0xffff0000, v0
	v_lshl_add_u32 v0, v10, 12, v0
	v_and_b32_e32 v1, 1, v9
	v_lshl_or_b32 v0, v1, 6, v0
	v_lshl_add_u32 v136, v11, 1, v0
	v_lshlrev_b32_e32 v0, 15, v13
	v_and_b32_e32 v0, 0xffff0000, v0
	s_waitcnt vmcnt(6)
	s_mov_b32 s98, 0
	v_lshl_add_u32 v0, v12, 12, v0
	v_and_b32_e32 v1, 1, v13
	s_sext_i32_i16 s53, s44
	s_cselect_b64 s[44:45], -1, 0
	s_bitcmp1_b32 s33, 8
	s_cbranch_scc1 .Lsp_13
	s_setprio 1
.Lsp_13:
	s_and_b32 s2, s15, 0x400
	v_mov_b32_e32 v137, 0
	v_lshl_or_b32 v0, v1, 6, v0
	s_add_i32 s51, 0, 0x10000
	s_add_i32 s52, 0, 0x14000
	s_bfe_u32 s49, s46, 0x10001
	s_or_b32 s50, s2, s47
	v_lshl_add_u32 v138, v14, 1, v0
	v_mov_b32_e32 v139, v137
	v_mov_b64_e32 v[140:141], 0x200
	v_mov_b64_e32 v[142:143], 0x1ff
	v_add_u32_e32 v145, s51, v144
	v_add_u32_e32 v146, s52, v144
	v_add_u32_e32 v147, 0, v2
	s_mov_b64 s[46:47], 0x100
	s_mov_b64 s[60:61], 0x180
	s_barrier
	s_branch .LBB0_2834

; template <class Epi, class Sched, bool ALIGN_EPI = false, bool SP2 = false, bool A_TILED = false>
; __device__ __forceinline__ void gemm_phase(PG8_LAS unsigned char* lds, const Gemm g, const Sched& S, const Epi& E, const int wave_s) {
;     ...
;         constexpr bool PEEL = SP2 && !Epi::AFTER_DRAIN;
;         if constexpr (PEEL) {
;             const char* a1 = cA + kstepA; const char* a2 = cA + 2 * kstepA; const char* b2 = cB + 2 * kstep; const char* a3 = a2 + kstepA; const char* b3 = b2 + kstep;
;             PG8_ITER(PG8_MMAZ)
.Lpw_15:
	s_barrier
	v_mfma_f32_16x16x32_bf16 v[88:91], v[0:3], v[56:59], 0
	v_mfma_f32_16x16x32_bf16 v[64:67], v[0:3], v[32:35], 0
	v_mfma_f32_16x16x32_bf16 v[68:71], v[8:11], v[32:35], 0
	v_mfma_f32_16x16x32_bf16 v[72:75], v[0:3], v[40:43], 0
	v_mfma_f32_16x16x32_bf16 v[76:79], v[8:11], v[40:43], 0
	v_mfma_f32_16x16x32_bf16 v[80:83], v[0:3], v[48:51], 0
	v_mfma_f32_16x16x32_bf16 v[84:87], v[8:11], v[48:51], 0
	v_mfma_f32_16x16x32_bf16 v[96:99], v[4:7], v[60:63], v[88:91]
	v_mfma_f32_16x16x32_bf16 v[88:91], v[8:11], v[56:59], 0
	v_mfma_f32_16x16x32_bf16 v[64:67], v[4:7], v[36:39], v[64:67]
	v_mfma_f32_16x16x32_bf16 v[68:71], v[12:15], v[36:39], v[68:71]
	v_mfma_f32_16x16x32_bf16 v[72:75], v[4:7], v[44:47], v[72:75]
	v_mfma_f32_16x16x32_bf16 v[76:79], v[12:15], v[44:47], v[76:79]
	v_mfma_f32_16x16x32_bf16 v[80:83], v[4:7], v[52:55], v[80:83]
	v_mfma_f32_16x16x32_bf16 v[84:87], v[12:15], v[52:55], v[84:87]
	v_mfma_f32_16x16x32_bf16 v[100:103], v[12:15], v[60:63], v[88:91]
	v_mfma_f32_16x16x32_bf16 v[88:91], v[16:19], v[32:35], 0
	v_mfma_f32_16x16x32_bf16 v[32:35], v[24:27], v[32:35], 0
	v_mfma_f32_16x16x32_bf16 v[112:115], v[20:23], v[36:39], v[88:91]
	v_mfma_f32_16x16x32_bf16 v[32:35], v[28:31], v[36:39], v[32:35]
	v_mfma_f32_16x16x32_bf16 v[36:39], v[16:19], v[40:43], 0
	v_mfma_f32_16x16x32_bf16 v[40:43], v[24:27], v[40:43], 0
	v_mfma_f32_16x16x32_bf16 v[36:39], v[20:23], v[44:47], v[36:39]
	v_mfma_f32_16x16x32_bf16 v[40:43], v[28:31], v[44:47], v[40:43]
	v_mfma_f32_16x16x32_bf16 v[44:47], v[16:19], v[48:51], 0
	v_mfma_f32_16x16x32_bf16 v[48:51], v[24:27], v[48:51], 0
	v_mfma_f32_16x16x32_bf16 v[44:47], v[20:23], v[52:55], v[44:47]
	v_mfma_f32_16x16x32_bf16 v[48:51], v[28:31], v[52:55], v[48:51]
	v_mfma_f32_16x16x32_bf16 v[52:55], v[16:19], v[56:59], 0
	v_mfma_f32_16x16x32_bf16 v[56:59], v[24:27], v[56:59], 0
	v_mfma_f32_16x16x32_bf16 v[52:55], v[20:23], v[60:63], v[52:55]
	v_mfma_f32_16x16x32_bf16 v[56:59], v[28:31], v[60:63], v[56:59]
	s_barrier
	s_add_i32 s63, s51, s15
	v_lshl_add_u64 v[242:243], s[72:73], 0, v[128:129]
	s_add_i32 s65, s63, 0x2000
	v_lshl_add_u64 v[148:149], v[242:243], 0, s[46:47]
	s_mov_b32 m0, s63
	v_lshl_add_u64 v[244:245], s[72:73], 0, v[130:131]
	s_add_u32 s76, s72, 0x80100
	ds_read_b128 v[60:63], v147 offset:16384
	ds_read_b128 v[88:91], v147 offset:17408
	ds_read_b128 v[92:95], v147 offset:18432
	ds_read_b128 v[104:107], v147 offset:19456
	ds_read_b128 v[108:111], v147 offset:20480
	ds_read_b128 v[116:119], v147 offset:21504
	ds_read_b128 v[120:123], v147 offset:22528
	ds_read_b128 v[124:127], v147 offset:23552
	global_load_lds_dwordx4 v[148:149], off
	v_lshl_add_u64 v[148:149], v[244:245], 0, s[46:47]
	s_mov_b32 m0, s65
	s_addc_u32 s77, s73, 0
	s_add_i32 s71, s52, s15
	global_load_lds_dwordx4 v[148:149], off
	v_lshl_add_u64 v[148:149], s[76:77], 0, v[128:129]
	s_mov_b32 m0, s71
	s_add_i32 s78, s71, 0x2000
	global_load_lds_dwordx4 v128, s[76:77]
	v_lshl_add_u64 v[148:149], s[76:77], 0, v[130:131]
	s_mov_b32 m0, s78
	v_lshl_add_u64 v[246:247], s[74:75], 0, v[134:135]
	global_load_lds_dwordx4 v130, s[76:77]
	v_lshl_add_u64 v[148:149], v[246:247], 0, s[46:47]
	s_mov_b32 m0, s22
	v_lshl_add_u64 v[248:249], s[74:75], 0, v[132:133]
	global_load_lds_dwordx4 v[148:149], off
	v_lshl_add_u64 v[148:149], v[248:249], 0, s[46:47]
	s_mov_b32 m0, s23
	s_nop 0
	global_load_lds_dwordx4 v[148:149], off
	s_waitcnt vmcnt(24) lgkmcnt(0)
	s_cmp_lg_u32 s98, 0
	s_cbranch_scc1 .Lpw_16
	s_waitcnt vmcnt(8)
.Lpw_16:
	s_barrier
	v_mfma_f32_16x16x32_bf16 v[148:151], v[0:3], v[60:63], 0
	v_mfma_f32_16x16x32_bf16 v[158:161], v[0:3], v[92:95], 0
	v_mfma_f32_16x16x32_bf16 v[166:169], v[0:3], v[108:111], 0
	v_mfma_f32_16x16x32_bf16 v[0:3], v[0:3], v[120:123], 0
	v_mfma_f32_16x16x32_bf16 v[150:153], v[4:7], v[88:91], v[148:151]
	v_mfma_f32_16x16x32_bf16 v[158:161], v[4:7], v[104:107], v[158:161]
	v_mfma_f32_16x16x32_bf16 v[166:169], v[4:7], v[116:119], v[166:169]
	v_mfma_f32_16x16x32_bf16 v[0:3], v[4:7], v[124:127], v[0:3]
	v_mfma_f32_16x16x32_bf16 v[4:7], v[8:11], v[120:123], 0
	v_mfma_f32_16x16x32_bf16 v[154:157], v[8:11], v[60:63], 0
	v_mfma_f32_16x16x32_bf16 v[162:165], v[8:11], v[92:95], 0
	v_mfma_f32_16x16x32_bf16 v[170:173], v[8:11], v[108:111], 0
	v_mfma_f32_16x16x32_bf16 v[4:7], v[12:15], v[124:127], v[4:7]
	v_mfma_f32_16x16x32_bf16 v[154:157], v[12:15], v[88:91], v[154:157]
	v_mfma_f32_16x16x32_bf16 v[162:165], v[12:15], v[104:107], v[162:165]
	v_mfma_f32_16x16x32_bf16 v[170:173], v[12:15], v[116:119], v[170:173]
	v_mfma_f32_16x16x32_bf16 v[8:11], v[16:19], v[60:63], 0
	v_mfma_f32_16x16x32_bf16 v[174:177], v[20:23], v[88:91], v[8:11]
	v_mfma_f32_16x16x32_bf16 v[8:11], v[24:27], v[60:63], 0
	v_mfma_f32_16x16x32_bf16 v[60:63], v[28:31], v[88:91], v[8:11]
	v_mfma_f32_16x16x32_bf16 v[8:11], v[16:19], v[92:95], 0
	v_mfma_f32_16x16x32_bf16 v[178:181], v[20:23], v[104:107], v[8:11]
	v_mfma_f32_16x16x32_bf16 v[8:11], v[24:27], v[92:95], 0
	v_mfma_f32_16x16x32_bf16 v[182:185], v[28:31], v[104:107], v[8:11]
	v_mfma_f32_16x16x32_bf16 v[8:11], v[16:19], v[108:111], 0
	v_mfma_f32_16x16x32_bf16 v[186:189], v[20:23], v[116:119], v[8:11]
	v_mfma_f32_16x16x32_bf16 v[8:11], v[24:27], v[108:111], 0
	v_mfma_f32_16x16x32_bf16 v[190:193], v[28:31], v[116:119], v[8:11]
	v_mfma_f32_16x16x32_bf16 v[8:11], v[16:19], v[120:123], 0
	v_mfma_f32_16x16x32_bf16 v[194:197], v[20:23], v[124:127], v[8:11]
	v_mfma_f32_16x16x32_bf16 v[8:11], v[24:27], v[120:123], 0
	v_mfma_f32_16x16x32_bf16 v[198:201], v[28:31], v[124:127], v[8:11]
	s_barrier
; template <class Epi, class Sched, bool ALIGN_EPI = false, bool SP2 = false, bool A_TILED = false>
; __device__ __forceinline__ void gemm_phase(PG8_LAS unsigned char* lds, const Gemm g, const Sched& S, const Epi& E, const int wave_s) {
;     ...
;         for (int t = PEEL ? 2 : 0; t < nt; t += 2) {
;             const bool last = (t == nt - 2);
;             const char* a1 = cA + (size_t)(t + 1) * kstepA;
;             const char* a2 = last ? nA : cA + (size_t)(t + 2) * kstepA; const char* b2 = last ? nB : cB + (size_t)(t + 2) * kstep;
;             const char* a3 = a2 + kstepA; const char* b3 = b2 + kstep;
	s_add_i32 s79, 0, 0x18000
	s_add_i32 s81, 0, 0x1c000
	v_add_u32_e32 v148, s79, v144
	v_add_u32_e32 v149, s81, v144
	s_nop 0
	ds_read_b128 v[8:11], v148
	ds_read_b128 v[12:15], v148 offset:1024
	ds_read_b128 v[16:19], v148 offset:2048
	ds_read_b128 v[20:23], v148 offset:3072
	ds_read_b128 v[202:205], v149
	ds_read_b128 v[206:209], v149 offset:1024
	ds_read_b128 v[210:213], v149 offset:2048
	ds_read_b128 v[214:217], v149 offset:3072
	s_add_u32 s76, s74, 0x80100
	s_addc_u32 s77, s75, 0
	s_mov_b32 m0, s36
	v_lshl_add_u64 v[88:89], s[76:77], 0, v[134:135]
	ds_read_b128 v[24:27], v147 offset:32768
	ds_read_b128 v[28:31], v147 offset:33792
	ds_read_b128 v[218:221], v147 offset:34816
	ds_read_b128 v[222:225], v147 offset:35840
	ds_read_b128 v[226:229], v147 offset:36864
	ds_read_b128 v[230:233], v147 offset:37888
	ds_read_b128 v[234:237], v147 offset:38912
	ds_read_b128 v[238:241], v147 offset:39936
	global_load_lds_dwordx4 v134, s[76:77]
	v_lshl_add_u64 v[88:89], s[76:77], 0, v[132:133]
	s_mov_b32 m0, s37
	s_nop 0
	global_load_lds_dwordx4 v132, s[76:77]
	s_waitcnt vmcnt(8) lgkmcnt(0)
	s_barrier
	v_mfma_f32_16x16x32_bf16 v[64:67], v[8:11], v[24:27], v[64:67]
	v_mfma_f32_16x16x32_bf16 v[120:123], v[12:15], v[28:31], v[64:67]
	v_mfma_f32_16x16x32_bf16 v[64:67], v[16:19], v[24:27], v[68:71]
	v_mfma_f32_16x16x32_bf16 v[124:127], v[20:23], v[28:31], v[64:67]
	v_mfma_f32_16x16x32_bf16 v[64:67], v[8:11], v[218:221], v[72:75]
	v_mfma_f32_16x16x32_bf16 v[104:107], v[12:15], v[222:225], v[64:67]
	v_mfma_f32_16x16x32_bf16 v[64:67], v[16:19], v[218:221], v[76:79]
	v_mfma_f32_16x16x32_bf16 v[108:111], v[20:23], v[222:225], v[64:67]
	v_mfma_f32_16x16x32_bf16 v[64:67], v[8:11], v[226:229], v[80:83]
	v_mfma_f32_16x16x32_bf16 v[88:91], v[12:15], v[230:233], v[64:67]
	v_mfma_f32_16x16x32_bf16 v[64:67], v[16:19], v[226:229], v[84:87]
	v_mfma_f32_16x16x32_bf16 v[92:95], v[20:23], v[230:233], v[64:67]
	v_mfma_f32_16x16x32_bf16 v[64:67], v[8:11], v[234:237], v[96:99]
	v_mfma_f32_16x16x32_bf16 v[68:71], v[16:19], v[234:237], v[100:103]
	v_mfma_f32_16x16x32_bf16 v[64:67], v[12:15], v[238:241], v[64:67]
	v_mfma_f32_16x16x32_bf16 v[68:71], v[20:23], v[238:241], v[68:71]
	v_mfma_f32_16x16x32_bf16 v[72:75], v[202:205], v[24:27], v[112:115]
	v_mfma_f32_16x16x32_bf16 v[24:27], v[210:213], v[24:27], v[32:35]
	v_mfma_f32_16x16x32_bf16 v[116:119], v[214:217], v[28:31], v[24:27]
	v_mfma_f32_16x16x32_bf16 v[24:27], v[202:205], v[218:221], v[36:39]
	v_mfma_f32_16x16x32_bf16 v[96:99], v[206:209], v[222:225], v[24:27]
	v_mfma_f32_16x16x32_bf16 v[24:27], v[210:213], v[218:221], v[40:43]
	v_mfma_f32_16x16x32_bf16 v[100:103], v[214:217], v[222:225], v[24:27]
	v_mfma_f32_16x16x32_bf16 v[24:27], v[202:205], v[226:229], v[44:47]
	v_mfma_f32_16x16x32_bf16 v[80:83], v[206:209], v[230:233], v[24:27]
	v_mfma_f32_16x16x32_bf16 v[24:27], v[210:213], v[226:229], v[48:51]
	v_mfma_f32_16x16x32_bf16 v[84:87], v[214:217], v[230:233], v[24:27]
	v_mfma_f32_16x16x32_bf16 v[24:27], v[202:205], v[234:237], v[52:55]
	v_mfma_f32_16x16x32_bf16 v[48:51], v[206:209], v[238:241], v[24:27]
	v_mfma_f32_16x16x32_bf16 v[24:27], v[210:213], v[234:237], v[56:59]
	v_mfma_f32_16x16x32_bf16 v[112:115], v[206:209], v[28:31], v[72:75]
	v_mfma_f32_16x16x32_bf16 v[52:55], v[214:217], v[238:241], v[24:27]
	s_barrier
	s_add_i32 s79, s79, s15
	s_add_i32 s80, s79, 0x2000
	s_nop 1
	v_lshl_add_u64 v[24:25], v[242:243], 0, s[60:61]
	s_mov_b32 m0, s79
	s_add_u32 s76, s72, 0x80180
	ds_read_b128 v[32:35], v147 offset:49152
	ds_read_b128 v[36:39], v147 offset:50176
	ds_read_b128 v[218:221], v147 offset:51200
	ds_read_b128 v[222:225], v147 offset:52224
	ds_read_b128 v[226:229], v147 offset:53248
	ds_read_b128 v[230:233], v147 offset:54272
	ds_read_b128 v[234:237], v147 offset:55296
	ds_read_b128 v[238:241], v147 offset:56320
	global_load_lds_dwordx4 v[24:25], off
	v_lshl_add_u64 v[24:25], v[244:245], 0, s[60:61]
	s_mov_b32 m0, s80
	s_addc_u32 s77, s73, 0
	s_add_i32 s81, s81, s15
	global_load_lds_dwordx4 v[24:25], off
	v_lshl_add_u64 v[24:25], s[76:77], 0, v[128:129]
	s_mov_b32 m0, s81
	s_add_i32 s82, s81, 0x2000
	global_load_lds_dwordx4 v128, s[76:77]
	v_lshl_add_u64 v[24:25], s[76:77], 0, v[130:131]
	s_mov_b32 m0, s82
	s_nop 0
	global_load_lds_dwordx4 v130, s[76:77]
	v_lshl_add_u64 v[24:25], v[246:247], 0, s[60:61]
	s_mov_b32 m0, s43
	s_nop 0
	global_load_lds_dwordx4 v[24:25], off
	v_lshl_add_u64 v[24:25], v[248:249], 0, s[60:61]
	s_mov_b32 m0, s48
	s_nop 0
	global_load_lds_dwordx4 v[24:25], off
	s_waitcnt vmcnt(8) lgkmcnt(0)
	s_barrier
	v_mfma_f32_16x16x32_bf16 v[24:27], v[8:11], v[32:35], v[150:153]
	v_mfma_f32_16x16x32_bf16 v[72:75], v[12:15], v[36:39], v[24:27]
	v_mfma_f32_16x16x32_bf16 v[24:27], v[16:19], v[32:35], v[154:157]
	v_mfma_f32_16x16x32_bf16 v[76:79], v[20:23], v[36:39], v[24:27]
	v_mfma_f32_16x16x32_bf16 v[24:27], v[8:11], v[218:221], v[158:161]
	v_mfma_f32_16x16x32_bf16 v[40:43], v[12:15], v[222:225], v[24:27]
	v_mfma_f32_16x16x32_bf16 v[24:27], v[16:19], v[218:221], v[162:165]
	v_mfma_f32_16x16x32_bf16 v[0:3], v[8:11], v[234:237], v[0:3]
	v_mfma_f32_16x16x32_bf16 v[44:47], v[20:23], v[222:225], v[24:27]
	v_mfma_f32_16x16x32_bf16 v[24:27], v[8:11], v[226:229], v[166:169]
	v_mfma_f32_16x16x32_bf16 v[28:31], v[16:19], v[226:229], v[170:173]
	v_mfma_f32_16x16x32_bf16 v[8:11], v[12:15], v[238:241], v[0:3]
	v_mfma_f32_16x16x32_bf16 v[0:3], v[16:19], v[234:237], v[4:7]
	v_mfma_f32_16x16x32_bf16 v[24:27], v[12:15], v[230:233], v[24:27]
	v_mfma_f32_16x16x32_bf16 v[28:31], v[20:23], v[230:233], v[28:31]
	v_mfma_f32_16x16x32_bf16 v[12:15], v[20:23], v[238:241], v[0:3]
	v_mfma_f32_16x16x32_bf16 v[0:3], v[202:205], v[32:35], v[174:177]
	v_mfma_f32_16x16x32_bf16 v[56:59], v[206:209], v[36:39], v[0:3]
	v_mfma_f32_16x16x32_bf16 v[0:3], v[210:213], v[32:35], v[60:63]
	v_mfma_f32_16x16x32_bf16 v[60:63], v[214:217], v[36:39], v[0:3]
	v_mfma_f32_16x16x32_bf16 v[0:3], v[202:205], v[218:221], v[178:181]
	v_mfma_f32_16x16x32_bf16 v[32:35], v[206:209], v[222:225], v[0:3]
	v_mfma_f32_16x16x32_bf16 v[0:3], v[210:213], v[218:221], v[182:185]
	v_mfma_f32_16x16x32_bf16 v[36:39], v[214:217], v[222:225], v[0:3]
	v_mfma_f32_16x16x32_bf16 v[0:3], v[202:205], v[226:229], v[186:189]
	v_mfma_f32_16x16x32_bf16 v[16:19], v[206:209], v[230:233], v[0:3]
	v_mfma_f32_16x16x32_bf16 v[0:3], v[210:213], v[226:229], v[190:193]
	v_mfma_f32_16x16x32_bf16 v[20:23], v[214:217], v[230:233], v[0:3]
	v_mfma_f32_16x16x32_bf16 v[0:3], v[202:205], v[234:237], v[194:197]
	v_mfma_f32_16x16x32_bf16 v[4:7], v[210:213], v[234:237], v[198:201]
	v_mfma_f32_16x16x32_bf16 v[0:3], v[206:209], v[238:241], v[0:3]
	v_mfma_f32_16x16x32_bf16 v[4:7], v[214:217], v[238:241], v[4:7]
	s_barrier
	s_add_u32 s83, s72, 0x200
	s_addc_u32 s85, s73, 0
	s_add_u32 s72, s74, 0x80180
	s_addc_u32 s73, s75, 0
	s_mov_b32 s88, 0
; #define PG8_MMA(ai, bj, At, Bt) do { __builtin_amdgcn_s_setprio(1); _Pragma("unroll") for (int m = 0; m < 4; ++m) _Pragma("unroll") for (int n = 0; n < 2; ++n) _Pragma("unroll") for (int k = 0; k < 2; ++k) \
;         acc[ai][bj][m][n] = __builtin_amdgcn_mfma_f32_16x16x32_bf16(Bt[n][k], At[m][k], acc[ai][bj][m][n], 0, 0, 0); __builtin_amdgcn_s_setprio(0); } while (0)
; template <class Epi, class Sched, bool ALIGN_EPI = false, bool SP2 = false, bool A_TILED = false>
; __device__ __forceinline__ void gemm_phase(PG8_LAS unsigned char* lds, const Gemm g, const Sched& S, const Epi& E, const int wave_s) {
;     ...
;         for (int t = PEEL ? 2 : 0; t < nt; t += 2) {
;             const bool last = (t == nt - 2);
;             const char* a1 = cA + (size_t)(t + 1) * kstepA;
;             const char* a2 = last ? nA : cA + (size_t)(t + 2) * kstepA; const char* b2 = last ? nB : cB + (size_t)(t + 2) * kstep;
;             const char* a3 = a2 + kstepA; const char* b3 = b2 + kstep;
;             if (last && has_next) S.a_ready(nxt);
;             if constexpr (SP2) {
;             PG8_ITER(PG8_MMA)
.LBB0_2841:
	ds_read_b128 v[150:153], v145
	ds_read_b128 v[154:157], v145 offset:1024
	ds_read_b128 v[158:161], v145 offset:2048
	ds_read_b128 v[162:165], v145 offset:3072
	ds_read_b128 v[166:169], v146
	ds_read_b128 v[170:173], v146 offset:1024
	ds_read_b128 v[174:177], v146 offset:2048
	ds_read_b128 v[178:181], v146 offset:3072
	s_add_u32 s74, s72, 0xfff80080
	s_addc_u32 s75, s73, -1
	s_cmp_eq_u32 s88, 28
	s_cselect_b32 s77, s54, s75
	s_cselect_b32 s76, s55, s74
	s_cselect_b32 s75, s56, s85
	s_cselect_b32 s74, s57, s83
	s_mov_b32 m0, s58
	v_lshl_add_u64 v[214:215], s[72:73], 0, v[138:139]
	ds_read_b128 v[182:185], v147
	ds_read_b128 v[186:189], v147 offset:1024
	ds_read_b128 v[190:193], v147 offset:2048
	ds_read_b128 v[194:197], v147 offset:3072
	ds_read_b128 v[198:201], v147 offset:4096
	ds_read_b128 v[202:205], v147 offset:5120
	ds_read_b128 v[206:209], v147 offset:6144
	ds_read_b128 v[210:213], v147 offset:7168
	global_load_lds_dwordx4 v138, s[72:73]
	v_lshl_add_u64 v[214:215], s[72:73], 0, v[136:137]
	s_mov_b32 m0, s59
	s_nop 0
	global_load_lds_dwordx4 v136, s[72:73]
	s_waitcnt vmcnt(8) lgkmcnt(0)
	s_barrier
	v_mfma_f32_16x16x32_bf16 v[120:123], v[150:153], v[182:185], v[120:123]
	v_mfma_f32_16x16x32_bf16 v[124:127], v[158:161], v[182:185], v[124:127]
	v_mfma_f32_16x16x32_bf16 v[104:107], v[150:153], v[190:193], v[104:107]
	v_mfma_f32_16x16x32_bf16 v[108:111], v[158:161], v[190:193], v[108:111]
	v_mfma_f32_16x16x32_bf16 v[88:91], v[150:153], v[198:201], v[88:91]
	v_mfma_f32_16x16x32_bf16 v[92:95], v[158:161], v[198:201], v[92:95]
	v_mfma_f32_16x16x32_bf16 v[64:67], v[150:153], v[206:209], v[64:67]
	v_mfma_f32_16x16x32_bf16 v[68:71], v[158:161], v[206:209], v[68:71]
	v_mfma_f32_16x16x32_bf16 v[120:123], v[154:157], v[186:189], v[120:123]
	v_mfma_f32_16x16x32_bf16 v[124:127], v[162:165], v[186:189], v[124:127]
	v_mfma_f32_16x16x32_bf16 v[104:107], v[154:157], v[194:197], v[104:107]
	v_mfma_f32_16x16x32_bf16 v[108:111], v[162:165], v[194:197], v[108:111]
	v_mfma_f32_16x16x32_bf16 v[88:91], v[154:157], v[202:205], v[88:91]
	v_mfma_f32_16x16x32_bf16 v[92:95], v[162:165], v[202:205], v[92:95]
	v_mfma_f32_16x16x32_bf16 v[64:67], v[154:157], v[210:213], v[64:67]
	v_mfma_f32_16x16x32_bf16 v[68:71], v[162:165], v[210:213], v[68:71]
	v_mfma_f32_16x16x32_bf16 v[112:115], v[166:169], v[182:185], v[112:115]
	v_mfma_f32_16x16x32_bf16 v[116:119], v[174:177], v[182:185], v[116:119]
	v_mfma_f32_16x16x32_bf16 v[96:99], v[166:169], v[190:193], v[96:99]
	v_mfma_f32_16x16x32_bf16 v[100:103], v[174:177], v[190:193], v[100:103]
	v_mfma_f32_16x16x32_bf16 v[80:83], v[166:169], v[198:201], v[80:83]
	v_mfma_f32_16x16x32_bf16 v[84:87], v[174:177], v[198:201], v[84:87]
	v_mfma_f32_16x16x32_bf16 v[48:51], v[166:169], v[206:209], v[48:51]
	v_mfma_f32_16x16x32_bf16 v[52:55], v[174:177], v[206:209], v[52:55]
	v_mfma_f32_16x16x32_bf16 v[112:115], v[170:173], v[186:189], v[112:115]
	v_mfma_f32_16x16x32_bf16 v[116:119], v[178:181], v[186:189], v[116:119]
	v_mfma_f32_16x16x32_bf16 v[96:99], v[170:173], v[194:197], v[96:99]
	v_mfma_f32_16x16x32_bf16 v[100:103], v[178:181], v[194:197], v[100:103]
	v_mfma_f32_16x16x32_bf16 v[80:83], v[170:173], v[202:205], v[80:83]
	v_mfma_f32_16x16x32_bf16 v[84:87], v[178:181], v[202:205], v[84:87]
	v_mfma_f32_16x16x32_bf16 v[48:51], v[170:173], v[210:213], v[48:51]
	v_mfma_f32_16x16x32_bf16 v[52:55], v[178:181], v[210:213], v[52:55]
	s_barrier
	s_mov_b32 m0, s63
	v_lshl_add_u64 v[214:215], s[74:75], 0, v[128:129]
	s_add_u32 s90, s74, 0x80000
	ds_read_b128 v[182:185], v147 offset:16384
	ds_read_b128 v[186:189], v147 offset:17408
	ds_read_b128 v[190:193], v147 offset:18432
	ds_read_b128 v[194:197], v147 offset:19456
	ds_read_b128 v[198:201], v147 offset:20480
	ds_read_b128 v[202:205], v147 offset:21504
	ds_read_b128 v[206:209], v147 offset:22528
	ds_read_b128 v[210:213], v147 offset:23552
	global_load_lds_dwordx4 v128, s[74:75]
	v_lshl_add_u64 v[216:217], s[74:75], 0, v[130:131]
	s_mov_b32 m0, s65
	s_addc_u32 s91, s75, 0
	global_load_lds_dwordx4 v130, s[74:75]
	v_lshl_add_u64 v[218:219], s[90:91], 0, v[128:129]
	s_mov_b32 m0, s71
	v_lshl_add_u64 v[220:221], s[76:77], 0, v[132:133]
	global_load_lds_dwordx4 v128, s[90:91]
	v_lshl_add_u64 v[218:219], s[90:91], 0, v[130:131]
	s_mov_b32 m0, s78
	s_nop 0
	global_load_lds_dwordx4 v130, s[90:91]
	v_lshl_add_u64 v[218:219], s[76:77], 0, v[134:135]
	s_mov_b32 m0, s22
	s_nop 0
	global_load_lds_dwordx4 v134, s[76:77]
	s_mov_b32 m0, s23
	s_nop 0
	global_load_lds_dwordx4 v132, s[76:77]
	s_waitcnt vmcnt(8) lgkmcnt(0)
	s_barrier
	v_mfma_f32_16x16x32_bf16 v[72:75], v[150:153], v[182:185], v[72:75]
	v_mfma_f32_16x16x32_bf16 v[76:79], v[158:161], v[182:185], v[76:79]
	v_mfma_f32_16x16x32_bf16 v[40:43], v[150:153], v[190:193], v[40:43]
	v_mfma_f32_16x16x32_bf16 v[44:47], v[158:161], v[190:193], v[44:47]
	v_mfma_f32_16x16x32_bf16 v[24:27], v[150:153], v[198:201], v[24:27]
	v_mfma_f32_16x16x32_bf16 v[28:31], v[158:161], v[198:201], v[28:31]
	v_mfma_f32_16x16x32_bf16 v[8:11], v[150:153], v[206:209], v[8:11]
	v_mfma_f32_16x16x32_bf16 v[12:15], v[158:161], v[206:209], v[12:15]
	v_mfma_f32_16x16x32_bf16 v[72:75], v[154:157], v[186:189], v[72:75]
	v_mfma_f32_16x16x32_bf16 v[76:79], v[162:165], v[186:189], v[76:79]
	v_mfma_f32_16x16x32_bf16 v[40:43], v[154:157], v[194:197], v[40:43]
	v_mfma_f32_16x16x32_bf16 v[44:47], v[162:165], v[194:197], v[44:47]
	v_mfma_f32_16x16x32_bf16 v[24:27], v[154:157], v[202:205], v[24:27]
	v_mfma_f32_16x16x32_bf16 v[28:31], v[162:165], v[202:205], v[28:31]
	v_mfma_f32_16x16x32_bf16 v[8:11], v[154:157], v[210:213], v[8:11]
	v_mfma_f32_16x16x32_bf16 v[12:15], v[162:165], v[210:213], v[12:15]
	v_mfma_f32_16x16x32_bf16 v[56:59], v[166:169], v[182:185], v[56:59]
	v_mfma_f32_16x16x32_bf16 v[60:63], v[174:177], v[182:185], v[60:63]
	v_mfma_f32_16x16x32_bf16 v[32:35], v[166:169], v[190:193], v[32:35]
	v_mfma_f32_16x16x32_bf16 v[36:39], v[174:177], v[190:193], v[36:39]
	v_mfma_f32_16x16x32_bf16 v[16:19], v[166:169], v[198:201], v[16:19]
	v_mfma_f32_16x16x32_bf16 v[20:23], v[174:177], v[198:201], v[20:23]
	v_mfma_f32_16x16x32_bf16 v[0:3], v[166:169], v[206:209], v[0:3]
	v_mfma_f32_16x16x32_bf16 v[4:7], v[174:177], v[206:209], v[4:7]
	v_mfma_f32_16x16x32_bf16 v[56:59], v[170:173], v[186:189], v[56:59]
	v_mfma_f32_16x16x32_bf16 v[60:63], v[178:181], v[186:189], v[60:63]
	v_mfma_f32_16x16x32_bf16 v[32:35], v[170:173], v[194:197], v[32:35]
	v_mfma_f32_16x16x32_bf16 v[36:39], v[178:181], v[194:197], v[36:39]
	v_mfma_f32_16x16x32_bf16 v[16:19], v[170:173], v[202:205], v[16:19]
	v_mfma_f32_16x16x32_bf16 v[20:23], v[178:181], v[202:205], v[20:23]
	v_mfma_f32_16x16x32_bf16 v[0:3], v[170:173], v[210:213], v[0:3]
	v_mfma_f32_16x16x32_bf16 v[4:7], v[178:181], v[210:213], v[4:7]
	s_barrier
	ds_read_b128 v[150:153], v148
	ds_read_b128 v[154:157], v148 offset:1024
	ds_read_b128 v[158:161], v148 offset:2048
	ds_read_b128 v[162:165], v148 offset:3072
	ds_read_b128 v[166:169], v149
	ds_read_b128 v[170:173], v149 offset:1024
	ds_read_b128 v[174:177], v149 offset:2048
	ds_read_b128 v[178:181], v149 offset:3072
	s_add_u32 s76, s76, 0x80000
	s_addc_u32 s77, s77, 0
	s_mov_b32 m0, s36
	v_lshl_add_u64 v[222:223], s[76:77], 0, v[134:135]
	ds_read_b128 v[182:185], v147 offset:32768
	ds_read_b128 v[186:189], v147 offset:33792
	ds_read_b128 v[190:193], v147 offset:34816
	ds_read_b128 v[194:197], v147 offset:35840
	ds_read_b128 v[198:201], v147 offset:36864
	ds_read_b128 v[202:205], v147 offset:37888
	ds_read_b128 v[206:209], v147 offset:38912
	ds_read_b128 v[210:213], v147 offset:39936
	global_load_lds_dwordx4 v134, s[76:77]
	v_lshl_add_u64 v[222:223], s[76:77], 0, v[132:133]
	s_mov_b32 m0, s37
	s_nop 0
	global_load_lds_dwordx4 v132, s[76:77]
	s_waitcnt vmcnt(8) lgkmcnt(0)
	s_barrier
	v_mfma_f32_16x16x32_bf16 v[120:123], v[150:153], v[182:185], v[120:123]
	v_mfma_f32_16x16x32_bf16 v[124:127], v[158:161], v[182:185], v[124:127]
	v_mfma_f32_16x16x32_bf16 v[104:107], v[150:153], v[190:193], v[104:107]
	v_mfma_f32_16x16x32_bf16 v[108:111], v[158:161], v[190:193], v[108:111]
	v_mfma_f32_16x16x32_bf16 v[88:91], v[150:153], v[198:201], v[88:91]
	v_mfma_f32_16x16x32_bf16 v[92:95], v[158:161], v[198:201], v[92:95]
	v_mfma_f32_16x16x32_bf16 v[64:67], v[150:153], v[206:209], v[64:67]
	v_mfma_f32_16x16x32_bf16 v[68:71], v[158:161], v[206:209], v[68:71]
	v_mfma_f32_16x16x32_bf16 v[120:123], v[154:157], v[186:189], v[120:123]
	v_mfma_f32_16x16x32_bf16 v[124:127], v[162:165], v[186:189], v[124:127]
	v_mfma_f32_16x16x32_bf16 v[104:107], v[154:157], v[194:197], v[104:107]
	v_mfma_f32_16x16x32_bf16 v[108:111], v[162:165], v[194:197], v[108:111]
	v_mfma_f32_16x16x32_bf16 v[88:91], v[154:157], v[202:205], v[88:91]
	v_mfma_f32_16x16x32_bf16 v[92:95], v[162:165], v[202:205], v[92:95]
	v_mfma_f32_16x16x32_bf16 v[64:67], v[154:157], v[210:213], v[64:67]
	v_mfma_f32_16x16x32_bf16 v[68:71], v[162:165], v[210:213], v[68:71]
	v_mfma_f32_16x16x32_bf16 v[112:115], v[166:169], v[182:185], v[112:115]
	v_mfma_f32_16x16x32_bf16 v[116:119], v[174:177], v[182:185], v[116:119]
	v_mfma_f32_16x16x32_bf16 v[96:99], v[166:169], v[190:193], v[96:99]
	v_mfma_f32_16x16x32_bf16 v[100:103], v[174:177], v[190:193], v[100:103]
	v_mfma_f32_16x16x32_bf16 v[80:83], v[166:169], v[198:201], v[80:83]
	v_mfma_f32_16x16x32_bf16 v[84:87], v[174:177], v[198:201], v[84:87]
	v_mfma_f32_16x16x32_bf16 v[48:51], v[166:169], v[206:209], v[48:51]
	v_mfma_f32_16x16x32_bf16 v[52:55], v[174:177], v[206:209], v[52:55]
	v_mfma_f32_16x16x32_bf16 v[112:115], v[170:173], v[186:189], v[112:115]
	v_mfma_f32_16x16x32_bf16 v[116:119], v[178:181], v[186:189], v[116:119]
	v_mfma_f32_16x16x32_bf16 v[96:99], v[170:173], v[194:197], v[96:99]
	v_mfma_f32_16x16x32_bf16 v[100:103], v[178:181], v[194:197], v[100:103]
	v_mfma_f32_16x16x32_bf16 v[80:83], v[170:173], v[202:205], v[80:83]
	v_mfma_f32_16x16x32_bf16 v[84:87], v[178:181], v[202:205], v[84:87]
	v_mfma_f32_16x16x32_bf16 v[48:51], v[170:173], v[210:213], v[48:51]
	v_mfma_f32_16x16x32_bf16 v[52:55], v[178:181], v[210:213], v[52:55]
	s_barrier
; #define PG8_STAGE(bufoff, gbase, voff) do { _Pragma("unroll") for (int _i = 0; _i < 2; ++_i) \
;         __builtin_amdgcn_global_load_lds((const unsigned*)((const char*)(gbase) + (voff)[_i]), (PG8_LAS unsigned*)(lds + (bufoff) + ldsw + _i * 8192), 16, 0, 0); } while (0)
; #define PG8_BAR __builtin_amdgcn_s_barrier()
; template <class Epi, class Sched, bool ALIGN_EPI = false, bool SP2 = false, bool A_TILED = false>
; __device__ __forceinline__ void gemm_phase(PG8_LAS unsigned char* lds, const Gemm g, const Sched& S, const Epi& E, const int wave_s) {
;     ...
;         for (int t = PEEL ? 2 : 0; t < nt; t += 2) {
;             const bool last = (t == nt - 2);
;             const char* a1 = cA + (size_t)(t + 1) * kstepA;
;             const char* a2 = last ? nA : cA + (size_t)(t + 2) * kstepA; const char* b2 = last ? nB : cB + (size_t)(t + 2) * kstep;
;             const char* a3 = a2 + kstepA; const char* b3 = b2 + kstep;
;             if (last && has_next) S.a_ready(nxt);
;             if constexpr (SP2) {
;             PG8_ITER(PG8_MMA)
;             } else {
;             PG8_LDB(B0, 0, 0); PG8_SCHED; PG8_LDA(At, 0, 0); PG8_STAGE(PG8_SA(1, 1), a1 + hstepA, voffA);
;             PG8_WAIT_L(8); PG8_BAR; PG8_WAIT_L(0); PG8_MMA(0, 0, At, B0); PG8_BAR; PG8_SCHED;
;             PG8_LDB(B1, 0, 1); PG8_STAGE(PG8_SB(0, 0), b2, voffB);
;             PG8_BAR; PG8_WAIT_L(0); PG8_MMA(0, 1, At, B1); PG8_BAR;
;             PG8_LDA(At, 0, 1); PG8_STAGE(PG8_SA(0, 0), a2, voffA);
;             PG8_BAR; PG8_WAIT_L(0); PG8_MMA(1, 0, At, B0); PG8_BAR; PG8_SCHED;
;             PG8_STAGE(PG8_SB(0, 1), b2 + hstep, voffB);
;             PG8_WAIT_V(6); PG8_BAR; PG8_MMA(1, 1, At, B1); PG8_BAR;
;             PG8_LDB(B0, 1, 0); PG8_SCHED; PG8_LDA(At, 1, 0); PG8_STAGE(PG8_SA(0, 1), a2 + hstepA, voffA);
;             PG8_WAIT_L(8); PG8_BAR; PG8_WAIT_L(0); PG8_MMA(0, 0, At, B0); PG8_BAR; PG8_SCHED;
;             PG8_LDB(B1, 1, 1); PG8_STAGE(PG8_SB(1, 0), b3, voffB);
;             PG8_BAR; PG8_WAIT_L(0); PG8_MMA(0, 1, At, B1); PG8_BAR;
;             PG8_LDA(At, 1, 1); PG8_STAGE(PG8_SA(1, 0), a3, voffA);
;             PG8_BAR; PG8_WAIT_L(0); PG8_MMA(1, 0, At, B0); PG8_BAR; PG8_SCHED;
;             PG8_STAGE(PG8_SB(1, 1), b3 + hstep, voffB);
;             PG8_WAIT_V(6); PG8_BAR; PG8_MMA(1, 1, At, B1); PG8_BAR;
;             }
;         }
;         if constexpr (ALIGN_EPI) { if (wr == 0) PG8_BAR; }
	s_mov_b32 m0, s79
	v_lshl_add_u64 v[214:215], v[214:215], 0, s[12:13]
	s_add_u32 s74, s74, 0x80080
	ds_read_b128 v[182:185], v147 offset:49152
	ds_read_b128 v[186:189], v147 offset:50176
	ds_read_b128 v[190:193], v147 offset:51200
	ds_read_b128 v[194:197], v147 offset:52224
	ds_read_b128 v[198:201], v147 offset:53248
	ds_read_b128 v[202:205], v147 offset:54272
	ds_read_b128 v[206:209], v147 offset:55296
	ds_read_b128 v[210:213], v147 offset:56320
	global_load_lds_dwordx4 v[214:215], off
	v_lshl_add_u64 v[214:215], v[216:217], 0, s[12:13]
	s_mov_b32 m0, s80
	s_addc_u32 s75, s75, 0
	global_load_lds_dwordx4 v[214:215], off
	v_lshl_add_u64 v[214:215], s[74:75], 0, v[128:129]
	s_mov_b32 m0, s81
	s_nop 0
	global_load_lds_dwordx4 v128, s[74:75]
	v_lshl_add_u64 v[214:215], s[74:75], 0, v[130:131]
	s_mov_b32 m0, s82
	s_nop 0
	global_load_lds_dwordx4 v130, s[74:75]
	v_lshl_add_u64 v[214:215], v[218:219], 0, s[12:13]
	s_mov_b32 m0, s43
	s_nop 0
	global_load_lds_dwordx4 v[214:215], off
	v_lshl_add_u64 v[214:215], v[220:221], 0, s[12:13]
	s_mov_b32 m0, s48
	s_nop 0
	global_load_lds_dwordx4 v[214:215], off
	s_waitcnt vmcnt(8) lgkmcnt(0)
	s_barrier
	v_mfma_f32_16x16x32_bf16 v[72:75], v[150:153], v[182:185], v[72:75]
	v_mfma_f32_16x16x32_bf16 v[76:79], v[158:161], v[182:185], v[76:79]
	v_mfma_f32_16x16x32_bf16 v[40:43], v[150:153], v[190:193], v[40:43]
	v_mfma_f32_16x16x32_bf16 v[44:47], v[158:161], v[190:193], v[44:47]
	v_mfma_f32_16x16x32_bf16 v[24:27], v[150:153], v[198:201], v[24:27]
	v_mfma_f32_16x16x32_bf16 v[28:31], v[158:161], v[198:201], v[28:31]
	v_mfma_f32_16x16x32_bf16 v[8:11], v[150:153], v[206:209], v[8:11]
	v_mfma_f32_16x16x32_bf16 v[12:15], v[158:161], v[206:209], v[12:15]
	v_mfma_f32_16x16x32_bf16 v[72:75], v[154:157], v[186:189], v[72:75]
	v_mfma_f32_16x16x32_bf16 v[76:79], v[162:165], v[186:189], v[76:79]
	v_mfma_f32_16x16x32_bf16 v[40:43], v[154:157], v[194:197], v[40:43]
	v_mfma_f32_16x16x32_bf16 v[44:47], v[162:165], v[194:197], v[44:47]
	v_mfma_f32_16x16x32_bf16 v[24:27], v[154:157], v[202:205], v[24:27]
	v_mfma_f32_16x16x32_bf16 v[28:31], v[162:165], v[202:205], v[28:31]
	v_mfma_f32_16x16x32_bf16 v[8:11], v[154:157], v[210:213], v[8:11]
	v_mfma_f32_16x16x32_bf16 v[12:15], v[162:165], v[210:213], v[12:15]
	v_mfma_f32_16x16x32_bf16 v[56:59], v[166:169], v[182:185], v[56:59]
	v_mfma_f32_16x16x32_bf16 v[60:63], v[174:177], v[182:185], v[60:63]
	v_mfma_f32_16x16x32_bf16 v[32:35], v[166:169], v[190:193], v[32:35]
	v_mfma_f32_16x16x32_bf16 v[36:39], v[174:177], v[190:193], v[36:39]
	v_mfma_f32_16x16x32_bf16 v[16:19], v[166:169], v[198:201], v[16:19]
	v_mfma_f32_16x16x32_bf16 v[20:23], v[174:177], v[198:201], v[20:23]
	v_mfma_f32_16x16x32_bf16 v[0:3], v[166:169], v[206:209], v[0:3]
	v_mfma_f32_16x16x32_bf16 v[4:7], v[174:177], v[206:209], v[4:7]
	v_mfma_f32_16x16x32_bf16 v[56:59], v[170:173], v[186:189], v[56:59]
	v_mfma_f32_16x16x32_bf16 v[60:63], v[178:181], v[186:189], v[60:63]
	v_mfma_f32_16x16x32_bf16 v[32:35], v[170:173], v[194:197], v[32:35]
	v_mfma_f32_16x16x32_bf16 v[36:39], v[178:181], v[194:197], v[36:39]
	v_mfma_f32_16x16x32_bf16 v[16:19], v[170:173], v[202:205], v[16:19]
	v_mfma_f32_16x16x32_bf16 v[20:23], v[178:181], v[202:205], v[20:23]
	v_mfma_f32_16x16x32_bf16 v[0:3], v[170:173], v[210:213], v[0:3]
	v_mfma_f32_16x16x32_bf16 v[4:7], v[178:181], v[210:213], v[4:7]
	s_barrier
	s_add_i32 s88, s88, 2
	s_add_u32 s83, s83, 0x100
	s_addc_u32 s85, s85, 0
	s_add_u32 s72, s72, 0x100
	s_addc_u32 s73, s73, 0
	s_cmp_gt_u32 s88, 29
	s_cbranch_scc0 .LBB0_2841
	s_and_b64 vcc, exec, s[44:45]
	s_cbranch_vccz .LBB0_2844
	s_barrier

; __device__ __forceinline__ int tid_now(int wave_s) { unsigned z = 0u; asm volatile("" : "+v"(z)); return (wave_s << 6) | (int)__builtin_amdgcn_mbcnt_hi(~0u, __builtin_amdgcn_mbcnt_lo(~0u, z)); }
; __device__ __forceinline__ unsigned xb_add(unsigned* p, unsigned v) { return __hip_atomic_fetch_add(p, v, __ATOMIC_RELAXED, __HIP_MEMORY_SCOPE_AGENT); }
; __device__ __forceinline__ void xcd_barrier(const XcdBarrier& b) {
;     asm volatile("s_waitcnt vmcnt(0)" ::: "memory");
;     __syncthreads();
;     if (tid_now(b.w) == 0) {
;         unsigned* bar = b.bar;
;         __builtin_amdgcn_s_waitcnt(0);
;         unsigned nloc = b.st[0], nx = b.st[1];
;         if (nloc == 0u) { xcd_barrier_complete(bar, b.x, nloc, nx, b.np); b.st[0] = nloc; b.st[1] = nx; }
;         const unsigned old = xb_add(&bar[XB_XSUB(b.x)], 1u);
.LBB0_2848:
	s_setprio 0
	s_cmp_gt_i32 s35, 19
	s_cselect_b64 s[2:3], -1, 0
	s_and_b64 s[0:1], s[4:5], s[2:3]
	s_andn2_b64 vcc, exec, s[0:1]
	s_cbranch_vccnz .LBB0_2902
	v_mov_b32_e32 v0, 0
	s_waitcnt vmcnt(0)
	s_waitcnt vmcnt(0) lgkmcnt(0)
	s_barrier
	s_nop 0
	v_mbcnt_lo_u32_b32 v0, -1, v0
	v_mbcnt_hi_u32_b32 v0, -1, v0
	v_or_b32_e32 v0, s33, v0
	v_cmp_eq_u32_e32 vcc, 0, v0
	s_and_saveexec_b64 s[4:5], vcc
	s_cbranch_execz .LBB0_2901
	s_add_i32 s0, 0, 0x27f68
	v_mov_b32_e32 v0, s0
	s_waitcnt vmcnt(0) expcnt(0) lgkmcnt(0)
	ds_read_b32 v2, v0
	s_add_i32 s0, 0, 0x27f6c
	v_mov_b32_e32 v0, s0
	ds_read_b32 v0, v0
	s_waitcnt lgkmcnt(1)
	v_cmp_ne_u32_e32 vcc, 0, v2
	s_cbranch_vccnz .LBB0_2865
	s_add_u32 s6, s10, 0x1000
	s_addc_u32 s7, s11, 0
	s_add_u32 s12, s10, 0x1100
	s_addc_u32 s13, s11, 0
	s_add_u32 s44, s10, 0x1200
	s_addc_u32 s45, s11, 0
	s_add_u32 s46, s10, 0x1300
	s_addc_u32 s47, s11, 0
	s_mov_b32 s0, 1
	v_mov_b32_e32 v16, 0
	s_branch .LBB0_2853

; #define PG8_STAGE(bufoff, gbase, voff) do { _Pragma("unroll") for (int _i = 0; _i < 2; ++_i) \
;         __builtin_amdgcn_global_load_lds((const unsigned*)((const char*)(gbase) + (voff)[_i]), (PG8_LAS unsigned*)(lds + (bufoff) + ldsw + _i * 8192), 16, 0, 0); } while (0)
; #define PG8_WAIT_V(n) asm volatile("s_waitcnt vmcnt(" #n ")" ::: "memory")
; #define PG8_BAR __builtin_amdgcn_s_barrier()
; template <class Epi, class Sched, bool ALIGN_EPI = false, bool SP2 = false, bool A_TILED = false>
; __device__ __forceinline__ void gemm_phase(PG8_LAS unsigned char* lds, const Gemm g, const Sched& S, const Epi& E, const int wave_s) {
;     ...
;         PG8_STAGE(PG8_SB(0, 0), cB, voffB); PG8_STAGE(PG8_SB(0, 1), cB + hstep, voffB); PG8_STAGE(PG8_SA(0, 0), cA, voffA); PG8_STAGE(PG8_SA(0, 1), cA + hstepA, voffA);
;         if (wr == 1) PG8_BAR;
;         PG8_WAIT_V(2); PG8_BAR;
;         PG8_STAGE(PG8_SB(1, 0), cB + kstep, voffB); PG8_STAGE(PG8_SA(1, 0), cA + kstepA, voffA); PG8_STAGE(PG8_SB(1, 1), cB + hstep + kstep, voffB);
;         PG8_WAIT_V(6); PG8_BAR;
;     } else {
;         PG8_STAGE(PG8_SB(0, 0), cB, voffB); PG8_STAGE(PG8_SA(0, 0), cA, voffA); PG8_STAGE(PG8_SB(0, 1), cB + hstep, voffB); PG8_STAGE(PG8_SA(0, 1), cA + hstepA, voffA);
;         if (wr == 1) PG8_BAR;
;         PG8_WAIT_V(4); PG8_BAR;
;         PG8_STAGE(PG8_SB(1, 0), cB + kstep, voffB); PG8_STAGE(PG8_SA(1, 0), cA + kstepA, voffA); PG8_STAGE(PG8_SB(1, 1), cB + hstep + kstep, voffB);
;         PG8_WAIT_V(6); PG8_BAR;
;     }
;     for (;;) {
;         const bool has_next = Epi::AFTER_DRAIN ? false : S.next(ui + 1, nxt);
;         const char* nA = has_next ? (const char*)g.A + (size_t)nxt.pm * tstepA : cA; const char* nB = has_next ? (const char*)g.Bt + (size_t)nxt.pn * tstep : cB;
;         constexpr bool PEEL = SP2 && !Epi::AFTER_DRAIN;
;         if constexpr (PEEL) {
;             const char* a1 = cA + kstepA; const char* a2 = cA + 2 * kstepA; const char* b2 = cB + 2 * kstep; const char* a3 = a2 + kstepA; const char* b3 = b2 + kstep;
;             PG8_ITER(PG8_MMAZ)
;         } else {
; #pragma unroll
;             for (int a = 0; a < 2; ++a)
; #pragma unroll
;                 for (int b = 0; b < 2; ++b)
; #pragma unroll
;                     for (int m = 0; m < 4; ++m)
; #pragma unroll
;                         for (int n = 0; n < 2; ++n) acc[a][b][m][n] = (f32x4){0.f, 0.f, 0.f, 0.f};
.LBB0_2913:
	v_and_b32_e32 v5, 48, v4
	v_lshlrev_b32_e32 v6, 6, v4
	s_movk_i32 s36, 0x3c0
	v_lshlrev_b32_e32 v4, 2, v4
	s_mov_b64 s[60:61], 0x80
	s_and_b32 s9, s1, 3
	s_lshl_b32 s8, s23, 6
	s_lshl_b32 s23, s23, 13
	v_and_or_b32 v5, v6, s36, v5
	v_and_b32_e32 v4, 32, v4
	s_add_i32 m0, s14, 0x18000
	v_lshl_add_u64 v[2:3], v[2:3], 0, s[60:61]
	v_bitop3_b32 v6, v5, s23, v4 bitop3:0xde
	s_lshl_b32 s23, s9, 12
	s_waitcnt vmcnt(2)
	s_barrier
	global_load_lds_dwordx4 v[2:3], off
	s_add_i32 m0, s14, 0x1a000
	s_add_u32 s36, s6, 0x8000
	v_bitop3_b32 v4, v5, s23, v4 bitop3:0xde
	v_lshl_add_u64 v[0:1], v[0:1], 0, s[60:61]
	s_addc_u32 s37, s7, 0
	s_add_i32 s23, s14, 0x8000
	global_load_lds_dwordx4 v[0:1], off
	v_lshl_add_u64 v[0:1], s[36:37], 0, v[32:33]
	s_mov_b32 m0, s23
	s_mov_b64 s[40:41], 0x3460c000
	global_load_lds_dwordx4 v32, s[36:37]
	v_lshl_add_u64 v[0:1], s[36:37], 0, v[132:133]
	s_add_i32 s36, s14, 0xa000
	s_add_u32 s38, s2, 0x200080
	s_mov_b32 m0, s36
	s_addc_u32 s39, s3, 0
	global_load_lds_dwordx4 v[0:1], off
	s_add_i32 m0, s14, 0x1c000
	v_lshl_add_u64 v[0:1], s[38:39], 0, v[34:35]
	global_load_lds_dwordx4 v34, s[38:39]
	v_lshl_add_u64 v[0:1], s[38:39], 0, v[134:135]
	s_add_i32 m0, s14, 0x1e000
	s_add_u32 s37, s64, 0x16600100
	global_load_lds_dwordx4 v134, s[38:39]
	s_addc_u32 s38, s65, 0
	v_lshl_add_u64 v[0:1], s[62:63], 0, v[132:133]
	v_lshl_add_u64 v[136:137], v[0:1], 0, s[40:41]
	v_lshl_add_u64 v[0:1], s[62:63], 0, v[32:33]
	s_add_u32 s39, s62, 0x34610000
	s_waitcnt vmcnt(6)
	v_lshl_add_u64 v[138:139], v[0:1], 0, s[40:41]
	s_addc_u32 s40, s63, 0
	s_bitcmp1_b32 s33, 8
	s_cbranch_scc1 .Lsp_14
	s_setprio 1
.Lsp_14:
	s_add_i32 s47, 0, 0x10000
	s_add_i32 s49, 0, 0x14000
	s_add_i32 s51, 0, 0x18000
	s_add_i32 s54, 0, 0x1c000
	v_add_u32_e32 v140, s47, v4
	v_add_u32_e32 v141, s49, v4
	s_add_i32 s47, s47, s53
	s_add_i32 s49, s49, s53
	v_add_u32_e32 v143, s51, v4
	s_add_i32 s51, s51, s53
	s_add_i32 s53, s54, s53
	s_mov_b32 s41, -2
	v_add_u32_e32 v142, 0, v6
	s_add_i32 s42, s14, 0xc000
	s_add_i32 s43, s14, 0xe000
	s_add_i32 s48, s47, 0x2000
	s_add_i32 s50, s49, 0x2000
	v_add_u32_e32 v144, s54, v4
	s_add_i32 s52, s51, 0x2000
	s_add_i32 s54, s53, 0x2000
	s_mov_b64 s[62:63], 0x10000
	v_mov_b32_e32 v0, v35
	v_mov_b32_e32 v1, v35
	v_mov_b32_e32 v2, v35
	v_mov_b32_e32 v3, v35
	v_mov_b32_e32 v4, v35
	v_mov_b32_e32 v5, v35
	v_mov_b32_e32 v6, v35
	v_mov_b32_e32 v7, v35
	v_mov_b32_e32 v40, v35
	v_mov_b32_e32 v41, v35
	v_mov_b32_e32 v42, v35
	v_mov_b32_e32 v43, v35
	v_mov_b32_e32 v44, v35
	v_mov_b32_e32 v45, v35
	v_mov_b32_e32 v46, v35
	v_mov_b32_e32 v47, v35
	v_mov_b32_e32 v88, v35
	v_mov_b32_e32 v89, v35
	v_mov_b32_e32 v90, v35
	v_mov_b32_e32 v91, v35
	v_mov_b32_e32 v92, v35
	v_mov_b32_e32 v93, v35
	v_mov_b32_e32 v94, v35
	v_mov_b32_e32 v95, v35
	v_mov_b32_e32 v112, v35
	v_mov_b32_e32 v113, v35
	v_mov_b32_e32 v114, v35
	v_mov_b32_e32 v115, v35
	v_mov_b32_e32 v124, v35
	v_mov_b32_e32 v125, v35
	v_mov_b32_e32 v126, v35
	v_mov_b32_e32 v127, v35
	v_mov_b32_e32 v24, v35
	v_mov_b32_e32 v25, v35
	v_mov_b32_e32 v26, v35
	v_mov_b32_e32 v27, v35
	v_mov_b32_e32 v36, v35
	v_mov_b32_e32 v37, v35
	v_mov_b32_e32 v38, v35
	v_mov_b32_e32 v39, v35
	v_mov_b32_e32 v80, v35
	v_mov_b32_e32 v81, v35
	v_mov_b32_e32 v82, v35
	v_mov_b32_e32 v83, v35
	v_mov_b32_e32 v84, v35
	v_mov_b32_e32 v85, v35
	v_mov_b32_e32 v86, v35
	v_mov_b32_e32 v87, v35
	v_mov_b32_e32 v120, v35
	v_mov_b32_e32 v121, v35
	v_mov_b32_e32 v122, v35
	v_mov_b32_e32 v123, v35
	v_mov_b32_e32 v116, v35
	v_mov_b32_e32 v117, v35
	v_mov_b32_e32 v118, v35
	v_mov_b32_e32 v119, v35
	v_mov_b32_e32 v104, v35
	v_mov_b32_e32 v105, v35
	v_mov_b32_e32 v106, v35
	v_mov_b32_e32 v107, v35
	v_mov_b32_e32 v100, v35
	v_mov_b32_e32 v101, v35
	v_mov_b32_e32 v102, v35
	v_mov_b32_e32 v103, v35
	v_mov_b32_e32 v96, v35
	v_mov_b32_e32 v97, v35
	v_mov_b32_e32 v98, v35
	v_mov_b32_e32 v99, v35
	v_mov_b32_e32 v108, v35
	v_mov_b32_e32 v109, v35
	v_mov_b32_e32 v110, v35
	v_mov_b32_e32 v111, v35
	v_mov_b32_e32 v64, v35
	v_mov_b32_e32 v65, v35
	v_mov_b32_e32 v66, v35
	v_mov_b32_e32 v67, v35
	v_mov_b32_e32 v72, v35
	v_mov_b32_e32 v73, v35
	v_mov_b32_e32 v74, v35
	v_mov_b32_e32 v75, v35
	v_mov_b32_e32 v48, v35
	v_mov_b32_e32 v49, v35
	v_mov_b32_e32 v50, v35
	v_mov_b32_e32 v51, v35
	v_mov_b32_e32 v56, v35
	v_mov_b32_e32 v57, v35
	v_mov_b32_e32 v58, v35
	v_mov_b32_e32 v59, v35
	v_mov_b32_e32 v16, v35
	v_mov_b32_e32 v17, v35
	v_mov_b32_e32 v18, v35
	v_mov_b32_e32 v19, v35
	v_mov_b32_e32 v28, v35
	v_mov_b32_e32 v29, v35
	v_mov_b32_e32 v30, v35
	v_mov_b32_e32 v31, v35
	v_mov_b32_e32 v68, v35
	v_mov_b32_e32 v69, v35
	v_mov_b32_e32 v70, v35
	v_mov_b32_e32 v71, v35
	v_mov_b32_e32 v128, v35
	v_mov_b32_e32 v129, v35
	v_mov_b32_e32 v130, v35
	v_mov_b32_e32 v131, v35
	v_mov_b32_e32 v52, v35
	v_mov_b32_e32 v53, v35
	v_mov_b32_e32 v54, v35
	v_mov_b32_e32 v55, v35
	v_mov_b32_e32 v76, v35
	v_mov_b32_e32 v77, v35
	v_mov_b32_e32 v78, v35
	v_mov_b32_e32 v79, v35
	v_mov_b32_e32 v20, v35
	v_mov_b32_e32 v21, v35
	v_mov_b32_e32 v22, v35
	v_mov_b32_e32 v23, v35
	v_mov_b32_e32 v60, v35
	v_mov_b32_e32 v61, v35
	v_mov_b32_e32 v62, v35
	v_mov_b32_e32 v63, v35
	v_mov_b32_e32 v12, v35
	v_mov_b32_e32 v13, v35
	v_mov_b32_e32 v14, v35
	v_mov_b32_e32 v15, v35
	v_mov_b32_e32 v8, v35
	v_mov_b32_e32 v9, v35
	v_mov_b32_e32 v10, v35
	v_mov_b32_e32 v11, v35
	s_barrier
; template <class Epi, class Sched, bool ALIGN_EPI = false, bool SP2 = false, bool A_TILED = false>
; __device__ __forceinline__ void gemm_phase(PG8_LAS unsigned char* lds, const Gemm g, const Sched& S, const Epi& E, const int wave_s) {
;     ...
;         for (int t = PEEL ? 2 : 0; t < nt; t += 2) {
;             const bool last = (t == nt - 2);
;             const char* a1 = cA + (size_t)(t + 1) * kstepA;
;             const char* a2 = last ? nA : cA + (size_t)(t + 2) * kstepA; const char* b2 = last ? nB : cB + (size_t)(t + 2) * kstep;
;             const char* a3 = a2 + kstepA; const char* b3 = b2 + kstep;
;             if (last && has_next) S.a_ready(nxt);
.LBB0_2914:
	ds_read_b128 v[146:149], v140
	ds_read_b128 v[150:153], v140 offset:1024
	ds_read_b128 v[154:157], v140 offset:2048
	ds_read_b128 v[158:161], v140 offset:3072
	ds_read_b128 v[162:165], v141
	ds_read_b128 v[166:169], v141 offset:1024
	ds_read_b128 v[170:173], v141 offset:2048
	ds_read_b128 v[174:177], v141 offset:3072
	s_add_u32 s55, s44, s39
	s_addc_u32 s56, s45, s40
	s_add_u32 s57, s44, s37
	s_addc_u32 s58, s45, s38
	s_cmpk_eq_i32 s41, 0x7c
	s_cselect_b32 s68, s6, s55
	s_cselect_b32 s69, s7, s56
	s_cselect_b32 s66, s2, s57
	s_cselect_b32 s67, s3, s58
	s_add_u32 s64, s68, 0x8000
	s_addc_u32 s65, s69, 0
	s_mov_b32 m0, s42
	v_lshl_add_u64 v[210:211], s[44:45], 0, v[138:139]
	ds_read_b128 v[178:181], v142
	ds_read_b128 v[182:185], v142 offset:1024
	ds_read_b128 v[186:189], v142 offset:2048
	ds_read_b128 v[190:193], v142 offset:3072
	ds_read_b128 v[194:197], v142 offset:4096
	ds_read_b128 v[198:201], v142 offset:5120
	ds_read_b128 v[202:205], v142 offset:6144
	ds_read_b128 v[206:209], v142 offset:7168
	global_load_lds_dwordx4 v[210:211], off
	v_lshl_add_u64 v[210:211], s[44:45], 0, v[136:137]
	s_mov_b32 m0, s43
	s_nop 0
	global_load_lds_dwordx4 v[210:211], off
	s_waitcnt vmcnt(8) lgkmcnt(0)
	s_barrier
	v_mfma_f32_16x16x32_bf16 v[8:11], v[146:149], v[178:181], v[8:11]
	v_mfma_f32_16x16x32_bf16 v[12:15], v[154:157], v[178:181], v[12:15]
	v_mfma_f32_16x16x32_bf16 v[60:63], v[146:149], v[186:189], v[60:63]
	v_mfma_f32_16x16x32_bf16 v[20:23], v[154:157], v[186:189], v[20:23]
	v_mfma_f32_16x16x32_bf16 v[76:79], v[146:149], v[194:197], v[76:79]
	v_mfma_f32_16x16x32_bf16 v[52:55], v[154:157], v[194:197], v[52:55]
	v_mfma_f32_16x16x32_bf16 v[128:131], v[146:149], v[202:205], v[128:131]
	v_mfma_f32_16x16x32_bf16 v[68:71], v[154:157], v[202:205], v[68:71]
	v_mfma_f32_16x16x32_bf16 v[8:11], v[150:153], v[182:185], v[8:11]
	v_mfma_f32_16x16x32_bf16 v[12:15], v[158:161], v[182:185], v[12:15]
	v_mfma_f32_16x16x32_bf16 v[60:63], v[150:153], v[190:193], v[60:63]
	v_mfma_f32_16x16x32_bf16 v[20:23], v[158:161], v[190:193], v[20:23]
	v_mfma_f32_16x16x32_bf16 v[76:79], v[150:153], v[198:201], v[76:79]
	v_mfma_f32_16x16x32_bf16 v[52:55], v[158:161], v[198:201], v[52:55]
	v_mfma_f32_16x16x32_bf16 v[128:131], v[150:153], v[206:209], v[128:131]
	v_mfma_f32_16x16x32_bf16 v[68:71], v[158:161], v[206:209], v[68:71]
	v_mfma_f32_16x16x32_bf16 v[28:31], v[162:165], v[178:181], v[28:31]
	v_mfma_f32_16x16x32_bf16 v[16:19], v[170:173], v[178:181], v[16:19]
	v_mfma_f32_16x16x32_bf16 v[56:59], v[162:165], v[186:189], v[56:59]
	v_mfma_f32_16x16x32_bf16 v[48:51], v[170:173], v[186:189], v[48:51]
	v_mfma_f32_16x16x32_bf16 v[72:75], v[162:165], v[194:197], v[72:75]
	v_mfma_f32_16x16x32_bf16 v[64:67], v[170:173], v[194:197], v[64:67]
	v_mfma_f32_16x16x32_bf16 v[108:111], v[162:165], v[202:205], v[108:111]
	v_mfma_f32_16x16x32_bf16 v[96:99], v[170:173], v[202:205], v[96:99]
	v_mfma_f32_16x16x32_bf16 v[28:31], v[166:169], v[182:185], v[28:31]
	v_mfma_f32_16x16x32_bf16 v[16:19], v[174:177], v[182:185], v[16:19]
	v_mfma_f32_16x16x32_bf16 v[56:59], v[166:169], v[190:193], v[56:59]
	v_mfma_f32_16x16x32_bf16 v[48:51], v[174:177], v[190:193], v[48:51]
	v_mfma_f32_16x16x32_bf16 v[72:75], v[166:169], v[198:201], v[72:75]
	v_mfma_f32_16x16x32_bf16 v[64:67], v[174:177], v[198:201], v[64:67]
	v_mfma_f32_16x16x32_bf16 v[108:111], v[166:169], v[206:209], v[108:111]
	v_mfma_f32_16x16x32_bf16 v[96:99], v[174:177], v[206:209], v[96:99]
	s_barrier
	s_mov_b32 m0, s47
	v_lshl_add_u64 v[210:211], s[66:67], 0, v[34:35]
	s_add_u32 s56, s66, 0x200000
	ds_read_b128 v[178:181], v142 offset:16384
	ds_read_b128 v[182:185], v142 offset:17408
	ds_read_b128 v[186:189], v142 offset:18432
	ds_read_b128 v[190:193], v142 offset:19456
	ds_read_b128 v[194:197], v142 offset:20480
	ds_read_b128 v[198:201], v142 offset:21504
	ds_read_b128 v[202:205], v142 offset:22528
	ds_read_b128 v[206:209], v142 offset:23552
	global_load_lds_dwordx4 v34, s[66:67]
	v_lshl_add_u64 v[212:213], s[66:67], 0, v[134:135]
	s_mov_b32 m0, s48
	s_addc_u32 s57, s67, 0
	global_load_lds_dwordx4 v134, s[66:67]
	v_lshl_add_u64 v[214:215], s[56:57], 0, v[34:35]
	s_mov_b32 m0, s49
	s_nop 0
	global_load_lds_dwordx4 v34, s[56:57]
	v_lshl_add_u64 v[214:215], s[56:57], 0, v[134:135]
	s_mov_b32 m0, s50
	s_nop 0
	global_load_lds_dwordx4 v134, s[56:57]
	v_lshl_add_u64 v[214:215], s[68:69], 0, v[32:33]
	s_mov_b32 m0, s14
	s_nop 0
	global_load_lds_dwordx4 v32, s[68:69]
	v_lshl_add_u64 v[214:215], s[68:69], 0, v[132:133]
	s_mov_b32 m0, s15
	s_nop 0
	global_load_lds_dwordx4 v132, s[68:69]
	s_waitcnt vmcnt(8) lgkmcnt(0)
	s_barrier
	v_mfma_f32_16x16x32_bf16 v[100:103], v[146:149], v[178:181], v[100:103]
	v_mfma_f32_16x16x32_bf16 v[104:107], v[154:157], v[178:181], v[104:107]
	v_mfma_f32_16x16x32_bf16 v[116:119], v[146:149], v[186:189], v[116:119]
	v_mfma_f32_16x16x32_bf16 v[120:123], v[154:157], v[186:189], v[120:123]
	v_mfma_f32_16x16x32_bf16 v[84:87], v[146:149], v[194:197], v[84:87]
	v_mfma_f32_16x16x32_bf16 v[80:83], v[154:157], v[194:197], v[80:83]
	v_mfma_f32_16x16x32_bf16 v[36:39], v[146:149], v[202:205], v[36:39]
	v_mfma_f32_16x16x32_bf16 v[24:27], v[154:157], v[202:205], v[24:27]
	v_mfma_f32_16x16x32_bf16 v[100:103], v[150:153], v[182:185], v[100:103]
	v_mfma_f32_16x16x32_bf16 v[104:107], v[158:161], v[182:185], v[104:107]
	v_mfma_f32_16x16x32_bf16 v[116:119], v[150:153], v[190:193], v[116:119]
	v_mfma_f32_16x16x32_bf16 v[120:123], v[158:161], v[190:193], v[120:123]
	v_mfma_f32_16x16x32_bf16 v[84:87], v[150:153], v[198:201], v[84:87]
	v_mfma_f32_16x16x32_bf16 v[80:83], v[158:161], v[198:201], v[80:83]
	v_mfma_f32_16x16x32_bf16 v[36:39], v[150:153], v[206:209], v[36:39]
	v_mfma_f32_16x16x32_bf16 v[24:27], v[158:161], v[206:209], v[24:27]
	v_mfma_f32_16x16x32_bf16 v[124:127], v[162:165], v[178:181], v[124:127]
	v_mfma_f32_16x16x32_bf16 v[112:115], v[170:173], v[178:181], v[112:115]
	v_mfma_f32_16x16x32_bf16 v[92:95], v[162:165], v[186:189], v[92:95]
	v_mfma_f32_16x16x32_bf16 v[88:91], v[170:173], v[186:189], v[88:91]
	v_mfma_f32_16x16x32_bf16 v[44:47], v[162:165], v[194:197], v[44:47]
	v_mfma_f32_16x16x32_bf16 v[40:43], v[170:173], v[194:197], v[40:43]
	v_mfma_f32_16x16x32_bf16 v[4:7], v[162:165], v[202:205], v[4:7]
	v_mfma_f32_16x16x32_bf16 v[0:3], v[170:173], v[202:205], v[0:3]
	v_mfma_f32_16x16x32_bf16 v[124:127], v[166:169], v[182:185], v[124:127]
	v_mfma_f32_16x16x32_bf16 v[112:115], v[174:177], v[182:185], v[112:115]
	v_mfma_f32_16x16x32_bf16 v[92:95], v[166:169], v[190:193], v[92:95]
	v_mfma_f32_16x16x32_bf16 v[88:91], v[174:177], v[190:193], v[88:91]
	v_mfma_f32_16x16x32_bf16 v[44:47], v[166:169], v[198:201], v[44:47]
	v_mfma_f32_16x16x32_bf16 v[40:43], v[174:177], v[198:201], v[40:43]
	v_mfma_f32_16x16x32_bf16 v[4:7], v[166:169], v[206:209], v[4:7]
	v_mfma_f32_16x16x32_bf16 v[0:3], v[174:177], v[206:209], v[0:3]
	s_barrier
	ds_read_b128 v[146:149], v143
	ds_read_b128 v[150:153], v143 offset:1024
	ds_read_b128 v[154:157], v143 offset:2048
	ds_read_b128 v[158:161], v143 offset:3072
	ds_read_b128 v[162:165], v144
	ds_read_b128 v[166:169], v144 offset:1024
	ds_read_b128 v[170:173], v144 offset:2048
	ds_read_b128 v[174:177], v144 offset:3072
	s_add_u32 s56, s68, 0x4000
	s_addc_u32 s57, s69, 0
	s_mov_b32 m0, s21
	v_lshl_add_u64 v[214:215], s[56:57], 0, v[32:33]
	ds_read_b128 v[178:181], v142 offset:32768
	ds_read_b128 v[182:185], v142 offset:33792
	ds_read_b128 v[186:189], v142 offset:34816
	ds_read_b128 v[190:193], v142 offset:35840
	ds_read_b128 v[194:197], v142 offset:36864
	ds_read_b128 v[198:201], v142 offset:37888
	ds_read_b128 v[202:205], v142 offset:38912
	ds_read_b128 v[206:209], v142 offset:39936
	global_load_lds_dwordx4 v32, s[56:57]
	v_lshl_add_u64 v[214:215], s[56:57], 0, v[132:133]
	s_mov_b32 m0, s22
	s_nop 0
	global_load_lds_dwordx4 v132, s[56:57]
	s_waitcnt vmcnt(8) lgkmcnt(0)
	s_barrier
	v_mfma_f32_16x16x32_bf16 v[8:11], v[146:149], v[178:181], v[8:11]
	v_mfma_f32_16x16x32_bf16 v[12:15], v[154:157], v[178:181], v[12:15]
	v_mfma_f32_16x16x32_bf16 v[60:63], v[146:149], v[186:189], v[60:63]
	v_mfma_f32_16x16x32_bf16 v[20:23], v[154:157], v[186:189], v[20:23]
	v_mfma_f32_16x16x32_bf16 v[76:79], v[146:149], v[194:197], v[76:79]
	v_mfma_f32_16x16x32_bf16 v[52:55], v[154:157], v[194:197], v[52:55]
	v_mfma_f32_16x16x32_bf16 v[128:131], v[146:149], v[202:205], v[128:131]
	v_mfma_f32_16x16x32_bf16 v[68:71], v[154:157], v[202:205], v[68:71]
	v_mfma_f32_16x16x32_bf16 v[8:11], v[150:153], v[182:185], v[8:11]
	v_mfma_f32_16x16x32_bf16 v[12:15], v[158:161], v[182:185], v[12:15]
	v_mfma_f32_16x16x32_bf16 v[60:63], v[150:153], v[190:193], v[60:63]
	v_mfma_f32_16x16x32_bf16 v[20:23], v[158:161], v[190:193], v[20:23]
	v_mfma_f32_16x16x32_bf16 v[76:79], v[150:153], v[198:201], v[76:79]
	v_mfma_f32_16x16x32_bf16 v[52:55], v[158:161], v[198:201], v[52:55]
	v_mfma_f32_16x16x32_bf16 v[128:131], v[150:153], v[206:209], v[128:131]
	v_mfma_f32_16x16x32_bf16 v[68:71], v[158:161], v[206:209], v[68:71]
	v_mfma_f32_16x16x32_bf16 v[28:31], v[162:165], v[178:181], v[28:31]
	v_mfma_f32_16x16x32_bf16 v[16:19], v[170:173], v[178:181], v[16:19]
	v_mfma_f32_16x16x32_bf16 v[56:59], v[162:165], v[186:189], v[56:59]
	v_mfma_f32_16x16x32_bf16 v[48:51], v[170:173], v[186:189], v[48:51]
	v_mfma_f32_16x16x32_bf16 v[72:75], v[162:165], v[194:197], v[72:75]
	v_mfma_f32_16x16x32_bf16 v[64:67], v[170:173], v[194:197], v[64:67]
	v_mfma_f32_16x16x32_bf16 v[108:111], v[162:165], v[202:205], v[108:111]
	v_mfma_f32_16x16x32_bf16 v[96:99], v[170:173], v[202:205], v[96:99]
	v_mfma_f32_16x16x32_bf16 v[28:31], v[166:169], v[182:185], v[28:31]
	v_mfma_f32_16x16x32_bf16 v[16:19], v[174:177], v[182:185], v[16:19]
	v_mfma_f32_16x16x32_bf16 v[56:59], v[166:169], v[190:193], v[56:59]
	v_mfma_f32_16x16x32_bf16 v[48:51], v[174:177], v[190:193], v[48:51]
	v_mfma_f32_16x16x32_bf16 v[72:75], v[166:169], v[198:201], v[72:75]
	v_mfma_f32_16x16x32_bf16 v[64:67], v[174:177], v[198:201], v[64:67]
	v_mfma_f32_16x16x32_bf16 v[108:111], v[166:169], v[206:209], v[108:111]
	v_mfma_f32_16x16x32_bf16 v[96:99], v[174:177], v[206:209], v[96:99]
	s_barrier
; template <class Epi, class Sched, bool ALIGN_EPI = false, bool SP2 = false, bool A_TILED = false>
; __device__ __forceinline__ void gemm_phase(PG8_LAS unsigned char* lds, const Gemm g, const Sched& S, const Epi& E, const int wave_s) {
;     ...
;         for (int t = PEEL ? 2 : 0; t < nt; t += 2) {
;             const bool last = (t == nt - 2);
;             const char* a1 = cA + (size_t)(t + 1) * kstepA;
	s_mov_b32 m0, s51
	v_lshl_add_u64 v[210:211], v[210:211], 0, s[60:61]
	s_add_u32 s56, s66, 0x200080
	ds_read_b128 v[178:181], v142 offset:49152
	ds_read_b128 v[182:185], v142 offset:50176
	ds_read_b128 v[186:189], v142 offset:51200
	ds_read_b128 v[190:193], v142 offset:52224
	ds_read_b128 v[194:197], v142 offset:53248
	ds_read_b128 v[198:201], v142 offset:54272
	ds_read_b128 v[202:205], v142 offset:55296
	ds_read_b128 v[206:209], v142 offset:56320
	global_load_lds_dwordx4 v[210:211], off
	v_lshl_add_u64 v[210:211], v[212:213], 0, s[60:61]
	s_mov_b32 m0, s52
	s_addc_u32 s57, s67, 0
	global_load_lds_dwordx4 v[210:211], off
	v_lshl_add_u64 v[210:211], s[56:57], 0, v[34:35]
	s_mov_b32 m0, s53
	s_nop 0
	global_load_lds_dwordx4 v34, s[56:57]
	v_lshl_add_u64 v[210:211], s[56:57], 0, v[134:135]
	s_mov_b32 m0, s54
	s_nop 0
	global_load_lds_dwordx4 v134, s[56:57]
	v_lshl_add_u64 v[210:211], s[64:65], 0, v[32:33]
	s_mov_b32 m0, s23
	s_nop 0
	global_load_lds_dwordx4 v32, s[64:65]
	v_lshl_add_u64 v[210:211], s[64:65], 0, v[132:133]
	s_mov_b32 m0, s36
	s_nop 0
	global_load_lds_dwordx4 v132, s[64:65]
	s_waitcnt vmcnt(8) lgkmcnt(0)
	s_barrier
	v_mfma_f32_16x16x32_bf16 v[100:103], v[146:149], v[178:181], v[100:103]
	v_mfma_f32_16x16x32_bf16 v[104:107], v[154:157], v[178:181], v[104:107]
	v_mfma_f32_16x16x32_bf16 v[116:119], v[146:149], v[186:189], v[116:119]
	v_mfma_f32_16x16x32_bf16 v[120:123], v[154:157], v[186:189], v[120:123]
	v_mfma_f32_16x16x32_bf16 v[84:87], v[146:149], v[194:197], v[84:87]
	v_mfma_f32_16x16x32_bf16 v[80:83], v[154:157], v[194:197], v[80:83]
	v_mfma_f32_16x16x32_bf16 v[36:39], v[146:149], v[202:205], v[36:39]
	v_mfma_f32_16x16x32_bf16 v[24:27], v[154:157], v[202:205], v[24:27]
	v_mfma_f32_16x16x32_bf16 v[100:103], v[150:153], v[182:185], v[100:103]
	v_mfma_f32_16x16x32_bf16 v[104:107], v[158:161], v[182:185], v[104:107]
	v_mfma_f32_16x16x32_bf16 v[116:119], v[150:153], v[190:193], v[116:119]
	v_mfma_f32_16x16x32_bf16 v[120:123], v[158:161], v[190:193], v[120:123]
	v_mfma_f32_16x16x32_bf16 v[84:87], v[150:153], v[198:201], v[84:87]
	v_mfma_f32_16x16x32_bf16 v[80:83], v[158:161], v[198:201], v[80:83]
	v_mfma_f32_16x16x32_bf16 v[36:39], v[150:153], v[206:209], v[36:39]
	v_mfma_f32_16x16x32_bf16 v[24:27], v[158:161], v[206:209], v[24:27]
	v_mfma_f32_16x16x32_bf16 v[124:127], v[162:165], v[178:181], v[124:127]
	v_mfma_f32_16x16x32_bf16 v[112:115], v[170:173], v[178:181], v[112:115]
	v_mfma_f32_16x16x32_bf16 v[92:95], v[162:165], v[186:189], v[92:95]
	v_mfma_f32_16x16x32_bf16 v[88:91], v[170:173], v[186:189], v[88:91]
	v_mfma_f32_16x16x32_bf16 v[44:47], v[162:165], v[194:197], v[44:47]
	v_mfma_f32_16x16x32_bf16 v[40:43], v[170:173], v[194:197], v[40:43]
	v_mfma_f32_16x16x32_bf16 v[4:7], v[162:165], v[202:205], v[4:7]
	v_mfma_f32_16x16x32_bf16 v[0:3], v[170:173], v[202:205], v[0:3]
	v_mfma_f32_16x16x32_bf16 v[124:127], v[166:169], v[182:185], v[124:127]
	v_mfma_f32_16x16x32_bf16 v[112:115], v[174:177], v[182:185], v[112:115]
	v_mfma_f32_16x16x32_bf16 v[92:95], v[166:169], v[190:193], v[92:95]
	v_mfma_f32_16x16x32_bf16 v[88:91], v[174:177], v[190:193], v[88:91]
	v_mfma_f32_16x16x32_bf16 v[44:47], v[166:169], v[198:201], v[44:47]
	v_mfma_f32_16x16x32_bf16 v[40:43], v[174:177], v[198:201], v[40:43]
	v_mfma_f32_16x16x32_bf16 v[4:7], v[166:169], v[206:209], v[4:7]
	v_mfma_f32_16x16x32_bf16 v[0:3], v[174:177], v[206:209], v[0:3]
	s_barrier
	s_add_i32 s41, s41, 2
	s_add_u32 s37, s37, 0x100
	s_addc_u32 s38, s38, 0
	s_add_u32 s39, s39, 0x10000
	s_addc_u32 s40, s40, 0
	v_lshl_add_u64 v[136:137], v[136:137], 0, s[62:63]
	s_cmpk_gt_u32 s41, 0x7d
	v_lshl_add_u64 v[138:139], v[138:139], 0, s[62:63]
	s_cbranch_scc0 .LBB0_2914
	s_waitcnt vmcnt(0)
	s_cmpk_lt_u32 s0, 0x100
	s_cbranch_scc0 .LBB0_2917
	s_barrier

; __device__ __forceinline__ int tid_now(int wave_s) { unsigned z = 0u; asm volatile("" : "+v"(z)); return (wave_s << 6) | (int)__builtin_amdgcn_mbcnt_hi(~0u, __builtin_amdgcn_mbcnt_lo(~0u, z)); }
; __device__ __forceinline__ unsigned xb_add(unsigned* p, unsigned v) { return __hip_atomic_fetch_add(p, v, __ATOMIC_RELAXED, __HIP_MEMORY_SCOPE_AGENT); }
; __device__ __forceinline__ void xcd_barrier(const XcdBarrier& b) {
;     asm volatile("s_waitcnt vmcnt(0)" ::: "memory");
;     __syncthreads();
;     if (tid_now(b.w) == 0) {
;         unsigned* bar = b.bar;
;         __builtin_amdgcn_s_waitcnt(0);
;         unsigned nloc = b.st[0], nx = b.st[1];
;         if (nloc == 0u) { xcd_barrier_complete(bar, b.x, nloc, nx, b.np); b.st[0] = nloc; b.st[1] = nx; }
;         const unsigned old = xb_add(&bar[XB_XSUB(b.x)], 1u);
.LBB0_2958:
	s_setprio 0
	s_cmp_gt_i32 s35, 20
	s_cselect_b64 s[4:5], -1, 0
	s_and_b64 s[0:1], s[12:13], s[4:5]
	s_andn2_b64 vcc, exec, s[0:1]
	s_cbranch_vccnz .LBB0_3012
	v_mov_b32_e32 v0, 0
	s_waitcnt vmcnt(0)
	s_waitcnt vmcnt(0) lgkmcnt(0)
	s_barrier
	s_nop 0
	v_mbcnt_lo_u32_b32 v0, -1, v0
	v_mbcnt_hi_u32_b32 v0, -1, v0
	v_or_b32_e32 v0, s33, v0
	v_cmp_eq_u32_e32 vcc, 0, v0
	s_and_saveexec_b64 s[2:3], vcc
	s_cbranch_execz .LBB0_3011
	s_add_i32 s0, 0, 0x27f68
	v_mov_b32_e32 v0, s0
	s_waitcnt vmcnt(0) expcnt(0) lgkmcnt(0)
	ds_read_b32 v2, v0
	s_add_i32 s0, 0, 0x27f6c
	v_mov_b32_e32 v0, s0
	ds_read_b32 v0, v0
	s_waitcnt lgkmcnt(1)
	v_cmp_ne_u32_e32 vcc, 0, v2
	s_cbranch_vccnz .LBB0_2975
	s_add_u32 s6, s10, 0x1000
	s_addc_u32 s7, s11, 0
	s_add_u32 s12, s10, 0x1100
	s_addc_u32 s13, s11, 0
	s_add_u32 s16, s10, 0x1200
	s_addc_u32 s17, s11, 0
	s_add_u32 s44, s10, 0x1300
	s_addc_u32 s45, s11, 0
	s_mov_b32 s0, 1
	v_mov_b32_e32 v16, 0
	s_branch .LBB0_2963

; #define PG8_STAGE(bufoff, gbase, voff) do { _Pragma("unroll") for (int _i = 0; _i < 2; ++_i) \
;         __builtin_amdgcn_global_load_lds((const unsigned*)((const char*)(gbase) + (voff)[_i]), (PG8_LAS unsigned*)(lds + (bufoff) + ldsw + _i * 8192), 16, 0, 0); } while (0)
; #define PG8_WAIT_V(n) asm volatile("s_waitcnt vmcnt(" #n ")" ::: "memory")
; #define PG8_BAR __builtin_amdgcn_s_barrier()
; template <class Epi, class Sched, bool ALIGN_EPI = false, bool SP2 = false, bool A_TILED = false>
; __device__ __forceinline__ void gemm_phase(PG8_LAS unsigned char* lds, const Gemm g, const Sched& S, const Epi& E, const int wave_s) {
;     ...
;         PG8_STAGE(PG8_SB(0, 0), cB, voffB); PG8_STAGE(PG8_SB(0, 1), cB + hstep, voffB); PG8_STAGE(PG8_SA(0, 0), cA, voffA); PG8_STAGE(PG8_SA(0, 1), cA + hstepA, voffA);
;         if (wr == 1) PG8_BAR;
;         PG8_WAIT_V(2); PG8_BAR;
;         PG8_STAGE(PG8_SB(1, 0), cB + kstep, voffB); PG8_STAGE(PG8_SA(1, 0), cA + kstepA, voffA); PG8_STAGE(PG8_SB(1, 1), cB + hstep + kstep, voffB);
;         PG8_WAIT_V(6); PG8_BAR;
;     } else {
;         PG8_STAGE(PG8_SB(0, 0), cB, voffB); PG8_STAGE(PG8_SA(0, 0), cA, voffA); PG8_STAGE(PG8_SB(0, 1), cB + hstep, voffB); PG8_STAGE(PG8_SA(0, 1), cA + hstepA, voffA);
;         if (wr == 1) PG8_BAR;
;         PG8_WAIT_V(4); PG8_BAR;
;         PG8_STAGE(PG8_SB(1, 0), cB + kstep, voffB); PG8_STAGE(PG8_SA(1, 0), cA + kstepA, voffA); PG8_STAGE(PG8_SB(1, 1), cB + hstep + kstep, voffB);
;         PG8_WAIT_V(6); PG8_BAR;
;     }
;     for (;;) {
;         const bool has_next = Epi::AFTER_DRAIN ? false : S.next(ui + 1, nxt);
;         const char* nA = has_next ? (const char*)g.A + (size_t)nxt.pm * tstepA : cA; const char* nB = has_next ? (const char*)g.Bt + (size_t)nxt.pn * tstep : cB;
;         constexpr bool PEEL = SP2 && !Epi::AFTER_DRAIN;
;         if constexpr (PEEL) {
;             const char* a1 = cA + kstepA; const char* a2 = cA + 2 * kstepA; const char* b2 = cB + 2 * kstep; const char* a3 = a2 + kstepA; const char* b3 = b2 + kstep;
;             PG8_ITER(PG8_MMAZ)
.LBB0_3336:
	s_ashr_i32 s56, s86, 31
	s_add_u32 s0, s0, s29
	s_addc_u32 s1, s1, 0
	s_add_u32 s6, s0, 0x22600000
	s_addc_u32 s7, s1, 0
	s_lshl_b32 s57, s13, 6
	s_lshl_b32 s16, s13, 13
	s_lshl_b32 s0, s12, 5
	s_mov_b64 s[12:13], 0x80
	s_and_b32 s58, s0, 0x60
	s_add_i32 m0, s41, 0x18000
	v_lshl_add_u64 v[6:7], v[6:7], 0, s[12:13]
	s_lshl_b32 s17, s58, 7
	s_waitcnt vmcnt(2)
	s_barrier
	global_load_lds_dwordx4 v[6:7], off
	v_lshl_add_u64 v[4:5], v[4:5], 0, s[12:13]
	s_add_i32 m0, s41, 0x1a000
	s_add_i32 s59, s41, 0x8000
	s_add_i32 s60, s41, 0xa000
	global_load_lds_dwordx4 v[4:5], off
	v_lshl_add_u64 v[0:1], v[0:1], 0, s[12:13]
	s_mov_b32 m0, s59
	s_add_u32 s0, s42, 0x80080
	global_load_lds_dwordx4 v[0:1], off
	v_lshl_add_u64 v[0:1], v[2:3], 0, s[12:13]
	s_mov_b32 m0, s60
	s_addc_u32 s1, s43, 0
	global_load_lds_dwordx4 v[0:1], off
	s_add_i32 m0, s41, 0x1c000
	v_lshl_add_u64 v[0:1], s[0:1], 0, v[128:129]
	global_load_lds_dwordx4 v128, s[0:1]
	v_lshl_add_u64 v[0:1], s[0:1], 0, v[130:131]
	s_add_i32 m0, s41, 0x1e000
	s_movk_i32 s0, 0x3c0
	global_load_lds_dwordx4 v[0:1], off
	v_and_b32_e32 v0, 48, v8
	v_lshlrev_b32_e32 v1, 6, v8
	v_and_or_b32 v0, v1, s0, v0
	v_lshlrev_b32_e32 v1, 2, v8
	v_and_b32_e32 v1, 32, v1
	v_bitop3_b32 v2, v0, s16, v1 bitop3:0xde
	v_bitop3_b32 v148, s17, v0, v1 bitop3:0xf6
	v_lshlrev_b32_e32 v0, 15, v9
	v_and_b32_e32 v0, 0xffff0000, v0
	v_lshl_add_u32 v0, v10, 12, v0
	v_and_b32_e32 v1, 1, v9
	v_lshl_or_b32 v0, v1, 6, v0
	v_lshl_add_u32 v136, v11, 1, v0
	v_lshlrev_b32_e32 v0, 15, v13
	v_and_b32_e32 v0, 0xffff0000, v0
	s_waitcnt vmcnt(6)
	s_mov_b32 s98, 0
	s_bitcmp1_b32 s33, 8
	s_cbranch_scc1 .Lsp_15
	s_setprio 1
.Lsp_15:
	s_cmpk_lt_u32 s15, 0x100
	v_lshl_add_u32 v0, v12, 12, v0
	v_and_b32_e32 v1, 1, v13
	s_sext_i32_i16 s66, s14
	s_cselect_b64 s[14:15], -1, 0
	v_mov_b32_e32 v137, 0
	v_lshl_or_b32 v0, v1, 6, v0
	s_add_i32 s61, 0, 0x10000
	s_add_i32 s62, 0, 0x14000
	v_lshl_add_u32 v138, v14, 1, v0
	v_mov_b32_e32 v139, v137
	s_mov_b64 s[16:17], 0x180
	v_add_u32_e32 v149, s61, v148
	v_add_u32_e32 v150, s62, v148
	v_add_u32_e32 v151, 0, v2
	s_mov_b64 s[20:21], 0x100
	s_movk_i32 s63, 0x3000
	s_add_i32 s64, s41, 0xc000
	s_add_i32 s65, s41, 0xe000
	s_barrier
	s_branch .LBB0_3339

; template <class Epi, class Sched, bool ALIGN_EPI = false, bool SP2 = false, bool A_TILED = false>
; __device__ __forceinline__ void gemm_phase(PG8_LAS unsigned char* lds, const Gemm g, const Sched& S, const Epi& E, const int wave_s) {
;     ...
;         if constexpr (PEEL) {
;             const char* a1 = cA + kstepA; const char* a2 = cA + 2 * kstepA; const char* b2 = cB + 2 * kstep; const char* a3 = a2 + kstepA; const char* b3 = b2 + kstep;
;             PG8_ITER(PG8_MMAZ)
.Lpw_17:
	s_barrier
	v_mfma_f32_16x16x32_bf16 v[88:91], v[0:3], v[56:59], 0
	v_mfma_f32_16x16x32_bf16 v[64:67], v[0:3], v[32:35], 0
	v_mfma_f32_16x16x32_bf16 v[68:71], v[8:11], v[32:35], 0
	v_mfma_f32_16x16x32_bf16 v[72:75], v[0:3], v[40:43], 0
	v_mfma_f32_16x16x32_bf16 v[76:79], v[8:11], v[40:43], 0
	v_mfma_f32_16x16x32_bf16 v[80:83], v[0:3], v[48:51], 0
	v_mfma_f32_16x16x32_bf16 v[84:87], v[8:11], v[48:51], 0
	v_mfma_f32_16x16x32_bf16 v[92:95], v[4:7], v[60:63], v[88:91]
	v_mfma_f32_16x16x32_bf16 v[88:91], v[8:11], v[56:59], 0
	v_mfma_f32_16x16x32_bf16 v[64:67], v[4:7], v[36:39], v[64:67]
	v_mfma_f32_16x16x32_bf16 v[68:71], v[12:15], v[36:39], v[68:71]
	v_mfma_f32_16x16x32_bf16 v[72:75], v[4:7], v[44:47], v[72:75]
	v_mfma_f32_16x16x32_bf16 v[76:79], v[12:15], v[44:47], v[76:79]
	v_mfma_f32_16x16x32_bf16 v[80:83], v[4:7], v[52:55], v[80:83]
	v_mfma_f32_16x16x32_bf16 v[84:87], v[12:15], v[52:55], v[84:87]
	v_mfma_f32_16x16x32_bf16 v[100:103], v[12:15], v[60:63], v[88:91]
	v_mfma_f32_16x16x32_bf16 v[88:91], v[16:19], v[32:35], 0
	v_mfma_f32_16x16x32_bf16 v[32:35], v[24:27], v[32:35], 0
	v_mfma_f32_16x16x32_bf16 v[108:111], v[20:23], v[36:39], v[88:91]
	v_mfma_f32_16x16x32_bf16 v[32:35], v[28:31], v[36:39], v[32:35]
	v_mfma_f32_16x16x32_bf16 v[36:39], v[16:19], v[40:43], 0
	v_mfma_f32_16x16x32_bf16 v[40:43], v[24:27], v[40:43], 0
	v_mfma_f32_16x16x32_bf16 v[36:39], v[20:23], v[44:47], v[36:39]
	v_mfma_f32_16x16x32_bf16 v[40:43], v[28:31], v[44:47], v[40:43]
	v_mfma_f32_16x16x32_bf16 v[44:47], v[16:19], v[48:51], 0
	v_mfma_f32_16x16x32_bf16 v[48:51], v[24:27], v[48:51], 0
	v_mfma_f32_16x16x32_bf16 v[44:47], v[20:23], v[52:55], v[44:47]
	v_mfma_f32_16x16x32_bf16 v[52:55], v[28:31], v[52:55], v[48:51]
	v_mfma_f32_16x16x32_bf16 v[48:51], v[16:19], v[56:59], 0
	v_mfma_f32_16x16x32_bf16 v[152:155], v[20:23], v[60:63], v[48:51]
	v_mfma_f32_16x16x32_bf16 v[48:51], v[24:27], v[56:59], 0
	v_mfma_f32_16x16x32_bf16 v[156:159], v[28:31], v[60:63], v[48:51]
	s_barrier
	s_add_i32 s69, s61, s49
	v_lshl_add_u64 v[146:147], s[42:43], 0, v[128:129]
	s_add_i32 s70, s69, 0x2000
	v_lshl_add_u64 v[120:121], v[146:147], 0, s[20:21]
	s_mov_b32 m0, s69
	v_lshl_add_u64 v[252:253], s[42:43], 0, v[130:131]
	s_add_u32 s46, s42, 0x80100
	ds_read_b128 v[48:51], v151 offset:16384
	ds_read_b128 v[56:59], v151 offset:17408
	ds_read_b128 v[60:63], v151 offset:18432
	ds_read_b128 v[88:91], v151 offset:19456
	ds_read_b128 v[96:99], v151 offset:20480
	ds_read_b128 v[104:107], v151 offset:21504
	ds_read_b128 v[112:115], v151 offset:22528
	ds_read_b128 v[116:119], v151 offset:23552
	global_load_lds_dwordx4 v[120:121], off
	v_lshl_add_u64 v[120:121], v[252:253], 0, s[20:21]
	s_mov_b32 m0, s70
	s_addc_u32 s47, s43, 0
	s_add_i32 s71, s62, s49
	global_load_lds_dwordx4 v[120:121], off
	v_lshl_add_u64 v[120:121], s[46:47], 0, v[128:129]
	s_mov_b32 m0, s71
	s_add_i32 s72, s71, 0x2000
	global_load_lds_dwordx4 v128, s[46:47]
	v_lshl_add_u64 v[120:121], s[46:47], 0, v[130:131]
	s_mov_b32 m0, s72
	v_lshl_add_u64 v[140:141], s[44:45], 0, v[134:135]
	global_load_lds_dwordx4 v130, s[46:47]
	v_lshl_add_u64 v[120:121], v[140:141], 0, s[20:21]
	s_mov_b32 m0, s41
	v_lshl_add_u64 v[142:143], s[44:45], 0, v[132:133]
	global_load_lds_dwordx4 v[120:121], off
	v_lshl_add_u64 v[120:121], v[142:143], 0, s[20:21]
	s_mov_b32 m0, s52
	s_nop 0
	global_load_lds_dwordx4 v[120:121], off
	s_waitcnt vmcnt(24) lgkmcnt(0)
	s_cmp_lg_u32 s98, 0
	s_cbranch_scc1 .Lpw_18
	s_waitcnt vmcnt(8)
.Lpw_18:
	s_barrier
	v_mfma_f32_16x16x32_bf16 v[120:123], v[0:3], v[48:51], 0
	v_mfma_f32_16x16x32_bf16 v[160:163], v[4:7], v[56:59], v[120:123]
	v_mfma_f32_16x16x32_bf16 v[120:123], v[8:11], v[48:51], 0
	v_mfma_f32_16x16x32_bf16 v[164:167], v[12:15], v[56:59], v[120:123]
	v_mfma_f32_16x16x32_bf16 v[120:123], v[0:3], v[60:63], 0
	v_mfma_f32_16x16x32_bf16 v[168:171], v[4:7], v[88:91], v[120:123]
	v_mfma_f32_16x16x32_bf16 v[120:123], v[8:11], v[60:63], 0
	v_mfma_f32_16x16x32_bf16 v[172:175], v[12:15], v[88:91], v[120:123]
	v_mfma_f32_16x16x32_bf16 v[120:123], v[0:3], v[96:99], 0
	v_mfma_f32_16x16x32_bf16 v[0:3], v[0:3], v[112:115], 0
	v_mfma_f32_16x16x32_bf16 v[176:179], v[4:7], v[104:107], v[120:123]
	v_mfma_f32_16x16x32_bf16 v[0:3], v[4:7], v[116:119], v[0:3]
	v_mfma_f32_16x16x32_bf16 v[4:7], v[8:11], v[112:115], 0
	v_mfma_f32_16x16x32_bf16 v[120:123], v[8:11], v[96:99], 0
	v_mfma_f32_16x16x32_bf16 v[4:7], v[12:15], v[116:119], v[4:7]
	v_mfma_f32_16x16x32_bf16 v[180:183], v[12:15], v[104:107], v[120:123]
	v_mfma_f32_16x16x32_bf16 v[8:11], v[16:19], v[48:51], 0
	v_mfma_f32_16x16x32_bf16 v[12:15], v[20:23], v[56:59], v[8:11]
	v_mfma_f32_16x16x32_bf16 v[8:11], v[24:27], v[48:51], 0
	v_mfma_f32_16x16x32_bf16 v[184:187], v[28:31], v[56:59], v[8:11]
	v_mfma_f32_16x16x32_bf16 v[8:11], v[16:19], v[60:63], 0
	v_mfma_f32_16x16x32_bf16 v[188:191], v[20:23], v[88:91], v[8:11]
	v_mfma_f32_16x16x32_bf16 v[8:11], v[24:27], v[60:63], 0
	v_mfma_f32_16x16x32_bf16 v[192:195], v[28:31], v[88:91], v[8:11]
	v_mfma_f32_16x16x32_bf16 v[8:11], v[16:19], v[96:99], 0
	v_mfma_f32_16x16x32_bf16 v[196:199], v[20:23], v[104:107], v[8:11]
	v_mfma_f32_16x16x32_bf16 v[8:11], v[24:27], v[96:99], 0
	v_mfma_f32_16x16x32_bf16 v[200:203], v[28:31], v[104:107], v[8:11]
	v_mfma_f32_16x16x32_bf16 v[8:11], v[16:19], v[112:115], 0
	v_mfma_f32_16x16x32_bf16 v[204:207], v[20:23], v[116:119], v[8:11]
	v_mfma_f32_16x16x32_bf16 v[8:11], v[24:27], v[112:115], 0
	v_mfma_f32_16x16x32_bf16 v[208:211], v[28:31], v[116:119], v[8:11]
	s_barrier
	s_add_i32 s73, 0, 0x18000
	s_add_i32 s75, 0, 0x1c000
	v_add_u32_e32 v144, s73, v148
	v_add_u32_e32 v145, s75, v148
	s_nop 0
	ds_read_b128 v[8:11], v144
	ds_read_b128 v[20:23], v144 offset:1024
	ds_read_b128 v[28:31], v144 offset:2048
	ds_read_b128 v[212:215], v144 offset:3072
	ds_read_b128 v[216:219], v145
	ds_read_b128 v[220:223], v145 offset:1024
	ds_read_b128 v[224:227], v145 offset:2048
	ds_read_b128 v[228:231], v145 offset:3072
	s_add_u32 s46, s44, 0x80100
	s_addc_u32 s47, s45, 0
	s_mov_b32 m0, s53
	v_lshl_add_u64 v[48:49], s[46:47], 0, v[134:135]
	ds_read_b128 v[16:19], v151 offset:32768
	ds_read_b128 v[24:27], v151 offset:33792
	ds_read_b128 v[60:63], v151 offset:34816
	ds_read_b128 v[232:235], v151 offset:35840
	ds_read_b128 v[236:239], v151 offset:36864
	ds_read_b128 v[240:243], v151 offset:37888
	ds_read_b128 v[244:247], v151 offset:38912
	ds_read_b128 v[248:251], v151 offset:39936
	global_load_lds_dwordx4 v134, s[46:47]
	v_lshl_add_u64 v[48:49], s[46:47], 0, v[132:133]
	s_mov_b32 m0, s54
	s_nop 0
	global_load_lds_dwordx4 v132, s[46:47]
	s_waitcnt vmcnt(8) lgkmcnt(0)
	s_barrier
	v_mfma_f32_16x16x32_bf16 v[48:51], v[8:11], v[16:19], v[64:67]
	v_mfma_f32_16x16x32_bf16 v[120:123], v[20:23], v[24:27], v[48:51]
	v_mfma_f32_16x16x32_bf16 v[48:51], v[28:31], v[16:19], v[68:71]
	v_mfma_f32_16x16x32_bf16 v[112:115], v[212:215], v[24:27], v[48:51]
	v_mfma_f32_16x16x32_bf16 v[48:51], v[8:11], v[60:63], v[72:75]
	v_mfma_f32_16x16x32_bf16 v[104:107], v[20:23], v[232:235], v[48:51]
	v_mfma_f32_16x16x32_bf16 v[48:51], v[28:31], v[60:63], v[76:79]
	v_mfma_f32_16x16x32_bf16 v[96:99], v[212:215], v[232:235], v[48:51]
	v_mfma_f32_16x16x32_bf16 v[48:51], v[8:11], v[236:239], v[80:83]
	v_mfma_f32_16x16x32_bf16 v[88:91], v[20:23], v[240:243], v[48:51]
	v_mfma_f32_16x16x32_bf16 v[48:51], v[28:31], v[236:239], v[84:87]
	v_mfma_f32_16x16x32_bf16 v[80:83], v[212:215], v[240:243], v[48:51]
	v_mfma_f32_16x16x32_bf16 v[48:51], v[8:11], v[244:247], v[92:95]
	v_mfma_f32_16x16x32_bf16 v[56:59], v[20:23], v[248:251], v[48:51]
	v_mfma_f32_16x16x32_bf16 v[48:51], v[28:31], v[244:247], v[100:103]
	v_mfma_f32_16x16x32_bf16 v[48:51], v[212:215], v[248:251], v[48:51]
	v_mfma_f32_16x16x32_bf16 v[64:67], v[216:219], v[16:19], v[108:111]
	v_mfma_f32_16x16x32_bf16 v[16:19], v[224:227], v[16:19], v[32:35]
	v_mfma_f32_16x16x32_bf16 v[116:119], v[228:231], v[24:27], v[16:19]
	v_mfma_f32_16x16x32_bf16 v[16:19], v[216:219], v[60:63], v[36:39]
	v_mfma_f32_16x16x32_bf16 v[108:111], v[220:223], v[232:235], v[16:19]
	v_mfma_f32_16x16x32_bf16 v[16:19], v[224:227], v[60:63], v[40:43]
	v_mfma_f32_16x16x32_bf16 v[100:103], v[228:231], v[232:235], v[16:19]
	v_mfma_f32_16x16x32_bf16 v[16:19], v[216:219], v[236:239], v[44:47]
	v_mfma_f32_16x16x32_bf16 v[92:95], v[220:223], v[240:243], v[16:19]
	v_mfma_f32_16x16x32_bf16 v[16:19], v[224:227], v[236:239], v[52:55]
	v_mfma_f32_16x16x32_bf16 v[84:87], v[228:231], v[240:243], v[16:19]
	v_mfma_f32_16x16x32_bf16 v[16:19], v[216:219], v[244:247], v[152:155]
	v_mfma_f32_16x16x32_bf16 v[60:63], v[220:223], v[248:251], v[16:19]
	v_mfma_f32_16x16x32_bf16 v[16:19], v[224:227], v[244:247], v[156:159]
	v_mfma_f32_16x16x32_bf16 v[124:127], v[220:223], v[24:27], v[64:67]
	v_mfma_f32_16x16x32_bf16 v[52:55], v[228:231], v[248:251], v[16:19]
	s_barrier
	s_add_i32 s73, s73, s49
	s_add_i32 s74, s73, 0x2000
	s_nop 1
	v_lshl_add_u64 v[16:17], v[146:147], 0, s[16:17]
	s_mov_b32 m0, s73
	s_add_u32 s46, s42, 0x80180
	ds_read_b128 v[36:39], v151 offset:49152
	ds_read_b128 v[44:47], v151 offset:50176
	ds_read_b128 v[152:155], v151 offset:51200
	ds_read_b128 v[156:159], v151 offset:52224
	ds_read_b128 v[232:235], v151 offset:53248
	ds_read_b128 v[236:239], v151 offset:54272
	ds_read_b128 v[240:243], v151 offset:55296
	ds_read_b128 v[244:247], v151 offset:56320
	global_load_lds_dwordx4 v[16:17], off
	v_lshl_add_u64 v[16:17], v[252:253], 0, s[16:17]
	s_mov_b32 m0, s74
	s_addc_u32 s47, s43, 0
	s_add_i32 s75, s75, s49
	global_load_lds_dwordx4 v[16:17], off
	v_lshl_add_u64 v[16:17], s[46:47], 0, v[128:129]
	s_mov_b32 m0, s75
	s_add_i32 s76, s75, 0x2000
	global_load_lds_dwordx4 v128, s[46:47]
	v_lshl_add_u64 v[16:17], s[46:47], 0, v[130:131]
	s_mov_b32 m0, s76
	s_nop 0
	global_load_lds_dwordx4 v130, s[46:47]
	v_lshl_add_u64 v[16:17], v[140:141], 0, s[16:17]
	s_mov_b32 m0, s59
	s_nop 0
	global_load_lds_dwordx4 v[16:17], off
	v_lshl_add_u64 v[16:17], v[142:143], 0, s[16:17]
	s_mov_b32 m0, s60
	s_nop 0
	global_load_lds_dwordx4 v[16:17], off
	s_waitcnt vmcnt(8) lgkmcnt(0)
	s_barrier
	v_mfma_f32_16x16x32_bf16 v[16:19], v[8:11], v[36:39], v[160:163]
	v_mfma_f32_16x16x32_bf16 v[72:75], v[20:23], v[44:47], v[16:19]
	v_mfma_f32_16x16x32_bf16 v[16:19], v[28:31], v[36:39], v[164:167]
	v_mfma_f32_16x16x32_bf16 v[64:67], v[212:215], v[44:47], v[16:19]
	v_mfma_f32_16x16x32_bf16 v[16:19], v[8:11], v[152:155], v[168:171]
	v_mfma_f32_16x16x32_bf16 v[40:43], v[20:23], v[156:159], v[16:19]
	v_mfma_f32_16x16x32_bf16 v[16:19], v[28:31], v[152:155], v[172:175]
	v_mfma_f32_16x16x32_bf16 v[32:35], v[212:215], v[156:159], v[16:19]
	v_mfma_f32_16x16x32_bf16 v[16:19], v[8:11], v[232:235], v[176:179]
	v_mfma_f32_16x16x32_bf16 v[0:3], v[8:11], v[240:243], v[0:3]
	v_mfma_f32_16x16x32_bf16 v[24:27], v[20:23], v[236:239], v[16:19]
	v_mfma_f32_16x16x32_bf16 v[16:19], v[28:31], v[232:235], v[180:183]
	v_mfma_f32_16x16x32_bf16 v[8:11], v[20:23], v[244:247], v[0:3]
	v_mfma_f32_16x16x32_bf16 v[0:3], v[28:31], v[240:243], v[4:7]
	v_mfma_f32_16x16x32_bf16 v[16:19], v[212:215], v[236:239], v[16:19]
	v_mfma_f32_16x16x32_bf16 v[0:3], v[212:215], v[244:247], v[0:3]
	v_mfma_f32_16x16x32_bf16 v[4:7], v[216:219], v[36:39], v[12:15]
	v_mfma_f32_16x16x32_bf16 v[76:79], v[220:223], v[44:47], v[4:7]
	v_mfma_f32_16x16x32_bf16 v[4:7], v[224:227], v[36:39], v[184:187]
	v_mfma_f32_16x16x32_bf16 v[68:71], v[228:231], v[44:47], v[4:7]
	v_mfma_f32_16x16x32_bf16 v[4:7], v[216:219], v[152:155], v[188:191]
	v_mfma_f32_16x16x32_bf16 v[44:47], v[220:223], v[156:159], v[4:7]
	v_mfma_f32_16x16x32_bf16 v[4:7], v[224:227], v[152:155], v[192:195]
	v_mfma_f32_16x16x32_bf16 v[36:39], v[228:231], v[156:159], v[4:7]
	v_mfma_f32_16x16x32_bf16 v[4:7], v[216:219], v[232:235], v[196:199]
	v_mfma_f32_16x16x32_bf16 v[28:31], v[220:223], v[236:239], v[4:7]
	v_mfma_f32_16x16x32_bf16 v[4:7], v[224:227], v[232:235], v[200:203]
	v_mfma_f32_16x16x32_bf16 v[20:23], v[228:231], v[236:239], v[4:7]
	v_mfma_f32_16x16x32_bf16 v[4:7], v[216:219], v[240:243], v[204:207]
	v_mfma_f32_16x16x32_bf16 v[12:15], v[220:223], v[244:247], v[4:7]
	v_mfma_f32_16x16x32_bf16 v[4:7], v[224:227], v[240:243], v[208:211]
	v_mfma_f32_16x16x32_bf16 v[4:7], v[228:231], v[244:247], v[4:7]
	s_barrier
	s_add_u32 s77, s42, 0x200
	s_addc_u32 s78, s43, 0
	s_add_u32 s42, s44, 0x80180
	s_addc_u32 s43, s45, 0
	s_mov_b32 s79, 0
; template <class Epi, class Sched, bool ALIGN_EPI = false, bool SP2 = false, bool A_TILED = false>
; __device__ __forceinline__ void gemm_phase(PG8_LAS unsigned char* lds, const Gemm g, const Sched& S, const Epi& E, const int wave_s) {
;     ...
;         for (int t = PEEL ? 2 : 0; t < nt; t += 2) {
;             const bool last = (t == nt - 2);
;             const char* a1 = cA + (size_t)(t + 1) * kstepA;
;             const char* a2 = last ? nA : cA + (size_t)(t + 2) * kstepA; const char* b2 = last ? nB : cB + (size_t)(t + 2) * kstep;
;             const char* a3 = a2 + kstepA; const char* b3 = b2 + kstep;
;             if (last && has_next) S.a_ready(nxt);
.LBB0_3342:
	ds_read_b128 v[152:155], v149
	ds_read_b128 v[156:159], v149 offset:1024
	ds_read_b128 v[160:163], v149 offset:2048
	ds_read_b128 v[164:167], v149 offset:3072
	ds_read_b128 v[168:171], v150
	ds_read_b128 v[172:175], v150 offset:1024
	ds_read_b128 v[176:179], v150 offset:2048
	ds_read_b128 v[180:183], v150 offset:3072
	s_add_u32 s44, s42, 0xfff80080
	s_addc_u32 s45, s43, -1
	s_cmp_eq_u32 s79, 28
	s_cselect_b32 s47, s25, s45
	s_cselect_b32 s46, s67, s44
	s_cselect_b32 s45, s23, s78
	s_cselect_b32 s44, s68, s77
	s_mov_b32 m0, s64
	v_lshl_add_u64 v[140:141], s[42:43], 0, v[138:139]
	ds_read_b128 v[184:187], v151
	ds_read_b128 v[188:191], v151 offset:1024
	ds_read_b128 v[192:195], v151 offset:2048
	ds_read_b128 v[196:199], v151 offset:3072
	ds_read_b128 v[200:203], v151 offset:4096
	ds_read_b128 v[204:207], v151 offset:5120
	ds_read_b128 v[208:211], v151 offset:6144
	ds_read_b128 v[212:215], v151 offset:7168
	global_load_lds_dwordx4 v138, s[42:43]
	v_lshl_add_u64 v[140:141], s[42:43], 0, v[136:137]
	s_mov_b32 m0, s65
	s_nop 0
	global_load_lds_dwordx4 v136, s[42:43]
	s_waitcnt vmcnt(8) lgkmcnt(0)
	s_barrier
	v_mfma_f32_16x16x32_bf16 v[120:123], v[152:155], v[184:187], v[120:123]
	v_mfma_f32_16x16x32_bf16 v[112:115], v[160:163], v[184:187], v[112:115]
	v_mfma_f32_16x16x32_bf16 v[104:107], v[152:155], v[192:195], v[104:107]
	v_mfma_f32_16x16x32_bf16 v[96:99], v[160:163], v[192:195], v[96:99]
	v_mfma_f32_16x16x32_bf16 v[88:91], v[152:155], v[200:203], v[88:91]
	v_mfma_f32_16x16x32_bf16 v[80:83], v[160:163], v[200:203], v[80:83]
	v_mfma_f32_16x16x32_bf16 v[56:59], v[152:155], v[208:211], v[56:59]
	v_mfma_f32_16x16x32_bf16 v[48:51], v[160:163], v[208:211], v[48:51]
	v_mfma_f32_16x16x32_bf16 v[120:123], v[156:159], v[188:191], v[120:123]
	v_mfma_f32_16x16x32_bf16 v[112:115], v[164:167], v[188:191], v[112:115]
	v_mfma_f32_16x16x32_bf16 v[104:107], v[156:159], v[196:199], v[104:107]
	v_mfma_f32_16x16x32_bf16 v[96:99], v[164:167], v[196:199], v[96:99]
	v_mfma_f32_16x16x32_bf16 v[88:91], v[156:159], v[204:207], v[88:91]
	v_mfma_f32_16x16x32_bf16 v[80:83], v[164:167], v[204:207], v[80:83]
	v_mfma_f32_16x16x32_bf16 v[56:59], v[156:159], v[212:215], v[56:59]
	v_mfma_f32_16x16x32_bf16 v[48:51], v[164:167], v[212:215], v[48:51]
	v_mfma_f32_16x16x32_bf16 v[124:127], v[168:171], v[184:187], v[124:127]
	v_mfma_f32_16x16x32_bf16 v[116:119], v[176:179], v[184:187], v[116:119]
	v_mfma_f32_16x16x32_bf16 v[108:111], v[168:171], v[192:195], v[108:111]
	v_mfma_f32_16x16x32_bf16 v[100:103], v[176:179], v[192:195], v[100:103]
	v_mfma_f32_16x16x32_bf16 v[92:95], v[168:171], v[200:203], v[92:95]
	v_mfma_f32_16x16x32_bf16 v[84:87], v[176:179], v[200:203], v[84:87]
	v_mfma_f32_16x16x32_bf16 v[60:63], v[168:171], v[208:211], v[60:63]
	v_mfma_f32_16x16x32_bf16 v[52:55], v[176:179], v[208:211], v[52:55]
	v_mfma_f32_16x16x32_bf16 v[124:127], v[172:175], v[188:191], v[124:127]
	v_mfma_f32_16x16x32_bf16 v[116:119], v[180:183], v[188:191], v[116:119]
	v_mfma_f32_16x16x32_bf16 v[108:111], v[172:175], v[196:199], v[108:111]
	v_mfma_f32_16x16x32_bf16 v[100:103], v[180:183], v[196:199], v[100:103]
	v_mfma_f32_16x16x32_bf16 v[92:95], v[172:175], v[204:207], v[92:95]
	v_mfma_f32_16x16x32_bf16 v[84:87], v[180:183], v[204:207], v[84:87]
	v_mfma_f32_16x16x32_bf16 v[60:63], v[172:175], v[212:215], v[60:63]
	v_mfma_f32_16x16x32_bf16 v[52:55], v[180:183], v[212:215], v[52:55]
	s_barrier
	s_mov_b32 m0, s69
	v_lshl_add_u64 v[140:141], s[44:45], 0, v[128:129]
	s_add_u32 s80, s44, 0x80000
	ds_read_b128 v[184:187], v151 offset:16384
	ds_read_b128 v[188:191], v151 offset:17408
	ds_read_b128 v[192:195], v151 offset:18432
	ds_read_b128 v[196:199], v151 offset:19456
	ds_read_b128 v[200:203], v151 offset:20480
	ds_read_b128 v[204:207], v151 offset:21504
	ds_read_b128 v[208:211], v151 offset:22528
	ds_read_b128 v[212:215], v151 offset:23552
	global_load_lds_dwordx4 v128, s[44:45]
	v_lshl_add_u64 v[142:143], s[44:45], 0, v[130:131]
	s_mov_b32 m0, s70
	s_addc_u32 s81, s45, 0
	global_load_lds_dwordx4 v130, s[44:45]
	v_lshl_add_u64 v[146:147], s[80:81], 0, v[128:129]
	s_mov_b32 m0, s71
	v_lshl_add_u64 v[216:217], s[46:47], 0, v[132:133]
	global_load_lds_dwordx4 v128, s[80:81]
	v_lshl_add_u64 v[146:147], s[80:81], 0, v[130:131]
	s_mov_b32 m0, s72
	s_nop 0
	global_load_lds_dwordx4 v130, s[80:81]
	v_lshl_add_u64 v[146:147], s[46:47], 0, v[134:135]
	s_mov_b32 m0, s41
	s_nop 0
	global_load_lds_dwordx4 v134, s[46:47]
	s_mov_b32 m0, s52
	s_nop 0
	global_load_lds_dwordx4 v132, s[46:47]
	s_waitcnt vmcnt(8) lgkmcnt(0)
	s_barrier
	v_mfma_f32_16x16x32_bf16 v[72:75], v[152:155], v[184:187], v[72:75]
	v_mfma_f32_16x16x32_bf16 v[64:67], v[160:163], v[184:187], v[64:67]
	v_mfma_f32_16x16x32_bf16 v[40:43], v[152:155], v[192:195], v[40:43]
	v_mfma_f32_16x16x32_bf16 v[32:35], v[160:163], v[192:195], v[32:35]
	v_mfma_f32_16x16x32_bf16 v[24:27], v[152:155], v[200:203], v[24:27]
	v_mfma_f32_16x16x32_bf16 v[16:19], v[160:163], v[200:203], v[16:19]
	v_mfma_f32_16x16x32_bf16 v[8:11], v[152:155], v[208:211], v[8:11]
	v_mfma_f32_16x16x32_bf16 v[0:3], v[160:163], v[208:211], v[0:3]
	v_mfma_f32_16x16x32_bf16 v[72:75], v[156:159], v[188:191], v[72:75]
	v_mfma_f32_16x16x32_bf16 v[64:67], v[164:167], v[188:191], v[64:67]
	v_mfma_f32_16x16x32_bf16 v[40:43], v[156:159], v[196:199], v[40:43]
	v_mfma_f32_16x16x32_bf16 v[32:35], v[164:167], v[196:199], v[32:35]
	v_mfma_f32_16x16x32_bf16 v[24:27], v[156:159], v[204:207], v[24:27]
	v_mfma_f32_16x16x32_bf16 v[16:19], v[164:167], v[204:207], v[16:19]
	v_mfma_f32_16x16x32_bf16 v[8:11], v[156:159], v[212:215], v[8:11]
	v_mfma_f32_16x16x32_bf16 v[0:3], v[164:167], v[212:215], v[0:3]
	v_mfma_f32_16x16x32_bf16 v[76:79], v[168:171], v[184:187], v[76:79]
	v_mfma_f32_16x16x32_bf16 v[68:71], v[176:179], v[184:187], v[68:71]
	v_mfma_f32_16x16x32_bf16 v[44:47], v[168:171], v[192:195], v[44:47]
	v_mfma_f32_16x16x32_bf16 v[36:39], v[176:179], v[192:195], v[36:39]
	v_mfma_f32_16x16x32_bf16 v[28:31], v[168:171], v[200:203], v[28:31]
	v_mfma_f32_16x16x32_bf16 v[20:23], v[176:179], v[200:203], v[20:23]
	v_mfma_f32_16x16x32_bf16 v[12:15], v[168:171], v[208:211], v[12:15]
	v_mfma_f32_16x16x32_bf16 v[4:7], v[176:179], v[208:211], v[4:7]
	v_mfma_f32_16x16x32_bf16 v[76:79], v[172:175], v[188:191], v[76:79]
	v_mfma_f32_16x16x32_bf16 v[68:71], v[180:183], v[188:191], v[68:71]
	v_mfma_f32_16x16x32_bf16 v[44:47], v[172:175], v[196:199], v[44:47]
	v_mfma_f32_16x16x32_bf16 v[36:39], v[180:183], v[196:199], v[36:39]
	v_mfma_f32_16x16x32_bf16 v[28:31], v[172:175], v[204:207], v[28:31]
	v_mfma_f32_16x16x32_bf16 v[20:23], v[180:183], v[204:207], v[20:23]
	v_mfma_f32_16x16x32_bf16 v[12:15], v[172:175], v[212:215], v[12:15]
	v_mfma_f32_16x16x32_bf16 v[4:7], v[180:183], v[212:215], v[4:7]
	s_barrier
	ds_read_b128 v[152:155], v144
	ds_read_b128 v[156:159], v144 offset:1024
	ds_read_b128 v[160:163], v144 offset:2048
	ds_read_b128 v[164:167], v144 offset:3072
	ds_read_b128 v[168:171], v145
	ds_read_b128 v[172:175], v145 offset:1024
	ds_read_b128 v[176:179], v145 offset:2048
	ds_read_b128 v[180:183], v145 offset:3072
	s_add_u32 s46, s46, 0x80000
	s_addc_u32 s47, s47, 0
	s_mov_b32 m0, s53
	v_lshl_add_u64 v[218:219], s[46:47], 0, v[134:135]
	ds_read_b128 v[184:187], v151 offset:32768
	ds_read_b128 v[188:191], v151 offset:33792
	ds_read_b128 v[192:195], v151 offset:34816
	ds_read_b128 v[196:199], v151 offset:35840
	ds_read_b128 v[200:203], v151 offset:36864
	ds_read_b128 v[204:207], v151 offset:37888
	ds_read_b128 v[208:211], v151 offset:38912
	ds_read_b128 v[212:215], v151 offset:39936
	global_load_lds_dwordx4 v134, s[46:47]
	v_lshl_add_u64 v[218:219], s[46:47], 0, v[132:133]
	s_mov_b32 m0, s54
	s_nop 0
	global_load_lds_dwordx4 v132, s[46:47]
	s_waitcnt vmcnt(8) lgkmcnt(0)
	s_barrier
	v_mfma_f32_16x16x32_bf16 v[120:123], v[152:155], v[184:187], v[120:123]
	v_mfma_f32_16x16x32_bf16 v[112:115], v[160:163], v[184:187], v[112:115]
	v_mfma_f32_16x16x32_bf16 v[104:107], v[152:155], v[192:195], v[104:107]
	v_mfma_f32_16x16x32_bf16 v[96:99], v[160:163], v[192:195], v[96:99]
	v_mfma_f32_16x16x32_bf16 v[88:91], v[152:155], v[200:203], v[88:91]
	v_mfma_f32_16x16x32_bf16 v[80:83], v[160:163], v[200:203], v[80:83]
	v_mfma_f32_16x16x32_bf16 v[56:59], v[152:155], v[208:211], v[56:59]
	v_mfma_f32_16x16x32_bf16 v[48:51], v[160:163], v[208:211], v[48:51]
	v_mfma_f32_16x16x32_bf16 v[120:123], v[156:159], v[188:191], v[120:123]
	v_mfma_f32_16x16x32_bf16 v[112:115], v[164:167], v[188:191], v[112:115]
	v_mfma_f32_16x16x32_bf16 v[104:107], v[156:159], v[196:199], v[104:107]
	v_mfma_f32_16x16x32_bf16 v[96:99], v[164:167], v[196:199], v[96:99]
	v_mfma_f32_16x16x32_bf16 v[88:91], v[156:159], v[204:207], v[88:91]
	v_mfma_f32_16x16x32_bf16 v[80:83], v[164:167], v[204:207], v[80:83]
	v_mfma_f32_16x16x32_bf16 v[56:59], v[156:159], v[212:215], v[56:59]
	v_mfma_f32_16x16x32_bf16 v[48:51], v[164:167], v[212:215], v[48:51]
	v_mfma_f32_16x16x32_bf16 v[124:127], v[168:171], v[184:187], v[124:127]
	v_mfma_f32_16x16x32_bf16 v[116:119], v[176:179], v[184:187], v[116:119]
	v_mfma_f32_16x16x32_bf16 v[108:111], v[168:171], v[192:195], v[108:111]
	v_mfma_f32_16x16x32_bf16 v[100:103], v[176:179], v[192:195], v[100:103]
	v_mfma_f32_16x16x32_bf16 v[92:95], v[168:171], v[200:203], v[92:95]
	v_mfma_f32_16x16x32_bf16 v[84:87], v[176:179], v[200:203], v[84:87]
	v_mfma_f32_16x16x32_bf16 v[60:63], v[168:171], v[208:211], v[60:63]
	v_mfma_f32_16x16x32_bf16 v[52:55], v[176:179], v[208:211], v[52:55]
	v_mfma_f32_16x16x32_bf16 v[124:127], v[172:175], v[188:191], v[124:127]
	v_mfma_f32_16x16x32_bf16 v[116:119], v[180:183], v[188:191], v[116:119]
	v_mfma_f32_16x16x32_bf16 v[108:111], v[172:175], v[196:199], v[108:111]
	v_mfma_f32_16x16x32_bf16 v[100:103], v[180:183], v[196:199], v[100:103]
	v_mfma_f32_16x16x32_bf16 v[92:95], v[172:175], v[204:207], v[92:95]
	v_mfma_f32_16x16x32_bf16 v[84:87], v[180:183], v[204:207], v[84:87]
	v_mfma_f32_16x16x32_bf16 v[60:63], v[172:175], v[212:215], v[60:63]
	v_mfma_f32_16x16x32_bf16 v[52:55], v[180:183], v[212:215], v[52:55]
	s_barrier
; template <class Epi, class Sched, bool ALIGN_EPI = false, bool SP2 = false, bool A_TILED = false>
; __device__ __forceinline__ void gemm_phase(PG8_LAS unsigned char* lds, const Gemm g, const Sched& S, const Epi& E, const int wave_s) {
;     ...
;         for (int t = PEEL ? 2 : 0; t < nt; t += 2) {
;             const bool last = (t == nt - 2);
;             const char* a1 = cA + (size_t)(t + 1) * kstepA;
	s_mov_b32 m0, s73
	v_lshl_add_u64 v[140:141], v[140:141], 0, s[12:13]
	s_add_u32 s44, s44, 0x80080
	ds_read_b128 v[184:187], v151 offset:49152
	ds_read_b128 v[188:191], v151 offset:50176
	ds_read_b128 v[192:195], v151 offset:51200
	ds_read_b128 v[196:199], v151 offset:52224
	ds_read_b128 v[200:203], v151 offset:53248
	ds_read_b128 v[204:207], v151 offset:54272
	ds_read_b128 v[208:211], v151 offset:55296
	ds_read_b128 v[212:215], v151 offset:56320
	global_load_lds_dwordx4 v[140:141], off
	v_lshl_add_u64 v[140:141], v[142:143], 0, s[12:13]
	s_mov_b32 m0, s74
	s_addc_u32 s45, s45, 0
	global_load_lds_dwordx4 v[140:141], off
	v_lshl_add_u64 v[140:141], s[44:45], 0, v[128:129]
	s_mov_b32 m0, s75
	s_nop 0
	global_load_lds_dwordx4 v128, s[44:45]
	v_lshl_add_u64 v[140:141], s[44:45], 0, v[130:131]
	s_mov_b32 m0, s76
	s_nop 0
	global_load_lds_dwordx4 v130, s[44:45]
	v_lshl_add_u64 v[140:141], v[146:147], 0, s[12:13]
	s_mov_b32 m0, s59
	s_nop 0
	global_load_lds_dwordx4 v[140:141], off
	v_lshl_add_u64 v[140:141], v[216:217], 0, s[12:13]
	s_mov_b32 m0, s60
	s_nop 0
	global_load_lds_dwordx4 v[140:141], off
	s_waitcnt vmcnt(8) lgkmcnt(0)
	s_barrier
	v_mfma_f32_16x16x32_bf16 v[72:75], v[152:155], v[184:187], v[72:75]
	v_mfma_f32_16x16x32_bf16 v[64:67], v[160:163], v[184:187], v[64:67]
	v_mfma_f32_16x16x32_bf16 v[40:43], v[152:155], v[192:195], v[40:43]
	v_mfma_f32_16x16x32_bf16 v[32:35], v[160:163], v[192:195], v[32:35]
	v_mfma_f32_16x16x32_bf16 v[24:27], v[152:155], v[200:203], v[24:27]
	v_mfma_f32_16x16x32_bf16 v[16:19], v[160:163], v[200:203], v[16:19]
	v_mfma_f32_16x16x32_bf16 v[8:11], v[152:155], v[208:211], v[8:11]
	v_mfma_f32_16x16x32_bf16 v[0:3], v[160:163], v[208:211], v[0:3]
	v_mfma_f32_16x16x32_bf16 v[72:75], v[156:159], v[188:191], v[72:75]
	v_mfma_f32_16x16x32_bf16 v[64:67], v[164:167], v[188:191], v[64:67]
	v_mfma_f32_16x16x32_bf16 v[40:43], v[156:159], v[196:199], v[40:43]
	v_mfma_f32_16x16x32_bf16 v[32:35], v[164:167], v[196:199], v[32:35]
	v_mfma_f32_16x16x32_bf16 v[24:27], v[156:159], v[204:207], v[24:27]
	v_mfma_f32_16x16x32_bf16 v[16:19], v[164:167], v[204:207], v[16:19]
	v_mfma_f32_16x16x32_bf16 v[8:11], v[156:159], v[212:215], v[8:11]
	v_mfma_f32_16x16x32_bf16 v[0:3], v[164:167], v[212:215], v[0:3]
	v_mfma_f32_16x16x32_bf16 v[76:79], v[168:171], v[184:187], v[76:79]
	v_mfma_f32_16x16x32_bf16 v[68:71], v[176:179], v[184:187], v[68:71]
	v_mfma_f32_16x16x32_bf16 v[44:47], v[168:171], v[192:195], v[44:47]
	v_mfma_f32_16x16x32_bf16 v[36:39], v[176:179], v[192:195], v[36:39]
	v_mfma_f32_16x16x32_bf16 v[28:31], v[168:171], v[200:203], v[28:31]
	v_mfma_f32_16x16x32_bf16 v[20:23], v[176:179], v[200:203], v[20:23]
	v_mfma_f32_16x16x32_bf16 v[12:15], v[168:171], v[208:211], v[12:15]
	v_mfma_f32_16x16x32_bf16 v[4:7], v[176:179], v[208:211], v[4:7]
	v_mfma_f32_16x16x32_bf16 v[76:79], v[172:175], v[188:191], v[76:79]
	v_mfma_f32_16x16x32_bf16 v[68:71], v[180:183], v[188:191], v[68:71]
	v_mfma_f32_16x16x32_bf16 v[44:47], v[172:175], v[196:199], v[44:47]
	v_mfma_f32_16x16x32_bf16 v[36:39], v[180:183], v[196:199], v[36:39]
	v_mfma_f32_16x16x32_bf16 v[28:31], v[172:175], v[204:207], v[28:31]
	v_mfma_f32_16x16x32_bf16 v[20:23], v[180:183], v[204:207], v[20:23]
	v_mfma_f32_16x16x32_bf16 v[12:15], v[172:175], v[212:215], v[12:15]
	v_mfma_f32_16x16x32_bf16 v[4:7], v[180:183], v[212:215], v[4:7]
	s_barrier
	s_add_i32 s79, s79, 2
	s_add_u32 s77, s77, 0x100
	s_addc_u32 s78, s78, 0
	s_add_u32 s42, s42, 0x100
	s_addc_u32 s43, s43, 0
	s_cmp_gt_u32 s79, 29
	s_cbranch_scc0 .LBB0_3342
	s_and_b64 vcc, exec, s[14:15]
	s_cbranch_vccz .LBB0_3345
	s_barrier

; __device__ __forceinline__ int tid_now(int wave_s) { unsigned z = 0u; asm volatile("" : "+v"(z)); return (wave_s << 6) | (int)__builtin_amdgcn_mbcnt_hi(~0u, __builtin_amdgcn_mbcnt_lo(~0u, z)); }
; __device__ __forceinline__ unsigned xb_add(unsigned* p, unsigned v) { return __hip_atomic_fetch_add(p, v, __ATOMIC_RELAXED, __HIP_MEMORY_SCOPE_AGENT); }
; __device__ __forceinline__ void xcd_barrier(const XcdBarrier& b) {
;     asm volatile("s_waitcnt vmcnt(0)" ::: "memory");
;     __syncthreads();
;     if (tid_now(b.w) == 0) {
;         unsigned* bar = b.bar;
;         __builtin_amdgcn_s_waitcnt(0);
;         unsigned nloc = b.st[0], nx = b.st[1];
;         if (nloc == 0u) { xcd_barrier_complete(bar, b.x, nloc, nx, b.np); b.st[0] = nloc; b.st[1] = nx; }
;         const unsigned old = xb_add(&bar[XB_XSUB(b.x)], 1u);
.LBB0_3349:
	s_setprio 0
	s_cmp_gt_i32 s35, 21
	s_cselect_b64 s[0:1], -1, 0
	s_and_b64 s[2:3], s[2:3], s[0:1]
	s_andn2_b64 vcc, exec, s[2:3]
	s_cbranch_vccnz .LBB0_3403
	v_mov_b32_e32 v0, 0
	s_waitcnt vmcnt(0)
	s_waitcnt vmcnt(0) lgkmcnt(0)
	s_barrier
	s_nop 0
	v_mbcnt_lo_u32_b32 v0, -1, v0
	v_mbcnt_hi_u32_b32 v0, -1, v0
	v_or_b32_e32 v0, s33, v0
	v_cmp_eq_u32_e32 vcc, 0, v0
	s_and_saveexec_b64 s[2:3], vcc
	s_cbranch_execz .LBB0_3402
	s_add_i32 s4, 0, 0x27f68
	v_mov_b32_e32 v0, s4
	s_waitcnt vmcnt(0) expcnt(0) lgkmcnt(0)
	ds_read_b32 v2, v0
	s_add_i32 s4, 0, 0x27f6c
	v_mov_b32_e32 v0, s4
	ds_read_b32 v0, v0
	s_waitcnt lgkmcnt(1)
	v_cmp_ne_u32_e32 vcc, 0, v2
	s_cbranch_vccnz .LBB0_3366
	s_add_u32 s4, s10, 0x1000
	s_addc_u32 s5, s11, 0
	s_add_u32 s6, s10, 0x1100
	s_addc_u32 s7, s11, 0
	s_add_u32 s12, s10, 0x1200
	s_addc_u32 s13, s11, 0
	s_add_u32 s14, s10, 0x1300
	s_addc_u32 s15, s11, 0
	s_mov_b32 s8, 1
	v_mov_b32_e32 v16, 0
	s_branch .LBB0_3354

; __device__ __forceinline__ int tid_now(int wave_s) { unsigned z = 0u; asm volatile("" : "+v"(z)); return (wave_s << 6) | (int)__builtin_amdgcn_mbcnt_hi(~0u, __builtin_amdgcn_mbcnt_lo(~0u, z)); }
; __device__ __forceinline__ unsigned xb_add(unsigned* p, unsigned v) { return __hip_atomic_fetch_add(p, v, __ATOMIC_RELAXED, __HIP_MEMORY_SCOPE_AGENT); }
; __device__ __forceinline__ void xcd_barrier(const XcdBarrier& b) {
;     asm volatile("s_waitcnt vmcnt(0)" ::: "memory");
;     __syncthreads();
;     if (tid_now(b.w) == 0) {
;         unsigned* bar = b.bar;
;         __builtin_amdgcn_s_waitcnt(0);
;         unsigned nloc = b.st[0], nx = b.st[1];
;         if (nloc == 0u) { xcd_barrier_complete(bar, b.x, nloc, nx, b.np); b.st[0] = nloc; b.st[1] = nx; }
;         const unsigned old = xb_add(&bar[XB_XSUB(b.x)], 1u);
.LBB0_3542:
	s_setprio 0
	s_cmp_gt_i32 s35, 22
	s_cselect_b64 s[0:1], -1, 0
	s_and_b64 s[2:3], s[2:3], s[0:1]
	s_andn2_b64 vcc, exec, s[2:3]
	s_cbranch_vccnz .LBB0_3596
	s_waitcnt vmcnt(0)
	v_mov_b32_e32 v0, 0
	s_waitcnt vmcnt(0)
	s_waitcnt lgkmcnt(0)
	s_barrier
	s_nop 0
	v_mbcnt_lo_u32_b32 v0, -1, v0
	v_mbcnt_hi_u32_b32 v0, -1, v0
	v_or_b32_e32 v0, s33, v0
	v_cmp_eq_u32_e32 vcc, 0, v0
	s_and_saveexec_b64 s[2:3], vcc
	s_cbranch_execz .LBB0_3595
	s_add_i32 s4, 0, 0x27f68
	v_mov_b32_e32 v0, s4
	s_waitcnt vmcnt(0) expcnt(0) lgkmcnt(0)
	ds_read_b32 v2, v0
	s_add_i32 s4, 0, 0x27f6c
	v_mov_b32_e32 v0, s4
	ds_read_b32 v0, v0
	s_waitcnt lgkmcnt(1)
	v_cmp_ne_u32_e32 vcc, 0, v2
	s_cbranch_vccnz .LBB0_3559
	s_add_u32 s4, s10, 0x1000
	s_addc_u32 s5, s11, 0
	s_add_u32 s6, s10, 0x1100
	s_addc_u32 s7, s11, 0
	s_add_u32 s8, s10, 0x1200
	s_addc_u32 s9, s11, 0
	s_add_u32 s12, s10, 0x1300
	s_addc_u32 s13, s11, 0
	s_mov_b32 s22, 1
	v_mov_b32_e32 v16, 0
	s_branch .LBB0_3547

; #define PG8_STAGE(bufoff, gbase, voff) do { _Pragma("unroll") for (int _i = 0; _i < 2; ++_i) \
;         __builtin_amdgcn_global_load_lds((const unsigned*)((const char*)(gbase) + (voff)[_i]), (PG8_LAS unsigned*)(lds + (bufoff) + ldsw + _i * 8192), 16, 0, 0); } while (0)
; #define PG8_WAIT_V(n) asm volatile("s_waitcnt vmcnt(" #n ")" ::: "memory")
; #define PG8_BAR __builtin_amdgcn_s_barrier()
; template <class Epi, class Sched, bool ALIGN_EPI = false, bool SP2 = false, bool A_TILED = false>
; __device__ __forceinline__ void gemm_phase(PG8_LAS unsigned char* lds, const Gemm g, const Sched& S, const Epi& E, const int wave_s) {
;     ...
;         PG8_STAGE(PG8_SB(0, 0), cB, voffB); PG8_STAGE(PG8_SB(0, 1), cB + hstep, voffB); PG8_STAGE(PG8_SA(0, 0), cA, voffA); PG8_STAGE(PG8_SA(0, 1), cA + hstepA, voffA);
;         if (wr == 1) PG8_BAR;
;         PG8_WAIT_V(2); PG8_BAR;
;         PG8_STAGE(PG8_SB(1, 0), cB + kstep, voffB); PG8_STAGE(PG8_SA(1, 0), cA + kstepA, voffA); PG8_STAGE(PG8_SB(1, 1), cB + hstep + kstep, voffB);
;         PG8_WAIT_V(6); PG8_BAR;
;     } else {
;         PG8_STAGE(PG8_SB(0, 0), cB, voffB); PG8_STAGE(PG8_SA(0, 0), cA, voffA); PG8_STAGE(PG8_SB(0, 1), cB + hstep, voffB); PG8_STAGE(PG8_SA(0, 1), cA + hstepA, voffA);
;         if (wr == 1) PG8_BAR;
;         PG8_WAIT_V(4); PG8_BAR;
;         PG8_STAGE(PG8_SB(1, 0), cB + kstep, voffB); PG8_STAGE(PG8_SA(1, 0), cA + kstepA, voffA); PG8_STAGE(PG8_SB(1, 1), cB + hstep + kstep, voffB);
;         PG8_WAIT_V(6); PG8_BAR;
;     }
;     for (;;) {
;         const bool has_next = Epi::AFTER_DRAIN ? false : S.next(ui + 1, nxt);
;         const char* nA = has_next ? (const char*)g.A + (size_t)nxt.pm * tstepA : cA; const char* nB = has_next ? (const char*)g.Bt + (size_t)nxt.pn * tstep : cB;
;         constexpr bool PEEL = SP2 && !Epi::AFTER_DRAIN;
;         if constexpr (PEEL) {
;             const char* a1 = cA + kstepA; const char* a2 = cA + 2 * kstepA; const char* b2 = cB + 2 * kstep; const char* a3 = a2 + kstepA; const char* b3 = b2 + kstep;
;             PG8_ITER(PG8_MMAZ)
;         } else {
; #pragma unroll
;             for (int a = 0; a < 2; ++a)
; #pragma unroll
;                 for (int b = 0; b < 2; ++b)
; #pragma unroll
;                     for (int m = 0; m < 4; ++m)
; #pragma unroll
;                         for (int n = 0; n < 2; ++n) acc[a][b][m][n] = (f32x4){0.f, 0.f, 0.f, 0.f};
.LBB0_3607:
	v_and_b32_e32 v15, 48, v8
	v_lshlrev_b32_e32 v16, 6, v8
	s_movk_i32 s15, 0x3c0
	v_lshlrev_b32_e32 v8, 2, v8
	s_and_b32 s26, s25, 3
	s_lshl_b32 s13, s14, 6
	s_lshl_b32 s14, s14, 13
	v_and_or_b32 v15, v16, s15, v15
	v_and_b32_e32 v8, 32, v8
	v_bitop3_b32 v16, v15, s14, v8 bitop3:0xde
	s_lshl_b32 s14, s26, 12
	v_bitop3_b32 v8, v15, s14, v8 bitop3:0xde
	s_mov_b64 s[14:15], 0x80
	s_add_i32 m0, s27, 0x18000
	v_lshl_add_u64 v[6:7], v[6:7], 0, s[14:15]
	s_waitcnt vmcnt(2)
	s_barrier
	global_load_lds_dwordx4 v[6:7], off
	v_lshl_add_u64 v[4:5], v[4:5], 0, s[14:15]
	s_add_i32 m0, s27, 0x1a000
	s_add_i32 s39, s27, 0x8000
	s_add_i32 s40, s27, 0xa000
	global_load_lds_dwordx4 v[4:5], off
	v_lshl_add_u64 v[2:3], v[2:3], 0, s[14:15]
	s_mov_b32 m0, s39
	s_add_u32 s42, s0, 0x80080
	global_load_lds_dwordx4 v[2:3], off
	v_lshl_add_u64 v[0:1], v[0:1], 0, s[14:15]
	s_mov_b32 m0, s40
	s_addc_u32 s43, s1, 0
	global_load_lds_dwordx4 v[0:1], off
	s_add_i32 m0, s27, 0x1c000
	v_lshl_add_u64 v[0:1], s[42:43], 0, v[34:35]
	global_load_lds_dwordx4 v34, s[42:43]
	v_lshl_add_u64 v[0:1], s[42:43], 0, v[134:135]
	s_add_i32 m0, s27, 0x1e000
	s_add_u32 s41, s20, 0x3a00100
	global_load_lds_dwordx4 v134, s[42:43]
	v_lshlrev_b32_e32 v0, 15, v12
	v_and_b32_e32 v0, 0xffff0000, v0
	v_lshl_add_u32 v0, v13, 12, v0
	v_and_b32_e32 v1, 1, v12
	v_lshl_or_b32 v0, v1, 6, v0
	v_lshl_add_u32 v0, v14, 1, v0
	v_mov_b32_e32 v1, v35
	s_addc_u32 s42, s21, 0
	v_lshl_add_u64 v[0:1], s[16:17], 0, v[0:1]
	s_mov_b64 s[20:21], 0x20680080
	v_lshl_add_u64 v[136:137], v[0:1], 0, s[20:21]
	v_lshlrev_b32_e32 v0, 15, v9
	v_and_b32_e32 v0, 0xffff0000, v0
	v_lshl_add_u32 v0, v10, 12, v0
	v_and_b32_e32 v1, 1, v9
	v_lshl_or_b32 v0, v1, 6, v0
	s_add_u32 s43, s16, 0x20600100
	s_waitcnt vmcnt(6)
	v_lshl_add_u32 v0, v11, 1, v0
	v_mov_b32_e32 v1, v35
	s_addc_u32 s44, s17, 0
	s_bitcmp1_b32 s33, 8
	s_cbranch_scc1 .Lsp_16
	s_setprio 1
.Lsp_16:
	s_add_i32 s48, 0, 0x10000
	s_add_i32 s50, 0, 0x14000
	s_add_i32 s52, 0, 0x18000
	s_add_i32 s54, 0, 0x1c000
	v_lshl_add_u64 v[0:1], s[16:17], 0, v[0:1]
	v_add_u32_e32 v140, s48, v8
	v_add_u32_e32 v141, s50, v8
	s_add_i32 s48, s48, s22
	s_add_i32 s50, s50, s22
	v_add_u32_e32 v143, s52, v8
	v_add_u32_e32 v144, s54, v8
	s_add_i32 s52, s52, s22
	s_add_i32 s54, s54, s22
	v_lshl_add_u64 v[138:139], v[0:1], 0, s[20:21]
	s_mov_b32 s45, -2
	v_add_u32_e32 v142, 0, v16
	s_add_i32 s46, s27, 0xc000
	s_add_i32 s47, s27, 0xe000
	s_add_i32 s49, s48, 0x2000
	s_add_i32 s51, s50, 0x2000
	s_add_i32 s53, s52, 0x2000
	s_add_i32 s55, s54, 0x2000
	s_mov_b64 s[16:17], 0x100
	v_mov_b32_e32 v0, v35
	v_mov_b32_e32 v1, v35
	v_mov_b32_e32 v2, v35
	v_mov_b32_e32 v3, v35
	v_mov_b32_e32 v4, v35
	v_mov_b32_e32 v5, v35
	v_mov_b32_e32 v6, v35
	v_mov_b32_e32 v7, v35
	v_mov_b32_e32 v40, v35
	v_mov_b32_e32 v41, v35
	v_mov_b32_e32 v42, v35
	v_mov_b32_e32 v43, v35
	v_mov_b32_e32 v44, v35
	v_mov_b32_e32 v45, v35
	v_mov_b32_e32 v46, v35
	v_mov_b32_e32 v47, v35
	v_mov_b32_e32 v88, v35
	v_mov_b32_e32 v89, v35
	v_mov_b32_e32 v90, v35
	v_mov_b32_e32 v91, v35
	v_mov_b32_e32 v92, v35
	v_mov_b32_e32 v93, v35
	v_mov_b32_e32 v94, v35
	v_mov_b32_e32 v95, v35
	v_mov_b32_e32 v112, v35
	v_mov_b32_e32 v113, v35
	v_mov_b32_e32 v114, v35
	v_mov_b32_e32 v115, v35
	v_mov_b32_e32 v124, v35
	v_mov_b32_e32 v125, v35
	v_mov_b32_e32 v126, v35
	v_mov_b32_e32 v127, v35
	v_mov_b32_e32 v28, v35
	v_mov_b32_e32 v29, v35
	v_mov_b32_e32 v30, v35
	v_mov_b32_e32 v31, v35
	v_mov_b32_e32 v36, v35
	v_mov_b32_e32 v37, v35
	v_mov_b32_e32 v38, v35
	v_mov_b32_e32 v39, v35
	v_mov_b32_e32 v80, v35
	v_mov_b32_e32 v81, v35
	v_mov_b32_e32 v82, v35
	v_mov_b32_e32 v83, v35
	v_mov_b32_e32 v84, v35
	v_mov_b32_e32 v85, v35
	v_mov_b32_e32 v86, v35
	v_mov_b32_e32 v87, v35
	v_mov_b32_e32 v120, v35
	v_mov_b32_e32 v121, v35
	v_mov_b32_e32 v122, v35
	v_mov_b32_e32 v123, v35
	v_mov_b32_e32 v116, v35
	v_mov_b32_e32 v117, v35
	v_mov_b32_e32 v118, v35
	v_mov_b32_e32 v119, v35
	v_mov_b32_e32 v104, v35
	v_mov_b32_e32 v105, v35
	v_mov_b32_e32 v106, v35
	v_mov_b32_e32 v107, v35
	v_mov_b32_e32 v100, v35
	v_mov_b32_e32 v101, v35
	v_mov_b32_e32 v102, v35
	v_mov_b32_e32 v103, v35
	v_mov_b32_e32 v96, v35
	v_mov_b32_e32 v97, v35
	v_mov_b32_e32 v98, v35
	v_mov_b32_e32 v99, v35
	v_mov_b32_e32 v108, v35
	v_mov_b32_e32 v109, v35
	v_mov_b32_e32 v110, v35
	v_mov_b32_e32 v111, v35
	v_mov_b32_e32 v64, v35
	v_mov_b32_e32 v65, v35
	v_mov_b32_e32 v66, v35
	v_mov_b32_e32 v67, v35
	v_mov_b32_e32 v72, v35
	v_mov_b32_e32 v73, v35
	v_mov_b32_e32 v74, v35
	v_mov_b32_e32 v75, v35
	v_mov_b32_e32 v48, v35
	v_mov_b32_e32 v49, v35
	v_mov_b32_e32 v50, v35
	v_mov_b32_e32 v51, v35
	v_mov_b32_e32 v56, v35
	v_mov_b32_e32 v57, v35
	v_mov_b32_e32 v58, v35
	v_mov_b32_e32 v59, v35
	v_mov_b32_e32 v16, v35
	v_mov_b32_e32 v17, v35
	v_mov_b32_e32 v18, v35
	v_mov_b32_e32 v19, v35
	v_mov_b32_e32 v24, v35
	v_mov_b32_e32 v25, v35
	v_mov_b32_e32 v26, v35
	v_mov_b32_e32 v27, v35
	v_mov_b32_e32 v68, v35
	v_mov_b32_e32 v69, v35
	v_mov_b32_e32 v70, v35
	v_mov_b32_e32 v71, v35
	v_mov_b32_e32 v128, v35
	v_mov_b32_e32 v129, v35
	v_mov_b32_e32 v130, v35
	v_mov_b32_e32 v131, v35
	v_mov_b32_e32 v52, v35
	v_mov_b32_e32 v53, v35
	v_mov_b32_e32 v54, v35
	v_mov_b32_e32 v55, v35
	v_mov_b32_e32 v76, v35
	v_mov_b32_e32 v77, v35
	v_mov_b32_e32 v78, v35
	v_mov_b32_e32 v79, v35
	v_mov_b32_e32 v20, v35
	v_mov_b32_e32 v21, v35
	v_mov_b32_e32 v22, v35
	v_mov_b32_e32 v23, v35
	v_mov_b32_e32 v60, v35
	v_mov_b32_e32 v61, v35
	v_mov_b32_e32 v62, v35
	v_mov_b32_e32 v63, v35
	v_mov_b32_e32 v12, v35
	v_mov_b32_e32 v13, v35
	v_mov_b32_e32 v14, v35
	v_mov_b32_e32 v15, v35
	v_mov_b32_e32 v8, v35
	v_mov_b32_e32 v9, v35
	v_mov_b32_e32 v10, v35
	v_mov_b32_e32 v11, v35
	s_barrier
; template <class Epi, class Sched, bool ALIGN_EPI = false, bool SP2 = false, bool A_TILED = false>
; __device__ __forceinline__ void gemm_phase(PG8_LAS unsigned char* lds, const Gemm g, const Sched& S, const Epi& E, const int wave_s) {
;     ...
;         for (int t = PEEL ? 2 : 0; t < nt; t += 2) {
;             const bool last = (t == nt - 2);
;             const char* a1 = cA + (size_t)(t + 1) * kstepA;
;             const char* a2 = last ? nA : cA + (size_t)(t + 2) * kstepA; const char* b2 = last ? nB : cB + (size_t)(t + 2) * kstep;
;             const char* a3 = a2 + kstepA; const char* b3 = b2 + kstep;
;             if (last && has_next) S.a_ready(nxt);
.LBB0_3608:
	ds_read_b128 v[146:149], v140
	ds_read_b128 v[150:153], v140 offset:1024
	ds_read_b128 v[154:157], v140 offset:2048
	ds_read_b128 v[158:161], v140 offset:3072
	ds_read_b128 v[162:165], v141
	ds_read_b128 v[166:169], v141 offset:1024
	ds_read_b128 v[170:173], v141 offset:2048
	ds_read_b128 v[174:177], v141 offset:3072
	s_add_u32 s20, s8, s43
	s_addc_u32 s21, s9, s44
	s_add_u32 s56, s8, s41
	s_addc_u32 s57, s9, s42
	s_cmp_eq_u32 s45, 28
	s_cselect_b32 s23, s5, s21
	s_cselect_b32 s22, s4, s20
	s_cselect_b32 s21, s1, s57
	s_cselect_b32 s20, s0, s56
	s_mov_b32 m0, s46
	v_lshl_add_u64 v[210:211], s[8:9], 0, v[138:139]
	ds_read_b128 v[178:181], v142
	ds_read_b128 v[182:185], v142 offset:1024
	ds_read_b128 v[186:189], v142 offset:2048
	ds_read_b128 v[190:193], v142 offset:3072
	ds_read_b128 v[194:197], v142 offset:4096
	ds_read_b128 v[198:201], v142 offset:5120
	ds_read_b128 v[202:205], v142 offset:6144
	ds_read_b128 v[206:209], v142 offset:7168
	global_load_lds_dwordx4 v[210:211], off
	v_lshl_add_u64 v[210:211], s[8:9], 0, v[136:137]
	s_mov_b32 m0, s47
	s_nop 0
	global_load_lds_dwordx4 v[210:211], off
	s_waitcnt vmcnt(8) lgkmcnt(0)
	s_barrier
	v_mfma_f32_16x16x32_bf16 v[8:11], v[146:149], v[178:181], v[8:11]
	v_mfma_f32_16x16x32_bf16 v[12:15], v[154:157], v[178:181], v[12:15]
	v_mfma_f32_16x16x32_bf16 v[60:63], v[146:149], v[186:189], v[60:63]
	v_mfma_f32_16x16x32_bf16 v[20:23], v[154:157], v[186:189], v[20:23]
	v_mfma_f32_16x16x32_bf16 v[76:79], v[146:149], v[194:197], v[76:79]
	v_mfma_f32_16x16x32_bf16 v[52:55], v[154:157], v[194:197], v[52:55]
	v_mfma_f32_16x16x32_bf16 v[128:131], v[146:149], v[202:205], v[128:131]
	v_mfma_f32_16x16x32_bf16 v[68:71], v[154:157], v[202:205], v[68:71]
	v_mfma_f32_16x16x32_bf16 v[8:11], v[150:153], v[182:185], v[8:11]
	v_mfma_f32_16x16x32_bf16 v[12:15], v[158:161], v[182:185], v[12:15]
	v_mfma_f32_16x16x32_bf16 v[60:63], v[150:153], v[190:193], v[60:63]
	v_mfma_f32_16x16x32_bf16 v[20:23], v[158:161], v[190:193], v[20:23]
	v_mfma_f32_16x16x32_bf16 v[76:79], v[150:153], v[198:201], v[76:79]
	v_mfma_f32_16x16x32_bf16 v[52:55], v[158:161], v[198:201], v[52:55]
	v_mfma_f32_16x16x32_bf16 v[128:131], v[150:153], v[206:209], v[128:131]
	v_mfma_f32_16x16x32_bf16 v[68:71], v[158:161], v[206:209], v[68:71]
	v_mfma_f32_16x16x32_bf16 v[24:27], v[162:165], v[178:181], v[24:27]
	v_mfma_f32_16x16x32_bf16 v[16:19], v[170:173], v[178:181], v[16:19]
	v_mfma_f32_16x16x32_bf16 v[56:59], v[162:165], v[186:189], v[56:59]
	v_mfma_f32_16x16x32_bf16 v[48:51], v[170:173], v[186:189], v[48:51]
	v_mfma_f32_16x16x32_bf16 v[72:75], v[162:165], v[194:197], v[72:75]
	v_mfma_f32_16x16x32_bf16 v[64:67], v[170:173], v[194:197], v[64:67]
	v_mfma_f32_16x16x32_bf16 v[108:111], v[162:165], v[202:205], v[108:111]
	v_mfma_f32_16x16x32_bf16 v[96:99], v[170:173], v[202:205], v[96:99]
	v_mfma_f32_16x16x32_bf16 v[24:27], v[166:169], v[182:185], v[24:27]
	v_mfma_f32_16x16x32_bf16 v[16:19], v[174:177], v[182:185], v[16:19]
	v_mfma_f32_16x16x32_bf16 v[56:59], v[166:169], v[190:193], v[56:59]
	v_mfma_f32_16x16x32_bf16 v[48:51], v[174:177], v[190:193], v[48:51]
	v_mfma_f32_16x16x32_bf16 v[72:75], v[166:169], v[198:201], v[72:75]
	v_mfma_f32_16x16x32_bf16 v[64:67], v[174:177], v[198:201], v[64:67]
	v_mfma_f32_16x16x32_bf16 v[108:111], v[166:169], v[206:209], v[108:111]
	v_mfma_f32_16x16x32_bf16 v[96:99], v[174:177], v[206:209], v[96:99]
	s_barrier
	s_mov_b32 m0, s48
	v_lshl_add_u64 v[210:211], s[20:21], 0, v[34:35]
	s_add_u32 s56, s20, 0x80000
	ds_read_b128 v[178:181], v142 offset:16384
	ds_read_b128 v[182:185], v142 offset:17408
	ds_read_b128 v[186:189], v142 offset:18432
	ds_read_b128 v[190:193], v142 offset:19456
	ds_read_b128 v[194:197], v142 offset:20480
	ds_read_b128 v[198:201], v142 offset:21504
	ds_read_b128 v[202:205], v142 offset:22528
	ds_read_b128 v[206:209], v142 offset:23552
	global_load_lds_dwordx4 v34, s[20:21]
	v_lshl_add_u64 v[212:213], s[20:21], 0, v[134:135]
	s_mov_b32 m0, s49
	s_addc_u32 s57, s21, 0
	global_load_lds_dwordx4 v134, s[20:21]
	v_lshl_add_u64 v[214:215], s[56:57], 0, v[34:35]
	s_mov_b32 m0, s50
	v_lshl_add_u64 v[216:217], s[22:23], 0, v[132:133]
	global_load_lds_dwordx4 v34, s[56:57]
	v_lshl_add_u64 v[214:215], s[56:57], 0, v[134:135]
	s_mov_b32 m0, s51
	s_nop 0
	global_load_lds_dwordx4 v134, s[56:57]
	v_lshl_add_u64 v[214:215], s[22:23], 0, v[32:33]
	s_mov_b32 m0, s27
	s_nop 0
	global_load_lds_dwordx4 v32, s[22:23]
	s_mov_b32 m0, s36
	s_nop 0
	global_load_lds_dwordx4 v132, s[22:23]
	s_waitcnt vmcnt(8) lgkmcnt(0)
	s_barrier
	v_mfma_f32_16x16x32_bf16 v[100:103], v[146:149], v[178:181], v[100:103]
	v_mfma_f32_16x16x32_bf16 v[104:107], v[154:157], v[178:181], v[104:107]
	v_mfma_f32_16x16x32_bf16 v[116:119], v[146:149], v[186:189], v[116:119]
	v_mfma_f32_16x16x32_bf16 v[120:123], v[154:157], v[186:189], v[120:123]
	v_mfma_f32_16x16x32_bf16 v[84:87], v[146:149], v[194:197], v[84:87]
	v_mfma_f32_16x16x32_bf16 v[80:83], v[154:157], v[194:197], v[80:83]
	v_mfma_f32_16x16x32_bf16 v[36:39], v[146:149], v[202:205], v[36:39]
	v_mfma_f32_16x16x32_bf16 v[28:31], v[154:157], v[202:205], v[28:31]
	v_mfma_f32_16x16x32_bf16 v[100:103], v[150:153], v[182:185], v[100:103]
	v_mfma_f32_16x16x32_bf16 v[104:107], v[158:161], v[182:185], v[104:107]
	v_mfma_f32_16x16x32_bf16 v[116:119], v[150:153], v[190:193], v[116:119]
	v_mfma_f32_16x16x32_bf16 v[120:123], v[158:161], v[190:193], v[120:123]
	v_mfma_f32_16x16x32_bf16 v[84:87], v[150:153], v[198:201], v[84:87]
	v_mfma_f32_16x16x32_bf16 v[80:83], v[158:161], v[198:201], v[80:83]
	v_mfma_f32_16x16x32_bf16 v[36:39], v[150:153], v[206:209], v[36:39]
	v_mfma_f32_16x16x32_bf16 v[28:31], v[158:161], v[206:209], v[28:31]
	v_mfma_f32_16x16x32_bf16 v[124:127], v[162:165], v[178:181], v[124:127]
	v_mfma_f32_16x16x32_bf16 v[112:115], v[170:173], v[178:181], v[112:115]
	v_mfma_f32_16x16x32_bf16 v[92:95], v[162:165], v[186:189], v[92:95]
	v_mfma_f32_16x16x32_bf16 v[88:91], v[170:173], v[186:189], v[88:91]
	v_mfma_f32_16x16x32_bf16 v[44:47], v[162:165], v[194:197], v[44:47]
	v_mfma_f32_16x16x32_bf16 v[40:43], v[170:173], v[194:197], v[40:43]
	v_mfma_f32_16x16x32_bf16 v[4:7], v[162:165], v[202:205], v[4:7]
	v_mfma_f32_16x16x32_bf16 v[0:3], v[170:173], v[202:205], v[0:3]
	v_mfma_f32_16x16x32_bf16 v[124:127], v[166:169], v[182:185], v[124:127]
	v_mfma_f32_16x16x32_bf16 v[112:115], v[174:177], v[182:185], v[112:115]
	v_mfma_f32_16x16x32_bf16 v[92:95], v[166:169], v[190:193], v[92:95]
	v_mfma_f32_16x16x32_bf16 v[88:91], v[174:177], v[190:193], v[88:91]
	v_mfma_f32_16x16x32_bf16 v[44:47], v[166:169], v[198:201], v[44:47]
	v_mfma_f32_16x16x32_bf16 v[40:43], v[174:177], v[198:201], v[40:43]
	v_mfma_f32_16x16x32_bf16 v[4:7], v[166:169], v[206:209], v[4:7]
	v_mfma_f32_16x16x32_bf16 v[0:3], v[174:177], v[206:209], v[0:3]
	s_barrier
	ds_read_b128 v[146:149], v143
	ds_read_b128 v[150:153], v143 offset:1024
	ds_read_b128 v[154:157], v143 offset:2048
	ds_read_b128 v[158:161], v143 offset:3072
	ds_read_b128 v[162:165], v144
	ds_read_b128 v[166:169], v144 offset:1024
	ds_read_b128 v[170:173], v144 offset:2048
	ds_read_b128 v[174:177], v144 offset:3072
	s_add_u32 s22, s22, 0x80000
	s_addc_u32 s23, s23, 0
	s_mov_b32 m0, s37
	v_lshl_add_u64 v[218:219], s[22:23], 0, v[32:33]
	ds_read_b128 v[178:181], v142 offset:32768
	ds_read_b128 v[182:185], v142 offset:33792
	ds_read_b128 v[186:189], v142 offset:34816
	ds_read_b128 v[190:193], v142 offset:35840
	ds_read_b128 v[194:197], v142 offset:36864
	ds_read_b128 v[198:201], v142 offset:37888
	ds_read_b128 v[202:205], v142 offset:38912
	ds_read_b128 v[206:209], v142 offset:39936
	global_load_lds_dwordx4 v32, s[22:23]
	v_lshl_add_u64 v[218:219], s[22:23], 0, v[132:133]
	s_mov_b32 m0, s38
	s_nop 0
	global_load_lds_dwordx4 v132, s[22:23]
	s_waitcnt vmcnt(8) lgkmcnt(0)
	s_barrier
	v_mfma_f32_16x16x32_bf16 v[8:11], v[146:149], v[178:181], v[8:11]
	v_mfma_f32_16x16x32_bf16 v[12:15], v[154:157], v[178:181], v[12:15]
	v_mfma_f32_16x16x32_bf16 v[60:63], v[146:149], v[186:189], v[60:63]
	v_mfma_f32_16x16x32_bf16 v[20:23], v[154:157], v[186:189], v[20:23]
	v_mfma_f32_16x16x32_bf16 v[76:79], v[146:149], v[194:197], v[76:79]
	v_mfma_f32_16x16x32_bf16 v[52:55], v[154:157], v[194:197], v[52:55]
	v_mfma_f32_16x16x32_bf16 v[128:131], v[146:149], v[202:205], v[128:131]
	v_mfma_f32_16x16x32_bf16 v[68:71], v[154:157], v[202:205], v[68:71]
	v_mfma_f32_16x16x32_bf16 v[8:11], v[150:153], v[182:185], v[8:11]
	v_mfma_f32_16x16x32_bf16 v[12:15], v[158:161], v[182:185], v[12:15]
	v_mfma_f32_16x16x32_bf16 v[60:63], v[150:153], v[190:193], v[60:63]
	v_mfma_f32_16x16x32_bf16 v[20:23], v[158:161], v[190:193], v[20:23]
	v_mfma_f32_16x16x32_bf16 v[76:79], v[150:153], v[198:201], v[76:79]
	v_mfma_f32_16x16x32_bf16 v[52:55], v[158:161], v[198:201], v[52:55]
	v_mfma_f32_16x16x32_bf16 v[128:131], v[150:153], v[206:209], v[128:131]
	v_mfma_f32_16x16x32_bf16 v[68:71], v[158:161], v[206:209], v[68:71]
	v_mfma_f32_16x16x32_bf16 v[24:27], v[162:165], v[178:181], v[24:27]
	v_mfma_f32_16x16x32_bf16 v[16:19], v[170:173], v[178:181], v[16:19]
	v_mfma_f32_16x16x32_bf16 v[56:59], v[162:165], v[186:189], v[56:59]
	v_mfma_f32_16x16x32_bf16 v[48:51], v[170:173], v[186:189], v[48:51]
	v_mfma_f32_16x16x32_bf16 v[72:75], v[162:165], v[194:197], v[72:75]
	v_mfma_f32_16x16x32_bf16 v[64:67], v[170:173], v[194:197], v[64:67]
	v_mfma_f32_16x16x32_bf16 v[108:111], v[162:165], v[202:205], v[108:111]
	v_mfma_f32_16x16x32_bf16 v[96:99], v[170:173], v[202:205], v[96:99]
	v_mfma_f32_16x16x32_bf16 v[24:27], v[166:169], v[182:185], v[24:27]
	v_mfma_f32_16x16x32_bf16 v[16:19], v[174:177], v[182:185], v[16:19]
	v_mfma_f32_16x16x32_bf16 v[56:59], v[166:169], v[190:193], v[56:59]
	v_mfma_f32_16x16x32_bf16 v[48:51], v[174:177], v[190:193], v[48:51]
	v_mfma_f32_16x16x32_bf16 v[72:75], v[166:169], v[198:201], v[72:75]
	v_mfma_f32_16x16x32_bf16 v[64:67], v[174:177], v[198:201], v[64:67]
	v_mfma_f32_16x16x32_bf16 v[108:111], v[166:169], v[206:209], v[108:111]
	v_mfma_f32_16x16x32_bf16 v[96:99], v[174:177], v[206:209], v[96:99]
	s_barrier
; template <class Epi, class Sched, bool ALIGN_EPI = false, bool SP2 = false, bool A_TILED = false>
; __device__ __forceinline__ void gemm_phase(PG8_LAS unsigned char* lds, const Gemm g, const Sched& S, const Epi& E, const int wave_s) {
;     ...
;         for (int t = PEEL ? 2 : 0; t < nt; t += 2) {
;             const bool last = (t == nt - 2);
;             const char* a1 = cA + (size_t)(t + 1) * kstepA;
	s_mov_b32 m0, s52
	v_lshl_add_u64 v[210:211], v[210:211], 0, s[14:15]
	s_add_u32 s20, s20, 0x80080
	ds_read_b128 v[178:181], v142 offset:49152
	ds_read_b128 v[182:185], v142 offset:50176
	ds_read_b128 v[186:189], v142 offset:51200
	ds_read_b128 v[190:193], v142 offset:52224
	ds_read_b128 v[194:197], v142 offset:53248
	ds_read_b128 v[198:201], v142 offset:54272
	ds_read_b128 v[202:205], v142 offset:55296
	ds_read_b128 v[206:209], v142 offset:56320
	global_load_lds_dwordx4 v[210:211], off
	v_lshl_add_u64 v[210:211], v[212:213], 0, s[14:15]
	s_mov_b32 m0, s53
	s_addc_u32 s21, s21, 0
	global_load_lds_dwordx4 v[210:211], off
	v_lshl_add_u64 v[210:211], s[20:21], 0, v[34:35]
	s_mov_b32 m0, s54
	s_nop 0
	global_load_lds_dwordx4 v34, s[20:21]
	v_lshl_add_u64 v[210:211], s[20:21], 0, v[134:135]
	s_mov_b32 m0, s55
	s_nop 0
	global_load_lds_dwordx4 v134, s[20:21]
	v_lshl_add_u64 v[210:211], v[214:215], 0, s[14:15]
	s_mov_b32 m0, s39
	s_nop 0
	global_load_lds_dwordx4 v[210:211], off
	v_lshl_add_u64 v[210:211], v[216:217], 0, s[14:15]
	s_mov_b32 m0, s40
	s_nop 0
	global_load_lds_dwordx4 v[210:211], off
	s_waitcnt vmcnt(8) lgkmcnt(0)
	s_barrier
	v_mfma_f32_16x16x32_bf16 v[100:103], v[146:149], v[178:181], v[100:103]
	v_mfma_f32_16x16x32_bf16 v[104:107], v[154:157], v[178:181], v[104:107]
	v_mfma_f32_16x16x32_bf16 v[116:119], v[146:149], v[186:189], v[116:119]
	v_mfma_f32_16x16x32_bf16 v[120:123], v[154:157], v[186:189], v[120:123]
	v_mfma_f32_16x16x32_bf16 v[84:87], v[146:149], v[194:197], v[84:87]
	v_mfma_f32_16x16x32_bf16 v[80:83], v[154:157], v[194:197], v[80:83]
	v_mfma_f32_16x16x32_bf16 v[36:39], v[146:149], v[202:205], v[36:39]
	v_mfma_f32_16x16x32_bf16 v[28:31], v[154:157], v[202:205], v[28:31]
	v_mfma_f32_16x16x32_bf16 v[100:103], v[150:153], v[182:185], v[100:103]
	v_mfma_f32_16x16x32_bf16 v[104:107], v[158:161], v[182:185], v[104:107]
	v_mfma_f32_16x16x32_bf16 v[116:119], v[150:153], v[190:193], v[116:119]
	v_mfma_f32_16x16x32_bf16 v[120:123], v[158:161], v[190:193], v[120:123]
	v_mfma_f32_16x16x32_bf16 v[84:87], v[150:153], v[198:201], v[84:87]
	v_mfma_f32_16x16x32_bf16 v[80:83], v[158:161], v[198:201], v[80:83]
	v_mfma_f32_16x16x32_bf16 v[36:39], v[150:153], v[206:209], v[36:39]
	v_mfma_f32_16x16x32_bf16 v[28:31], v[158:161], v[206:209], v[28:31]
	v_mfma_f32_16x16x32_bf16 v[124:127], v[162:165], v[178:181], v[124:127]
	v_mfma_f32_16x16x32_bf16 v[112:115], v[170:173], v[178:181], v[112:115]
	v_mfma_f32_16x16x32_bf16 v[92:95], v[162:165], v[186:189], v[92:95]
	v_mfma_f32_16x16x32_bf16 v[88:91], v[170:173], v[186:189], v[88:91]
	v_mfma_f32_16x16x32_bf16 v[44:47], v[162:165], v[194:197], v[44:47]
	v_mfma_f32_16x16x32_bf16 v[40:43], v[170:173], v[194:197], v[40:43]
	v_mfma_f32_16x16x32_bf16 v[4:7], v[162:165], v[202:205], v[4:7]
	v_mfma_f32_16x16x32_bf16 v[0:3], v[170:173], v[202:205], v[0:3]
	v_mfma_f32_16x16x32_bf16 v[124:127], v[166:169], v[182:185], v[124:127]
	v_mfma_f32_16x16x32_bf16 v[112:115], v[174:177], v[182:185], v[112:115]
	v_mfma_f32_16x16x32_bf16 v[92:95], v[166:169], v[190:193], v[92:95]
	v_mfma_f32_16x16x32_bf16 v[88:91], v[174:177], v[190:193], v[88:91]
	v_mfma_f32_16x16x32_bf16 v[44:47], v[166:169], v[198:201], v[44:47]
	v_mfma_f32_16x16x32_bf16 v[40:43], v[174:177], v[198:201], v[40:43]
	v_mfma_f32_16x16x32_bf16 v[4:7], v[166:169], v[206:209], v[4:7]
	v_mfma_f32_16x16x32_bf16 v[0:3], v[174:177], v[206:209], v[0:3]
	s_barrier
	s_add_i32 s45, s45, 2
	s_add_u32 s41, s41, 0x100
	s_addc_u32 s42, s42, 0
	s_add_u32 s43, s43, 0x100
	s_addc_u32 s44, s44, 0
	v_lshl_add_u64 v[136:137], v[136:137], 0, s[16:17]
	s_cmp_gt_u32 s45, 29
	v_lshl_add_u64 v[138:139], v[138:139], 0, s[16:17]
	s_cbranch_scc0 .LBB0_3608
	s_waitcnt vmcnt(0)
	s_cmpk_lt_u32 s24, 0x100
	s_cbranch_scc0 .LBB0_3611
	s_barrier

; __device__ __forceinline__ int tid_now(int wave_s) { unsigned z = 0u; asm volatile("" : "+v"(z)); return (wave_s << 6) | (int)__builtin_amdgcn_mbcnt_hi(~0u, __builtin_amdgcn_mbcnt_lo(~0u, z)); }
; __device__ __forceinline__ unsigned xb_add(unsigned* p, unsigned v) { return __hip_atomic_fetch_add(p, v, __ATOMIC_RELAXED, __HIP_MEMORY_SCOPE_AGENT); }
; __device__ __forceinline__ void xcd_barrier(const XcdBarrier& b) {
;     asm volatile("s_waitcnt vmcnt(0)" ::: "memory");
;     __syncthreads();
;     if (tid_now(b.w) == 0) {
;         unsigned* bar = b.bar;
;         __builtin_amdgcn_s_waitcnt(0);
;         unsigned nloc = b.st[0], nx = b.st[1];
;         if (nloc == 0u) { xcd_barrier_complete(bar, b.x, nloc, nx, b.np); b.st[0] = nloc; b.st[1] = nx; }
;         const unsigned old = xb_add(&bar[XB_XSUB(b.x)], 1u);
.LBB0_3652:
	s_setprio 0
	s_cmp_gt_i32 s35, 23
	s_cselect_b64 s[0:1], -1, 0
	s_and_b64 s[2:3], s[6:7], s[0:1]
	s_andn2_b64 vcc, exec, s[2:3]
	s_cbranch_vccnz .LBB0_3706
	s_waitcnt vmcnt(0)
	v_mov_b32_e32 v0, 0
	s_waitcnt vmcnt(0)
	s_waitcnt lgkmcnt(0)
	s_barrier
	s_nop 0
	v_mbcnt_lo_u32_b32 v0, -1, v0
	v_mbcnt_hi_u32_b32 v0, -1, v0
	v_or_b32_e32 v0, s33, v0
	v_cmp_eq_u32_e32 vcc, 0, v0
	s_and_saveexec_b64 s[2:3], vcc
	s_cbranch_execz .LBB0_3705
	s_add_i32 s4, 0, 0x27f68
	v_mov_b32_e32 v0, s4
	s_waitcnt vmcnt(0) expcnt(0) lgkmcnt(0)
	ds_read_b32 v2, v0
	s_add_i32 s4, 0, 0x27f6c
	v_mov_b32_e32 v0, s4
	ds_read_b32 v0, v0
	s_waitcnt lgkmcnt(1)
	v_cmp_ne_u32_e32 vcc, 0, v2
	s_cbranch_vccnz .LBB0_3669
	s_add_u32 s4, s10, 0x1000
	s_addc_u32 s5, s11, 0
	s_add_u32 s6, s10, 0x1100
	s_addc_u32 s7, s11, 0
	s_add_u32 s8, s10, 0x1200
	s_addc_u32 s9, s11, 0
	s_add_u32 s12, s10, 0x1300
	s_addc_u32 s13, s11, 0
	s_mov_b32 s20, 1
	v_mov_b32_e32 v16, 0
	s_branch .LBB0_3657

; #define PG8_STAGE(bufoff, gbase, voff) do { _Pragma("unroll") for (int _i = 0; _i < 2; ++_i) \
;         __builtin_amdgcn_global_load_lds((const unsigned*)((const char*)(gbase) + (voff)[_i]), (PG8_LAS unsigned*)(lds + (bufoff) + ldsw + _i * 8192), 16, 0, 0); } while (0)
; #define PG8_WAIT_V(n) asm volatile("s_waitcnt vmcnt(" #n ")" ::: "memory")
; #define PG8_BAR __builtin_amdgcn_s_barrier()
; template <class Epi, class Sched, bool ALIGN_EPI = false, bool SP2 = false, bool A_TILED = false>
; __device__ __forceinline__ void gemm_phase(PG8_LAS unsigned char* lds, const Gemm g, const Sched& S, const Epi& E, const int wave_s) {
;     ...
;         PG8_STAGE(PG8_SB(0, 0), cB, voffB); PG8_STAGE(PG8_SB(0, 1), cB + hstep, voffB); PG8_STAGE(PG8_SA(0, 0), cA, voffA); PG8_STAGE(PG8_SA(0, 1), cA + hstepA, voffA);
;         if (wr == 1) PG8_BAR;
;         PG8_WAIT_V(2); PG8_BAR;
;         PG8_STAGE(PG8_SB(1, 0), cB + kstep, voffB); PG8_STAGE(PG8_SA(1, 0), cA + kstepA, voffA); PG8_STAGE(PG8_SB(1, 1), cB + hstep + kstep, voffB);
;         PG8_WAIT_V(6); PG8_BAR;
;     } else {
;         PG8_STAGE(PG8_SB(0, 0), cB, voffB); PG8_STAGE(PG8_SA(0, 0), cA, voffA); PG8_STAGE(PG8_SB(0, 1), cB + hstep, voffB); PG8_STAGE(PG8_SA(0, 1), cA + hstepA, voffA);
;         if (wr == 1) PG8_BAR;
;         PG8_WAIT_V(4); PG8_BAR;
;         PG8_STAGE(PG8_SB(1, 0), cB + kstep, voffB); PG8_STAGE(PG8_SA(1, 0), cA + kstepA, voffA); PG8_STAGE(PG8_SB(1, 1), cB + hstep + kstep, voffB);
;         PG8_WAIT_V(6); PG8_BAR;
;     }
;     for (;;) {
;         const bool has_next = Epi::AFTER_DRAIN ? false : S.next(ui + 1, nxt);
;         const char* nA = has_next ? (const char*)g.A + (size_t)nxt.pm * tstepA : cA; const char* nB = has_next ? (const char*)g.Bt + (size_t)nxt.pn * tstep : cB;
;         constexpr bool PEEL = SP2 && !Epi::AFTER_DRAIN;
;         if constexpr (PEEL) {
;             const char* a1 = cA + kstepA; const char* a2 = cA + 2 * kstepA; const char* b2 = cB + 2 * kstep; const char* a3 = a2 + kstepA; const char* b3 = b2 + kstep;
;             PG8_ITER(PG8_MMAZ)
.LBB0_3710:
	s_ashr_i32 s53, s86, 31
	s_add_u32 s54, s0, 0x34600000
	s_addc_u32 s55, s1, 0
	s_lshl_b32 s13, s6, 13
	s_mov_b64 s[6:7], 0x80
	s_and_b32 s0, s12, 3
	s_add_i32 m0, s47, 0x18000
	v_lshl_add_u64 v[6:7], v[6:7], 0, s[6:7]
	s_lshl_b32 s14, s0, 12
	s_waitcnt vmcnt(2)
	s_barrier
	global_load_lds_dwordx4 v[6:7], off
	v_lshl_add_u64 v[4:5], v[4:5], 0, s[6:7]
	s_add_i32 m0, s47, 0x1a000
	s_add_i32 s56, s47, 0x8000
	s_add_i32 s57, s47, 0xa000
	global_load_lds_dwordx4 v[4:5], off
	v_lshl_add_u64 v[0:1], v[0:1], 0, s[6:7]
	s_mov_b32 m0, s56
	s_add_u32 s0, s26, 0x80080
	global_load_lds_dwordx4 v[0:1], off
	v_lshl_add_u64 v[0:1], v[2:3], 0, s[6:7]
	s_mov_b32 m0, s57
	s_addc_u32 s1, s27, 0
	global_load_lds_dwordx4 v[0:1], off
	s_add_i32 m0, s47, 0x1c000
	v_lshl_add_u64 v[0:1], s[0:1], 0, v[128:129]
	global_load_lds_dwordx4 v128, s[0:1]
	v_lshl_add_u64 v[0:1], s[0:1], 0, v[130:131]
	s_add_i32 m0, s47, 0x1e000
	s_cmpk_lt_u32 s9, 0x100
	global_load_lds_dwordx4 v130, s[0:1]
	v_and_b32_e32 v0, 15, v8
	v_and_b32_e32 v1, 48, v8
	v_lshl_or_b32 v0, v0, 6, v1
	v_lshlrev_b32_e32 v1, 2, v8
	v_and_b32_e32 v1, 32, v1
	v_bitop3_b32 v2, v0, s13, v1 bitop3:0xde
	v_bitop3_b32 v144, v0, s14, v1 bitop3:0xde
	v_lshlrev_b32_e32 v0, 15, v9
	v_and_b32_e32 v0, 0xffff0000, v0
	v_lshl_add_u32 v0, v10, 12, v0
	v_and_b32_e32 v1, 1, v9
	v_lshl_or_b32 v0, v1, 6, v0
	v_lshl_add_u32 v136, v11, 1, v0
	v_lshlrev_b32_e32 v0, 15, v13
	v_and_b32_e32 v0, 0xffff0000, v0
	s_waitcnt vmcnt(6)
	s_mov_b32 s98, 0
	v_lshl_add_u32 v0, v12, 12, v0
	v_and_b32_e32 v1, 1, v13
	s_sext_i32_i16 s25, s8
	s_cselect_b64 s[8:9], -1, 0
	s_bitcmp1_b32 s33, 8
	s_cbranch_scc1 .Lsp_17
	s_setprio 1
.Lsp_17:
	s_and_b32 s0, s45, 0x400
	v_mov_b32_e32 v137, 0
	v_lshl_or_b32 v0, v1, 6, v0
	s_add_i32 s60, 0, 0x10000
	s_add_i32 s61, 0, 0x14000
	s_bfe_u32 s58, s12, 0x10001
	s_or_b32 s59, s0, s13
	v_lshl_add_u32 v138, v14, 1, v0
	v_mov_b32_e32 v139, v137
	v_mov_b64_e32 v[140:141], 0x200
	v_mov_b64_e32 v[142:143], 0x1ff
	v_add_u32_e32 v145, s60, v144
	v_add_u32_e32 v146, s61, v144
	v_add_u32_e32 v147, 0, v2
	s_mov_b64 s[12:13], 0x100
	s_mov_b64 s[14:15], 0x180
	s_barrier
	s_branch .LBB0_3713

; template <class Epi, class Sched, bool ALIGN_EPI = false, bool SP2 = false, bool A_TILED = false>
; __device__ __forceinline__ void gemm_phase(PG8_LAS unsigned char* lds, const Gemm g, const Sched& S, const Epi& E, const int wave_s) {
;     ...
;         if constexpr (PEEL) {
;             const char* a1 = cA + kstepA; const char* a2 = cA + 2 * kstepA; const char* b2 = cB + 2 * kstep; const char* a3 = a2 + kstepA; const char* b3 = b2 + kstep;
;             PG8_ITER(PG8_MMAZ)
.Lpw_19:
	s_barrier
	v_mfma_f32_16x16x32_bf16 v[88:91], v[0:3], v[56:59], 0
	v_mfma_f32_16x16x32_bf16 v[64:67], v[0:3], v[32:35], 0
	v_mfma_f32_16x16x32_bf16 v[68:71], v[8:11], v[32:35], 0
	v_mfma_f32_16x16x32_bf16 v[72:75], v[0:3], v[40:43], 0
	v_mfma_f32_16x16x32_bf16 v[76:79], v[8:11], v[40:43], 0
	v_mfma_f32_16x16x32_bf16 v[80:83], v[0:3], v[48:51], 0
	v_mfma_f32_16x16x32_bf16 v[84:87], v[8:11], v[48:51], 0
	v_mfma_f32_16x16x32_bf16 v[96:99], v[4:7], v[60:63], v[88:91]
	v_mfma_f32_16x16x32_bf16 v[88:91], v[8:11], v[56:59], 0
	v_mfma_f32_16x16x32_bf16 v[64:67], v[4:7], v[36:39], v[64:67]
	v_mfma_f32_16x16x32_bf16 v[68:71], v[12:15], v[36:39], v[68:71]
	v_mfma_f32_16x16x32_bf16 v[72:75], v[4:7], v[44:47], v[72:75]
	v_mfma_f32_16x16x32_bf16 v[76:79], v[12:15], v[44:47], v[76:79]
	v_mfma_f32_16x16x32_bf16 v[80:83], v[4:7], v[52:55], v[80:83]
	v_mfma_f32_16x16x32_bf16 v[84:87], v[12:15], v[52:55], v[84:87]
	v_mfma_f32_16x16x32_bf16 v[100:103], v[12:15], v[60:63], v[88:91]
	v_mfma_f32_16x16x32_bf16 v[88:91], v[16:19], v[32:35], 0
	v_mfma_f32_16x16x32_bf16 v[32:35], v[24:27], v[32:35], 0
	v_mfma_f32_16x16x32_bf16 v[112:115], v[20:23], v[36:39], v[88:91]
	v_mfma_f32_16x16x32_bf16 v[32:35], v[28:31], v[36:39], v[32:35]
	v_mfma_f32_16x16x32_bf16 v[36:39], v[16:19], v[40:43], 0
	v_mfma_f32_16x16x32_bf16 v[40:43], v[24:27], v[40:43], 0
	v_mfma_f32_16x16x32_bf16 v[36:39], v[20:23], v[44:47], v[36:39]
	v_mfma_f32_16x16x32_bf16 v[40:43], v[28:31], v[44:47], v[40:43]
	v_mfma_f32_16x16x32_bf16 v[44:47], v[16:19], v[48:51], 0
	v_mfma_f32_16x16x32_bf16 v[48:51], v[24:27], v[48:51], 0
	v_mfma_f32_16x16x32_bf16 v[44:47], v[20:23], v[52:55], v[44:47]
	v_mfma_f32_16x16x32_bf16 v[48:51], v[28:31], v[52:55], v[48:51]
	v_mfma_f32_16x16x32_bf16 v[52:55], v[16:19], v[56:59], 0
	v_mfma_f32_16x16x32_bf16 v[56:59], v[24:27], v[56:59], 0
	v_mfma_f32_16x16x32_bf16 v[52:55], v[20:23], v[60:63], v[52:55]
	v_mfma_f32_16x16x32_bf16 v[56:59], v[28:31], v[60:63], v[56:59]
	s_barrier
	s_add_i32 s66, s60, s45
	v_lshl_add_u64 v[242:243], s[26:27], 0, v[128:129]
	s_add_i32 s67, s66, 0x2000
	v_lshl_add_u64 v[148:149], v[242:243], 0, s[12:13]
	s_mov_b32 m0, s66
	v_lshl_add_u64 v[244:245], s[26:27], 0, v[130:131]
	s_add_u32 s38, s26, 0x80100
	ds_read_b128 v[60:63], v147 offset:16384
	ds_read_b128 v[88:91], v147 offset:17408
	ds_read_b128 v[92:95], v147 offset:18432
	ds_read_b128 v[104:107], v147 offset:19456
	ds_read_b128 v[108:111], v147 offset:20480
	ds_read_b128 v[116:119], v147 offset:21504
	ds_read_b128 v[120:123], v147 offset:22528
	ds_read_b128 v[124:127], v147 offset:23552
	global_load_lds_dwordx4 v[148:149], off
	v_lshl_add_u64 v[148:149], v[244:245], 0, s[12:13]
	s_mov_b32 m0, s67
	s_addc_u32 s39, s27, 0
	s_add_i32 s68, s61, s45
	global_load_lds_dwordx4 v[148:149], off
	v_lshl_add_u64 v[148:149], s[38:39], 0, v[128:129]
	s_mov_b32 m0, s68
	s_add_i32 s69, s68, 0x2000
	global_load_lds_dwordx4 v128, s[38:39]
	v_lshl_add_u64 v[148:149], s[38:39], 0, v[130:131]
	s_mov_b32 m0, s69
	v_lshl_add_u64 v[246:247], s[36:37], 0, v[134:135]
	global_load_lds_dwordx4 v130, s[38:39]
	v_lshl_add_u64 v[148:149], v[246:247], 0, s[12:13]
	s_mov_b32 m0, s47
	v_lshl_add_u64 v[248:249], s[36:37], 0, v[132:133]
	global_load_lds_dwordx4 v[148:149], off
	v_lshl_add_u64 v[148:149], v[248:249], 0, s[12:13]
	s_mov_b32 m0, s48
	s_nop 0
	global_load_lds_dwordx4 v[148:149], off
	s_waitcnt vmcnt(24) lgkmcnt(0)
	s_cmp_lg_u32 s98, 0
	s_cbranch_scc1 .Lpw_20
	s_waitcnt vmcnt(8)
.Lpw_20:
	s_barrier
	v_mfma_f32_16x16x32_bf16 v[148:151], v[0:3], v[60:63], 0
	v_mfma_f32_16x16x32_bf16 v[158:161], v[0:3], v[92:95], 0
	v_mfma_f32_16x16x32_bf16 v[166:169], v[0:3], v[108:111], 0
	v_mfma_f32_16x16x32_bf16 v[0:3], v[0:3], v[120:123], 0
	v_mfma_f32_16x16x32_bf16 v[150:153], v[4:7], v[88:91], v[148:151]
	v_mfma_f32_16x16x32_bf16 v[158:161], v[4:7], v[104:107], v[158:161]
	v_mfma_f32_16x16x32_bf16 v[166:169], v[4:7], v[116:119], v[166:169]
	v_mfma_f32_16x16x32_bf16 v[0:3], v[4:7], v[124:127], v[0:3]
	v_mfma_f32_16x16x32_bf16 v[4:7], v[8:11], v[120:123], 0
	v_mfma_f32_16x16x32_bf16 v[154:157], v[8:11], v[60:63], 0
	v_mfma_f32_16x16x32_bf16 v[162:165], v[8:11], v[92:95], 0
	v_mfma_f32_16x16x32_bf16 v[170:173], v[8:11], v[108:111], 0
	v_mfma_f32_16x16x32_bf16 v[4:7], v[12:15], v[124:127], v[4:7]
	v_mfma_f32_16x16x32_bf16 v[154:157], v[12:15], v[88:91], v[154:157]
	v_mfma_f32_16x16x32_bf16 v[162:165], v[12:15], v[104:107], v[162:165]
	v_mfma_f32_16x16x32_bf16 v[170:173], v[12:15], v[116:119], v[170:173]
	v_mfma_f32_16x16x32_bf16 v[8:11], v[16:19], v[60:63], 0
	v_mfma_f32_16x16x32_bf16 v[174:177], v[20:23], v[88:91], v[8:11]
	v_mfma_f32_16x16x32_bf16 v[8:11], v[24:27], v[60:63], 0
	v_mfma_f32_16x16x32_bf16 v[60:63], v[28:31], v[88:91], v[8:11]
	v_mfma_f32_16x16x32_bf16 v[8:11], v[16:19], v[92:95], 0
	v_mfma_f32_16x16x32_bf16 v[178:181], v[20:23], v[104:107], v[8:11]
	v_mfma_f32_16x16x32_bf16 v[8:11], v[24:27], v[92:95], 0
	v_mfma_f32_16x16x32_bf16 v[182:185], v[28:31], v[104:107], v[8:11]
	v_mfma_f32_16x16x32_bf16 v[8:11], v[16:19], v[108:111], 0
	v_mfma_f32_16x16x32_bf16 v[186:189], v[20:23], v[116:119], v[8:11]
	v_mfma_f32_16x16x32_bf16 v[8:11], v[24:27], v[108:111], 0
	v_mfma_f32_16x16x32_bf16 v[190:193], v[28:31], v[116:119], v[8:11]
	v_mfma_f32_16x16x32_bf16 v[8:11], v[16:19], v[120:123], 0
	v_mfma_f32_16x16x32_bf16 v[194:197], v[20:23], v[124:127], v[8:11]
	v_mfma_f32_16x16x32_bf16 v[8:11], v[24:27], v[120:123], 0
	v_mfma_f32_16x16x32_bf16 v[198:201], v[28:31], v[124:127], v[8:11]
	s_barrier
	s_add_i32 s70, 0, 0x18000
	s_add_i32 s72, 0, 0x1c000
	v_add_u32_e32 v148, s70, v144
	v_add_u32_e32 v149, s72, v144
	s_nop 0
	ds_read_b128 v[8:11], v148
	ds_read_b128 v[12:15], v148 offset:1024
	ds_read_b128 v[16:19], v148 offset:2048
	ds_read_b128 v[20:23], v148 offset:3072
	ds_read_b128 v[202:205], v149
	ds_read_b128 v[206:209], v149 offset:1024
	ds_read_b128 v[210:213], v149 offset:2048
	ds_read_b128 v[214:217], v149 offset:3072
	s_add_u32 s38, s36, 0x80100
	s_addc_u32 s39, s37, 0
	s_mov_b32 m0, s49
	v_lshl_add_u64 v[88:89], s[38:39], 0, v[134:135]
	ds_read_b128 v[24:27], v147 offset:32768
	ds_read_b128 v[28:31], v147 offset:33792
	ds_read_b128 v[218:221], v147 offset:34816
	ds_read_b128 v[222:225], v147 offset:35840
	ds_read_b128 v[226:229], v147 offset:36864
	ds_read_b128 v[230:233], v147 offset:37888
	ds_read_b128 v[234:237], v147 offset:38912
	ds_read_b128 v[238:241], v147 offset:39936
	global_load_lds_dwordx4 v134, s[38:39]
	v_lshl_add_u64 v[88:89], s[38:39], 0, v[132:133]
	s_mov_b32 m0, s50
	s_nop 0
	global_load_lds_dwordx4 v132, s[38:39]
	s_waitcnt vmcnt(8) lgkmcnt(0)
	s_barrier
	v_mfma_f32_16x16x32_bf16 v[64:67], v[8:11], v[24:27], v[64:67]
	v_mfma_f32_16x16x32_bf16 v[120:123], v[12:15], v[28:31], v[64:67]
	v_mfma_f32_16x16x32_bf16 v[64:67], v[16:19], v[24:27], v[68:71]
	v_mfma_f32_16x16x32_bf16 v[124:127], v[20:23], v[28:31], v[64:67]
	v_mfma_f32_16x16x32_bf16 v[64:67], v[8:11], v[218:221], v[72:75]
	v_mfma_f32_16x16x32_bf16 v[104:107], v[12:15], v[222:225], v[64:67]
	v_mfma_f32_16x16x32_bf16 v[64:67], v[16:19], v[218:221], v[76:79]
	v_mfma_f32_16x16x32_bf16 v[108:111], v[20:23], v[222:225], v[64:67]
	v_mfma_f32_16x16x32_bf16 v[64:67], v[8:11], v[226:229], v[80:83]
	v_mfma_f32_16x16x32_bf16 v[88:91], v[12:15], v[230:233], v[64:67]
	v_mfma_f32_16x16x32_bf16 v[64:67], v[16:19], v[226:229], v[84:87]
	v_mfma_f32_16x16x32_bf16 v[92:95], v[20:23], v[230:233], v[64:67]
	v_mfma_f32_16x16x32_bf16 v[64:67], v[8:11], v[234:237], v[96:99]
	v_mfma_f32_16x16x32_bf16 v[68:71], v[16:19], v[234:237], v[100:103]
	v_mfma_f32_16x16x32_bf16 v[64:67], v[12:15], v[238:241], v[64:67]
	v_mfma_f32_16x16x32_bf16 v[68:71], v[20:23], v[238:241], v[68:71]
	v_mfma_f32_16x16x32_bf16 v[72:75], v[202:205], v[24:27], v[112:115]
	v_mfma_f32_16x16x32_bf16 v[24:27], v[210:213], v[24:27], v[32:35]
	v_mfma_f32_16x16x32_bf16 v[116:119], v[214:217], v[28:31], v[24:27]
	v_mfma_f32_16x16x32_bf16 v[24:27], v[202:205], v[218:221], v[36:39]
	v_mfma_f32_16x16x32_bf16 v[96:99], v[206:209], v[222:225], v[24:27]
	v_mfma_f32_16x16x32_bf16 v[24:27], v[210:213], v[218:221], v[40:43]
	v_mfma_f32_16x16x32_bf16 v[100:103], v[214:217], v[222:225], v[24:27]
	v_mfma_f32_16x16x32_bf16 v[24:27], v[202:205], v[226:229], v[44:47]
	v_mfma_f32_16x16x32_bf16 v[80:83], v[206:209], v[230:233], v[24:27]
	v_mfma_f32_16x16x32_bf16 v[24:27], v[210:213], v[226:229], v[48:51]
	v_mfma_f32_16x16x32_bf16 v[84:87], v[214:217], v[230:233], v[24:27]
	v_mfma_f32_16x16x32_bf16 v[24:27], v[202:205], v[234:237], v[52:55]
	v_mfma_f32_16x16x32_bf16 v[48:51], v[206:209], v[238:241], v[24:27]
	v_mfma_f32_16x16x32_bf16 v[24:27], v[210:213], v[234:237], v[56:59]
	v_mfma_f32_16x16x32_bf16 v[112:115], v[206:209], v[28:31], v[72:75]
	v_mfma_f32_16x16x32_bf16 v[52:55], v[214:217], v[238:241], v[24:27]
	s_barrier
	s_add_i32 s70, s70, s45
	s_add_i32 s71, s70, 0x2000
	s_nop 1
	v_lshl_add_u64 v[24:25], v[242:243], 0, s[14:15]
	s_mov_b32 m0, s70
	s_add_u32 s38, s26, 0x80180
	ds_read_b128 v[32:35], v147 offset:49152
	ds_read_b128 v[36:39], v147 offset:50176
	ds_read_b128 v[218:221], v147 offset:51200
	ds_read_b128 v[222:225], v147 offset:52224
	ds_read_b128 v[226:229], v147 offset:53248
	ds_read_b128 v[230:233], v147 offset:54272
	ds_read_b128 v[234:237], v147 offset:55296
	ds_read_b128 v[238:241], v147 offset:56320
	global_load_lds_dwordx4 v[24:25], off
	v_lshl_add_u64 v[24:25], v[244:245], 0, s[14:15]
	s_mov_b32 m0, s71
	s_addc_u32 s39, s27, 0
	s_add_i32 s72, s72, s45
	global_load_lds_dwordx4 v[24:25], off
	v_lshl_add_u64 v[24:25], s[38:39], 0, v[128:129]
	s_mov_b32 m0, s72
	s_add_i32 s73, s72, 0x2000
	global_load_lds_dwordx4 v128, s[38:39]
	v_lshl_add_u64 v[24:25], s[38:39], 0, v[130:131]
	s_mov_b32 m0, s73
	s_nop 0
	global_load_lds_dwordx4 v130, s[38:39]
	v_lshl_add_u64 v[24:25], v[246:247], 0, s[14:15]
	s_mov_b32 m0, s56
	s_nop 0
	global_load_lds_dwordx4 v[24:25], off
	v_lshl_add_u64 v[24:25], v[248:249], 0, s[14:15]
	s_mov_b32 m0, s57
	s_nop 0
	global_load_lds_dwordx4 v[24:25], off
	s_waitcnt vmcnt(8) lgkmcnt(0)
	s_barrier
	v_mfma_f32_16x16x32_bf16 v[24:27], v[8:11], v[32:35], v[150:153]
	v_mfma_f32_16x16x32_bf16 v[72:75], v[12:15], v[36:39], v[24:27]
	v_mfma_f32_16x16x32_bf16 v[24:27], v[16:19], v[32:35], v[154:157]
	v_mfma_f32_16x16x32_bf16 v[76:79], v[20:23], v[36:39], v[24:27]
	v_mfma_f32_16x16x32_bf16 v[24:27], v[8:11], v[218:221], v[158:161]
	v_mfma_f32_16x16x32_bf16 v[40:43], v[12:15], v[222:225], v[24:27]
	v_mfma_f32_16x16x32_bf16 v[24:27], v[16:19], v[218:221], v[162:165]
	v_mfma_f32_16x16x32_bf16 v[0:3], v[8:11], v[234:237], v[0:3]
	v_mfma_f32_16x16x32_bf16 v[44:47], v[20:23], v[222:225], v[24:27]
	v_mfma_f32_16x16x32_bf16 v[24:27], v[8:11], v[226:229], v[166:169]
	v_mfma_f32_16x16x32_bf16 v[28:31], v[16:19], v[226:229], v[170:173]
	v_mfma_f32_16x16x32_bf16 v[8:11], v[12:15], v[238:241], v[0:3]
	v_mfma_f32_16x16x32_bf16 v[0:3], v[16:19], v[234:237], v[4:7]
	v_mfma_f32_16x16x32_bf16 v[24:27], v[12:15], v[230:233], v[24:27]
	v_mfma_f32_16x16x32_bf16 v[28:31], v[20:23], v[230:233], v[28:31]
	v_mfma_f32_16x16x32_bf16 v[12:15], v[20:23], v[238:241], v[0:3]
	v_mfma_f32_16x16x32_bf16 v[0:3], v[202:205], v[32:35], v[174:177]
	v_mfma_f32_16x16x32_bf16 v[56:59], v[206:209], v[36:39], v[0:3]
	v_mfma_f32_16x16x32_bf16 v[0:3], v[210:213], v[32:35], v[60:63]
	v_mfma_f32_16x16x32_bf16 v[60:63], v[214:217], v[36:39], v[0:3]
	v_mfma_f32_16x16x32_bf16 v[0:3], v[202:205], v[218:221], v[178:181]
	v_mfma_f32_16x16x32_bf16 v[32:35], v[206:209], v[222:225], v[0:3]
	v_mfma_f32_16x16x32_bf16 v[0:3], v[210:213], v[218:221], v[182:185]
	v_mfma_f32_16x16x32_bf16 v[36:39], v[214:217], v[222:225], v[0:3]
	v_mfma_f32_16x16x32_bf16 v[0:3], v[202:205], v[226:229], v[186:189]
	v_mfma_f32_16x16x32_bf16 v[16:19], v[206:209], v[230:233], v[0:3]
	v_mfma_f32_16x16x32_bf16 v[0:3], v[210:213], v[226:229], v[190:193]
	v_mfma_f32_16x16x32_bf16 v[20:23], v[214:217], v[230:233], v[0:3]
	v_mfma_f32_16x16x32_bf16 v[0:3], v[202:205], v[234:237], v[194:197]
	v_mfma_f32_16x16x32_bf16 v[4:7], v[210:213], v[234:237], v[198:201]
	v_mfma_f32_16x16x32_bf16 v[0:3], v[206:209], v[238:241], v[0:3]
	v_mfma_f32_16x16x32_bf16 v[4:7], v[214:217], v[238:241], v[4:7]
	s_barrier
	s_add_u32 s74, s26, 0x200
	s_addc_u32 s75, s27, 0
	s_add_u32 s26, s36, 0x80180
	s_addc_u32 s27, s37, 0
	s_mov_b32 s76, 0
; template <class Epi, class Sched, bool ALIGN_EPI = false, bool SP2 = false, bool A_TILED = false>
; __device__ __forceinline__ void gemm_phase(PG8_LAS unsigned char* lds, const Gemm g, const Sched& S, const Epi& E, const int wave_s) {
;     ...
;         for (int t = PEEL ? 2 : 0; t < nt; t += 2) {
;             const bool last = (t == nt - 2);
;             const char* a1 = cA + (size_t)(t + 1) * kstepA;
;             const char* a2 = last ? nA : cA + (size_t)(t + 2) * kstepA; const char* b2 = last ? nB : cB + (size_t)(t + 2) * kstep;
;             const char* a3 = a2 + kstepA; const char* b3 = b2 + kstep;
;             if (last && has_next) S.a_ready(nxt);
.LBB0_3720:
	ds_read_b128 v[150:153], v145
	ds_read_b128 v[154:157], v145 offset:1024
	ds_read_b128 v[158:161], v145 offset:2048
	ds_read_b128 v[162:165], v145 offset:3072
	ds_read_b128 v[166:169], v146
	ds_read_b128 v[170:173], v146 offset:1024
	ds_read_b128 v[174:177], v146 offset:2048
	ds_read_b128 v[178:181], v146 offset:3072
	s_add_u32 s36, s26, 0xfff80080
	s_addc_u32 s37, s27, -1
	s_cmp_eq_u32 s76, 28
	s_cselect_b32 s39, s17, s37
	s_cselect_b32 s38, s19, s36
	s_cselect_b32 s37, s62, s75
	s_cselect_b32 s36, s63, s74
	s_mov_b32 m0, s64
	v_lshl_add_u64 v[214:215], s[26:27], 0, v[138:139]
	ds_read_b128 v[182:185], v147
	ds_read_b128 v[186:189], v147 offset:1024
	ds_read_b128 v[190:193], v147 offset:2048
	ds_read_b128 v[194:197], v147 offset:3072
	ds_read_b128 v[198:201], v147 offset:4096
	ds_read_b128 v[202:205], v147 offset:5120
	ds_read_b128 v[206:209], v147 offset:6144
	ds_read_b128 v[210:213], v147 offset:7168
	global_load_lds_dwordx4 v138, s[26:27]
	v_lshl_add_u64 v[214:215], s[26:27], 0, v[136:137]
	s_mov_b32 m0, s65
	s_nop 0
	global_load_lds_dwordx4 v136, s[26:27]
	s_waitcnt vmcnt(8) lgkmcnt(0)
	s_barrier
	v_mfma_f32_16x16x32_bf16 v[120:123], v[150:153], v[182:185], v[120:123]
	v_mfma_f32_16x16x32_bf16 v[124:127], v[158:161], v[182:185], v[124:127]
	v_mfma_f32_16x16x32_bf16 v[104:107], v[150:153], v[190:193], v[104:107]
	v_mfma_f32_16x16x32_bf16 v[108:111], v[158:161], v[190:193], v[108:111]
	v_mfma_f32_16x16x32_bf16 v[88:91], v[150:153], v[198:201], v[88:91]
	v_mfma_f32_16x16x32_bf16 v[92:95], v[158:161], v[198:201], v[92:95]
	v_mfma_f32_16x16x32_bf16 v[64:67], v[150:153], v[206:209], v[64:67]
	v_mfma_f32_16x16x32_bf16 v[68:71], v[158:161], v[206:209], v[68:71]
	v_mfma_f32_16x16x32_bf16 v[120:123], v[154:157], v[186:189], v[120:123]
	v_mfma_f32_16x16x32_bf16 v[124:127], v[162:165], v[186:189], v[124:127]
	v_mfma_f32_16x16x32_bf16 v[104:107], v[154:157], v[194:197], v[104:107]
	v_mfma_f32_16x16x32_bf16 v[108:111], v[162:165], v[194:197], v[108:111]
	v_mfma_f32_16x16x32_bf16 v[88:91], v[154:157], v[202:205], v[88:91]
	v_mfma_f32_16x16x32_bf16 v[92:95], v[162:165], v[202:205], v[92:95]
	v_mfma_f32_16x16x32_bf16 v[64:67], v[154:157], v[210:213], v[64:67]
	v_mfma_f32_16x16x32_bf16 v[68:71], v[162:165], v[210:213], v[68:71]
	v_mfma_f32_16x16x32_bf16 v[112:115], v[166:169], v[182:185], v[112:115]
	v_mfma_f32_16x16x32_bf16 v[116:119], v[174:177], v[182:185], v[116:119]
	v_mfma_f32_16x16x32_bf16 v[96:99], v[166:169], v[190:193], v[96:99]
	v_mfma_f32_16x16x32_bf16 v[100:103], v[174:177], v[190:193], v[100:103]
	v_mfma_f32_16x16x32_bf16 v[80:83], v[166:169], v[198:201], v[80:83]
	v_mfma_f32_16x16x32_bf16 v[84:87], v[174:177], v[198:201], v[84:87]
	v_mfma_f32_16x16x32_bf16 v[48:51], v[166:169], v[206:209], v[48:51]
	v_mfma_f32_16x16x32_bf16 v[52:55], v[174:177], v[206:209], v[52:55]
	v_mfma_f32_16x16x32_bf16 v[112:115], v[170:173], v[186:189], v[112:115]
	v_mfma_f32_16x16x32_bf16 v[116:119], v[178:181], v[186:189], v[116:119]
	v_mfma_f32_16x16x32_bf16 v[96:99], v[170:173], v[194:197], v[96:99]
	v_mfma_f32_16x16x32_bf16 v[100:103], v[178:181], v[194:197], v[100:103]
	v_mfma_f32_16x16x32_bf16 v[80:83], v[170:173], v[202:205], v[80:83]
	v_mfma_f32_16x16x32_bf16 v[84:87], v[178:181], v[202:205], v[84:87]
	v_mfma_f32_16x16x32_bf16 v[48:51], v[170:173], v[210:213], v[48:51]
	v_mfma_f32_16x16x32_bf16 v[52:55], v[178:181], v[210:213], v[52:55]
	s_barrier
	s_mov_b32 m0, s66
	v_lshl_add_u64 v[214:215], s[36:37], 0, v[128:129]
	s_add_u32 s78, s36, 0x80000
	ds_read_b128 v[182:185], v147 offset:16384
	ds_read_b128 v[186:189], v147 offset:17408
	ds_read_b128 v[190:193], v147 offset:18432
	ds_read_b128 v[194:197], v147 offset:19456
	ds_read_b128 v[198:201], v147 offset:20480
	ds_read_b128 v[202:205], v147 offset:21504
	ds_read_b128 v[206:209], v147 offset:22528
	ds_read_b128 v[210:213], v147 offset:23552
	global_load_lds_dwordx4 v128, s[36:37]
	v_lshl_add_u64 v[216:217], s[36:37], 0, v[130:131]
	s_mov_b32 m0, s67
	s_addc_u32 s79, s37, 0
	global_load_lds_dwordx4 v130, s[36:37]
	v_lshl_add_u64 v[218:219], s[78:79], 0, v[128:129]
	s_mov_b32 m0, s68
	v_lshl_add_u64 v[220:221], s[38:39], 0, v[132:133]
	global_load_lds_dwordx4 v128, s[78:79]
	v_lshl_add_u64 v[218:219], s[78:79], 0, v[130:131]
	s_mov_b32 m0, s69
	s_nop 0
	global_load_lds_dwordx4 v130, s[78:79]
	v_lshl_add_u64 v[218:219], s[38:39], 0, v[134:135]
	s_mov_b32 m0, s47
	s_nop 0
	global_load_lds_dwordx4 v134, s[38:39]
	s_mov_b32 m0, s48
	s_nop 0
	global_load_lds_dwordx4 v132, s[38:39]
	s_waitcnt vmcnt(8) lgkmcnt(0)
	s_barrier
	v_mfma_f32_16x16x32_bf16 v[72:75], v[150:153], v[182:185], v[72:75]
	v_mfma_f32_16x16x32_bf16 v[76:79], v[158:161], v[182:185], v[76:79]
	v_mfma_f32_16x16x32_bf16 v[40:43], v[150:153], v[190:193], v[40:43]
	v_mfma_f32_16x16x32_bf16 v[44:47], v[158:161], v[190:193], v[44:47]
	v_mfma_f32_16x16x32_bf16 v[24:27], v[150:153], v[198:201], v[24:27]
	v_mfma_f32_16x16x32_bf16 v[28:31], v[158:161], v[198:201], v[28:31]
	v_mfma_f32_16x16x32_bf16 v[8:11], v[150:153], v[206:209], v[8:11]
	v_mfma_f32_16x16x32_bf16 v[12:15], v[158:161], v[206:209], v[12:15]
	v_mfma_f32_16x16x32_bf16 v[72:75], v[154:157], v[186:189], v[72:75]
	v_mfma_f32_16x16x32_bf16 v[76:79], v[162:165], v[186:189], v[76:79]
	v_mfma_f32_16x16x32_bf16 v[40:43], v[154:157], v[194:197], v[40:43]
	v_mfma_f32_16x16x32_bf16 v[44:47], v[162:165], v[194:197], v[44:47]
	v_mfma_f32_16x16x32_bf16 v[24:27], v[154:157], v[202:205], v[24:27]
	v_mfma_f32_16x16x32_bf16 v[28:31], v[162:165], v[202:205], v[28:31]
	v_mfma_f32_16x16x32_bf16 v[8:11], v[154:157], v[210:213], v[8:11]
	v_mfma_f32_16x16x32_bf16 v[12:15], v[162:165], v[210:213], v[12:15]
	v_mfma_f32_16x16x32_bf16 v[56:59], v[166:169], v[182:185], v[56:59]
	v_mfma_f32_16x16x32_bf16 v[60:63], v[174:177], v[182:185], v[60:63]
	v_mfma_f32_16x16x32_bf16 v[32:35], v[166:169], v[190:193], v[32:35]
	v_mfma_f32_16x16x32_bf16 v[36:39], v[174:177], v[190:193], v[36:39]
	v_mfma_f32_16x16x32_bf16 v[16:19], v[166:169], v[198:201], v[16:19]
	v_mfma_f32_16x16x32_bf16 v[20:23], v[174:177], v[198:201], v[20:23]
	v_mfma_f32_16x16x32_bf16 v[0:3], v[166:169], v[206:209], v[0:3]
	v_mfma_f32_16x16x32_bf16 v[4:7], v[174:177], v[206:209], v[4:7]
	v_mfma_f32_16x16x32_bf16 v[56:59], v[170:173], v[186:189], v[56:59]
	v_mfma_f32_16x16x32_bf16 v[60:63], v[178:181], v[186:189], v[60:63]
	v_mfma_f32_16x16x32_bf16 v[32:35], v[170:173], v[194:197], v[32:35]
	v_mfma_f32_16x16x32_bf16 v[36:39], v[178:181], v[194:197], v[36:39]
	v_mfma_f32_16x16x32_bf16 v[16:19], v[170:173], v[202:205], v[16:19]
	v_mfma_f32_16x16x32_bf16 v[20:23], v[178:181], v[202:205], v[20:23]
	v_mfma_f32_16x16x32_bf16 v[0:3], v[170:173], v[210:213], v[0:3]
	v_mfma_f32_16x16x32_bf16 v[4:7], v[178:181], v[210:213], v[4:7]
	s_barrier
	ds_read_b128 v[150:153], v148
	ds_read_b128 v[154:157], v148 offset:1024
	ds_read_b128 v[158:161], v148 offset:2048
	ds_read_b128 v[162:165], v148 offset:3072
	ds_read_b128 v[166:169], v149
	ds_read_b128 v[170:173], v149 offset:1024
	ds_read_b128 v[174:177], v149 offset:2048
	ds_read_b128 v[178:181], v149 offset:3072
	s_add_u32 s38, s38, 0x80000
	s_addc_u32 s39, s39, 0
	s_mov_b32 m0, s49
	v_lshl_add_u64 v[222:223], s[38:39], 0, v[134:135]
	ds_read_b128 v[182:185], v147 offset:32768
	ds_read_b128 v[186:189], v147 offset:33792
	ds_read_b128 v[190:193], v147 offset:34816
	ds_read_b128 v[194:197], v147 offset:35840
	ds_read_b128 v[198:201], v147 offset:36864
	ds_read_b128 v[202:205], v147 offset:37888
	ds_read_b128 v[206:209], v147 offset:38912
	ds_read_b128 v[210:213], v147 offset:39936
	global_load_lds_dwordx4 v134, s[38:39]
	v_lshl_add_u64 v[222:223], s[38:39], 0, v[132:133]
	s_mov_b32 m0, s50
	s_nop 0
	global_load_lds_dwordx4 v132, s[38:39]
	s_waitcnt vmcnt(8) lgkmcnt(0)
	s_barrier
	v_mfma_f32_16x16x32_bf16 v[120:123], v[150:153], v[182:185], v[120:123]
	v_mfma_f32_16x16x32_bf16 v[124:127], v[158:161], v[182:185], v[124:127]
	v_mfma_f32_16x16x32_bf16 v[104:107], v[150:153], v[190:193], v[104:107]
	v_mfma_f32_16x16x32_bf16 v[108:111], v[158:161], v[190:193], v[108:111]
	v_mfma_f32_16x16x32_bf16 v[88:91], v[150:153], v[198:201], v[88:91]
	v_mfma_f32_16x16x32_bf16 v[92:95], v[158:161], v[198:201], v[92:95]
	v_mfma_f32_16x16x32_bf16 v[64:67], v[150:153], v[206:209], v[64:67]
	v_mfma_f32_16x16x32_bf16 v[68:71], v[158:161], v[206:209], v[68:71]
	v_mfma_f32_16x16x32_bf16 v[120:123], v[154:157], v[186:189], v[120:123]
	v_mfma_f32_16x16x32_bf16 v[124:127], v[162:165], v[186:189], v[124:127]
	v_mfma_f32_16x16x32_bf16 v[104:107], v[154:157], v[194:197], v[104:107]
	v_mfma_f32_16x16x32_bf16 v[108:111], v[162:165], v[194:197], v[108:111]
	v_mfma_f32_16x16x32_bf16 v[88:91], v[154:157], v[202:205], v[88:91]
	v_mfma_f32_16x16x32_bf16 v[92:95], v[162:165], v[202:205], v[92:95]
	v_mfma_f32_16x16x32_bf16 v[64:67], v[154:157], v[210:213], v[64:67]
	v_mfma_f32_16x16x32_bf16 v[68:71], v[162:165], v[210:213], v[68:71]
	v_mfma_f32_16x16x32_bf16 v[112:115], v[166:169], v[182:185], v[112:115]
	v_mfma_f32_16x16x32_bf16 v[116:119], v[174:177], v[182:185], v[116:119]
	v_mfma_f32_16x16x32_bf16 v[96:99], v[166:169], v[190:193], v[96:99]
	v_mfma_f32_16x16x32_bf16 v[100:103], v[174:177], v[190:193], v[100:103]
	v_mfma_f32_16x16x32_bf16 v[80:83], v[166:169], v[198:201], v[80:83]
	v_mfma_f32_16x16x32_bf16 v[84:87], v[174:177], v[198:201], v[84:87]
	v_mfma_f32_16x16x32_bf16 v[48:51], v[166:169], v[206:209], v[48:51]
	v_mfma_f32_16x16x32_bf16 v[52:55], v[174:177], v[206:209], v[52:55]
	v_mfma_f32_16x16x32_bf16 v[112:115], v[170:173], v[186:189], v[112:115]
	v_mfma_f32_16x16x32_bf16 v[116:119], v[178:181], v[186:189], v[116:119]
	v_mfma_f32_16x16x32_bf16 v[96:99], v[170:173], v[194:197], v[96:99]
	v_mfma_f32_16x16x32_bf16 v[100:103], v[178:181], v[194:197], v[100:103]
	v_mfma_f32_16x16x32_bf16 v[80:83], v[170:173], v[202:205], v[80:83]
	v_mfma_f32_16x16x32_bf16 v[84:87], v[178:181], v[202:205], v[84:87]
	v_mfma_f32_16x16x32_bf16 v[48:51], v[170:173], v[210:213], v[48:51]
	v_mfma_f32_16x16x32_bf16 v[52:55], v[178:181], v[210:213], v[52:55]
	s_barrier
; template <class Epi, class Sched, bool ALIGN_EPI = false, bool SP2 = false, bool A_TILED = false>
; __device__ __forceinline__ void gemm_phase(PG8_LAS unsigned char* lds, const Gemm g, const Sched& S, const Epi& E, const int wave_s) {
;     ...
;         for (int t = PEEL ? 2 : 0; t < nt; t += 2) {
;             const bool last = (t == nt - 2);
;             const char* a1 = cA + (size_t)(t + 1) * kstepA;
	s_mov_b32 m0, s70
	v_lshl_add_u64 v[214:215], v[214:215], 0, s[6:7]
	s_add_u32 s36, s36, 0x80080
	ds_read_b128 v[182:185], v147 offset:49152
	ds_read_b128 v[186:189], v147 offset:50176
	ds_read_b128 v[190:193], v147 offset:51200
	ds_read_b128 v[194:197], v147 offset:52224
	ds_read_b128 v[198:201], v147 offset:53248
	ds_read_b128 v[202:205], v147 offset:54272
	ds_read_b128 v[206:209], v147 offset:55296
	ds_read_b128 v[210:213], v147 offset:56320
	global_load_lds_dwordx4 v[214:215], off
	v_lshl_add_u64 v[214:215], v[216:217], 0, s[6:7]
	s_mov_b32 m0, s71
	s_addc_u32 s37, s37, 0
	global_load_lds_dwordx4 v[214:215], off
	v_lshl_add_u64 v[214:215], s[36:37], 0, v[128:129]
	s_mov_b32 m0, s72
	s_nop 0
	global_load_lds_dwordx4 v128, s[36:37]
	v_lshl_add_u64 v[214:215], s[36:37], 0, v[130:131]
	s_mov_b32 m0, s73
	s_nop 0
	global_load_lds_dwordx4 v130, s[36:37]
	v_lshl_add_u64 v[214:215], v[218:219], 0, s[6:7]
	s_mov_b32 m0, s56
	s_nop 0
	global_load_lds_dwordx4 v[214:215], off
	v_lshl_add_u64 v[214:215], v[220:221], 0, s[6:7]
	s_mov_b32 m0, s57
	s_nop 0
	global_load_lds_dwordx4 v[214:215], off
	s_waitcnt vmcnt(8) lgkmcnt(0)
	s_barrier
	v_mfma_f32_16x16x32_bf16 v[72:75], v[150:153], v[182:185], v[72:75]
	v_mfma_f32_16x16x32_bf16 v[76:79], v[158:161], v[182:185], v[76:79]
	v_mfma_f32_16x16x32_bf16 v[40:43], v[150:153], v[190:193], v[40:43]
	v_mfma_f32_16x16x32_bf16 v[44:47], v[158:161], v[190:193], v[44:47]
	v_mfma_f32_16x16x32_bf16 v[24:27], v[150:153], v[198:201], v[24:27]
	v_mfma_f32_16x16x32_bf16 v[28:31], v[158:161], v[198:201], v[28:31]
	v_mfma_f32_16x16x32_bf16 v[8:11], v[150:153], v[206:209], v[8:11]
	v_mfma_f32_16x16x32_bf16 v[12:15], v[158:161], v[206:209], v[12:15]
	v_mfma_f32_16x16x32_bf16 v[72:75], v[154:157], v[186:189], v[72:75]
	v_mfma_f32_16x16x32_bf16 v[76:79], v[162:165], v[186:189], v[76:79]
	v_mfma_f32_16x16x32_bf16 v[40:43], v[154:157], v[194:197], v[40:43]
	v_mfma_f32_16x16x32_bf16 v[44:47], v[162:165], v[194:197], v[44:47]
	v_mfma_f32_16x16x32_bf16 v[24:27], v[154:157], v[202:205], v[24:27]
	v_mfma_f32_16x16x32_bf16 v[28:31], v[162:165], v[202:205], v[28:31]
	v_mfma_f32_16x16x32_bf16 v[8:11], v[154:157], v[210:213], v[8:11]
	v_mfma_f32_16x16x32_bf16 v[12:15], v[162:165], v[210:213], v[12:15]
	v_mfma_f32_16x16x32_bf16 v[56:59], v[166:169], v[182:185], v[56:59]
	v_mfma_f32_16x16x32_bf16 v[60:63], v[174:177], v[182:185], v[60:63]
	v_mfma_f32_16x16x32_bf16 v[32:35], v[166:169], v[190:193], v[32:35]
	v_mfma_f32_16x16x32_bf16 v[36:39], v[174:177], v[190:193], v[36:39]
	v_mfma_f32_16x16x32_bf16 v[16:19], v[166:169], v[198:201], v[16:19]
	v_mfma_f32_16x16x32_bf16 v[20:23], v[174:177], v[198:201], v[20:23]
	v_mfma_f32_16x16x32_bf16 v[0:3], v[166:169], v[206:209], v[0:3]
	v_mfma_f32_16x16x32_bf16 v[4:7], v[174:177], v[206:209], v[4:7]
	v_mfma_f32_16x16x32_bf16 v[56:59], v[170:173], v[186:189], v[56:59]
	v_mfma_f32_16x16x32_bf16 v[60:63], v[178:181], v[186:189], v[60:63]
	v_mfma_f32_16x16x32_bf16 v[32:35], v[170:173], v[194:197], v[32:35]
	v_mfma_f32_16x16x32_bf16 v[36:39], v[178:181], v[194:197], v[36:39]
	v_mfma_f32_16x16x32_bf16 v[16:19], v[170:173], v[202:205], v[16:19]
	v_mfma_f32_16x16x32_bf16 v[20:23], v[178:181], v[202:205], v[20:23]
	v_mfma_f32_16x16x32_bf16 v[0:3], v[170:173], v[210:213], v[0:3]
	v_mfma_f32_16x16x32_bf16 v[4:7], v[178:181], v[210:213], v[4:7]
	s_barrier
	s_add_i32 s76, s76, 2
	s_add_u32 s74, s74, 0x100
	s_addc_u32 s75, s75, 0
	s_add_u32 s26, s26, 0x100
	s_addc_u32 s27, s27, 0
	s_cmp_gt_u32 s76, 29
	s_cbranch_scc0 .LBB0_3720
	s_and_b64 vcc, exec, s[8:9]
	s_cbranch_vccz .LBB0_3723
	s_barrier

; __device__ __forceinline__ int tid_now(int wave_s) { unsigned z = 0u; asm volatile("" : "+v"(z)); return (wave_s << 6) | (int)__builtin_amdgcn_mbcnt_hi(~0u, __builtin_amdgcn_mbcnt_lo(~0u, z)); }
; __device__ __forceinline__ unsigned xb_add(unsigned* p, unsigned v) { return __hip_atomic_fetch_add(p, v, __ATOMIC_RELAXED, __HIP_MEMORY_SCOPE_AGENT); }
; __device__ __forceinline__ void xcd_barrier(const XcdBarrier& b) {
;     asm volatile("s_waitcnt vmcnt(0)" ::: "memory");
;     __syncthreads();
;     if (tid_now(b.w) == 0) {
;         unsigned* bar = b.bar;
;         __builtin_amdgcn_s_waitcnt(0);
;         unsigned nloc = b.st[0], nx = b.st[1];
;         if (nloc == 0u) { xcd_barrier_complete(bar, b.x, nloc, nx, b.np); b.st[0] = nloc; b.st[1] = nx; }
;         const unsigned old = xb_add(&bar[XB_XSUB(b.x)], 1u);
.LBB0_3727:
	s_setprio 0
	s_cmp_gt_i32 s35, 24
	s_cselect_b64 s[0:1], -1, 0
	s_and_b64 s[2:3], s[2:3], s[0:1]
	s_andn2_b64 vcc, exec, s[2:3]
	s_cbranch_vccnz .LBB0_3781
	s_waitcnt vmcnt(0)
	v_mov_b32_e32 v0, 0
	s_waitcnt vmcnt(0)
	s_waitcnt lgkmcnt(0)
	s_barrier
	s_nop 0
	v_mbcnt_lo_u32_b32 v0, -1, v0
	v_mbcnt_hi_u32_b32 v0, -1, v0
	v_or_b32_e32 v0, s33, v0
	v_cmp_eq_u32_e32 vcc, 0, v0
	s_and_saveexec_b64 s[2:3], vcc
	s_cbranch_execz .LBB0_3780
	s_add_i32 s4, 0, 0x27f68
	v_mov_b32_e32 v0, s4
	s_waitcnt vmcnt(0) expcnt(0) lgkmcnt(0)
	ds_read_b32 v2, v0
	s_add_i32 s4, 0, 0x27f6c
	v_mov_b32_e32 v0, s4
	ds_read_b32 v0, v0
	s_waitcnt lgkmcnt(1)
	v_cmp_ne_u32_e32 vcc, 0, v2
	s_cbranch_vccnz .LBB0_3744
	s_add_u32 s4, s10, 0x1000
	s_addc_u32 s5, s11, 0
	s_add_u32 s6, s10, 0x1100
	s_addc_u32 s7, s11, 0
	s_add_u32 s8, s10, 0x1200
	s_addc_u32 s9, s11, 0
	s_add_u32 s12, s10, 0x1300
	s_addc_u32 s13, s11, 0
	s_mov_b32 s20, 1
	v_mov_b32_e32 v16, 0
	s_branch .LBB0_3732

; #define PG8_STAGE(bufoff, gbase, voff) do { _Pragma("unroll") for (int _i = 0; _i < 2; ++_i) \
;         __builtin_amdgcn_global_load_lds((const unsigned*)((const char*)(gbase) + (voff)[_i]), (PG8_LAS unsigned*)(lds + (bufoff) + ldsw + _i * 8192), 16, 0, 0); } while (0)
; #define PG8_WAIT_V(n) asm volatile("s_waitcnt vmcnt(" #n ")" ::: "memory")
; #define PG8_BAR __builtin_amdgcn_s_barrier()
; template <class Epi, class Sched, bool ALIGN_EPI = false, bool SP2 = false, bool A_TILED = false>
; __device__ __forceinline__ void gemm_phase(PG8_LAS unsigned char* lds, const Gemm g, const Sched& S, const Epi& E, const int wave_s) {
;     ...
;         PG8_STAGE(PG8_SB(0, 0), cB, voffB); PG8_STAGE(PG8_SB(0, 1), cB + hstep, voffB); PG8_STAGE(PG8_SA(0, 0), cA, voffA); PG8_STAGE(PG8_SA(0, 1), cA + hstepA, voffA);
;         if (wr == 1) PG8_BAR;
;         PG8_WAIT_V(2); PG8_BAR;
;         PG8_STAGE(PG8_SB(1, 0), cB + kstep, voffB); PG8_STAGE(PG8_SA(1, 0), cA + kstepA, voffA); PG8_STAGE(PG8_SB(1, 1), cB + hstep + kstep, voffB);
;         PG8_WAIT_V(6); PG8_BAR;
;     } else {
;         PG8_STAGE(PG8_SB(0, 0), cB, voffB); PG8_STAGE(PG8_SA(0, 0), cA, voffA); PG8_STAGE(PG8_SB(0, 1), cB + hstep, voffB); PG8_STAGE(PG8_SA(0, 1), cA + hstepA, voffA);
;         if (wr == 1) PG8_BAR;
;         PG8_WAIT_V(4); PG8_BAR;
;         PG8_STAGE(PG8_SB(1, 0), cB + kstep, voffB); PG8_STAGE(PG8_SA(1, 0), cA + kstepA, voffA); PG8_STAGE(PG8_SB(1, 1), cB + hstep + kstep, voffB);
;         PG8_WAIT_V(6); PG8_BAR;
;     }
;     for (;;) {
;         const bool has_next = Epi::AFTER_DRAIN ? false : S.next(ui + 1, nxt);
;         const char* nA = has_next ? (const char*)g.A + (size_t)nxt.pm * tstepA : cA; const char* nB = has_next ? (const char*)g.Bt + (size_t)nxt.pn * tstep : cB;
;         constexpr bool PEEL = SP2 && !Epi::AFTER_DRAIN;
;         if constexpr (PEEL) {
;             const char* a1 = cA + kstepA; const char* a2 = cA + 2 * kstepA; const char* b2 = cB + 2 * kstep; const char* a3 = a2 + kstepA; const char* b3 = b2 + kstep;
;             PG8_ITER(PG8_MMAZ)
;         } else {
; #pragma unroll
;             for (int a = 0; a < 2; ++a)
; #pragma unroll
;                 for (int b = 0; b < 2; ++b)
; #pragma unroll
;                     for (int m = 0; m < 4; ++m)
; #pragma unroll
;                         for (int n = 0; n < 2; ++n) acc[a][b][m][n] = (f32x4){0.f, 0.f, 0.f, 0.f};
.LBB0_3792:
	v_and_b32_e32 v5, 48, v4
	v_lshlrev_b32_e32 v6, 6, v4
	s_movk_i32 s13, 0x3c0
	v_lshlrev_b32_e32 v4, 2, v4
	s_and_b32 s24, s23, 3
	s_lshl_b32 s9, s12, 6
	s_lshl_b32 s12, s12, 13
	v_and_or_b32 v5, v6, s13, v5
	v_and_b32_e32 v4, 32, v4
	v_bitop3_b32 v6, v5, s12, v4 bitop3:0xde
	s_lshl_b32 s12, s24, 12
	v_bitop3_b32 v4, v5, s12, v4 bitop3:0xde
	s_mov_b64 s[12:13], 0x80
	s_add_i32 m0, s25, 0x18000
	v_lshl_add_u64 v[2:3], v[2:3], 0, s[12:13]
	s_waitcnt vmcnt(2)
	s_barrier
	global_load_lds_dwordx4 v[2:3], off
	s_add_i32 m0, s25, 0x1a000
	s_add_u32 s20, s4, 0x8000
	v_lshl_add_u64 v[0:1], v[0:1], 0, s[12:13]
	s_addc_u32 s21, s5, 0
	s_add_i32 s36, s25, 0x8000
	global_load_lds_dwordx4 v[0:1], off
	v_lshl_add_u64 v[0:1], s[20:21], 0, v[128:129]
	s_mov_b32 m0, s36
	s_add_i32 s37, s25, 0xa000
	global_load_lds_dwordx4 v128, s[20:21]
	v_lshl_add_u64 v[0:1], s[20:21], 0, v[132:133]
	s_add_u32 s20, s0, 0x200080
	s_mov_b32 m0, s37
	s_addc_u32 s21, s1, 0
	global_load_lds_dwordx4 v[0:1], off
	s_add_i32 m0, s25, 0x1c000
	v_lshl_add_u64 v[0:1], s[20:21], 0, v[130:131]
	global_load_lds_dwordx4 v130, s[20:21]
	v_lshl_add_u64 v[0:1], s[20:21], 0, v[134:135]
	s_add_i32 m0, s25, 0x1e000
	s_add_u32 s38, s16, 0x18600100
	global_load_lds_dwordx4 v134, s[20:21]
	s_addc_u32 s39, s17, 0
	s_add_u32 s40, s14, 0x34610000
	s_waitcnt vmcnt(6)
	v_lshl_add_u64 v[0:1], s[14:15], 0, v[132:133]
	s_mov_b64 s[16:17], 0x3460c000
	s_addc_u32 s41, s15, 0
	s_bitcmp1_b32 s33, 8
	s_cbranch_scc1 .Lsp_18
	s_setprio 1
.Lsp_18:
	s_add_i32 s45, 0, 0x10000
	s_add_i32 s47, 0, 0x14000
	s_add_i32 s49, 0, 0x18000
	s_add_i32 s51, 0, 0x1c000
	v_lshl_add_u64 v[136:137], v[0:1], 0, s[16:17]
	v_lshl_add_u64 v[0:1], s[14:15], 0, v[128:129]
	v_add_u32_e32 v140, s45, v4
	v_add_u32_e32 v141, s47, v4
	s_add_i32 s45, s45, s18
	s_add_i32 s47, s47, s18
	v_add_u32_e32 v143, s49, v4
	v_add_u32_e32 v144, s51, v4
	s_add_i32 s49, s49, s18
	s_add_i32 s51, s51, s18
	v_readlane_b32 s56, v254, 43
	v_lshl_add_u64 v[138:139], v[0:1], 0, s[16:17]
	s_mov_b32 s42, -2
	v_add_u32_e32 v142, 0, v6
	s_add_i32 s43, s25, 0xc000
	s_add_i32 s44, s25, 0xe000
	s_add_i32 s46, s45, 0x2000
	s_add_i32 s48, s47, 0x2000
	s_add_i32 s50, s49, 0x2000
	s_add_i32 s52, s51, 0x2000
	s_mov_b64 s[14:15], 0x10000
	v_mov_b32_e32 v0, v131
	v_mov_b32_e32 v1, v131
	v_mov_b32_e32 v2, v131
	v_mov_b32_e32 v3, v131
	v_mov_b32_e32 v4, v131
	v_mov_b32_e32 v5, v131
	v_mov_b32_e32 v6, v131
	v_mov_b32_e32 v7, v131
	v_mov_b32_e32 v16, v131
	v_mov_b32_e32 v17, v131
	v_mov_b32_e32 v18, v131
	v_mov_b32_e32 v19, v131
	v_mov_b32_e32 v20, v131
	v_mov_b32_e32 v21, v131
	v_mov_b32_e32 v22, v131
	v_mov_b32_e32 v23, v131
	v_mov_b32_e32 v48, v131
	v_mov_b32_e32 v49, v131
	v_mov_b32_e32 v50, v131
	v_mov_b32_e32 v51, v131
	v_mov_b32_e32 v52, v131
	v_mov_b32_e32 v53, v131
	v_mov_b32_e32 v54, v131
	v_mov_b32_e32 v55, v131
	v_mov_b32_e32 v112, v131
	v_mov_b32_e32 v113, v131
	v_mov_b32_e32 v114, v131
	v_mov_b32_e32 v115, v131
	v_mov_b32_e32 v116, v131
	v_mov_b32_e32 v117, v131
	v_mov_b32_e32 v118, v131
	v_mov_b32_e32 v119, v131
	v_mov_b32_e32 v8, v131
	v_mov_b32_e32 v9, v131
	v_mov_b32_e32 v10, v131
	v_mov_b32_e32 v11, v131
	v_mov_b32_e32 v12, v131
	v_mov_b32_e32 v13, v131
	v_mov_b32_e32 v14, v131
	v_mov_b32_e32 v15, v131
	v_mov_b32_e32 v24, v131
	v_mov_b32_e32 v25, v131
	v_mov_b32_e32 v26, v131
	v_mov_b32_e32 v27, v131
	v_mov_b32_e32 v28, v131
	v_mov_b32_e32 v29, v131
	v_mov_b32_e32 v30, v131
	v_mov_b32_e32 v31, v131
	v_mov_b32_e32 v72, v131
	v_mov_b32_e32 v73, v131
	v_mov_b32_e32 v74, v131
	v_mov_b32_e32 v75, v131
	v_mov_b32_e32 v88, v131
	v_mov_b32_e32 v89, v131
	v_mov_b32_e32 v90, v131
	v_mov_b32_e32 v91, v131
	v_mov_b32_e32 v120, v131
	v_mov_b32_e32 v121, v131
	v_mov_b32_e32 v122, v131
	v_mov_b32_e32 v123, v131
	v_mov_b32_e32 v124, v131
	v_mov_b32_e32 v125, v131
	v_mov_b32_e32 v126, v131
	v_mov_b32_e32 v127, v131
	v_mov_b32_e32 v96, v131
	v_mov_b32_e32 v97, v131
	v_mov_b32_e32 v98, v131
	v_mov_b32_e32 v99, v131
	v_mov_b32_e32 v100, v131
	v_mov_b32_e32 v101, v131
	v_mov_b32_e32 v102, v131
	v_mov_b32_e32 v103, v131
	v_mov_b32_e32 v56, v131
	v_mov_b32_e32 v57, v131
	v_mov_b32_e32 v58, v131
	v_mov_b32_e32 v59, v131
	v_mov_b32_e32 v60, v131
	v_mov_b32_e32 v61, v131
	v_mov_b32_e32 v62, v131
	v_mov_b32_e32 v63, v131
	v_mov_b32_e32 v64, v131
	v_mov_b32_e32 v65, v131
	v_mov_b32_e32 v66, v131
	v_mov_b32_e32 v67, v131
	v_mov_b32_e32 v68, v131
	v_mov_b32_e32 v69, v131
	v_mov_b32_e32 v70, v131
	v_mov_b32_e32 v71, v131
	v_mov_b32_e32 v44, v131
	v_mov_b32_e32 v45, v131
	v_mov_b32_e32 v46, v131
	v_mov_b32_e32 v47, v131
	v_mov_b32_e32 v40, v131
	v_mov_b32_e32 v41, v131
	v_mov_b32_e32 v42, v131
	v_mov_b32_e32 v43, v131
	v_mov_b32_e32 v104, v131
	v_mov_b32_e32 v105, v131
	v_mov_b32_e32 v106, v131
	v_mov_b32_e32 v107, v131
	v_mov_b32_e32 v108, v131
	v_mov_b32_e32 v109, v131
	v_mov_b32_e32 v110, v131
	v_mov_b32_e32 v111, v131
	v_mov_b32_e32 v84, v131
	v_mov_b32_e32 v85, v131
	v_mov_b32_e32 v86, v131
	v_mov_b32_e32 v87, v131
	v_mov_b32_e32 v92, v131
	v_mov_b32_e32 v93, v131
	v_mov_b32_e32 v94, v131
	v_mov_b32_e32 v95, v131
	v_mov_b32_e32 v80, v131
	v_mov_b32_e32 v81, v131
	v_mov_b32_e32 v82, v131
	v_mov_b32_e32 v83, v131
	v_mov_b32_e32 v76, v131
	v_mov_b32_e32 v77, v131
	v_mov_b32_e32 v78, v131
	v_mov_b32_e32 v79, v131
	v_mov_b32_e32 v36, v131
	v_mov_b32_e32 v37, v131
	v_mov_b32_e32 v38, v131
	v_mov_b32_e32 v39, v131
	v_mov_b32_e32 v32, v131
	v_mov_b32_e32 v33, v131
	v_mov_b32_e32 v34, v131
	v_mov_b32_e32 v35, v131
	v_readlane_b32 s58, v254, 45
	v_readlane_b32 s59, v254, 46
	s_barrier
	v_readlane_b32 s57, v254, 44
; template <class Epi, class Sched, bool ALIGN_EPI = false, bool SP2 = false, bool A_TILED = false>
; __device__ __forceinline__ void gemm_phase(PG8_LAS unsigned char* lds, const Gemm g, const Sched& S, const Epi& E, const int wave_s) {
;     ...
;         for (int t = PEEL ? 2 : 0; t < nt; t += 2) {
;             const bool last = (t == nt - 2);
;             const char* a1 = cA + (size_t)(t + 1) * kstepA;
;             const char* a2 = last ? nA : cA + (size_t)(t + 2) * kstepA; const char* b2 = last ? nB : cB + (size_t)(t + 2) * kstep;
;             const char* a3 = a2 + kstepA; const char* b3 = b2 + kstep;
;             if (last && has_next) S.a_ready(nxt);
.LBB0_3793:
	ds_read_b128 v[146:149], v140
	ds_read_b128 v[150:153], v140 offset:1024
	ds_read_b128 v[154:157], v140 offset:2048
	ds_read_b128 v[158:161], v140 offset:3072
	ds_read_b128 v[162:165], v141
	ds_read_b128 v[166:169], v141 offset:1024
	ds_read_b128 v[170:173], v141 offset:2048
	ds_read_b128 v[174:177], v141 offset:3072
	s_add_u32 s16, s58, s40
	s_addc_u32 s17, s59, s41
	s_add_u32 s18, s58, s38
	s_addc_u32 s19, s59, s39
	s_cmpk_eq_i32 s42, 0x7c
	s_cselect_b32 s20, s4, s16
	s_cselect_b32 s21, s5, s17
	s_cselect_b32 s18, s0, s18
	s_cselect_b32 s19, s1, s19
	s_add_u32 s16, s20, 0x8000
	s_addc_u32 s17, s21, 0
	s_mov_b32 m0, s43
	v_lshl_add_u64 v[210:211], s[58:59], 0, v[138:139]
	ds_read_b128 v[178:181], v142
	ds_read_b128 v[182:185], v142 offset:1024
	ds_read_b128 v[186:189], v142 offset:2048
	ds_read_b128 v[190:193], v142 offset:3072
	ds_read_b128 v[194:197], v142 offset:4096
	ds_read_b128 v[198:201], v142 offset:5120
	ds_read_b128 v[202:205], v142 offset:6144
	ds_read_b128 v[206:209], v142 offset:7168
	global_load_lds_dwordx4 v[210:211], off
	v_lshl_add_u64 v[210:211], s[58:59], 0, v[136:137]
	s_mov_b32 m0, s44
	s_nop 0
	global_load_lds_dwordx4 v[210:211], off
	s_waitcnt vmcnt(8) lgkmcnt(0)
	s_barrier
	v_mfma_f32_16x16x32_bf16 v[32:35], v[146:149], v[178:181], v[32:35]
	v_mfma_f32_16x16x32_bf16 v[36:39], v[154:157], v[178:181], v[36:39]
	v_mfma_f32_16x16x32_bf16 v[76:79], v[146:149], v[186:189], v[76:79]
	v_mfma_f32_16x16x32_bf16 v[80:83], v[154:157], v[186:189], v[80:83]
	v_mfma_f32_16x16x32_bf16 v[92:95], v[146:149], v[194:197], v[92:95]
	v_mfma_f32_16x16x32_bf16 v[84:87], v[154:157], v[194:197], v[84:87]
	v_mfma_f32_16x16x32_bf16 v[108:111], v[146:149], v[202:205], v[108:111]
	v_mfma_f32_16x16x32_bf16 v[104:107], v[154:157], v[202:205], v[104:107]
	v_mfma_f32_16x16x32_bf16 v[32:35], v[150:153], v[182:185], v[32:35]
	v_mfma_f32_16x16x32_bf16 v[36:39], v[158:161], v[182:185], v[36:39]
	v_mfma_f32_16x16x32_bf16 v[76:79], v[150:153], v[190:193], v[76:79]
	v_mfma_f32_16x16x32_bf16 v[80:83], v[158:161], v[190:193], v[80:83]
	v_mfma_f32_16x16x32_bf16 v[92:95], v[150:153], v[198:201], v[92:95]
	v_mfma_f32_16x16x32_bf16 v[84:87], v[158:161], v[198:201], v[84:87]
	v_mfma_f32_16x16x32_bf16 v[108:111], v[150:153], v[206:209], v[108:111]
	v_mfma_f32_16x16x32_bf16 v[104:107], v[158:161], v[206:209], v[104:107]
	v_mfma_f32_16x16x32_bf16 v[40:43], v[162:165], v[178:181], v[40:43]
	v_mfma_f32_16x16x32_bf16 v[44:47], v[170:173], v[178:181], v[44:47]
	v_mfma_f32_16x16x32_bf16 v[68:71], v[162:165], v[186:189], v[68:71]
	v_mfma_f32_16x16x32_bf16 v[64:67], v[170:173], v[186:189], v[64:67]
	v_mfma_f32_16x16x32_bf16 v[60:63], v[162:165], v[194:197], v[60:63]
	v_mfma_f32_16x16x32_bf16 v[56:59], v[170:173], v[194:197], v[56:59]
	v_mfma_f32_16x16x32_bf16 v[100:103], v[162:165], v[202:205], v[100:103]
	v_mfma_f32_16x16x32_bf16 v[96:99], v[170:173], v[202:205], v[96:99]
	v_mfma_f32_16x16x32_bf16 v[40:43], v[166:169], v[182:185], v[40:43]
	v_mfma_f32_16x16x32_bf16 v[44:47], v[174:177], v[182:185], v[44:47]
	v_mfma_f32_16x16x32_bf16 v[68:71], v[166:169], v[190:193], v[68:71]
	v_mfma_f32_16x16x32_bf16 v[64:67], v[174:177], v[190:193], v[64:67]
	v_mfma_f32_16x16x32_bf16 v[60:63], v[166:169], v[198:201], v[60:63]
	v_mfma_f32_16x16x32_bf16 v[56:59], v[174:177], v[198:201], v[56:59]
	v_mfma_f32_16x16x32_bf16 v[100:103], v[166:169], v[206:209], v[100:103]
	v_mfma_f32_16x16x32_bf16 v[96:99], v[174:177], v[206:209], v[96:99]
	s_barrier
	s_mov_b32 m0, s45
	v_lshl_add_u64 v[210:211], s[18:19], 0, v[130:131]
	s_add_u32 s54, s18, 0x200000
	ds_read_b128 v[178:181], v142 offset:16384
	ds_read_b128 v[182:185], v142 offset:17408
	ds_read_b128 v[186:189], v142 offset:18432
	ds_read_b128 v[190:193], v142 offset:19456
	ds_read_b128 v[194:197], v142 offset:20480
	ds_read_b128 v[198:201], v142 offset:21504
	ds_read_b128 v[202:205], v142 offset:22528
	ds_read_b128 v[206:209], v142 offset:23552
	global_load_lds_dwordx4 v130, s[18:19]
	v_lshl_add_u64 v[212:213], s[18:19], 0, v[134:135]
	s_mov_b32 m0, s46
	s_addc_u32 s55, s19, 0
	global_load_lds_dwordx4 v134, s[18:19]
	v_lshl_add_u64 v[214:215], s[54:55], 0, v[130:131]
	s_mov_b32 m0, s47
	s_nop 0
	global_load_lds_dwordx4 v130, s[54:55]
	v_lshl_add_u64 v[214:215], s[54:55], 0, v[134:135]
	s_mov_b32 m0, s48
	s_nop 0
	global_load_lds_dwordx4 v134, s[54:55]
	v_lshl_add_u64 v[214:215], s[20:21], 0, v[128:129]
	s_mov_b32 m0, s25
	s_nop 0
	global_load_lds_dwordx4 v128, s[20:21]
	v_lshl_add_u64 v[214:215], s[20:21], 0, v[132:133]
	s_mov_b32 m0, s26
	s_nop 0
	global_load_lds_dwordx4 v132, s[20:21]
	s_waitcnt vmcnt(8) lgkmcnt(0)
	s_barrier
	v_mfma_f32_16x16x32_bf16 v[124:127], v[146:149], v[178:181], v[124:127]
	v_mfma_f32_16x16x32_bf16 v[120:123], v[154:157], v[178:181], v[120:123]
	v_mfma_f32_16x16x32_bf16 v[88:91], v[146:149], v[186:189], v[88:91]
	v_mfma_f32_16x16x32_bf16 v[72:75], v[154:157], v[186:189], v[72:75]
	v_mfma_f32_16x16x32_bf16 v[28:31], v[146:149], v[194:197], v[28:31]
	v_mfma_f32_16x16x32_bf16 v[24:27], v[154:157], v[194:197], v[24:27]
	v_mfma_f32_16x16x32_bf16 v[12:15], v[146:149], v[202:205], v[12:15]
	v_mfma_f32_16x16x32_bf16 v[8:11], v[154:157], v[202:205], v[8:11]
	v_mfma_f32_16x16x32_bf16 v[124:127], v[150:153], v[182:185], v[124:127]
	v_mfma_f32_16x16x32_bf16 v[120:123], v[158:161], v[182:185], v[120:123]
	v_mfma_f32_16x16x32_bf16 v[88:91], v[150:153], v[190:193], v[88:91]
	v_mfma_f32_16x16x32_bf16 v[72:75], v[158:161], v[190:193], v[72:75]
	v_mfma_f32_16x16x32_bf16 v[28:31], v[150:153], v[198:201], v[28:31]
	v_mfma_f32_16x16x32_bf16 v[24:27], v[158:161], v[198:201], v[24:27]
	v_mfma_f32_16x16x32_bf16 v[12:15], v[150:153], v[206:209], v[12:15]
	v_mfma_f32_16x16x32_bf16 v[8:11], v[158:161], v[206:209], v[8:11]
	v_mfma_f32_16x16x32_bf16 v[116:119], v[162:165], v[178:181], v[116:119]
	v_mfma_f32_16x16x32_bf16 v[112:115], v[170:173], v[178:181], v[112:115]
	v_mfma_f32_16x16x32_bf16 v[52:55], v[162:165], v[186:189], v[52:55]
	v_mfma_f32_16x16x32_bf16 v[48:51], v[170:173], v[186:189], v[48:51]
	v_mfma_f32_16x16x32_bf16 v[20:23], v[162:165], v[194:197], v[20:23]
	v_mfma_f32_16x16x32_bf16 v[16:19], v[170:173], v[194:197], v[16:19]
	v_mfma_f32_16x16x32_bf16 v[4:7], v[162:165], v[202:205], v[4:7]
	v_mfma_f32_16x16x32_bf16 v[0:3], v[170:173], v[202:205], v[0:3]
	v_mfma_f32_16x16x32_bf16 v[116:119], v[166:169], v[182:185], v[116:119]
	v_mfma_f32_16x16x32_bf16 v[112:115], v[174:177], v[182:185], v[112:115]
	v_mfma_f32_16x16x32_bf16 v[52:55], v[166:169], v[190:193], v[52:55]
	v_mfma_f32_16x16x32_bf16 v[48:51], v[174:177], v[190:193], v[48:51]
	v_mfma_f32_16x16x32_bf16 v[20:23], v[166:169], v[198:201], v[20:23]
	v_mfma_f32_16x16x32_bf16 v[16:19], v[174:177], v[198:201], v[16:19]
	v_mfma_f32_16x16x32_bf16 v[4:7], v[166:169], v[206:209], v[4:7]
	v_mfma_f32_16x16x32_bf16 v[0:3], v[174:177], v[206:209], v[0:3]
	s_barrier
	ds_read_b128 v[146:149], v143
	ds_read_b128 v[150:153], v143 offset:1024
	ds_read_b128 v[154:157], v143 offset:2048
	ds_read_b128 v[158:161], v143 offset:3072
	ds_read_b128 v[162:165], v144
	ds_read_b128 v[166:169], v144 offset:1024
	ds_read_b128 v[170:173], v144 offset:2048
	ds_read_b128 v[174:177], v144 offset:3072
	s_add_u32 s20, s20, 0x4000
	s_addc_u32 s21, s21, 0
	s_mov_b32 m0, s27
	v_lshl_add_u64 v[214:215], s[20:21], 0, v[128:129]
	ds_read_b128 v[178:181], v142 offset:32768
	ds_read_b128 v[182:185], v142 offset:33792
	ds_read_b128 v[186:189], v142 offset:34816
	ds_read_b128 v[190:193], v142 offset:35840
	ds_read_b128 v[194:197], v142 offset:36864
	ds_read_b128 v[198:201], v142 offset:37888
	ds_read_b128 v[202:205], v142 offset:38912
	ds_read_b128 v[206:209], v142 offset:39936
	global_load_lds_dwordx4 v128, s[20:21]
	v_lshl_add_u64 v[214:215], s[20:21], 0, v[132:133]
	s_mov_b32 m0, s34
	s_nop 0
	global_load_lds_dwordx4 v132, s[20:21]
	s_waitcnt vmcnt(8) lgkmcnt(0)
	s_barrier
	v_mfma_f32_16x16x32_bf16 v[32:35], v[146:149], v[178:181], v[32:35]
	v_mfma_f32_16x16x32_bf16 v[36:39], v[154:157], v[178:181], v[36:39]
	v_mfma_f32_16x16x32_bf16 v[76:79], v[146:149], v[186:189], v[76:79]
	v_mfma_f32_16x16x32_bf16 v[80:83], v[154:157], v[186:189], v[80:83]
	v_mfma_f32_16x16x32_bf16 v[92:95], v[146:149], v[194:197], v[92:95]
	v_mfma_f32_16x16x32_bf16 v[84:87], v[154:157], v[194:197], v[84:87]
	v_mfma_f32_16x16x32_bf16 v[108:111], v[146:149], v[202:205], v[108:111]
	v_mfma_f32_16x16x32_bf16 v[104:107], v[154:157], v[202:205], v[104:107]
	v_mfma_f32_16x16x32_bf16 v[32:35], v[150:153], v[182:185], v[32:35]
	v_mfma_f32_16x16x32_bf16 v[36:39], v[158:161], v[182:185], v[36:39]
	v_mfma_f32_16x16x32_bf16 v[76:79], v[150:153], v[190:193], v[76:79]
	v_mfma_f32_16x16x32_bf16 v[80:83], v[158:161], v[190:193], v[80:83]
	v_mfma_f32_16x16x32_bf16 v[92:95], v[150:153], v[198:201], v[92:95]
	v_mfma_f32_16x16x32_bf16 v[84:87], v[158:161], v[198:201], v[84:87]
	v_mfma_f32_16x16x32_bf16 v[108:111], v[150:153], v[206:209], v[108:111]
	v_mfma_f32_16x16x32_bf16 v[104:107], v[158:161], v[206:209], v[104:107]
	v_mfma_f32_16x16x32_bf16 v[40:43], v[162:165], v[178:181], v[40:43]
	v_mfma_f32_16x16x32_bf16 v[44:47], v[170:173], v[178:181], v[44:47]
	v_mfma_f32_16x16x32_bf16 v[68:71], v[162:165], v[186:189], v[68:71]
	v_mfma_f32_16x16x32_bf16 v[64:67], v[170:173], v[186:189], v[64:67]
	v_mfma_f32_16x16x32_bf16 v[60:63], v[162:165], v[194:197], v[60:63]
	v_mfma_f32_16x16x32_bf16 v[56:59], v[170:173], v[194:197], v[56:59]
	v_mfma_f32_16x16x32_bf16 v[100:103], v[162:165], v[202:205], v[100:103]
	v_mfma_f32_16x16x32_bf16 v[96:99], v[170:173], v[202:205], v[96:99]
	v_mfma_f32_16x16x32_bf16 v[40:43], v[166:169], v[182:185], v[40:43]
	v_mfma_f32_16x16x32_bf16 v[44:47], v[174:177], v[182:185], v[44:47]
	v_mfma_f32_16x16x32_bf16 v[68:71], v[166:169], v[190:193], v[68:71]
	v_mfma_f32_16x16x32_bf16 v[64:67], v[174:177], v[190:193], v[64:67]
	v_mfma_f32_16x16x32_bf16 v[60:63], v[166:169], v[198:201], v[60:63]
	v_mfma_f32_16x16x32_bf16 v[56:59], v[174:177], v[198:201], v[56:59]
	v_mfma_f32_16x16x32_bf16 v[100:103], v[166:169], v[206:209], v[100:103]
	v_mfma_f32_16x16x32_bf16 v[96:99], v[174:177], v[206:209], v[96:99]
	s_barrier
; template <class Epi, class Sched, bool ALIGN_EPI = false, bool SP2 = false, bool A_TILED = false>
; __device__ __forceinline__ void gemm_phase(PG8_LAS unsigned char* lds, const Gemm g, const Sched& S, const Epi& E, const int wave_s) {
;     ...
;         for (int t = PEEL ? 2 : 0; t < nt; t += 2) {
;             const bool last = (t == nt - 2);
;             const char* a1 = cA + (size_t)(t + 1) * kstepA;
	s_mov_b32 m0, s49
	v_lshl_add_u64 v[210:211], v[210:211], 0, s[12:13]
	s_add_u32 s18, s18, 0x200080
	ds_read_b128 v[178:181], v142 offset:49152
	ds_read_b128 v[182:185], v142 offset:50176
	ds_read_b128 v[186:189], v142 offset:51200
	ds_read_b128 v[190:193], v142 offset:52224
	ds_read_b128 v[194:197], v142 offset:53248
	ds_read_b128 v[198:201], v142 offset:54272
	ds_read_b128 v[202:205], v142 offset:55296
	ds_read_b128 v[206:209], v142 offset:56320
	global_load_lds_dwordx4 v[210:211], off
	v_lshl_add_u64 v[210:211], v[212:213], 0, s[12:13]
	s_mov_b32 m0, s50
	s_addc_u32 s19, s19, 0
	global_load_lds_dwordx4 v[210:211], off
	v_lshl_add_u64 v[210:211], s[18:19], 0, v[130:131]
	s_mov_b32 m0, s51
	s_nop 0
	global_load_lds_dwordx4 v130, s[18:19]
	v_lshl_add_u64 v[210:211], s[18:19], 0, v[134:135]
	s_mov_b32 m0, s52
	s_nop 0
	global_load_lds_dwordx4 v134, s[18:19]
	v_lshl_add_u64 v[210:211], s[16:17], 0, v[128:129]
	s_mov_b32 m0, s36
	s_nop 0
	global_load_lds_dwordx4 v128, s[16:17]
	v_lshl_add_u64 v[210:211], s[16:17], 0, v[132:133]
	s_mov_b32 m0, s37
	s_nop 0
	global_load_lds_dwordx4 v132, s[16:17]
	s_waitcnt vmcnt(8) lgkmcnt(0)
	s_barrier
	v_mfma_f32_16x16x32_bf16 v[124:127], v[146:149], v[178:181], v[124:127]
	v_mfma_f32_16x16x32_bf16 v[120:123], v[154:157], v[178:181], v[120:123]
	v_mfma_f32_16x16x32_bf16 v[88:91], v[146:149], v[186:189], v[88:91]
	v_mfma_f32_16x16x32_bf16 v[72:75], v[154:157], v[186:189], v[72:75]
	v_mfma_f32_16x16x32_bf16 v[28:31], v[146:149], v[194:197], v[28:31]
	v_mfma_f32_16x16x32_bf16 v[24:27], v[154:157], v[194:197], v[24:27]
	v_mfma_f32_16x16x32_bf16 v[12:15], v[146:149], v[202:205], v[12:15]
	v_mfma_f32_16x16x32_bf16 v[8:11], v[154:157], v[202:205], v[8:11]
	v_mfma_f32_16x16x32_bf16 v[124:127], v[150:153], v[182:185], v[124:127]
	v_mfma_f32_16x16x32_bf16 v[120:123], v[158:161], v[182:185], v[120:123]
	v_mfma_f32_16x16x32_bf16 v[88:91], v[150:153], v[190:193], v[88:91]
	v_mfma_f32_16x16x32_bf16 v[72:75], v[158:161], v[190:193], v[72:75]
	v_mfma_f32_16x16x32_bf16 v[28:31], v[150:153], v[198:201], v[28:31]
	v_mfma_f32_16x16x32_bf16 v[24:27], v[158:161], v[198:201], v[24:27]
	v_mfma_f32_16x16x32_bf16 v[12:15], v[150:153], v[206:209], v[12:15]
	v_mfma_f32_16x16x32_bf16 v[8:11], v[158:161], v[206:209], v[8:11]
	v_mfma_f32_16x16x32_bf16 v[116:119], v[162:165], v[178:181], v[116:119]
	v_mfma_f32_16x16x32_bf16 v[112:115], v[170:173], v[178:181], v[112:115]
	v_mfma_f32_16x16x32_bf16 v[52:55], v[162:165], v[186:189], v[52:55]
	v_mfma_f32_16x16x32_bf16 v[48:51], v[170:173], v[186:189], v[48:51]
	v_mfma_f32_16x16x32_bf16 v[20:23], v[162:165], v[194:197], v[20:23]
	v_mfma_f32_16x16x32_bf16 v[16:19], v[170:173], v[194:197], v[16:19]
	v_mfma_f32_16x16x32_bf16 v[4:7], v[162:165], v[202:205], v[4:7]
	v_mfma_f32_16x16x32_bf16 v[0:3], v[170:173], v[202:205], v[0:3]
	v_mfma_f32_16x16x32_bf16 v[116:119], v[166:169], v[182:185], v[116:119]
	v_mfma_f32_16x16x32_bf16 v[112:115], v[174:177], v[182:185], v[112:115]
	v_mfma_f32_16x16x32_bf16 v[52:55], v[166:169], v[190:193], v[52:55]
	v_mfma_f32_16x16x32_bf16 v[48:51], v[174:177], v[190:193], v[48:51]
	v_mfma_f32_16x16x32_bf16 v[20:23], v[166:169], v[198:201], v[20:23]
	v_mfma_f32_16x16x32_bf16 v[16:19], v[174:177], v[198:201], v[16:19]
	v_mfma_f32_16x16x32_bf16 v[4:7], v[166:169], v[206:209], v[4:7]
	v_mfma_f32_16x16x32_bf16 v[0:3], v[174:177], v[206:209], v[0:3]
	s_barrier
	s_add_i32 s42, s42, 2
	s_add_u32 s38, s38, 0x100
	s_addc_u32 s39, s39, 0
	s_add_u32 s40, s40, 0x10000
	s_addc_u32 s41, s41, 0
	v_lshl_add_u64 v[136:137], v[136:137], 0, s[14:15]
	s_cmpk_gt_u32 s42, 0x7d
	v_lshl_add_u64 v[138:139], v[138:139], 0, s[14:15]
	s_cbranch_scc0 .LBB0_3793
	s_waitcnt vmcnt(0)
	s_cmpk_lt_u32 s22, 0x100
	s_cbranch_scc0 .LBB0_3796
	s_barrier

; __device__ __forceinline__ int tid_now(int wave_s) { unsigned z = 0u; asm volatile("" : "+v"(z)); return (wave_s << 6) | (int)__builtin_amdgcn_mbcnt_hi(~0u, __builtin_amdgcn_mbcnt_lo(~0u, z)); }
; __device__ __forceinline__ unsigned xb_add(unsigned* p, unsigned v) { return __hip_atomic_fetch_add(p, v, __ATOMIC_RELAXED, __HIP_MEMORY_SCOPE_AGENT); }
; __device__ __forceinline__ void xcd_barrier(const XcdBarrier& b) {
;     asm volatile("s_waitcnt vmcnt(0)" ::: "memory");
;     __syncthreads();
;     if (tid_now(b.w) == 0) {
;         unsigned* bar = b.bar;
;         __builtin_amdgcn_s_waitcnt(0);
;         unsigned nloc = b.st[0], nx = b.st[1];
;         if (nloc == 0u) { xcd_barrier_complete(bar, b.x, nloc, nx, b.np); b.st[0] = nloc; b.st[1] = nx; }
;         const unsigned old = xb_add(&bar[XB_XSUB(b.x)], 1u);
.LBB0_3837:
	s_setprio 0
	s_cmp_gt_i32 s35, 25
	s_cselect_b64 s[0:1], -1, 0
	s_and_b64 s[0:1], s[6:7], s[0:1]
	s_andn2_b64 vcc, exec, s[0:1]
	s_branch .LBB0_3891
	s_waitcnt vmcnt(0)
	v_mov_b32_e32 v0, 0
	s_waitcnt vmcnt(0)
	s_waitcnt lgkmcnt(0)
	s_barrier
	s_nop 0
	v_mbcnt_lo_u32_b32 v0, -1, v0
	v_mbcnt_hi_u32_b32 v0, -1, v0
	v_or_b32_e32 v0, s33, v0
	v_cmp_eq_u32_e32 vcc, 0, v0
	s_and_saveexec_b64 s[0:1], vcc
	s_cbranch_execz .LBB0_3890
	s_add_i32 s2, 0, 0x27f68
	v_mov_b32_e32 v0, s2
	s_waitcnt vmcnt(0) expcnt(0) lgkmcnt(0)
	ds_read_b32 v2, v0
	s_add_i32 s2, 0, 0x27f6c
	v_mov_b32_e32 v0, s2
	ds_read_b32 v0, v0
	s_waitcnt lgkmcnt(1)
	v_cmp_ne_u32_e32 vcc, 0, v2
	s_cbranch_vccnz .LBB0_3854
	s_add_u32 s2, s10, 0x1000
	s_addc_u32 s3, s11, 0
	s_add_u32 s4, s10, 0x1100
	s_addc_u32 s5, s11, 0
	s_add_u32 s6, s10, 0x1200
	s_addc_u32 s7, s11, 0
	s_add_u32 s8, s10, 0x1300
	s_addc_u32 s9, s11, 0
	s_mov_b32 s18, 1
	v_mov_b32_e32 v16, 0
	s_branch .LBB0_3842
